# ring-pipelined gather_u/gather_v, coalesced table conversion loads, and the redundant grid sync between weight conversion and the first rmsnorm removed (phase 1 reads nothing phase 0 writes)
# speedup vs baseline: 1.1663x; 1.0465x over previous
.LBB0_35:
	s_or_b64 exec, exec, s[0:1]
	s_and_b32 s0, 0xffff, s20
	s_cmp_lg_u32 s0, 0
	s_cselect_b64 s[6:7], -1, 0
	s_cmp_lg_u64 s[6:7], 0
	s_addc_u32 s92, s96, 0
	s_lshr_b32 s3, s92, 1
	v_cvt_f32_u32_e32 v1, s3
	s_sub_i32 s0, 0, s3
	v_mov_b32_e32 v2, v205
	v_mov_b32_e32 v3, v205
	v_rcp_iflag_f32_e32 v1, v1
	v_mbcnt_lo_u32_b32 v207, -1, 0
	v_mul_f32_e32 v1, 0x4f7ffffe, v1
	v_cvt_u32_f32_e32 v1, v1
	v_ashrrev_i32_e32 v3, 6, v3
	v_readfirstlane_b32 s1, v1
	s_mul_i32 s0, s0, s1
	s_mul_hi_u32 s0, s1, s0
	s_add_i32 s1, s1, s0
	s_mul_hi_u32 s0, s2, s1
	s_mul_i32 s0, s0, s3
	s_sub_i32 s0, s2, s0
	s_sub_i32 s1, s0, s3
	s_cmp_ge_u32 s0, s3
	s_cselect_b32 s0, s1, s0
	s_sub_i32 s1, s0, s3
	s_cmp_ge_u32 s0, s3
	s_cselect_b32 s0, s1, s0
	s_add_u32 s52, s26, 0x1400000
	s_addc_u32 s53, s27, 0
	s_and_b32 s19, s92, -2
	s_lshl_b32 s0, s0, 3
	s_cmp_lt_u32 s2, s3
	s_cselect_b32 s1, 0, 4
	s_or_b32 s21, s0, s1
	v_add_u32_e32 v1, s21, v3
	s_movk_i32 s0, 0x2000
	v_cmp_gt_i32_e32 vcc, s0, v1
	s_and_saveexec_b64 s[14:15], vcc
	s_cbranch_execz .LBB0_40
	v_and_b32_e32 v5, 31, v2
	v_bfe_u32 v4, v2, 5, 1
	v_lshlrev_b32_e32 v2, 4, v5
	v_mov_b32_e32 v3, 0
	v_mbcnt_hi_u32_b32 v6, -1, v207
	v_lshl_add_u64 v[26:27], s[8:9], 0, v[2:3]
	v_and_b32_e32 v2, 64, v6
	v_add_u32_e32 v7, 64, v2
	v_and_b32_e32 v2, 7, v5
	v_mul_u32_u24_e32 v2, 24, v2
	v_lshrrev_b32_e32 v3, 3, v5
	v_mul_u32_u24_e32 v3, 0x300000, v3
	v_add_u32_e32 v2, v2, v3
	v_mov_b32_e32 v3, 0
	v_lshl_add_u64 v[2:3], s[26:27], 0, v[2:3]
	s_mov_b64 s[0:1], 0x1800000
	v_lshl_add_u64 v[28:29], v[2:3], 0, s[0:1]
	v_xor_b32_e32 v2, 16, v6
	v_cmp_lt_i32_e32 vcc, v2, v7
	v_cmp_eq_u32_e64 s[0:1], 0, v5
	s_lshl_b32 s28, s19, 2
	v_cndmask_b32_e32 v2, v6, v2, vcc
	v_lshlrev_b32_e32 v38, 2, v2
	v_xor_b32_e32 v2, 8, v6
	v_cmp_lt_i32_e32 vcc, v2, v7
	v_lshl_or_b32 v30, v1, 1, v4
	s_lshl_b32 s29, s3, 4
	v_cndmask_b32_e32 v2, v6, v2, vcc
	v_lshlrev_b32_e32 v39, 2, v2
	v_xor_b32_e32 v2, 4, v6
	v_cmp_lt_i32_e32 vcc, v2, v7
	s_mov_b64 s[16:17], 0
	s_movk_i32 s30, 0xc0
	v_cndmask_b32_e32 v2, v6, v2, vcc
	v_lshlrev_b32_e32 v40, 2, v2
	v_xor_b32_e32 v2, 2, v6
	v_cmp_lt_i32_e32 vcc, v2, v7
	s_mov_b32 s31, 0x40f00000
	s_mov_b32 s18, 0x41000000
	v_cndmask_b32_e32 v2, v6, v2, vcc
	v_lshlrev_b32_e32 v41, 2, v2
	v_xor_b32_e32 v2, 1, v6
	v_cmp_lt_i32_e32 vcc, v2, v7
	s_mov_b32 s20, 0x41800000
	s_movk_i32 s34, 0x1fff
	v_cndmask_b32_e32 v2, v6, v2, vcc
	v_lshlrev_b32_e32 v42, 2, v2
	s_branch .LBB0_38

.LBB0_38:
	v_ashrrev_i32_e32 v31, 31, v30
	v_lshlrev_b64 v[2:3], 12, v[30:31]
	v_lshl_add_u64 v[10:11], v[26:27], 0, v[2:3]
	global_load_dwordx4 v[2:5], v[10:11], off offset:1024
	global_load_dwordx4 v[22:25], v[10:11], off offset:1536
	global_load_dwordx4 v[6:9], v[10:11], off offset:2048
	global_load_dwordx4 v[44:47], v[10:11], off
	global_load_dwordx4 v[48:51], v[10:11], off offset:512
	global_load_dwordx4 v[18:21], v[10:11], off offset:2560
	global_load_dwordx4 v[14:17], v[10:11], off offset:3072
	s_nop 0
	global_load_dwordx4 v[10:13], v[10:11], off offset:3584
	s_waitcnt vmcnt(7)
	v_max_f32_e64 v32, |v5|, |v5|
	v_max_f32_e64 v33, |v4|, |v4|
	s_waitcnt vmcnt(6)
	v_max_f32_e64 v34, |v25|, |v25|
	v_max_f32_e64 v35, |v24|, |v24|
	s_waitcnt vmcnt(5)
	v_max_f32_e64 v36, |v7|, |v7|
	v_max_f32_e64 v37, |v6|, |v6|
	s_waitcnt vmcnt(4)
	v_max_f32_e64 v43, |v45|, |v45|
	v_max_f32_e64 v52, |v44|, |v44|
	v_max_f32_e64 v53, |v47|, |v47|
	v_max_f32_e64 v54, |v46|, |v46|
	s_waitcnt vmcnt(3)
	v_max_f32_e64 v55, |v49|, |v49|
	v_max_f32_e64 v56, |v48|, |v48|
	v_max_f32_e64 v57, |v51|, |v51|
	v_max_f32_e64 v58, |v50|, |v50|
	v_max_f32_e32 v32, v33, v32
	v_max_f32_e32 v33, v35, v34
	v_max_f32_e32 v34, v37, v36
	v_max_f32_e32 v35, v52, v43
	v_max_f32_e32 v36, v54, v53
	v_max_f32_e64 v59, |v3|, |v3|
	v_max_f32_e64 v60, |v2|, |v2|
	v_max_f32_e32 v37, v56, v55
	v_max_f32_e32 v43, v58, v57
	v_max3_f32 v35, v35, 0, v36
	v_max_f32_e64 v61, |v23|, |v23|
	v_max_f32_e64 v62, |v22|, |v22|
	v_max_f32_e32 v52, v60, v59
	v_max3_f32 v35, v35, v37, v43
	v_max_f32_e64 v63, |v9|, |v9|
	v_max_f32_e64 v64, |v8|, |v8|
	v_max_f32_e32 v53, v62, v61
	v_max3_f32 v32, v35, v52, v32
	s_waitcnt vmcnt(2)
	v_max_f32_e64 v65, |v19|, |v19|
	v_max_f32_e64 v66, |v18|, |v18|
	v_max_f32_e64 v67, |v21|, |v21|
	v_max_f32_e64 v68, |v20|, |v20|
	v_max_f32_e32 v54, v64, v63
	v_max3_f32 v32, v32, v53, v33
	s_waitcnt vmcnt(1)
	v_max_f32_e64 v69, |v15|, |v15|
	v_max_f32_e64 v70, |v14|, |v14|
	v_max_f32_e64 v71, |v17|, |v17|
	v_max_f32_e64 v72, |v16|, |v16|
	v_max_f32_e32 v55, v66, v65
	v_max_f32_e32 v56, v68, v67
	v_max3_f32 v32, v32, v34, v54
	s_waitcnt vmcnt(0)
	v_max_f32_e64 v73, |v11|, |v11|
	v_max_f32_e64 v74, |v10|, |v10|
	v_max_f32_e64 v75, |v13|, |v13|
	v_max_f32_e64 v76, |v12|, |v12|
	v_max_f32_e32 v57, v70, v69
	v_max_f32_e32 v58, v72, v71
	v_max3_f32 v32, v32, v55, v56
	v_max_f32_e32 v59, v74, v73
	v_max_f32_e32 v60, v76, v75
	v_max3_f32 v32, v32, v57, v58
	v_max3_f32 v32, v32, v59, v60
	ds_bpermute_b32 v33, v38, v32
	v_mov_b32_e32 v36, v22
	v_mov_b32_e32 v37, v8
	v_mov_b32_e32 v8, v23
	v_mov_b32_e32 v52, v45
	s_waitcnt lgkmcnt(0)
	v_max_f32_e32 v33, v33, v33
	v_max_f32_e32 v32, v32, v33
	ds_bpermute_b32 v33, v39, v32
	v_mov_b32_e32 v53, v50
	v_mov_b32_e32 v50, v46
	v_mov_b32_e32 v46, v47
	v_mov_b32_e32 v47, v2
	s_waitcnt lgkmcnt(0)
	v_max_f32_e32 v33, v33, v33
	v_max_f32_e32 v34, v32, v33
	ds_bpermute_b32 v35, v40, v34
	v_mov_b32_e32 v2, v48
	v_mad_i64_i32 v[32:33], s[4:5], v30, s30, v[28:29]
	s_waitcnt lgkmcnt(0)
	v_max_f32_e32 v35, v35, v35
	v_max_f32_e32 v34, v34, v35
	ds_bpermute_b32 v35, v41, v34
	s_waitcnt lgkmcnt(0)
	v_max_f32_e32 v35, v35, v35
	v_max_f32_e32 v35, v34, v35
	ds_bpermute_b32 v43, v42, v35
	v_mov_b32_e32 v34, v24
	s_waitcnt lgkmcnt(0)
	v_max_f32_e32 v22, v43, v43
	v_max_f32_e32 v24, v35, v22
	v_div_scale_f32 v22, s[4:5], v24, v24, s31
	v_rcp_f32_e32 v23, v22
	v_mov_b32_e32 v35, v18
	v_div_scale_f32 v18, vcc, s31, v24, s31
	v_fma_f32 v43, -v22, v23, 1.0
	v_fmac_f32_e32 v23, v43, v23
	v_mul_f32_e32 v43, v18, v23
	v_fma_f32 v45, -v22, v43, v18
	v_fmac_f32_e32 v43, v45, v23
	v_fma_f32 v18, -v22, v43, v18
	v_div_fmas_f32 v18, v18, v23, v43
	v_div_fixup_f32 v18, v18, v24, s31
	v_cmp_lt_f32_e32 vcc, 0, v24
	s_nop 1
	v_cndmask_b32_e32 v18, 1.0, v18, vcc
	v_mul_f32_e32 v22, v44, v18
	v_pk_mul_f32 v[56:57], v[2:3], v[18:19] op_sel_hi:[1,0]
	v_min_f32_e64 v2, |v22|, s31
	v_mul_f32_e32 v43, 4.0, v2
	v_mul_f32_e32 v23, 0x41000000, v2
	v_add_f32_e32 v44, v2, v2
	v_rndne_f32_e32 v43, v43
	v_rndne_f32_e32 v23, v23
	v_rndne_f32_e32 v44, v44
	v_add_f32_e32 v43, 0x41000000, v43
	v_cmp_nle_f32_e64 s[4:5], 2.0, v2
	v_add_f32_e32 v44, 0x41800000, v44
	v_pk_mul_f32 v[54:55], v[46:47], v[18:19] op_sel_hi:[1,0]
	v_cndmask_b32_e64 v23, v43, v23, s[4:5]
	v_cmp_nle_f32_e64 s[4:5], 4.0, v2
	v_pk_mul_f32 v[52:53], v[52:53], v[18:19] op_sel_hi:[1,0]
	v_min_f32_e64 v67, |v54|, s31
	v_cndmask_b32_e64 v2, v44, v23, s[4:5]
	v_cvt_u32_f32_e32 v2, v2
	v_lshrrev_b32_e32 v3, 26, v22
	v_min_f32_e64 v22, |v52|, s31
	v_mul_f32_e32 v61, 0x41000000, v67
	v_add_f32_e32 v47, v22, v22
	v_rndne_f32_e32 v69, v61
	v_min_f32_e64 v61, |v53|, s31
	v_rndne_f32_e32 v48, v47
	v_min_u32_e32 v2, 31, v2
	v_mul_f32_e32 v47, 0x41000000, v61
	v_mul_f32_e32 v46, 4.0, v22
	v_and_or_b32 v43, v3, 32, v2
	v_mul_f32_e32 v3, v49, v18
	v_rndne_f32_e32 v49, v47
	v_mul_f32_e32 v47, 4.0, v61
	v_mul_f32_e32 v45, 0x41000000, v22
	v_rndne_f32_e32 v46, v46
	v_rndne_f32_e32 v47, v47
	v_rndne_f32_e32 v45, v45
	v_pk_add_f32 v[46:47], v[46:47], s[18:19] op_sel_hi:[1,0]
	v_cmp_nle_f32_e64 s[4:5], 2.0, v22
	v_pk_mul_f32 v[50:51], v[50:51], v[18:19] op_sel_hi:[1,0]
	v_min_f32_e64 v44, |v3|, s31
	v_cndmask_b32_e64 v45, v46, v45, s[4:5]
	v_cmp_nle_f32_e64 s[4:5], 2.0, v61
	v_add_f32_e32 v46, v61, v61
	v_min_f32_e64 v63, |v50|, s31
	v_cndmask_b32_e64 v72, v47, v49, s[4:5]
	v_rndne_f32_e32 v49, v46
	v_pk_add_f32 v[46:47], v[48:49], s[20:21] op_sel_hi:[1,0]
	v_cmp_nle_f32_e64 s[4:5], 4.0, v61
	v_mul_f32_e32 v58, 0x41000000, v63
	v_mul_f32_e32 v59, 4.0, v63
	v_cndmask_b32_e64 v47, v47, v72, s[4:5]
	v_cmp_nle_f32_e64 s[4:5], 4.0, v22
	v_rndne_f32_e32 v65, v58
	v_rndne_f32_e32 v58, v59
	v_cndmask_b32_e64 v22, v46, v45, s[4:5]
	v_cvt_u32_f32_e32 v46, v47
	v_cvt_u32_f32_e32 v47, v22
	v_lshrrev_b32_e32 v45, 26, v3
	v_add_f32_e32 v59, v44, v44
	v_min_u32_e32 v3, 31, v46
	v_lshrrev_b32_e32 v46, 26, v53
	v_min_f32_e64 v53, |v51|, s31
	v_and_b32_e32 v49, 32, v46
	v_mul_f32_e32 v46, 0x41000000, v53
	v_rndne_f32_e32 v61, v46
	v_mul_f32_e32 v46, 4.0, v53
	v_rndne_f32_e32 v22, v59
	v_min_u32_e32 v48, 31, v47
	v_lshrrev_b32_e32 v47, 26, v52
	v_rndne_f32_e32 v59, v46
	v_and_b32_e32 v52, 32, v47
	v_pk_add_f32 v[46:47], v[58:59], s[18:19] op_sel_hi:[1,0]
	v_cmp_nle_f32_e64 s[4:5], 2.0, v63
	v_add_f32_e32 v60, v63, v63
	v_rndne_f32_e32 v60, v60
	v_cndmask_b32_e64 v58, v46, v65, s[4:5]
	v_cmp_nle_f32_e64 s[4:5], 2.0, v53
	v_add_f32_e32 v46, v53, v53
	v_or_b32_e32 v3, v3, v49
	v_cndmask_b32_e64 v59, v47, v61, s[4:5]
	v_rndne_f32_e32 v61, v46
	v_pk_add_f32 v[46:47], v[60:61], s[20:21] op_sel_hi:[1,0]
	v_cmp_nle_f32_e64 s[4:5], 4.0, v53
	v_lshrrev_b32_e32 v49, 26, v50
	v_mul_f32_e32 v62, 4.0, v67
	v_cndmask_b32_e64 v47, v47, v59, s[4:5]
	v_cmp_nle_f32_e64 s[4:5], 4.0, v63
	v_rndne_f32_e32 v62, v62
	v_cvt_u32_f32_e32 v47, v47
	v_cndmask_b32_e64 v46, v46, v58, s[4:5]
	v_cvt_u32_f32_e32 v53, v46
	v_or_b32_e32 v46, v48, v52
	v_lshrrev_b32_e32 v48, 26, v51
	v_and_b32_e32 v50, 32, v48
	v_min_u32_e32 v52, 31, v53
	v_min_f32_e64 v53, |v55|, s31
	v_mul_f32_e32 v48, 0x41000000, v53
	v_rndne_f32_e32 v58, v48
	v_mul_f32_e32 v48, 4.0, v53
	v_rndne_f32_e32 v63, v48
	v_and_b32_e32 v51, 32, v49
	v_pk_add_f32 v[48:49], v[62:63], s[18:19] op_sel_hi:[1,0]
	v_cmp_nle_f32_e64 s[4:5], 2.0, v67
	v_add_f32_e32 v64, v67, v67
	v_rndne_f32_e32 v64, v64
	v_cndmask_b32_e64 v59, v48, v69, s[4:5]
	v_add_f32_e32 v48, v53, v53
	v_cmp_nle_f32_e64 s[4:5], 2.0, v53
	v_rndne_f32_e32 v65, v48
	v_min_u32_e32 v47, 31, v47
	v_cndmask_b32_e64 v58, v49, v58, s[4:5]
	v_pk_add_f32 v[48:49], v[64:65], s[20:21] op_sel_hi:[1,0]
	v_cmp_nle_f32_e64 s[4:5], 4.0, v53
	v_min_f32_e64 v70, |v56|, s31
	v_mul_f32_e32 v2, 0x41000000, v70
	v_cndmask_b32_e64 v49, v49, v58, s[4:5]
	v_cvt_u32_f32_e32 v53, v49
	v_or_b32_e32 v49, v47, v50
	v_or_b32_e32 v50, v52, v51
	v_lshrrev_b32_e32 v51, 26, v55
	v_lshrrev_b32_e32 v52, 26, v54
	v_min_f32_e64 v55, |v57|, s31
	v_and_b32_e32 v54, 32, v52
	v_mul_f32_e32 v52, 0x41000000, v55
	v_rndne_f32_e32 v71, v2
	v_mul_f32_e32 v2, 4.0, v70
	v_rndne_f32_e32 v58, v52
	v_mul_f32_e32 v52, 4.0, v55
	v_rndne_f32_e32 v66, v2
	v_cmp_nle_f32_e64 s[4:5], 4.0, v67
	v_rndne_f32_e32 v67, v52
	v_min_u32_e32 v47, 31, v53
	v_cndmask_b32_e64 v48, v48, v59, s[4:5]
	v_pk_add_f32 v[52:53], v[66:67], s[18:19] op_sel_hi:[1,0]
	v_cmp_nle_f32_e64 s[4:5], 2.0, v70
	v_add_f32_e32 v2, v70, v70
	v_rndne_f32_e32 v68, v2
	v_cndmask_b32_e64 v59, v52, v71, s[4:5]
	v_add_f32_e32 v52, v55, v55
	v_cmp_nle_f32_e64 s[4:5], 2.0, v55
	v_rndne_f32_e32 v69, v52
	v_cvt_u32_f32_e32 v48, v48
	v_cndmask_b32_e64 v58, v53, v58, s[4:5]
	v_pk_add_f32 v[52:53], v[68:69], s[20:21] op_sel_hi:[1,0]
	v_cmp_nle_f32_e64 s[4:5], 4.0, v55
	v_mul_f32_e32 v5, v5, v18
	v_min_u32_e32 v48, 31, v48
	v_cndmask_b32_e64 v53, v53, v58, s[4:5]
	v_cvt_u32_f32_e32 v53, v53
	v_and_b32_e32 v51, 32, v51
	v_min_f32_e64 v55, |v5|, s31
	v_or_b32_sdwa v47, v47, v51 dst_sel:WORD_1 dst_unused:UNUSED_PAD src0_sel:DWORD src1_sel:DWORD
	v_or_b32_e32 v51, v48, v54
	v_min_u32_e32 v48, 31, v53
	v_lshrrev_b32_e32 v53, 26, v57
	v_mul_f32_e32 v57, 4.0, v55
	v_cmp_nle_f32_e64 s[4:5], 4.0, v70
	v_lshrrev_b32_e32 v54, 26, v56
	v_mul_f32_e32 v56, 0x41000000, v55
	v_rndne_f32_e32 v57, v57
	v_cndmask_b32_e64 v52, v52, v59, s[4:5]
	v_rndne_f32_e32 v56, v56
	v_add_f32_e32 v57, 0x41000000, v57
	v_cmp_nle_f32_e64 s[4:5], 2.0, v55
	v_cvt_u32_f32_e32 v52, v52
	v_and_b32_e32 v53, 32, v53
	v_cndmask_b32_e64 v56, v57, v56, s[4:5]
	v_add_f32_e32 v57, v55, v55
	v_rndne_f32_e32 v57, v57
	v_add_f32_e32 v57, 0x41800000, v57
	v_cmp_nle_f32_e64 s[4:5], 4.0, v55
	v_min_u32_e32 v52, 31, v52
	v_and_b32_e32 v54, 32, v54
	v_cndmask_b32_e64 v55, v57, v56, s[4:5]
	v_cvt_u32_f32_e32 v55, v55
	v_or_b32_e32 v66, v48, v53
	v_or_b32_sdwa v48, v52, v54 dst_sel:BYTE_3 dst_unused:UNUSED_PAD src0_sel:DWORD src1_sel:DWORD
	v_lshrrev_b32_e32 v5, 26, v5
	v_min_u32_e32 v52, 31, v55
	v_pk_mul_f32 v[36:37], v[36:37], v[18:19] op_sel_hi:[1,0]
	v_and_or_b32 v67, v5, 32, v52
	v_min_f32_e64 v5, |v36|, s31
	v_pk_mul_f32 v[8:9], v[8:9], v[18:19] op_sel_hi:[1,0]
	v_add_f32_e32 v53, v5, v5
	v_min_f32_e64 v61, |v8|, s31
	v_rndne_f32_e32 v54, v53
	v_mul_f32_e32 v53, 0x41000000, v61
	v_rndne_f32_e32 v59, v53
	v_mul_f32_e32 v53, 4.0, v61
	v_pk_mul_f32 v[34:35], v[34:35], v[18:19] op_sel_hi:[1,0]
	v_rndne_f32_e32 v56, v53
	v_add_f32_e32 v53, v61, v61
	v_min_f32_e64 v64, |v34|, s31
	v_rndne_f32_e32 v58, v53
	v_mul_f32_e32 v53, 0x41000000, v64
	v_rndne_f32_e32 v63, v53
	v_mul_f32_e32 v53, 4.0, v64
	v_mul_f32_e32 v25, v25, v18
	v_rndne_f32_e32 v60, v53
	v_min_f32_e64 v53, |v25|, s31
	v_mul_f32_e32 v62, 4.0, v53
	v_mul_f32_e32 v57, 0x41000000, v53
	v_rndne_f32_e32 v62, v62
	v_rndne_f32_e32 v57, v57
	v_add_f32_e32 v62, 0x41000000, v62
	v_cmp_nle_f32_e64 s[4:5], 2.0, v53
	v_mul_f32_e32 v6, v6, v18
	v_mul_f32_e32 v52, 0x41000000, v5
	v_cndmask_b32_e64 v57, v62, v57, s[4:5]
	v_add_f32_e32 v62, v53, v53
	v_rndne_f32_e32 v62, v62
	v_add_f32_e32 v62, 0x41800000, v62
	v_cmp_nle_f32_e64 s[4:5], 4.0, v53
	v_rndne_f32_e32 v55, v52
	v_mul_f32_e32 v52, 4.0, v5
	v_cndmask_b32_e64 v53, v62, v57, s[4:5]
	v_min_f32_e64 v57, |v6|, s31
	v_mul_f32_e32 v65, 4.0, v57
	v_mul_f32_e32 v62, 0x41000000, v57
	v_rndne_f32_e32 v65, v65
	v_rndne_f32_e32 v62, v62
	v_add_f32_e32 v65, 0x41000000, v65
	v_cmp_nle_f32_e64 s[4:5], 2.0, v57
	v_cvt_u32_f32_e32 v53, v53
	v_rndne_f32_e32 v52, v52
	v_cndmask_b32_e64 v62, v65, v62, s[4:5]
	v_add_f32_e32 v65, v57, v57
	v_rndne_f32_e32 v65, v65
	v_add_f32_e32 v65, 0x41800000, v65
	v_cmp_nle_f32_e64 s[4:5], 4.0, v57
	v_min_u32_e32 v68, 31, v53
	v_lshrrev_b32_e32 v36, 26, v36
	v_cndmask_b32_e64 v57, v65, v62, s[4:5]
	v_min_f32_e64 v65, |v37|, s31
	v_mul_f32_e32 v53, 0x41000000, v65
	v_rndne_f32_e32 v69, v53
	v_mul_f32_e32 v53, 4.0, v65
	v_rndne_f32_e32 v53, v53
	v_pk_add_f32 v[52:53], v[52:53], s[18:19] op_sel_hi:[1,0]
	v_cmp_nle_f32_e64 s[4:5], 2.0, v5
	v_cvt_u32_f32_e32 v57, v57
	v_lshrrev_b32_e32 v6, 26, v6
	v_cndmask_b32_e64 v70, v52, v55, s[4:5]
	v_add_f32_e32 v52, v65, v65
	v_cmp_nle_f32_e64 s[4:5], 2.0, v65
	v_rndne_f32_e32 v55, v52
	v_min_u32_e32 v57, 31, v57
	v_cndmask_b32_e64 v69, v53, v69, s[4:5]
	v_pk_add_f32 v[52:53], v[54:55], s[20:21] op_sel_hi:[1,0]
	v_min_f32_e64 v55, |v9|, s31
	v_and_b32_e32 v54, 32, v36
	v_mul_f32_e32 v36, 0x41000000, v55
	v_cmp_nle_f32_e64 s[4:5], 4.0, v65
	v_rndne_f32_e32 v65, v36
	v_mul_f32_e32 v36, 4.0, v55
	v_cndmask_b32_e64 v53, v53, v69, s[4:5]
	v_cmp_nle_f32_e64 s[4:5], 4.0, v5
	v_and_or_b32 v6, v6, 32, v57
	v_lshrrev_b32_e32 v37, 26, v37
	v_rndne_f32_e32 v57, v36
	v_cndmask_b32_e64 v5, v52, v70, s[4:5]
	v_cvt_u32_f32_e32 v52, v53
	v_and_b32_e32 v53, 32, v37
	v_pk_add_f32 v[36:37], v[56:57], s[18:19] op_sel_hi:[1,0]
	v_cmp_nle_f32_e64 s[4:5], 2.0, v61
	v_cvt_u32_f32_e32 v5, v5
	v_min_u32_e32 v52, 31, v52
	v_cndmask_b32_e64 v56, v36, v59, s[4:5]
	v_add_f32_e32 v36, v55, v55
	v_cmp_nle_f32_e64 s[4:5], 2.0, v55
	v_rndne_f32_e32 v59, v36
	v_or_b32_e32 v69, v52, v53
	v_cndmask_b32_e64 v57, v37, v65, s[4:5]
	v_pk_add_f32 v[36:37], v[58:59], s[20:21] op_sel_hi:[1,0]
	v_cmp_nle_f32_e64 s[4:5], 4.0, v55
	v_lshrrev_b32_e32 v8, 26, v8
	v_min_f32_e64 v53, |v35|, s31
	v_cndmask_b32_e64 v37, v37, v57, s[4:5]
	v_cvt_u32_f32_e32 v37, v37
	v_min_u32_e32 v5, 31, v5
	v_and_b32_e32 v52, 32, v8
	v_mul_f32_e32 v8, 0x41000000, v53
	v_or_b32_e32 v70, v5, v54
	v_rndne_f32_e32 v54, v8
	v_mul_f32_e32 v8, 4.0, v53
	v_cmp_nle_f32_e64 s[4:5], 4.0, v61
	v_lshrrev_b32_e32 v9, 26, v9
	v_rndne_f32_e32 v61, v8
	v_cndmask_b32_e64 v36, v36, v56, s[4:5]
	v_min_u32_e32 v5, 31, v37
	v_and_b32_e32 v37, 32, v9
	v_pk_add_f32 v[8:9], v[60:61], s[18:19] op_sel_hi:[1,0]
	v_cmp_nle_f32_e64 s[4:5], 2.0, v64
	v_add_f32_e32 v62, v64, v64
	v_rndne_f32_e32 v62, v62
	v_cndmask_b32_e64 v55, v8, v63, s[4:5]
	v_add_f32_e32 v8, v53, v53
	v_cmp_nle_f32_e64 s[4:5], 2.0, v53
	v_rndne_f32_e32 v63, v8
	v_or_b32_e32 v71, v5, v37
	v_cndmask_b32_e64 v54, v9, v54, s[4:5]
	v_pk_add_f32 v[8:9], v[62:63], s[20:21] op_sel_hi:[1,0]
	v_cmp_nle_f32_e64 s[4:5], 4.0, v53
	v_lshrrev_b32_e32 v34, 26, v34
	v_and_b32_e32 v34, 32, v34
	v_cndmask_b32_e64 v9, v9, v54, s[4:5]
	v_cmp_nle_f32_e64 s[4:5], 4.0, v64
	v_cvt_u32_f32_e32 v9, v9
	v_cvt_u32_f32_e32 v36, v36
	v_cndmask_b32_e64 v8, v8, v55, s[4:5]
	v_cvt_u32_f32_e32 v8, v8
	v_min_u32_e32 v5, 31, v9
	v_lshrrev_b32_e32 v9, 26, v35
	v_and_b32_e32 v9, 32, v9
	v_min_u32_e32 v8, 31, v8
	v_or_b32_sdwa v73, v5, v9 dst_sel:BYTE_3 dst_unused:UNUSED_PAD src0_sel:DWORD src1_sel:DWORD
	v_or_b32_e32 v74, v8, v34
	v_mov_b32_e32 v8, v19
	v_mov_b32_e32 v9, v16
	v_pk_mul_f32 v[8:9], v[8:9], v[18:19] op_sel_hi:[1,0]
	v_mov_b32_e32 v16, v20
	v_min_f32_e64 v19, |v8|, s31
	v_mul_f32_e32 v5, 0x41000000, v19
	v_rndne_f32_e32 v37, v5
	v_mul_f32_e32 v5, 4.0, v19
	v_pk_mul_f32 v[16:17], v[16:17], v[18:19] op_sel_hi:[1,0]
	v_min_u32_e32 v36, 31, v36
	v_rndne_f32_e32 v34, v5
	v_add_f32_e32 v5, v19, v19
	v_min_f32_e64 v57, |v16|, s31
	v_or_b32_e32 v72, v36, v52
	v_rndne_f32_e32 v36, v5
	v_mul_f32_e32 v5, 0x41000000, v57
	v_mov_b32_e32 v54, v21
	v_mov_b32_e32 v55, v10
	v_rndne_f32_e32 v53, v5
	v_mul_f32_e32 v5, 4.0, v57
	v_pk_mul_f32 v[54:55], v[54:55], v[18:19] op_sel_hi:[1,0]
	v_rndne_f32_e32 v20, v5
	v_add_f32_e32 v5, v57, v57
	v_min_f32_e64 v61, |v54|, s31
	v_rndne_f32_e32 v52, v5
	v_mul_f32_e32 v5, 0x41000000, v61
	v_rndne_f32_e32 v65, v5
	v_mul_f32_e32 v5, 4.0, v61
	v_rndne_f32_e32 v10, v5
	v_add_f32_e32 v5, v61, v61
	v_rndne_f32_e32 v56, v5
	v_mov_b32_e32 v58, v11
	v_mov_b32_e32 v59, v12
	v_mov_b32_e32 v5, v14
	v_pk_mov_b32 v[58:59], v[4:5], v[58:59] op_sel:[1,0]
	v_mov_b32_e32 v62, v15
	v_pk_mul_f32 v[58:59], v[58:59], v[18:19] op_sel_hi:[1,0]
	v_mov_b32_e32 v63, v12
	v_min_f32_e64 v5, |v58|, s31
	v_mul_f32_e32 v11, 0x41000000, v5
	v_rndne_f32_e32 v75, v11
	v_mul_f32_e32 v11, 4.0, v5
	v_pk_mul_f32 v[62:63], v[62:63], v[18:19] op_sel_hi:[1,0]
	v_rndne_f32_e32 v14, v11
	v_add_f32_e32 v11, v5, v5
	v_min_f32_e64 v12, |v62|, s31
	v_rndne_f32_e32 v60, v11
	v_mul_f32_e32 v11, 0x41000000, v12
	v_rndne_f32_e32 v76, v11
	v_mul_f32_e32 v11, 4.0, v12
	v_rndne_f32_e32 v64, v11
	v_min_f32_e64 v11, |v9|, s31
	v_mul_f32_e32 v21, 4.0, v11
	v_rndne_f32_e32 v35, v21
	v_pk_add_f32 v[34:35], v[34:35], s[18:19] op_sel_hi:[1,0]
	v_cmp_nle_f32_e64 s[4:5], 2.0, v19
	v_mul_f32_e32 v15, 0x41000000, v11
	v_rndne_f32_e32 v15, v15
	v_cndmask_b32_e64 v21, v34, v37, s[4:5]
	v_add_f32_e32 v34, v11, v11
	v_cmp_nle_f32_e64 s[4:5], 2.0, v11
	v_rndne_f32_e32 v37, v34
	v_lshrrev_b32_e32 v8, 26, v8
	v_cndmask_b32_e64 v15, v35, v15, s[4:5]
	v_pk_add_f32 v[34:35], v[36:37], s[20:21] op_sel_hi:[1,0]
	v_cmp_nle_f32_e64 s[4:5], 4.0, v11
	v_lshrrev_b32_e32 v9, 26, v9
	v_mul_f32_e32 v13, v13, v18
	v_cndmask_b32_e64 v11, v35, v15, s[4:5]
	v_cmp_nle_f32_e64 s[4:5], 4.0, v19
	v_cvt_u32_f32_e32 v11, v11
	v_min_f32_e64 v35, |v17|, s31
	v_cndmask_b32_e64 v15, v34, v21, s[4:5]
	v_cvt_u32_f32_e32 v15, v15
	v_add_f32_e32 v19, v12, v12
	v_rndne_f32_e32 v34, v19
	v_min_u32_e32 v19, 31, v11
	v_min_u32_e32 v36, 31, v15
	v_and_b32_e32 v15, 32, v8
	v_mul_f32_e32 v8, 0x41000000, v35
	v_rndne_f32_e32 v37, v8
	v_mul_f32_e32 v8, 4.0, v35
	v_rndne_f32_e32 v21, v8
	v_and_b32_e32 v11, 32, v9
	v_pk_add_f32 v[8:9], v[20:21], s[18:19] op_sel_hi:[1,0]
	v_cmp_nle_f32_e64 s[4:5], 2.0, v57
	v_mul_f32_e32 v2, 0x41000000, v44
	v_rndne_f32_e32 v23, v2
	v_cndmask_b32_e64 v20, v8, v53, s[4:5]
	v_add_f32_e32 v8, v35, v35
	v_cmp_nle_f32_e64 s[4:5], 2.0, v35
	v_rndne_f32_e32 v53, v8
	v_mul_f32_e32 v2, 4.0, v44
	v_cndmask_b32_e64 v21, v9, v37, s[4:5]
	v_pk_add_f32 v[8:9], v[52:53], s[20:21] op_sel_hi:[1,0]
	v_cmp_nle_f32_e64 s[4:5], 4.0, v35
	v_min_f32_e64 v37, |v55|, s31
	v_rndne_f32_e32 v2, v2
	v_cndmask_b32_e64 v9, v9, v21, s[4:5]
	v_cmp_nle_f32_e64 s[4:5], 4.0, v57
	v_cvt_u32_f32_e32 v9, v9
	v_or_b32_e32 v21, v36, v15
	v_cndmask_b32_e64 v8, v8, v20, s[4:5]
	v_cvt_u32_f32_e32 v8, v8
	v_min_u32_e32 v15, 31, v9
	v_lshrrev_b32_e32 v9, 26, v16
	v_or_b32_e32 v20, v19, v11
	v_min_u32_e32 v35, 31, v8
	v_lshrrev_b32_e32 v8, 26, v17
	v_and_b32_e32 v16, 32, v8
	v_mul_f32_e32 v8, 0x41000000, v37
	v_rndne_f32_e32 v52, v8
	v_mul_f32_e32 v8, 4.0, v37
	v_rndne_f32_e32 v11, v8
	v_and_b32_e32 v17, 32, v9
	v_pk_add_f32 v[8:9], v[10:11], s[18:19] op_sel_hi:[1,0]
	v_cmp_nle_f32_e64 s[4:5], 2.0, v61
	s_nop 1
	v_cndmask_b32_e64 v10, v8, v65, s[4:5]
	v_add_f32_e32 v8, v37, v37
	v_cmp_nle_f32_e64 s[4:5], 2.0, v37
	v_rndne_f32_e32 v57, v8
	s_nop 0
	v_cndmask_b32_e64 v11, v9, v52, s[4:5]
	v_pk_add_f32 v[8:9], v[56:57], s[20:21] op_sel_hi:[1,0]
	v_cmp_nle_f32_e64 s[4:5], 4.0, v37
	v_min_f32_e64 v52, |v59|, s31
	s_nop 0
	v_cndmask_b32_e64 v9, v9, v11, s[4:5]
	v_cmp_nle_f32_e64 s[4:5], 4.0, v61
	v_cvt_u32_f32_e32 v9, v9
	v_or_b32_e32 v11, v35, v17
	v_cndmask_b32_e64 v8, v8, v10, s[4:5]
	v_cvt_u32_f32_e32 v8, v8
	v_or_b32_e32 v10, v15, v16
	v_min_u32_e32 v16, 31, v9
	v_lshrrev_b32_e32 v9, 26, v54
	v_min_u32_e32 v17, 31, v8
	v_lshrrev_b32_e32 v8, 26, v55
	v_and_b32_e32 v35, 32, v8
	v_mul_f32_e32 v8, 0x41000000, v52
	v_rndne_f32_e32 v53, v8
	v_mul_f32_e32 v8, 4.0, v52
	v_rndne_f32_e32 v15, v8
	v_and_b32_e32 v37, 32, v9
	v_pk_add_f32 v[8:9], v[14:15], s[18:19] op_sel_hi:[1,0]
	v_cmp_nle_f32_e64 s[4:5], 2.0, v5
	v_lshlrev_b32_e32 v10, 2, v10
	v_lshlrev_b32_e32 v11, 4, v11
	v_cndmask_b32_e64 v14, v8, v75, s[4:5]
	v_add_f32_e32 v8, v52, v52
	v_cmp_nle_f32_e64 s[4:5], 2.0, v52
	v_rndne_f32_e32 v61, v8
	s_nop 0
	v_cndmask_b32_e64 v15, v9, v53, s[4:5]
	v_pk_add_f32 v[8:9], v[60:61], s[20:21] op_sel_hi:[1,0]
	v_cmp_nle_f32_e64 s[4:5], 4.0, v52
	v_min_f32_e64 v52, |v63|, s31
	s_nop 0
	v_cndmask_b32_e64 v9, v9, v15, s[4:5]
	v_cmp_nle_f32_e64 s[4:5], 4.0, v5
	v_or_b32_e32 v15, v17, v37
	s_nop 0
	v_cndmask_b32_e64 v5, v8, v14, s[4:5]
	v_cvt_u32_f32_e32 v8, v9
	v_or_b32_e32 v14, v16, v35
	v_cvt_u32_f32_e32 v5, v5
	v_lshrrev_b32_e32 v9, 26, v58
	v_min_u32_e32 v16, 31, v8
	v_lshrrev_b32_e32 v8, 26, v59
	v_and_b32_e32 v17, 32, v8
	v_mul_f32_e32 v8, 0x41000000, v52
	v_rndne_f32_e32 v35, v8
	v_mul_f32_e32 v8, 4.0, v52
	v_rndne_f32_e32 v65, v8
	v_and_b32_e32 v37, 32, v9
	v_pk_add_f32 v[8:9], v[64:65], s[18:19] op_sel_hi:[1,0]
	v_cmp_nle_f32_e64 s[4:5], 2.0, v12
	v_min_u32_e32 v5, 31, v5
	s_nop 0
	v_cndmask_b32_e64 v53, v8, v76, s[4:5]
	v_cmp_nle_f32_e64 s[4:5], 2.0, v52
	v_add_f32_e32 v8, v52, v52
	s_nop 0
	v_cndmask_b32_e64 v54, v9, v35, s[4:5]
	v_rndne_f32_e32 v35, v8
	v_pk_add_f32 v[8:9], v[34:35], s[20:21] op_sel_hi:[1,0]
	v_cmp_nle_f32_e64 s[4:5], 4.0, v52
	v_min_f32_e64 v34, |v13|, s31
	v_mul_f32_e32 v35, 0x41000000, v34
	v_cndmask_b32_e64 v9, v9, v54, s[4:5]
	v_cmp_nle_f32_e64 s[4:5], 4.0, v12
	v_or_b32_e32 v12, v16, v17
	v_or_b32_sdwa v16, v5, v37 dst_sel:WORD_1 dst_unused:UNUSED_PAD src0_sel:DWORD src1_sel:DWORD
	v_mul_f32_e32 v37, 4.0, v34
	v_rndne_f32_e32 v37, v37
	v_cndmask_b32_e64 v8, v8, v53, s[4:5]
	v_rndne_f32_e32 v35, v35
	v_add_f32_e32 v37, 0x41000000, v37
	v_cmp_nle_f32_e64 s[4:5], 2.0, v34
	v_cvt_u32_f32_e32 v9, v9
	v_cvt_u32_f32_e32 v8, v8
	v_cndmask_b32_e64 v35, v37, v35, s[4:5]
	v_add_f32_e32 v37, v34, v34
	v_rndne_f32_e32 v37, v37
	v_add_f32_e32 v37, 0x41800000, v37
	v_cmp_nle_f32_e64 s[4:5], 4.0, v34
	v_min_u32_e32 v5, 31, v9
	v_lshrrev_b32_e32 v9, 26, v63
	v_cndmask_b32_e64 v34, v37, v35, s[4:5]
	v_cvt_u32_f32_e32 v34, v34
	v_and_b32_e32 v9, 32, v9
	v_lshrrev_b32_e32 v17, 26, v62
	v_or_b32_e32 v9, v5, v9
	v_mov_b32_e32 v5, v7
	v_min_u32_e32 v8, 31, v8
	v_and_b32_e32 v17, 32, v17
	v_pk_mul_f32 v[4:5], v[4:5], v[18:19] op_sel_hi:[1,0]
	v_or_b32_e32 v8, v8, v17
	v_min_u32_e32 v17, 31, v34
	v_lshlrev_b32_e32 v34, 4, v3
	v_and_b32_e32 v3, 0x80000000, v25
	v_min_f32_e64 v7, |v4|, s31
	v_lshl_or_b32 v25, v68, 26, v3
	v_mul_f32_e32 v3, 0x41000000, v7
	v_rndne_f32_e32 v18, v3
	v_mul_f32_e32 v3, 4.0, v7
	v_rndne_f32_e32 v3, v3
	v_pk_add_f32 v[2:3], v[2:3], s[18:19] op_sel_hi:[1,0]
	v_cmp_nle_f32_e64 s[4:5], 2.0, v44
	v_lshlrev_b32_e32 v37, 10, v49
	v_lshrrev_b32_e32 v4, 26, v4
	v_cndmask_b32_e64 v52, v2, v23, s[4:5]
	v_cmp_nle_f32_e64 s[4:5], 2.0, v7
	v_add_f32_e32 v2, v7, v7
	v_rndne_f32_e32 v23, v2
	v_cndmask_b32_e64 v18, v3, v18, s[4:5]
	v_cmp_nle_f32_e64 s[4:5], 4.0, v7
	v_min_f32_e64 v7, |v5|, s31
	v_pk_add_f32 v[2:3], v[22:23], s[20:21] op_sel_hi:[1,0]
	v_mul_f32_e32 v22, 4.0, v7
	v_cndmask_b32_e64 v3, v3, v18, s[4:5]
	v_cmp_nle_f32_e64 s[4:5], 4.0, v44
	v_mul_f32_e32 v18, 0x41000000, v7
	v_rndne_f32_e32 v22, v22
	v_cndmask_b32_e64 v2, v2, v52, s[4:5]
	v_rndne_f32_e32 v18, v18
	v_add_f32_e32 v22, 0x41000000, v22
	v_cmp_nle_f32_e64 s[4:5], 2.0, v7
	v_cvt_u32_f32_e32 v2, v2
	v_cvt_u32_f32_e32 v3, v3
	v_cndmask_b32_e64 v18, v22, v18, s[4:5]
	v_add_f32_e32 v22, v7, v7
	v_rndne_f32_e32 v22, v22
	v_add_f32_e32 v22, 0x41800000, v22
	v_cmp_nle_f32_e64 s[4:5], 4.0, v7
	v_min_u32_e32 v2, 31, v2
	v_lshrrev_b32_e32 v5, 26, v5
	v_cndmask_b32_e64 v7, v22, v18, s[4:5]
	v_cvt_u32_f32_e32 v7, v7
	v_and_or_b32 v18, v45, 32, v2
	v_and_b32_e32 v5, 32, v5
	v_lshlrev_b32_e32 v35, 6, v46
	v_min_u32_e32 v7, 31, v7
	v_or_b32_e32 v5, v7, v5
	v_lshrrev_b32_e32 v7, 2, v18
	v_or_b32_e32 v7, v34, v7
	v_min_u32_e32 v3, 31, v3
	v_and_b32_e32 v4, 32, v4
	v_or_b32_e32 v7, v7, v37
	v_lshlrev_b32_e32 v46, 12, v50
	v_lshlrev_b32_e32 v50, 22, v66
	v_or_b32_e32 v4, v3, v4
	v_or_b32_e32 v18, v35, v43
	v_or_b32_e32 v7, v7, v47
	v_lshlrev_b32_e32 v49, 18, v51
	v_lshlrev_b32_e32 v51, 2, v67
	v_or_b32_e32 v18, v18, v46
	v_or_b32_e32 v7, v7, v50
	v_lshlrev_b32_e32 v3, 28, v3
	v_lshrrev_b32_e32 v4, 4, v4
	v_or_b32_e32 v18, v18, v49
	v_or_b32_e32 v3, v7, v3
	v_or_b32_e32 v4, v4, v51
	v_lshlrev_b32_e32 v7, 8, v70
	v_or_b32_e32 v18, v18, v48
	v_lshlrev_b32_e32 v2, 30, v2
	v_or_b32_e32 v4, v4, v7
	v_lshlrev_b32_e32 v7, 14, v72
	v_or_b32_e32 v2, v18, v2
	v_lshlrev_b32_e32 v5, 6, v5
	v_or_b32_e32 v4, v4, v7
	v_lshrrev_b32_e32 v7, 4, v20
	v_lshrrev_b32_e32 v18, 2, v21
	v_or_b32_e32 v5, v5, v6
	v_lshlrev_b32_e32 v6, 12, v69
	v_or_b32_e32 v7, v7, v10
	v_or_b32_e32 v10, v18, v11
	v_lshlrev_b32_e32 v11, 8, v14
	v_or_b32_e32 v5, v5, v6
	v_lshlrev_b32_e32 v6, 18, v71
	v_lshlrev_b32_e32 v14, 10, v15
	v_or_b32_e32 v7, v7, v11
	v_lshlrev_b32_e32 v11, 14, v12
	v_or_b32_e32 v5, v5, v6
	v_lshlrev_b32_e32 v6, 20, v74
	v_or_b32_e32 v10, v10, v14
	v_or_b32_e32 v7, v7, v11
	v_lshlrev_b32_e32 v9, 20, v9
	v_or_b32_e32 v5, v5, v73
	v_or_b32_e32 v4, v4, v6
	v_lshlrev_b32_e32 v6, 30, v36
	v_or_b32_e32 v10, v10, v16
	v_lshlrev_b32_e32 v8, 22, v8
	v_or_b32_e32 v7, v7, v9
	v_and_b32_e32 v9, 0x80000000, v13
	v_or_b32_e32 v5, v5, v6
	v_or_b32_e32 v4, v4, v25
	v_lshlrev_b32_e32 v6, 28, v19
	v_or_b32_e32 v8, v10, v8
	v_lshl_or_b32 v9, v17, 26, v9
	v_or_b32_e32 v7, v7, v9
	v_or_b32_e32 v6, v8, v6
	global_store_dwordx4 v[32:33], v[2:5], off
	global_store_dwordx2 v[32:33], v[6:7], off offset:16
	s_and_saveexec_b64 s[4:5], s[0:1]
	s_cbranch_execz .LBB0_37
	v_mul_f32_e32 v4, 0x3e088889, v24
	v_lshl_add_u64 v[2:3], v[30:31], 2, s[52:53]
	v_cndmask_b32_e32 v4, 1.0, v4, vcc
	global_store_dword v[2:3], v4, off
	s_branch .LBB0_37
.LBB0_40:
	s_or_b64 exec, exec, s[14:15]
	v_mov_b32_e32 v2, v205
	v_mov_b32_e32 v1, v205
	s_add_u32 s54, s26, 0x1410000
	v_ashrrev_i32_e32 v1, 6, v1
	v_add_u32_e32 v1, s21, v1
	s_movk_i32 s0, 0x2000
	s_addc_u32 s55, s27, 0
	v_cmp_gt_i32_e32 vcc, s0, v1
	s_and_saveexec_b64 s[14:15], vcc
	s_cbranch_execz .LBB0_45
	v_and_b32_e32 v5, 31, v2
	v_bfe_u32 v4, v2, 5, 1
	v_lshlrev_b32_e32 v2, 4, v5
	v_mov_b32_e32 v3, 0
	v_mbcnt_hi_u32_b32 v6, -1, v207
	v_lshl_add_u64 v[26:27], s[10:11], 0, v[2:3]
	v_and_b32_e32 v2, 64, v6
	v_add_u32_e32 v7, 64, v2
	v_and_b32_e32 v2, 7, v5
	v_mul_u32_u24_e32 v2, 24, v2
	v_lshrrev_b32_e32 v3, 3, v5
	v_mul_u32_u24_e32 v3, 0x300000, v3
	v_add_u32_e32 v2, v2, v3
	v_mov_b32_e32 v3, 0
	v_lshl_add_u64 v[2:3], s[26:27], 0, v[2:3]
	s_mov_b64 s[0:1], 0x3800000
	v_lshl_add_u64 v[28:29], v[2:3], 0, s[0:1]
	v_xor_b32_e32 v2, 16, v6
	v_cmp_lt_i32_e32 vcc, v2, v7
	v_cmp_eq_u32_e64 s[0:1], 0, v5
	s_lshl_b32 s28, s19, 2
	v_cndmask_b32_e32 v2, v6, v2, vcc
	v_lshlrev_b32_e32 v38, 2, v2
	v_xor_b32_e32 v2, 8, v6
	v_cmp_lt_i32_e32 vcc, v2, v7
	v_lshl_or_b32 v30, v1, 1, v4
	s_lshl_b32 s29, s3, 4
	v_cndmask_b32_e32 v2, v6, v2, vcc
	v_lshlrev_b32_e32 v39, 2, v2
	v_xor_b32_e32 v2, 4, v6
	v_cmp_lt_i32_e32 vcc, v2, v7
	s_mov_b64 s[16:17], 0
	s_movk_i32 s30, 0xc0
	v_cndmask_b32_e32 v2, v6, v2, vcc
	v_lshlrev_b32_e32 v40, 2, v2
	v_xor_b32_e32 v2, 2, v6
	v_cmp_lt_i32_e32 vcc, v2, v7
	s_mov_b32 s31, 0x40f00000
	s_mov_b32 s18, 0x41000000
	v_cndmask_b32_e32 v2, v6, v2, vcc
	v_lshlrev_b32_e32 v41, 2, v2
	v_xor_b32_e32 v2, 1, v6
	v_cmp_lt_i32_e32 vcc, v2, v7
	s_mov_b32 s20, 0x41800000
	s_movk_i32 s34, 0x1fff
	v_cndmask_b32_e32 v2, v6, v2, vcc
	v_lshlrev_b32_e32 v42, 2, v2
	s_branch .LBB0_43

.LBB0_43:
	v_ashrrev_i32_e32 v31, 31, v30
	v_lshlrev_b64 v[2:3], 12, v[30:31]
	v_lshl_add_u64 v[10:11], v[26:27], 0, v[2:3]
	global_load_dwordx4 v[2:5], v[10:11], off offset:1024
	global_load_dwordx4 v[22:25], v[10:11], off offset:1536
	global_load_dwordx4 v[6:9], v[10:11], off offset:2048
	global_load_dwordx4 v[44:47], v[10:11], off
	global_load_dwordx4 v[48:51], v[10:11], off offset:512
	global_load_dwordx4 v[18:21], v[10:11], off offset:2560
	global_load_dwordx4 v[14:17], v[10:11], off offset:3072
	s_nop 0
	global_load_dwordx4 v[10:13], v[10:11], off offset:3584
	s_waitcnt vmcnt(7)
	v_max_f32_e64 v32, |v5|, |v5|
	v_max_f32_e64 v33, |v4|, |v4|
	s_waitcnt vmcnt(6)
	v_max_f32_e64 v34, |v25|, |v25|
	v_max_f32_e64 v35, |v24|, |v24|
	s_waitcnt vmcnt(5)
	v_max_f32_e64 v36, |v7|, |v7|
	v_max_f32_e64 v37, |v6|, |v6|
	s_waitcnt vmcnt(4)
	v_max_f32_e64 v43, |v45|, |v45|
	v_max_f32_e64 v52, |v44|, |v44|
	v_max_f32_e64 v53, |v47|, |v47|
	v_max_f32_e64 v54, |v46|, |v46|
	s_waitcnt vmcnt(3)
	v_max_f32_e64 v55, |v49|, |v49|
	v_max_f32_e64 v56, |v48|, |v48|
	v_max_f32_e64 v57, |v51|, |v51|
	v_max_f32_e64 v58, |v50|, |v50|
	v_max_f32_e32 v32, v33, v32
	v_max_f32_e32 v33, v35, v34
	v_max_f32_e32 v34, v37, v36
	v_max_f32_e32 v35, v52, v43
	v_max_f32_e32 v36, v54, v53
	v_max_f32_e64 v59, |v3|, |v3|
	v_max_f32_e64 v60, |v2|, |v2|
	v_max_f32_e32 v37, v56, v55
	v_max_f32_e32 v43, v58, v57
	v_max3_f32 v35, v35, 0, v36
	v_max_f32_e64 v61, |v23|, |v23|
	v_max_f32_e64 v62, |v22|, |v22|
	v_max_f32_e32 v52, v60, v59
	v_max3_f32 v35, v35, v37, v43
	v_max_f32_e64 v63, |v9|, |v9|
	v_max_f32_e64 v64, |v8|, |v8|
	v_max_f32_e32 v53, v62, v61
	v_max3_f32 v32, v35, v52, v32
	s_waitcnt vmcnt(2)
	v_max_f32_e64 v65, |v19|, |v19|
	v_max_f32_e64 v66, |v18|, |v18|
	v_max_f32_e64 v67, |v21|, |v21|
	v_max_f32_e64 v68, |v20|, |v20|
	v_max_f32_e32 v54, v64, v63
	v_max3_f32 v32, v32, v53, v33
	s_waitcnt vmcnt(1)
	v_max_f32_e64 v69, |v15|, |v15|
	v_max_f32_e64 v70, |v14|, |v14|
	v_max_f32_e64 v71, |v17|, |v17|
	v_max_f32_e64 v72, |v16|, |v16|
	v_max_f32_e32 v55, v66, v65
	v_max_f32_e32 v56, v68, v67
	v_max3_f32 v32, v32, v34, v54
	s_waitcnt vmcnt(0)
	v_max_f32_e64 v73, |v11|, |v11|
	v_max_f32_e64 v74, |v10|, |v10|
	v_max_f32_e64 v75, |v13|, |v13|
	v_max_f32_e64 v76, |v12|, |v12|
	v_max_f32_e32 v57, v70, v69
	v_max_f32_e32 v58, v72, v71
	v_max3_f32 v32, v32, v55, v56
	v_max_f32_e32 v59, v74, v73
	v_max_f32_e32 v60, v76, v75
	v_max3_f32 v32, v32, v57, v58
	v_max3_f32 v32, v32, v59, v60
	ds_bpermute_b32 v33, v38, v32
	v_mov_b32_e32 v36, v22
	v_mov_b32_e32 v37, v8
	v_mov_b32_e32 v8, v23
	v_mov_b32_e32 v52, v45
	s_waitcnt lgkmcnt(0)
	v_max_f32_e32 v33, v33, v33
	v_max_f32_e32 v32, v32, v33
	ds_bpermute_b32 v33, v39, v32
	v_mov_b32_e32 v53, v50
	v_mov_b32_e32 v50, v46
	v_mov_b32_e32 v46, v47
	v_mov_b32_e32 v47, v2
	s_waitcnt lgkmcnt(0)
	v_max_f32_e32 v33, v33, v33
	v_max_f32_e32 v34, v32, v33
	ds_bpermute_b32 v35, v40, v34
	v_mov_b32_e32 v2, v48
	v_mad_i64_i32 v[32:33], s[4:5], v30, s30, v[28:29]
	s_waitcnt lgkmcnt(0)
	v_max_f32_e32 v35, v35, v35
	v_max_f32_e32 v34, v34, v35
	ds_bpermute_b32 v35, v41, v34
	s_waitcnt lgkmcnt(0)
	v_max_f32_e32 v35, v35, v35
	v_max_f32_e32 v35, v34, v35
	ds_bpermute_b32 v43, v42, v35
	v_mov_b32_e32 v34, v24
	s_waitcnt lgkmcnt(0)
	v_max_f32_e32 v22, v43, v43
	v_max_f32_e32 v24, v35, v22
	v_div_scale_f32 v22, s[4:5], v24, v24, s31
	v_rcp_f32_e32 v23, v22
	v_mov_b32_e32 v35, v18
	v_div_scale_f32 v18, vcc, s31, v24, s31
	v_fma_f32 v43, -v22, v23, 1.0
	v_fmac_f32_e32 v23, v43, v23
	v_mul_f32_e32 v43, v18, v23
	v_fma_f32 v45, -v22, v43, v18
	v_fmac_f32_e32 v43, v45, v23
	v_fma_f32 v18, -v22, v43, v18
	v_div_fmas_f32 v18, v18, v23, v43
	v_div_fixup_f32 v18, v18, v24, s31
	v_cmp_lt_f32_e32 vcc, 0, v24
	s_nop 1
	v_cndmask_b32_e32 v18, 1.0, v18, vcc
	v_mul_f32_e32 v22, v44, v18
	v_pk_mul_f32 v[56:57], v[2:3], v[18:19] op_sel_hi:[1,0]
	v_min_f32_e64 v2, |v22|, s31
	v_mul_f32_e32 v43, 4.0, v2
	v_mul_f32_e32 v23, 0x41000000, v2
	v_add_f32_e32 v44, v2, v2
	v_rndne_f32_e32 v43, v43
	v_rndne_f32_e32 v23, v23
	v_rndne_f32_e32 v44, v44
	v_add_f32_e32 v43, 0x41000000, v43
	v_cmp_nle_f32_e64 s[4:5], 2.0, v2
	v_add_f32_e32 v44, 0x41800000, v44
	v_pk_mul_f32 v[54:55], v[46:47], v[18:19] op_sel_hi:[1,0]
	v_cndmask_b32_e64 v23, v43, v23, s[4:5]
	v_cmp_nle_f32_e64 s[4:5], 4.0, v2
	v_pk_mul_f32 v[52:53], v[52:53], v[18:19] op_sel_hi:[1,0]
	v_min_f32_e64 v67, |v54|, s31
	v_cndmask_b32_e64 v2, v44, v23, s[4:5]
	v_cvt_u32_f32_e32 v2, v2
	v_lshrrev_b32_e32 v3, 26, v22
	v_min_f32_e64 v22, |v52|, s31
	v_mul_f32_e32 v61, 0x41000000, v67
	v_add_f32_e32 v47, v22, v22
	v_rndne_f32_e32 v69, v61
	v_min_f32_e64 v61, |v53|, s31
	v_rndne_f32_e32 v48, v47
	v_min_u32_e32 v2, 31, v2
	v_mul_f32_e32 v47, 0x41000000, v61
	v_mul_f32_e32 v46, 4.0, v22
	v_and_or_b32 v43, v3, 32, v2
	v_mul_f32_e32 v3, v49, v18
	v_rndne_f32_e32 v49, v47
	v_mul_f32_e32 v47, 4.0, v61
	v_mul_f32_e32 v45, 0x41000000, v22
	v_rndne_f32_e32 v46, v46
	v_rndne_f32_e32 v47, v47
	v_rndne_f32_e32 v45, v45
	v_pk_add_f32 v[46:47], v[46:47], s[18:19] op_sel_hi:[1,0]
	v_cmp_nle_f32_e64 s[4:5], 2.0, v22
	v_pk_mul_f32 v[50:51], v[50:51], v[18:19] op_sel_hi:[1,0]
	v_min_f32_e64 v44, |v3|, s31
	v_cndmask_b32_e64 v45, v46, v45, s[4:5]
	v_cmp_nle_f32_e64 s[4:5], 2.0, v61
	v_add_f32_e32 v46, v61, v61
	v_min_f32_e64 v63, |v50|, s31
	v_cndmask_b32_e64 v72, v47, v49, s[4:5]
	v_rndne_f32_e32 v49, v46
	v_pk_add_f32 v[46:47], v[48:49], s[20:21] op_sel_hi:[1,0]
	v_cmp_nle_f32_e64 s[4:5], 4.0, v61
	v_mul_f32_e32 v58, 0x41000000, v63
	v_mul_f32_e32 v59, 4.0, v63
	v_cndmask_b32_e64 v47, v47, v72, s[4:5]
	v_cmp_nle_f32_e64 s[4:5], 4.0, v22
	v_rndne_f32_e32 v65, v58
	v_rndne_f32_e32 v58, v59
	v_cndmask_b32_e64 v22, v46, v45, s[4:5]
	v_cvt_u32_f32_e32 v46, v47
	v_cvt_u32_f32_e32 v47, v22
	v_lshrrev_b32_e32 v45, 26, v3
	v_add_f32_e32 v59, v44, v44
	v_min_u32_e32 v3, 31, v46
	v_lshrrev_b32_e32 v46, 26, v53
	v_min_f32_e64 v53, |v51|, s31
	v_and_b32_e32 v49, 32, v46
	v_mul_f32_e32 v46, 0x41000000, v53
	v_rndne_f32_e32 v61, v46
	v_mul_f32_e32 v46, 4.0, v53
	v_rndne_f32_e32 v22, v59
	v_min_u32_e32 v48, 31, v47
	v_lshrrev_b32_e32 v47, 26, v52
	v_rndne_f32_e32 v59, v46
	v_and_b32_e32 v52, 32, v47
	v_pk_add_f32 v[46:47], v[58:59], s[18:19] op_sel_hi:[1,0]
	v_cmp_nle_f32_e64 s[4:5], 2.0, v63
	v_add_f32_e32 v60, v63, v63
	v_rndne_f32_e32 v60, v60
	v_cndmask_b32_e64 v58, v46, v65, s[4:5]
	v_cmp_nle_f32_e64 s[4:5], 2.0, v53
	v_add_f32_e32 v46, v53, v53
	v_or_b32_e32 v3, v3, v49
	v_cndmask_b32_e64 v59, v47, v61, s[4:5]
	v_rndne_f32_e32 v61, v46
	v_pk_add_f32 v[46:47], v[60:61], s[20:21] op_sel_hi:[1,0]
	v_cmp_nle_f32_e64 s[4:5], 4.0, v53
	v_lshrrev_b32_e32 v49, 26, v50
	v_mul_f32_e32 v62, 4.0, v67
	v_cndmask_b32_e64 v47, v47, v59, s[4:5]
	v_cmp_nle_f32_e64 s[4:5], 4.0, v63
	v_rndne_f32_e32 v62, v62
	v_cvt_u32_f32_e32 v47, v47
	v_cndmask_b32_e64 v46, v46, v58, s[4:5]
	v_cvt_u32_f32_e32 v53, v46
	v_or_b32_e32 v46, v48, v52
	v_lshrrev_b32_e32 v48, 26, v51
	v_and_b32_e32 v50, 32, v48
	v_min_u32_e32 v52, 31, v53
	v_min_f32_e64 v53, |v55|, s31
	v_mul_f32_e32 v48, 0x41000000, v53
	v_rndne_f32_e32 v58, v48
	v_mul_f32_e32 v48, 4.0, v53
	v_rndne_f32_e32 v63, v48
	v_and_b32_e32 v51, 32, v49
	v_pk_add_f32 v[48:49], v[62:63], s[18:19] op_sel_hi:[1,0]
	v_cmp_nle_f32_e64 s[4:5], 2.0, v67
	v_add_f32_e32 v64, v67, v67
	v_rndne_f32_e32 v64, v64
	v_cndmask_b32_e64 v59, v48, v69, s[4:5]
	v_add_f32_e32 v48, v53, v53
	v_cmp_nle_f32_e64 s[4:5], 2.0, v53
	v_rndne_f32_e32 v65, v48
	v_min_u32_e32 v47, 31, v47
	v_cndmask_b32_e64 v58, v49, v58, s[4:5]
	v_pk_add_f32 v[48:49], v[64:65], s[20:21] op_sel_hi:[1,0]
	v_cmp_nle_f32_e64 s[4:5], 4.0, v53
	v_min_f32_e64 v70, |v56|, s31
	v_mul_f32_e32 v2, 0x41000000, v70
	v_cndmask_b32_e64 v49, v49, v58, s[4:5]
	v_cvt_u32_f32_e32 v53, v49
	v_or_b32_e32 v49, v47, v50
	v_or_b32_e32 v50, v52, v51
	v_lshrrev_b32_e32 v51, 26, v55
	v_lshrrev_b32_e32 v52, 26, v54
	v_min_f32_e64 v55, |v57|, s31
	v_and_b32_e32 v54, 32, v52
	v_mul_f32_e32 v52, 0x41000000, v55
	v_rndne_f32_e32 v71, v2
	v_mul_f32_e32 v2, 4.0, v70
	v_rndne_f32_e32 v58, v52
	v_mul_f32_e32 v52, 4.0, v55
	v_rndne_f32_e32 v66, v2
	v_cmp_nle_f32_e64 s[4:5], 4.0, v67
	v_rndne_f32_e32 v67, v52
	v_min_u32_e32 v47, 31, v53
	v_cndmask_b32_e64 v48, v48, v59, s[4:5]
	v_pk_add_f32 v[52:53], v[66:67], s[18:19] op_sel_hi:[1,0]
	v_cmp_nle_f32_e64 s[4:5], 2.0, v70
	v_add_f32_e32 v2, v70, v70
	v_rndne_f32_e32 v68, v2
	v_cndmask_b32_e64 v59, v52, v71, s[4:5]
	v_add_f32_e32 v52, v55, v55
	v_cmp_nle_f32_e64 s[4:5], 2.0, v55
	v_rndne_f32_e32 v69, v52
	v_cvt_u32_f32_e32 v48, v48
	v_cndmask_b32_e64 v58, v53, v58, s[4:5]
	v_pk_add_f32 v[52:53], v[68:69], s[20:21] op_sel_hi:[1,0]
	v_cmp_nle_f32_e64 s[4:5], 4.0, v55
	v_mul_f32_e32 v5, v5, v18
	v_min_u32_e32 v48, 31, v48
	v_cndmask_b32_e64 v53, v53, v58, s[4:5]
	v_cvt_u32_f32_e32 v53, v53
	v_and_b32_e32 v51, 32, v51
	v_min_f32_e64 v55, |v5|, s31
	v_or_b32_sdwa v47, v47, v51 dst_sel:WORD_1 dst_unused:UNUSED_PAD src0_sel:DWORD src1_sel:DWORD
	v_or_b32_e32 v51, v48, v54
	v_min_u32_e32 v48, 31, v53
	v_lshrrev_b32_e32 v53, 26, v57
	v_mul_f32_e32 v57, 4.0, v55
	v_cmp_nle_f32_e64 s[4:5], 4.0, v70
	v_lshrrev_b32_e32 v54, 26, v56
	v_mul_f32_e32 v56, 0x41000000, v55
	v_rndne_f32_e32 v57, v57
	v_cndmask_b32_e64 v52, v52, v59, s[4:5]
	v_rndne_f32_e32 v56, v56
	v_add_f32_e32 v57, 0x41000000, v57
	v_cmp_nle_f32_e64 s[4:5], 2.0, v55
	v_cvt_u32_f32_e32 v52, v52
	v_and_b32_e32 v53, 32, v53
	v_cndmask_b32_e64 v56, v57, v56, s[4:5]
	v_add_f32_e32 v57, v55, v55
	v_rndne_f32_e32 v57, v57
	v_add_f32_e32 v57, 0x41800000, v57
	v_cmp_nle_f32_e64 s[4:5], 4.0, v55
	v_min_u32_e32 v52, 31, v52
	v_and_b32_e32 v54, 32, v54
	v_cndmask_b32_e64 v55, v57, v56, s[4:5]
	v_cvt_u32_f32_e32 v55, v55
	v_or_b32_e32 v66, v48, v53
	v_or_b32_sdwa v48, v52, v54 dst_sel:BYTE_3 dst_unused:UNUSED_PAD src0_sel:DWORD src1_sel:DWORD
	v_lshrrev_b32_e32 v5, 26, v5
	v_min_u32_e32 v52, 31, v55
	v_pk_mul_f32 v[36:37], v[36:37], v[18:19] op_sel_hi:[1,0]
	v_and_or_b32 v67, v5, 32, v52
	v_min_f32_e64 v5, |v36|, s31
	v_pk_mul_f32 v[8:9], v[8:9], v[18:19] op_sel_hi:[1,0]
	v_add_f32_e32 v53, v5, v5
	v_min_f32_e64 v61, |v8|, s31
	v_rndne_f32_e32 v54, v53
	v_mul_f32_e32 v53, 0x41000000, v61
	v_rndne_f32_e32 v59, v53
	v_mul_f32_e32 v53, 4.0, v61
	v_pk_mul_f32 v[34:35], v[34:35], v[18:19] op_sel_hi:[1,0]
	v_rndne_f32_e32 v56, v53
	v_add_f32_e32 v53, v61, v61
	v_min_f32_e64 v64, |v34|, s31
	v_rndne_f32_e32 v58, v53
	v_mul_f32_e32 v53, 0x41000000, v64
	v_rndne_f32_e32 v63, v53
	v_mul_f32_e32 v53, 4.0, v64
	v_mul_f32_e32 v25, v25, v18
	v_rndne_f32_e32 v60, v53
	v_min_f32_e64 v53, |v25|, s31
	v_mul_f32_e32 v62, 4.0, v53
	v_mul_f32_e32 v57, 0x41000000, v53
	v_rndne_f32_e32 v62, v62
	v_rndne_f32_e32 v57, v57
	v_add_f32_e32 v62, 0x41000000, v62
	v_cmp_nle_f32_e64 s[4:5], 2.0, v53
	v_mul_f32_e32 v6, v6, v18
	v_mul_f32_e32 v52, 0x41000000, v5
	v_cndmask_b32_e64 v57, v62, v57, s[4:5]
	v_add_f32_e32 v62, v53, v53
	v_rndne_f32_e32 v62, v62
	v_add_f32_e32 v62, 0x41800000, v62
	v_cmp_nle_f32_e64 s[4:5], 4.0, v53
	v_rndne_f32_e32 v55, v52
	v_mul_f32_e32 v52, 4.0, v5
	v_cndmask_b32_e64 v53, v62, v57, s[4:5]
	v_min_f32_e64 v57, |v6|, s31
	v_mul_f32_e32 v65, 4.0, v57
	v_mul_f32_e32 v62, 0x41000000, v57
	v_rndne_f32_e32 v65, v65
	v_rndne_f32_e32 v62, v62
	v_add_f32_e32 v65, 0x41000000, v65
	v_cmp_nle_f32_e64 s[4:5], 2.0, v57
	v_cvt_u32_f32_e32 v53, v53
	v_rndne_f32_e32 v52, v52
	v_cndmask_b32_e64 v62, v65, v62, s[4:5]
	v_add_f32_e32 v65, v57, v57
	v_rndne_f32_e32 v65, v65
	v_add_f32_e32 v65, 0x41800000, v65
	v_cmp_nle_f32_e64 s[4:5], 4.0, v57
	v_min_u32_e32 v68, 31, v53
	v_lshrrev_b32_e32 v36, 26, v36
	v_cndmask_b32_e64 v57, v65, v62, s[4:5]
	v_min_f32_e64 v65, |v37|, s31
	v_mul_f32_e32 v53, 0x41000000, v65
	v_rndne_f32_e32 v69, v53
	v_mul_f32_e32 v53, 4.0, v65
	v_rndne_f32_e32 v53, v53
	v_pk_add_f32 v[52:53], v[52:53], s[18:19] op_sel_hi:[1,0]
	v_cmp_nle_f32_e64 s[4:5], 2.0, v5
	v_cvt_u32_f32_e32 v57, v57
	v_lshrrev_b32_e32 v6, 26, v6
	v_cndmask_b32_e64 v70, v52, v55, s[4:5]
	v_add_f32_e32 v52, v65, v65
	v_cmp_nle_f32_e64 s[4:5], 2.0, v65
	v_rndne_f32_e32 v55, v52
	v_min_u32_e32 v57, 31, v57
	v_cndmask_b32_e64 v69, v53, v69, s[4:5]
	v_pk_add_f32 v[52:53], v[54:55], s[20:21] op_sel_hi:[1,0]
	v_min_f32_e64 v55, |v9|, s31
	v_and_b32_e32 v54, 32, v36
	v_mul_f32_e32 v36, 0x41000000, v55
	v_cmp_nle_f32_e64 s[4:5], 4.0, v65
	v_rndne_f32_e32 v65, v36
	v_mul_f32_e32 v36, 4.0, v55
	v_cndmask_b32_e64 v53, v53, v69, s[4:5]
	v_cmp_nle_f32_e64 s[4:5], 4.0, v5
	v_and_or_b32 v6, v6, 32, v57
	v_lshrrev_b32_e32 v37, 26, v37
	v_rndne_f32_e32 v57, v36
	v_cndmask_b32_e64 v5, v52, v70, s[4:5]
	v_cvt_u32_f32_e32 v52, v53
	v_and_b32_e32 v53, 32, v37
	v_pk_add_f32 v[36:37], v[56:57], s[18:19] op_sel_hi:[1,0]
	v_cmp_nle_f32_e64 s[4:5], 2.0, v61
	v_cvt_u32_f32_e32 v5, v5
	v_min_u32_e32 v52, 31, v52
	v_cndmask_b32_e64 v56, v36, v59, s[4:5]
	v_add_f32_e32 v36, v55, v55
	v_cmp_nle_f32_e64 s[4:5], 2.0, v55
	v_rndne_f32_e32 v59, v36
	v_or_b32_e32 v69, v52, v53
	v_cndmask_b32_e64 v57, v37, v65, s[4:5]
	v_pk_add_f32 v[36:37], v[58:59], s[20:21] op_sel_hi:[1,0]
	v_cmp_nle_f32_e64 s[4:5], 4.0, v55
	v_lshrrev_b32_e32 v8, 26, v8
	v_min_f32_e64 v53, |v35|, s31
	v_cndmask_b32_e64 v37, v37, v57, s[4:5]
	v_cvt_u32_f32_e32 v37, v37
	v_min_u32_e32 v5, 31, v5
	v_and_b32_e32 v52, 32, v8
	v_mul_f32_e32 v8, 0x41000000, v53
	v_or_b32_e32 v70, v5, v54
	v_rndne_f32_e32 v54, v8
	v_mul_f32_e32 v8, 4.0, v53
	v_cmp_nle_f32_e64 s[4:5], 4.0, v61
	v_lshrrev_b32_e32 v9, 26, v9
	v_rndne_f32_e32 v61, v8
	v_cndmask_b32_e64 v36, v36, v56, s[4:5]
	v_min_u32_e32 v5, 31, v37
	v_and_b32_e32 v37, 32, v9
	v_pk_add_f32 v[8:9], v[60:61], s[18:19] op_sel_hi:[1,0]
	v_cmp_nle_f32_e64 s[4:5], 2.0, v64
	v_add_f32_e32 v62, v64, v64
	v_rndne_f32_e32 v62, v62
	v_cndmask_b32_e64 v55, v8, v63, s[4:5]
	v_add_f32_e32 v8, v53, v53
	v_cmp_nle_f32_e64 s[4:5], 2.0, v53
	v_rndne_f32_e32 v63, v8
	v_or_b32_e32 v71, v5, v37
	v_cndmask_b32_e64 v54, v9, v54, s[4:5]
	v_pk_add_f32 v[8:9], v[62:63], s[20:21] op_sel_hi:[1,0]
	v_cmp_nle_f32_e64 s[4:5], 4.0, v53
	v_lshrrev_b32_e32 v34, 26, v34
	v_and_b32_e32 v34, 32, v34
	v_cndmask_b32_e64 v9, v9, v54, s[4:5]
	v_cmp_nle_f32_e64 s[4:5], 4.0, v64
	v_cvt_u32_f32_e32 v9, v9
	v_cvt_u32_f32_e32 v36, v36
	v_cndmask_b32_e64 v8, v8, v55, s[4:5]
	v_cvt_u32_f32_e32 v8, v8
	v_min_u32_e32 v5, 31, v9
	v_lshrrev_b32_e32 v9, 26, v35
	v_and_b32_e32 v9, 32, v9
	v_min_u32_e32 v8, 31, v8
	v_or_b32_sdwa v73, v5, v9 dst_sel:BYTE_3 dst_unused:UNUSED_PAD src0_sel:DWORD src1_sel:DWORD
	v_or_b32_e32 v74, v8, v34
	v_mov_b32_e32 v8, v19
	v_mov_b32_e32 v9, v16
	v_pk_mul_f32 v[8:9], v[8:9], v[18:19] op_sel_hi:[1,0]
	v_mov_b32_e32 v16, v20
	v_min_f32_e64 v19, |v8|, s31
	v_mul_f32_e32 v5, 0x41000000, v19
	v_rndne_f32_e32 v37, v5
	v_mul_f32_e32 v5, 4.0, v19
	v_pk_mul_f32 v[16:17], v[16:17], v[18:19] op_sel_hi:[1,0]
	v_min_u32_e32 v36, 31, v36
	v_rndne_f32_e32 v34, v5
	v_add_f32_e32 v5, v19, v19
	v_min_f32_e64 v57, |v16|, s31
	v_or_b32_e32 v72, v36, v52
	v_rndne_f32_e32 v36, v5
	v_mul_f32_e32 v5, 0x41000000, v57
	v_mov_b32_e32 v54, v21
	v_mov_b32_e32 v55, v10
	v_rndne_f32_e32 v53, v5
	v_mul_f32_e32 v5, 4.0, v57
	v_pk_mul_f32 v[54:55], v[54:55], v[18:19] op_sel_hi:[1,0]
	v_rndne_f32_e32 v20, v5
	v_add_f32_e32 v5, v57, v57
	v_min_f32_e64 v61, |v54|, s31
	v_rndne_f32_e32 v52, v5
	v_mul_f32_e32 v5, 0x41000000, v61
	v_rndne_f32_e32 v65, v5
	v_mul_f32_e32 v5, 4.0, v61
	v_rndne_f32_e32 v10, v5
	v_add_f32_e32 v5, v61, v61
	v_rndne_f32_e32 v56, v5
	v_mov_b32_e32 v58, v11
	v_mov_b32_e32 v59, v12
	v_mov_b32_e32 v5, v14
	v_pk_mov_b32 v[58:59], v[4:5], v[58:59] op_sel:[1,0]
	v_mov_b32_e32 v62, v15
	v_pk_mul_f32 v[58:59], v[58:59], v[18:19] op_sel_hi:[1,0]
	v_mov_b32_e32 v63, v12
	v_min_f32_e64 v5, |v58|, s31
	v_mul_f32_e32 v11, 0x41000000, v5
	v_rndne_f32_e32 v75, v11
	v_mul_f32_e32 v11, 4.0, v5
	v_pk_mul_f32 v[62:63], v[62:63], v[18:19] op_sel_hi:[1,0]
	v_rndne_f32_e32 v14, v11
	v_add_f32_e32 v11, v5, v5
	v_min_f32_e64 v12, |v62|, s31
	v_rndne_f32_e32 v60, v11
	v_mul_f32_e32 v11, 0x41000000, v12
	v_rndne_f32_e32 v76, v11
	v_mul_f32_e32 v11, 4.0, v12
	v_rndne_f32_e32 v64, v11
	v_min_f32_e64 v11, |v9|, s31
	v_mul_f32_e32 v21, 4.0, v11
	v_rndne_f32_e32 v35, v21
	v_pk_add_f32 v[34:35], v[34:35], s[18:19] op_sel_hi:[1,0]
	v_cmp_nle_f32_e64 s[4:5], 2.0, v19
	v_mul_f32_e32 v15, 0x41000000, v11
	v_rndne_f32_e32 v15, v15
	v_cndmask_b32_e64 v21, v34, v37, s[4:5]
	v_add_f32_e32 v34, v11, v11
	v_cmp_nle_f32_e64 s[4:5], 2.0, v11
	v_rndne_f32_e32 v37, v34
	v_lshrrev_b32_e32 v8, 26, v8
	v_cndmask_b32_e64 v15, v35, v15, s[4:5]
	v_pk_add_f32 v[34:35], v[36:37], s[20:21] op_sel_hi:[1,0]
	v_cmp_nle_f32_e64 s[4:5], 4.0, v11
	v_lshrrev_b32_e32 v9, 26, v9
	v_mul_f32_e32 v13, v13, v18
	v_cndmask_b32_e64 v11, v35, v15, s[4:5]
	v_cmp_nle_f32_e64 s[4:5], 4.0, v19
	v_cvt_u32_f32_e32 v11, v11
	v_min_f32_e64 v35, |v17|, s31
	v_cndmask_b32_e64 v15, v34, v21, s[4:5]
	v_cvt_u32_f32_e32 v15, v15
	v_add_f32_e32 v19, v12, v12
	v_rndne_f32_e32 v34, v19
	v_min_u32_e32 v19, 31, v11
	v_min_u32_e32 v36, 31, v15
	v_and_b32_e32 v15, 32, v8
	v_mul_f32_e32 v8, 0x41000000, v35
	v_rndne_f32_e32 v37, v8
	v_mul_f32_e32 v8, 4.0, v35
	v_rndne_f32_e32 v21, v8
	v_and_b32_e32 v11, 32, v9
	v_pk_add_f32 v[8:9], v[20:21], s[18:19] op_sel_hi:[1,0]
	v_cmp_nle_f32_e64 s[4:5], 2.0, v57
	v_mul_f32_e32 v2, 0x41000000, v44
	v_rndne_f32_e32 v23, v2
	v_cndmask_b32_e64 v20, v8, v53, s[4:5]
	v_add_f32_e32 v8, v35, v35
	v_cmp_nle_f32_e64 s[4:5], 2.0, v35
	v_rndne_f32_e32 v53, v8
	v_mul_f32_e32 v2, 4.0, v44
	v_cndmask_b32_e64 v21, v9, v37, s[4:5]
	v_pk_add_f32 v[8:9], v[52:53], s[20:21] op_sel_hi:[1,0]
	v_cmp_nle_f32_e64 s[4:5], 4.0, v35
	v_min_f32_e64 v37, |v55|, s31
	v_rndne_f32_e32 v2, v2
	v_cndmask_b32_e64 v9, v9, v21, s[4:5]
	v_cmp_nle_f32_e64 s[4:5], 4.0, v57
	v_cvt_u32_f32_e32 v9, v9
	v_or_b32_e32 v21, v36, v15
	v_cndmask_b32_e64 v8, v8, v20, s[4:5]
	v_cvt_u32_f32_e32 v8, v8
	v_min_u32_e32 v15, 31, v9
	v_lshrrev_b32_e32 v9, 26, v16
	v_or_b32_e32 v20, v19, v11
	v_min_u32_e32 v35, 31, v8
	v_lshrrev_b32_e32 v8, 26, v17
	v_and_b32_e32 v16, 32, v8
	v_mul_f32_e32 v8, 0x41000000, v37
	v_rndne_f32_e32 v52, v8
	v_mul_f32_e32 v8, 4.0, v37
	v_rndne_f32_e32 v11, v8
	v_and_b32_e32 v17, 32, v9
	v_pk_add_f32 v[8:9], v[10:11], s[18:19] op_sel_hi:[1,0]
	v_cmp_nle_f32_e64 s[4:5], 2.0, v61
	s_nop 1
	v_cndmask_b32_e64 v10, v8, v65, s[4:5]
	v_add_f32_e32 v8, v37, v37
	v_cmp_nle_f32_e64 s[4:5], 2.0, v37
	v_rndne_f32_e32 v57, v8
	s_nop 0
	v_cndmask_b32_e64 v11, v9, v52, s[4:5]
	v_pk_add_f32 v[8:9], v[56:57], s[20:21] op_sel_hi:[1,0]
	v_cmp_nle_f32_e64 s[4:5], 4.0, v37
	v_min_f32_e64 v52, |v59|, s31
	s_nop 0
	v_cndmask_b32_e64 v9, v9, v11, s[4:5]
	v_cmp_nle_f32_e64 s[4:5], 4.0, v61
	v_cvt_u32_f32_e32 v9, v9
	v_or_b32_e32 v11, v35, v17
	v_cndmask_b32_e64 v8, v8, v10, s[4:5]
	v_cvt_u32_f32_e32 v8, v8
	v_or_b32_e32 v10, v15, v16
	v_min_u32_e32 v16, 31, v9
	v_lshrrev_b32_e32 v9, 26, v54
	v_min_u32_e32 v17, 31, v8
	v_lshrrev_b32_e32 v8, 26, v55
	v_and_b32_e32 v35, 32, v8
	v_mul_f32_e32 v8, 0x41000000, v52
	v_rndne_f32_e32 v53, v8
	v_mul_f32_e32 v8, 4.0, v52
	v_rndne_f32_e32 v15, v8
	v_and_b32_e32 v37, 32, v9
	v_pk_add_f32 v[8:9], v[14:15], s[18:19] op_sel_hi:[1,0]
	v_cmp_nle_f32_e64 s[4:5], 2.0, v5
	v_lshlrev_b32_e32 v10, 2, v10
	v_lshlrev_b32_e32 v11, 4, v11
	v_cndmask_b32_e64 v14, v8, v75, s[4:5]
	v_add_f32_e32 v8, v52, v52
	v_cmp_nle_f32_e64 s[4:5], 2.0, v52
	v_rndne_f32_e32 v61, v8
	s_nop 0
	v_cndmask_b32_e64 v15, v9, v53, s[4:5]
	v_pk_add_f32 v[8:9], v[60:61], s[20:21] op_sel_hi:[1,0]
	v_cmp_nle_f32_e64 s[4:5], 4.0, v52
	v_min_f32_e64 v52, |v63|, s31
	s_nop 0
	v_cndmask_b32_e64 v9, v9, v15, s[4:5]
	v_cmp_nle_f32_e64 s[4:5], 4.0, v5
	v_or_b32_e32 v15, v17, v37
	s_nop 0
	v_cndmask_b32_e64 v5, v8, v14, s[4:5]
	v_cvt_u32_f32_e32 v8, v9
	v_or_b32_e32 v14, v16, v35
	v_cvt_u32_f32_e32 v5, v5
	v_lshrrev_b32_e32 v9, 26, v58
	v_min_u32_e32 v16, 31, v8
	v_lshrrev_b32_e32 v8, 26, v59
	v_and_b32_e32 v17, 32, v8
	v_mul_f32_e32 v8, 0x41000000, v52
	v_rndne_f32_e32 v35, v8
	v_mul_f32_e32 v8, 4.0, v52
	v_rndne_f32_e32 v65, v8
	v_and_b32_e32 v37, 32, v9
	v_pk_add_f32 v[8:9], v[64:65], s[18:19] op_sel_hi:[1,0]
	v_cmp_nle_f32_e64 s[4:5], 2.0, v12
	v_min_u32_e32 v5, 31, v5
	s_nop 0
	v_cndmask_b32_e64 v53, v8, v76, s[4:5]
	v_cmp_nle_f32_e64 s[4:5], 2.0, v52
	v_add_f32_e32 v8, v52, v52
	s_nop 0
	v_cndmask_b32_e64 v54, v9, v35, s[4:5]
	v_rndne_f32_e32 v35, v8
	v_pk_add_f32 v[8:9], v[34:35], s[20:21] op_sel_hi:[1,0]
	v_cmp_nle_f32_e64 s[4:5], 4.0, v52
	v_min_f32_e64 v34, |v13|, s31
	v_mul_f32_e32 v35, 0x41000000, v34
	v_cndmask_b32_e64 v9, v9, v54, s[4:5]
	v_cmp_nle_f32_e64 s[4:5], 4.0, v12
	v_or_b32_e32 v12, v16, v17
	v_or_b32_sdwa v16, v5, v37 dst_sel:WORD_1 dst_unused:UNUSED_PAD src0_sel:DWORD src1_sel:DWORD
	v_mul_f32_e32 v37, 4.0, v34
	v_rndne_f32_e32 v37, v37
	v_cndmask_b32_e64 v8, v8, v53, s[4:5]
	v_rndne_f32_e32 v35, v35
	v_add_f32_e32 v37, 0x41000000, v37
	v_cmp_nle_f32_e64 s[4:5], 2.0, v34
	v_cvt_u32_f32_e32 v9, v9
	v_cvt_u32_f32_e32 v8, v8
	v_cndmask_b32_e64 v35, v37, v35, s[4:5]
	v_add_f32_e32 v37, v34, v34
	v_rndne_f32_e32 v37, v37
	v_add_f32_e32 v37, 0x41800000, v37
	v_cmp_nle_f32_e64 s[4:5], 4.0, v34
	v_min_u32_e32 v5, 31, v9
	v_lshrrev_b32_e32 v9, 26, v63
	v_cndmask_b32_e64 v34, v37, v35, s[4:5]
	v_cvt_u32_f32_e32 v34, v34
	v_and_b32_e32 v9, 32, v9
	v_lshrrev_b32_e32 v17, 26, v62
	v_or_b32_e32 v9, v5, v9
	v_mov_b32_e32 v5, v7
	v_min_u32_e32 v8, 31, v8
	v_and_b32_e32 v17, 32, v17
	v_pk_mul_f32 v[4:5], v[4:5], v[18:19] op_sel_hi:[1,0]
	v_or_b32_e32 v8, v8, v17
	v_min_u32_e32 v17, 31, v34
	v_lshlrev_b32_e32 v34, 4, v3
	v_and_b32_e32 v3, 0x80000000, v25
	v_min_f32_e64 v7, |v4|, s31
	v_lshl_or_b32 v25, v68, 26, v3
	v_mul_f32_e32 v3, 0x41000000, v7
	v_rndne_f32_e32 v18, v3
	v_mul_f32_e32 v3, 4.0, v7
	v_rndne_f32_e32 v3, v3
	v_pk_add_f32 v[2:3], v[2:3], s[18:19] op_sel_hi:[1,0]
	v_cmp_nle_f32_e64 s[4:5], 2.0, v44
	v_lshlrev_b32_e32 v37, 10, v49
	v_lshrrev_b32_e32 v4, 26, v4
	v_cndmask_b32_e64 v52, v2, v23, s[4:5]
	v_cmp_nle_f32_e64 s[4:5], 2.0, v7
	v_add_f32_e32 v2, v7, v7
	v_rndne_f32_e32 v23, v2
	v_cndmask_b32_e64 v18, v3, v18, s[4:5]
	v_cmp_nle_f32_e64 s[4:5], 4.0, v7
	v_min_f32_e64 v7, |v5|, s31
	v_pk_add_f32 v[2:3], v[22:23], s[20:21] op_sel_hi:[1,0]
	v_mul_f32_e32 v22, 4.0, v7
	v_cndmask_b32_e64 v3, v3, v18, s[4:5]
	v_cmp_nle_f32_e64 s[4:5], 4.0, v44
	v_mul_f32_e32 v18, 0x41000000, v7
	v_rndne_f32_e32 v22, v22
	v_cndmask_b32_e64 v2, v2, v52, s[4:5]
	v_rndne_f32_e32 v18, v18
	v_add_f32_e32 v22, 0x41000000, v22
	v_cmp_nle_f32_e64 s[4:5], 2.0, v7
	v_cvt_u32_f32_e32 v2, v2
	v_cvt_u32_f32_e32 v3, v3
	v_cndmask_b32_e64 v18, v22, v18, s[4:5]
	v_add_f32_e32 v22, v7, v7
	v_rndne_f32_e32 v22, v22
	v_add_f32_e32 v22, 0x41800000, v22
	v_cmp_nle_f32_e64 s[4:5], 4.0, v7
	v_min_u32_e32 v2, 31, v2
	v_lshrrev_b32_e32 v5, 26, v5
	v_cndmask_b32_e64 v7, v22, v18, s[4:5]
	v_cvt_u32_f32_e32 v7, v7
	v_and_or_b32 v18, v45, 32, v2
	v_and_b32_e32 v5, 32, v5
	v_lshlrev_b32_e32 v35, 6, v46
	v_min_u32_e32 v7, 31, v7
	v_or_b32_e32 v5, v7, v5
	v_lshrrev_b32_e32 v7, 2, v18
	v_or_b32_e32 v7, v34, v7
	v_min_u32_e32 v3, 31, v3
	v_and_b32_e32 v4, 32, v4
	v_or_b32_e32 v7, v7, v37
	v_lshlrev_b32_e32 v46, 12, v50
	v_lshlrev_b32_e32 v50, 22, v66
	v_or_b32_e32 v4, v3, v4
	v_or_b32_e32 v18, v35, v43
	v_or_b32_e32 v7, v7, v47
	v_lshlrev_b32_e32 v49, 18, v51
	v_lshlrev_b32_e32 v51, 2, v67
	v_or_b32_e32 v18, v18, v46
	v_or_b32_e32 v7, v7, v50
	v_lshlrev_b32_e32 v3, 28, v3
	v_lshrrev_b32_e32 v4, 4, v4
	v_or_b32_e32 v18, v18, v49
	v_or_b32_e32 v3, v7, v3
	v_or_b32_e32 v4, v4, v51
	v_lshlrev_b32_e32 v7, 8, v70
	v_or_b32_e32 v18, v18, v48
	v_lshlrev_b32_e32 v2, 30, v2
	v_or_b32_e32 v4, v4, v7
	v_lshlrev_b32_e32 v7, 14, v72
	v_or_b32_e32 v2, v18, v2
	v_lshlrev_b32_e32 v5, 6, v5
	v_or_b32_e32 v4, v4, v7
	v_lshrrev_b32_e32 v7, 4, v20
	v_lshrrev_b32_e32 v18, 2, v21
	v_or_b32_e32 v5, v5, v6
	v_lshlrev_b32_e32 v6, 12, v69
	v_or_b32_e32 v7, v7, v10
	v_or_b32_e32 v10, v18, v11
	v_lshlrev_b32_e32 v11, 8, v14
	v_or_b32_e32 v5, v5, v6
	v_lshlrev_b32_e32 v6, 18, v71
	v_lshlrev_b32_e32 v14, 10, v15
	v_or_b32_e32 v7, v7, v11
	v_lshlrev_b32_e32 v11, 14, v12
	v_or_b32_e32 v5, v5, v6
	v_lshlrev_b32_e32 v6, 20, v74
	v_or_b32_e32 v10, v10, v14
	v_or_b32_e32 v7, v7, v11
	v_lshlrev_b32_e32 v9, 20, v9
	v_or_b32_e32 v5, v5, v73
	v_or_b32_e32 v4, v4, v6
	v_lshlrev_b32_e32 v6, 30, v36
	v_or_b32_e32 v10, v10, v16
	v_lshlrev_b32_e32 v8, 22, v8
	v_or_b32_e32 v7, v7, v9
	v_and_b32_e32 v9, 0x80000000, v13
	v_or_b32_e32 v5, v5, v6
	v_or_b32_e32 v4, v4, v25
	v_lshlrev_b32_e32 v6, 28, v19
	v_or_b32_e32 v8, v10, v8
	v_lshl_or_b32 v9, v17, 26, v9
	v_or_b32_e32 v7, v7, v9
	v_or_b32_e32 v6, v8, v6
	global_store_dwordx4 v[32:33], v[2:5], off
	global_store_dwordx2 v[32:33], v[6:7], off offset:16
	s_and_saveexec_b64 s[4:5], s[0:1]
	s_cbranch_execz .LBB0_42
	v_mul_f32_e32 v4, 0x3e088889, v24
	v_lshl_add_u64 v[2:3], v[30:31], 2, s[54:55]
	v_cndmask_b32_e32 v4, 1.0, v4, vcc
	global_store_dword v[2:3], v4, off
	s_branch .LBB0_42
.LBB0_45:
	s_or_b64 exec, exec, s[14:15]
	v_mov_b32_e32 v2, v205
	v_mov_b32_e32 v1, v205
	s_add_u32 s28, s26, 0x1420000
	v_ashrrev_i32_e32 v1, 6, v1
	v_add_u32_e32 v1, s21, v1
	s_movk_i32 s0, 0x2000
	s_addc_u32 s29, s27, 0
	v_cmp_gt_i32_e32 vcc, s0, v1
	s_and_saveexec_b64 s[14:15], vcc
	s_cbranch_execz .LBB0_50
	v_and_b32_e32 v7, 31, v2
	v_bfe_u32 v6, v2, 5, 1
	v_lshlrev_b32_e32 v2, 4, v7
	v_mov_b32_e32 v3, 0
	v_lshl_add_u64 v[4:5], s[8:9], 0, v[2:3]
	s_mov_b64 s[0:1], 0x4000000
	v_lshl_add_u64 v[26:27], v[4:5], 0, s[0:1]
	v_mbcnt_hi_u32_b32 v4, -1, v207
	v_and_b32_e32 v2, 64, v4
	v_add_u32_e32 v5, 64, v2
	v_and_b32_e32 v2, 7, v7
	v_mul_u32_u24_e32 v2, 24, v2
	v_lshrrev_b32_e32 v3, 3, v7
	v_mul_u32_u24_e32 v3, 0x300000, v3
	v_add_u32_e32 v2, v2, v3
	v_mov_b32_e32 v3, 0
	v_lshl_add_u64 v[2:3], s[26:27], 0, v[2:3]
	s_mov_b64 s[0:1], 0x2800000
	v_lshl_add_u64 v[28:29], v[2:3], 0, s[0:1]
	v_xor_b32_e32 v2, 16, v4
	v_cmp_lt_i32_e32 vcc, v2, v5
	v_cmp_eq_u32_e64 s[0:1], 0, v7
	s_lshl_b32 s17, s19, 2
	v_cndmask_b32_e32 v2, v4, v2, vcc
	v_lshlrev_b32_e32 v38, 2, v2
	v_xor_b32_e32 v2, 8, v4
	v_cmp_lt_i32_e32 vcc, v2, v5
	v_lshl_or_b32 v30, v1, 1, v6
	s_lshl_b32 s20, s3, 4
	v_cndmask_b32_e32 v2, v4, v2, vcc
	v_lshlrev_b32_e32 v39, 2, v2
	v_xor_b32_e32 v2, 4, v4
	v_cmp_lt_i32_e32 vcc, v2, v5
	s_mov_b64 s[8:9], 0
	s_movk_i32 s30, 0xc0
	v_cndmask_b32_e32 v2, v4, v2, vcc
	v_lshlrev_b32_e32 v40, 2, v2
	v_xor_b32_e32 v2, 2, v4
	v_cmp_lt_i32_e32 vcc, v2, v5
	s_mov_b32 s31, 0x40f00000
	s_mov_b32 s16, 0x41000000
	v_cndmask_b32_e32 v2, v4, v2, vcc
	v_lshlrev_b32_e32 v41, 2, v2
	v_xor_b32_e32 v2, 1, v4
	v_cmp_lt_i32_e32 vcc, v2, v5
	s_mov_b32 s18, 0x41800000
	s_movk_i32 s34, 0x1fff
	v_cndmask_b32_e32 v2, v4, v2, vcc
	v_lshlrev_b32_e32 v42, 2, v2
	s_branch .LBB0_48

.LBB0_48:
	v_ashrrev_i32_e32 v31, 31, v30
	v_lshlrev_b64 v[2:3], 12, v[30:31]
	v_lshl_add_u64 v[10:11], v[26:27], 0, v[2:3]
	global_load_dwordx4 v[2:5], v[10:11], off offset:1024
	global_load_dwordx4 v[22:25], v[10:11], off offset:1536
	global_load_dwordx4 v[6:9], v[10:11], off offset:2048
	global_load_dwordx4 v[44:47], v[10:11], off
	global_load_dwordx4 v[48:51], v[10:11], off offset:512
	global_load_dwordx4 v[18:21], v[10:11], off offset:2560
	global_load_dwordx4 v[14:17], v[10:11], off offset:3072
	s_nop 0
	global_load_dwordx4 v[10:13], v[10:11], off offset:3584
	s_waitcnt vmcnt(7)
	v_max_f32_e64 v32, |v5|, |v5|
	v_max_f32_e64 v33, |v4|, |v4|
	s_waitcnt vmcnt(6)
	v_max_f32_e64 v34, |v25|, |v25|
	v_max_f32_e64 v35, |v24|, |v24|
	s_waitcnt vmcnt(5)
	v_max_f32_e64 v36, |v7|, |v7|
	v_max_f32_e64 v37, |v6|, |v6|
	s_waitcnt vmcnt(4)
	v_max_f32_e64 v43, |v45|, |v45|
	v_max_f32_e64 v52, |v44|, |v44|
	v_max_f32_e64 v53, |v47|, |v47|
	v_max_f32_e64 v54, |v46|, |v46|
	s_waitcnt vmcnt(3)
	v_max_f32_e64 v55, |v49|, |v49|
	v_max_f32_e64 v56, |v48|, |v48|
	v_max_f32_e64 v57, |v51|, |v51|
	v_max_f32_e64 v58, |v50|, |v50|
	v_max_f32_e32 v32, v33, v32
	v_max_f32_e32 v33, v35, v34
	v_max_f32_e32 v34, v37, v36
	v_max_f32_e32 v35, v52, v43
	v_max_f32_e32 v36, v54, v53
	v_max_f32_e64 v59, |v3|, |v3|
	v_max_f32_e64 v60, |v2|, |v2|
	v_max_f32_e32 v37, v56, v55
	v_max_f32_e32 v43, v58, v57
	v_max3_f32 v35, v35, 0, v36
	v_max_f32_e64 v61, |v23|, |v23|
	v_max_f32_e64 v62, |v22|, |v22|
	v_max_f32_e32 v52, v60, v59
	v_max3_f32 v35, v35, v37, v43
	v_max_f32_e64 v63, |v9|, |v9|
	v_max_f32_e64 v64, |v8|, |v8|
	v_max_f32_e32 v53, v62, v61
	v_max3_f32 v32, v35, v52, v32
	s_waitcnt vmcnt(2)
	v_max_f32_e64 v65, |v19|, |v19|
	v_max_f32_e64 v66, |v18|, |v18|
	v_max_f32_e64 v67, |v21|, |v21|
	v_max_f32_e64 v68, |v20|, |v20|
	v_max_f32_e32 v54, v64, v63
	v_max3_f32 v32, v32, v53, v33
	s_waitcnt vmcnt(1)
	v_max_f32_e64 v69, |v15|, |v15|
	v_max_f32_e64 v70, |v14|, |v14|
	v_max_f32_e64 v71, |v17|, |v17|
	v_max_f32_e64 v72, |v16|, |v16|
	v_max_f32_e32 v55, v66, v65
	v_max_f32_e32 v56, v68, v67
	v_max3_f32 v32, v32, v34, v54
	s_waitcnt vmcnt(0)
	v_max_f32_e64 v73, |v11|, |v11|
	v_max_f32_e64 v74, |v10|, |v10|
	v_max_f32_e64 v75, |v13|, |v13|
	v_max_f32_e64 v76, |v12|, |v12|
	v_max_f32_e32 v57, v70, v69
	v_max_f32_e32 v58, v72, v71
	v_max3_f32 v32, v32, v55, v56
	v_max_f32_e32 v59, v74, v73
	v_max_f32_e32 v60, v76, v75
	v_max3_f32 v32, v32, v57, v58
	v_max3_f32 v32, v32, v59, v60
	ds_bpermute_b32 v33, v38, v32
	v_mov_b32_e32 v36, v22
	v_mov_b32_e32 v37, v8
	v_mov_b32_e32 v8, v23
	v_mov_b32_e32 v52, v45
	s_waitcnt lgkmcnt(0)
	v_max_f32_e32 v33, v33, v33
	v_max_f32_e32 v32, v32, v33
	ds_bpermute_b32 v33, v39, v32
	v_mov_b32_e32 v53, v50
	v_mov_b32_e32 v50, v46
	v_mov_b32_e32 v46, v47
	v_mov_b32_e32 v47, v2
	s_waitcnt lgkmcnt(0)
	v_max_f32_e32 v33, v33, v33
	v_max_f32_e32 v34, v32, v33
	ds_bpermute_b32 v35, v40, v34
	v_mov_b32_e32 v2, v48
	v_mad_i64_i32 v[32:33], s[4:5], v30, s30, v[28:29]
	s_waitcnt lgkmcnt(0)
	v_max_f32_e32 v35, v35, v35
	v_max_f32_e32 v34, v34, v35
	ds_bpermute_b32 v35, v41, v34
	s_waitcnt lgkmcnt(0)
	v_max_f32_e32 v35, v35, v35
	v_max_f32_e32 v35, v34, v35
	ds_bpermute_b32 v43, v42, v35
	v_mov_b32_e32 v34, v24
	s_waitcnt lgkmcnt(0)
	v_max_f32_e32 v22, v43, v43
	v_max_f32_e32 v24, v35, v22
	v_div_scale_f32 v22, s[4:5], v24, v24, s31
	v_rcp_f32_e32 v23, v22
	v_mov_b32_e32 v35, v18
	v_div_scale_f32 v18, vcc, s31, v24, s31
	v_fma_f32 v43, -v22, v23, 1.0
	v_fmac_f32_e32 v23, v43, v23
	v_mul_f32_e32 v43, v18, v23
	v_fma_f32 v45, -v22, v43, v18
	v_fmac_f32_e32 v43, v45, v23
	v_fma_f32 v18, -v22, v43, v18
	v_div_fmas_f32 v18, v18, v23, v43
	v_div_fixup_f32 v18, v18, v24, s31
	v_cmp_lt_f32_e32 vcc, 0, v24
	s_nop 1
	v_cndmask_b32_e32 v18, 1.0, v18, vcc
	v_mul_f32_e32 v22, v44, v18
	v_pk_mul_f32 v[56:57], v[2:3], v[18:19] op_sel_hi:[1,0]
	v_min_f32_e64 v2, |v22|, s31
	v_mul_f32_e32 v43, 4.0, v2
	v_mul_f32_e32 v23, 0x41000000, v2
	v_add_f32_e32 v44, v2, v2
	v_rndne_f32_e32 v43, v43
	v_rndne_f32_e32 v23, v23
	v_rndne_f32_e32 v44, v44
	v_add_f32_e32 v43, 0x41000000, v43
	v_cmp_nle_f32_e64 s[4:5], 2.0, v2
	v_add_f32_e32 v44, 0x41800000, v44
	v_pk_mul_f32 v[54:55], v[46:47], v[18:19] op_sel_hi:[1,0]
	v_cndmask_b32_e64 v23, v43, v23, s[4:5]
	v_cmp_nle_f32_e64 s[4:5], 4.0, v2
	v_pk_mul_f32 v[52:53], v[52:53], v[18:19] op_sel_hi:[1,0]
	v_min_f32_e64 v67, |v54|, s31
	v_cndmask_b32_e64 v2, v44, v23, s[4:5]
	v_cvt_u32_f32_e32 v2, v2
	v_lshrrev_b32_e32 v3, 26, v22
	v_min_f32_e64 v22, |v52|, s31
	v_mul_f32_e32 v61, 0x41000000, v67
	v_add_f32_e32 v47, v22, v22
	v_rndne_f32_e32 v69, v61
	v_min_f32_e64 v61, |v53|, s31
	v_rndne_f32_e32 v48, v47
	v_min_u32_e32 v2, 31, v2
	v_mul_f32_e32 v47, 0x41000000, v61
	v_mul_f32_e32 v46, 4.0, v22
	v_and_or_b32 v43, v3, 32, v2
	v_mul_f32_e32 v3, v49, v18
	v_rndne_f32_e32 v49, v47
	v_mul_f32_e32 v47, 4.0, v61
	v_mul_f32_e32 v45, 0x41000000, v22
	v_rndne_f32_e32 v46, v46
	v_rndne_f32_e32 v47, v47
	v_rndne_f32_e32 v45, v45
	v_pk_add_f32 v[46:47], v[46:47], s[16:17] op_sel_hi:[1,0]
	v_cmp_nle_f32_e64 s[4:5], 2.0, v22
	v_pk_mul_f32 v[50:51], v[50:51], v[18:19] op_sel_hi:[1,0]
	v_min_f32_e64 v44, |v3|, s31
	v_cndmask_b32_e64 v45, v46, v45, s[4:5]
	v_cmp_nle_f32_e64 s[4:5], 2.0, v61
	v_add_f32_e32 v46, v61, v61
	v_min_f32_e64 v63, |v50|, s31
	v_cndmask_b32_e64 v72, v47, v49, s[4:5]
	v_rndne_f32_e32 v49, v46
	v_pk_add_f32 v[46:47], v[48:49], s[18:19] op_sel_hi:[1,0]
	v_cmp_nle_f32_e64 s[4:5], 4.0, v61
	v_mul_f32_e32 v58, 0x41000000, v63
	v_mul_f32_e32 v59, 4.0, v63
	v_cndmask_b32_e64 v47, v47, v72, s[4:5]
	v_cmp_nle_f32_e64 s[4:5], 4.0, v22
	v_rndne_f32_e32 v65, v58
	v_rndne_f32_e32 v58, v59
	v_cndmask_b32_e64 v22, v46, v45, s[4:5]
	v_cvt_u32_f32_e32 v46, v47
	v_cvt_u32_f32_e32 v47, v22
	v_lshrrev_b32_e32 v45, 26, v3
	v_add_f32_e32 v59, v44, v44
	v_min_u32_e32 v3, 31, v46
	v_lshrrev_b32_e32 v46, 26, v53
	v_min_f32_e64 v53, |v51|, s31
	v_and_b32_e32 v49, 32, v46
	v_mul_f32_e32 v46, 0x41000000, v53
	v_rndne_f32_e32 v61, v46
	v_mul_f32_e32 v46, 4.0, v53
	v_rndne_f32_e32 v22, v59
	v_min_u32_e32 v48, 31, v47
	v_lshrrev_b32_e32 v47, 26, v52
	v_rndne_f32_e32 v59, v46
	v_and_b32_e32 v52, 32, v47
	v_pk_add_f32 v[46:47], v[58:59], s[16:17] op_sel_hi:[1,0]
	v_cmp_nle_f32_e64 s[4:5], 2.0, v63
	v_add_f32_e32 v60, v63, v63
	v_rndne_f32_e32 v60, v60
	v_cndmask_b32_e64 v58, v46, v65, s[4:5]
	v_cmp_nle_f32_e64 s[4:5], 2.0, v53
	v_add_f32_e32 v46, v53, v53
	v_or_b32_e32 v3, v3, v49
	v_cndmask_b32_e64 v59, v47, v61, s[4:5]
	v_rndne_f32_e32 v61, v46
	v_pk_add_f32 v[46:47], v[60:61], s[18:19] op_sel_hi:[1,0]
	v_cmp_nle_f32_e64 s[4:5], 4.0, v53
	v_lshrrev_b32_e32 v49, 26, v50
	v_mul_f32_e32 v62, 4.0, v67
	v_cndmask_b32_e64 v47, v47, v59, s[4:5]
	v_cmp_nle_f32_e64 s[4:5], 4.0, v63
	v_rndne_f32_e32 v62, v62
	v_cvt_u32_f32_e32 v47, v47
	v_cndmask_b32_e64 v46, v46, v58, s[4:5]
	v_cvt_u32_f32_e32 v53, v46
	v_or_b32_e32 v46, v48, v52
	v_lshrrev_b32_e32 v48, 26, v51
	v_and_b32_e32 v50, 32, v48
	v_min_u32_e32 v52, 31, v53
	v_min_f32_e64 v53, |v55|, s31
	v_mul_f32_e32 v48, 0x41000000, v53
	v_rndne_f32_e32 v58, v48
	v_mul_f32_e32 v48, 4.0, v53
	v_rndne_f32_e32 v63, v48
	v_and_b32_e32 v51, 32, v49
	v_pk_add_f32 v[48:49], v[62:63], s[16:17] op_sel_hi:[1,0]
	v_cmp_nle_f32_e64 s[4:5], 2.0, v67
	v_add_f32_e32 v64, v67, v67
	v_rndne_f32_e32 v64, v64
	v_cndmask_b32_e64 v59, v48, v69, s[4:5]
	v_add_f32_e32 v48, v53, v53
	v_cmp_nle_f32_e64 s[4:5], 2.0, v53
	v_rndne_f32_e32 v65, v48
	v_min_u32_e32 v47, 31, v47
	v_cndmask_b32_e64 v58, v49, v58, s[4:5]
	v_pk_add_f32 v[48:49], v[64:65], s[18:19] op_sel_hi:[1,0]
	v_cmp_nle_f32_e64 s[4:5], 4.0, v53
	v_min_f32_e64 v70, |v56|, s31
	v_mul_f32_e32 v2, 0x41000000, v70
	v_cndmask_b32_e64 v49, v49, v58, s[4:5]
	v_cvt_u32_f32_e32 v53, v49
	v_or_b32_e32 v49, v47, v50
	v_or_b32_e32 v50, v52, v51
	v_lshrrev_b32_e32 v51, 26, v55
	v_lshrrev_b32_e32 v52, 26, v54
	v_min_f32_e64 v55, |v57|, s31
	v_and_b32_e32 v54, 32, v52
	v_mul_f32_e32 v52, 0x41000000, v55
	v_rndne_f32_e32 v71, v2
	v_mul_f32_e32 v2, 4.0, v70
	v_rndne_f32_e32 v58, v52
	v_mul_f32_e32 v52, 4.0, v55
	v_rndne_f32_e32 v66, v2
	v_cmp_nle_f32_e64 s[4:5], 4.0, v67
	v_rndne_f32_e32 v67, v52
	v_min_u32_e32 v47, 31, v53
	v_cndmask_b32_e64 v48, v48, v59, s[4:5]
	v_pk_add_f32 v[52:53], v[66:67], s[16:17] op_sel_hi:[1,0]
	v_cmp_nle_f32_e64 s[4:5], 2.0, v70
	v_add_f32_e32 v2, v70, v70
	v_rndne_f32_e32 v68, v2
	v_cndmask_b32_e64 v59, v52, v71, s[4:5]
	v_add_f32_e32 v52, v55, v55
	v_cmp_nle_f32_e64 s[4:5], 2.0, v55
	v_rndne_f32_e32 v69, v52
	v_cvt_u32_f32_e32 v48, v48
	v_cndmask_b32_e64 v58, v53, v58, s[4:5]
	v_pk_add_f32 v[52:53], v[68:69], s[18:19] op_sel_hi:[1,0]
	v_cmp_nle_f32_e64 s[4:5], 4.0, v55
	v_mul_f32_e32 v5, v5, v18
	v_min_u32_e32 v48, 31, v48
	v_cndmask_b32_e64 v53, v53, v58, s[4:5]
	v_cvt_u32_f32_e32 v53, v53
	v_and_b32_e32 v51, 32, v51
	v_min_f32_e64 v55, |v5|, s31
	v_or_b32_sdwa v47, v47, v51 dst_sel:WORD_1 dst_unused:UNUSED_PAD src0_sel:DWORD src1_sel:DWORD
	v_or_b32_e32 v51, v48, v54
	v_min_u32_e32 v48, 31, v53
	v_lshrrev_b32_e32 v53, 26, v57
	v_mul_f32_e32 v57, 4.0, v55
	v_cmp_nle_f32_e64 s[4:5], 4.0, v70
	v_lshrrev_b32_e32 v54, 26, v56
	v_mul_f32_e32 v56, 0x41000000, v55
	v_rndne_f32_e32 v57, v57
	v_cndmask_b32_e64 v52, v52, v59, s[4:5]
	v_rndne_f32_e32 v56, v56
	v_add_f32_e32 v57, 0x41000000, v57
	v_cmp_nle_f32_e64 s[4:5], 2.0, v55
	v_cvt_u32_f32_e32 v52, v52
	v_and_b32_e32 v53, 32, v53
	v_cndmask_b32_e64 v56, v57, v56, s[4:5]
	v_add_f32_e32 v57, v55, v55
	v_rndne_f32_e32 v57, v57
	v_add_f32_e32 v57, 0x41800000, v57
	v_cmp_nle_f32_e64 s[4:5], 4.0, v55
	v_min_u32_e32 v52, 31, v52
	v_and_b32_e32 v54, 32, v54
	v_cndmask_b32_e64 v55, v57, v56, s[4:5]
	v_cvt_u32_f32_e32 v55, v55
	v_or_b32_e32 v66, v48, v53
	v_or_b32_sdwa v48, v52, v54 dst_sel:BYTE_3 dst_unused:UNUSED_PAD src0_sel:DWORD src1_sel:DWORD
	v_lshrrev_b32_e32 v5, 26, v5
	v_min_u32_e32 v52, 31, v55
	v_pk_mul_f32 v[36:37], v[36:37], v[18:19] op_sel_hi:[1,0]
	v_and_or_b32 v67, v5, 32, v52
	v_min_f32_e64 v5, |v36|, s31
	v_pk_mul_f32 v[8:9], v[8:9], v[18:19] op_sel_hi:[1,0]
	v_add_f32_e32 v53, v5, v5
	v_min_f32_e64 v61, |v8|, s31
	v_rndne_f32_e32 v54, v53
	v_mul_f32_e32 v53, 0x41000000, v61
	v_rndne_f32_e32 v59, v53
	v_mul_f32_e32 v53, 4.0, v61
	v_pk_mul_f32 v[34:35], v[34:35], v[18:19] op_sel_hi:[1,0]
	v_rndne_f32_e32 v56, v53
	v_add_f32_e32 v53, v61, v61
	v_min_f32_e64 v64, |v34|, s31
	v_rndne_f32_e32 v58, v53
	v_mul_f32_e32 v53, 0x41000000, v64
	v_rndne_f32_e32 v63, v53
	v_mul_f32_e32 v53, 4.0, v64
	v_mul_f32_e32 v25, v25, v18
	v_rndne_f32_e32 v60, v53
	v_min_f32_e64 v53, |v25|, s31
	v_mul_f32_e32 v62, 4.0, v53
	v_mul_f32_e32 v57, 0x41000000, v53
	v_rndne_f32_e32 v62, v62
	v_rndne_f32_e32 v57, v57
	v_add_f32_e32 v62, 0x41000000, v62
	v_cmp_nle_f32_e64 s[4:5], 2.0, v53
	v_mul_f32_e32 v6, v6, v18
	v_mul_f32_e32 v52, 0x41000000, v5
	v_cndmask_b32_e64 v57, v62, v57, s[4:5]
	v_add_f32_e32 v62, v53, v53
	v_rndne_f32_e32 v62, v62
	v_add_f32_e32 v62, 0x41800000, v62
	v_cmp_nle_f32_e64 s[4:5], 4.0, v53
	v_rndne_f32_e32 v55, v52
	v_mul_f32_e32 v52, 4.0, v5
	v_cndmask_b32_e64 v53, v62, v57, s[4:5]
	v_min_f32_e64 v57, |v6|, s31
	v_mul_f32_e32 v65, 4.0, v57
	v_mul_f32_e32 v62, 0x41000000, v57
	v_rndne_f32_e32 v65, v65
	v_rndne_f32_e32 v62, v62
	v_add_f32_e32 v65, 0x41000000, v65
	v_cmp_nle_f32_e64 s[4:5], 2.0, v57
	v_cvt_u32_f32_e32 v53, v53
	v_rndne_f32_e32 v52, v52
	v_cndmask_b32_e64 v62, v65, v62, s[4:5]
	v_add_f32_e32 v65, v57, v57
	v_rndne_f32_e32 v65, v65
	v_add_f32_e32 v65, 0x41800000, v65
	v_cmp_nle_f32_e64 s[4:5], 4.0, v57
	v_min_u32_e32 v68, 31, v53
	v_lshrrev_b32_e32 v36, 26, v36
	v_cndmask_b32_e64 v57, v65, v62, s[4:5]
	v_min_f32_e64 v65, |v37|, s31
	v_mul_f32_e32 v53, 0x41000000, v65
	v_rndne_f32_e32 v69, v53
	v_mul_f32_e32 v53, 4.0, v65
	v_rndne_f32_e32 v53, v53
	v_pk_add_f32 v[52:53], v[52:53], s[16:17] op_sel_hi:[1,0]
	v_cmp_nle_f32_e64 s[4:5], 2.0, v5
	v_cvt_u32_f32_e32 v57, v57
	v_lshrrev_b32_e32 v6, 26, v6
	v_cndmask_b32_e64 v70, v52, v55, s[4:5]
	v_add_f32_e32 v52, v65, v65
	v_cmp_nle_f32_e64 s[4:5], 2.0, v65
	v_rndne_f32_e32 v55, v52
	v_min_u32_e32 v57, 31, v57
	v_cndmask_b32_e64 v69, v53, v69, s[4:5]
	v_pk_add_f32 v[52:53], v[54:55], s[18:19] op_sel_hi:[1,0]
	v_min_f32_e64 v55, |v9|, s31
	v_and_b32_e32 v54, 32, v36
	v_mul_f32_e32 v36, 0x41000000, v55
	v_cmp_nle_f32_e64 s[4:5], 4.0, v65
	v_rndne_f32_e32 v65, v36
	v_mul_f32_e32 v36, 4.0, v55
	v_cndmask_b32_e64 v53, v53, v69, s[4:5]
	v_cmp_nle_f32_e64 s[4:5], 4.0, v5
	v_and_or_b32 v6, v6, 32, v57
	v_lshrrev_b32_e32 v37, 26, v37
	v_rndne_f32_e32 v57, v36
	v_cndmask_b32_e64 v5, v52, v70, s[4:5]
	v_cvt_u32_f32_e32 v52, v53
	v_and_b32_e32 v53, 32, v37
	v_pk_add_f32 v[36:37], v[56:57], s[16:17] op_sel_hi:[1,0]
	v_cmp_nle_f32_e64 s[4:5], 2.0, v61
	v_cvt_u32_f32_e32 v5, v5
	v_min_u32_e32 v52, 31, v52
	v_cndmask_b32_e64 v56, v36, v59, s[4:5]
	v_add_f32_e32 v36, v55, v55
	v_cmp_nle_f32_e64 s[4:5], 2.0, v55
	v_rndne_f32_e32 v59, v36
	v_or_b32_e32 v69, v52, v53
	v_cndmask_b32_e64 v57, v37, v65, s[4:5]
	v_pk_add_f32 v[36:37], v[58:59], s[18:19] op_sel_hi:[1,0]
	v_cmp_nle_f32_e64 s[4:5], 4.0, v55
	v_lshrrev_b32_e32 v8, 26, v8
	v_min_f32_e64 v53, |v35|, s31
	v_cndmask_b32_e64 v37, v37, v57, s[4:5]
	v_cvt_u32_f32_e32 v37, v37
	v_min_u32_e32 v5, 31, v5
	v_and_b32_e32 v52, 32, v8
	v_mul_f32_e32 v8, 0x41000000, v53
	v_or_b32_e32 v70, v5, v54
	v_rndne_f32_e32 v54, v8
	v_mul_f32_e32 v8, 4.0, v53
	v_cmp_nle_f32_e64 s[4:5], 4.0, v61
	v_lshrrev_b32_e32 v9, 26, v9
	v_rndne_f32_e32 v61, v8
	v_cndmask_b32_e64 v36, v36, v56, s[4:5]
	v_min_u32_e32 v5, 31, v37
	v_and_b32_e32 v37, 32, v9
	v_pk_add_f32 v[8:9], v[60:61], s[16:17] op_sel_hi:[1,0]
	v_cmp_nle_f32_e64 s[4:5], 2.0, v64
	v_add_f32_e32 v62, v64, v64
	v_rndne_f32_e32 v62, v62
	v_cndmask_b32_e64 v55, v8, v63, s[4:5]
	v_add_f32_e32 v8, v53, v53
	v_cmp_nle_f32_e64 s[4:5], 2.0, v53
	v_rndne_f32_e32 v63, v8
	v_or_b32_e32 v71, v5, v37
	v_cndmask_b32_e64 v54, v9, v54, s[4:5]
	v_pk_add_f32 v[8:9], v[62:63], s[18:19] op_sel_hi:[1,0]
	v_cmp_nle_f32_e64 s[4:5], 4.0, v53
	v_lshrrev_b32_e32 v34, 26, v34
	v_and_b32_e32 v34, 32, v34
	v_cndmask_b32_e64 v9, v9, v54, s[4:5]
	v_cmp_nle_f32_e64 s[4:5], 4.0, v64
	v_cvt_u32_f32_e32 v9, v9
	v_cvt_u32_f32_e32 v36, v36
	v_cndmask_b32_e64 v8, v8, v55, s[4:5]
	v_cvt_u32_f32_e32 v8, v8
	v_min_u32_e32 v5, 31, v9
	v_lshrrev_b32_e32 v9, 26, v35
	v_and_b32_e32 v9, 32, v9
	v_min_u32_e32 v8, 31, v8
	v_or_b32_sdwa v73, v5, v9 dst_sel:BYTE_3 dst_unused:UNUSED_PAD src0_sel:DWORD src1_sel:DWORD
	v_or_b32_e32 v74, v8, v34
	v_mov_b32_e32 v8, v19
	v_mov_b32_e32 v9, v16
	v_pk_mul_f32 v[8:9], v[8:9], v[18:19] op_sel_hi:[1,0]
	v_mov_b32_e32 v16, v20
	v_min_f32_e64 v19, |v8|, s31
	v_mul_f32_e32 v5, 0x41000000, v19
	v_rndne_f32_e32 v37, v5
	v_mul_f32_e32 v5, 4.0, v19
	v_pk_mul_f32 v[16:17], v[16:17], v[18:19] op_sel_hi:[1,0]
	v_min_u32_e32 v36, 31, v36
	v_rndne_f32_e32 v34, v5
	v_add_f32_e32 v5, v19, v19
	v_min_f32_e64 v57, |v16|, s31
	v_or_b32_e32 v72, v36, v52
	v_rndne_f32_e32 v36, v5
	v_mul_f32_e32 v5, 0x41000000, v57
	v_mov_b32_e32 v54, v21
	v_mov_b32_e32 v55, v10
	v_rndne_f32_e32 v53, v5
	v_mul_f32_e32 v5, 4.0, v57
	v_pk_mul_f32 v[54:55], v[54:55], v[18:19] op_sel_hi:[1,0]
	v_rndne_f32_e32 v20, v5
	v_add_f32_e32 v5, v57, v57
	v_min_f32_e64 v61, |v54|, s31
	v_rndne_f32_e32 v52, v5
	v_mul_f32_e32 v5, 0x41000000, v61
	v_rndne_f32_e32 v65, v5
	v_mul_f32_e32 v5, 4.0, v61
	v_rndne_f32_e32 v10, v5
	v_add_f32_e32 v5, v61, v61
	v_rndne_f32_e32 v56, v5
	v_mov_b32_e32 v58, v11
	v_mov_b32_e32 v59, v12
	v_mov_b32_e32 v5, v14
	v_pk_mov_b32 v[58:59], v[4:5], v[58:59] op_sel:[1,0]
	v_mov_b32_e32 v62, v15
	v_pk_mul_f32 v[58:59], v[58:59], v[18:19] op_sel_hi:[1,0]
	v_mov_b32_e32 v63, v12
	v_min_f32_e64 v5, |v58|, s31
	v_mul_f32_e32 v11, 0x41000000, v5
	v_rndne_f32_e32 v75, v11
	v_mul_f32_e32 v11, 4.0, v5
	v_pk_mul_f32 v[62:63], v[62:63], v[18:19] op_sel_hi:[1,0]
	v_rndne_f32_e32 v14, v11
	v_add_f32_e32 v11, v5, v5
	v_min_f32_e64 v12, |v62|, s31
	v_rndne_f32_e32 v60, v11
	v_mul_f32_e32 v11, 0x41000000, v12
	v_rndne_f32_e32 v76, v11
	v_mul_f32_e32 v11, 4.0, v12
	v_rndne_f32_e32 v64, v11
	v_min_f32_e64 v11, |v9|, s31
	v_mul_f32_e32 v21, 4.0, v11
	v_rndne_f32_e32 v35, v21
	v_pk_add_f32 v[34:35], v[34:35], s[16:17] op_sel_hi:[1,0]
	v_cmp_nle_f32_e64 s[4:5], 2.0, v19
	v_mul_f32_e32 v15, 0x41000000, v11
	v_rndne_f32_e32 v15, v15
	v_cndmask_b32_e64 v21, v34, v37, s[4:5]
	v_add_f32_e32 v34, v11, v11
	v_cmp_nle_f32_e64 s[4:5], 2.0, v11
	v_rndne_f32_e32 v37, v34
	v_lshrrev_b32_e32 v8, 26, v8
	v_cndmask_b32_e64 v15, v35, v15, s[4:5]
	v_pk_add_f32 v[34:35], v[36:37], s[18:19] op_sel_hi:[1,0]
	v_cmp_nle_f32_e64 s[4:5], 4.0, v11
	v_lshrrev_b32_e32 v9, 26, v9
	v_mul_f32_e32 v13, v13, v18
	v_cndmask_b32_e64 v11, v35, v15, s[4:5]
	v_cmp_nle_f32_e64 s[4:5], 4.0, v19
	v_cvt_u32_f32_e32 v11, v11
	v_min_f32_e64 v35, |v17|, s31
	v_cndmask_b32_e64 v15, v34, v21, s[4:5]
	v_cvt_u32_f32_e32 v15, v15
	v_add_f32_e32 v19, v12, v12
	v_rndne_f32_e32 v34, v19
	v_min_u32_e32 v19, 31, v11
	v_min_u32_e32 v36, 31, v15
	v_and_b32_e32 v15, 32, v8
	v_mul_f32_e32 v8, 0x41000000, v35
	v_rndne_f32_e32 v37, v8
	v_mul_f32_e32 v8, 4.0, v35
	v_rndne_f32_e32 v21, v8
	v_and_b32_e32 v11, 32, v9
	v_pk_add_f32 v[8:9], v[20:21], s[16:17] op_sel_hi:[1,0]
	v_cmp_nle_f32_e64 s[4:5], 2.0, v57
	v_mul_f32_e32 v2, 0x41000000, v44
	v_rndne_f32_e32 v23, v2
	v_cndmask_b32_e64 v20, v8, v53, s[4:5]
	v_add_f32_e32 v8, v35, v35
	v_cmp_nle_f32_e64 s[4:5], 2.0, v35
	v_rndne_f32_e32 v53, v8
	v_mul_f32_e32 v2, 4.0, v44
	v_cndmask_b32_e64 v21, v9, v37, s[4:5]
	v_pk_add_f32 v[8:9], v[52:53], s[18:19] op_sel_hi:[1,0]
	v_cmp_nle_f32_e64 s[4:5], 4.0, v35
	v_min_f32_e64 v37, |v55|, s31
	v_rndne_f32_e32 v2, v2
	v_cndmask_b32_e64 v9, v9, v21, s[4:5]
	v_cmp_nle_f32_e64 s[4:5], 4.0, v57
	v_cvt_u32_f32_e32 v9, v9
	v_or_b32_e32 v21, v36, v15
	v_cndmask_b32_e64 v8, v8, v20, s[4:5]
	v_cvt_u32_f32_e32 v8, v8
	v_min_u32_e32 v15, 31, v9
	v_lshrrev_b32_e32 v9, 26, v16
	v_or_b32_e32 v20, v19, v11
	v_min_u32_e32 v35, 31, v8
	v_lshrrev_b32_e32 v8, 26, v17
	v_and_b32_e32 v16, 32, v8
	v_mul_f32_e32 v8, 0x41000000, v37
	v_rndne_f32_e32 v52, v8
	v_mul_f32_e32 v8, 4.0, v37
	v_rndne_f32_e32 v11, v8
	v_and_b32_e32 v17, 32, v9
	v_pk_add_f32 v[8:9], v[10:11], s[16:17] op_sel_hi:[1,0]
	v_cmp_nle_f32_e64 s[4:5], 2.0, v61
	s_nop 1
	v_cndmask_b32_e64 v10, v8, v65, s[4:5]
	v_add_f32_e32 v8, v37, v37
	v_cmp_nle_f32_e64 s[4:5], 2.0, v37
	v_rndne_f32_e32 v57, v8
	s_nop 0
	v_cndmask_b32_e64 v11, v9, v52, s[4:5]
	v_pk_add_f32 v[8:9], v[56:57], s[18:19] op_sel_hi:[1,0]
	v_cmp_nle_f32_e64 s[4:5], 4.0, v37
	v_min_f32_e64 v52, |v59|, s31
	s_nop 0
	v_cndmask_b32_e64 v9, v9, v11, s[4:5]
	v_cmp_nle_f32_e64 s[4:5], 4.0, v61
	v_cvt_u32_f32_e32 v9, v9
	v_or_b32_e32 v11, v35, v17
	v_cndmask_b32_e64 v8, v8, v10, s[4:5]
	v_cvt_u32_f32_e32 v8, v8
	v_or_b32_e32 v10, v15, v16
	v_min_u32_e32 v16, 31, v9
	v_lshrrev_b32_e32 v9, 26, v54
	v_min_u32_e32 v17, 31, v8
	v_lshrrev_b32_e32 v8, 26, v55
	v_and_b32_e32 v35, 32, v8
	v_mul_f32_e32 v8, 0x41000000, v52
	v_rndne_f32_e32 v53, v8
	v_mul_f32_e32 v8, 4.0, v52
	v_rndne_f32_e32 v15, v8
	v_and_b32_e32 v37, 32, v9
	v_pk_add_f32 v[8:9], v[14:15], s[16:17] op_sel_hi:[1,0]
	v_cmp_nle_f32_e64 s[4:5], 2.0, v5
	v_lshlrev_b32_e32 v10, 2, v10
	v_lshlrev_b32_e32 v11, 4, v11
	v_cndmask_b32_e64 v14, v8, v75, s[4:5]
	v_add_f32_e32 v8, v52, v52
	v_cmp_nle_f32_e64 s[4:5], 2.0, v52
	v_rndne_f32_e32 v61, v8
	s_nop 0
	v_cndmask_b32_e64 v15, v9, v53, s[4:5]
	v_pk_add_f32 v[8:9], v[60:61], s[18:19] op_sel_hi:[1,0]
	v_cmp_nle_f32_e64 s[4:5], 4.0, v52
	v_min_f32_e64 v52, |v63|, s31
	s_nop 0
	v_cndmask_b32_e64 v9, v9, v15, s[4:5]
	v_cmp_nle_f32_e64 s[4:5], 4.0, v5
	v_or_b32_e32 v15, v17, v37
	s_nop 0
	v_cndmask_b32_e64 v5, v8, v14, s[4:5]
	v_cvt_u32_f32_e32 v8, v9
	v_or_b32_e32 v14, v16, v35
	v_cvt_u32_f32_e32 v5, v5
	v_lshrrev_b32_e32 v9, 26, v58
	v_min_u32_e32 v16, 31, v8
	v_lshrrev_b32_e32 v8, 26, v59
	v_and_b32_e32 v17, 32, v8
	v_mul_f32_e32 v8, 0x41000000, v52
	v_rndne_f32_e32 v35, v8
	v_mul_f32_e32 v8, 4.0, v52
	v_rndne_f32_e32 v65, v8
	v_and_b32_e32 v37, 32, v9
	v_pk_add_f32 v[8:9], v[64:65], s[16:17] op_sel_hi:[1,0]
	v_cmp_nle_f32_e64 s[4:5], 2.0, v12
	v_min_u32_e32 v5, 31, v5
	s_nop 0
	v_cndmask_b32_e64 v53, v8, v76, s[4:5]
	v_cmp_nle_f32_e64 s[4:5], 2.0, v52
	v_add_f32_e32 v8, v52, v52
	s_nop 0
	v_cndmask_b32_e64 v54, v9, v35, s[4:5]
	v_rndne_f32_e32 v35, v8
	v_pk_add_f32 v[8:9], v[34:35], s[18:19] op_sel_hi:[1,0]
	v_cmp_nle_f32_e64 s[4:5], 4.0, v52
	v_min_f32_e64 v34, |v13|, s31
	v_mul_f32_e32 v35, 0x41000000, v34
	v_cndmask_b32_e64 v9, v9, v54, s[4:5]
	v_cmp_nle_f32_e64 s[4:5], 4.0, v12
	v_or_b32_e32 v12, v16, v17
	v_or_b32_sdwa v16, v5, v37 dst_sel:WORD_1 dst_unused:UNUSED_PAD src0_sel:DWORD src1_sel:DWORD
	v_mul_f32_e32 v37, 4.0, v34
	v_rndne_f32_e32 v37, v37
	v_cndmask_b32_e64 v8, v8, v53, s[4:5]
	v_rndne_f32_e32 v35, v35
	v_add_f32_e32 v37, 0x41000000, v37
	v_cmp_nle_f32_e64 s[4:5], 2.0, v34
	v_cvt_u32_f32_e32 v9, v9
	v_cvt_u32_f32_e32 v8, v8
	v_cndmask_b32_e64 v35, v37, v35, s[4:5]
	v_add_f32_e32 v37, v34, v34
	v_rndne_f32_e32 v37, v37
	v_add_f32_e32 v37, 0x41800000, v37
	v_cmp_nle_f32_e64 s[4:5], 4.0, v34
	v_min_u32_e32 v5, 31, v9
	v_lshrrev_b32_e32 v9, 26, v63
	v_cndmask_b32_e64 v34, v37, v35, s[4:5]
	v_cvt_u32_f32_e32 v34, v34
	v_and_b32_e32 v9, 32, v9
	v_lshrrev_b32_e32 v17, 26, v62
	v_or_b32_e32 v9, v5, v9
	v_mov_b32_e32 v5, v7
	v_min_u32_e32 v8, 31, v8
	v_and_b32_e32 v17, 32, v17
	v_pk_mul_f32 v[4:5], v[4:5], v[18:19] op_sel_hi:[1,0]
	v_or_b32_e32 v8, v8, v17
	v_min_u32_e32 v17, 31, v34
	v_lshlrev_b32_e32 v34, 4, v3
	v_and_b32_e32 v3, 0x80000000, v25
	v_min_f32_e64 v7, |v4|, s31
	v_lshl_or_b32 v25, v68, 26, v3
	v_mul_f32_e32 v3, 0x41000000, v7
	v_rndne_f32_e32 v18, v3
	v_mul_f32_e32 v3, 4.0, v7
	v_rndne_f32_e32 v3, v3
	v_pk_add_f32 v[2:3], v[2:3], s[16:17] op_sel_hi:[1,0]
	v_cmp_nle_f32_e64 s[4:5], 2.0, v44
	v_lshlrev_b32_e32 v37, 10, v49
	v_lshrrev_b32_e32 v4, 26, v4
	v_cndmask_b32_e64 v52, v2, v23, s[4:5]
	v_cmp_nle_f32_e64 s[4:5], 2.0, v7
	v_add_f32_e32 v2, v7, v7
	v_rndne_f32_e32 v23, v2
	v_cndmask_b32_e64 v18, v3, v18, s[4:5]
	v_cmp_nle_f32_e64 s[4:5], 4.0, v7
	v_min_f32_e64 v7, |v5|, s31
	v_pk_add_f32 v[2:3], v[22:23], s[18:19] op_sel_hi:[1,0]
	v_mul_f32_e32 v22, 4.0, v7
	v_cndmask_b32_e64 v3, v3, v18, s[4:5]
	v_cmp_nle_f32_e64 s[4:5], 4.0, v44
	v_mul_f32_e32 v18, 0x41000000, v7
	v_rndne_f32_e32 v22, v22
	v_cndmask_b32_e64 v2, v2, v52, s[4:5]
	v_rndne_f32_e32 v18, v18
	v_add_f32_e32 v22, 0x41000000, v22
	v_cmp_nle_f32_e64 s[4:5], 2.0, v7
	v_cvt_u32_f32_e32 v2, v2
	v_cvt_u32_f32_e32 v3, v3
	v_cndmask_b32_e64 v18, v22, v18, s[4:5]
	v_add_f32_e32 v22, v7, v7
	v_rndne_f32_e32 v22, v22
	v_add_f32_e32 v22, 0x41800000, v22
	v_cmp_nle_f32_e64 s[4:5], 4.0, v7
	v_min_u32_e32 v2, 31, v2
	v_lshrrev_b32_e32 v5, 26, v5
	v_cndmask_b32_e64 v7, v22, v18, s[4:5]
	v_cvt_u32_f32_e32 v7, v7
	v_and_or_b32 v18, v45, 32, v2
	v_and_b32_e32 v5, 32, v5
	v_lshlrev_b32_e32 v35, 6, v46
	v_min_u32_e32 v7, 31, v7
	v_or_b32_e32 v5, v7, v5
	v_lshrrev_b32_e32 v7, 2, v18
	v_or_b32_e32 v7, v34, v7
	v_min_u32_e32 v3, 31, v3
	v_and_b32_e32 v4, 32, v4
	v_or_b32_e32 v7, v7, v37
	v_lshlrev_b32_e32 v46, 12, v50
	v_lshlrev_b32_e32 v50, 22, v66
	v_or_b32_e32 v4, v3, v4
	v_or_b32_e32 v18, v35, v43
	v_or_b32_e32 v7, v7, v47
	v_lshlrev_b32_e32 v49, 18, v51
	v_lshlrev_b32_e32 v51, 2, v67
	v_or_b32_e32 v18, v18, v46
	v_or_b32_e32 v7, v7, v50
	v_lshlrev_b32_e32 v3, 28, v3
	v_lshrrev_b32_e32 v4, 4, v4
	v_or_b32_e32 v18, v18, v49
	v_or_b32_e32 v3, v7, v3
	v_or_b32_e32 v4, v4, v51
	v_lshlrev_b32_e32 v7, 8, v70
	v_or_b32_e32 v18, v18, v48
	v_lshlrev_b32_e32 v2, 30, v2
	v_or_b32_e32 v4, v4, v7
	v_lshlrev_b32_e32 v7, 14, v72
	v_or_b32_e32 v2, v18, v2
	v_lshlrev_b32_e32 v5, 6, v5
	v_or_b32_e32 v4, v4, v7
	v_lshrrev_b32_e32 v7, 4, v20
	v_lshrrev_b32_e32 v18, 2, v21
	v_or_b32_e32 v5, v5, v6
	v_lshlrev_b32_e32 v6, 12, v69
	v_or_b32_e32 v7, v7, v10
	v_or_b32_e32 v10, v18, v11
	v_lshlrev_b32_e32 v11, 8, v14
	v_or_b32_e32 v5, v5, v6
	v_lshlrev_b32_e32 v6, 18, v71
	v_lshlrev_b32_e32 v14, 10, v15
	v_or_b32_e32 v7, v7, v11
	v_lshlrev_b32_e32 v11, 14, v12
	v_or_b32_e32 v5, v5, v6
	v_lshlrev_b32_e32 v6, 20, v74
	v_or_b32_e32 v10, v10, v14
	v_or_b32_e32 v7, v7, v11
	v_lshlrev_b32_e32 v9, 20, v9
	v_or_b32_e32 v5, v5, v73
	v_or_b32_e32 v4, v4, v6
	v_lshlrev_b32_e32 v6, 30, v36
	v_or_b32_e32 v10, v10, v16
	v_lshlrev_b32_e32 v8, 22, v8
	v_or_b32_e32 v7, v7, v9
	v_and_b32_e32 v9, 0x80000000, v13
	v_or_b32_e32 v5, v5, v6
	v_or_b32_e32 v4, v4, v25
	v_lshlrev_b32_e32 v6, 28, v19
	v_or_b32_e32 v8, v10, v8
	v_lshl_or_b32 v9, v17, 26, v9
	v_or_b32_e32 v7, v7, v9
	v_or_b32_e32 v6, v8, v6
	global_store_dwordx4 v[32:33], v[2:5], off
	global_store_dwordx2 v[32:33], v[6:7], off offset:16
	s_and_saveexec_b64 s[4:5], s[0:1]
	s_cbranch_execz .LBB0_47
	v_mul_f32_e32 v4, 0x3e088889, v24
	v_lshl_add_u64 v[2:3], v[30:31], 2, s[28:29]
	v_cndmask_b32_e32 v4, 1.0, v4, vcc
	global_store_dword v[2:3], v4, off
	s_branch .LBB0_47
.LBB0_50:
	s_or_b64 exec, exec, s[14:15]
	v_mov_b32_e32 v2, v205
	v_mov_b32_e32 v1, v205
	s_add_u32 s30, s26, 0x1430000
	v_ashrrev_i32_e32 v1, 6, v1
	v_add_u32_e32 v1, s21, v1
	s_movk_i32 s0, 0x2000
	s_addc_u32 s31, s27, 0
	v_cmp_gt_i32_e32 vcc, s0, v1
	s_and_saveexec_b64 s[8:9], vcc
	s_cbranch_execz .LBB0_55
	v_and_b32_e32 v7, 31, v2
	v_bfe_u32 v6, v2, 5, 1
	v_lshlrev_b32_e32 v2, 4, v7
	v_mov_b32_e32 v3, 0
	v_lshl_add_u64 v[4:5], s[10:11], 0, v[2:3]
	s_mov_b64 s[0:1], 0x4000000
	v_lshl_add_u64 v[26:27], v[4:5], 0, s[0:1]
	v_mbcnt_hi_u32_b32 v4, -1, v207
	v_and_b32_e32 v2, 64, v4
	v_add_u32_e32 v5, 64, v2
	v_and_b32_e32 v2, 7, v7
	v_mul_u32_u24_e32 v2, 24, v2
	v_lshrrev_b32_e32 v3, 3, v7
	v_mul_u32_u24_e32 v3, 0x300000, v3
	v_add_u32_e32 v2, v2, v3
	v_mov_b32_e32 v3, 0
	v_lshl_add_u64 v[2:3], s[26:27], 0, v[2:3]
	s_mov_b64 s[0:1], 0x4800000
	v_lshl_add_u64 v[28:29], v[2:3], 0, s[0:1]
	v_xor_b32_e32 v2, 16, v4
	v_cmp_lt_i32_e32 vcc, v2, v5
	v_cmp_eq_u32_e64 s[0:1], 0, v7
	s_lshl_b32 s15, s19, 2
	v_cndmask_b32_e32 v2, v4, v2, vcc
	v_lshlrev_b32_e32 v38, 2, v2
	v_xor_b32_e32 v2, 8, v4
	v_cmp_lt_i32_e32 vcc, v2, v5
	v_lshl_or_b32 v30, v1, 1, v6
	s_lshl_b32 s3, s3, 4
	v_cndmask_b32_e32 v2, v4, v2, vcc
	v_lshlrev_b32_e32 v39, 2, v2
	v_xor_b32_e32 v2, 4, v4
	v_cmp_lt_i32_e32 vcc, v2, v5
	s_mov_b64 s[10:11], 0
	s_movk_i32 s17, 0xc0
	v_cndmask_b32_e32 v2, v4, v2, vcc
	v_lshlrev_b32_e32 v40, 2, v2
	v_xor_b32_e32 v2, 2, v4
	v_cmp_lt_i32_e32 vcc, v2, v5
	s_mov_b32 s18, 0x40f00000
	s_mov_b32 s14, 0x41000000
	v_cndmask_b32_e32 v2, v4, v2, vcc
	v_lshlrev_b32_e32 v41, 2, v2
	v_xor_b32_e32 v2, 1, v4
	v_cmp_lt_i32_e32 vcc, v2, v5
	s_mov_b32 s16, 0x41800000
	s_movk_i32 s19, 0x1fff
	v_cndmask_b32_e32 v2, v4, v2, vcc
	v_lshlrev_b32_e32 v42, 2, v2
	s_branch .LBB0_53

.LBB0_53:
	v_ashrrev_i32_e32 v31, 31, v30
	v_lshlrev_b64 v[2:3], 12, v[30:31]
	v_lshl_add_u64 v[10:11], v[26:27], 0, v[2:3]
	global_load_dwordx4 v[2:5], v[10:11], off offset:1024
	global_load_dwordx4 v[22:25], v[10:11], off offset:1536
	global_load_dwordx4 v[6:9], v[10:11], off offset:2048
	global_load_dwordx4 v[44:47], v[10:11], off
	global_load_dwordx4 v[48:51], v[10:11], off offset:512
	global_load_dwordx4 v[18:21], v[10:11], off offset:2560
	global_load_dwordx4 v[14:17], v[10:11], off offset:3072
	s_nop 0
	global_load_dwordx4 v[10:13], v[10:11], off offset:3584
	s_waitcnt vmcnt(7)
	v_max_f32_e64 v32, |v5|, |v5|
	v_max_f32_e64 v33, |v4|, |v4|
	s_waitcnt vmcnt(6)
	v_max_f32_e64 v34, |v25|, |v25|
	v_max_f32_e64 v35, |v24|, |v24|
	s_waitcnt vmcnt(5)
	v_max_f32_e64 v36, |v7|, |v7|
	v_max_f32_e64 v37, |v6|, |v6|
	s_waitcnt vmcnt(4)
	v_max_f32_e64 v43, |v45|, |v45|
	v_max_f32_e64 v52, |v44|, |v44|
	v_max_f32_e64 v53, |v47|, |v47|
	v_max_f32_e64 v54, |v46|, |v46|
	s_waitcnt vmcnt(3)
	v_max_f32_e64 v55, |v49|, |v49|
	v_max_f32_e64 v56, |v48|, |v48|
	v_max_f32_e64 v57, |v51|, |v51|
	v_max_f32_e64 v58, |v50|, |v50|
	v_max_f32_e32 v32, v33, v32
	v_max_f32_e32 v33, v35, v34
	v_max_f32_e32 v34, v37, v36
	v_max_f32_e32 v35, v52, v43
	v_max_f32_e32 v36, v54, v53
	v_max_f32_e64 v59, |v3|, |v3|
	v_max_f32_e64 v60, |v2|, |v2|
	v_max_f32_e32 v37, v56, v55
	v_max_f32_e32 v43, v58, v57
	v_max3_f32 v35, v35, 0, v36
	v_max_f32_e64 v61, |v23|, |v23|
	v_max_f32_e64 v62, |v22|, |v22|
	v_max_f32_e32 v52, v60, v59
	v_max3_f32 v35, v35, v37, v43
	v_max_f32_e64 v63, |v9|, |v9|
	v_max_f32_e64 v64, |v8|, |v8|
	v_max_f32_e32 v53, v62, v61
	v_max3_f32 v32, v35, v52, v32
	s_waitcnt vmcnt(2)
	v_max_f32_e64 v65, |v19|, |v19|
	v_max_f32_e64 v66, |v18|, |v18|
	v_max_f32_e64 v67, |v21|, |v21|
	v_max_f32_e64 v68, |v20|, |v20|
	v_max_f32_e32 v54, v64, v63
	v_max3_f32 v32, v32, v53, v33
	s_waitcnt vmcnt(1)
	v_max_f32_e64 v69, |v15|, |v15|
	v_max_f32_e64 v70, |v14|, |v14|
	v_max_f32_e64 v71, |v17|, |v17|
	v_max_f32_e64 v72, |v16|, |v16|
	v_max_f32_e32 v55, v66, v65
	v_max_f32_e32 v56, v68, v67
	v_max3_f32 v32, v32, v34, v54
	s_waitcnt vmcnt(0)
	v_max_f32_e64 v73, |v11|, |v11|
	v_max_f32_e64 v74, |v10|, |v10|
	v_max_f32_e64 v75, |v13|, |v13|
	v_max_f32_e64 v76, |v12|, |v12|
	v_max_f32_e32 v57, v70, v69
	v_max_f32_e32 v58, v72, v71
	v_max3_f32 v32, v32, v55, v56
	v_max_f32_e32 v59, v74, v73
	v_max_f32_e32 v60, v76, v75
	v_max3_f32 v32, v32, v57, v58
	v_max3_f32 v32, v32, v59, v60
	ds_bpermute_b32 v33, v38, v32
	v_mov_b32_e32 v36, v22
	v_mov_b32_e32 v37, v8
	v_mov_b32_e32 v8, v23
	v_mov_b32_e32 v52, v45
	s_waitcnt lgkmcnt(0)
	v_max_f32_e32 v33, v33, v33
	v_max_f32_e32 v32, v32, v33
	ds_bpermute_b32 v33, v39, v32
	v_mov_b32_e32 v53, v50
	v_mov_b32_e32 v50, v46
	v_mov_b32_e32 v46, v47
	v_mov_b32_e32 v47, v2
	s_waitcnt lgkmcnt(0)
	v_max_f32_e32 v33, v33, v33
	v_max_f32_e32 v34, v32, v33
	ds_bpermute_b32 v35, v40, v34
	v_mov_b32_e32 v2, v48
	v_mad_i64_i32 v[32:33], s[4:5], v30, s17, v[28:29]
	s_waitcnt lgkmcnt(0)
	v_max_f32_e32 v35, v35, v35
	v_max_f32_e32 v34, v34, v35
	ds_bpermute_b32 v35, v41, v34
	s_waitcnt lgkmcnt(0)
	v_max_f32_e32 v35, v35, v35
	v_max_f32_e32 v35, v34, v35
	ds_bpermute_b32 v43, v42, v35
	v_mov_b32_e32 v34, v24
	s_waitcnt lgkmcnt(0)
	v_max_f32_e32 v22, v43, v43
	v_max_f32_e32 v24, v35, v22
	v_div_scale_f32 v22, s[4:5], v24, v24, s18
	v_rcp_f32_e32 v23, v22
	v_mov_b32_e32 v35, v18
	v_div_scale_f32 v18, vcc, s18, v24, s18
	v_fma_f32 v43, -v22, v23, 1.0
	v_fmac_f32_e32 v23, v43, v23
	v_mul_f32_e32 v43, v18, v23
	v_fma_f32 v45, -v22, v43, v18
	v_fmac_f32_e32 v43, v45, v23
	v_fma_f32 v18, -v22, v43, v18
	v_div_fmas_f32 v18, v18, v23, v43
	v_div_fixup_f32 v18, v18, v24, s18
	v_cmp_lt_f32_e32 vcc, 0, v24
	s_nop 1
	v_cndmask_b32_e32 v18, 1.0, v18, vcc
	v_mul_f32_e32 v22, v44, v18
	v_pk_mul_f32 v[56:57], v[2:3], v[18:19] op_sel_hi:[1,0]
	v_min_f32_e64 v2, |v22|, s18
	v_mul_f32_e32 v43, 4.0, v2
	v_mul_f32_e32 v23, 0x41000000, v2
	v_add_f32_e32 v44, v2, v2
	v_rndne_f32_e32 v43, v43
	v_rndne_f32_e32 v23, v23
	v_rndne_f32_e32 v44, v44
	v_add_f32_e32 v43, 0x41000000, v43
	v_cmp_nle_f32_e64 s[4:5], 2.0, v2
	v_add_f32_e32 v44, 0x41800000, v44
	v_pk_mul_f32 v[54:55], v[46:47], v[18:19] op_sel_hi:[1,0]
	v_cndmask_b32_e64 v23, v43, v23, s[4:5]
	v_cmp_nle_f32_e64 s[4:5], 4.0, v2
	v_pk_mul_f32 v[52:53], v[52:53], v[18:19] op_sel_hi:[1,0]
	v_min_f32_e64 v67, |v54|, s18
	v_cndmask_b32_e64 v2, v44, v23, s[4:5]
	v_cvt_u32_f32_e32 v2, v2
	v_lshrrev_b32_e32 v3, 26, v22
	v_min_f32_e64 v22, |v52|, s18
	v_mul_f32_e32 v61, 0x41000000, v67
	v_add_f32_e32 v47, v22, v22
	v_rndne_f32_e32 v69, v61
	v_min_f32_e64 v61, |v53|, s18
	v_rndne_f32_e32 v48, v47
	v_min_u32_e32 v2, 31, v2
	v_mul_f32_e32 v47, 0x41000000, v61
	v_mul_f32_e32 v46, 4.0, v22
	v_and_or_b32 v43, v3, 32, v2
	v_mul_f32_e32 v3, v49, v18
	v_rndne_f32_e32 v49, v47
	v_mul_f32_e32 v47, 4.0, v61
	v_mul_f32_e32 v45, 0x41000000, v22
	v_rndne_f32_e32 v46, v46
	v_rndne_f32_e32 v47, v47
	v_rndne_f32_e32 v45, v45
	v_pk_add_f32 v[46:47], v[46:47], s[14:15] op_sel_hi:[1,0]
	v_cmp_nle_f32_e64 s[4:5], 2.0, v22
	v_pk_mul_f32 v[50:51], v[50:51], v[18:19] op_sel_hi:[1,0]
	v_min_f32_e64 v44, |v3|, s18
	v_cndmask_b32_e64 v45, v46, v45, s[4:5]
	v_cmp_nle_f32_e64 s[4:5], 2.0, v61
	v_add_f32_e32 v46, v61, v61
	v_min_f32_e64 v63, |v50|, s18
	v_cndmask_b32_e64 v72, v47, v49, s[4:5]
	v_rndne_f32_e32 v49, v46
	v_pk_add_f32 v[46:47], v[48:49], s[16:17] op_sel_hi:[1,0]
	v_cmp_nle_f32_e64 s[4:5], 4.0, v61
	v_mul_f32_e32 v58, 0x41000000, v63
	v_mul_f32_e32 v59, 4.0, v63
	v_cndmask_b32_e64 v47, v47, v72, s[4:5]
	v_cmp_nle_f32_e64 s[4:5], 4.0, v22
	v_rndne_f32_e32 v65, v58
	v_rndne_f32_e32 v58, v59
	v_cndmask_b32_e64 v22, v46, v45, s[4:5]
	v_cvt_u32_f32_e32 v46, v47
	v_cvt_u32_f32_e32 v47, v22
	v_lshrrev_b32_e32 v45, 26, v3
	v_add_f32_e32 v59, v44, v44
	v_min_u32_e32 v3, 31, v46
	v_lshrrev_b32_e32 v46, 26, v53
	v_min_f32_e64 v53, |v51|, s18
	v_and_b32_e32 v49, 32, v46
	v_mul_f32_e32 v46, 0x41000000, v53
	v_rndne_f32_e32 v61, v46
	v_mul_f32_e32 v46, 4.0, v53
	v_rndne_f32_e32 v22, v59
	v_min_u32_e32 v48, 31, v47
	v_lshrrev_b32_e32 v47, 26, v52
	v_rndne_f32_e32 v59, v46
	v_and_b32_e32 v52, 32, v47
	v_pk_add_f32 v[46:47], v[58:59], s[14:15] op_sel_hi:[1,0]
	v_cmp_nle_f32_e64 s[4:5], 2.0, v63
	v_add_f32_e32 v60, v63, v63
	v_rndne_f32_e32 v60, v60
	v_cndmask_b32_e64 v58, v46, v65, s[4:5]
	v_cmp_nle_f32_e64 s[4:5], 2.0, v53
	v_add_f32_e32 v46, v53, v53
	v_or_b32_e32 v3, v3, v49
	v_cndmask_b32_e64 v59, v47, v61, s[4:5]
	v_rndne_f32_e32 v61, v46
	v_pk_add_f32 v[46:47], v[60:61], s[16:17] op_sel_hi:[1,0]
	v_cmp_nle_f32_e64 s[4:5], 4.0, v53
	v_lshrrev_b32_e32 v49, 26, v50
	v_mul_f32_e32 v62, 4.0, v67
	v_cndmask_b32_e64 v47, v47, v59, s[4:5]
	v_cmp_nle_f32_e64 s[4:5], 4.0, v63
	v_rndne_f32_e32 v62, v62
	v_cvt_u32_f32_e32 v47, v47
	v_cndmask_b32_e64 v46, v46, v58, s[4:5]
	v_cvt_u32_f32_e32 v53, v46
	v_or_b32_e32 v46, v48, v52
	v_lshrrev_b32_e32 v48, 26, v51
	v_and_b32_e32 v50, 32, v48
	v_min_u32_e32 v52, 31, v53
	v_min_f32_e64 v53, |v55|, s18
	v_mul_f32_e32 v48, 0x41000000, v53
	v_rndne_f32_e32 v58, v48
	v_mul_f32_e32 v48, 4.0, v53
	v_rndne_f32_e32 v63, v48
	v_and_b32_e32 v51, 32, v49
	v_pk_add_f32 v[48:49], v[62:63], s[14:15] op_sel_hi:[1,0]
	v_cmp_nle_f32_e64 s[4:5], 2.0, v67
	v_add_f32_e32 v64, v67, v67
	v_rndne_f32_e32 v64, v64
	v_cndmask_b32_e64 v59, v48, v69, s[4:5]
	v_add_f32_e32 v48, v53, v53
	v_cmp_nle_f32_e64 s[4:5], 2.0, v53
	v_rndne_f32_e32 v65, v48
	v_min_u32_e32 v47, 31, v47
	v_cndmask_b32_e64 v58, v49, v58, s[4:5]
	v_pk_add_f32 v[48:49], v[64:65], s[16:17] op_sel_hi:[1,0]
	v_cmp_nle_f32_e64 s[4:5], 4.0, v53
	v_min_f32_e64 v70, |v56|, s18
	v_mul_f32_e32 v2, 0x41000000, v70
	v_cndmask_b32_e64 v49, v49, v58, s[4:5]
	v_cvt_u32_f32_e32 v53, v49
	v_or_b32_e32 v49, v47, v50
	v_or_b32_e32 v50, v52, v51
	v_lshrrev_b32_e32 v51, 26, v55
	v_lshrrev_b32_e32 v52, 26, v54
	v_min_f32_e64 v55, |v57|, s18
	v_and_b32_e32 v54, 32, v52
	v_mul_f32_e32 v52, 0x41000000, v55
	v_rndne_f32_e32 v71, v2
	v_mul_f32_e32 v2, 4.0, v70
	v_rndne_f32_e32 v58, v52
	v_mul_f32_e32 v52, 4.0, v55
	v_rndne_f32_e32 v66, v2
	v_cmp_nle_f32_e64 s[4:5], 4.0, v67
	v_rndne_f32_e32 v67, v52
	v_min_u32_e32 v47, 31, v53
	v_cndmask_b32_e64 v48, v48, v59, s[4:5]
	v_pk_add_f32 v[52:53], v[66:67], s[14:15] op_sel_hi:[1,0]
	v_cmp_nle_f32_e64 s[4:5], 2.0, v70
	v_add_f32_e32 v2, v70, v70
	v_rndne_f32_e32 v68, v2
	v_cndmask_b32_e64 v59, v52, v71, s[4:5]
	v_add_f32_e32 v52, v55, v55
	v_cmp_nle_f32_e64 s[4:5], 2.0, v55
	v_rndne_f32_e32 v69, v52
	v_cvt_u32_f32_e32 v48, v48
	v_cndmask_b32_e64 v58, v53, v58, s[4:5]
	v_pk_add_f32 v[52:53], v[68:69], s[16:17] op_sel_hi:[1,0]
	v_cmp_nle_f32_e64 s[4:5], 4.0, v55
	v_mul_f32_e32 v5, v5, v18
	v_min_u32_e32 v48, 31, v48
	v_cndmask_b32_e64 v53, v53, v58, s[4:5]
	v_cvt_u32_f32_e32 v53, v53
	v_and_b32_e32 v51, 32, v51
	v_min_f32_e64 v55, |v5|, s18
	v_or_b32_sdwa v47, v47, v51 dst_sel:WORD_1 dst_unused:UNUSED_PAD src0_sel:DWORD src1_sel:DWORD
	v_or_b32_e32 v51, v48, v54
	v_min_u32_e32 v48, 31, v53
	v_lshrrev_b32_e32 v53, 26, v57
	v_mul_f32_e32 v57, 4.0, v55
	v_cmp_nle_f32_e64 s[4:5], 4.0, v70
	v_lshrrev_b32_e32 v54, 26, v56
	v_mul_f32_e32 v56, 0x41000000, v55
	v_rndne_f32_e32 v57, v57
	v_cndmask_b32_e64 v52, v52, v59, s[4:5]
	v_rndne_f32_e32 v56, v56
	v_add_f32_e32 v57, 0x41000000, v57
	v_cmp_nle_f32_e64 s[4:5], 2.0, v55
	v_cvt_u32_f32_e32 v52, v52
	v_and_b32_e32 v53, 32, v53
	v_cndmask_b32_e64 v56, v57, v56, s[4:5]
	v_add_f32_e32 v57, v55, v55
	v_rndne_f32_e32 v57, v57
	v_add_f32_e32 v57, 0x41800000, v57
	v_cmp_nle_f32_e64 s[4:5], 4.0, v55
	v_min_u32_e32 v52, 31, v52
	v_and_b32_e32 v54, 32, v54
	v_cndmask_b32_e64 v55, v57, v56, s[4:5]
	v_cvt_u32_f32_e32 v55, v55
	v_or_b32_e32 v66, v48, v53
	v_or_b32_sdwa v48, v52, v54 dst_sel:BYTE_3 dst_unused:UNUSED_PAD src0_sel:DWORD src1_sel:DWORD
	v_lshrrev_b32_e32 v5, 26, v5
	v_min_u32_e32 v52, 31, v55
	v_pk_mul_f32 v[36:37], v[36:37], v[18:19] op_sel_hi:[1,0]
	v_and_or_b32 v67, v5, 32, v52
	v_min_f32_e64 v5, |v36|, s18
	v_pk_mul_f32 v[8:9], v[8:9], v[18:19] op_sel_hi:[1,0]
	v_add_f32_e32 v53, v5, v5
	v_min_f32_e64 v61, |v8|, s18
	v_rndne_f32_e32 v54, v53
	v_mul_f32_e32 v53, 0x41000000, v61
	v_rndne_f32_e32 v59, v53
	v_mul_f32_e32 v53, 4.0, v61
	v_pk_mul_f32 v[34:35], v[34:35], v[18:19] op_sel_hi:[1,0]
	v_rndne_f32_e32 v56, v53
	v_add_f32_e32 v53, v61, v61
	v_min_f32_e64 v64, |v34|, s18
	v_rndne_f32_e32 v58, v53
	v_mul_f32_e32 v53, 0x41000000, v64
	v_rndne_f32_e32 v63, v53
	v_mul_f32_e32 v53, 4.0, v64
	v_mul_f32_e32 v25, v25, v18
	v_rndne_f32_e32 v60, v53
	v_min_f32_e64 v53, |v25|, s18
	v_mul_f32_e32 v62, 4.0, v53
	v_mul_f32_e32 v57, 0x41000000, v53
	v_rndne_f32_e32 v62, v62
	v_rndne_f32_e32 v57, v57
	v_add_f32_e32 v62, 0x41000000, v62
	v_cmp_nle_f32_e64 s[4:5], 2.0, v53
	v_mul_f32_e32 v6, v6, v18
	v_mul_f32_e32 v52, 0x41000000, v5
	v_cndmask_b32_e64 v57, v62, v57, s[4:5]
	v_add_f32_e32 v62, v53, v53
	v_rndne_f32_e32 v62, v62
	v_add_f32_e32 v62, 0x41800000, v62
	v_cmp_nle_f32_e64 s[4:5], 4.0, v53
	v_rndne_f32_e32 v55, v52
	v_mul_f32_e32 v52, 4.0, v5
	v_cndmask_b32_e64 v53, v62, v57, s[4:5]
	v_min_f32_e64 v57, |v6|, s18
	v_mul_f32_e32 v65, 4.0, v57
	v_mul_f32_e32 v62, 0x41000000, v57
	v_rndne_f32_e32 v65, v65
	v_rndne_f32_e32 v62, v62
	v_add_f32_e32 v65, 0x41000000, v65
	v_cmp_nle_f32_e64 s[4:5], 2.0, v57
	v_cvt_u32_f32_e32 v53, v53
	v_rndne_f32_e32 v52, v52
	v_cndmask_b32_e64 v62, v65, v62, s[4:5]
	v_add_f32_e32 v65, v57, v57
	v_rndne_f32_e32 v65, v65
	v_add_f32_e32 v65, 0x41800000, v65
	v_cmp_nle_f32_e64 s[4:5], 4.0, v57
	v_min_u32_e32 v68, 31, v53
	v_lshrrev_b32_e32 v36, 26, v36
	v_cndmask_b32_e64 v57, v65, v62, s[4:5]
	v_min_f32_e64 v65, |v37|, s18
	v_mul_f32_e32 v53, 0x41000000, v65
	v_rndne_f32_e32 v69, v53
	v_mul_f32_e32 v53, 4.0, v65
	v_rndne_f32_e32 v53, v53
	v_pk_add_f32 v[52:53], v[52:53], s[14:15] op_sel_hi:[1,0]
	v_cmp_nle_f32_e64 s[4:5], 2.0, v5
	v_cvt_u32_f32_e32 v57, v57
	v_lshrrev_b32_e32 v6, 26, v6
	v_cndmask_b32_e64 v70, v52, v55, s[4:5]
	v_add_f32_e32 v52, v65, v65
	v_cmp_nle_f32_e64 s[4:5], 2.0, v65
	v_rndne_f32_e32 v55, v52
	v_min_u32_e32 v57, 31, v57
	v_cndmask_b32_e64 v69, v53, v69, s[4:5]
	v_pk_add_f32 v[52:53], v[54:55], s[16:17] op_sel_hi:[1,0]
	v_min_f32_e64 v55, |v9|, s18
	v_and_b32_e32 v54, 32, v36
	v_mul_f32_e32 v36, 0x41000000, v55
	v_cmp_nle_f32_e64 s[4:5], 4.0, v65
	v_rndne_f32_e32 v65, v36
	v_mul_f32_e32 v36, 4.0, v55
	v_cndmask_b32_e64 v53, v53, v69, s[4:5]
	v_cmp_nle_f32_e64 s[4:5], 4.0, v5
	v_and_or_b32 v6, v6, 32, v57
	v_lshrrev_b32_e32 v37, 26, v37
	v_rndne_f32_e32 v57, v36
	v_cndmask_b32_e64 v5, v52, v70, s[4:5]
	v_cvt_u32_f32_e32 v52, v53
	v_and_b32_e32 v53, 32, v37
	v_pk_add_f32 v[36:37], v[56:57], s[14:15] op_sel_hi:[1,0]
	v_cmp_nle_f32_e64 s[4:5], 2.0, v61
	v_cvt_u32_f32_e32 v5, v5
	v_min_u32_e32 v52, 31, v52
	v_cndmask_b32_e64 v56, v36, v59, s[4:5]
	v_add_f32_e32 v36, v55, v55
	v_cmp_nle_f32_e64 s[4:5], 2.0, v55
	v_rndne_f32_e32 v59, v36
	v_or_b32_e32 v69, v52, v53
	v_cndmask_b32_e64 v57, v37, v65, s[4:5]
	v_pk_add_f32 v[36:37], v[58:59], s[16:17] op_sel_hi:[1,0]
	v_cmp_nle_f32_e64 s[4:5], 4.0, v55
	v_lshrrev_b32_e32 v8, 26, v8
	v_min_f32_e64 v53, |v35|, s18
	v_cndmask_b32_e64 v37, v37, v57, s[4:5]
	v_cvt_u32_f32_e32 v37, v37
	v_min_u32_e32 v5, 31, v5
	v_and_b32_e32 v52, 32, v8
	v_mul_f32_e32 v8, 0x41000000, v53
	v_or_b32_e32 v70, v5, v54
	v_rndne_f32_e32 v54, v8
	v_mul_f32_e32 v8, 4.0, v53
	v_cmp_nle_f32_e64 s[4:5], 4.0, v61
	v_lshrrev_b32_e32 v9, 26, v9
	v_rndne_f32_e32 v61, v8
	v_cndmask_b32_e64 v36, v36, v56, s[4:5]
	v_min_u32_e32 v5, 31, v37
	v_and_b32_e32 v37, 32, v9
	v_pk_add_f32 v[8:9], v[60:61], s[14:15] op_sel_hi:[1,0]
	v_cmp_nle_f32_e64 s[4:5], 2.0, v64
	v_add_f32_e32 v62, v64, v64
	v_rndne_f32_e32 v62, v62
	v_cndmask_b32_e64 v55, v8, v63, s[4:5]
	v_add_f32_e32 v8, v53, v53
	v_cmp_nle_f32_e64 s[4:5], 2.0, v53
	v_rndne_f32_e32 v63, v8
	v_or_b32_e32 v71, v5, v37
	v_cndmask_b32_e64 v54, v9, v54, s[4:5]
	v_pk_add_f32 v[8:9], v[62:63], s[16:17] op_sel_hi:[1,0]
	v_cmp_nle_f32_e64 s[4:5], 4.0, v53
	v_lshrrev_b32_e32 v34, 26, v34
	v_and_b32_e32 v34, 32, v34
	v_cndmask_b32_e64 v9, v9, v54, s[4:5]
	v_cmp_nle_f32_e64 s[4:5], 4.0, v64
	v_cvt_u32_f32_e32 v9, v9
	v_cvt_u32_f32_e32 v36, v36
	v_cndmask_b32_e64 v8, v8, v55, s[4:5]
	v_cvt_u32_f32_e32 v8, v8
	v_min_u32_e32 v5, 31, v9
	v_lshrrev_b32_e32 v9, 26, v35
	v_and_b32_e32 v9, 32, v9
	v_min_u32_e32 v8, 31, v8
	v_or_b32_sdwa v73, v5, v9 dst_sel:BYTE_3 dst_unused:UNUSED_PAD src0_sel:DWORD src1_sel:DWORD
	v_or_b32_e32 v74, v8, v34
	v_mov_b32_e32 v8, v19
	v_mov_b32_e32 v9, v16
	v_pk_mul_f32 v[8:9], v[8:9], v[18:19] op_sel_hi:[1,0]
	v_mov_b32_e32 v16, v20
	v_min_f32_e64 v19, |v8|, s18
	v_mul_f32_e32 v5, 0x41000000, v19
	v_rndne_f32_e32 v37, v5
	v_mul_f32_e32 v5, 4.0, v19
	v_pk_mul_f32 v[16:17], v[16:17], v[18:19] op_sel_hi:[1,0]
	v_min_u32_e32 v36, 31, v36
	v_rndne_f32_e32 v34, v5
	v_add_f32_e32 v5, v19, v19
	v_min_f32_e64 v57, |v16|, s18
	v_or_b32_e32 v72, v36, v52
	v_rndne_f32_e32 v36, v5
	v_mul_f32_e32 v5, 0x41000000, v57
	v_mov_b32_e32 v54, v21
	v_mov_b32_e32 v55, v10
	v_rndne_f32_e32 v53, v5
	v_mul_f32_e32 v5, 4.0, v57
	v_pk_mul_f32 v[54:55], v[54:55], v[18:19] op_sel_hi:[1,0]
	v_rndne_f32_e32 v20, v5
	v_add_f32_e32 v5, v57, v57
	v_min_f32_e64 v61, |v54|, s18
	v_rndne_f32_e32 v52, v5
	v_mul_f32_e32 v5, 0x41000000, v61
	v_rndne_f32_e32 v65, v5
	v_mul_f32_e32 v5, 4.0, v61
	v_rndne_f32_e32 v10, v5
	v_add_f32_e32 v5, v61, v61
	v_rndne_f32_e32 v56, v5
	v_mov_b32_e32 v58, v11
	v_mov_b32_e32 v59, v12
	v_mov_b32_e32 v5, v14
	v_pk_mov_b32 v[58:59], v[4:5], v[58:59] op_sel:[1,0]
	v_mov_b32_e32 v62, v15
	v_pk_mul_f32 v[58:59], v[58:59], v[18:19] op_sel_hi:[1,0]
	v_mov_b32_e32 v63, v12
	v_min_f32_e64 v5, |v58|, s18
	v_mul_f32_e32 v11, 0x41000000, v5
	v_rndne_f32_e32 v75, v11
	v_mul_f32_e32 v11, 4.0, v5
	v_pk_mul_f32 v[62:63], v[62:63], v[18:19] op_sel_hi:[1,0]
	v_rndne_f32_e32 v14, v11
	v_add_f32_e32 v11, v5, v5
	v_min_f32_e64 v12, |v62|, s18
	v_rndne_f32_e32 v60, v11
	v_mul_f32_e32 v11, 0x41000000, v12
	v_rndne_f32_e32 v76, v11
	v_mul_f32_e32 v11, 4.0, v12
	v_rndne_f32_e32 v64, v11
	v_min_f32_e64 v11, |v9|, s18
	v_mul_f32_e32 v21, 4.0, v11
	v_rndne_f32_e32 v35, v21
	v_pk_add_f32 v[34:35], v[34:35], s[14:15] op_sel_hi:[1,0]
	v_cmp_nle_f32_e64 s[4:5], 2.0, v19
	v_mul_f32_e32 v15, 0x41000000, v11
	v_rndne_f32_e32 v15, v15
	v_cndmask_b32_e64 v21, v34, v37, s[4:5]
	v_add_f32_e32 v34, v11, v11
	v_cmp_nle_f32_e64 s[4:5], 2.0, v11
	v_rndne_f32_e32 v37, v34
	v_lshrrev_b32_e32 v8, 26, v8
	v_cndmask_b32_e64 v15, v35, v15, s[4:5]
	v_pk_add_f32 v[34:35], v[36:37], s[16:17] op_sel_hi:[1,0]
	v_cmp_nle_f32_e64 s[4:5], 4.0, v11
	v_lshrrev_b32_e32 v9, 26, v9
	v_mul_f32_e32 v13, v13, v18
	v_cndmask_b32_e64 v11, v35, v15, s[4:5]
	v_cmp_nle_f32_e64 s[4:5], 4.0, v19
	v_cvt_u32_f32_e32 v11, v11
	v_min_f32_e64 v35, |v17|, s18
	v_cndmask_b32_e64 v15, v34, v21, s[4:5]
	v_cvt_u32_f32_e32 v15, v15
	v_add_f32_e32 v19, v12, v12
	v_rndne_f32_e32 v34, v19
	v_min_u32_e32 v19, 31, v11
	v_min_u32_e32 v36, 31, v15
	v_and_b32_e32 v15, 32, v8
	v_mul_f32_e32 v8, 0x41000000, v35
	v_rndne_f32_e32 v37, v8
	v_mul_f32_e32 v8, 4.0, v35
	v_rndne_f32_e32 v21, v8
	v_and_b32_e32 v11, 32, v9
	v_pk_add_f32 v[8:9], v[20:21], s[14:15] op_sel_hi:[1,0]
	v_cmp_nle_f32_e64 s[4:5], 2.0, v57
	v_mul_f32_e32 v2, 0x41000000, v44
	v_rndne_f32_e32 v23, v2
	v_cndmask_b32_e64 v20, v8, v53, s[4:5]
	v_add_f32_e32 v8, v35, v35
	v_cmp_nle_f32_e64 s[4:5], 2.0, v35
	v_rndne_f32_e32 v53, v8
	v_mul_f32_e32 v2, 4.0, v44
	v_cndmask_b32_e64 v21, v9, v37, s[4:5]
	v_pk_add_f32 v[8:9], v[52:53], s[16:17] op_sel_hi:[1,0]
	v_cmp_nle_f32_e64 s[4:5], 4.0, v35
	v_min_f32_e64 v37, |v55|, s18
	v_rndne_f32_e32 v2, v2
	v_cndmask_b32_e64 v9, v9, v21, s[4:5]
	v_cmp_nle_f32_e64 s[4:5], 4.0, v57
	v_cvt_u32_f32_e32 v9, v9
	v_or_b32_e32 v21, v36, v15
	v_cndmask_b32_e64 v8, v8, v20, s[4:5]
	v_cvt_u32_f32_e32 v8, v8
	v_min_u32_e32 v15, 31, v9
	v_lshrrev_b32_e32 v9, 26, v16
	v_or_b32_e32 v20, v19, v11
	v_min_u32_e32 v35, 31, v8
	v_lshrrev_b32_e32 v8, 26, v17
	v_and_b32_e32 v16, 32, v8
	v_mul_f32_e32 v8, 0x41000000, v37
	v_rndne_f32_e32 v52, v8
	v_mul_f32_e32 v8, 4.0, v37
	v_rndne_f32_e32 v11, v8
	v_and_b32_e32 v17, 32, v9
	v_pk_add_f32 v[8:9], v[10:11], s[14:15] op_sel_hi:[1,0]
	v_cmp_nle_f32_e64 s[4:5], 2.0, v61
	s_nop 1
	v_cndmask_b32_e64 v10, v8, v65, s[4:5]
	v_add_f32_e32 v8, v37, v37
	v_cmp_nle_f32_e64 s[4:5], 2.0, v37
	v_rndne_f32_e32 v57, v8
	s_nop 0
	v_cndmask_b32_e64 v11, v9, v52, s[4:5]
	v_pk_add_f32 v[8:9], v[56:57], s[16:17] op_sel_hi:[1,0]
	v_cmp_nle_f32_e64 s[4:5], 4.0, v37
	v_min_f32_e64 v52, |v59|, s18
	s_nop 0
	v_cndmask_b32_e64 v9, v9, v11, s[4:5]
	v_cmp_nle_f32_e64 s[4:5], 4.0, v61
	v_cvt_u32_f32_e32 v9, v9
	v_or_b32_e32 v11, v35, v17
	v_cndmask_b32_e64 v8, v8, v10, s[4:5]
	v_cvt_u32_f32_e32 v8, v8
	v_or_b32_e32 v10, v15, v16
	v_min_u32_e32 v16, 31, v9
	v_lshrrev_b32_e32 v9, 26, v54
	v_min_u32_e32 v17, 31, v8
	v_lshrrev_b32_e32 v8, 26, v55
	v_and_b32_e32 v35, 32, v8
	v_mul_f32_e32 v8, 0x41000000, v52
	v_rndne_f32_e32 v53, v8
	v_mul_f32_e32 v8, 4.0, v52
	v_rndne_f32_e32 v15, v8
	v_and_b32_e32 v37, 32, v9
	v_pk_add_f32 v[8:9], v[14:15], s[14:15] op_sel_hi:[1,0]
	v_cmp_nle_f32_e64 s[4:5], 2.0, v5
	v_lshlrev_b32_e32 v10, 2, v10
	v_lshlrev_b32_e32 v11, 4, v11
	v_cndmask_b32_e64 v14, v8, v75, s[4:5]
	v_add_f32_e32 v8, v52, v52
	v_cmp_nle_f32_e64 s[4:5], 2.0, v52
	v_rndne_f32_e32 v61, v8
	s_nop 0
	v_cndmask_b32_e64 v15, v9, v53, s[4:5]
	v_pk_add_f32 v[8:9], v[60:61], s[16:17] op_sel_hi:[1,0]
	v_cmp_nle_f32_e64 s[4:5], 4.0, v52
	v_min_f32_e64 v52, |v63|, s18
	s_nop 0
	v_cndmask_b32_e64 v9, v9, v15, s[4:5]
	v_cmp_nle_f32_e64 s[4:5], 4.0, v5
	v_or_b32_e32 v15, v17, v37
	s_nop 0
	v_cndmask_b32_e64 v5, v8, v14, s[4:5]
	v_cvt_u32_f32_e32 v8, v9
	v_or_b32_e32 v14, v16, v35
	v_cvt_u32_f32_e32 v5, v5
	v_lshrrev_b32_e32 v9, 26, v58
	v_min_u32_e32 v16, 31, v8
	v_lshrrev_b32_e32 v8, 26, v59
	v_and_b32_e32 v17, 32, v8
	v_mul_f32_e32 v8, 0x41000000, v52
	v_rndne_f32_e32 v35, v8
	v_mul_f32_e32 v8, 4.0, v52
	v_rndne_f32_e32 v65, v8
	v_and_b32_e32 v37, 32, v9
	v_pk_add_f32 v[8:9], v[64:65], s[14:15] op_sel_hi:[1,0]
	v_cmp_nle_f32_e64 s[4:5], 2.0, v12
	v_min_u32_e32 v5, 31, v5
	s_nop 0
	v_cndmask_b32_e64 v53, v8, v76, s[4:5]
	v_cmp_nle_f32_e64 s[4:5], 2.0, v52
	v_add_f32_e32 v8, v52, v52
	s_nop 0
	v_cndmask_b32_e64 v54, v9, v35, s[4:5]
	v_rndne_f32_e32 v35, v8
	v_pk_add_f32 v[8:9], v[34:35], s[16:17] op_sel_hi:[1,0]
	v_cmp_nle_f32_e64 s[4:5], 4.0, v52
	v_min_f32_e64 v34, |v13|, s18
	v_mul_f32_e32 v35, 0x41000000, v34
	v_cndmask_b32_e64 v9, v9, v54, s[4:5]
	v_cmp_nle_f32_e64 s[4:5], 4.0, v12
	v_or_b32_e32 v12, v16, v17
	v_or_b32_sdwa v16, v5, v37 dst_sel:WORD_1 dst_unused:UNUSED_PAD src0_sel:DWORD src1_sel:DWORD
	v_mul_f32_e32 v37, 4.0, v34
	v_rndne_f32_e32 v37, v37
	v_cndmask_b32_e64 v8, v8, v53, s[4:5]
	v_rndne_f32_e32 v35, v35
	v_add_f32_e32 v37, 0x41000000, v37
	v_cmp_nle_f32_e64 s[4:5], 2.0, v34
	v_cvt_u32_f32_e32 v9, v9
	v_cvt_u32_f32_e32 v8, v8
	v_cndmask_b32_e64 v35, v37, v35, s[4:5]
	v_add_f32_e32 v37, v34, v34
	v_rndne_f32_e32 v37, v37
	v_add_f32_e32 v37, 0x41800000, v37
	v_cmp_nle_f32_e64 s[4:5], 4.0, v34
	v_min_u32_e32 v5, 31, v9
	v_lshrrev_b32_e32 v9, 26, v63
	v_cndmask_b32_e64 v34, v37, v35, s[4:5]
	v_cvt_u32_f32_e32 v34, v34
	v_and_b32_e32 v9, 32, v9
	v_lshrrev_b32_e32 v17, 26, v62
	v_or_b32_e32 v9, v5, v9
	v_mov_b32_e32 v5, v7
	v_min_u32_e32 v8, 31, v8
	v_and_b32_e32 v17, 32, v17
	v_pk_mul_f32 v[4:5], v[4:5], v[18:19] op_sel_hi:[1,0]
	v_or_b32_e32 v8, v8, v17
	v_min_u32_e32 v17, 31, v34
	v_lshlrev_b32_e32 v34, 4, v3
	v_and_b32_e32 v3, 0x80000000, v25
	v_min_f32_e64 v7, |v4|, s18
	v_lshl_or_b32 v25, v68, 26, v3
	v_mul_f32_e32 v3, 0x41000000, v7
	v_rndne_f32_e32 v18, v3
	v_mul_f32_e32 v3, 4.0, v7
	v_rndne_f32_e32 v3, v3
	v_pk_add_f32 v[2:3], v[2:3], s[14:15] op_sel_hi:[1,0]
	v_cmp_nle_f32_e64 s[4:5], 2.0, v44
	v_lshlrev_b32_e32 v37, 10, v49
	v_lshrrev_b32_e32 v4, 26, v4
	v_cndmask_b32_e64 v52, v2, v23, s[4:5]
	v_cmp_nle_f32_e64 s[4:5], 2.0, v7
	v_add_f32_e32 v2, v7, v7
	v_rndne_f32_e32 v23, v2
	v_cndmask_b32_e64 v18, v3, v18, s[4:5]
	v_cmp_nle_f32_e64 s[4:5], 4.0, v7
	v_min_f32_e64 v7, |v5|, s18
	v_pk_add_f32 v[2:3], v[22:23], s[16:17] op_sel_hi:[1,0]
	v_mul_f32_e32 v22, 4.0, v7
	v_cndmask_b32_e64 v3, v3, v18, s[4:5]
	v_cmp_nle_f32_e64 s[4:5], 4.0, v44
	v_mul_f32_e32 v18, 0x41000000, v7
	v_rndne_f32_e32 v22, v22
	v_cndmask_b32_e64 v2, v2, v52, s[4:5]
	v_rndne_f32_e32 v18, v18
	v_add_f32_e32 v22, 0x41000000, v22
	v_cmp_nle_f32_e64 s[4:5], 2.0, v7
	v_cvt_u32_f32_e32 v2, v2
	v_cvt_u32_f32_e32 v3, v3
	v_cndmask_b32_e64 v18, v22, v18, s[4:5]
	v_add_f32_e32 v22, v7, v7
	v_rndne_f32_e32 v22, v22
	v_add_f32_e32 v22, 0x41800000, v22
	v_cmp_nle_f32_e64 s[4:5], 4.0, v7
	v_min_u32_e32 v2, 31, v2
	v_lshrrev_b32_e32 v5, 26, v5
	v_cndmask_b32_e64 v7, v22, v18, s[4:5]
	v_cvt_u32_f32_e32 v7, v7
	v_and_or_b32 v18, v45, 32, v2
	v_and_b32_e32 v5, 32, v5
	v_lshlrev_b32_e32 v35, 6, v46
	v_min_u32_e32 v7, 31, v7
	v_or_b32_e32 v5, v7, v5
	v_lshrrev_b32_e32 v7, 2, v18
	v_or_b32_e32 v7, v34, v7
	v_min_u32_e32 v3, 31, v3
	v_and_b32_e32 v4, 32, v4
	v_or_b32_e32 v7, v7, v37
	v_lshlrev_b32_e32 v46, 12, v50
	v_lshlrev_b32_e32 v50, 22, v66
	v_or_b32_e32 v4, v3, v4
	v_or_b32_e32 v18, v35, v43
	v_or_b32_e32 v7, v7, v47
	v_lshlrev_b32_e32 v49, 18, v51
	v_lshlrev_b32_e32 v51, 2, v67
	v_or_b32_e32 v18, v18, v46
	v_or_b32_e32 v7, v7, v50
	v_lshlrev_b32_e32 v3, 28, v3
	v_lshrrev_b32_e32 v4, 4, v4
	v_or_b32_e32 v18, v18, v49
	v_or_b32_e32 v3, v7, v3
	v_or_b32_e32 v4, v4, v51
	v_lshlrev_b32_e32 v7, 8, v70
	v_or_b32_e32 v18, v18, v48
	v_lshlrev_b32_e32 v2, 30, v2
	v_or_b32_e32 v4, v4, v7
	v_lshlrev_b32_e32 v7, 14, v72
	v_or_b32_e32 v2, v18, v2
	v_lshlrev_b32_e32 v5, 6, v5
	v_or_b32_e32 v4, v4, v7
	v_lshrrev_b32_e32 v7, 4, v20
	v_lshrrev_b32_e32 v18, 2, v21
	v_or_b32_e32 v5, v5, v6
	v_lshlrev_b32_e32 v6, 12, v69
	v_or_b32_e32 v7, v7, v10
	v_or_b32_e32 v10, v18, v11
	v_lshlrev_b32_e32 v11, 8, v14
	v_or_b32_e32 v5, v5, v6
	v_lshlrev_b32_e32 v6, 18, v71
	v_lshlrev_b32_e32 v14, 10, v15
	v_or_b32_e32 v7, v7, v11
	v_lshlrev_b32_e32 v11, 14, v12
	v_or_b32_e32 v5, v5, v6
	v_lshlrev_b32_e32 v6, 20, v74
	v_or_b32_e32 v10, v10, v14
	v_or_b32_e32 v7, v7, v11
	v_lshlrev_b32_e32 v9, 20, v9
	v_or_b32_e32 v5, v5, v73
	v_or_b32_e32 v4, v4, v6
	v_lshlrev_b32_e32 v6, 30, v36
	v_or_b32_e32 v10, v10, v16
	v_lshlrev_b32_e32 v8, 22, v8
	v_or_b32_e32 v7, v7, v9
	v_and_b32_e32 v9, 0x80000000, v13
	v_or_b32_e32 v5, v5, v6
	v_or_b32_e32 v4, v4, v25
	v_lshlrev_b32_e32 v6, 28, v19
	v_or_b32_e32 v8, v10, v8
	v_lshl_or_b32 v9, v17, 26, v9
	v_or_b32_e32 v7, v7, v9
	v_or_b32_e32 v6, v8, v6
	global_store_dwordx4 v[32:33], v[2:5], off
	global_store_dwordx2 v[32:33], v[6:7], off offset:16
	s_and_saveexec_b64 s[4:5], s[0:1]
	s_cbranch_execz .LBB0_52
	v_mul_f32_e32 v4, 0x3e088889, v24
	v_lshl_add_u64 v[2:3], v[30:31], 2, s[30:31]
	v_cndmask_b32_e32 v4, 1.0, v4, vcc
	global_store_dword v[2:3], v4, off
	s_branch .LBB0_52
.LBB0_55:
	s_or_b64 exec, exec, s[8:9]
	s_load_dwordx2 s[4:5], s[12:13], 0x4
	s_load_dword s3, s[12:13], 0x14
	v_lshrrev_b32_e32 v1, 20, v0
	v_lshrrev_b32_e32 v0, 10, v0
	v_or_b32_e32 v0, v0, v1
	s_movk_i32 s0, 0x3ff
	v_and_or_b32 v0, v0, s0, v205
	v_cmp_eq_u32_e32 vcc, 0, v0
	s_waitcnt lgkmcnt(0)
	s_barrier
	s_and_saveexec_b64 s[0:1], vcc
	s_branch .LBB0_65
	buffer_wbl2 sc1
	s_waitcnt vmcnt(0)
	s_load_dwordx2 s[8:9], s[12:13], 0x58
	v_mov_b32_e32 v2, 0
	s_mov_b64 s[10:11], exec
	v_mbcnt_lo_u32_b32 v1, s10, 0
	v_mbcnt_hi_u32_b32 v1, s11, v1
	s_waitcnt lgkmcnt(0)
	global_load_dword v0, v2, s[8:9] offset:40
	v_cmp_eq_u32_e32 vcc, 0, v1
	s_and_saveexec_b64 s[12:13], vcc
	s_cbranch_execz .LBB0_58
	s_bcnt1_i32_b64 s10, s[10:11]
	v_mov_b32_e32 v3, s10
	global_atomic_add v3, v2, v3, s[8:9] offset:32 sc0

.Lgu0_start:
	s_mov_b64 exec, -1
	v_and_b32_e32 v171, 63, v205
	v_lshrrev_b32_e32 v172, 6, v205
	v_lshlrev_b32_e32 v160, 2, v171
	v_readfirstlane_b32 s68, v172
	v_and_b32_e32 v172, 7, v171
	v_lshlrev_b32_e32 v163, 3, v172
	v_mul_u32_u24_e32 v164, 24, v172
	s_nop 3
	s_lshl_b32 s17, s68, 14
	s_add_i32 s69, s93, s68
	v_lshrrev_b32_e32 v172, 3, v171
	v_lshl_add_u32 v162, v172, 2, s17
	v_add_u32_e32 v161, 0x2000, v162
	v_and_b32_e32 v172, 7, v171
	v_lshl_add_u32 v162, v172, 5, v162
	v_lshl_add_u32 v173, v171, 4, s17
	v_add_u32_e32 v175, s17, v160
	v_add_u32_e32 v174, 0x2000, v175
.Lgu0_chunk:
	s_movk_i32 s64, 0xc0
	s_lshl_b32 s65, s92, 13
	s_mov_b32 s14, 0xaaaaaaaa
	s_mov_b32 s15, 0xaaaaaaaa
	s_mov_b32 s100, 0xcccccccc
	s_mov_b32 s101, 0xcccccccc
	s_add_u32 s10, s26, 0xd800000
	s_addc_u32 s11, s27, 0
	s_lshl_b32 s17, s69, 9
	s_add_u32 s10, s10, s17
	s_addc_u32 s11, s11, 0
	s_lshl_b32 s18, s92, 11
	global_load_dword v16, v160, s[10:11]
	global_load_dword v17, v160, s[10:11] offset:256
	s_add_u32 s10, s10, s18
	s_addc_u32 s11, s11, 0
	global_load_dword v18, v160, s[10:11]
	global_load_dword v19, v160, s[10:11] offset:256
	s_add_u32 s10, s10, s18
	s_addc_u32 s11, s11, 0
	global_load_dword v20, v160, s[10:11]
	global_load_dword v21, v160, s[10:11] offset:256
	s_add_u32 s10, s10, s18
	s_addc_u32 s11, s11, 0
	global_load_dword v22, v160, s[10:11]
	global_load_dword v23, v160, s[10:11] offset:256
	s_add_u32 s10, s10, s18
	s_addc_u32 s11, s11, 0
	global_load_dword v24, v160, s[10:11]
	global_load_dword v25, v160, s[10:11] offset:256
	s_add_u32 s10, s10, s18
	s_addc_u32 s11, s11, 0
	global_load_dword v26, v160, s[10:11]
	global_load_dword v27, v160, s[10:11] offset:256
	s_add_u32 s10, s10, s18
	s_addc_u32 s11, s11, 0
	global_load_dword v28, v160, s[10:11]
	global_load_dword v29, v160, s[10:11] offset:256
	s_add_u32 s10, s10, s18
	s_addc_u32 s11, s11, 0
	global_load_dword v30, v160, s[10:11]
	global_load_dword v31, v160, s[10:11] offset:256
	s_add_u32 s10, s10, s18
	s_addc_u32 s11, s11, 0
	global_load_dword v32, v160, s[10:11]
	global_load_dword v33, v160, s[10:11] offset:256
	s_add_u32 s10, s10, s18
	s_addc_u32 s11, s11, 0
	global_load_dword v34, v160, s[10:11]
	global_load_dword v35, v160, s[10:11] offset:256
	s_add_u32 s10, s10, s18
	s_addc_u32 s11, s11, 0
	global_load_dword v36, v160, s[10:11]
	global_load_dword v37, v160, s[10:11] offset:256
	s_add_u32 s10, s10, s18
	s_addc_u32 s11, s11, 0
	global_load_dword v38, v160, s[10:11]
	global_load_dword v39, v160, s[10:11] offset:256
	s_add_u32 s10, s10, s18
	s_addc_u32 s11, s11, 0
	global_load_dword v40, v160, s[10:11]
	global_load_dword v41, v160, s[10:11] offset:256
	s_add_u32 s10, s10, s18
	s_addc_u32 s11, s11, 0
	global_load_dword v42, v160, s[10:11]
	global_load_dword v43, v160, s[10:11] offset:256
	s_add_u32 s10, s10, s18
	s_addc_u32 s11, s11, 0
	global_load_dword v44, v160, s[10:11]
	global_load_dword v45, v160, s[10:11] offset:256
	s_add_u32 s10, s10, s18
	s_addc_u32 s11, s11, 0
	global_load_dword v46, v160, s[10:11]
	global_load_dword v47, v160, s[10:11] offset:256
	s_add_u32 s10, s10, s18
	s_addc_u32 s11, s11, 0
	v_mov_b32_e32 v0, 0
	v_mov_b32_e32 v1, 0
	v_mov_b32_e32 v2, 0
	v_mov_b32_e32 v3, 0
	ds_write_b128 v173, v[0:3] offset:0
	ds_write_b128 v173, v[0:3] offset:1024
	ds_write_b128 v173, v[0:3] offset:2048
	ds_write_b128 v173, v[0:3] offset:3072
	ds_write_b128 v173, v[0:3] offset:4096
	ds_write_b128 v173, v[0:3] offset:5120
	ds_write_b128 v173, v[0:3] offset:6144
	ds_write_b128 v173, v[0:3] offset:7168
	s_waitcnt vmcnt(0)
	ds_write2st64_b32 v174, v16, v17 offset0:0 offset1:1
	ds_write2st64_b32 v174, v18, v19 offset0:2 offset1:3
	ds_write2st64_b32 v174, v20, v21 offset0:4 offset1:5
	ds_write2st64_b32 v174, v22, v23 offset0:6 offset1:7
	ds_write2st64_b32 v174, v24, v25 offset0:8 offset1:9
	ds_write2st64_b32 v174, v26, v27 offset0:10 offset1:11
	ds_write2st64_b32 v174, v28, v29 offset0:12 offset1:13
	ds_write2st64_b32 v174, v30, v31 offset0:14 offset1:15
	ds_write2st64_b32 v174, v32, v33 offset0:16 offset1:17
	ds_write2st64_b32 v174, v34, v35 offset0:18 offset1:19
	ds_write2st64_b32 v174, v36, v37 offset0:20 offset1:21
	ds_write2st64_b32 v174, v38, v39 offset0:22 offset1:23
	ds_write2st64_b32 v174, v40, v41 offset0:24 offset1:25
	ds_write2st64_b32 v174, v42, v43 offset0:26 offset1:27
	ds_write2st64_b32 v174, v44, v45 offset0:28 offset1:29
	ds_write2st64_b32 v174, v46, v47 offset0:30 offset1:31
	s_waitcnt lgkmcnt(0)
	s_add_u32 s4, s26, 0x1800000
	s_addc_u32 s5, s27, 0
	s_add_u32 s8, s26, 0x5800000
	s_addc_u32 s9, s27, 0
	s_lshl_b32 s17, s69, 11
	s_add_u32 s8, s8, s17
	s_addc_u32 s9, s9, 0
	s_mov_b32 s16, 0
	s_and_b32 s19, s16, 15
	s_lshr_b32 s50, s16, 4
	s_lshl_b32 s51, s19, 9
	s_mul_i32 s17, s19, s65
	s_lshl_b32 s18, s50, 6
	s_add_u32 s17, s17, s18
	s_add_u32 s10, s8, s17
	s_addc_u32 s11, s9, 0
	s_mul_i32 s17, s50, 0x300000
	s_add_u32 s4, s26, 0x1800000
	s_addc_u32 s5, s27, 0
	s_add_u32 s4, s4, s17
	s_addc_u32 s5, s5, 0
	v_add_u32_e32 v167, s51, v161
	ds_read2_b32 v[144:145], v167 offset0:0 offset1:8
	ds_read2_b32 v[146:147], v167 offset0:16 offset1:24
	global_load_dwordx2 v[112:113], v163, s[10:11]
	global_load_dwordx2 v[114:115], v163, s[10:11] offset:256
	global_load_dwordx2 v[116:117], v163, s[10:11] offset:512
	global_load_dwordx2 v[118:119], v163, s[10:11] offset:768
	global_load_dwordx2 v[120:121], v163, s[10:11] offset:1024
	global_load_dwordx2 v[122:123], v163, s[10:11] offset:1280
	global_load_dwordx2 v[124:125], v163, s[10:11] offset:1536
	global_load_dwordx2 v[126:127], v163, s[10:11] offset:1792
	s_waitcnt lgkmcnt(0)
	v_mad_u32_u24 v144, v144, s64, v164
	v_mad_u32_u24 v145, v145, s64, v164
	v_mad_u32_u24 v146, v146, s64, v164
	v_mad_u32_u24 v147, v147, s64, v164
	global_load_dwordx4 v[16:19], v144, s[4:5]
	global_load_dwordx2 v[20:21], v144, s[4:5] offset:16
	global_load_dwordx4 v[22:25], v145, s[4:5]
	global_load_dwordx2 v[26:27], v145, s[4:5] offset:16
	global_load_dwordx4 v[28:31], v146, s[4:5]
	global_load_dwordx2 v[32:33], v146, s[4:5] offset:16
	global_load_dwordx4 v[34:37], v147, s[4:5]
	global_load_dwordx2 v[38:39], v147, s[4:5] offset:16
	ds_read2_b32 v[176:177], v167 offset0:32 offset1:40
	ds_read2_b32 v[178:179], v167 offset0:48 offset1:56
	s_waitcnt lgkmcnt(0)
	v_mad_u32_u24 v176, v176, s64, v164
	v_mad_u32_u24 v177, v177, s64, v164
	v_mad_u32_u24 v178, v178, s64, v164
	v_mad_u32_u24 v179, v179, s64, v164
	global_load_dwordx4 v[40:43], v176, s[4:5]
	global_load_dwordx2 v[44:45], v176, s[4:5] offset:16
	global_load_dwordx4 v[46:49], v177, s[4:5]
	global_load_dwordx2 v[50:51], v177, s[4:5] offset:16
	global_load_dwordx4 v[52:55], v178, s[4:5]
	global_load_dwordx2 v[56:57], v178, s[4:5] offset:16
	global_load_dwordx4 v[58:61], v179, s[4:5]
	global_load_dwordx2 v[62:63], v179, s[4:5] offset:16
	ds_read2_b32 v[144:145], v167 offset0:64 offset1:72
	ds_read2_b32 v[146:147], v167 offset0:80 offset1:88
	s_waitcnt lgkmcnt(0)
	v_mad_u32_u24 v144, v144, s64, v164
	v_mad_u32_u24 v145, v145, s64, v164
	v_mad_u32_u24 v146, v146, s64, v164
	v_mad_u32_u24 v147, v147, s64, v164
	global_load_dwordx4 v[64:67], v144, s[4:5]
	global_load_dwordx2 v[68:69], v144, s[4:5] offset:16
	global_load_dwordx4 v[70:73], v145, s[4:5]
	global_load_dwordx2 v[74:75], v145, s[4:5] offset:16
	global_load_dwordx4 v[76:79], v146, s[4:5]
	global_load_dwordx2 v[80:81], v146, s[4:5] offset:16
	global_load_dwordx4 v[82:85], v147, s[4:5]
	global_load_dwordx2 v[86:87], v147, s[4:5] offset:16
	ds_read2_b32 v[176:177], v167 offset0:96 offset1:104
	ds_read2_b32 v[178:179], v167 offset0:112 offset1:120
	s_waitcnt lgkmcnt(0)
	v_mad_u32_u24 v176, v176, s64, v164
	v_mad_u32_u24 v177, v177, s64, v164
	v_mad_u32_u24 v178, v178, s64, v164
	v_mad_u32_u24 v179, v179, s64, v164
	global_load_dwordx4 v[88:91], v176, s[4:5]
	global_load_dwordx2 v[92:93], v176, s[4:5] offset:16
	global_load_dwordx4 v[94:97], v177, s[4:5]
	global_load_dwordx2 v[98:99], v177, s[4:5] offset:16
	global_load_dwordx4 v[100:103], v178, s[4:5]
	global_load_dwordx2 v[104:105], v178, s[4:5] offset:16
	global_load_dwordx4 v[106:109], v179, s[4:5]
	global_load_dwordx2 v[110:111], v179, s[4:5] offset:16
	s_mov_b32 s70, 1
	s_and_b32 s19, s70, 15
	s_lshr_b32 s50, s70, 4
	s_lshl_b32 s51, s19, 9
	s_mul_i32 s17, s19, s65
	s_lshl_b32 s18, s50, 6
	s_add_u32 s17, s17, s18
	s_add_u32 s12, s8, s17
	s_addc_u32 s13, s9, 0
	s_mul_i32 s17, s50, 0x300000
	s_add_u32 s4, s26, 0x1800000
	s_addc_u32 s5, s27, 0
	s_add_u32 s4, s4, s17
	s_addc_u32 s5, s5, 0
	v_add_u32_e32 v168, s51, v161
	ds_read2_b32 v[144:145], v168 offset0:0 offset1:8
	ds_read2_b32 v[146:147], v168 offset0:16 offset1:24
.Lgu0_loop:
	s_and_b32 s19, s16, 15
	s_lshl_b32 s51, s19, 9
	v_add_u32_e32 v169, s51, v162
	s_waitcnt vmcnt(30)
	v_cvt_scalef32_pk32_bf16_fp6 v[0:15], v[16:21], 1.0
	v_dot2_f32_bf16 v152, v0, v112, 0
	v_dot2_f32_bf16 v153, v1, v113, 0
	v_dot2_f32_bf16 v154, v2, v114, 0
	v_dot2_f32_bf16 v155, v3, v115, 0
	v_dot2c_f32_bf16_e32 v152, v4, v116
	v_dot2c_f32_bf16_e32 v153, v5, v117
	v_dot2c_f32_bf16_e32 v154, v6, v118
	v_dot2c_f32_bf16_e32 v155, v7, v119
	v_dot2c_f32_bf16_e32 v152, v8, v120
	v_dot2c_f32_bf16_e32 v153, v9, v121
	v_dot2c_f32_bf16_e32 v154, v10, v122
	v_dot2c_f32_bf16_e32 v155, v11, v123
	v_dot2c_f32_bf16_e32 v152, v12, v124
	v_dot2c_f32_bf16_e32 v153, v13, v125
	v_dot2c_f32_bf16_e32 v154, v14, v126
	v_dot2c_f32_bf16_e32 v155, v15, v127
	s_waitcnt vmcnt(28)
	v_cvt_scalef32_pk32_bf16_fp6 v[0:15], v[22:27], 1.0
	v_dot2_f32_bf16 v192, v0, v112, 0
	v_dot2_f32_bf16 v193, v1, v113, 0
	v_dot2_f32_bf16 v194, v2, v114, 0
	v_dot2_f32_bf16 v195, v3, v115, 0
	v_dot2c_f32_bf16_e32 v192, v4, v116
	v_dot2c_f32_bf16_e32 v193, v5, v117
	v_add_f32_e32 v156, v152, v153
	v_dot2c_f32_bf16_e32 v194, v6, v118
	v_dot2c_f32_bf16_e32 v195, v7, v119
	v_dot2c_f32_bf16_e32 v192, v8, v120
	v_add_f32_e32 v157, v154, v155
	v_dot2c_f32_bf16_e32 v193, v9, v121
	v_dot2c_f32_bf16_e32 v194, v10, v122
	v_dot2c_f32_bf16_e32 v195, v11, v123
	v_add_f32_e32 v184, v156, v157
	v_dot2c_f32_bf16_e32 v192, v12, v124
	v_dot2c_f32_bf16_e32 v193, v13, v125
	v_dot2c_f32_bf16_e32 v194, v14, v126
	v_dot2c_f32_bf16_e32 v195, v15, v127
	s_waitcnt vmcnt(26)
	v_cvt_scalef32_pk32_bf16_fp6 v[0:15], v[28:33], 1.0
	v_dot2_f32_bf16 v152, v0, v112, 0
	v_dot2_f32_bf16 v153, v1, v113, 0
	v_dot2_f32_bf16 v154, v2, v114, 0
	v_dot2_f32_bf16 v155, v3, v115, 0
	v_dot2c_f32_bf16_e32 v152, v4, v116
	v_dot2c_f32_bf16_e32 v153, v5, v117
	v_add_f32_e32 v156, v192, v193
	v_dot2c_f32_bf16_e32 v154, v6, v118
	v_dot2c_f32_bf16_e32 v155, v7, v119
	v_dot2c_f32_bf16_e32 v152, v8, v120
	v_add_f32_e32 v157, v194, v195
	v_dot2c_f32_bf16_e32 v153, v9, v121
	v_dot2c_f32_bf16_e32 v154, v10, v122
	v_dot2c_f32_bf16_e32 v155, v11, v123
	v_add_f32_e32 v185, v156, v157
	v_dot2c_f32_bf16_e32 v152, v12, v124
	v_dot2c_f32_bf16_e32 v153, v13, v125
	v_dot2c_f32_bf16_e32 v154, v14, v126
	v_dot2c_f32_bf16_e32 v155, v15, v127
	s_waitcnt vmcnt(24)
	v_cvt_scalef32_pk32_bf16_fp6 v[0:15], v[34:39], 1.0
	v_dot2_f32_bf16 v192, v0, v112, 0
	v_dot2_f32_bf16 v193, v1, v113, 0
	v_dot2_f32_bf16 v194, v2, v114, 0
	v_dot2_f32_bf16 v195, v3, v115, 0
	v_dot2c_f32_bf16_e32 v192, v4, v116
	v_dot2c_f32_bf16_e32 v193, v5, v117
	v_add_f32_e32 v156, v152, v153
	v_dot2c_f32_bf16_e32 v194, v6, v118
	v_dot2c_f32_bf16_e32 v195, v7, v119
	v_dot2c_f32_bf16_e32 v192, v8, v120
	v_add_f32_e32 v157, v154, v155
	v_dot2c_f32_bf16_e32 v193, v9, v121
	v_dot2c_f32_bf16_e32 v194, v10, v122
	v_dot2c_f32_bf16_e32 v195, v11, v123
	v_add_f32_e32 v186, v156, v157
	v_dot2c_f32_bf16_e32 v192, v12, v124
	v_dot2c_f32_bf16_e32 v193, v13, v125
	v_dot2c_f32_bf16_e32 v194, v14, v126
	v_dot2c_f32_bf16_e32 v195, v15, v127
	global_load_dwordx2 v[128:129], v163, s[12:13]
	global_load_dwordx2 v[130:131], v163, s[12:13] offset:256
	global_load_dwordx2 v[132:133], v163, s[12:13] offset:512
	global_load_dwordx2 v[134:135], v163, s[12:13] offset:768
	global_load_dwordx2 v[136:137], v163, s[12:13] offset:1024
	global_load_dwordx2 v[138:139], v163, s[12:13] offset:1280
	global_load_dwordx2 v[140:141], v163, s[12:13] offset:1536
	global_load_dwordx2 v[142:143], v163, s[12:13] offset:1792
	s_waitcnt lgkmcnt(0)
	v_mad_u32_u24 v144, v144, s64, v164
	v_mad_u32_u24 v145, v145, s64, v164
	v_mad_u32_u24 v146, v146, s64, v164
	v_mad_u32_u24 v147, v147, s64, v164
	global_load_dwordx4 v[16:19], v144, s[4:5]
	global_load_dwordx2 v[20:21], v144, s[4:5] offset:16
	global_load_dwordx4 v[22:25], v145, s[4:5]
	global_load_dwordx2 v[26:27], v145, s[4:5] offset:16
	global_load_dwordx4 v[28:31], v146, s[4:5]
	global_load_dwordx2 v[32:33], v146, s[4:5] offset:16
	global_load_dwordx4 v[34:37], v147, s[4:5]
	global_load_dwordx2 v[38:39], v147, s[4:5] offset:16
	ds_read2_b32 v[176:177], v168 offset0:32 offset1:40
	ds_read2_b32 v[178:179], v168 offset0:48 offset1:56
	s_waitcnt vmcnt(38)
	v_cvt_scalef32_pk32_bf16_fp6 v[0:15], v[40:45], 1.0
	v_dot2_f32_bf16 v152, v0, v112, 0
	v_dot2_f32_bf16 v153, v1, v113, 0
	v_dot2_f32_bf16 v154, v2, v114, 0
	v_dot2_f32_bf16 v155, v3, v115, 0
	v_dot2c_f32_bf16_e32 v152, v4, v116
	v_dot2c_f32_bf16_e32 v153, v5, v117
	v_add_f32_e32 v156, v192, v193
	v_dot2c_f32_bf16_e32 v154, v6, v118
	v_dot2c_f32_bf16_e32 v155, v7, v119
	v_dot2c_f32_bf16_e32 v152, v8, v120
	v_add_f32_e32 v157, v194, v195
	v_dot2c_f32_bf16_e32 v153, v9, v121
	v_dot2c_f32_bf16_e32 v154, v10, v122
	v_dot2c_f32_bf16_e32 v155, v11, v123
	v_add_f32_e32 v187, v156, v157
	v_dot2c_f32_bf16_e32 v152, v12, v124
	v_dot2c_f32_bf16_e32 v153, v13, v125
	v_dot2c_f32_bf16_e32 v154, v14, v126
	v_dot2c_f32_bf16_e32 v155, v15, v127
	s_waitcnt vmcnt(36)
	v_cvt_scalef32_pk32_bf16_fp6 v[0:15], v[46:51], 1.0
	v_dot2_f32_bf16 v192, v0, v112, 0
	v_dot2_f32_bf16 v193, v1, v113, 0
	v_dot2_f32_bf16 v194, v2, v114, 0
	v_dot2_f32_bf16 v195, v3, v115, 0
	v_dot2c_f32_bf16_e32 v192, v4, v116
	v_dot2c_f32_bf16_e32 v193, v5, v117
	v_add_f32_e32 v156, v152, v153
	v_dot2c_f32_bf16_e32 v194, v6, v118
	v_dot2c_f32_bf16_e32 v195, v7, v119
	v_dot2c_f32_bf16_e32 v192, v8, v120
	v_add_f32_e32 v157, v154, v155
	v_dot2c_f32_bf16_e32 v193, v9, v121
	v_dot2c_f32_bf16_e32 v194, v10, v122
	v_dot2c_f32_bf16_e32 v195, v11, v123
	v_add_f32_e32 v188, v156, v157
	v_dot2c_f32_bf16_e32 v192, v12, v124
	v_dot2c_f32_bf16_e32 v193, v13, v125
	v_dot2c_f32_bf16_e32 v194, v14, v126
	v_dot2c_f32_bf16_e32 v195, v15, v127
	s_waitcnt vmcnt(34)
	v_cvt_scalef32_pk32_bf16_fp6 v[0:15], v[52:57], 1.0
	v_dot2_f32_bf16 v152, v0, v112, 0
	v_dot2_f32_bf16 v153, v1, v113, 0
	v_dot2_f32_bf16 v154, v2, v114, 0
	v_dot2_f32_bf16 v155, v3, v115, 0
	v_dot2c_f32_bf16_e32 v152, v4, v116
	v_dot2c_f32_bf16_e32 v153, v5, v117
	v_add_f32_e32 v156, v192, v193
	v_dot2c_f32_bf16_e32 v154, v6, v118
	v_dot2c_f32_bf16_e32 v155, v7, v119
	v_dot2c_f32_bf16_e32 v152, v8, v120
	v_add_f32_e32 v157, v194, v195
	v_dot2c_f32_bf16_e32 v153, v9, v121
	v_dot2c_f32_bf16_e32 v154, v10, v122
	v_dot2c_f32_bf16_e32 v155, v11, v123
	v_add_f32_e32 v189, v156, v157
	v_dot2c_f32_bf16_e32 v152, v12, v124
	v_dot2c_f32_bf16_e32 v153, v13, v125
	v_dot2c_f32_bf16_e32 v154, v14, v126
	v_dot2c_f32_bf16_e32 v155, v15, v127
	s_waitcnt vmcnt(32)
	v_cvt_scalef32_pk32_bf16_fp6 v[0:15], v[58:63], 1.0
	v_dot2_f32_bf16 v192, v0, v112, 0
	v_dot2_f32_bf16 v193, v1, v113, 0
	v_dot2_f32_bf16 v194, v2, v114, 0
	v_dot2_f32_bf16 v195, v3, v115, 0
	v_dot2c_f32_bf16_e32 v192, v4, v116
	v_dot2c_f32_bf16_e32 v193, v5, v117
	v_add_f32_e32 v156, v152, v153
	v_dot2c_f32_bf16_e32 v194, v6, v118
	v_dot2c_f32_bf16_e32 v195, v7, v119
	v_dot2c_f32_bf16_e32 v192, v8, v120
	v_add_f32_e32 v157, v154, v155
	v_dot2c_f32_bf16_e32 v193, v9, v121
	v_dot2c_f32_bf16_e32 v194, v10, v122
	v_dot2c_f32_bf16_e32 v195, v11, v123
	v_add_f32_e32 v190, v156, v157
	v_dot2c_f32_bf16_e32 v192, v12, v124
	v_dot2c_f32_bf16_e32 v193, v13, v125
	v_dot2c_f32_bf16_e32 v194, v14, v126
	v_dot2c_f32_bf16_e32 v195, v15, v127
	s_nop 1
	v_add_f32_e32 v156, v192, v193
	v_add_f32_e32 v157, v194, v195
	v_add_f32_e32 v191, v156, v157
	v_add_f32_dpp v184, v184, v184 row_half_mirror row_mask:0xf bank_mask:0x5
	v_add_f32_dpp v185, v185, v185 row_half_mirror row_mask:0xf bank_mask:0x5
	v_add_f32_dpp v186, v186, v186 row_half_mirror row_mask:0xf bank_mask:0x5
	v_add_f32_dpp v187, v187, v187 row_half_mirror row_mask:0xf bank_mask:0x5
	v_add_f32_dpp v184, v188, v188 row_half_mirror row_mask:0xf bank_mask:0xa
	v_add_f32_dpp v185, v189, v189 row_half_mirror row_mask:0xf bank_mask:0xa
	v_add_f32_dpp v186, v190, v190 row_half_mirror row_mask:0xf bank_mask:0xa
	v_add_f32_dpp v187, v191, v191 row_half_mirror row_mask:0xf bank_mask:0xa
	v_add_f32_dpp v184, v184, v184 quad_perm:[1,0,3,2] row_mask:0xf bank_mask:0xf
	v_add_f32_dpp v185, v185, v185 quad_perm:[1,0,3,2] row_mask:0xf bank_mask:0xf
	v_add_f32_dpp v186, v186, v186 quad_perm:[1,0,3,2] row_mask:0xf bank_mask:0xf
	v_add_f32_dpp v187, v187, v187 quad_perm:[1,0,3,2] row_mask:0xf bank_mask:0xf
	v_add_f32_dpp v184, v184, v184 quad_perm:[2,3,0,1] row_mask:0xf bank_mask:0xf
	v_add_f32_dpp v185, v185, v185 quad_perm:[2,3,0,1] row_mask:0xf bank_mask:0xf
	v_add_f32_dpp v186, v186, v186 quad_perm:[2,3,0,1] row_mask:0xf bank_mask:0xf
	v_add_f32_dpp v187, v187, v187 quad_perm:[2,3,0,1] row_mask:0xf bank_mask:0xf
	v_cndmask_b32_e64 v156, v184, v185, s[14:15]
	v_cndmask_b32_e64 v157, v186, v187, s[14:15]
	v_cndmask_b32_e64 v198, v156, v157, s[100:101]
	s_waitcnt lgkmcnt(0)
	v_mad_u32_u24 v176, v176, s64, v164
	v_mad_u32_u24 v177, v177, s64, v164
	v_mad_u32_u24 v178, v178, s64, v164
	v_mad_u32_u24 v179, v179, s64, v164
	global_load_dwordx4 v[40:43], v176, s[4:5]
	global_load_dwordx2 v[44:45], v176, s[4:5] offset:16
	global_load_dwordx4 v[46:49], v177, s[4:5]
	global_load_dwordx2 v[50:51], v177, s[4:5] offset:16
	global_load_dwordx4 v[52:55], v178, s[4:5]
	global_load_dwordx2 v[56:57], v178, s[4:5] offset:16
	global_load_dwordx4 v[58:61], v179, s[4:5]
	global_load_dwordx2 v[62:63], v179, s[4:5] offset:16
	ds_add_f32 v169, v198 offset:0
	ds_read2_b32 v[144:145], v168 offset0:64 offset1:72
	ds_read2_b32 v[146:147], v168 offset0:80 offset1:88
	s_waitcnt vmcnt(38)
	v_cvt_scalef32_pk32_bf16_fp6 v[0:15], v[64:69], 1.0
	v_dot2_f32_bf16 v152, v0, v112, 0
	v_dot2_f32_bf16 v153, v1, v113, 0
	v_dot2_f32_bf16 v154, v2, v114, 0
	v_dot2_f32_bf16 v155, v3, v115, 0
	v_dot2c_f32_bf16_e32 v152, v4, v116
	v_dot2c_f32_bf16_e32 v153, v5, v117
	v_dot2c_f32_bf16_e32 v154, v6, v118
	v_dot2c_f32_bf16_e32 v155, v7, v119
	v_dot2c_f32_bf16_e32 v152, v8, v120
	v_dot2c_f32_bf16_e32 v153, v9, v121
	v_dot2c_f32_bf16_e32 v154, v10, v122
	v_dot2c_f32_bf16_e32 v155, v11, v123
	v_dot2c_f32_bf16_e32 v152, v12, v124
	v_dot2c_f32_bf16_e32 v153, v13, v125
	v_dot2c_f32_bf16_e32 v154, v14, v126
	v_dot2c_f32_bf16_e32 v155, v15, v127
	s_waitcnt vmcnt(36)
	v_cvt_scalef32_pk32_bf16_fp6 v[0:15], v[70:75], 1.0
	v_dot2_f32_bf16 v192, v0, v112, 0
	v_dot2_f32_bf16 v193, v1, v113, 0
	v_dot2_f32_bf16 v194, v2, v114, 0
	v_dot2_f32_bf16 v195, v3, v115, 0
	v_dot2c_f32_bf16_e32 v192, v4, v116
	v_dot2c_f32_bf16_e32 v193, v5, v117
	v_add_f32_e32 v156, v152, v153
	v_dot2c_f32_bf16_e32 v194, v6, v118
	v_dot2c_f32_bf16_e32 v195, v7, v119
	v_dot2c_f32_bf16_e32 v192, v8, v120
	v_add_f32_e32 v157, v154, v155
	v_dot2c_f32_bf16_e32 v193, v9, v121
	v_dot2c_f32_bf16_e32 v194, v10, v122
	v_dot2c_f32_bf16_e32 v195, v11, v123
	v_add_f32_e32 v184, v156, v157
	v_dot2c_f32_bf16_e32 v192, v12, v124
	v_dot2c_f32_bf16_e32 v193, v13, v125
	v_dot2c_f32_bf16_e32 v194, v14, v126
	v_dot2c_f32_bf16_e32 v195, v15, v127
	s_waitcnt vmcnt(34)
	v_cvt_scalef32_pk32_bf16_fp6 v[0:15], v[76:81], 1.0
	v_dot2_f32_bf16 v152, v0, v112, 0
	v_dot2_f32_bf16 v153, v1, v113, 0
	v_dot2_f32_bf16 v154, v2, v114, 0
	v_dot2_f32_bf16 v155, v3, v115, 0
	v_dot2c_f32_bf16_e32 v152, v4, v116
	v_dot2c_f32_bf16_e32 v153, v5, v117
	v_add_f32_e32 v156, v192, v193
	v_dot2c_f32_bf16_e32 v154, v6, v118
	v_dot2c_f32_bf16_e32 v155, v7, v119
	v_dot2c_f32_bf16_e32 v152, v8, v120
	v_add_f32_e32 v157, v194, v195
	v_dot2c_f32_bf16_e32 v153, v9, v121
	v_dot2c_f32_bf16_e32 v154, v10, v122
	v_dot2c_f32_bf16_e32 v155, v11, v123
	v_add_f32_e32 v185, v156, v157
	v_dot2c_f32_bf16_e32 v152, v12, v124
	v_dot2c_f32_bf16_e32 v153, v13, v125
	v_dot2c_f32_bf16_e32 v154, v14, v126
	v_dot2c_f32_bf16_e32 v155, v15, v127
	s_waitcnt vmcnt(32)
	v_cvt_scalef32_pk32_bf16_fp6 v[0:15], v[82:87], 1.0
	v_dot2_f32_bf16 v192, v0, v112, 0
	v_dot2_f32_bf16 v193, v1, v113, 0
	v_dot2_f32_bf16 v194, v2, v114, 0
	v_dot2_f32_bf16 v195, v3, v115, 0
	v_dot2c_f32_bf16_e32 v192, v4, v116
	v_dot2c_f32_bf16_e32 v193, v5, v117
	v_add_f32_e32 v156, v152, v153
	v_dot2c_f32_bf16_e32 v194, v6, v118
	v_dot2c_f32_bf16_e32 v195, v7, v119
	v_dot2c_f32_bf16_e32 v192, v8, v120
	v_add_f32_e32 v157, v154, v155
	v_dot2c_f32_bf16_e32 v193, v9, v121
	v_dot2c_f32_bf16_e32 v194, v10, v122
	v_dot2c_f32_bf16_e32 v195, v11, v123
	v_add_f32_e32 v186, v156, v157
	v_dot2c_f32_bf16_e32 v192, v12, v124
	v_dot2c_f32_bf16_e32 v193, v13, v125
	v_dot2c_f32_bf16_e32 v194, v14, v126
	v_dot2c_f32_bf16_e32 v195, v15, v127
	s_waitcnt lgkmcnt(0)
	v_mad_u32_u24 v144, v144, s64, v164
	v_mad_u32_u24 v145, v145, s64, v164
	v_mad_u32_u24 v146, v146, s64, v164
	v_mad_u32_u24 v147, v147, s64, v164
	global_load_dwordx4 v[64:67], v144, s[4:5]
	global_load_dwordx2 v[68:69], v144, s[4:5] offset:16
	global_load_dwordx4 v[70:73], v145, s[4:5]
	global_load_dwordx2 v[74:75], v145, s[4:5] offset:16
	global_load_dwordx4 v[76:79], v146, s[4:5]
	global_load_dwordx2 v[80:81], v146, s[4:5] offset:16
	global_load_dwordx4 v[82:85], v147, s[4:5]
	global_load_dwordx2 v[86:87], v147, s[4:5] offset:16
	ds_read2_b32 v[176:177], v168 offset0:96 offset1:104
	ds_read2_b32 v[178:179], v168 offset0:112 offset1:120
	s_waitcnt vmcnt(38)
	v_cvt_scalef32_pk32_bf16_fp6 v[0:15], v[88:93], 1.0
	v_dot2_f32_bf16 v152, v0, v112, 0
	v_dot2_f32_bf16 v153, v1, v113, 0
	v_dot2_f32_bf16 v154, v2, v114, 0
	v_dot2_f32_bf16 v155, v3, v115, 0
	v_dot2c_f32_bf16_e32 v152, v4, v116
	v_dot2c_f32_bf16_e32 v153, v5, v117
	v_add_f32_e32 v156, v192, v193
	v_dot2c_f32_bf16_e32 v154, v6, v118
	v_dot2c_f32_bf16_e32 v155, v7, v119
	v_dot2c_f32_bf16_e32 v152, v8, v120
	v_add_f32_e32 v157, v194, v195
	v_dot2c_f32_bf16_e32 v153, v9, v121
	v_dot2c_f32_bf16_e32 v154, v10, v122
	v_dot2c_f32_bf16_e32 v155, v11, v123
	v_add_f32_e32 v187, v156, v157
	v_dot2c_f32_bf16_e32 v152, v12, v124
	v_dot2c_f32_bf16_e32 v153, v13, v125
	v_dot2c_f32_bf16_e32 v154, v14, v126
	v_dot2c_f32_bf16_e32 v155, v15, v127
	s_waitcnt vmcnt(36)
	v_cvt_scalef32_pk32_bf16_fp6 v[0:15], v[94:99], 1.0
	v_dot2_f32_bf16 v192, v0, v112, 0
	v_dot2_f32_bf16 v193, v1, v113, 0
	v_dot2_f32_bf16 v194, v2, v114, 0
	v_dot2_f32_bf16 v195, v3, v115, 0
	v_dot2c_f32_bf16_e32 v192, v4, v116
	v_dot2c_f32_bf16_e32 v193, v5, v117
	v_add_f32_e32 v156, v152, v153
	v_dot2c_f32_bf16_e32 v194, v6, v118
	v_dot2c_f32_bf16_e32 v195, v7, v119
	v_dot2c_f32_bf16_e32 v192, v8, v120
	v_add_f32_e32 v157, v154, v155
	v_dot2c_f32_bf16_e32 v193, v9, v121
	v_dot2c_f32_bf16_e32 v194, v10, v122
	v_dot2c_f32_bf16_e32 v195, v11, v123
	v_add_f32_e32 v188, v156, v157
	v_dot2c_f32_bf16_e32 v192, v12, v124
	v_dot2c_f32_bf16_e32 v193, v13, v125
	v_dot2c_f32_bf16_e32 v194, v14, v126
	v_dot2c_f32_bf16_e32 v195, v15, v127
	s_waitcnt vmcnt(34)
	v_cvt_scalef32_pk32_bf16_fp6 v[0:15], v[100:105], 1.0
	v_dot2_f32_bf16 v152, v0, v112, 0
	v_dot2_f32_bf16 v153, v1, v113, 0
	v_dot2_f32_bf16 v154, v2, v114, 0
	v_dot2_f32_bf16 v155, v3, v115, 0
	v_dot2c_f32_bf16_e32 v152, v4, v116
	v_dot2c_f32_bf16_e32 v153, v5, v117
	v_add_f32_e32 v156, v192, v193
	v_dot2c_f32_bf16_e32 v154, v6, v118
	v_dot2c_f32_bf16_e32 v155, v7, v119
	v_dot2c_f32_bf16_e32 v152, v8, v120
	v_add_f32_e32 v157, v194, v195
	v_dot2c_f32_bf16_e32 v153, v9, v121
	v_dot2c_f32_bf16_e32 v154, v10, v122
	v_dot2c_f32_bf16_e32 v155, v11, v123
	v_add_f32_e32 v189, v156, v157
	v_dot2c_f32_bf16_e32 v152, v12, v124
	v_dot2c_f32_bf16_e32 v153, v13, v125
	v_dot2c_f32_bf16_e32 v154, v14, v126
	v_dot2c_f32_bf16_e32 v155, v15, v127
	s_waitcnt vmcnt(32)
	v_cvt_scalef32_pk32_bf16_fp6 v[0:15], v[106:111], 1.0
	v_dot2_f32_bf16 v192, v0, v112, 0
	v_dot2_f32_bf16 v193, v1, v113, 0
	v_dot2_f32_bf16 v194, v2, v114, 0
	v_dot2_f32_bf16 v195, v3, v115, 0
	v_dot2c_f32_bf16_e32 v192, v4, v116
	v_dot2c_f32_bf16_e32 v193, v5, v117
	v_add_f32_e32 v156, v152, v153
	v_dot2c_f32_bf16_e32 v194, v6, v118
	v_dot2c_f32_bf16_e32 v195, v7, v119
	v_dot2c_f32_bf16_e32 v192, v8, v120
	v_add_f32_e32 v157, v154, v155
	v_dot2c_f32_bf16_e32 v193, v9, v121
	v_dot2c_f32_bf16_e32 v194, v10, v122
	v_dot2c_f32_bf16_e32 v195, v11, v123
	v_add_f32_e32 v190, v156, v157
	v_dot2c_f32_bf16_e32 v192, v12, v124
	v_dot2c_f32_bf16_e32 v193, v13, v125
	v_dot2c_f32_bf16_e32 v194, v14, v126
	v_dot2c_f32_bf16_e32 v195, v15, v127
	s_nop 1
	v_add_f32_e32 v156, v192, v193
	v_add_f32_e32 v157, v194, v195
	v_add_f32_e32 v191, v156, v157
	v_add_f32_dpp v184, v184, v184 row_half_mirror row_mask:0xf bank_mask:0x5
	v_add_f32_dpp v185, v185, v185 row_half_mirror row_mask:0xf bank_mask:0x5
	v_add_f32_dpp v186, v186, v186 row_half_mirror row_mask:0xf bank_mask:0x5
	v_add_f32_dpp v187, v187, v187 row_half_mirror row_mask:0xf bank_mask:0x5
	v_add_f32_dpp v184, v188, v188 row_half_mirror row_mask:0xf bank_mask:0xa
	v_add_f32_dpp v185, v189, v189 row_half_mirror row_mask:0xf bank_mask:0xa
	v_add_f32_dpp v186, v190, v190 row_half_mirror row_mask:0xf bank_mask:0xa
	v_add_f32_dpp v187, v191, v191 row_half_mirror row_mask:0xf bank_mask:0xa
	v_add_f32_dpp v184, v184, v184 quad_perm:[1,0,3,2] row_mask:0xf bank_mask:0xf
	v_add_f32_dpp v185, v185, v185 quad_perm:[1,0,3,2] row_mask:0xf bank_mask:0xf
	v_add_f32_dpp v186, v186, v186 quad_perm:[1,0,3,2] row_mask:0xf bank_mask:0xf
	v_add_f32_dpp v187, v187, v187 quad_perm:[1,0,3,2] row_mask:0xf bank_mask:0xf
	v_add_f32_dpp v184, v184, v184 quad_perm:[2,3,0,1] row_mask:0xf bank_mask:0xf
	v_add_f32_dpp v185, v185, v185 quad_perm:[2,3,0,1] row_mask:0xf bank_mask:0xf
	v_add_f32_dpp v186, v186, v186 quad_perm:[2,3,0,1] row_mask:0xf bank_mask:0xf
	v_add_f32_dpp v187, v187, v187 quad_perm:[2,3,0,1] row_mask:0xf bank_mask:0xf
	v_cndmask_b32_e64 v156, v184, v185, s[14:15]
	v_cndmask_b32_e64 v157, v186, v187, s[14:15]
	v_cndmask_b32_e64 v198, v156, v157, s[100:101]
	s_waitcnt lgkmcnt(0)
	v_mad_u32_u24 v176, v176, s64, v164
	v_mad_u32_u24 v177, v177, s64, v164
	v_mad_u32_u24 v178, v178, s64, v164
	v_mad_u32_u24 v179, v179, s64, v164
	global_load_dwordx4 v[88:91], v176, s[4:5]
	global_load_dwordx2 v[92:93], v176, s[4:5] offset:16
	global_load_dwordx4 v[94:97], v177, s[4:5]
	global_load_dwordx2 v[98:99], v177, s[4:5] offset:16
	global_load_dwordx4 v[100:103], v178, s[4:5]
	global_load_dwordx2 v[104:105], v178, s[4:5] offset:16
	global_load_dwordx4 v[106:109], v179, s[4:5]
	global_load_dwordx2 v[110:111], v179, s[4:5] offset:16
	ds_add_f32 v169, v198 offset:256
	s_add_u32 s16, s16, 1
	s_and_b32 s16, s16, 63
	s_add_u32 s18, s16, 1
	s_and_b32 s70, s18, 63
	s_and_b32 s19, s70, 15
	s_lshr_b32 s50, s70, 4
	s_lshl_b32 s51, s19, 9
	s_mul_i32 s17, s19, s65
	s_lshl_b32 s18, s50, 6
	s_add_u32 s17, s17, s18
	s_add_u32 s10, s8, s17
	s_addc_u32 s11, s9, 0
	s_mul_i32 s17, s50, 0x300000
	s_add_u32 s4, s26, 0x1800000
	s_addc_u32 s5, s27, 0
	s_add_u32 s4, s4, s17
	s_addc_u32 s5, s5, 0
	v_add_u32_e32 v167, s51, v161
	ds_read2_b32 v[144:145], v167 offset0:0 offset1:8
	ds_read2_b32 v[146:147], v167 offset0:16 offset1:24
	s_and_b32 s19, s16, 15
	s_lshl_b32 s51, s19, 9
	v_add_u32_e32 v170, s51, v162
	s_waitcnt vmcnt(30)
	v_cvt_scalef32_pk32_bf16_fp6 v[0:15], v[16:21], 1.0
	v_dot2_f32_bf16 v152, v0, v128, 0
	v_dot2_f32_bf16 v153, v1, v129, 0
	v_dot2_f32_bf16 v154, v2, v130, 0
	v_dot2_f32_bf16 v155, v3, v131, 0
	v_dot2c_f32_bf16_e32 v152, v4, v132
	v_dot2c_f32_bf16_e32 v153, v5, v133
	v_dot2c_f32_bf16_e32 v154, v6, v134
	v_dot2c_f32_bf16_e32 v155, v7, v135
	v_dot2c_f32_bf16_e32 v152, v8, v136
	v_dot2c_f32_bf16_e32 v153, v9, v137
	v_dot2c_f32_bf16_e32 v154, v10, v138
	v_dot2c_f32_bf16_e32 v155, v11, v139
	v_dot2c_f32_bf16_e32 v152, v12, v140
	v_dot2c_f32_bf16_e32 v153, v13, v141
	v_dot2c_f32_bf16_e32 v154, v14, v142
	v_dot2c_f32_bf16_e32 v155, v15, v143
	s_waitcnt vmcnt(28)
	v_cvt_scalef32_pk32_bf16_fp6 v[0:15], v[22:27], 1.0
	v_dot2_f32_bf16 v192, v0, v128, 0
	v_dot2_f32_bf16 v193, v1, v129, 0
	v_dot2_f32_bf16 v194, v2, v130, 0
	v_dot2_f32_bf16 v195, v3, v131, 0
	v_dot2c_f32_bf16_e32 v192, v4, v132
	v_dot2c_f32_bf16_e32 v193, v5, v133
	v_add_f32_e32 v156, v152, v153
	v_dot2c_f32_bf16_e32 v194, v6, v134
	v_dot2c_f32_bf16_e32 v195, v7, v135
	v_dot2c_f32_bf16_e32 v192, v8, v136
	v_add_f32_e32 v157, v154, v155
	v_dot2c_f32_bf16_e32 v193, v9, v137
	v_dot2c_f32_bf16_e32 v194, v10, v138
	v_dot2c_f32_bf16_e32 v195, v11, v139
	v_add_f32_e32 v184, v156, v157
	v_dot2c_f32_bf16_e32 v192, v12, v140
	v_dot2c_f32_bf16_e32 v193, v13, v141
	v_dot2c_f32_bf16_e32 v194, v14, v142
	v_dot2c_f32_bf16_e32 v195, v15, v143
	s_waitcnt vmcnt(26)
	v_cvt_scalef32_pk32_bf16_fp6 v[0:15], v[28:33], 1.0
	v_dot2_f32_bf16 v152, v0, v128, 0
	v_dot2_f32_bf16 v153, v1, v129, 0
	v_dot2_f32_bf16 v154, v2, v130, 0
	v_dot2_f32_bf16 v155, v3, v131, 0
	v_dot2c_f32_bf16_e32 v152, v4, v132
	v_dot2c_f32_bf16_e32 v153, v5, v133
	v_add_f32_e32 v156, v192, v193
	v_dot2c_f32_bf16_e32 v154, v6, v134
	v_dot2c_f32_bf16_e32 v155, v7, v135
	v_dot2c_f32_bf16_e32 v152, v8, v136
	v_add_f32_e32 v157, v194, v195
	v_dot2c_f32_bf16_e32 v153, v9, v137
	v_dot2c_f32_bf16_e32 v154, v10, v138
	v_dot2c_f32_bf16_e32 v155, v11, v139
	v_add_f32_e32 v185, v156, v157
	v_dot2c_f32_bf16_e32 v152, v12, v140
	v_dot2c_f32_bf16_e32 v153, v13, v141
	v_dot2c_f32_bf16_e32 v154, v14, v142
	v_dot2c_f32_bf16_e32 v155, v15, v143
	s_waitcnt vmcnt(24)
	v_cvt_scalef32_pk32_bf16_fp6 v[0:15], v[34:39], 1.0
	v_dot2_f32_bf16 v192, v0, v128, 0
	v_dot2_f32_bf16 v193, v1, v129, 0
	v_dot2_f32_bf16 v194, v2, v130, 0
	v_dot2_f32_bf16 v195, v3, v131, 0
	v_dot2c_f32_bf16_e32 v192, v4, v132
	v_dot2c_f32_bf16_e32 v193, v5, v133
	v_add_f32_e32 v156, v152, v153
	v_dot2c_f32_bf16_e32 v194, v6, v134
	v_dot2c_f32_bf16_e32 v195, v7, v135
	v_dot2c_f32_bf16_e32 v192, v8, v136
	v_add_f32_e32 v157, v154, v155
	v_dot2c_f32_bf16_e32 v193, v9, v137
	v_dot2c_f32_bf16_e32 v194, v10, v138
	v_dot2c_f32_bf16_e32 v195, v11, v139
	v_add_f32_e32 v186, v156, v157
	v_dot2c_f32_bf16_e32 v192, v12, v140
	v_dot2c_f32_bf16_e32 v193, v13, v141
	v_dot2c_f32_bf16_e32 v194, v14, v142
	v_dot2c_f32_bf16_e32 v195, v15, v143
	global_load_dwordx2 v[112:113], v163, s[10:11]
	global_load_dwordx2 v[114:115], v163, s[10:11] offset:256
	global_load_dwordx2 v[116:117], v163, s[10:11] offset:512
	global_load_dwordx2 v[118:119], v163, s[10:11] offset:768
	global_load_dwordx2 v[120:121], v163, s[10:11] offset:1024
	global_load_dwordx2 v[122:123], v163, s[10:11] offset:1280
	global_load_dwordx2 v[124:125], v163, s[10:11] offset:1536
	global_load_dwordx2 v[126:127], v163, s[10:11] offset:1792
	s_waitcnt lgkmcnt(0)
	v_mad_u32_u24 v144, v144, s64, v164
	v_mad_u32_u24 v145, v145, s64, v164
	v_mad_u32_u24 v146, v146, s64, v164
	v_mad_u32_u24 v147, v147, s64, v164
	global_load_dwordx4 v[16:19], v144, s[4:5]
	global_load_dwordx2 v[20:21], v144, s[4:5] offset:16
	global_load_dwordx4 v[22:25], v145, s[4:5]
	global_load_dwordx2 v[26:27], v145, s[4:5] offset:16
	global_load_dwordx4 v[28:31], v146, s[4:5]
	global_load_dwordx2 v[32:33], v146, s[4:5] offset:16
	global_load_dwordx4 v[34:37], v147, s[4:5]
	global_load_dwordx2 v[38:39], v147, s[4:5] offset:16
	ds_read2_b32 v[176:177], v167 offset0:32 offset1:40
	ds_read2_b32 v[178:179], v167 offset0:48 offset1:56
	s_waitcnt vmcnt(38)
	v_cvt_scalef32_pk32_bf16_fp6 v[0:15], v[40:45], 1.0
	v_dot2_f32_bf16 v152, v0, v128, 0
	v_dot2_f32_bf16 v153, v1, v129, 0
	v_dot2_f32_bf16 v154, v2, v130, 0
	v_dot2_f32_bf16 v155, v3, v131, 0
	v_dot2c_f32_bf16_e32 v152, v4, v132
	v_dot2c_f32_bf16_e32 v153, v5, v133
	v_add_f32_e32 v156, v192, v193
	v_dot2c_f32_bf16_e32 v154, v6, v134
	v_dot2c_f32_bf16_e32 v155, v7, v135
	v_dot2c_f32_bf16_e32 v152, v8, v136
	v_add_f32_e32 v157, v194, v195
	v_dot2c_f32_bf16_e32 v153, v9, v137
	v_dot2c_f32_bf16_e32 v154, v10, v138
	v_dot2c_f32_bf16_e32 v155, v11, v139
	v_add_f32_e32 v187, v156, v157
	v_dot2c_f32_bf16_e32 v152, v12, v140
	v_dot2c_f32_bf16_e32 v153, v13, v141
	v_dot2c_f32_bf16_e32 v154, v14, v142
	v_dot2c_f32_bf16_e32 v155, v15, v143
	s_waitcnt vmcnt(36)
	v_cvt_scalef32_pk32_bf16_fp6 v[0:15], v[46:51], 1.0
	v_dot2_f32_bf16 v192, v0, v128, 0
	v_dot2_f32_bf16 v193, v1, v129, 0
	v_dot2_f32_bf16 v194, v2, v130, 0
	v_dot2_f32_bf16 v195, v3, v131, 0
	v_dot2c_f32_bf16_e32 v192, v4, v132
	v_dot2c_f32_bf16_e32 v193, v5, v133
	v_add_f32_e32 v156, v152, v153
	v_dot2c_f32_bf16_e32 v194, v6, v134
	v_dot2c_f32_bf16_e32 v195, v7, v135
	v_dot2c_f32_bf16_e32 v192, v8, v136
	v_add_f32_e32 v157, v154, v155
	v_dot2c_f32_bf16_e32 v193, v9, v137
	v_dot2c_f32_bf16_e32 v194, v10, v138
	v_dot2c_f32_bf16_e32 v195, v11, v139
	v_add_f32_e32 v188, v156, v157
	v_dot2c_f32_bf16_e32 v192, v12, v140
	v_dot2c_f32_bf16_e32 v193, v13, v141
	v_dot2c_f32_bf16_e32 v194, v14, v142
	v_dot2c_f32_bf16_e32 v195, v15, v143
	s_waitcnt vmcnt(34)
	v_cvt_scalef32_pk32_bf16_fp6 v[0:15], v[52:57], 1.0
	v_dot2_f32_bf16 v152, v0, v128, 0
	v_dot2_f32_bf16 v153, v1, v129, 0
	v_dot2_f32_bf16 v154, v2, v130, 0
	v_dot2_f32_bf16 v155, v3, v131, 0
	v_dot2c_f32_bf16_e32 v152, v4, v132
	v_dot2c_f32_bf16_e32 v153, v5, v133
	v_add_f32_e32 v156, v192, v193
	v_dot2c_f32_bf16_e32 v154, v6, v134
	v_dot2c_f32_bf16_e32 v155, v7, v135
	v_dot2c_f32_bf16_e32 v152, v8, v136
	v_add_f32_e32 v157, v194, v195
	v_dot2c_f32_bf16_e32 v153, v9, v137
	v_dot2c_f32_bf16_e32 v154, v10, v138
	v_dot2c_f32_bf16_e32 v155, v11, v139
	v_add_f32_e32 v189, v156, v157
	v_dot2c_f32_bf16_e32 v152, v12, v140
	v_dot2c_f32_bf16_e32 v153, v13, v141
	v_dot2c_f32_bf16_e32 v154, v14, v142
	v_dot2c_f32_bf16_e32 v155, v15, v143
	s_waitcnt vmcnt(32)
	v_cvt_scalef32_pk32_bf16_fp6 v[0:15], v[58:63], 1.0
	v_dot2_f32_bf16 v192, v0, v128, 0
	v_dot2_f32_bf16 v193, v1, v129, 0
	v_dot2_f32_bf16 v194, v2, v130, 0
	v_dot2_f32_bf16 v195, v3, v131, 0
	v_dot2c_f32_bf16_e32 v192, v4, v132
	v_dot2c_f32_bf16_e32 v193, v5, v133
	v_add_f32_e32 v156, v152, v153
	v_dot2c_f32_bf16_e32 v194, v6, v134
	v_dot2c_f32_bf16_e32 v195, v7, v135
	v_dot2c_f32_bf16_e32 v192, v8, v136
	v_add_f32_e32 v157, v154, v155
	v_dot2c_f32_bf16_e32 v193, v9, v137
	v_dot2c_f32_bf16_e32 v194, v10, v138
	v_dot2c_f32_bf16_e32 v195, v11, v139
	v_add_f32_e32 v190, v156, v157
	v_dot2c_f32_bf16_e32 v192, v12, v140
	v_dot2c_f32_bf16_e32 v193, v13, v141
	v_dot2c_f32_bf16_e32 v194, v14, v142
	v_dot2c_f32_bf16_e32 v195, v15, v143
	s_nop 1
	v_add_f32_e32 v156, v192, v193
	v_add_f32_e32 v157, v194, v195
	v_add_f32_e32 v191, v156, v157
	v_add_f32_dpp v184, v184, v184 row_half_mirror row_mask:0xf bank_mask:0x5
	v_add_f32_dpp v185, v185, v185 row_half_mirror row_mask:0xf bank_mask:0x5
	v_add_f32_dpp v186, v186, v186 row_half_mirror row_mask:0xf bank_mask:0x5
	v_add_f32_dpp v187, v187, v187 row_half_mirror row_mask:0xf bank_mask:0x5
	v_add_f32_dpp v184, v188, v188 row_half_mirror row_mask:0xf bank_mask:0xa
	v_add_f32_dpp v185, v189, v189 row_half_mirror row_mask:0xf bank_mask:0xa
	v_add_f32_dpp v186, v190, v190 row_half_mirror row_mask:0xf bank_mask:0xa
	v_add_f32_dpp v187, v191, v191 row_half_mirror row_mask:0xf bank_mask:0xa
	v_add_f32_dpp v184, v184, v184 quad_perm:[1,0,3,2] row_mask:0xf bank_mask:0xf
	v_add_f32_dpp v185, v185, v185 quad_perm:[1,0,3,2] row_mask:0xf bank_mask:0xf
	v_add_f32_dpp v186, v186, v186 quad_perm:[1,0,3,2] row_mask:0xf bank_mask:0xf
	v_add_f32_dpp v187, v187, v187 quad_perm:[1,0,3,2] row_mask:0xf bank_mask:0xf
	v_add_f32_dpp v184, v184, v184 quad_perm:[2,3,0,1] row_mask:0xf bank_mask:0xf
	v_add_f32_dpp v185, v185, v185 quad_perm:[2,3,0,1] row_mask:0xf bank_mask:0xf
	v_add_f32_dpp v186, v186, v186 quad_perm:[2,3,0,1] row_mask:0xf bank_mask:0xf
	v_add_f32_dpp v187, v187, v187 quad_perm:[2,3,0,1] row_mask:0xf bank_mask:0xf
	v_cndmask_b32_e64 v156, v184, v185, s[14:15]
	v_cndmask_b32_e64 v157, v186, v187, s[14:15]
	v_cndmask_b32_e64 v198, v156, v157, s[100:101]
	s_waitcnt lgkmcnt(0)
	v_mad_u32_u24 v176, v176, s64, v164
	v_mad_u32_u24 v177, v177, s64, v164
	v_mad_u32_u24 v178, v178, s64, v164
	v_mad_u32_u24 v179, v179, s64, v164
	global_load_dwordx4 v[40:43], v176, s[4:5]
	global_load_dwordx2 v[44:45], v176, s[4:5] offset:16
	global_load_dwordx4 v[46:49], v177, s[4:5]
	global_load_dwordx2 v[50:51], v177, s[4:5] offset:16
	global_load_dwordx4 v[52:55], v178, s[4:5]
	global_load_dwordx2 v[56:57], v178, s[4:5] offset:16
	global_load_dwordx4 v[58:61], v179, s[4:5]
	global_load_dwordx2 v[62:63], v179, s[4:5] offset:16
	ds_add_f32 v170, v198 offset:0
	ds_read2_b32 v[144:145], v167 offset0:64 offset1:72
	ds_read2_b32 v[146:147], v167 offset0:80 offset1:88
	s_waitcnt vmcnt(38)
	v_cvt_scalef32_pk32_bf16_fp6 v[0:15], v[64:69], 1.0
	v_dot2_f32_bf16 v152, v0, v128, 0
	v_dot2_f32_bf16 v153, v1, v129, 0
	v_dot2_f32_bf16 v154, v2, v130, 0
	v_dot2_f32_bf16 v155, v3, v131, 0
	v_dot2c_f32_bf16_e32 v152, v4, v132
	v_dot2c_f32_bf16_e32 v153, v5, v133
	v_dot2c_f32_bf16_e32 v154, v6, v134
	v_dot2c_f32_bf16_e32 v155, v7, v135
	v_dot2c_f32_bf16_e32 v152, v8, v136
	v_dot2c_f32_bf16_e32 v153, v9, v137
	v_dot2c_f32_bf16_e32 v154, v10, v138
	v_dot2c_f32_bf16_e32 v155, v11, v139
	v_dot2c_f32_bf16_e32 v152, v12, v140
	v_dot2c_f32_bf16_e32 v153, v13, v141
	v_dot2c_f32_bf16_e32 v154, v14, v142
	v_dot2c_f32_bf16_e32 v155, v15, v143
	s_waitcnt vmcnt(36)
	v_cvt_scalef32_pk32_bf16_fp6 v[0:15], v[70:75], 1.0
	v_dot2_f32_bf16 v192, v0, v128, 0
	v_dot2_f32_bf16 v193, v1, v129, 0
	v_dot2_f32_bf16 v194, v2, v130, 0
	v_dot2_f32_bf16 v195, v3, v131, 0
	v_dot2c_f32_bf16_e32 v192, v4, v132
	v_dot2c_f32_bf16_e32 v193, v5, v133
	v_add_f32_e32 v156, v152, v153
	v_dot2c_f32_bf16_e32 v194, v6, v134
	v_dot2c_f32_bf16_e32 v195, v7, v135
	v_dot2c_f32_bf16_e32 v192, v8, v136
	v_add_f32_e32 v157, v154, v155
	v_dot2c_f32_bf16_e32 v193, v9, v137
	v_dot2c_f32_bf16_e32 v194, v10, v138
	v_dot2c_f32_bf16_e32 v195, v11, v139
	v_add_f32_e32 v184, v156, v157
	v_dot2c_f32_bf16_e32 v192, v12, v140
	v_dot2c_f32_bf16_e32 v193, v13, v141
	v_dot2c_f32_bf16_e32 v194, v14, v142
	v_dot2c_f32_bf16_e32 v195, v15, v143
	s_waitcnt vmcnt(34)
	v_cvt_scalef32_pk32_bf16_fp6 v[0:15], v[76:81], 1.0
	v_dot2_f32_bf16 v152, v0, v128, 0
	v_dot2_f32_bf16 v153, v1, v129, 0
	v_dot2_f32_bf16 v154, v2, v130, 0
	v_dot2_f32_bf16 v155, v3, v131, 0
	v_dot2c_f32_bf16_e32 v152, v4, v132
	v_dot2c_f32_bf16_e32 v153, v5, v133
	v_add_f32_e32 v156, v192, v193
	v_dot2c_f32_bf16_e32 v154, v6, v134
	v_dot2c_f32_bf16_e32 v155, v7, v135
	v_dot2c_f32_bf16_e32 v152, v8, v136
	v_add_f32_e32 v157, v194, v195
	v_dot2c_f32_bf16_e32 v153, v9, v137
	v_dot2c_f32_bf16_e32 v154, v10, v138
	v_dot2c_f32_bf16_e32 v155, v11, v139
	v_add_f32_e32 v185, v156, v157
	v_dot2c_f32_bf16_e32 v152, v12, v140
	v_dot2c_f32_bf16_e32 v153, v13, v141
	v_dot2c_f32_bf16_e32 v154, v14, v142
	v_dot2c_f32_bf16_e32 v155, v15, v143
	s_waitcnt vmcnt(32)
	v_cvt_scalef32_pk32_bf16_fp6 v[0:15], v[82:87], 1.0
	v_dot2_f32_bf16 v192, v0, v128, 0
	v_dot2_f32_bf16 v193, v1, v129, 0
	v_dot2_f32_bf16 v194, v2, v130, 0
	v_dot2_f32_bf16 v195, v3, v131, 0
	v_dot2c_f32_bf16_e32 v192, v4, v132
	v_dot2c_f32_bf16_e32 v193, v5, v133
	v_add_f32_e32 v156, v152, v153
	v_dot2c_f32_bf16_e32 v194, v6, v134
	v_dot2c_f32_bf16_e32 v195, v7, v135
	v_dot2c_f32_bf16_e32 v192, v8, v136
	v_add_f32_e32 v157, v154, v155
	v_dot2c_f32_bf16_e32 v193, v9, v137
	v_dot2c_f32_bf16_e32 v194, v10, v138
	v_dot2c_f32_bf16_e32 v195, v11, v139
	v_add_f32_e32 v186, v156, v157
	v_dot2c_f32_bf16_e32 v192, v12, v140
	v_dot2c_f32_bf16_e32 v193, v13, v141
	v_dot2c_f32_bf16_e32 v194, v14, v142
	v_dot2c_f32_bf16_e32 v195, v15, v143
	s_waitcnt lgkmcnt(0)
	v_mad_u32_u24 v144, v144, s64, v164
	v_mad_u32_u24 v145, v145, s64, v164
	v_mad_u32_u24 v146, v146, s64, v164
	v_mad_u32_u24 v147, v147, s64, v164
	global_load_dwordx4 v[64:67], v144, s[4:5]
	global_load_dwordx2 v[68:69], v144, s[4:5] offset:16
	global_load_dwordx4 v[70:73], v145, s[4:5]
	global_load_dwordx2 v[74:75], v145, s[4:5] offset:16
	global_load_dwordx4 v[76:79], v146, s[4:5]
	global_load_dwordx2 v[80:81], v146, s[4:5] offset:16
	global_load_dwordx4 v[82:85], v147, s[4:5]
	global_load_dwordx2 v[86:87], v147, s[4:5] offset:16
	ds_read2_b32 v[176:177], v167 offset0:96 offset1:104
	ds_read2_b32 v[178:179], v167 offset0:112 offset1:120
	s_waitcnt vmcnt(38)
	v_cvt_scalef32_pk32_bf16_fp6 v[0:15], v[88:93], 1.0
	v_dot2_f32_bf16 v152, v0, v128, 0
	v_dot2_f32_bf16 v153, v1, v129, 0
	v_dot2_f32_bf16 v154, v2, v130, 0
	v_dot2_f32_bf16 v155, v3, v131, 0
	v_dot2c_f32_bf16_e32 v152, v4, v132
	v_dot2c_f32_bf16_e32 v153, v5, v133
	v_add_f32_e32 v156, v192, v193
	v_dot2c_f32_bf16_e32 v154, v6, v134
	v_dot2c_f32_bf16_e32 v155, v7, v135
	v_dot2c_f32_bf16_e32 v152, v8, v136
	v_add_f32_e32 v157, v194, v195
	v_dot2c_f32_bf16_e32 v153, v9, v137
	v_dot2c_f32_bf16_e32 v154, v10, v138
	v_dot2c_f32_bf16_e32 v155, v11, v139
	v_add_f32_e32 v187, v156, v157
	v_dot2c_f32_bf16_e32 v152, v12, v140
	v_dot2c_f32_bf16_e32 v153, v13, v141
	v_dot2c_f32_bf16_e32 v154, v14, v142
	v_dot2c_f32_bf16_e32 v155, v15, v143
	s_waitcnt vmcnt(36)
	v_cvt_scalef32_pk32_bf16_fp6 v[0:15], v[94:99], 1.0
	v_dot2_f32_bf16 v192, v0, v128, 0
	v_dot2_f32_bf16 v193, v1, v129, 0
	v_dot2_f32_bf16 v194, v2, v130, 0
	v_dot2_f32_bf16 v195, v3, v131, 0
	v_dot2c_f32_bf16_e32 v192, v4, v132
	v_dot2c_f32_bf16_e32 v193, v5, v133
	v_add_f32_e32 v156, v152, v153
	v_dot2c_f32_bf16_e32 v194, v6, v134
	v_dot2c_f32_bf16_e32 v195, v7, v135
	v_dot2c_f32_bf16_e32 v192, v8, v136
	v_add_f32_e32 v157, v154, v155
	v_dot2c_f32_bf16_e32 v193, v9, v137
	v_dot2c_f32_bf16_e32 v194, v10, v138
	v_dot2c_f32_bf16_e32 v195, v11, v139
	v_add_f32_e32 v188, v156, v157
	v_dot2c_f32_bf16_e32 v192, v12, v140
	v_dot2c_f32_bf16_e32 v193, v13, v141
	v_dot2c_f32_bf16_e32 v194, v14, v142
	v_dot2c_f32_bf16_e32 v195, v15, v143
	s_waitcnt vmcnt(34)
	v_cvt_scalef32_pk32_bf16_fp6 v[0:15], v[100:105], 1.0
	v_dot2_f32_bf16 v152, v0, v128, 0
	v_dot2_f32_bf16 v153, v1, v129, 0
	v_dot2_f32_bf16 v154, v2, v130, 0
	v_dot2_f32_bf16 v155, v3, v131, 0
	v_dot2c_f32_bf16_e32 v152, v4, v132
	v_dot2c_f32_bf16_e32 v153, v5, v133
	v_add_f32_e32 v156, v192, v193
	v_dot2c_f32_bf16_e32 v154, v6, v134
	v_dot2c_f32_bf16_e32 v155, v7, v135
	v_dot2c_f32_bf16_e32 v152, v8, v136
	v_add_f32_e32 v157, v194, v195
	v_dot2c_f32_bf16_e32 v153, v9, v137
	v_dot2c_f32_bf16_e32 v154, v10, v138
	v_dot2c_f32_bf16_e32 v155, v11, v139
	v_add_f32_e32 v189, v156, v157
	v_dot2c_f32_bf16_e32 v152, v12, v140
	v_dot2c_f32_bf16_e32 v153, v13, v141
	v_dot2c_f32_bf16_e32 v154, v14, v142
	v_dot2c_f32_bf16_e32 v155, v15, v143
	s_waitcnt vmcnt(32)
	v_cvt_scalef32_pk32_bf16_fp6 v[0:15], v[106:111], 1.0
	v_dot2_f32_bf16 v192, v0, v128, 0
	v_dot2_f32_bf16 v193, v1, v129, 0
	v_dot2_f32_bf16 v194, v2, v130, 0
	v_dot2_f32_bf16 v195, v3, v131, 0
	v_dot2c_f32_bf16_e32 v192, v4, v132
	v_dot2c_f32_bf16_e32 v193, v5, v133
	v_add_f32_e32 v156, v152, v153
	v_dot2c_f32_bf16_e32 v194, v6, v134
	v_dot2c_f32_bf16_e32 v195, v7, v135
	v_dot2c_f32_bf16_e32 v192, v8, v136
	v_add_f32_e32 v157, v154, v155
	v_dot2c_f32_bf16_e32 v193, v9, v137
	v_dot2c_f32_bf16_e32 v194, v10, v138
	v_dot2c_f32_bf16_e32 v195, v11, v139
	v_add_f32_e32 v190, v156, v157
	v_dot2c_f32_bf16_e32 v192, v12, v140
	v_dot2c_f32_bf16_e32 v193, v13, v141
	v_dot2c_f32_bf16_e32 v194, v14, v142
	v_dot2c_f32_bf16_e32 v195, v15, v143
	s_nop 1
	v_add_f32_e32 v156, v192, v193
	v_add_f32_e32 v157, v194, v195
	v_add_f32_e32 v191, v156, v157
	v_add_f32_dpp v184, v184, v184 row_half_mirror row_mask:0xf bank_mask:0x5
	v_add_f32_dpp v185, v185, v185 row_half_mirror row_mask:0xf bank_mask:0x5
	v_add_f32_dpp v186, v186, v186 row_half_mirror row_mask:0xf bank_mask:0x5
	v_add_f32_dpp v187, v187, v187 row_half_mirror row_mask:0xf bank_mask:0x5
	v_add_f32_dpp v184, v188, v188 row_half_mirror row_mask:0xf bank_mask:0xa
	v_add_f32_dpp v185, v189, v189 row_half_mirror row_mask:0xf bank_mask:0xa
	v_add_f32_dpp v186, v190, v190 row_half_mirror row_mask:0xf bank_mask:0xa
	v_add_f32_dpp v187, v191, v191 row_half_mirror row_mask:0xf bank_mask:0xa
	v_add_f32_dpp v184, v184, v184 quad_perm:[1,0,3,2] row_mask:0xf bank_mask:0xf
	v_add_f32_dpp v185, v185, v185 quad_perm:[1,0,3,2] row_mask:0xf bank_mask:0xf
	v_add_f32_dpp v186, v186, v186 quad_perm:[1,0,3,2] row_mask:0xf bank_mask:0xf
	v_add_f32_dpp v187, v187, v187 quad_perm:[1,0,3,2] row_mask:0xf bank_mask:0xf
	v_add_f32_dpp v184, v184, v184 quad_perm:[2,3,0,1] row_mask:0xf bank_mask:0xf
	v_add_f32_dpp v185, v185, v185 quad_perm:[2,3,0,1] row_mask:0xf bank_mask:0xf
	v_add_f32_dpp v186, v186, v186 quad_perm:[2,3,0,1] row_mask:0xf bank_mask:0xf
	v_add_f32_dpp v187, v187, v187 quad_perm:[2,3,0,1] row_mask:0xf bank_mask:0xf
	v_cndmask_b32_e64 v156, v184, v185, s[14:15]
	v_cndmask_b32_e64 v157, v186, v187, s[14:15]
	v_cndmask_b32_e64 v198, v156, v157, s[100:101]
	s_waitcnt lgkmcnt(0)
	v_mad_u32_u24 v176, v176, s64, v164
	v_mad_u32_u24 v177, v177, s64, v164
	v_mad_u32_u24 v178, v178, s64, v164
	v_mad_u32_u24 v179, v179, s64, v164
	global_load_dwordx4 v[88:91], v176, s[4:5]
	global_load_dwordx2 v[92:93], v176, s[4:5] offset:16
	global_load_dwordx4 v[94:97], v177, s[4:5]
	global_load_dwordx2 v[98:99], v177, s[4:5] offset:16
	global_load_dwordx4 v[100:103], v178, s[4:5]
	global_load_dwordx2 v[104:105], v178, s[4:5] offset:16
	global_load_dwordx4 v[106:109], v179, s[4:5]
	global_load_dwordx2 v[110:111], v179, s[4:5] offset:16
	ds_add_f32 v170, v198 offset:256
	s_add_u32 s16, s16, 1
	s_and_b32 s16, s16, 63
	s_add_u32 s18, s16, 1
	s_and_b32 s70, s18, 63
	s_and_b32 s19, s70, 15
	s_lshr_b32 s50, s70, 4
	s_lshl_b32 s51, s19, 9
	s_mul_i32 s17, s19, s65
	s_lshl_b32 s18, s50, 6
	s_add_u32 s17, s17, s18
	s_add_u32 s12, s8, s17
	s_addc_u32 s13, s9, 0
	s_mul_i32 s17, s50, 0x300000
	s_add_u32 s4, s26, 0x1800000
	s_addc_u32 s5, s27, 0
	s_add_u32 s4, s4, s17
	s_addc_u32 s5, s5, 0
	v_add_u32_e32 v168, s51, v161
	ds_read2_b32 v[144:145], v168 offset0:0 offset1:8
	ds_read2_b32 v[146:147], v168 offset0:16 offset1:24
	s_cmp_lg_u32 s16, 0
	s_cbranch_scc1 .Lgu0_loop
	s_waitcnt vmcnt(0) lgkmcnt(0)
	s_add_u32 s4, s26, 0x1400000
	s_addc_u32 s5, s27, 0
	s_add_u32 s8, s26, 0x1410000
	s_addc_u32 s9, s27, 0
	s_lshl_b32 s17, s69, 9
	s_add_u32 s10, s26, 0xe800000
	s_addc_u32 s11, s27, 0
	s_add_u32 s10, s10, s17
	s_addc_u32 s11, s11, 0
	s_add_u32 s12, s26, 0xf800000
	s_addc_u32 s13, s27, 0
	s_add_u32 s12, s12, s17
	s_addc_u32 s13, s13, 0
	s_lshl_b32 s18, s92, 11
	s_mov_b32 s16, 0x378e98ab
	s_mov_b32 s19, 0x3b7cd369
	s_mov_b32 s50, 0xbcc618b2
	s_mov_b32 s51, 0x3dda74e4
	s_mov_b32 s64, 0x3f228afd
	s_mov_b32 s65, 0x3e03c728
	s_mov_b32 s98, 0xbfb8aa3b
	s_mov_b32 s70, 0x42ce8ed0
	s_mov_b32 s71, 0xc2b17218
	s_mov_b32 s14, 0x7fffffff
	v_mov_b32_e32 v176, 0x3ba10414
	v_mov_b32_e32 v177, 0xb9c68948
	v_mov_b32_e32 v178, 0x7f800000
	ds_read2st64_b32 v[16:17], v174 offset0:0 offset1:1
	ds_read2st64_b32 v[80:81], v175 offset0:0 offset1:1
	ds_read2st64_b32 v[18:19], v174 offset0:2 offset1:3
	ds_read2st64_b32 v[82:83], v175 offset0:2 offset1:3
	ds_read2st64_b32 v[20:21], v174 offset0:4 offset1:5
	ds_read2st64_b32 v[84:85], v175 offset0:4 offset1:5
	ds_read2st64_b32 v[22:23], v174 offset0:6 offset1:7
	ds_read2st64_b32 v[86:87], v175 offset0:6 offset1:7
	ds_read2st64_b32 v[24:25], v174 offset0:8 offset1:9
	ds_read2st64_b32 v[88:89], v175 offset0:8 offset1:9
	ds_read2st64_b32 v[26:27], v174 offset0:10 offset1:11
	ds_read2st64_b32 v[90:91], v175 offset0:10 offset1:11
	ds_read2st64_b32 v[28:29], v174 offset0:12 offset1:13
	ds_read2st64_b32 v[92:93], v175 offset0:12 offset1:13
	ds_read2st64_b32 v[30:31], v174 offset0:14 offset1:15
	ds_read2st64_b32 v[94:95], v175 offset0:14 offset1:15
	s_waitcnt lgkmcnt(0)
	v_lshlrev_b32_e32 v16, 2, v16
	v_lshlrev_b32_e32 v17, 2, v17
	v_lshlrev_b32_e32 v18, 2, v18
	v_lshlrev_b32_e32 v19, 2, v19
	v_lshlrev_b32_e32 v20, 2, v20
	v_lshlrev_b32_e32 v21, 2, v21
	v_lshlrev_b32_e32 v22, 2, v22
	v_lshlrev_b32_e32 v23, 2, v23
	v_lshlrev_b32_e32 v24, 2, v24
	v_lshlrev_b32_e32 v25, 2, v25
	v_lshlrev_b32_e32 v26, 2, v26
	v_lshlrev_b32_e32 v27, 2, v27
	v_lshlrev_b32_e32 v28, 2, v28
	v_lshlrev_b32_e32 v29, 2, v29
	v_lshlrev_b32_e32 v30, 2, v30
	v_lshlrev_b32_e32 v31, 2, v31
	global_load_dword v32, v160, s[10:11]
	global_load_dword v33, v160, s[10:11] offset:256
	global_load_dword v34, v16, s[4:5]
	global_load_dword v35, v17, s[4:5]
	global_load_dword v36, v16, s[8:9]
	global_load_dword v37, v17, s[8:9]
	s_add_u32 s10, s10, s18
	s_addc_u32 s11, s11, 0
	global_load_dword v38, v160, s[10:11]
	global_load_dword v39, v160, s[10:11] offset:256
	global_load_dword v40, v18, s[4:5]
	global_load_dword v41, v19, s[4:5]
	global_load_dword v42, v18, s[8:9]
	global_load_dword v43, v19, s[8:9]
	s_add_u32 s10, s10, s18
	s_addc_u32 s11, s11, 0
	global_load_dword v44, v160, s[10:11]
	global_load_dword v45, v160, s[10:11] offset:256
	global_load_dword v46, v20, s[4:5]
	global_load_dword v47, v21, s[4:5]
	global_load_dword v48, v20, s[8:9]
	global_load_dword v49, v21, s[8:9]
	s_add_u32 s10, s10, s18
	s_addc_u32 s11, s11, 0
	global_load_dword v50, v160, s[10:11]
	global_load_dword v51, v160, s[10:11] offset:256
	global_load_dword v52, v22, s[4:5]
	global_load_dword v53, v23, s[4:5]
	global_load_dword v54, v22, s[8:9]
	global_load_dword v55, v23, s[8:9]
	s_add_u32 s10, s10, s18
	s_addc_u32 s11, s11, 0
	global_load_dword v56, v160, s[10:11]
	global_load_dword v57, v160, s[10:11] offset:256
	global_load_dword v58, v24, s[4:5]
	global_load_dword v59, v25, s[4:5]
	global_load_dword v60, v24, s[8:9]
	global_load_dword v61, v25, s[8:9]
	s_add_u32 s10, s10, s18
	s_addc_u32 s11, s11, 0
	global_load_dword v62, v160, s[10:11]
	global_load_dword v63, v160, s[10:11] offset:256
	global_load_dword v64, v26, s[4:5]
	global_load_dword v65, v27, s[4:5]
	global_load_dword v66, v26, s[8:9]
	global_load_dword v67, v27, s[8:9]
	s_add_u32 s10, s10, s18
	s_addc_u32 s11, s11, 0
	global_load_dword v68, v160, s[10:11]
	global_load_dword v69, v160, s[10:11] offset:256
	global_load_dword v70, v28, s[4:5]
	global_load_dword v71, v29, s[4:5]
	global_load_dword v72, v28, s[8:9]
	global_load_dword v73, v29, s[8:9]
	s_add_u32 s10, s10, s18
	s_addc_u32 s11, s11, 0
	global_load_dword v74, v160, s[10:11]
	global_load_dword v75, v160, s[10:11] offset:256
	global_load_dword v76, v30, s[4:5]
	global_load_dword v77, v31, s[4:5]
	global_load_dword v78, v30, s[8:9]
	global_load_dword v79, v31, s[8:9]
	s_add_u32 s10, s10, s18
	s_addc_u32 s11, s11, 0
	s_waitcnt vmcnt(0)
	v_mul_f32_e32 v80, v34, v80
	v_mul_f32_e32 v180, 0x3f3504f3, v80
	v_fma_f32 v182, |v180|, s16, v177
	v_fma_f32 v182, |v180|, v182, s19
	v_fma_f32 v182, |v180|, v182, s50
	v_fma_f32 v182, |v180|, v182, s51
	v_fma_f32 v182, |v180|, v182, s64
	v_fma_f32 v182, |v180|, v182, s65
	v_fma_f32 v182, |v180|, v182, |v180|
	v_mul_f32_e32 v184, 0xbfb8aa3b, v182
	v_fma_f32 v185, v182, s98, -v184
	v_rndne_f32_e32 v186, v184
	v_fmac_f32_e32 v185, 0xb2a5705f, v182
	v_sub_f32_e32 v184, v184, v186
	v_add_f32_e32 v184, v184, v185
	v_cvt_i32_f32_e32 v185, v186
	v_exp_f32_e32 v184, v184
	v_cmp_nlt_f32_e32 vcc, s70, v182
	v_ldexp_f32 v184, v184, v185
	s_nop 0
	v_cndmask_b32_e32 v184, 0, v184, vcc
	v_cmp_ngt_f32_e32 vcc, s71, v182
	s_nop 1
	v_cndmask_b32_e32 v184, v178, v184, vcc
	v_sub_f32_e32 v184, 1.0, v184
	v_mul_f32_e32 v183, v180, v180
	v_fmamk_f32 v185, v183, 0xba1345e1, v176
	v_fmaak_f32 v185, v183, v185, 0xbcdac9b8
	v_fmaak_f32 v185, v183, v185, 0x3de703be
	v_fmaak_f32 v185, v183, v185, 0xbec09330
	v_fmaak_f32 v183, v183, v185, 0x3e0375d0
	v_fma_f32 v183, |v180|, v183, |v180|
	v_cmp_nlt_f32_e64 vcc, |v180|, 1.0
	s_nop 1
	v_cndmask_b32_e32 v184, v183, v184, vcc
	v_bfi_b32 v184, s14, v184, v180
	v_add_f32_e32 v184, 1.0, v184
	v_mul_f32_e32 v80, 0.5, v80
	v_mul_f32_e32 v32, v32, v36
	v_mul_f32_e32 v80, v80, v184
	v_mul_f32_e32 v80, v32, v80
	v_mul_f32_e32 v81, v35, v81
	v_mul_f32_e32 v180, 0x3f3504f3, v81
	v_fma_f32 v182, |v180|, s16, v177
	v_fma_f32 v182, |v180|, v182, s19
	v_fma_f32 v182, |v180|, v182, s50
	v_fma_f32 v182, |v180|, v182, s51
	v_fma_f32 v182, |v180|, v182, s64
	v_fma_f32 v182, |v180|, v182, s65
	v_fma_f32 v182, |v180|, v182, |v180|
	v_mul_f32_e32 v184, 0xbfb8aa3b, v182
	v_fma_f32 v185, v182, s98, -v184
	v_rndne_f32_e32 v186, v184
	v_fmac_f32_e32 v185, 0xb2a5705f, v182
	v_sub_f32_e32 v184, v184, v186
	v_add_f32_e32 v184, v184, v185
	v_cvt_i32_f32_e32 v185, v186
	v_exp_f32_e32 v184, v184
	v_cmp_nlt_f32_e32 vcc, s70, v182
	v_ldexp_f32 v184, v184, v185
	s_nop 0
	v_cndmask_b32_e32 v184, 0, v184, vcc
	v_cmp_ngt_f32_e32 vcc, s71, v182
	s_nop 1
	v_cndmask_b32_e32 v184, v178, v184, vcc
	v_sub_f32_e32 v184, 1.0, v184
	v_mul_f32_e32 v183, v180, v180
	v_fmamk_f32 v185, v183, 0xba1345e1, v176
	v_fmaak_f32 v185, v183, v185, 0xbcdac9b8
	v_fmaak_f32 v185, v183, v185, 0x3de703be
	v_fmaak_f32 v185, v183, v185, 0xbec09330
	v_fmaak_f32 v183, v183, v185, 0x3e0375d0
	v_fma_f32 v183, |v180|, v183, |v180|
	v_cmp_nlt_f32_e64 vcc, |v180|, 1.0
	s_nop 1
	v_cndmask_b32_e32 v184, v183, v184, vcc
	v_bfi_b32 v184, s14, v184, v180
	v_add_f32_e32 v184, 1.0, v184
	v_mul_f32_e32 v81, 0.5, v81
	v_mul_f32_e32 v33, v33, v37
	v_mul_f32_e32 v81, v81, v184
	v_mul_f32_e32 v81, v33, v81
	global_store_dword v160, v80, s[12:13]
	global_store_dword v160, v81, s[12:13] offset:256
	s_add_u32 s12, s12, s18
	s_addc_u32 s13, s13, 0
	v_mul_f32_e32 v82, v40, v82
	v_mul_f32_e32 v180, 0x3f3504f3, v82
	v_fma_f32 v182, |v180|, s16, v177
	v_fma_f32 v182, |v180|, v182, s19
	v_fma_f32 v182, |v180|, v182, s50
	v_fma_f32 v182, |v180|, v182, s51
	v_fma_f32 v182, |v180|, v182, s64
	v_fma_f32 v182, |v180|, v182, s65
	v_fma_f32 v182, |v180|, v182, |v180|
	v_mul_f32_e32 v184, 0xbfb8aa3b, v182
	v_fma_f32 v185, v182, s98, -v184
	v_rndne_f32_e32 v186, v184
	v_fmac_f32_e32 v185, 0xb2a5705f, v182
	v_sub_f32_e32 v184, v184, v186
	v_add_f32_e32 v184, v184, v185
	v_cvt_i32_f32_e32 v185, v186
	v_exp_f32_e32 v184, v184
	v_cmp_nlt_f32_e32 vcc, s70, v182
	v_ldexp_f32 v184, v184, v185
	s_nop 0
	v_cndmask_b32_e32 v184, 0, v184, vcc
	v_cmp_ngt_f32_e32 vcc, s71, v182
	s_nop 1
	v_cndmask_b32_e32 v184, v178, v184, vcc
	v_sub_f32_e32 v184, 1.0, v184
	v_mul_f32_e32 v183, v180, v180
	v_fmamk_f32 v185, v183, 0xba1345e1, v176
	v_fmaak_f32 v185, v183, v185, 0xbcdac9b8
	v_fmaak_f32 v185, v183, v185, 0x3de703be
	v_fmaak_f32 v185, v183, v185, 0xbec09330
	v_fmaak_f32 v183, v183, v185, 0x3e0375d0
	v_fma_f32 v183, |v180|, v183, |v180|
	v_cmp_nlt_f32_e64 vcc, |v180|, 1.0
	s_nop 1
	v_cndmask_b32_e32 v184, v183, v184, vcc
	v_bfi_b32 v184, s14, v184, v180
	v_add_f32_e32 v184, 1.0, v184
	v_mul_f32_e32 v82, 0.5, v82
	v_mul_f32_e32 v38, v38, v42
	v_mul_f32_e32 v82, v82, v184
	v_mul_f32_e32 v82, v38, v82
	v_mul_f32_e32 v83, v41, v83
	v_mul_f32_e32 v180, 0x3f3504f3, v83
	v_fma_f32 v182, |v180|, s16, v177
	v_fma_f32 v182, |v180|, v182, s19
	v_fma_f32 v182, |v180|, v182, s50
	v_fma_f32 v182, |v180|, v182, s51
	v_fma_f32 v182, |v180|, v182, s64
	v_fma_f32 v182, |v180|, v182, s65
	v_fma_f32 v182, |v180|, v182, |v180|
	v_mul_f32_e32 v184, 0xbfb8aa3b, v182
	v_fma_f32 v185, v182, s98, -v184
	v_rndne_f32_e32 v186, v184
	v_fmac_f32_e32 v185, 0xb2a5705f, v182
	v_sub_f32_e32 v184, v184, v186
	v_add_f32_e32 v184, v184, v185
	v_cvt_i32_f32_e32 v185, v186
	v_exp_f32_e32 v184, v184
	v_cmp_nlt_f32_e32 vcc, s70, v182
	v_ldexp_f32 v184, v184, v185
	s_nop 0
	v_cndmask_b32_e32 v184, 0, v184, vcc
	v_cmp_ngt_f32_e32 vcc, s71, v182
	s_nop 1
	v_cndmask_b32_e32 v184, v178, v184, vcc
	v_sub_f32_e32 v184, 1.0, v184
	v_mul_f32_e32 v183, v180, v180
	v_fmamk_f32 v185, v183, 0xba1345e1, v176
	v_fmaak_f32 v185, v183, v185, 0xbcdac9b8
	v_fmaak_f32 v185, v183, v185, 0x3de703be
	v_fmaak_f32 v185, v183, v185, 0xbec09330
	v_fmaak_f32 v183, v183, v185, 0x3e0375d0
	v_fma_f32 v183, |v180|, v183, |v180|
	v_cmp_nlt_f32_e64 vcc, |v180|, 1.0
	s_nop 1
	v_cndmask_b32_e32 v184, v183, v184, vcc
	v_bfi_b32 v184, s14, v184, v180
	v_add_f32_e32 v184, 1.0, v184
	v_mul_f32_e32 v83, 0.5, v83
	v_mul_f32_e32 v39, v39, v43
	v_mul_f32_e32 v83, v83, v184
	v_mul_f32_e32 v83, v39, v83
	global_store_dword v160, v82, s[12:13]
	global_store_dword v160, v83, s[12:13] offset:256
	s_add_u32 s12, s12, s18
	s_addc_u32 s13, s13, 0
	v_mul_f32_e32 v84, v46, v84
	v_mul_f32_e32 v180, 0x3f3504f3, v84
	v_fma_f32 v182, |v180|, s16, v177
	v_fma_f32 v182, |v180|, v182, s19
	v_fma_f32 v182, |v180|, v182, s50
	v_fma_f32 v182, |v180|, v182, s51
	v_fma_f32 v182, |v180|, v182, s64
	v_fma_f32 v182, |v180|, v182, s65
	v_fma_f32 v182, |v180|, v182, |v180|
	v_mul_f32_e32 v184, 0xbfb8aa3b, v182
	v_fma_f32 v185, v182, s98, -v184
	v_rndne_f32_e32 v186, v184
	v_fmac_f32_e32 v185, 0xb2a5705f, v182
	v_sub_f32_e32 v184, v184, v186
	v_add_f32_e32 v184, v184, v185
	v_cvt_i32_f32_e32 v185, v186
	v_exp_f32_e32 v184, v184
	v_cmp_nlt_f32_e32 vcc, s70, v182
	v_ldexp_f32 v184, v184, v185
	s_nop 0
	v_cndmask_b32_e32 v184, 0, v184, vcc
	v_cmp_ngt_f32_e32 vcc, s71, v182
	s_nop 1
	v_cndmask_b32_e32 v184, v178, v184, vcc
	v_sub_f32_e32 v184, 1.0, v184
	v_mul_f32_e32 v183, v180, v180
	v_fmamk_f32 v185, v183, 0xba1345e1, v176
	v_fmaak_f32 v185, v183, v185, 0xbcdac9b8
	v_fmaak_f32 v185, v183, v185, 0x3de703be
	v_fmaak_f32 v185, v183, v185, 0xbec09330
	v_fmaak_f32 v183, v183, v185, 0x3e0375d0
	v_fma_f32 v183, |v180|, v183, |v180|
	v_cmp_nlt_f32_e64 vcc, |v180|, 1.0
	s_nop 1
	v_cndmask_b32_e32 v184, v183, v184, vcc
	v_bfi_b32 v184, s14, v184, v180
	v_add_f32_e32 v184, 1.0, v184
	v_mul_f32_e32 v84, 0.5, v84
	v_mul_f32_e32 v44, v44, v48
	v_mul_f32_e32 v84, v84, v184
	v_mul_f32_e32 v84, v44, v84
	v_mul_f32_e32 v85, v47, v85
	v_mul_f32_e32 v180, 0x3f3504f3, v85
	v_fma_f32 v182, |v180|, s16, v177
	v_fma_f32 v182, |v180|, v182, s19
	v_fma_f32 v182, |v180|, v182, s50
	v_fma_f32 v182, |v180|, v182, s51
	v_fma_f32 v182, |v180|, v182, s64
	v_fma_f32 v182, |v180|, v182, s65
	v_fma_f32 v182, |v180|, v182, |v180|
	v_mul_f32_e32 v184, 0xbfb8aa3b, v182
	v_fma_f32 v185, v182, s98, -v184
	v_rndne_f32_e32 v186, v184
	v_fmac_f32_e32 v185, 0xb2a5705f, v182
	v_sub_f32_e32 v184, v184, v186
	v_add_f32_e32 v184, v184, v185
	v_cvt_i32_f32_e32 v185, v186
	v_exp_f32_e32 v184, v184
	v_cmp_nlt_f32_e32 vcc, s70, v182
	v_ldexp_f32 v184, v184, v185
	s_nop 0
	v_cndmask_b32_e32 v184, 0, v184, vcc
	v_cmp_ngt_f32_e32 vcc, s71, v182
	s_nop 1
	v_cndmask_b32_e32 v184, v178, v184, vcc
	v_sub_f32_e32 v184, 1.0, v184
	v_mul_f32_e32 v183, v180, v180
	v_fmamk_f32 v185, v183, 0xba1345e1, v176
	v_fmaak_f32 v185, v183, v185, 0xbcdac9b8
	v_fmaak_f32 v185, v183, v185, 0x3de703be
	v_fmaak_f32 v185, v183, v185, 0xbec09330
	v_fmaak_f32 v183, v183, v185, 0x3e0375d0
	v_fma_f32 v183, |v180|, v183, |v180|
	v_cmp_nlt_f32_e64 vcc, |v180|, 1.0
	s_nop 1
	v_cndmask_b32_e32 v184, v183, v184, vcc
	v_bfi_b32 v184, s14, v184, v180
	v_add_f32_e32 v184, 1.0, v184
	v_mul_f32_e32 v85, 0.5, v85
	v_mul_f32_e32 v45, v45, v49
	v_mul_f32_e32 v85, v85, v184
	v_mul_f32_e32 v85, v45, v85
	global_store_dword v160, v84, s[12:13]
	global_store_dword v160, v85, s[12:13] offset:256
	s_add_u32 s12, s12, s18
	s_addc_u32 s13, s13, 0
	v_mul_f32_e32 v86, v52, v86
	v_mul_f32_e32 v180, 0x3f3504f3, v86
	v_fma_f32 v182, |v180|, s16, v177
	v_fma_f32 v182, |v180|, v182, s19
	v_fma_f32 v182, |v180|, v182, s50
	v_fma_f32 v182, |v180|, v182, s51
	v_fma_f32 v182, |v180|, v182, s64
	v_fma_f32 v182, |v180|, v182, s65
	v_fma_f32 v182, |v180|, v182, |v180|
	v_mul_f32_e32 v184, 0xbfb8aa3b, v182
	v_fma_f32 v185, v182, s98, -v184
	v_rndne_f32_e32 v186, v184
	v_fmac_f32_e32 v185, 0xb2a5705f, v182
	v_sub_f32_e32 v184, v184, v186
	v_add_f32_e32 v184, v184, v185
	v_cvt_i32_f32_e32 v185, v186
	v_exp_f32_e32 v184, v184
	v_cmp_nlt_f32_e32 vcc, s70, v182
	v_ldexp_f32 v184, v184, v185
	s_nop 0
	v_cndmask_b32_e32 v184, 0, v184, vcc
	v_cmp_ngt_f32_e32 vcc, s71, v182
	s_nop 1
	v_cndmask_b32_e32 v184, v178, v184, vcc
	v_sub_f32_e32 v184, 1.0, v184
	v_mul_f32_e32 v183, v180, v180
	v_fmamk_f32 v185, v183, 0xba1345e1, v176
	v_fmaak_f32 v185, v183, v185, 0xbcdac9b8
	v_fmaak_f32 v185, v183, v185, 0x3de703be
	v_fmaak_f32 v185, v183, v185, 0xbec09330
	v_fmaak_f32 v183, v183, v185, 0x3e0375d0
	v_fma_f32 v183, |v180|, v183, |v180|
	v_cmp_nlt_f32_e64 vcc, |v180|, 1.0
	s_nop 1
	v_cndmask_b32_e32 v184, v183, v184, vcc
	v_bfi_b32 v184, s14, v184, v180
	v_add_f32_e32 v184, 1.0, v184
	v_mul_f32_e32 v86, 0.5, v86
	v_mul_f32_e32 v50, v50, v54
	v_mul_f32_e32 v86, v86, v184
	v_mul_f32_e32 v86, v50, v86
	v_mul_f32_e32 v87, v53, v87
	v_mul_f32_e32 v180, 0x3f3504f3, v87
	v_fma_f32 v182, |v180|, s16, v177
	v_fma_f32 v182, |v180|, v182, s19
	v_fma_f32 v182, |v180|, v182, s50
	v_fma_f32 v182, |v180|, v182, s51
	v_fma_f32 v182, |v180|, v182, s64
	v_fma_f32 v182, |v180|, v182, s65
	v_fma_f32 v182, |v180|, v182, |v180|
	v_mul_f32_e32 v184, 0xbfb8aa3b, v182
	v_fma_f32 v185, v182, s98, -v184
	v_rndne_f32_e32 v186, v184
	v_fmac_f32_e32 v185, 0xb2a5705f, v182
	v_sub_f32_e32 v184, v184, v186
	v_add_f32_e32 v184, v184, v185
	v_cvt_i32_f32_e32 v185, v186
	v_exp_f32_e32 v184, v184
	v_cmp_nlt_f32_e32 vcc, s70, v182
	v_ldexp_f32 v184, v184, v185
	s_nop 0
	v_cndmask_b32_e32 v184, 0, v184, vcc
	v_cmp_ngt_f32_e32 vcc, s71, v182
	s_nop 1
	v_cndmask_b32_e32 v184, v178, v184, vcc
	v_sub_f32_e32 v184, 1.0, v184
	v_mul_f32_e32 v183, v180, v180
	v_fmamk_f32 v185, v183, 0xba1345e1, v176
	v_fmaak_f32 v185, v183, v185, 0xbcdac9b8
	v_fmaak_f32 v185, v183, v185, 0x3de703be
	v_fmaak_f32 v185, v183, v185, 0xbec09330
	v_fmaak_f32 v183, v183, v185, 0x3e0375d0
	v_fma_f32 v183, |v180|, v183, |v180|
	v_cmp_nlt_f32_e64 vcc, |v180|, 1.0
	s_nop 1
	v_cndmask_b32_e32 v184, v183, v184, vcc
	v_bfi_b32 v184, s14, v184, v180
	v_add_f32_e32 v184, 1.0, v184
	v_mul_f32_e32 v87, 0.5, v87
	v_mul_f32_e32 v51, v51, v55
	v_mul_f32_e32 v87, v87, v184
	v_mul_f32_e32 v87, v51, v87
	global_store_dword v160, v86, s[12:13]
	global_store_dword v160, v87, s[12:13] offset:256
	s_add_u32 s12, s12, s18
	s_addc_u32 s13, s13, 0
	v_mul_f32_e32 v88, v58, v88
	v_mul_f32_e32 v180, 0x3f3504f3, v88
	v_fma_f32 v182, |v180|, s16, v177
	v_fma_f32 v182, |v180|, v182, s19
	v_fma_f32 v182, |v180|, v182, s50
	v_fma_f32 v182, |v180|, v182, s51
	v_fma_f32 v182, |v180|, v182, s64
	v_fma_f32 v182, |v180|, v182, s65
	v_fma_f32 v182, |v180|, v182, |v180|
	v_mul_f32_e32 v184, 0xbfb8aa3b, v182
	v_fma_f32 v185, v182, s98, -v184
	v_rndne_f32_e32 v186, v184
	v_fmac_f32_e32 v185, 0xb2a5705f, v182
	v_sub_f32_e32 v184, v184, v186
	v_add_f32_e32 v184, v184, v185
	v_cvt_i32_f32_e32 v185, v186
	v_exp_f32_e32 v184, v184
	v_cmp_nlt_f32_e32 vcc, s70, v182
	v_ldexp_f32 v184, v184, v185
	s_nop 0
	v_cndmask_b32_e32 v184, 0, v184, vcc
	v_cmp_ngt_f32_e32 vcc, s71, v182
	s_nop 1
	v_cndmask_b32_e32 v184, v178, v184, vcc
	v_sub_f32_e32 v184, 1.0, v184
	v_mul_f32_e32 v183, v180, v180
	v_fmamk_f32 v185, v183, 0xba1345e1, v176
	v_fmaak_f32 v185, v183, v185, 0xbcdac9b8
	v_fmaak_f32 v185, v183, v185, 0x3de703be
	v_fmaak_f32 v185, v183, v185, 0xbec09330
	v_fmaak_f32 v183, v183, v185, 0x3e0375d0
	v_fma_f32 v183, |v180|, v183, |v180|
	v_cmp_nlt_f32_e64 vcc, |v180|, 1.0
	s_nop 1
	v_cndmask_b32_e32 v184, v183, v184, vcc
	v_bfi_b32 v184, s14, v184, v180
	v_add_f32_e32 v184, 1.0, v184
	v_mul_f32_e32 v88, 0.5, v88
	v_mul_f32_e32 v56, v56, v60
	v_mul_f32_e32 v88, v88, v184
	v_mul_f32_e32 v88, v56, v88
	v_mul_f32_e32 v89, v59, v89
	v_mul_f32_e32 v180, 0x3f3504f3, v89
	v_fma_f32 v182, |v180|, s16, v177
	v_fma_f32 v182, |v180|, v182, s19
	v_fma_f32 v182, |v180|, v182, s50
	v_fma_f32 v182, |v180|, v182, s51
	v_fma_f32 v182, |v180|, v182, s64
	v_fma_f32 v182, |v180|, v182, s65
	v_fma_f32 v182, |v180|, v182, |v180|
	v_mul_f32_e32 v184, 0xbfb8aa3b, v182
	v_fma_f32 v185, v182, s98, -v184
	v_rndne_f32_e32 v186, v184
	v_fmac_f32_e32 v185, 0xb2a5705f, v182
	v_sub_f32_e32 v184, v184, v186
	v_add_f32_e32 v184, v184, v185
	v_cvt_i32_f32_e32 v185, v186
	v_exp_f32_e32 v184, v184
	v_cmp_nlt_f32_e32 vcc, s70, v182
	v_ldexp_f32 v184, v184, v185
	s_nop 0
	v_cndmask_b32_e32 v184, 0, v184, vcc
	v_cmp_ngt_f32_e32 vcc, s71, v182
	s_nop 1
	v_cndmask_b32_e32 v184, v178, v184, vcc
	v_sub_f32_e32 v184, 1.0, v184
	v_mul_f32_e32 v183, v180, v180
	v_fmamk_f32 v185, v183, 0xba1345e1, v176
	v_fmaak_f32 v185, v183, v185, 0xbcdac9b8
	v_fmaak_f32 v185, v183, v185, 0x3de703be
	v_fmaak_f32 v185, v183, v185, 0xbec09330
	v_fmaak_f32 v183, v183, v185, 0x3e0375d0
	v_fma_f32 v183, |v180|, v183, |v180|
	v_cmp_nlt_f32_e64 vcc, |v180|, 1.0
	s_nop 1
	v_cndmask_b32_e32 v184, v183, v184, vcc
	v_bfi_b32 v184, s14, v184, v180
	v_add_f32_e32 v184, 1.0, v184
	v_mul_f32_e32 v89, 0.5, v89
	v_mul_f32_e32 v57, v57, v61
	v_mul_f32_e32 v89, v89, v184
	v_mul_f32_e32 v89, v57, v89
	global_store_dword v160, v88, s[12:13]
	global_store_dword v160, v89, s[12:13] offset:256
	s_add_u32 s12, s12, s18
	s_addc_u32 s13, s13, 0
	v_mul_f32_e32 v90, v64, v90
	v_mul_f32_e32 v180, 0x3f3504f3, v90
	v_fma_f32 v182, |v180|, s16, v177
	v_fma_f32 v182, |v180|, v182, s19
	v_fma_f32 v182, |v180|, v182, s50
	v_fma_f32 v182, |v180|, v182, s51
	v_fma_f32 v182, |v180|, v182, s64
	v_fma_f32 v182, |v180|, v182, s65
	v_fma_f32 v182, |v180|, v182, |v180|
	v_mul_f32_e32 v184, 0xbfb8aa3b, v182
	v_fma_f32 v185, v182, s98, -v184
	v_rndne_f32_e32 v186, v184
	v_fmac_f32_e32 v185, 0xb2a5705f, v182
	v_sub_f32_e32 v184, v184, v186
	v_add_f32_e32 v184, v184, v185
	v_cvt_i32_f32_e32 v185, v186
	v_exp_f32_e32 v184, v184
	v_cmp_nlt_f32_e32 vcc, s70, v182
	v_ldexp_f32 v184, v184, v185
	s_nop 0
	v_cndmask_b32_e32 v184, 0, v184, vcc
	v_cmp_ngt_f32_e32 vcc, s71, v182
	s_nop 1
	v_cndmask_b32_e32 v184, v178, v184, vcc
	v_sub_f32_e32 v184, 1.0, v184
	v_mul_f32_e32 v183, v180, v180
	v_fmamk_f32 v185, v183, 0xba1345e1, v176
	v_fmaak_f32 v185, v183, v185, 0xbcdac9b8
	v_fmaak_f32 v185, v183, v185, 0x3de703be
	v_fmaak_f32 v185, v183, v185, 0xbec09330
	v_fmaak_f32 v183, v183, v185, 0x3e0375d0
	v_fma_f32 v183, |v180|, v183, |v180|
	v_cmp_nlt_f32_e64 vcc, |v180|, 1.0
	s_nop 1
	v_cndmask_b32_e32 v184, v183, v184, vcc
	v_bfi_b32 v184, s14, v184, v180
	v_add_f32_e32 v184, 1.0, v184
	v_mul_f32_e32 v90, 0.5, v90
	v_mul_f32_e32 v62, v62, v66
	v_mul_f32_e32 v90, v90, v184
	v_mul_f32_e32 v90, v62, v90
	v_mul_f32_e32 v91, v65, v91
	v_mul_f32_e32 v180, 0x3f3504f3, v91
	v_fma_f32 v182, |v180|, s16, v177
	v_fma_f32 v182, |v180|, v182, s19
	v_fma_f32 v182, |v180|, v182, s50
	v_fma_f32 v182, |v180|, v182, s51
	v_fma_f32 v182, |v180|, v182, s64
	v_fma_f32 v182, |v180|, v182, s65
	v_fma_f32 v182, |v180|, v182, |v180|
	v_mul_f32_e32 v184, 0xbfb8aa3b, v182
	v_fma_f32 v185, v182, s98, -v184
	v_rndne_f32_e32 v186, v184
	v_fmac_f32_e32 v185, 0xb2a5705f, v182
	v_sub_f32_e32 v184, v184, v186
	v_add_f32_e32 v184, v184, v185
	v_cvt_i32_f32_e32 v185, v186
	v_exp_f32_e32 v184, v184
	v_cmp_nlt_f32_e32 vcc, s70, v182
	v_ldexp_f32 v184, v184, v185
	s_nop 0
	v_cndmask_b32_e32 v184, 0, v184, vcc
	v_cmp_ngt_f32_e32 vcc, s71, v182
	s_nop 1
	v_cndmask_b32_e32 v184, v178, v184, vcc
	v_sub_f32_e32 v184, 1.0, v184
	v_mul_f32_e32 v183, v180, v180
	v_fmamk_f32 v185, v183, 0xba1345e1, v176
	v_fmaak_f32 v185, v183, v185, 0xbcdac9b8
	v_fmaak_f32 v185, v183, v185, 0x3de703be
	v_fmaak_f32 v185, v183, v185, 0xbec09330
	v_fmaak_f32 v183, v183, v185, 0x3e0375d0
	v_fma_f32 v183, |v180|, v183, |v180|
	v_cmp_nlt_f32_e64 vcc, |v180|, 1.0
	s_nop 1
	v_cndmask_b32_e32 v184, v183, v184, vcc
	v_bfi_b32 v184, s14, v184, v180
	v_add_f32_e32 v184, 1.0, v184
	v_mul_f32_e32 v91, 0.5, v91
	v_mul_f32_e32 v63, v63, v67
	v_mul_f32_e32 v91, v91, v184
	v_mul_f32_e32 v91, v63, v91
	global_store_dword v160, v90, s[12:13]
	global_store_dword v160, v91, s[12:13] offset:256
	s_add_u32 s12, s12, s18
	s_addc_u32 s13, s13, 0
	v_mul_f32_e32 v92, v70, v92
	v_mul_f32_e32 v180, 0x3f3504f3, v92
	v_fma_f32 v182, |v180|, s16, v177
	v_fma_f32 v182, |v180|, v182, s19
	v_fma_f32 v182, |v180|, v182, s50
	v_fma_f32 v182, |v180|, v182, s51
	v_fma_f32 v182, |v180|, v182, s64
	v_fma_f32 v182, |v180|, v182, s65
	v_fma_f32 v182, |v180|, v182, |v180|
	v_mul_f32_e32 v184, 0xbfb8aa3b, v182
	v_fma_f32 v185, v182, s98, -v184
	v_rndne_f32_e32 v186, v184
	v_fmac_f32_e32 v185, 0xb2a5705f, v182
	v_sub_f32_e32 v184, v184, v186
	v_add_f32_e32 v184, v184, v185
	v_cvt_i32_f32_e32 v185, v186
	v_exp_f32_e32 v184, v184
	v_cmp_nlt_f32_e32 vcc, s70, v182
	v_ldexp_f32 v184, v184, v185
	s_nop 0
	v_cndmask_b32_e32 v184, 0, v184, vcc
	v_cmp_ngt_f32_e32 vcc, s71, v182
	s_nop 1
	v_cndmask_b32_e32 v184, v178, v184, vcc
	v_sub_f32_e32 v184, 1.0, v184
	v_mul_f32_e32 v183, v180, v180
	v_fmamk_f32 v185, v183, 0xba1345e1, v176
	v_fmaak_f32 v185, v183, v185, 0xbcdac9b8
	v_fmaak_f32 v185, v183, v185, 0x3de703be
	v_fmaak_f32 v185, v183, v185, 0xbec09330
	v_fmaak_f32 v183, v183, v185, 0x3e0375d0
	v_fma_f32 v183, |v180|, v183, |v180|
	v_cmp_nlt_f32_e64 vcc, |v180|, 1.0
	s_nop 1
	v_cndmask_b32_e32 v184, v183, v184, vcc
	v_bfi_b32 v184, s14, v184, v180
	v_add_f32_e32 v184, 1.0, v184
	v_mul_f32_e32 v92, 0.5, v92
	v_mul_f32_e32 v68, v68, v72
	v_mul_f32_e32 v92, v92, v184
	v_mul_f32_e32 v92, v68, v92
	v_mul_f32_e32 v93, v71, v93
	v_mul_f32_e32 v180, 0x3f3504f3, v93
	v_fma_f32 v182, |v180|, s16, v177
	v_fma_f32 v182, |v180|, v182, s19
	v_fma_f32 v182, |v180|, v182, s50
	v_fma_f32 v182, |v180|, v182, s51
	v_fma_f32 v182, |v180|, v182, s64
	v_fma_f32 v182, |v180|, v182, s65
	v_fma_f32 v182, |v180|, v182, |v180|
	v_mul_f32_e32 v184, 0xbfb8aa3b, v182
	v_fma_f32 v185, v182, s98, -v184
	v_rndne_f32_e32 v186, v184
	v_fmac_f32_e32 v185, 0xb2a5705f, v182
	v_sub_f32_e32 v184, v184, v186
	v_add_f32_e32 v184, v184, v185
	v_cvt_i32_f32_e32 v185, v186
	v_exp_f32_e32 v184, v184
	v_cmp_nlt_f32_e32 vcc, s70, v182
	v_ldexp_f32 v184, v184, v185
	s_nop 0
	v_cndmask_b32_e32 v184, 0, v184, vcc
	v_cmp_ngt_f32_e32 vcc, s71, v182
	s_nop 1
	v_cndmask_b32_e32 v184, v178, v184, vcc
	v_sub_f32_e32 v184, 1.0, v184
	v_mul_f32_e32 v183, v180, v180
	v_fmamk_f32 v185, v183, 0xba1345e1, v176
	v_fmaak_f32 v185, v183, v185, 0xbcdac9b8
	v_fmaak_f32 v185, v183, v185, 0x3de703be
	v_fmaak_f32 v185, v183, v185, 0xbec09330
	v_fmaak_f32 v183, v183, v185, 0x3e0375d0
	v_fma_f32 v183, |v180|, v183, |v180|
	v_cmp_nlt_f32_e64 vcc, |v180|, 1.0
	s_nop 1
	v_cndmask_b32_e32 v184, v183, v184, vcc
	v_bfi_b32 v184, s14, v184, v180
	v_add_f32_e32 v184, 1.0, v184
	v_mul_f32_e32 v93, 0.5, v93
	v_mul_f32_e32 v69, v69, v73
	v_mul_f32_e32 v93, v93, v184
	v_mul_f32_e32 v93, v69, v93
	global_store_dword v160, v92, s[12:13]
	global_store_dword v160, v93, s[12:13] offset:256
	s_add_u32 s12, s12, s18
	s_addc_u32 s13, s13, 0
	v_mul_f32_e32 v94, v76, v94
	v_mul_f32_e32 v180, 0x3f3504f3, v94
	v_fma_f32 v182, |v180|, s16, v177
	v_fma_f32 v182, |v180|, v182, s19
	v_fma_f32 v182, |v180|, v182, s50
	v_fma_f32 v182, |v180|, v182, s51
	v_fma_f32 v182, |v180|, v182, s64
	v_fma_f32 v182, |v180|, v182, s65
	v_fma_f32 v182, |v180|, v182, |v180|
	v_mul_f32_e32 v184, 0xbfb8aa3b, v182
	v_fma_f32 v185, v182, s98, -v184
	v_rndne_f32_e32 v186, v184
	v_fmac_f32_e32 v185, 0xb2a5705f, v182
	v_sub_f32_e32 v184, v184, v186
	v_add_f32_e32 v184, v184, v185
	v_cvt_i32_f32_e32 v185, v186
	v_exp_f32_e32 v184, v184
	v_cmp_nlt_f32_e32 vcc, s70, v182
	v_ldexp_f32 v184, v184, v185
	s_nop 0
	v_cndmask_b32_e32 v184, 0, v184, vcc
	v_cmp_ngt_f32_e32 vcc, s71, v182
	s_nop 1
	v_cndmask_b32_e32 v184, v178, v184, vcc
	v_sub_f32_e32 v184, 1.0, v184
	v_mul_f32_e32 v183, v180, v180
	v_fmamk_f32 v185, v183, 0xba1345e1, v176
	v_fmaak_f32 v185, v183, v185, 0xbcdac9b8
	v_fmaak_f32 v185, v183, v185, 0x3de703be
	v_fmaak_f32 v185, v183, v185, 0xbec09330
	v_fmaak_f32 v183, v183, v185, 0x3e0375d0
	v_fma_f32 v183, |v180|, v183, |v180|
	v_cmp_nlt_f32_e64 vcc, |v180|, 1.0
	s_nop 1
	v_cndmask_b32_e32 v184, v183, v184, vcc
	v_bfi_b32 v184, s14, v184, v180
	v_add_f32_e32 v184, 1.0, v184
	v_mul_f32_e32 v94, 0.5, v94
	v_mul_f32_e32 v74, v74, v78
	v_mul_f32_e32 v94, v94, v184
	v_mul_f32_e32 v94, v74, v94
	v_mul_f32_e32 v95, v77, v95
	v_mul_f32_e32 v180, 0x3f3504f3, v95
	v_fma_f32 v182, |v180|, s16, v177
	v_fma_f32 v182, |v180|, v182, s19
	v_fma_f32 v182, |v180|, v182, s50
	v_fma_f32 v182, |v180|, v182, s51
	v_fma_f32 v182, |v180|, v182, s64
	v_fma_f32 v182, |v180|, v182, s65
	v_fma_f32 v182, |v180|, v182, |v180|
	v_mul_f32_e32 v184, 0xbfb8aa3b, v182
	v_fma_f32 v185, v182, s98, -v184
	v_rndne_f32_e32 v186, v184
	v_fmac_f32_e32 v185, 0xb2a5705f, v182
	v_sub_f32_e32 v184, v184, v186
	v_add_f32_e32 v184, v184, v185
	v_cvt_i32_f32_e32 v185, v186
	v_exp_f32_e32 v184, v184
	v_cmp_nlt_f32_e32 vcc, s70, v182
	v_ldexp_f32 v184, v184, v185
	s_nop 0
	v_cndmask_b32_e32 v184, 0, v184, vcc
	v_cmp_ngt_f32_e32 vcc, s71, v182
	s_nop 1
	v_cndmask_b32_e32 v184, v178, v184, vcc
	v_sub_f32_e32 v184, 1.0, v184
	v_mul_f32_e32 v183, v180, v180
	v_fmamk_f32 v185, v183, 0xba1345e1, v176
	v_fmaak_f32 v185, v183, v185, 0xbcdac9b8
	v_fmaak_f32 v185, v183, v185, 0x3de703be
	v_fmaak_f32 v185, v183, v185, 0xbec09330
	v_fmaak_f32 v183, v183, v185, 0x3e0375d0
	v_fma_f32 v183, |v180|, v183, |v180|
	v_cmp_nlt_f32_e64 vcc, |v180|, 1.0
	s_nop 1
	v_cndmask_b32_e32 v184, v183, v184, vcc
	v_bfi_b32 v184, s14, v184, v180
	v_add_f32_e32 v184, 1.0, v184
	v_mul_f32_e32 v95, 0.5, v95
	v_mul_f32_e32 v75, v75, v79
	v_mul_f32_e32 v95, v95, v184
	v_mul_f32_e32 v95, v75, v95
	global_store_dword v160, v94, s[12:13]
	global_store_dword v160, v95, s[12:13] offset:256
	s_add_u32 s12, s12, s18
	s_addc_u32 s13, s13, 0
	ds_read2st64_b32 v[16:17], v174 offset0:16 offset1:17
	ds_read2st64_b32 v[80:81], v175 offset0:16 offset1:17
	ds_read2st64_b32 v[18:19], v174 offset0:18 offset1:19
	ds_read2st64_b32 v[82:83], v175 offset0:18 offset1:19
	ds_read2st64_b32 v[20:21], v174 offset0:20 offset1:21
	ds_read2st64_b32 v[84:85], v175 offset0:20 offset1:21
	ds_read2st64_b32 v[22:23], v174 offset0:22 offset1:23
	ds_read2st64_b32 v[86:87], v175 offset0:22 offset1:23
	ds_read2st64_b32 v[24:25], v174 offset0:24 offset1:25
	ds_read2st64_b32 v[88:89], v175 offset0:24 offset1:25
	ds_read2st64_b32 v[26:27], v174 offset0:26 offset1:27
	ds_read2st64_b32 v[90:91], v175 offset0:26 offset1:27
	ds_read2st64_b32 v[28:29], v174 offset0:28 offset1:29
	ds_read2st64_b32 v[92:93], v175 offset0:28 offset1:29
	ds_read2st64_b32 v[30:31], v174 offset0:30 offset1:31
	ds_read2st64_b32 v[94:95], v175 offset0:30 offset1:31
	s_waitcnt lgkmcnt(0)
	v_lshlrev_b32_e32 v16, 2, v16
	v_lshlrev_b32_e32 v17, 2, v17
	v_lshlrev_b32_e32 v18, 2, v18
	v_lshlrev_b32_e32 v19, 2, v19
	v_lshlrev_b32_e32 v20, 2, v20
	v_lshlrev_b32_e32 v21, 2, v21
	v_lshlrev_b32_e32 v22, 2, v22
	v_lshlrev_b32_e32 v23, 2, v23
	v_lshlrev_b32_e32 v24, 2, v24
	v_lshlrev_b32_e32 v25, 2, v25
	v_lshlrev_b32_e32 v26, 2, v26
	v_lshlrev_b32_e32 v27, 2, v27
	v_lshlrev_b32_e32 v28, 2, v28
	v_lshlrev_b32_e32 v29, 2, v29
	v_lshlrev_b32_e32 v30, 2, v30
	v_lshlrev_b32_e32 v31, 2, v31
	global_load_dword v32, v160, s[10:11]
	global_load_dword v33, v160, s[10:11] offset:256
	global_load_dword v34, v16, s[4:5]
	global_load_dword v35, v17, s[4:5]
	global_load_dword v36, v16, s[8:9]
	global_load_dword v37, v17, s[8:9]
	s_add_u32 s10, s10, s18
	s_addc_u32 s11, s11, 0
	global_load_dword v38, v160, s[10:11]
	global_load_dword v39, v160, s[10:11] offset:256
	global_load_dword v40, v18, s[4:5]
	global_load_dword v41, v19, s[4:5]
	global_load_dword v42, v18, s[8:9]
	global_load_dword v43, v19, s[8:9]
	s_add_u32 s10, s10, s18
	s_addc_u32 s11, s11, 0
	global_load_dword v44, v160, s[10:11]
	global_load_dword v45, v160, s[10:11] offset:256
	global_load_dword v46, v20, s[4:5]
	global_load_dword v47, v21, s[4:5]
	global_load_dword v48, v20, s[8:9]
	global_load_dword v49, v21, s[8:9]
	s_add_u32 s10, s10, s18
	s_addc_u32 s11, s11, 0
	global_load_dword v50, v160, s[10:11]
	global_load_dword v51, v160, s[10:11] offset:256
	global_load_dword v52, v22, s[4:5]
	global_load_dword v53, v23, s[4:5]
	global_load_dword v54, v22, s[8:9]
	global_load_dword v55, v23, s[8:9]
	s_add_u32 s10, s10, s18
	s_addc_u32 s11, s11, 0
	global_load_dword v56, v160, s[10:11]
	global_load_dword v57, v160, s[10:11] offset:256
	global_load_dword v58, v24, s[4:5]
	global_load_dword v59, v25, s[4:5]
	global_load_dword v60, v24, s[8:9]
	global_load_dword v61, v25, s[8:9]
	s_add_u32 s10, s10, s18
	s_addc_u32 s11, s11, 0
	global_load_dword v62, v160, s[10:11]
	global_load_dword v63, v160, s[10:11] offset:256
	global_load_dword v64, v26, s[4:5]
	global_load_dword v65, v27, s[4:5]
	global_load_dword v66, v26, s[8:9]
	global_load_dword v67, v27, s[8:9]
	s_add_u32 s10, s10, s18
	s_addc_u32 s11, s11, 0
	global_load_dword v68, v160, s[10:11]
	global_load_dword v69, v160, s[10:11] offset:256
	global_load_dword v70, v28, s[4:5]
	global_load_dword v71, v29, s[4:5]
	global_load_dword v72, v28, s[8:9]
	global_load_dword v73, v29, s[8:9]
	s_add_u32 s10, s10, s18
	s_addc_u32 s11, s11, 0
	global_load_dword v74, v160, s[10:11]
	global_load_dword v75, v160, s[10:11] offset:256
	global_load_dword v76, v30, s[4:5]
	global_load_dword v77, v31, s[4:5]
	global_load_dword v78, v30, s[8:9]
	global_load_dword v79, v31, s[8:9]
	s_add_u32 s10, s10, s18
	s_addc_u32 s11, s11, 0
	s_waitcnt vmcnt(0)
	v_mul_f32_e32 v80, v34, v80
	v_mul_f32_e32 v180, 0x3f3504f3, v80
	v_fma_f32 v182, |v180|, s16, v177
	v_fma_f32 v182, |v180|, v182, s19
	v_fma_f32 v182, |v180|, v182, s50
	v_fma_f32 v182, |v180|, v182, s51
	v_fma_f32 v182, |v180|, v182, s64
	v_fma_f32 v182, |v180|, v182, s65
	v_fma_f32 v182, |v180|, v182, |v180|
	v_mul_f32_e32 v184, 0xbfb8aa3b, v182
	v_fma_f32 v185, v182, s98, -v184
	v_rndne_f32_e32 v186, v184
	v_fmac_f32_e32 v185, 0xb2a5705f, v182
	v_sub_f32_e32 v184, v184, v186
	v_add_f32_e32 v184, v184, v185
	v_cvt_i32_f32_e32 v185, v186
	v_exp_f32_e32 v184, v184
	v_cmp_nlt_f32_e32 vcc, s70, v182
	v_ldexp_f32 v184, v184, v185
	s_nop 0
	v_cndmask_b32_e32 v184, 0, v184, vcc
	v_cmp_ngt_f32_e32 vcc, s71, v182
	s_nop 1
	v_cndmask_b32_e32 v184, v178, v184, vcc
	v_sub_f32_e32 v184, 1.0, v184
	v_mul_f32_e32 v183, v180, v180
	v_fmamk_f32 v185, v183, 0xba1345e1, v176
	v_fmaak_f32 v185, v183, v185, 0xbcdac9b8
	v_fmaak_f32 v185, v183, v185, 0x3de703be
	v_fmaak_f32 v185, v183, v185, 0xbec09330
	v_fmaak_f32 v183, v183, v185, 0x3e0375d0
	v_fma_f32 v183, |v180|, v183, |v180|
	v_cmp_nlt_f32_e64 vcc, |v180|, 1.0
	s_nop 1
	v_cndmask_b32_e32 v184, v183, v184, vcc
	v_bfi_b32 v184, s14, v184, v180
	v_add_f32_e32 v184, 1.0, v184
	v_mul_f32_e32 v80, 0.5, v80
	v_mul_f32_e32 v32, v32, v36
	v_mul_f32_e32 v80, v80, v184
	v_mul_f32_e32 v80, v32, v80
	v_mul_f32_e32 v81, v35, v81
	v_mul_f32_e32 v180, 0x3f3504f3, v81
	v_fma_f32 v182, |v180|, s16, v177
	v_fma_f32 v182, |v180|, v182, s19
	v_fma_f32 v182, |v180|, v182, s50
	v_fma_f32 v182, |v180|, v182, s51
	v_fma_f32 v182, |v180|, v182, s64
	v_fma_f32 v182, |v180|, v182, s65
	v_fma_f32 v182, |v180|, v182, |v180|
	v_mul_f32_e32 v184, 0xbfb8aa3b, v182
	v_fma_f32 v185, v182, s98, -v184
	v_rndne_f32_e32 v186, v184
	v_fmac_f32_e32 v185, 0xb2a5705f, v182
	v_sub_f32_e32 v184, v184, v186
	v_add_f32_e32 v184, v184, v185
	v_cvt_i32_f32_e32 v185, v186
	v_exp_f32_e32 v184, v184
	v_cmp_nlt_f32_e32 vcc, s70, v182
	v_ldexp_f32 v184, v184, v185
	s_nop 0
	v_cndmask_b32_e32 v184, 0, v184, vcc
	v_cmp_ngt_f32_e32 vcc, s71, v182
	s_nop 1
	v_cndmask_b32_e32 v184, v178, v184, vcc
	v_sub_f32_e32 v184, 1.0, v184
	v_mul_f32_e32 v183, v180, v180
	v_fmamk_f32 v185, v183, 0xba1345e1, v176
	v_fmaak_f32 v185, v183, v185, 0xbcdac9b8
	v_fmaak_f32 v185, v183, v185, 0x3de703be
	v_fmaak_f32 v185, v183, v185, 0xbec09330
	v_fmaak_f32 v183, v183, v185, 0x3e0375d0
	v_fma_f32 v183, |v180|, v183, |v180|
	v_cmp_nlt_f32_e64 vcc, |v180|, 1.0
	s_nop 1
	v_cndmask_b32_e32 v184, v183, v184, vcc
	v_bfi_b32 v184, s14, v184, v180
	v_add_f32_e32 v184, 1.0, v184
	v_mul_f32_e32 v81, 0.5, v81
	v_mul_f32_e32 v33, v33, v37
	v_mul_f32_e32 v81, v81, v184
	v_mul_f32_e32 v81, v33, v81
	global_store_dword v160, v80, s[12:13]
	global_store_dword v160, v81, s[12:13] offset:256
	s_add_u32 s12, s12, s18
	s_addc_u32 s13, s13, 0
	v_mul_f32_e32 v82, v40, v82
	v_mul_f32_e32 v180, 0x3f3504f3, v82
	v_fma_f32 v182, |v180|, s16, v177
	v_fma_f32 v182, |v180|, v182, s19
	v_fma_f32 v182, |v180|, v182, s50
	v_fma_f32 v182, |v180|, v182, s51
	v_fma_f32 v182, |v180|, v182, s64
	v_fma_f32 v182, |v180|, v182, s65
	v_fma_f32 v182, |v180|, v182, |v180|
	v_mul_f32_e32 v184, 0xbfb8aa3b, v182
	v_fma_f32 v185, v182, s98, -v184
	v_rndne_f32_e32 v186, v184
	v_fmac_f32_e32 v185, 0xb2a5705f, v182
	v_sub_f32_e32 v184, v184, v186
	v_add_f32_e32 v184, v184, v185
	v_cvt_i32_f32_e32 v185, v186
	v_exp_f32_e32 v184, v184
	v_cmp_nlt_f32_e32 vcc, s70, v182
	v_ldexp_f32 v184, v184, v185
	s_nop 0
	v_cndmask_b32_e32 v184, 0, v184, vcc
	v_cmp_ngt_f32_e32 vcc, s71, v182
	s_nop 1
	v_cndmask_b32_e32 v184, v178, v184, vcc
	v_sub_f32_e32 v184, 1.0, v184
	v_mul_f32_e32 v183, v180, v180
	v_fmamk_f32 v185, v183, 0xba1345e1, v176
	v_fmaak_f32 v185, v183, v185, 0xbcdac9b8
	v_fmaak_f32 v185, v183, v185, 0x3de703be
	v_fmaak_f32 v185, v183, v185, 0xbec09330
	v_fmaak_f32 v183, v183, v185, 0x3e0375d0
	v_fma_f32 v183, |v180|, v183, |v180|
	v_cmp_nlt_f32_e64 vcc, |v180|, 1.0
	s_nop 1
	v_cndmask_b32_e32 v184, v183, v184, vcc
	v_bfi_b32 v184, s14, v184, v180
	v_add_f32_e32 v184, 1.0, v184
	v_mul_f32_e32 v82, 0.5, v82
	v_mul_f32_e32 v38, v38, v42
	v_mul_f32_e32 v82, v82, v184
	v_mul_f32_e32 v82, v38, v82
	v_mul_f32_e32 v83, v41, v83
	v_mul_f32_e32 v180, 0x3f3504f3, v83
	v_fma_f32 v182, |v180|, s16, v177
	v_fma_f32 v182, |v180|, v182, s19
	v_fma_f32 v182, |v180|, v182, s50
	v_fma_f32 v182, |v180|, v182, s51
	v_fma_f32 v182, |v180|, v182, s64
	v_fma_f32 v182, |v180|, v182, s65
	v_fma_f32 v182, |v180|, v182, |v180|
	v_mul_f32_e32 v184, 0xbfb8aa3b, v182
	v_fma_f32 v185, v182, s98, -v184
	v_rndne_f32_e32 v186, v184
	v_fmac_f32_e32 v185, 0xb2a5705f, v182
	v_sub_f32_e32 v184, v184, v186
	v_add_f32_e32 v184, v184, v185
	v_cvt_i32_f32_e32 v185, v186
	v_exp_f32_e32 v184, v184
	v_cmp_nlt_f32_e32 vcc, s70, v182
	v_ldexp_f32 v184, v184, v185
	s_nop 0
	v_cndmask_b32_e32 v184, 0, v184, vcc
	v_cmp_ngt_f32_e32 vcc, s71, v182
	s_nop 1
	v_cndmask_b32_e32 v184, v178, v184, vcc
	v_sub_f32_e32 v184, 1.0, v184
	v_mul_f32_e32 v183, v180, v180
	v_fmamk_f32 v185, v183, 0xba1345e1, v176
	v_fmaak_f32 v185, v183, v185, 0xbcdac9b8
	v_fmaak_f32 v185, v183, v185, 0x3de703be
	v_fmaak_f32 v185, v183, v185, 0xbec09330
	v_fmaak_f32 v183, v183, v185, 0x3e0375d0
	v_fma_f32 v183, |v180|, v183, |v180|
	v_cmp_nlt_f32_e64 vcc, |v180|, 1.0
	s_nop 1
	v_cndmask_b32_e32 v184, v183, v184, vcc
	v_bfi_b32 v184, s14, v184, v180
	v_add_f32_e32 v184, 1.0, v184
	v_mul_f32_e32 v83, 0.5, v83
	v_mul_f32_e32 v39, v39, v43
	v_mul_f32_e32 v83, v83, v184
	v_mul_f32_e32 v83, v39, v83
	global_store_dword v160, v82, s[12:13]
	global_store_dword v160, v83, s[12:13] offset:256
	s_add_u32 s12, s12, s18
	s_addc_u32 s13, s13, 0
	v_mul_f32_e32 v84, v46, v84
	v_mul_f32_e32 v180, 0x3f3504f3, v84
	v_fma_f32 v182, |v180|, s16, v177
	v_fma_f32 v182, |v180|, v182, s19
	v_fma_f32 v182, |v180|, v182, s50
	v_fma_f32 v182, |v180|, v182, s51
	v_fma_f32 v182, |v180|, v182, s64
	v_fma_f32 v182, |v180|, v182, s65
	v_fma_f32 v182, |v180|, v182, |v180|
	v_mul_f32_e32 v184, 0xbfb8aa3b, v182
	v_fma_f32 v185, v182, s98, -v184
	v_rndne_f32_e32 v186, v184
	v_fmac_f32_e32 v185, 0xb2a5705f, v182
	v_sub_f32_e32 v184, v184, v186
	v_add_f32_e32 v184, v184, v185
	v_cvt_i32_f32_e32 v185, v186
	v_exp_f32_e32 v184, v184
	v_cmp_nlt_f32_e32 vcc, s70, v182
	v_ldexp_f32 v184, v184, v185
	s_nop 0
	v_cndmask_b32_e32 v184, 0, v184, vcc
	v_cmp_ngt_f32_e32 vcc, s71, v182
	s_nop 1
	v_cndmask_b32_e32 v184, v178, v184, vcc
	v_sub_f32_e32 v184, 1.0, v184
	v_mul_f32_e32 v183, v180, v180
	v_fmamk_f32 v185, v183, 0xba1345e1, v176
	v_fmaak_f32 v185, v183, v185, 0xbcdac9b8
	v_fmaak_f32 v185, v183, v185, 0x3de703be
	v_fmaak_f32 v185, v183, v185, 0xbec09330
	v_fmaak_f32 v183, v183, v185, 0x3e0375d0
	v_fma_f32 v183, |v180|, v183, |v180|
	v_cmp_nlt_f32_e64 vcc, |v180|, 1.0
	s_nop 1
	v_cndmask_b32_e32 v184, v183, v184, vcc
	v_bfi_b32 v184, s14, v184, v180
	v_add_f32_e32 v184, 1.0, v184
	v_mul_f32_e32 v84, 0.5, v84
	v_mul_f32_e32 v44, v44, v48
	v_mul_f32_e32 v84, v84, v184
	v_mul_f32_e32 v84, v44, v84
	v_mul_f32_e32 v85, v47, v85
	v_mul_f32_e32 v180, 0x3f3504f3, v85
	v_fma_f32 v182, |v180|, s16, v177
	v_fma_f32 v182, |v180|, v182, s19
	v_fma_f32 v182, |v180|, v182, s50
	v_fma_f32 v182, |v180|, v182, s51
	v_fma_f32 v182, |v180|, v182, s64
	v_fma_f32 v182, |v180|, v182, s65
	v_fma_f32 v182, |v180|, v182, |v180|
	v_mul_f32_e32 v184, 0xbfb8aa3b, v182
	v_fma_f32 v185, v182, s98, -v184
	v_rndne_f32_e32 v186, v184
	v_fmac_f32_e32 v185, 0xb2a5705f, v182
	v_sub_f32_e32 v184, v184, v186
	v_add_f32_e32 v184, v184, v185
	v_cvt_i32_f32_e32 v185, v186
	v_exp_f32_e32 v184, v184
	v_cmp_nlt_f32_e32 vcc, s70, v182
	v_ldexp_f32 v184, v184, v185
	s_nop 0
	v_cndmask_b32_e32 v184, 0, v184, vcc
	v_cmp_ngt_f32_e32 vcc, s71, v182
	s_nop 1
	v_cndmask_b32_e32 v184, v178, v184, vcc
	v_sub_f32_e32 v184, 1.0, v184
	v_mul_f32_e32 v183, v180, v180
	v_fmamk_f32 v185, v183, 0xba1345e1, v176
	v_fmaak_f32 v185, v183, v185, 0xbcdac9b8
	v_fmaak_f32 v185, v183, v185, 0x3de703be
	v_fmaak_f32 v185, v183, v185, 0xbec09330
	v_fmaak_f32 v183, v183, v185, 0x3e0375d0
	v_fma_f32 v183, |v180|, v183, |v180|
	v_cmp_nlt_f32_e64 vcc, |v180|, 1.0
	s_nop 1
	v_cndmask_b32_e32 v184, v183, v184, vcc
	v_bfi_b32 v184, s14, v184, v180
	v_add_f32_e32 v184, 1.0, v184
	v_mul_f32_e32 v85, 0.5, v85
	v_mul_f32_e32 v45, v45, v49
	v_mul_f32_e32 v85, v85, v184
	v_mul_f32_e32 v85, v45, v85
	global_store_dword v160, v84, s[12:13]
	global_store_dword v160, v85, s[12:13] offset:256
	s_add_u32 s12, s12, s18
	s_addc_u32 s13, s13, 0
	v_mul_f32_e32 v86, v52, v86
	v_mul_f32_e32 v180, 0x3f3504f3, v86
	v_fma_f32 v182, |v180|, s16, v177
	v_fma_f32 v182, |v180|, v182, s19
	v_fma_f32 v182, |v180|, v182, s50
	v_fma_f32 v182, |v180|, v182, s51
	v_fma_f32 v182, |v180|, v182, s64
	v_fma_f32 v182, |v180|, v182, s65
	v_fma_f32 v182, |v180|, v182, |v180|
	v_mul_f32_e32 v184, 0xbfb8aa3b, v182
	v_fma_f32 v185, v182, s98, -v184
	v_rndne_f32_e32 v186, v184
	v_fmac_f32_e32 v185, 0xb2a5705f, v182
	v_sub_f32_e32 v184, v184, v186
	v_add_f32_e32 v184, v184, v185
	v_cvt_i32_f32_e32 v185, v186
	v_exp_f32_e32 v184, v184
	v_cmp_nlt_f32_e32 vcc, s70, v182
	v_ldexp_f32 v184, v184, v185
	s_nop 0
	v_cndmask_b32_e32 v184, 0, v184, vcc
	v_cmp_ngt_f32_e32 vcc, s71, v182
	s_nop 1
	v_cndmask_b32_e32 v184, v178, v184, vcc
	v_sub_f32_e32 v184, 1.0, v184
	v_mul_f32_e32 v183, v180, v180
	v_fmamk_f32 v185, v183, 0xba1345e1, v176
	v_fmaak_f32 v185, v183, v185, 0xbcdac9b8
	v_fmaak_f32 v185, v183, v185, 0x3de703be
	v_fmaak_f32 v185, v183, v185, 0xbec09330
	v_fmaak_f32 v183, v183, v185, 0x3e0375d0
	v_fma_f32 v183, |v180|, v183, |v180|
	v_cmp_nlt_f32_e64 vcc, |v180|, 1.0
	s_nop 1
	v_cndmask_b32_e32 v184, v183, v184, vcc
	v_bfi_b32 v184, s14, v184, v180
	v_add_f32_e32 v184, 1.0, v184
	v_mul_f32_e32 v86, 0.5, v86
	v_mul_f32_e32 v50, v50, v54
	v_mul_f32_e32 v86, v86, v184
	v_mul_f32_e32 v86, v50, v86
	v_mul_f32_e32 v87, v53, v87
	v_mul_f32_e32 v180, 0x3f3504f3, v87
	v_fma_f32 v182, |v180|, s16, v177
	v_fma_f32 v182, |v180|, v182, s19
	v_fma_f32 v182, |v180|, v182, s50
	v_fma_f32 v182, |v180|, v182, s51
	v_fma_f32 v182, |v180|, v182, s64
	v_fma_f32 v182, |v180|, v182, s65
	v_fma_f32 v182, |v180|, v182, |v180|
	v_mul_f32_e32 v184, 0xbfb8aa3b, v182
	v_fma_f32 v185, v182, s98, -v184
	v_rndne_f32_e32 v186, v184
	v_fmac_f32_e32 v185, 0xb2a5705f, v182
	v_sub_f32_e32 v184, v184, v186
	v_add_f32_e32 v184, v184, v185
	v_cvt_i32_f32_e32 v185, v186
	v_exp_f32_e32 v184, v184
	v_cmp_nlt_f32_e32 vcc, s70, v182
	v_ldexp_f32 v184, v184, v185
	s_nop 0
	v_cndmask_b32_e32 v184, 0, v184, vcc
	v_cmp_ngt_f32_e32 vcc, s71, v182
	s_nop 1
	v_cndmask_b32_e32 v184, v178, v184, vcc
	v_sub_f32_e32 v184, 1.0, v184
	v_mul_f32_e32 v183, v180, v180
	v_fmamk_f32 v185, v183, 0xba1345e1, v176
	v_fmaak_f32 v185, v183, v185, 0xbcdac9b8
	v_fmaak_f32 v185, v183, v185, 0x3de703be
	v_fmaak_f32 v185, v183, v185, 0xbec09330
	v_fmaak_f32 v183, v183, v185, 0x3e0375d0
	v_fma_f32 v183, |v180|, v183, |v180|
	v_cmp_nlt_f32_e64 vcc, |v180|, 1.0
	s_nop 1
	v_cndmask_b32_e32 v184, v183, v184, vcc
	v_bfi_b32 v184, s14, v184, v180
	v_add_f32_e32 v184, 1.0, v184
	v_mul_f32_e32 v87, 0.5, v87
	v_mul_f32_e32 v51, v51, v55
	v_mul_f32_e32 v87, v87, v184
	v_mul_f32_e32 v87, v51, v87
	global_store_dword v160, v86, s[12:13]
	global_store_dword v160, v87, s[12:13] offset:256
	s_add_u32 s12, s12, s18
	s_addc_u32 s13, s13, 0
	v_mul_f32_e32 v88, v58, v88
	v_mul_f32_e32 v180, 0x3f3504f3, v88
	v_fma_f32 v182, |v180|, s16, v177
	v_fma_f32 v182, |v180|, v182, s19
	v_fma_f32 v182, |v180|, v182, s50
	v_fma_f32 v182, |v180|, v182, s51
	v_fma_f32 v182, |v180|, v182, s64
	v_fma_f32 v182, |v180|, v182, s65
	v_fma_f32 v182, |v180|, v182, |v180|
	v_mul_f32_e32 v184, 0xbfb8aa3b, v182
	v_fma_f32 v185, v182, s98, -v184
	v_rndne_f32_e32 v186, v184
	v_fmac_f32_e32 v185, 0xb2a5705f, v182
	v_sub_f32_e32 v184, v184, v186
	v_add_f32_e32 v184, v184, v185
	v_cvt_i32_f32_e32 v185, v186
	v_exp_f32_e32 v184, v184
	v_cmp_nlt_f32_e32 vcc, s70, v182
	v_ldexp_f32 v184, v184, v185
	s_nop 0
	v_cndmask_b32_e32 v184, 0, v184, vcc
	v_cmp_ngt_f32_e32 vcc, s71, v182
	s_nop 1
	v_cndmask_b32_e32 v184, v178, v184, vcc
	v_sub_f32_e32 v184, 1.0, v184
	v_mul_f32_e32 v183, v180, v180
	v_fmamk_f32 v185, v183, 0xba1345e1, v176
	v_fmaak_f32 v185, v183, v185, 0xbcdac9b8
	v_fmaak_f32 v185, v183, v185, 0x3de703be
	v_fmaak_f32 v185, v183, v185, 0xbec09330
	v_fmaak_f32 v183, v183, v185, 0x3e0375d0
	v_fma_f32 v183, |v180|, v183, |v180|
	v_cmp_nlt_f32_e64 vcc, |v180|, 1.0
	s_nop 1
	v_cndmask_b32_e32 v184, v183, v184, vcc
	v_bfi_b32 v184, s14, v184, v180
	v_add_f32_e32 v184, 1.0, v184
	v_mul_f32_e32 v88, 0.5, v88
	v_mul_f32_e32 v56, v56, v60
	v_mul_f32_e32 v88, v88, v184
	v_mul_f32_e32 v88, v56, v88
	v_mul_f32_e32 v89, v59, v89
	v_mul_f32_e32 v180, 0x3f3504f3, v89
	v_fma_f32 v182, |v180|, s16, v177
	v_fma_f32 v182, |v180|, v182, s19
	v_fma_f32 v182, |v180|, v182, s50
	v_fma_f32 v182, |v180|, v182, s51
	v_fma_f32 v182, |v180|, v182, s64
	v_fma_f32 v182, |v180|, v182, s65
	v_fma_f32 v182, |v180|, v182, |v180|
	v_mul_f32_e32 v184, 0xbfb8aa3b, v182
	v_fma_f32 v185, v182, s98, -v184
	v_rndne_f32_e32 v186, v184
	v_fmac_f32_e32 v185, 0xb2a5705f, v182
	v_sub_f32_e32 v184, v184, v186
	v_add_f32_e32 v184, v184, v185
	v_cvt_i32_f32_e32 v185, v186
	v_exp_f32_e32 v184, v184
	v_cmp_nlt_f32_e32 vcc, s70, v182
	v_ldexp_f32 v184, v184, v185
	s_nop 0
	v_cndmask_b32_e32 v184, 0, v184, vcc
	v_cmp_ngt_f32_e32 vcc, s71, v182
	s_nop 1
	v_cndmask_b32_e32 v184, v178, v184, vcc
	v_sub_f32_e32 v184, 1.0, v184
	v_mul_f32_e32 v183, v180, v180
	v_fmamk_f32 v185, v183, 0xba1345e1, v176
	v_fmaak_f32 v185, v183, v185, 0xbcdac9b8
	v_fmaak_f32 v185, v183, v185, 0x3de703be
	v_fmaak_f32 v185, v183, v185, 0xbec09330
	v_fmaak_f32 v183, v183, v185, 0x3e0375d0
	v_fma_f32 v183, |v180|, v183, |v180|
	v_cmp_nlt_f32_e64 vcc, |v180|, 1.0
	s_nop 1
	v_cndmask_b32_e32 v184, v183, v184, vcc
	v_bfi_b32 v184, s14, v184, v180
	v_add_f32_e32 v184, 1.0, v184
	v_mul_f32_e32 v89, 0.5, v89
	v_mul_f32_e32 v57, v57, v61
	v_mul_f32_e32 v89, v89, v184
	v_mul_f32_e32 v89, v57, v89
	global_store_dword v160, v88, s[12:13]
	global_store_dword v160, v89, s[12:13] offset:256
	s_add_u32 s12, s12, s18
	s_addc_u32 s13, s13, 0
	v_mul_f32_e32 v90, v64, v90
	v_mul_f32_e32 v180, 0x3f3504f3, v90
	v_fma_f32 v182, |v180|, s16, v177
	v_fma_f32 v182, |v180|, v182, s19
	v_fma_f32 v182, |v180|, v182, s50
	v_fma_f32 v182, |v180|, v182, s51
	v_fma_f32 v182, |v180|, v182, s64
	v_fma_f32 v182, |v180|, v182, s65
	v_fma_f32 v182, |v180|, v182, |v180|
	v_mul_f32_e32 v184, 0xbfb8aa3b, v182
	v_fma_f32 v185, v182, s98, -v184
	v_rndne_f32_e32 v186, v184
	v_fmac_f32_e32 v185, 0xb2a5705f, v182
	v_sub_f32_e32 v184, v184, v186
	v_add_f32_e32 v184, v184, v185
	v_cvt_i32_f32_e32 v185, v186
	v_exp_f32_e32 v184, v184
	v_cmp_nlt_f32_e32 vcc, s70, v182
	v_ldexp_f32 v184, v184, v185
	s_nop 0
	v_cndmask_b32_e32 v184, 0, v184, vcc
	v_cmp_ngt_f32_e32 vcc, s71, v182
	s_nop 1
	v_cndmask_b32_e32 v184, v178, v184, vcc
	v_sub_f32_e32 v184, 1.0, v184
	v_mul_f32_e32 v183, v180, v180
	v_fmamk_f32 v185, v183, 0xba1345e1, v176
	v_fmaak_f32 v185, v183, v185, 0xbcdac9b8
	v_fmaak_f32 v185, v183, v185, 0x3de703be
	v_fmaak_f32 v185, v183, v185, 0xbec09330
	v_fmaak_f32 v183, v183, v185, 0x3e0375d0
	v_fma_f32 v183, |v180|, v183, |v180|
	v_cmp_nlt_f32_e64 vcc, |v180|, 1.0
	s_nop 1
	v_cndmask_b32_e32 v184, v183, v184, vcc
	v_bfi_b32 v184, s14, v184, v180
	v_add_f32_e32 v184, 1.0, v184
	v_mul_f32_e32 v90, 0.5, v90
	v_mul_f32_e32 v62, v62, v66
	v_mul_f32_e32 v90, v90, v184
	v_mul_f32_e32 v90, v62, v90
	v_mul_f32_e32 v91, v65, v91
	v_mul_f32_e32 v180, 0x3f3504f3, v91
	v_fma_f32 v182, |v180|, s16, v177
	v_fma_f32 v182, |v180|, v182, s19
	v_fma_f32 v182, |v180|, v182, s50
	v_fma_f32 v182, |v180|, v182, s51
	v_fma_f32 v182, |v180|, v182, s64
	v_fma_f32 v182, |v180|, v182, s65
	v_fma_f32 v182, |v180|, v182, |v180|
	v_mul_f32_e32 v184, 0xbfb8aa3b, v182
	v_fma_f32 v185, v182, s98, -v184
	v_rndne_f32_e32 v186, v184
	v_fmac_f32_e32 v185, 0xb2a5705f, v182
	v_sub_f32_e32 v184, v184, v186
	v_add_f32_e32 v184, v184, v185
	v_cvt_i32_f32_e32 v185, v186
	v_exp_f32_e32 v184, v184
	v_cmp_nlt_f32_e32 vcc, s70, v182
	v_ldexp_f32 v184, v184, v185
	s_nop 0
	v_cndmask_b32_e32 v184, 0, v184, vcc
	v_cmp_ngt_f32_e32 vcc, s71, v182
	s_nop 1
	v_cndmask_b32_e32 v184, v178, v184, vcc
	v_sub_f32_e32 v184, 1.0, v184
	v_mul_f32_e32 v183, v180, v180
	v_fmamk_f32 v185, v183, 0xba1345e1, v176
	v_fmaak_f32 v185, v183, v185, 0xbcdac9b8
	v_fmaak_f32 v185, v183, v185, 0x3de703be
	v_fmaak_f32 v185, v183, v185, 0xbec09330
	v_fmaak_f32 v183, v183, v185, 0x3e0375d0
	v_fma_f32 v183, |v180|, v183, |v180|
	v_cmp_nlt_f32_e64 vcc, |v180|, 1.0
	s_nop 1
	v_cndmask_b32_e32 v184, v183, v184, vcc
	v_bfi_b32 v184, s14, v184, v180
	v_add_f32_e32 v184, 1.0, v184
	v_mul_f32_e32 v91, 0.5, v91
	v_mul_f32_e32 v63, v63, v67
	v_mul_f32_e32 v91, v91, v184
	v_mul_f32_e32 v91, v63, v91
	global_store_dword v160, v90, s[12:13]
	global_store_dword v160, v91, s[12:13] offset:256
	s_add_u32 s12, s12, s18
	s_addc_u32 s13, s13, 0
	v_mul_f32_e32 v92, v70, v92
	v_mul_f32_e32 v180, 0x3f3504f3, v92
	v_fma_f32 v182, |v180|, s16, v177
	v_fma_f32 v182, |v180|, v182, s19
	v_fma_f32 v182, |v180|, v182, s50
	v_fma_f32 v182, |v180|, v182, s51
	v_fma_f32 v182, |v180|, v182, s64
	v_fma_f32 v182, |v180|, v182, s65
	v_fma_f32 v182, |v180|, v182, |v180|
	v_mul_f32_e32 v184, 0xbfb8aa3b, v182
	v_fma_f32 v185, v182, s98, -v184
	v_rndne_f32_e32 v186, v184
	v_fmac_f32_e32 v185, 0xb2a5705f, v182
	v_sub_f32_e32 v184, v184, v186
	v_add_f32_e32 v184, v184, v185
	v_cvt_i32_f32_e32 v185, v186
	v_exp_f32_e32 v184, v184
	v_cmp_nlt_f32_e32 vcc, s70, v182
	v_ldexp_f32 v184, v184, v185
	s_nop 0
	v_cndmask_b32_e32 v184, 0, v184, vcc
	v_cmp_ngt_f32_e32 vcc, s71, v182
	s_nop 1
	v_cndmask_b32_e32 v184, v178, v184, vcc
	v_sub_f32_e32 v184, 1.0, v184
	v_mul_f32_e32 v183, v180, v180
	v_fmamk_f32 v185, v183, 0xba1345e1, v176
	v_fmaak_f32 v185, v183, v185, 0xbcdac9b8
	v_fmaak_f32 v185, v183, v185, 0x3de703be
	v_fmaak_f32 v185, v183, v185, 0xbec09330
	v_fmaak_f32 v183, v183, v185, 0x3e0375d0
	v_fma_f32 v183, |v180|, v183, |v180|
	v_cmp_nlt_f32_e64 vcc, |v180|, 1.0
	s_nop 1
	v_cndmask_b32_e32 v184, v183, v184, vcc
	v_bfi_b32 v184, s14, v184, v180
	v_add_f32_e32 v184, 1.0, v184
	v_mul_f32_e32 v92, 0.5, v92
	v_mul_f32_e32 v68, v68, v72
	v_mul_f32_e32 v92, v92, v184
	v_mul_f32_e32 v92, v68, v92
	v_mul_f32_e32 v93, v71, v93
	v_mul_f32_e32 v180, 0x3f3504f3, v93
	v_fma_f32 v182, |v180|, s16, v177
	v_fma_f32 v182, |v180|, v182, s19
	v_fma_f32 v182, |v180|, v182, s50
	v_fma_f32 v182, |v180|, v182, s51
	v_fma_f32 v182, |v180|, v182, s64
	v_fma_f32 v182, |v180|, v182, s65
	v_fma_f32 v182, |v180|, v182, |v180|
	v_mul_f32_e32 v184, 0xbfb8aa3b, v182
	v_fma_f32 v185, v182, s98, -v184
	v_rndne_f32_e32 v186, v184
	v_fmac_f32_e32 v185, 0xb2a5705f, v182
	v_sub_f32_e32 v184, v184, v186
	v_add_f32_e32 v184, v184, v185
	v_cvt_i32_f32_e32 v185, v186
	v_exp_f32_e32 v184, v184
	v_cmp_nlt_f32_e32 vcc, s70, v182
	v_ldexp_f32 v184, v184, v185
	s_nop 0
	v_cndmask_b32_e32 v184, 0, v184, vcc
	v_cmp_ngt_f32_e32 vcc, s71, v182
	s_nop 1
	v_cndmask_b32_e32 v184, v178, v184, vcc
	v_sub_f32_e32 v184, 1.0, v184
	v_mul_f32_e32 v183, v180, v180
	v_fmamk_f32 v185, v183, 0xba1345e1, v176
	v_fmaak_f32 v185, v183, v185, 0xbcdac9b8
	v_fmaak_f32 v185, v183, v185, 0x3de703be
	v_fmaak_f32 v185, v183, v185, 0xbec09330
	v_fmaak_f32 v183, v183, v185, 0x3e0375d0
	v_fma_f32 v183, |v180|, v183, |v180|
	v_cmp_nlt_f32_e64 vcc, |v180|, 1.0
	s_nop 1
	v_cndmask_b32_e32 v184, v183, v184, vcc
	v_bfi_b32 v184, s14, v184, v180
	v_add_f32_e32 v184, 1.0, v184
	v_mul_f32_e32 v93, 0.5, v93
	v_mul_f32_e32 v69, v69, v73
	v_mul_f32_e32 v93, v93, v184
	v_mul_f32_e32 v93, v69, v93
	global_store_dword v160, v92, s[12:13]
	global_store_dword v160, v93, s[12:13] offset:256
	s_add_u32 s12, s12, s18
	s_addc_u32 s13, s13, 0
	v_mul_f32_e32 v94, v76, v94
	v_mul_f32_e32 v180, 0x3f3504f3, v94
	v_fma_f32 v182, |v180|, s16, v177
	v_fma_f32 v182, |v180|, v182, s19
	v_fma_f32 v182, |v180|, v182, s50
	v_fma_f32 v182, |v180|, v182, s51
	v_fma_f32 v182, |v180|, v182, s64
	v_fma_f32 v182, |v180|, v182, s65
	v_fma_f32 v182, |v180|, v182, |v180|
	v_mul_f32_e32 v184, 0xbfb8aa3b, v182
	v_fma_f32 v185, v182, s98, -v184
	v_rndne_f32_e32 v186, v184
	v_fmac_f32_e32 v185, 0xb2a5705f, v182
	v_sub_f32_e32 v184, v184, v186
	v_add_f32_e32 v184, v184, v185
	v_cvt_i32_f32_e32 v185, v186
	v_exp_f32_e32 v184, v184
	v_cmp_nlt_f32_e32 vcc, s70, v182
	v_ldexp_f32 v184, v184, v185
	s_nop 0
	v_cndmask_b32_e32 v184, 0, v184, vcc
	v_cmp_ngt_f32_e32 vcc, s71, v182
	s_nop 1
	v_cndmask_b32_e32 v184, v178, v184, vcc
	v_sub_f32_e32 v184, 1.0, v184
	v_mul_f32_e32 v183, v180, v180
	v_fmamk_f32 v185, v183, 0xba1345e1, v176
	v_fmaak_f32 v185, v183, v185, 0xbcdac9b8
	v_fmaak_f32 v185, v183, v185, 0x3de703be
	v_fmaak_f32 v185, v183, v185, 0xbec09330
	v_fmaak_f32 v183, v183, v185, 0x3e0375d0
	v_fma_f32 v183, |v180|, v183, |v180|
	v_cmp_nlt_f32_e64 vcc, |v180|, 1.0
	s_nop 1
	v_cndmask_b32_e32 v184, v183, v184, vcc
	v_bfi_b32 v184, s14, v184, v180
	v_add_f32_e32 v184, 1.0, v184
	v_mul_f32_e32 v94, 0.5, v94
	v_mul_f32_e32 v74, v74, v78
	v_mul_f32_e32 v94, v94, v184
	v_mul_f32_e32 v94, v74, v94
	v_mul_f32_e32 v95, v77, v95
	v_mul_f32_e32 v180, 0x3f3504f3, v95
	v_fma_f32 v182, |v180|, s16, v177
	v_fma_f32 v182, |v180|, v182, s19
	v_fma_f32 v182, |v180|, v182, s50
	v_fma_f32 v182, |v180|, v182, s51
	v_fma_f32 v182, |v180|, v182, s64
	v_fma_f32 v182, |v180|, v182, s65
	v_fma_f32 v182, |v180|, v182, |v180|
	v_mul_f32_e32 v184, 0xbfb8aa3b, v182
	v_fma_f32 v185, v182, s98, -v184
	v_rndne_f32_e32 v186, v184
	v_fmac_f32_e32 v185, 0xb2a5705f, v182
	v_sub_f32_e32 v184, v184, v186
	v_add_f32_e32 v184, v184, v185
	v_cvt_i32_f32_e32 v185, v186
	v_exp_f32_e32 v184, v184
	v_cmp_nlt_f32_e32 vcc, s70, v182
	v_ldexp_f32 v184, v184, v185
	s_nop 0
	v_cndmask_b32_e32 v184, 0, v184, vcc
	v_cmp_ngt_f32_e32 vcc, s71, v182
	s_nop 1
	v_cndmask_b32_e32 v184, v178, v184, vcc
	v_sub_f32_e32 v184, 1.0, v184
	v_mul_f32_e32 v183, v180, v180
	v_fmamk_f32 v185, v183, 0xba1345e1, v176
	v_fmaak_f32 v185, v183, v185, 0xbcdac9b8
	v_fmaak_f32 v185, v183, v185, 0x3de703be
	v_fmaak_f32 v185, v183, v185, 0xbec09330
	v_fmaak_f32 v183, v183, v185, 0x3e0375d0
	v_fma_f32 v183, |v180|, v183, |v180|
	v_cmp_nlt_f32_e64 vcc, |v180|, 1.0
	s_nop 1
	v_cndmask_b32_e32 v184, v183, v184, vcc
	v_bfi_b32 v184, s14, v184, v180
	v_add_f32_e32 v184, 1.0, v184
	v_mul_f32_e32 v95, 0.5, v95
	v_mul_f32_e32 v75, v75, v79
	v_mul_f32_e32 v95, v95, v184
	v_mul_f32_e32 v95, v75, v95
	global_store_dword v160, v94, s[12:13]
	global_store_dword v160, v95, s[12:13] offset:256
	s_add_u32 s12, s12, s18
	s_addc_u32 s13, s13, 0
	s_lshl_b32 s17, s92, 6
	s_add_u32 s69, s69, s17
	s_cmpk_lt_u32 s69, 0x8000
	s_cbranch_scc1 .Lgu0_chunk
	s_branch .LBB0_578

.Lgv0_start:
	s_mov_b64 exec, -1
	v_and_b32_e32 v210, 63, v205
	v_lshrrev_b32_e32 v209, 6, v205
	v_lshlrev_b32_e32 v196, 2, v210
	v_readfirstlane_b32 s18, v209
	v_and_b32_e32 v209, 7, v210
	v_mul_u32_u24_e32 v199, 24, v209
	v_lshlrev_b32_e32 v200, 4, v209
	s_nop 3
	s_lshl_b32 s15, s18, 14
	s_add_i32 s101, s93, s18
	v_lshrrev_b32_e32 v209, 3, v210
	v_lshl_add_u32 v200, v209, 9, v200
	v_lshl_add_u32 v197, v209, 2, s15
	v_add_u32_e32 v198, 0x2000, v197
	v_add_u32_e32 v206, s15, v196
	v_add_u32_e32 v208, 0x2000, v206
	v_lshlrev_b32_e32 v211, 4, v210
.Lgv0_chunk:
	s_movk_i32 s100, 0xc0
	s_lshl_b32 s16, s92, 14
	s_add_u32 s12, s26, 0xd800000
	s_addc_u32 s13, s27, 0
	s_lshl_b32 s15, s101, 9
	s_add_u32 s12, s12, s15
	s_addc_u32 s13, s13, 0
	s_lshl_b32 s18, s92, 11
	global_load_dword v64, v196, s[12:13]
	global_load_dword v65, v196, s[12:13] offset:256
	s_add_u32 s12, s12, s18
	s_addc_u32 s13, s13, 0
	global_load_dword v66, v196, s[12:13]
	global_load_dword v67, v196, s[12:13] offset:256
	s_add_u32 s12, s12, s18
	s_addc_u32 s13, s13, 0
	global_load_dword v68, v196, s[12:13]
	global_load_dword v69, v196, s[12:13] offset:256
	s_add_u32 s12, s12, s18
	s_addc_u32 s13, s13, 0
	global_load_dword v70, v196, s[12:13]
	global_load_dword v71, v196, s[12:13] offset:256
	s_add_u32 s12, s12, s18
	s_addc_u32 s13, s13, 0
	global_load_dword v72, v196, s[12:13]
	global_load_dword v73, v196, s[12:13] offset:256
	s_add_u32 s12, s12, s18
	s_addc_u32 s13, s13, 0
	global_load_dword v74, v196, s[12:13]
	global_load_dword v75, v196, s[12:13] offset:256
	s_add_u32 s12, s12, s18
	s_addc_u32 s13, s13, 0
	global_load_dword v76, v196, s[12:13]
	global_load_dword v77, v196, s[12:13] offset:256
	s_add_u32 s12, s12, s18
	s_addc_u32 s13, s13, 0
	global_load_dword v78, v196, s[12:13]
	global_load_dword v79, v196, s[12:13] offset:256
	s_add_u32 s12, s12, s18
	s_addc_u32 s13, s13, 0
	global_load_dword v80, v196, s[12:13]
	global_load_dword v81, v196, s[12:13] offset:256
	s_add_u32 s12, s12, s18
	s_addc_u32 s13, s13, 0
	global_load_dword v82, v196, s[12:13]
	global_load_dword v83, v196, s[12:13] offset:256
	s_add_u32 s12, s12, s18
	s_addc_u32 s13, s13, 0
	global_load_dword v84, v196, s[12:13]
	global_load_dword v85, v196, s[12:13] offset:256
	s_add_u32 s12, s12, s18
	s_addc_u32 s13, s13, 0
	global_load_dword v86, v196, s[12:13]
	global_load_dword v87, v196, s[12:13] offset:256
	s_add_u32 s12, s12, s18
	s_addc_u32 s13, s13, 0
	global_load_dword v88, v196, s[12:13]
	global_load_dword v89, v196, s[12:13] offset:256
	s_add_u32 s12, s12, s18
	s_addc_u32 s13, s13, 0
	global_load_dword v90, v196, s[12:13]
	global_load_dword v91, v196, s[12:13] offset:256
	s_add_u32 s12, s12, s18
	s_addc_u32 s13, s13, 0
	global_load_dword v92, v196, s[12:13]
	global_load_dword v93, v196, s[12:13] offset:256
	s_add_u32 s12, s12, s18
	s_addc_u32 s13, s13, 0
	global_load_dword v94, v196, s[12:13]
	global_load_dword v95, v196, s[12:13] offset:256
	s_add_u32 s12, s12, s18
	s_addc_u32 s13, s13, 0
	s_waitcnt vmcnt(0)
	ds_write2st64_b32 v206, v64, v65 offset0:0 offset1:1
	ds_write2st64_b32 v206, v66, v67 offset0:2 offset1:3
	ds_write2st64_b32 v206, v68, v69 offset0:4 offset1:5
	ds_write2st64_b32 v206, v70, v71 offset0:6 offset1:7
	ds_write2st64_b32 v206, v72, v73 offset0:8 offset1:9
	ds_write2st64_b32 v206, v74, v75 offset0:10 offset1:11
	ds_write2st64_b32 v206, v76, v77 offset0:12 offset1:13
	ds_write2st64_b32 v206, v78, v79 offset0:14 offset1:15
	ds_write2st64_b32 v206, v80, v81 offset0:16 offset1:17
	ds_write2st64_b32 v206, v82, v83 offset0:18 offset1:19
	ds_write2st64_b32 v206, v84, v85 offset0:20 offset1:21
	ds_write2st64_b32 v206, v86, v87 offset0:22 offset1:23
	ds_write2st64_b32 v206, v88, v89 offset0:24 offset1:25
	ds_write2st64_b32 v206, v90, v91 offset0:26 offset1:27
	ds_write2st64_b32 v206, v92, v93 offset0:28 offset1:29
	ds_write2st64_b32 v206, v94, v95 offset0:30 offset1:31
	s_add_u32 s12, s26, 0xf800000
	s_addc_u32 s13, s27, 0
	s_lshl_b32 s15, s101, 9
	s_add_u32 s12, s12, s15
	s_addc_u32 s13, s13, 0
	s_lshl_b32 s18, s92, 11
	global_load_dword v64, v196, s[12:13]
	global_load_dword v65, v196, s[12:13] offset:256
	s_add_u32 s12, s12, s18
	s_addc_u32 s13, s13, 0
	global_load_dword v66, v196, s[12:13]
	global_load_dword v67, v196, s[12:13] offset:256
	s_add_u32 s12, s12, s18
	s_addc_u32 s13, s13, 0
	global_load_dword v68, v196, s[12:13]
	global_load_dword v69, v196, s[12:13] offset:256
	s_add_u32 s12, s12, s18
	s_addc_u32 s13, s13, 0
	global_load_dword v70, v196, s[12:13]
	global_load_dword v71, v196, s[12:13] offset:256
	s_add_u32 s12, s12, s18
	s_addc_u32 s13, s13, 0
	global_load_dword v72, v196, s[12:13]
	global_load_dword v73, v196, s[12:13] offset:256
	s_add_u32 s12, s12, s18
	s_addc_u32 s13, s13, 0
	global_load_dword v74, v196, s[12:13]
	global_load_dword v75, v196, s[12:13] offset:256
	s_add_u32 s12, s12, s18
	s_addc_u32 s13, s13, 0
	global_load_dword v76, v196, s[12:13]
	global_load_dword v77, v196, s[12:13] offset:256
	s_add_u32 s12, s12, s18
	s_addc_u32 s13, s13, 0
	global_load_dword v78, v196, s[12:13]
	global_load_dword v79, v196, s[12:13] offset:256
	s_add_u32 s12, s12, s18
	s_addc_u32 s13, s13, 0
	global_load_dword v80, v196, s[12:13]
	global_load_dword v81, v196, s[12:13] offset:256
	s_add_u32 s12, s12, s18
	s_addc_u32 s13, s13, 0
	global_load_dword v82, v196, s[12:13]
	global_load_dword v83, v196, s[12:13] offset:256
	s_add_u32 s12, s12, s18
	s_addc_u32 s13, s13, 0
	global_load_dword v84, v196, s[12:13]
	global_load_dword v85, v196, s[12:13] offset:256
	s_add_u32 s12, s12, s18
	s_addc_u32 s13, s13, 0
	global_load_dword v86, v196, s[12:13]
	global_load_dword v87, v196, s[12:13] offset:256
	s_add_u32 s12, s12, s18
	s_addc_u32 s13, s13, 0
	global_load_dword v88, v196, s[12:13]
	global_load_dword v89, v196, s[12:13] offset:256
	s_add_u32 s12, s12, s18
	s_addc_u32 s13, s13, 0
	global_load_dword v90, v196, s[12:13]
	global_load_dword v91, v196, s[12:13] offset:256
	s_add_u32 s12, s12, s18
	s_addc_u32 s13, s13, 0
	global_load_dword v92, v196, s[12:13]
	global_load_dword v93, v196, s[12:13] offset:256
	s_add_u32 s12, s12, s18
	s_addc_u32 s13, s13, 0
	global_load_dword v94, v196, s[12:13]
	global_load_dword v95, v196, s[12:13] offset:256
	s_add_u32 s12, s12, s18
	s_addc_u32 s13, s13, 0
	s_waitcnt vmcnt(0)
	ds_write2st64_b32 v208, v64, v65 offset0:0 offset1:1
	ds_write2st64_b32 v208, v66, v67 offset0:2 offset1:3
	ds_write2st64_b32 v208, v68, v69 offset0:4 offset1:5
	ds_write2st64_b32 v208, v70, v71 offset0:6 offset1:7
	ds_write2st64_b32 v208, v72, v73 offset0:8 offset1:9
	ds_write2st64_b32 v208, v74, v75 offset0:10 offset1:11
	ds_write2st64_b32 v208, v76, v77 offset0:12 offset1:13
	ds_write2st64_b32 v208, v78, v79 offset0:14 offset1:15
	ds_write2st64_b32 v208, v80, v81 offset0:16 offset1:17
	ds_write2st64_b32 v208, v82, v83 offset0:18 offset1:19
	ds_write2st64_b32 v208, v84, v85 offset0:20 offset1:21
	ds_write2st64_b32 v208, v86, v87 offset0:22 offset1:23
	ds_write2st64_b32 v208, v88, v89 offset0:24 offset1:25
	ds_write2st64_b32 v208, v90, v91 offset0:26 offset1:27
	ds_write2st64_b32 v208, v92, v93 offset0:28 offset1:29
	ds_write2st64_b32 v208, v94, v95 offset0:30 offset1:31
	s_waitcnt lgkmcnt(0)
	s_mov_b32 s14, 0
	s_mov_b32 s18, 0
	s_and_b32 s19, s18, 15
	s_lshr_b32 s98, s18, 4
	s_lshl_b32 s99, s19, 9
	s_mul_i32 s15, s19, s16
	s_lshl_b32 s18, s98, 7
	s_add_u32 s15, s15, s18
	s_lshl_b32 s18, s101, 12
	s_add_u32 s15, s15, s18
	s_add_u32 s8, s24, s15
	s_addc_u32 s9, s25, 0
	s_mul_i32 s15, s98, 0x300000
	s_add_u32 s4, s26, 0x3800000
	s_addc_u32 s5, s27, 0
	s_add_u32 s4, s4, s15
	s_addc_u32 s5, s5, 0
	v_add_u32_e32 v201, s99, v197
	v_add_u32_e32 v203, s99, v198
	ds_read2_b32 v[160:161], v201 offset0:0 offset1:8
	ds_read2_b32 v[162:163], v201 offset0:16 offset1:24
	s_waitcnt lgkmcnt(0)
	v_mad_u32_u24 v160, v160, s100, v199
	v_mad_u32_u24 v161, v161, s100, v199
	v_mad_u32_u24 v162, v162, s100, v199
	v_mad_u32_u24 v163, v163, s100, v199
	global_load_dwordx4 v[64:67], v160, s[4:5]
	global_load_dwordx2 v[68:69], v160, s[4:5] offset:16
	global_load_dwordx4 v[70:73], v161, s[4:5]
	global_load_dwordx2 v[74:75], v161, s[4:5] offset:16
	global_load_dwordx4 v[76:79], v162, s[4:5]
	global_load_dwordx2 v[80:81], v162, s[4:5] offset:16
	global_load_dwordx4 v[82:85], v163, s[4:5]
	global_load_dwordx2 v[86:87], v163, s[4:5] offset:16
	ds_read2_b32 v[168:169], v201 offset0:32 offset1:40
	ds_read2_b32 v[170:171], v201 offset0:48 offset1:56
	s_waitcnt lgkmcnt(0)
	v_mad_u32_u24 v168, v168, s100, v199
	v_mad_u32_u24 v169, v169, s100, v199
	v_mad_u32_u24 v170, v170, s100, v199
	v_mad_u32_u24 v171, v171, s100, v199
	global_load_dwordx4 v[88:91], v168, s[4:5]
	global_load_dwordx2 v[92:93], v168, s[4:5] offset:16
	global_load_dwordx4 v[94:97], v169, s[4:5]
	global_load_dwordx2 v[98:99], v169, s[4:5] offset:16
	global_load_dwordx4 v[100:103], v170, s[4:5]
	global_load_dwordx2 v[104:105], v170, s[4:5] offset:16
	global_load_dwordx4 v[106:109], v171, s[4:5]
	global_load_dwordx2 v[110:111], v171, s[4:5] offset:16
	ds_read2_b32 v[160:161], v201 offset0:64 offset1:72
	ds_read2_b32 v[162:163], v201 offset0:80 offset1:88
	s_waitcnt lgkmcnt(0)
	v_mad_u32_u24 v160, v160, s100, v199
	v_mad_u32_u24 v161, v161, s100, v199
	v_mad_u32_u24 v162, v162, s100, v199
	v_mad_u32_u24 v163, v163, s100, v199
	global_load_dwordx4 v[112:115], v160, s[4:5]
	global_load_dwordx2 v[116:117], v160, s[4:5] offset:16
	global_load_dwordx4 v[118:121], v161, s[4:5]
	global_load_dwordx2 v[122:123], v161, s[4:5] offset:16
	global_load_dwordx4 v[124:127], v162, s[4:5]
	global_load_dwordx2 v[128:129], v162, s[4:5] offset:16
	global_load_dwordx4 v[130:133], v163, s[4:5]
	global_load_dwordx2 v[134:135], v163, s[4:5] offset:16
	ds_read2_b32 v[168:169], v201 offset0:96 offset1:104
	ds_read2_b32 v[170:171], v201 offset0:112 offset1:120
	s_waitcnt lgkmcnt(0)
	v_mad_u32_u24 v168, v168, s100, v199
	v_mad_u32_u24 v169, v169, s100, v199
	v_mad_u32_u24 v170, v170, s100, v199
	v_mad_u32_u24 v171, v171, s100, v199
	global_load_dwordx4 v[136:139], v168, s[4:5]
	global_load_dwordx2 v[140:141], v168, s[4:5] offset:16
	global_load_dwordx4 v[142:145], v169, s[4:5]
	global_load_dwordx2 v[146:147], v169, s[4:5] offset:16
	global_load_dwordx4 v[148:151], v170, s[4:5]
	global_load_dwordx2 v[152:153], v170, s[4:5] offset:16
	global_load_dwordx4 v[154:157], v171, s[4:5]
	global_load_dwordx2 v[158:159], v171, s[4:5] offset:16
	global_load_dword v209, v200, s[8:9]
	ds_read2_b32 v[176:177], v203 offset0:0 offset1:8
	ds_read2_b32 v[178:179], v203 offset0:16 offset1:24
	s_mov_b32 s18, 1
	s_and_b32 s19, s18, 15
	s_lshr_b32 s98, s18, 4
	s_lshl_b32 s99, s19, 9
	s_mul_i32 s15, s19, s16
	s_lshl_b32 s18, s98, 7
	s_add_u32 s15, s15, s18
	s_lshl_b32 s18, s101, 12
	s_add_u32 s15, s15, s18
	s_add_u32 s10, s24, s15
	s_addc_u32 s11, s25, 0
	s_mul_i32 s15, s98, 0x300000
	s_add_u32 s4, s26, 0x3800000
	s_addc_u32 s5, s27, 0
	s_add_u32 s4, s4, s15
	s_addc_u32 s5, s5, 0
	v_add_u32_e32 v202, s99, v197
	v_add_u32_e32 v204, s99, v198
	ds_read2_b32 v[160:161], v202 offset0:0 offset1:8
	ds_read2_b32 v[162:163], v202 offset0:16 offset1:24
	s_waitcnt lgkmcnt(0)
.Lgv0_loop:
	global_load_dwordx4 v[192:195], v200, s[8:9]
	ds_read2_b32 v[184:185], v203 offset0:32 offset1:40
	ds_read2_b32 v[186:187], v203 offset0:48 offset1:56
	s_waitcnt vmcnt(32)
	v_cvt_scalef32_pk32_f32_fp6 v[32:63], v[64:69], 1.0
	v_pk_mul_f32 v[0:1], v[176:177], v[32:33] op_sel_hi:[0,1]
	v_pk_mul_f32 v[2:3], v[176:177], v[34:35] op_sel_hi:[0,1]
	v_pk_mul_f32 v[4:5], v[176:177], v[36:37] op_sel_hi:[0,1]
	v_pk_mul_f32 v[6:7], v[176:177], v[38:39] op_sel_hi:[0,1]
	v_pk_mul_f32 v[8:9], v[176:177], v[40:41] op_sel_hi:[0,1]
	v_pk_mul_f32 v[10:11], v[176:177], v[42:43] op_sel_hi:[0,1]
	v_pk_mul_f32 v[12:13], v[176:177], v[44:45] op_sel_hi:[0,1]
	v_pk_mul_f32 v[14:15], v[176:177], v[46:47] op_sel_hi:[0,1]
	v_pk_mul_f32 v[16:17], v[176:177], v[48:49] op_sel_hi:[0,1]
	v_pk_mul_f32 v[18:19], v[176:177], v[50:51] op_sel_hi:[0,1]
	v_pk_mul_f32 v[20:21], v[176:177], v[52:53] op_sel_hi:[0,1]
	v_pk_mul_f32 v[22:23], v[176:177], v[54:55] op_sel_hi:[0,1]
	v_pk_mul_f32 v[24:25], v[176:177], v[56:57] op_sel_hi:[0,1]
	v_pk_mul_f32 v[26:27], v[176:177], v[58:59] op_sel_hi:[0,1]
	v_pk_mul_f32 v[28:29], v[176:177], v[60:61] op_sel_hi:[0,1]
	v_pk_mul_f32 v[30:31], v[176:177], v[62:63] op_sel_hi:[0,1]
	s_waitcnt vmcnt(30)
	v_cvt_scalef32_pk32_f32_fp6 v[32:63], v[70:75], 1.0
	v_pk_fma_f32 v[0:1], v[176:177], v[32:33], v[0:1] op_sel:[1,0,0] op_sel_hi:[1,1,1]
	v_pk_fma_f32 v[2:3], v[176:177], v[34:35], v[2:3] op_sel:[1,0,0] op_sel_hi:[1,1,1]
	v_pk_fma_f32 v[4:5], v[176:177], v[36:37], v[4:5] op_sel:[1,0,0] op_sel_hi:[1,1,1]
	v_pk_fma_f32 v[6:7], v[176:177], v[38:39], v[6:7] op_sel:[1,0,0] op_sel_hi:[1,1,1]
	v_pk_fma_f32 v[8:9], v[176:177], v[40:41], v[8:9] op_sel:[1,0,0] op_sel_hi:[1,1,1]
	v_pk_fma_f32 v[10:11], v[176:177], v[42:43], v[10:11] op_sel:[1,0,0] op_sel_hi:[1,1,1]
	v_pk_fma_f32 v[12:13], v[176:177], v[44:45], v[12:13] op_sel:[1,0,0] op_sel_hi:[1,1,1]
	v_pk_fma_f32 v[14:15], v[176:177], v[46:47], v[14:15] op_sel:[1,0,0] op_sel_hi:[1,1,1]
	v_pk_fma_f32 v[16:17], v[176:177], v[48:49], v[16:17] op_sel:[1,0,0] op_sel_hi:[1,1,1]
	v_pk_fma_f32 v[18:19], v[176:177], v[50:51], v[18:19] op_sel:[1,0,0] op_sel_hi:[1,1,1]
	v_pk_fma_f32 v[20:21], v[176:177], v[52:53], v[20:21] op_sel:[1,0,0] op_sel_hi:[1,1,1]
	v_pk_fma_f32 v[22:23], v[176:177], v[54:55], v[22:23] op_sel:[1,0,0] op_sel_hi:[1,1,1]
	v_pk_fma_f32 v[24:25], v[176:177], v[56:57], v[24:25] op_sel:[1,0,0] op_sel_hi:[1,1,1]
	v_pk_fma_f32 v[26:27], v[176:177], v[58:59], v[26:27] op_sel:[1,0,0] op_sel_hi:[1,1,1]
	v_pk_fma_f32 v[28:29], v[176:177], v[60:61], v[28:29] op_sel:[1,0,0] op_sel_hi:[1,1,1]
	v_pk_fma_f32 v[30:31], v[176:177], v[62:63], v[30:31] op_sel:[1,0,0] op_sel_hi:[1,1,1]
	s_waitcnt vmcnt(28)
	v_cvt_scalef32_pk32_f32_fp6 v[32:63], v[76:81], 1.0
	v_pk_fma_f32 v[0:1], v[178:179], v[32:33], v[0:1] op_sel_hi:[0,1,1]
	v_pk_fma_f32 v[2:3], v[178:179], v[34:35], v[2:3] op_sel_hi:[0,1,1]
	v_pk_fma_f32 v[4:5], v[178:179], v[36:37], v[4:5] op_sel_hi:[0,1,1]
	v_pk_fma_f32 v[6:7], v[178:179], v[38:39], v[6:7] op_sel_hi:[0,1,1]
	v_pk_fma_f32 v[8:9], v[178:179], v[40:41], v[8:9] op_sel_hi:[0,1,1]
	v_pk_fma_f32 v[10:11], v[178:179], v[42:43], v[10:11] op_sel_hi:[0,1,1]
	v_pk_fma_f32 v[12:13], v[178:179], v[44:45], v[12:13] op_sel_hi:[0,1,1]
	v_pk_fma_f32 v[14:15], v[178:179], v[46:47], v[14:15] op_sel_hi:[0,1,1]
	v_pk_fma_f32 v[16:17], v[178:179], v[48:49], v[16:17] op_sel_hi:[0,1,1]
	v_pk_fma_f32 v[18:19], v[178:179], v[50:51], v[18:19] op_sel_hi:[0,1,1]
	v_pk_fma_f32 v[20:21], v[178:179], v[52:53], v[20:21] op_sel_hi:[0,1,1]
	v_pk_fma_f32 v[22:23], v[178:179], v[54:55], v[22:23] op_sel_hi:[0,1,1]
	v_pk_fma_f32 v[24:25], v[178:179], v[56:57], v[24:25] op_sel_hi:[0,1,1]
	v_pk_fma_f32 v[26:27], v[178:179], v[58:59], v[26:27] op_sel_hi:[0,1,1]
	v_pk_fma_f32 v[28:29], v[178:179], v[60:61], v[28:29] op_sel_hi:[0,1,1]
	v_pk_fma_f32 v[30:31], v[178:179], v[62:63], v[30:31] op_sel_hi:[0,1,1]
	s_waitcnt vmcnt(26)
	v_cvt_scalef32_pk32_f32_fp6 v[32:63], v[82:87], 1.0
	v_pk_fma_f32 v[0:1], v[178:179], v[32:33], v[0:1] op_sel:[1,0,0] op_sel_hi:[1,1,1]
	v_pk_fma_f32 v[2:3], v[178:179], v[34:35], v[2:3] op_sel:[1,0,0] op_sel_hi:[1,1,1]
	v_pk_fma_f32 v[4:5], v[178:179], v[36:37], v[4:5] op_sel:[1,0,0] op_sel_hi:[1,1,1]
	v_pk_fma_f32 v[6:7], v[178:179], v[38:39], v[6:7] op_sel:[1,0,0] op_sel_hi:[1,1,1]
	v_pk_fma_f32 v[8:9], v[178:179], v[40:41], v[8:9] op_sel:[1,0,0] op_sel_hi:[1,1,1]
	v_pk_fma_f32 v[10:11], v[178:179], v[42:43], v[10:11] op_sel:[1,0,0] op_sel_hi:[1,1,1]
	v_pk_fma_f32 v[12:13], v[178:179], v[44:45], v[12:13] op_sel:[1,0,0] op_sel_hi:[1,1,1]
	v_pk_fma_f32 v[14:15], v[178:179], v[46:47], v[14:15] op_sel:[1,0,0] op_sel_hi:[1,1,1]
	v_pk_fma_f32 v[16:17], v[178:179], v[48:49], v[16:17] op_sel:[1,0,0] op_sel_hi:[1,1,1]
	v_pk_fma_f32 v[18:19], v[178:179], v[50:51], v[18:19] op_sel:[1,0,0] op_sel_hi:[1,1,1]
	v_pk_fma_f32 v[20:21], v[178:179], v[52:53], v[20:21] op_sel:[1,0,0] op_sel_hi:[1,1,1]
	v_pk_fma_f32 v[22:23], v[178:179], v[54:55], v[22:23] op_sel:[1,0,0] op_sel_hi:[1,1,1]
	v_pk_fma_f32 v[24:25], v[178:179], v[56:57], v[24:25] op_sel:[1,0,0] op_sel_hi:[1,1,1]
	v_pk_fma_f32 v[26:27], v[178:179], v[58:59], v[26:27] op_sel:[1,0,0] op_sel_hi:[1,1,1]
	v_pk_fma_f32 v[28:29], v[178:179], v[60:61], v[28:29] op_sel:[1,0,0] op_sel_hi:[1,1,1]
	v_pk_fma_f32 v[30:31], v[178:179], v[62:63], v[30:31] op_sel:[1,0,0] op_sel_hi:[1,1,1]
	s_waitcnt lgkmcnt(0)
	v_mad_u32_u24 v160, v160, s100, v199
	v_mad_u32_u24 v161, v161, s100, v199
	v_mad_u32_u24 v162, v162, s100, v199
	v_mad_u32_u24 v163, v163, s100, v199
	global_load_dwordx4 v[64:67], v160, s[4:5]
	global_load_dwordx2 v[68:69], v160, s[4:5] offset:16
	global_load_dwordx4 v[70:73], v161, s[4:5]
	global_load_dwordx2 v[74:75], v161, s[4:5] offset:16
	global_load_dwordx4 v[76:79], v162, s[4:5]
	global_load_dwordx2 v[80:81], v162, s[4:5] offset:16
	global_load_dwordx4 v[82:85], v163, s[4:5]
	global_load_dwordx2 v[86:87], v163, s[4:5] offset:16
	ds_read2_b32 v[168:169], v202 offset0:32 offset1:40
	ds_read2_b32 v[170:171], v202 offset0:48 offset1:56
	ds_read2_b32 v[176:177], v203 offset0:64 offset1:72
	ds_read2_b32 v[178:179], v203 offset0:80 offset1:88
	s_waitcnt vmcnt(32)
	v_cvt_scalef32_pk32_f32_fp6 v[32:63], v[88:93], 1.0
	v_pk_fma_f32 v[0:1], v[184:185], v[32:33], v[0:1] op_sel_hi:[0,1,1]
	v_pk_fma_f32 v[2:3], v[184:185], v[34:35], v[2:3] op_sel_hi:[0,1,1]
	v_pk_fma_f32 v[4:5], v[184:185], v[36:37], v[4:5] op_sel_hi:[0,1,1]
	v_pk_fma_f32 v[6:7], v[184:185], v[38:39], v[6:7] op_sel_hi:[0,1,1]
	v_pk_fma_f32 v[8:9], v[184:185], v[40:41], v[8:9] op_sel_hi:[0,1,1]
	v_pk_fma_f32 v[10:11], v[184:185], v[42:43], v[10:11] op_sel_hi:[0,1,1]
	v_pk_fma_f32 v[12:13], v[184:185], v[44:45], v[12:13] op_sel_hi:[0,1,1]
	v_pk_fma_f32 v[14:15], v[184:185], v[46:47], v[14:15] op_sel_hi:[0,1,1]
	v_pk_fma_f32 v[16:17], v[184:185], v[48:49], v[16:17] op_sel_hi:[0,1,1]
	v_pk_fma_f32 v[18:19], v[184:185], v[50:51], v[18:19] op_sel_hi:[0,1,1]
	v_pk_fma_f32 v[20:21], v[184:185], v[52:53], v[20:21] op_sel_hi:[0,1,1]
	v_pk_fma_f32 v[22:23], v[184:185], v[54:55], v[22:23] op_sel_hi:[0,1,1]
	v_pk_fma_f32 v[24:25], v[184:185], v[56:57], v[24:25] op_sel_hi:[0,1,1]
	v_pk_fma_f32 v[26:27], v[184:185], v[58:59], v[26:27] op_sel_hi:[0,1,1]
	v_pk_fma_f32 v[28:29], v[184:185], v[60:61], v[28:29] op_sel_hi:[0,1,1]
	v_pk_fma_f32 v[30:31], v[184:185], v[62:63], v[30:31] op_sel_hi:[0,1,1]
	s_waitcnt vmcnt(30)
	v_cvt_scalef32_pk32_f32_fp6 v[32:63], v[94:99], 1.0
	v_pk_fma_f32 v[0:1], v[184:185], v[32:33], v[0:1] op_sel:[1,0,0] op_sel_hi:[1,1,1]
	v_pk_fma_f32 v[2:3], v[184:185], v[34:35], v[2:3] op_sel:[1,0,0] op_sel_hi:[1,1,1]
	v_pk_fma_f32 v[4:5], v[184:185], v[36:37], v[4:5] op_sel:[1,0,0] op_sel_hi:[1,1,1]
	v_pk_fma_f32 v[6:7], v[184:185], v[38:39], v[6:7] op_sel:[1,0,0] op_sel_hi:[1,1,1]
	v_pk_fma_f32 v[8:9], v[184:185], v[40:41], v[8:9] op_sel:[1,0,0] op_sel_hi:[1,1,1]
	v_pk_fma_f32 v[10:11], v[184:185], v[42:43], v[10:11] op_sel:[1,0,0] op_sel_hi:[1,1,1]
	v_pk_fma_f32 v[12:13], v[184:185], v[44:45], v[12:13] op_sel:[1,0,0] op_sel_hi:[1,1,1]
	v_pk_fma_f32 v[14:15], v[184:185], v[46:47], v[14:15] op_sel:[1,0,0] op_sel_hi:[1,1,1]
	v_pk_fma_f32 v[16:17], v[184:185], v[48:49], v[16:17] op_sel:[1,0,0] op_sel_hi:[1,1,1]
	v_pk_fma_f32 v[18:19], v[184:185], v[50:51], v[18:19] op_sel:[1,0,0] op_sel_hi:[1,1,1]
	v_pk_fma_f32 v[20:21], v[184:185], v[52:53], v[20:21] op_sel:[1,0,0] op_sel_hi:[1,1,1]
	v_pk_fma_f32 v[22:23], v[184:185], v[54:55], v[22:23] op_sel:[1,0,0] op_sel_hi:[1,1,1]
	v_pk_fma_f32 v[24:25], v[184:185], v[56:57], v[24:25] op_sel:[1,0,0] op_sel_hi:[1,1,1]
	v_pk_fma_f32 v[26:27], v[184:185], v[58:59], v[26:27] op_sel:[1,0,0] op_sel_hi:[1,1,1]
	v_pk_fma_f32 v[28:29], v[184:185], v[60:61], v[28:29] op_sel:[1,0,0] op_sel_hi:[1,1,1]
	v_pk_fma_f32 v[30:31], v[184:185], v[62:63], v[30:31] op_sel:[1,0,0] op_sel_hi:[1,1,1]
	s_waitcnt vmcnt(28)
	v_cvt_scalef32_pk32_f32_fp6 v[32:63], v[100:105], 1.0
	v_pk_fma_f32 v[0:1], v[186:187], v[32:33], v[0:1] op_sel_hi:[0,1,1]
	v_pk_fma_f32 v[2:3], v[186:187], v[34:35], v[2:3] op_sel_hi:[0,1,1]
	v_pk_fma_f32 v[4:5], v[186:187], v[36:37], v[4:5] op_sel_hi:[0,1,1]
	v_pk_fma_f32 v[6:7], v[186:187], v[38:39], v[6:7] op_sel_hi:[0,1,1]
	v_pk_fma_f32 v[8:9], v[186:187], v[40:41], v[8:9] op_sel_hi:[0,1,1]
	v_pk_fma_f32 v[10:11], v[186:187], v[42:43], v[10:11] op_sel_hi:[0,1,1]
	v_pk_fma_f32 v[12:13], v[186:187], v[44:45], v[12:13] op_sel_hi:[0,1,1]
	v_pk_fma_f32 v[14:15], v[186:187], v[46:47], v[14:15] op_sel_hi:[0,1,1]
	v_pk_fma_f32 v[16:17], v[186:187], v[48:49], v[16:17] op_sel_hi:[0,1,1]
	v_pk_fma_f32 v[18:19], v[186:187], v[50:51], v[18:19] op_sel_hi:[0,1,1]
	v_pk_fma_f32 v[20:21], v[186:187], v[52:53], v[20:21] op_sel_hi:[0,1,1]
	v_pk_fma_f32 v[22:23], v[186:187], v[54:55], v[22:23] op_sel_hi:[0,1,1]
	v_pk_fma_f32 v[24:25], v[186:187], v[56:57], v[24:25] op_sel_hi:[0,1,1]
	v_pk_fma_f32 v[26:27], v[186:187], v[58:59], v[26:27] op_sel_hi:[0,1,1]
	v_pk_fma_f32 v[28:29], v[186:187], v[60:61], v[28:29] op_sel_hi:[0,1,1]
	v_pk_fma_f32 v[30:31], v[186:187], v[62:63], v[30:31] op_sel_hi:[0,1,1]
	s_waitcnt vmcnt(26)
	v_cvt_scalef32_pk32_f32_fp6 v[32:63], v[106:111], 1.0
	v_pk_fma_f32 v[0:1], v[186:187], v[32:33], v[0:1] op_sel:[1,0,0] op_sel_hi:[1,1,1]
	v_pk_fma_f32 v[2:3], v[186:187], v[34:35], v[2:3] op_sel:[1,0,0] op_sel_hi:[1,1,1]
	v_pk_fma_f32 v[4:5], v[186:187], v[36:37], v[4:5] op_sel:[1,0,0] op_sel_hi:[1,1,1]
	v_pk_fma_f32 v[6:7], v[186:187], v[38:39], v[6:7] op_sel:[1,0,0] op_sel_hi:[1,1,1]
	v_pk_fma_f32 v[8:9], v[186:187], v[40:41], v[8:9] op_sel:[1,0,0] op_sel_hi:[1,1,1]
	v_pk_fma_f32 v[10:11], v[186:187], v[42:43], v[10:11] op_sel:[1,0,0] op_sel_hi:[1,1,1]
	v_pk_fma_f32 v[12:13], v[186:187], v[44:45], v[12:13] op_sel:[1,0,0] op_sel_hi:[1,1,1]
	v_pk_fma_f32 v[14:15], v[186:187], v[46:47], v[14:15] op_sel:[1,0,0] op_sel_hi:[1,1,1]
	v_pk_fma_f32 v[16:17], v[186:187], v[48:49], v[16:17] op_sel:[1,0,0] op_sel_hi:[1,1,1]
	v_pk_fma_f32 v[18:19], v[186:187], v[50:51], v[18:19] op_sel:[1,0,0] op_sel_hi:[1,1,1]
	v_pk_fma_f32 v[20:21], v[186:187], v[52:53], v[20:21] op_sel:[1,0,0] op_sel_hi:[1,1,1]
	v_pk_fma_f32 v[22:23], v[186:187], v[54:55], v[22:23] op_sel:[1,0,0] op_sel_hi:[1,1,1]
	v_pk_fma_f32 v[24:25], v[186:187], v[56:57], v[24:25] op_sel:[1,0,0] op_sel_hi:[1,1,1]
	v_pk_fma_f32 v[26:27], v[186:187], v[58:59], v[26:27] op_sel:[1,0,0] op_sel_hi:[1,1,1]
	v_pk_fma_f32 v[28:29], v[186:187], v[60:61], v[28:29] op_sel:[1,0,0] op_sel_hi:[1,1,1]
	v_pk_fma_f32 v[30:31], v[186:187], v[62:63], v[30:31] op_sel:[1,0,0] op_sel_hi:[1,1,1]
	s_waitcnt lgkmcnt(0)
	v_mad_u32_u24 v168, v168, s100, v199
	v_mad_u32_u24 v169, v169, s100, v199
	v_mad_u32_u24 v170, v170, s100, v199
	v_mad_u32_u24 v171, v171, s100, v199
	global_load_dwordx4 v[88:91], v168, s[4:5]
	global_load_dwordx2 v[92:93], v168, s[4:5] offset:16
	global_load_dwordx4 v[94:97], v169, s[4:5]
	global_load_dwordx2 v[98:99], v169, s[4:5] offset:16
	global_load_dwordx4 v[100:103], v170, s[4:5]
	global_load_dwordx2 v[104:105], v170, s[4:5] offset:16
	global_load_dwordx4 v[106:109], v171, s[4:5]
	global_load_dwordx2 v[110:111], v171, s[4:5] offset:16
	ds_read2_b32 v[160:161], v202 offset0:64 offset1:72
	ds_read2_b32 v[162:163], v202 offset0:80 offset1:88
	ds_read2_b32 v[184:185], v203 offset0:96 offset1:104
	ds_read2_b32 v[186:187], v203 offset0:112 offset1:120
	s_waitcnt vmcnt(32)
	v_cvt_scalef32_pk32_f32_fp6 v[32:63], v[112:117], 1.0
	v_pk_fma_f32 v[0:1], v[176:177], v[32:33], v[0:1] op_sel_hi:[0,1,1]
	v_pk_fma_f32 v[2:3], v[176:177], v[34:35], v[2:3] op_sel_hi:[0,1,1]
	v_pk_fma_f32 v[4:5], v[176:177], v[36:37], v[4:5] op_sel_hi:[0,1,1]
	v_pk_fma_f32 v[6:7], v[176:177], v[38:39], v[6:7] op_sel_hi:[0,1,1]
	v_pk_fma_f32 v[8:9], v[176:177], v[40:41], v[8:9] op_sel_hi:[0,1,1]
	v_pk_fma_f32 v[10:11], v[176:177], v[42:43], v[10:11] op_sel_hi:[0,1,1]
	v_pk_fma_f32 v[12:13], v[176:177], v[44:45], v[12:13] op_sel_hi:[0,1,1]
	v_pk_fma_f32 v[14:15], v[176:177], v[46:47], v[14:15] op_sel_hi:[0,1,1]
	v_pk_fma_f32 v[16:17], v[176:177], v[48:49], v[16:17] op_sel_hi:[0,1,1]
	v_pk_fma_f32 v[18:19], v[176:177], v[50:51], v[18:19] op_sel_hi:[0,1,1]
	v_pk_fma_f32 v[20:21], v[176:177], v[52:53], v[20:21] op_sel_hi:[0,1,1]
	v_pk_fma_f32 v[22:23], v[176:177], v[54:55], v[22:23] op_sel_hi:[0,1,1]
	v_pk_fma_f32 v[24:25], v[176:177], v[56:57], v[24:25] op_sel_hi:[0,1,1]
	v_pk_fma_f32 v[26:27], v[176:177], v[58:59], v[26:27] op_sel_hi:[0,1,1]
	v_pk_fma_f32 v[28:29], v[176:177], v[60:61], v[28:29] op_sel_hi:[0,1,1]
	v_pk_fma_f32 v[30:31], v[176:177], v[62:63], v[30:31] op_sel_hi:[0,1,1]
	s_waitcnt vmcnt(30)
	v_cvt_scalef32_pk32_f32_fp6 v[32:63], v[118:123], 1.0
	v_pk_fma_f32 v[0:1], v[176:177], v[32:33], v[0:1] op_sel:[1,0,0] op_sel_hi:[1,1,1]
	v_pk_fma_f32 v[2:3], v[176:177], v[34:35], v[2:3] op_sel:[1,0,0] op_sel_hi:[1,1,1]
	v_pk_fma_f32 v[4:5], v[176:177], v[36:37], v[4:5] op_sel:[1,0,0] op_sel_hi:[1,1,1]
	v_pk_fma_f32 v[6:7], v[176:177], v[38:39], v[6:7] op_sel:[1,0,0] op_sel_hi:[1,1,1]
	v_pk_fma_f32 v[8:9], v[176:177], v[40:41], v[8:9] op_sel:[1,0,0] op_sel_hi:[1,1,1]
	v_pk_fma_f32 v[10:11], v[176:177], v[42:43], v[10:11] op_sel:[1,0,0] op_sel_hi:[1,1,1]
	v_pk_fma_f32 v[12:13], v[176:177], v[44:45], v[12:13] op_sel:[1,0,0] op_sel_hi:[1,1,1]
	v_pk_fma_f32 v[14:15], v[176:177], v[46:47], v[14:15] op_sel:[1,0,0] op_sel_hi:[1,1,1]
	v_pk_fma_f32 v[16:17], v[176:177], v[48:49], v[16:17] op_sel:[1,0,0] op_sel_hi:[1,1,1]
	v_pk_fma_f32 v[18:19], v[176:177], v[50:51], v[18:19] op_sel:[1,0,0] op_sel_hi:[1,1,1]
	v_pk_fma_f32 v[20:21], v[176:177], v[52:53], v[20:21] op_sel:[1,0,0] op_sel_hi:[1,1,1]
	v_pk_fma_f32 v[22:23], v[176:177], v[54:55], v[22:23] op_sel:[1,0,0] op_sel_hi:[1,1,1]
	v_pk_fma_f32 v[24:25], v[176:177], v[56:57], v[24:25] op_sel:[1,0,0] op_sel_hi:[1,1,1]
	v_pk_fma_f32 v[26:27], v[176:177], v[58:59], v[26:27] op_sel:[1,0,0] op_sel_hi:[1,1,1]
	v_pk_fma_f32 v[28:29], v[176:177], v[60:61], v[28:29] op_sel:[1,0,0] op_sel_hi:[1,1,1]
	v_pk_fma_f32 v[30:31], v[176:177], v[62:63], v[30:31] op_sel:[1,0,0] op_sel_hi:[1,1,1]
	s_waitcnt vmcnt(28)
	v_cvt_scalef32_pk32_f32_fp6 v[32:63], v[124:129], 1.0
	v_pk_fma_f32 v[0:1], v[178:179], v[32:33], v[0:1] op_sel_hi:[0,1,1]
	v_pk_fma_f32 v[2:3], v[178:179], v[34:35], v[2:3] op_sel_hi:[0,1,1]
	v_pk_fma_f32 v[4:5], v[178:179], v[36:37], v[4:5] op_sel_hi:[0,1,1]
	v_pk_fma_f32 v[6:7], v[178:179], v[38:39], v[6:7] op_sel_hi:[0,1,1]
	v_pk_fma_f32 v[8:9], v[178:179], v[40:41], v[8:9] op_sel_hi:[0,1,1]
	v_pk_fma_f32 v[10:11], v[178:179], v[42:43], v[10:11] op_sel_hi:[0,1,1]
	v_pk_fma_f32 v[12:13], v[178:179], v[44:45], v[12:13] op_sel_hi:[0,1,1]
	v_pk_fma_f32 v[14:15], v[178:179], v[46:47], v[14:15] op_sel_hi:[0,1,1]
	v_pk_fma_f32 v[16:17], v[178:179], v[48:49], v[16:17] op_sel_hi:[0,1,1]
	v_pk_fma_f32 v[18:19], v[178:179], v[50:51], v[18:19] op_sel_hi:[0,1,1]
	v_pk_fma_f32 v[20:21], v[178:179], v[52:53], v[20:21] op_sel_hi:[0,1,1]
	v_pk_fma_f32 v[22:23], v[178:179], v[54:55], v[22:23] op_sel_hi:[0,1,1]
	v_pk_fma_f32 v[24:25], v[178:179], v[56:57], v[24:25] op_sel_hi:[0,1,1]
	v_pk_fma_f32 v[26:27], v[178:179], v[58:59], v[26:27] op_sel_hi:[0,1,1]
	v_pk_fma_f32 v[28:29], v[178:179], v[60:61], v[28:29] op_sel_hi:[0,1,1]
	v_pk_fma_f32 v[30:31], v[178:179], v[62:63], v[30:31] op_sel_hi:[0,1,1]
	s_waitcnt vmcnt(26)
	v_cvt_scalef32_pk32_f32_fp6 v[32:63], v[130:135], 1.0
	v_pk_fma_f32 v[0:1], v[178:179], v[32:33], v[0:1] op_sel:[1,0,0] op_sel_hi:[1,1,1]
	v_pk_fma_f32 v[2:3], v[178:179], v[34:35], v[2:3] op_sel:[1,0,0] op_sel_hi:[1,1,1]
	v_pk_fma_f32 v[4:5], v[178:179], v[36:37], v[4:5] op_sel:[1,0,0] op_sel_hi:[1,1,1]
	v_pk_fma_f32 v[6:7], v[178:179], v[38:39], v[6:7] op_sel:[1,0,0] op_sel_hi:[1,1,1]
	v_pk_fma_f32 v[8:9], v[178:179], v[40:41], v[8:9] op_sel:[1,0,0] op_sel_hi:[1,1,1]
	v_pk_fma_f32 v[10:11], v[178:179], v[42:43], v[10:11] op_sel:[1,0,0] op_sel_hi:[1,1,1]
	v_pk_fma_f32 v[12:13], v[178:179], v[44:45], v[12:13] op_sel:[1,0,0] op_sel_hi:[1,1,1]
	v_pk_fma_f32 v[14:15], v[178:179], v[46:47], v[14:15] op_sel:[1,0,0] op_sel_hi:[1,1,1]
	v_pk_fma_f32 v[16:17], v[178:179], v[48:49], v[16:17] op_sel:[1,0,0] op_sel_hi:[1,1,1]
	v_pk_fma_f32 v[18:19], v[178:179], v[50:51], v[18:19] op_sel:[1,0,0] op_sel_hi:[1,1,1]
	v_pk_fma_f32 v[20:21], v[178:179], v[52:53], v[20:21] op_sel:[1,0,0] op_sel_hi:[1,1,1]
	v_pk_fma_f32 v[22:23], v[178:179], v[54:55], v[22:23] op_sel:[1,0,0] op_sel_hi:[1,1,1]
	v_pk_fma_f32 v[24:25], v[178:179], v[56:57], v[24:25] op_sel:[1,0,0] op_sel_hi:[1,1,1]
	v_pk_fma_f32 v[26:27], v[178:179], v[58:59], v[26:27] op_sel:[1,0,0] op_sel_hi:[1,1,1]
	v_pk_fma_f32 v[28:29], v[178:179], v[60:61], v[28:29] op_sel:[1,0,0] op_sel_hi:[1,1,1]
	v_pk_fma_f32 v[30:31], v[178:179], v[62:63], v[30:31] op_sel:[1,0,0] op_sel_hi:[1,1,1]
	s_waitcnt lgkmcnt(0)
	v_mad_u32_u24 v160, v160, s100, v199
	v_mad_u32_u24 v161, v161, s100, v199
	v_mad_u32_u24 v162, v162, s100, v199
	v_mad_u32_u24 v163, v163, s100, v199
	global_load_dwordx4 v[112:115], v160, s[4:5]
	global_load_dwordx2 v[116:117], v160, s[4:5] offset:16
	global_load_dwordx4 v[118:121], v161, s[4:5]
	global_load_dwordx2 v[122:123], v161, s[4:5] offset:16
	global_load_dwordx4 v[124:127], v162, s[4:5]
	global_load_dwordx2 v[128:129], v162, s[4:5] offset:16
	global_load_dwordx4 v[130:133], v163, s[4:5]
	global_load_dwordx2 v[134:135], v163, s[4:5] offset:16
	ds_read2_b32 v[168:169], v202 offset0:96 offset1:104
	ds_read2_b32 v[170:171], v202 offset0:112 offset1:120
	ds_read2_b32 v[176:177], v204 offset0:0 offset1:8
	ds_read2_b32 v[178:179], v204 offset0:16 offset1:24
	s_waitcnt vmcnt(32)
	v_cvt_scalef32_pk32_f32_fp6 v[32:63], v[136:141], 1.0
	v_pk_fma_f32 v[0:1], v[184:185], v[32:33], v[0:1] op_sel_hi:[0,1,1]
	v_pk_fma_f32 v[2:3], v[184:185], v[34:35], v[2:3] op_sel_hi:[0,1,1]
	v_pk_fma_f32 v[4:5], v[184:185], v[36:37], v[4:5] op_sel_hi:[0,1,1]
	v_pk_fma_f32 v[6:7], v[184:185], v[38:39], v[6:7] op_sel_hi:[0,1,1]
	v_pk_fma_f32 v[8:9], v[184:185], v[40:41], v[8:9] op_sel_hi:[0,1,1]
	v_pk_fma_f32 v[10:11], v[184:185], v[42:43], v[10:11] op_sel_hi:[0,1,1]
	v_pk_fma_f32 v[12:13], v[184:185], v[44:45], v[12:13] op_sel_hi:[0,1,1]
	v_pk_fma_f32 v[14:15], v[184:185], v[46:47], v[14:15] op_sel_hi:[0,1,1]
	v_pk_fma_f32 v[16:17], v[184:185], v[48:49], v[16:17] op_sel_hi:[0,1,1]
	v_pk_fma_f32 v[18:19], v[184:185], v[50:51], v[18:19] op_sel_hi:[0,1,1]
	v_pk_fma_f32 v[20:21], v[184:185], v[52:53], v[20:21] op_sel_hi:[0,1,1]
	v_pk_fma_f32 v[22:23], v[184:185], v[54:55], v[22:23] op_sel_hi:[0,1,1]
	v_pk_fma_f32 v[24:25], v[184:185], v[56:57], v[24:25] op_sel_hi:[0,1,1]
	v_pk_fma_f32 v[26:27], v[184:185], v[58:59], v[26:27] op_sel_hi:[0,1,1]
	v_pk_fma_f32 v[28:29], v[184:185], v[60:61], v[28:29] op_sel_hi:[0,1,1]
	v_pk_fma_f32 v[30:31], v[184:185], v[62:63], v[30:31] op_sel_hi:[0,1,1]
	s_waitcnt vmcnt(30)
	v_cvt_scalef32_pk32_f32_fp6 v[32:63], v[142:147], 1.0
	v_pk_fma_f32 v[0:1], v[184:185], v[32:33], v[0:1] op_sel:[1,0,0] op_sel_hi:[1,1,1]
	v_pk_fma_f32 v[2:3], v[184:185], v[34:35], v[2:3] op_sel:[1,0,0] op_sel_hi:[1,1,1]
	v_pk_fma_f32 v[4:5], v[184:185], v[36:37], v[4:5] op_sel:[1,0,0] op_sel_hi:[1,1,1]
	v_pk_fma_f32 v[6:7], v[184:185], v[38:39], v[6:7] op_sel:[1,0,0] op_sel_hi:[1,1,1]
	v_pk_fma_f32 v[8:9], v[184:185], v[40:41], v[8:9] op_sel:[1,0,0] op_sel_hi:[1,1,1]
	v_pk_fma_f32 v[10:11], v[184:185], v[42:43], v[10:11] op_sel:[1,0,0] op_sel_hi:[1,1,1]
	v_pk_fma_f32 v[12:13], v[184:185], v[44:45], v[12:13] op_sel:[1,0,0] op_sel_hi:[1,1,1]
	v_pk_fma_f32 v[14:15], v[184:185], v[46:47], v[14:15] op_sel:[1,0,0] op_sel_hi:[1,1,1]
	v_pk_fma_f32 v[16:17], v[184:185], v[48:49], v[16:17] op_sel:[1,0,0] op_sel_hi:[1,1,1]
	v_pk_fma_f32 v[18:19], v[184:185], v[50:51], v[18:19] op_sel:[1,0,0] op_sel_hi:[1,1,1]
	v_pk_fma_f32 v[20:21], v[184:185], v[52:53], v[20:21] op_sel:[1,0,0] op_sel_hi:[1,1,1]
	v_pk_fma_f32 v[22:23], v[184:185], v[54:55], v[22:23] op_sel:[1,0,0] op_sel_hi:[1,1,1]
	v_pk_fma_f32 v[24:25], v[184:185], v[56:57], v[24:25] op_sel:[1,0,0] op_sel_hi:[1,1,1]
	v_pk_fma_f32 v[26:27], v[184:185], v[58:59], v[26:27] op_sel:[1,0,0] op_sel_hi:[1,1,1]
	v_pk_fma_f32 v[28:29], v[184:185], v[60:61], v[28:29] op_sel:[1,0,0] op_sel_hi:[1,1,1]
	v_pk_fma_f32 v[30:31], v[184:185], v[62:63], v[30:31] op_sel:[1,0,0] op_sel_hi:[1,1,1]
	s_waitcnt vmcnt(28)
	v_cvt_scalef32_pk32_f32_fp6 v[32:63], v[148:153], 1.0
	v_pk_fma_f32 v[0:1], v[186:187], v[32:33], v[0:1] op_sel_hi:[0,1,1]
	v_pk_fma_f32 v[2:3], v[186:187], v[34:35], v[2:3] op_sel_hi:[0,1,1]
	v_pk_fma_f32 v[4:5], v[186:187], v[36:37], v[4:5] op_sel_hi:[0,1,1]
	v_pk_fma_f32 v[6:7], v[186:187], v[38:39], v[6:7] op_sel_hi:[0,1,1]
	v_pk_fma_f32 v[8:9], v[186:187], v[40:41], v[8:9] op_sel_hi:[0,1,1]
	v_pk_fma_f32 v[10:11], v[186:187], v[42:43], v[10:11] op_sel_hi:[0,1,1]
	v_pk_fma_f32 v[12:13], v[186:187], v[44:45], v[12:13] op_sel_hi:[0,1,1]
	v_pk_fma_f32 v[14:15], v[186:187], v[46:47], v[14:15] op_sel_hi:[0,1,1]
	v_pk_fma_f32 v[16:17], v[186:187], v[48:49], v[16:17] op_sel_hi:[0,1,1]
	v_pk_fma_f32 v[18:19], v[186:187], v[50:51], v[18:19] op_sel_hi:[0,1,1]
	v_pk_fma_f32 v[20:21], v[186:187], v[52:53], v[20:21] op_sel_hi:[0,1,1]
	v_pk_fma_f32 v[22:23], v[186:187], v[54:55], v[22:23] op_sel_hi:[0,1,1]
	v_pk_fma_f32 v[24:25], v[186:187], v[56:57], v[24:25] op_sel_hi:[0,1,1]
	v_pk_fma_f32 v[26:27], v[186:187], v[58:59], v[26:27] op_sel_hi:[0,1,1]
	v_pk_fma_f32 v[28:29], v[186:187], v[60:61], v[28:29] op_sel_hi:[0,1,1]
	v_pk_fma_f32 v[30:31], v[186:187], v[62:63], v[30:31] op_sel_hi:[0,1,1]
	s_waitcnt vmcnt(26)
	v_cvt_scalef32_pk32_f32_fp6 v[32:63], v[154:159], 1.0
	v_pk_fma_f32 v[0:1], v[186:187], v[32:33], v[0:1] op_sel:[1,0,0] op_sel_hi:[1,1,1]
	v_pk_fma_f32 v[2:3], v[186:187], v[34:35], v[2:3] op_sel:[1,0,0] op_sel_hi:[1,1,1]
	v_pk_fma_f32 v[4:5], v[186:187], v[36:37], v[4:5] op_sel:[1,0,0] op_sel_hi:[1,1,1]
	v_pk_fma_f32 v[6:7], v[186:187], v[38:39], v[6:7] op_sel:[1,0,0] op_sel_hi:[1,1,1]
	v_pk_fma_f32 v[8:9], v[186:187], v[40:41], v[8:9] op_sel:[1,0,0] op_sel_hi:[1,1,1]
	v_pk_fma_f32 v[10:11], v[186:187], v[42:43], v[10:11] op_sel:[1,0,0] op_sel_hi:[1,1,1]
	v_pk_fma_f32 v[12:13], v[186:187], v[44:45], v[12:13] op_sel:[1,0,0] op_sel_hi:[1,1,1]
	v_pk_fma_f32 v[14:15], v[186:187], v[46:47], v[14:15] op_sel:[1,0,0] op_sel_hi:[1,1,1]
	v_pk_fma_f32 v[16:17], v[186:187], v[48:49], v[16:17] op_sel:[1,0,0] op_sel_hi:[1,1,1]
	v_pk_fma_f32 v[18:19], v[186:187], v[50:51], v[18:19] op_sel:[1,0,0] op_sel_hi:[1,1,1]
	v_pk_fma_f32 v[20:21], v[186:187], v[52:53], v[20:21] op_sel:[1,0,0] op_sel_hi:[1,1,1]
	v_pk_fma_f32 v[22:23], v[186:187], v[54:55], v[22:23] op_sel:[1,0,0] op_sel_hi:[1,1,1]
	v_pk_fma_f32 v[24:25], v[186:187], v[56:57], v[24:25] op_sel:[1,0,0] op_sel_hi:[1,1,1]
	v_pk_fma_f32 v[26:27], v[186:187], v[58:59], v[26:27] op_sel:[1,0,0] op_sel_hi:[1,1,1]
	v_pk_fma_f32 v[28:29], v[186:187], v[60:61], v[28:29] op_sel:[1,0,0] op_sel_hi:[1,1,1]
	v_pk_fma_f32 v[30:31], v[186:187], v[62:63], v[30:31] op_sel:[1,0,0] op_sel_hi:[1,1,1]
	s_waitcnt lgkmcnt(0)
	v_mad_u32_u24 v168, v168, s100, v199
	v_mad_u32_u24 v169, v169, s100, v199
	v_mad_u32_u24 v170, v170, s100, v199
	v_mad_u32_u24 v171, v171, s100, v199
	global_load_dwordx4 v[136:139], v168, s[4:5]
	global_load_dwordx2 v[140:141], v168, s[4:5] offset:16
	global_load_dwordx4 v[142:145], v169, s[4:5]
	global_load_dwordx2 v[146:147], v169, s[4:5] offset:16
	global_load_dwordx4 v[148:151], v170, s[4:5]
	global_load_dwordx2 v[152:153], v170, s[4:5] offset:16
	global_load_dwordx4 v[154:157], v171, s[4:5]
	global_load_dwordx2 v[158:159], v171, s[4:5] offset:16
	s_nop 1
	v_permlane32_swap_b32_e32 v0, v16
	v_permlane32_swap_b32_e32 v1, v17
	v_permlane32_swap_b32_e32 v2, v18
	v_permlane32_swap_b32_e32 v3, v19
	v_permlane32_swap_b32_e32 v4, v20
	v_permlane32_swap_b32_e32 v5, v21
	v_permlane32_swap_b32_e32 v6, v22
	v_permlane32_swap_b32_e32 v7, v23
	v_permlane32_swap_b32_e32 v8, v24
	v_permlane32_swap_b32_e32 v9, v25
	v_permlane32_swap_b32_e32 v10, v26
	v_permlane32_swap_b32_e32 v11, v27
	v_permlane32_swap_b32_e32 v12, v28
	v_permlane32_swap_b32_e32 v13, v29
	v_permlane32_swap_b32_e32 v14, v30
	v_permlane32_swap_b32_e32 v15, v31
	v_pk_add_f32 v[0:1], v[0:1], v[16:17]
	v_pk_add_f32 v[2:3], v[2:3], v[18:19]
	v_pk_add_f32 v[4:5], v[4:5], v[20:21]
	v_pk_add_f32 v[6:7], v[6:7], v[22:23]
	v_pk_add_f32 v[8:9], v[8:9], v[24:25]
	v_pk_add_f32 v[10:11], v[10:11], v[26:27]
	v_pk_add_f32 v[12:13], v[12:13], v[28:29]
	v_pk_add_f32 v[14:15], v[14:15], v[30:31]
	s_nop 1
	v_permlane16_swap_b32_e32 v0, v8
	v_permlane16_swap_b32_e32 v1, v9
	v_permlane16_swap_b32_e32 v2, v10
	v_permlane16_swap_b32_e32 v3, v11
	v_permlane16_swap_b32_e32 v4, v12
	v_permlane16_swap_b32_e32 v5, v13
	v_permlane16_swap_b32_e32 v6, v14
	v_permlane16_swap_b32_e32 v7, v15
	v_pk_add_f32 v[0:1], v[0:1], v[8:9]
	v_pk_add_f32 v[2:3], v[2:3], v[10:11]
	v_pk_add_f32 v[4:5], v[4:5], v[12:13]
	v_pk_add_f32 v[6:7], v[6:7], v[14:15]
	s_nop 1
	v_add_f32_dpp v0, v0, v0 row_ror:8 row_mask:0xf bank_mask:0x3
	v_add_f32_dpp v1, v1, v1 row_ror:8 row_mask:0xf bank_mask:0x3
	v_add_f32_dpp v2, v2, v2 row_ror:8 row_mask:0xf bank_mask:0x3
	v_add_f32_dpp v3, v3, v3 row_ror:8 row_mask:0xf bank_mask:0x3
	v_add_f32_dpp v0, v4, v4 row_ror:8 row_mask:0xf bank_mask:0xc
	v_add_f32_dpp v1, v5, v5 row_ror:8 row_mask:0xf bank_mask:0xc
	v_add_f32_dpp v2, v6, v6 row_ror:8 row_mask:0xf bank_mask:0xc
	v_add_f32_dpp v3, v7, v7 row_ror:8 row_mask:0xf bank_mask:0xc
	s_waitcnt vmcnt(32)
	v_pk_add_f32 v[192:193], v[192:193], v[0:1]
	v_pk_add_f32 v[194:195], v[194:195], v[2:3]
	global_store_dwordx4 v200, v[192:195], s[8:9]
	s_add_u32 s14, s14, 1
	s_and_b32 s14, s14, 63
	s_add_u32 s18, s14, 1
	s_and_b32 s98, s18, 63
	s_mov_b32 s100, s98
	s_and_b32 s19, s100, 15
	s_lshr_b32 s98, s100, 4
	s_lshl_b32 s99, s19, 9
	s_mul_i32 s15, s19, s16
	s_lshl_b32 s18, s98, 7
	s_add_u32 s15, s15, s18
	s_lshl_b32 s18, s101, 12
	s_add_u32 s15, s15, s18
	s_add_u32 s8, s24, s15
	s_addc_u32 s9, s25, 0
	s_mul_i32 s15, s98, 0x300000
	s_add_u32 s4, s26, 0x3800000
	s_addc_u32 s5, s27, 0
	s_add_u32 s4, s4, s15
	s_addc_u32 s5, s5, 0
	v_add_u32_e32 v201, s99, v197
	v_add_u32_e32 v203, s99, v198
	s_movk_i32 s100, 0xc0
	ds_read2_b32 v[160:161], v201 offset0:0 offset1:8
	ds_read2_b32 v[162:163], v201 offset0:16 offset1:24
	global_load_dwordx4 v[192:195], v200, s[10:11]
	ds_read2_b32 v[184:185], v204 offset0:32 offset1:40
	ds_read2_b32 v[186:187], v204 offset0:48 offset1:56
	s_waitcnt vmcnt(32)
	v_cvt_scalef32_pk32_f32_fp6 v[32:63], v[64:69], 1.0
	v_pk_mul_f32 v[0:1], v[176:177], v[32:33] op_sel_hi:[0,1]
	v_pk_mul_f32 v[2:3], v[176:177], v[34:35] op_sel_hi:[0,1]
	v_pk_mul_f32 v[4:5], v[176:177], v[36:37] op_sel_hi:[0,1]
	v_pk_mul_f32 v[6:7], v[176:177], v[38:39] op_sel_hi:[0,1]
	v_pk_mul_f32 v[8:9], v[176:177], v[40:41] op_sel_hi:[0,1]
	v_pk_mul_f32 v[10:11], v[176:177], v[42:43] op_sel_hi:[0,1]
	v_pk_mul_f32 v[12:13], v[176:177], v[44:45] op_sel_hi:[0,1]
	v_pk_mul_f32 v[14:15], v[176:177], v[46:47] op_sel_hi:[0,1]
	v_pk_mul_f32 v[16:17], v[176:177], v[48:49] op_sel_hi:[0,1]
	v_pk_mul_f32 v[18:19], v[176:177], v[50:51] op_sel_hi:[0,1]
	v_pk_mul_f32 v[20:21], v[176:177], v[52:53] op_sel_hi:[0,1]
	v_pk_mul_f32 v[22:23], v[176:177], v[54:55] op_sel_hi:[0,1]
	v_pk_mul_f32 v[24:25], v[176:177], v[56:57] op_sel_hi:[0,1]
	v_pk_mul_f32 v[26:27], v[176:177], v[58:59] op_sel_hi:[0,1]
	v_pk_mul_f32 v[28:29], v[176:177], v[60:61] op_sel_hi:[0,1]
	v_pk_mul_f32 v[30:31], v[176:177], v[62:63] op_sel_hi:[0,1]
	s_waitcnt vmcnt(30)
	v_cvt_scalef32_pk32_f32_fp6 v[32:63], v[70:75], 1.0
	v_pk_fma_f32 v[0:1], v[176:177], v[32:33], v[0:1] op_sel:[1,0,0] op_sel_hi:[1,1,1]
	v_pk_fma_f32 v[2:3], v[176:177], v[34:35], v[2:3] op_sel:[1,0,0] op_sel_hi:[1,1,1]
	v_pk_fma_f32 v[4:5], v[176:177], v[36:37], v[4:5] op_sel:[1,0,0] op_sel_hi:[1,1,1]
	v_pk_fma_f32 v[6:7], v[176:177], v[38:39], v[6:7] op_sel:[1,0,0] op_sel_hi:[1,1,1]
	v_pk_fma_f32 v[8:9], v[176:177], v[40:41], v[8:9] op_sel:[1,0,0] op_sel_hi:[1,1,1]
	v_pk_fma_f32 v[10:11], v[176:177], v[42:43], v[10:11] op_sel:[1,0,0] op_sel_hi:[1,1,1]
	v_pk_fma_f32 v[12:13], v[176:177], v[44:45], v[12:13] op_sel:[1,0,0] op_sel_hi:[1,1,1]
	v_pk_fma_f32 v[14:15], v[176:177], v[46:47], v[14:15] op_sel:[1,0,0] op_sel_hi:[1,1,1]
	v_pk_fma_f32 v[16:17], v[176:177], v[48:49], v[16:17] op_sel:[1,0,0] op_sel_hi:[1,1,1]
	v_pk_fma_f32 v[18:19], v[176:177], v[50:51], v[18:19] op_sel:[1,0,0] op_sel_hi:[1,1,1]
	v_pk_fma_f32 v[20:21], v[176:177], v[52:53], v[20:21] op_sel:[1,0,0] op_sel_hi:[1,1,1]
	v_pk_fma_f32 v[22:23], v[176:177], v[54:55], v[22:23] op_sel:[1,0,0] op_sel_hi:[1,1,1]
	v_pk_fma_f32 v[24:25], v[176:177], v[56:57], v[24:25] op_sel:[1,0,0] op_sel_hi:[1,1,1]
	v_pk_fma_f32 v[26:27], v[176:177], v[58:59], v[26:27] op_sel:[1,0,0] op_sel_hi:[1,1,1]
	v_pk_fma_f32 v[28:29], v[176:177], v[60:61], v[28:29] op_sel:[1,0,0] op_sel_hi:[1,1,1]
	v_pk_fma_f32 v[30:31], v[176:177], v[62:63], v[30:31] op_sel:[1,0,0] op_sel_hi:[1,1,1]
	s_waitcnt vmcnt(28)
	v_cvt_scalef32_pk32_f32_fp6 v[32:63], v[76:81], 1.0
	v_pk_fma_f32 v[0:1], v[178:179], v[32:33], v[0:1] op_sel_hi:[0,1,1]
	v_pk_fma_f32 v[2:3], v[178:179], v[34:35], v[2:3] op_sel_hi:[0,1,1]
	v_pk_fma_f32 v[4:5], v[178:179], v[36:37], v[4:5] op_sel_hi:[0,1,1]
	v_pk_fma_f32 v[6:7], v[178:179], v[38:39], v[6:7] op_sel_hi:[0,1,1]
	v_pk_fma_f32 v[8:9], v[178:179], v[40:41], v[8:9] op_sel_hi:[0,1,1]
	v_pk_fma_f32 v[10:11], v[178:179], v[42:43], v[10:11] op_sel_hi:[0,1,1]
	v_pk_fma_f32 v[12:13], v[178:179], v[44:45], v[12:13] op_sel_hi:[0,1,1]
	v_pk_fma_f32 v[14:15], v[178:179], v[46:47], v[14:15] op_sel_hi:[0,1,1]
	v_pk_fma_f32 v[16:17], v[178:179], v[48:49], v[16:17] op_sel_hi:[0,1,1]
	v_pk_fma_f32 v[18:19], v[178:179], v[50:51], v[18:19] op_sel_hi:[0,1,1]
	v_pk_fma_f32 v[20:21], v[178:179], v[52:53], v[20:21] op_sel_hi:[0,1,1]
	v_pk_fma_f32 v[22:23], v[178:179], v[54:55], v[22:23] op_sel_hi:[0,1,1]
	v_pk_fma_f32 v[24:25], v[178:179], v[56:57], v[24:25] op_sel_hi:[0,1,1]
	v_pk_fma_f32 v[26:27], v[178:179], v[58:59], v[26:27] op_sel_hi:[0,1,1]
	v_pk_fma_f32 v[28:29], v[178:179], v[60:61], v[28:29] op_sel_hi:[0,1,1]
	v_pk_fma_f32 v[30:31], v[178:179], v[62:63], v[30:31] op_sel_hi:[0,1,1]
	s_waitcnt vmcnt(26)
	v_cvt_scalef32_pk32_f32_fp6 v[32:63], v[82:87], 1.0
	v_pk_fma_f32 v[0:1], v[178:179], v[32:33], v[0:1] op_sel:[1,0,0] op_sel_hi:[1,1,1]
	v_pk_fma_f32 v[2:3], v[178:179], v[34:35], v[2:3] op_sel:[1,0,0] op_sel_hi:[1,1,1]
	v_pk_fma_f32 v[4:5], v[178:179], v[36:37], v[4:5] op_sel:[1,0,0] op_sel_hi:[1,1,1]
	v_pk_fma_f32 v[6:7], v[178:179], v[38:39], v[6:7] op_sel:[1,0,0] op_sel_hi:[1,1,1]
	v_pk_fma_f32 v[8:9], v[178:179], v[40:41], v[8:9] op_sel:[1,0,0] op_sel_hi:[1,1,1]
	v_pk_fma_f32 v[10:11], v[178:179], v[42:43], v[10:11] op_sel:[1,0,0] op_sel_hi:[1,1,1]
	v_pk_fma_f32 v[12:13], v[178:179], v[44:45], v[12:13] op_sel:[1,0,0] op_sel_hi:[1,1,1]
	v_pk_fma_f32 v[14:15], v[178:179], v[46:47], v[14:15] op_sel:[1,0,0] op_sel_hi:[1,1,1]
	v_pk_fma_f32 v[16:17], v[178:179], v[48:49], v[16:17] op_sel:[1,0,0] op_sel_hi:[1,1,1]
	v_pk_fma_f32 v[18:19], v[178:179], v[50:51], v[18:19] op_sel:[1,0,0] op_sel_hi:[1,1,1]
	v_pk_fma_f32 v[20:21], v[178:179], v[52:53], v[20:21] op_sel:[1,0,0] op_sel_hi:[1,1,1]
	v_pk_fma_f32 v[22:23], v[178:179], v[54:55], v[22:23] op_sel:[1,0,0] op_sel_hi:[1,1,1]
	v_pk_fma_f32 v[24:25], v[178:179], v[56:57], v[24:25] op_sel:[1,0,0] op_sel_hi:[1,1,1]
	v_pk_fma_f32 v[26:27], v[178:179], v[58:59], v[26:27] op_sel:[1,0,0] op_sel_hi:[1,1,1]
	v_pk_fma_f32 v[28:29], v[178:179], v[60:61], v[28:29] op_sel:[1,0,0] op_sel_hi:[1,1,1]
	v_pk_fma_f32 v[30:31], v[178:179], v[62:63], v[30:31] op_sel:[1,0,0] op_sel_hi:[1,1,1]
	s_waitcnt lgkmcnt(0)
	v_mad_u32_u24 v160, v160, s100, v199
	v_mad_u32_u24 v161, v161, s100, v199
	v_mad_u32_u24 v162, v162, s100, v199
	v_mad_u32_u24 v163, v163, s100, v199
	global_load_dwordx4 v[64:67], v160, s[4:5]
	global_load_dwordx2 v[68:69], v160, s[4:5] offset:16
	global_load_dwordx4 v[70:73], v161, s[4:5]
	global_load_dwordx2 v[74:75], v161, s[4:5] offset:16
	global_load_dwordx4 v[76:79], v162, s[4:5]
	global_load_dwordx2 v[80:81], v162, s[4:5] offset:16
	global_load_dwordx4 v[82:85], v163, s[4:5]
	global_load_dwordx2 v[86:87], v163, s[4:5] offset:16
	ds_read2_b32 v[168:169], v201 offset0:32 offset1:40
	ds_read2_b32 v[170:171], v201 offset0:48 offset1:56
	ds_read2_b32 v[176:177], v204 offset0:64 offset1:72
	ds_read2_b32 v[178:179], v204 offset0:80 offset1:88
	s_waitcnt vmcnt(32)
	v_cvt_scalef32_pk32_f32_fp6 v[32:63], v[88:93], 1.0
	v_pk_fma_f32 v[0:1], v[184:185], v[32:33], v[0:1] op_sel_hi:[0,1,1]
	v_pk_fma_f32 v[2:3], v[184:185], v[34:35], v[2:3] op_sel_hi:[0,1,1]
	v_pk_fma_f32 v[4:5], v[184:185], v[36:37], v[4:5] op_sel_hi:[0,1,1]
	v_pk_fma_f32 v[6:7], v[184:185], v[38:39], v[6:7] op_sel_hi:[0,1,1]
	v_pk_fma_f32 v[8:9], v[184:185], v[40:41], v[8:9] op_sel_hi:[0,1,1]
	v_pk_fma_f32 v[10:11], v[184:185], v[42:43], v[10:11] op_sel_hi:[0,1,1]
	v_pk_fma_f32 v[12:13], v[184:185], v[44:45], v[12:13] op_sel_hi:[0,1,1]
	v_pk_fma_f32 v[14:15], v[184:185], v[46:47], v[14:15] op_sel_hi:[0,1,1]
	v_pk_fma_f32 v[16:17], v[184:185], v[48:49], v[16:17] op_sel_hi:[0,1,1]
	v_pk_fma_f32 v[18:19], v[184:185], v[50:51], v[18:19] op_sel_hi:[0,1,1]
	v_pk_fma_f32 v[20:21], v[184:185], v[52:53], v[20:21] op_sel_hi:[0,1,1]
	v_pk_fma_f32 v[22:23], v[184:185], v[54:55], v[22:23] op_sel_hi:[0,1,1]
	v_pk_fma_f32 v[24:25], v[184:185], v[56:57], v[24:25] op_sel_hi:[0,1,1]
	v_pk_fma_f32 v[26:27], v[184:185], v[58:59], v[26:27] op_sel_hi:[0,1,1]
	v_pk_fma_f32 v[28:29], v[184:185], v[60:61], v[28:29] op_sel_hi:[0,1,1]
	v_pk_fma_f32 v[30:31], v[184:185], v[62:63], v[30:31] op_sel_hi:[0,1,1]
	s_waitcnt vmcnt(30)
	v_cvt_scalef32_pk32_f32_fp6 v[32:63], v[94:99], 1.0
	v_pk_fma_f32 v[0:1], v[184:185], v[32:33], v[0:1] op_sel:[1,0,0] op_sel_hi:[1,1,1]
	v_pk_fma_f32 v[2:3], v[184:185], v[34:35], v[2:3] op_sel:[1,0,0] op_sel_hi:[1,1,1]
	v_pk_fma_f32 v[4:5], v[184:185], v[36:37], v[4:5] op_sel:[1,0,0] op_sel_hi:[1,1,1]
	v_pk_fma_f32 v[6:7], v[184:185], v[38:39], v[6:7] op_sel:[1,0,0] op_sel_hi:[1,1,1]
	v_pk_fma_f32 v[8:9], v[184:185], v[40:41], v[8:9] op_sel:[1,0,0] op_sel_hi:[1,1,1]
	v_pk_fma_f32 v[10:11], v[184:185], v[42:43], v[10:11] op_sel:[1,0,0] op_sel_hi:[1,1,1]
	v_pk_fma_f32 v[12:13], v[184:185], v[44:45], v[12:13] op_sel:[1,0,0] op_sel_hi:[1,1,1]
	v_pk_fma_f32 v[14:15], v[184:185], v[46:47], v[14:15] op_sel:[1,0,0] op_sel_hi:[1,1,1]
	v_pk_fma_f32 v[16:17], v[184:185], v[48:49], v[16:17] op_sel:[1,0,0] op_sel_hi:[1,1,1]
	v_pk_fma_f32 v[18:19], v[184:185], v[50:51], v[18:19] op_sel:[1,0,0] op_sel_hi:[1,1,1]
	v_pk_fma_f32 v[20:21], v[184:185], v[52:53], v[20:21] op_sel:[1,0,0] op_sel_hi:[1,1,1]
	v_pk_fma_f32 v[22:23], v[184:185], v[54:55], v[22:23] op_sel:[1,0,0] op_sel_hi:[1,1,1]
	v_pk_fma_f32 v[24:25], v[184:185], v[56:57], v[24:25] op_sel:[1,0,0] op_sel_hi:[1,1,1]
	v_pk_fma_f32 v[26:27], v[184:185], v[58:59], v[26:27] op_sel:[1,0,0] op_sel_hi:[1,1,1]
	v_pk_fma_f32 v[28:29], v[184:185], v[60:61], v[28:29] op_sel:[1,0,0] op_sel_hi:[1,1,1]
	v_pk_fma_f32 v[30:31], v[184:185], v[62:63], v[30:31] op_sel:[1,0,0] op_sel_hi:[1,1,1]
	s_waitcnt vmcnt(28)
	v_cvt_scalef32_pk32_f32_fp6 v[32:63], v[100:105], 1.0
	v_pk_fma_f32 v[0:1], v[186:187], v[32:33], v[0:1] op_sel_hi:[0,1,1]
	v_pk_fma_f32 v[2:3], v[186:187], v[34:35], v[2:3] op_sel_hi:[0,1,1]
	v_pk_fma_f32 v[4:5], v[186:187], v[36:37], v[4:5] op_sel_hi:[0,1,1]
	v_pk_fma_f32 v[6:7], v[186:187], v[38:39], v[6:7] op_sel_hi:[0,1,1]
	v_pk_fma_f32 v[8:9], v[186:187], v[40:41], v[8:9] op_sel_hi:[0,1,1]
	v_pk_fma_f32 v[10:11], v[186:187], v[42:43], v[10:11] op_sel_hi:[0,1,1]
	v_pk_fma_f32 v[12:13], v[186:187], v[44:45], v[12:13] op_sel_hi:[0,1,1]
	v_pk_fma_f32 v[14:15], v[186:187], v[46:47], v[14:15] op_sel_hi:[0,1,1]
	v_pk_fma_f32 v[16:17], v[186:187], v[48:49], v[16:17] op_sel_hi:[0,1,1]
	v_pk_fma_f32 v[18:19], v[186:187], v[50:51], v[18:19] op_sel_hi:[0,1,1]
	v_pk_fma_f32 v[20:21], v[186:187], v[52:53], v[20:21] op_sel_hi:[0,1,1]
	v_pk_fma_f32 v[22:23], v[186:187], v[54:55], v[22:23] op_sel_hi:[0,1,1]
	v_pk_fma_f32 v[24:25], v[186:187], v[56:57], v[24:25] op_sel_hi:[0,1,1]
	v_pk_fma_f32 v[26:27], v[186:187], v[58:59], v[26:27] op_sel_hi:[0,1,1]
	v_pk_fma_f32 v[28:29], v[186:187], v[60:61], v[28:29] op_sel_hi:[0,1,1]
	v_pk_fma_f32 v[30:31], v[186:187], v[62:63], v[30:31] op_sel_hi:[0,1,1]
	s_waitcnt vmcnt(26)
	v_cvt_scalef32_pk32_f32_fp6 v[32:63], v[106:111], 1.0
	v_pk_fma_f32 v[0:1], v[186:187], v[32:33], v[0:1] op_sel:[1,0,0] op_sel_hi:[1,1,1]
	v_pk_fma_f32 v[2:3], v[186:187], v[34:35], v[2:3] op_sel:[1,0,0] op_sel_hi:[1,1,1]
	v_pk_fma_f32 v[4:5], v[186:187], v[36:37], v[4:5] op_sel:[1,0,0] op_sel_hi:[1,1,1]
	v_pk_fma_f32 v[6:7], v[186:187], v[38:39], v[6:7] op_sel:[1,0,0] op_sel_hi:[1,1,1]
	v_pk_fma_f32 v[8:9], v[186:187], v[40:41], v[8:9] op_sel:[1,0,0] op_sel_hi:[1,1,1]
	v_pk_fma_f32 v[10:11], v[186:187], v[42:43], v[10:11] op_sel:[1,0,0] op_sel_hi:[1,1,1]
	v_pk_fma_f32 v[12:13], v[186:187], v[44:45], v[12:13] op_sel:[1,0,0] op_sel_hi:[1,1,1]
	v_pk_fma_f32 v[14:15], v[186:187], v[46:47], v[14:15] op_sel:[1,0,0] op_sel_hi:[1,1,1]
	v_pk_fma_f32 v[16:17], v[186:187], v[48:49], v[16:17] op_sel:[1,0,0] op_sel_hi:[1,1,1]
	v_pk_fma_f32 v[18:19], v[186:187], v[50:51], v[18:19] op_sel:[1,0,0] op_sel_hi:[1,1,1]
	v_pk_fma_f32 v[20:21], v[186:187], v[52:53], v[20:21] op_sel:[1,0,0] op_sel_hi:[1,1,1]
	v_pk_fma_f32 v[22:23], v[186:187], v[54:55], v[22:23] op_sel:[1,0,0] op_sel_hi:[1,1,1]
	v_pk_fma_f32 v[24:25], v[186:187], v[56:57], v[24:25] op_sel:[1,0,0] op_sel_hi:[1,1,1]
	v_pk_fma_f32 v[26:27], v[186:187], v[58:59], v[26:27] op_sel:[1,0,0] op_sel_hi:[1,1,1]
	v_pk_fma_f32 v[28:29], v[186:187], v[60:61], v[28:29] op_sel:[1,0,0] op_sel_hi:[1,1,1]
	v_pk_fma_f32 v[30:31], v[186:187], v[62:63], v[30:31] op_sel:[1,0,0] op_sel_hi:[1,1,1]
	s_waitcnt lgkmcnt(0)
	v_mad_u32_u24 v168, v168, s100, v199
	v_mad_u32_u24 v169, v169, s100, v199
	v_mad_u32_u24 v170, v170, s100, v199
	v_mad_u32_u24 v171, v171, s100, v199
	global_load_dwordx4 v[88:91], v168, s[4:5]
	global_load_dwordx2 v[92:93], v168, s[4:5] offset:16
	global_load_dwordx4 v[94:97], v169, s[4:5]
	global_load_dwordx2 v[98:99], v169, s[4:5] offset:16
	global_load_dwordx4 v[100:103], v170, s[4:5]
	global_load_dwordx2 v[104:105], v170, s[4:5] offset:16
	global_load_dwordx4 v[106:109], v171, s[4:5]
	global_load_dwordx2 v[110:111], v171, s[4:5] offset:16
	ds_read2_b32 v[160:161], v201 offset0:64 offset1:72
	ds_read2_b32 v[162:163], v201 offset0:80 offset1:88
	ds_read2_b32 v[184:185], v204 offset0:96 offset1:104
	ds_read2_b32 v[186:187], v204 offset0:112 offset1:120
	s_waitcnt vmcnt(32)
	v_cvt_scalef32_pk32_f32_fp6 v[32:63], v[112:117], 1.0
	v_pk_fma_f32 v[0:1], v[176:177], v[32:33], v[0:1] op_sel_hi:[0,1,1]
	v_pk_fma_f32 v[2:3], v[176:177], v[34:35], v[2:3] op_sel_hi:[0,1,1]
	v_pk_fma_f32 v[4:5], v[176:177], v[36:37], v[4:5] op_sel_hi:[0,1,1]
	v_pk_fma_f32 v[6:7], v[176:177], v[38:39], v[6:7] op_sel_hi:[0,1,1]
	v_pk_fma_f32 v[8:9], v[176:177], v[40:41], v[8:9] op_sel_hi:[0,1,1]
	v_pk_fma_f32 v[10:11], v[176:177], v[42:43], v[10:11] op_sel_hi:[0,1,1]
	v_pk_fma_f32 v[12:13], v[176:177], v[44:45], v[12:13] op_sel_hi:[0,1,1]
	v_pk_fma_f32 v[14:15], v[176:177], v[46:47], v[14:15] op_sel_hi:[0,1,1]
	v_pk_fma_f32 v[16:17], v[176:177], v[48:49], v[16:17] op_sel_hi:[0,1,1]
	v_pk_fma_f32 v[18:19], v[176:177], v[50:51], v[18:19] op_sel_hi:[0,1,1]
	v_pk_fma_f32 v[20:21], v[176:177], v[52:53], v[20:21] op_sel_hi:[0,1,1]
	v_pk_fma_f32 v[22:23], v[176:177], v[54:55], v[22:23] op_sel_hi:[0,1,1]
	v_pk_fma_f32 v[24:25], v[176:177], v[56:57], v[24:25] op_sel_hi:[0,1,1]
	v_pk_fma_f32 v[26:27], v[176:177], v[58:59], v[26:27] op_sel_hi:[0,1,1]
	v_pk_fma_f32 v[28:29], v[176:177], v[60:61], v[28:29] op_sel_hi:[0,1,1]
	v_pk_fma_f32 v[30:31], v[176:177], v[62:63], v[30:31] op_sel_hi:[0,1,1]
	s_waitcnt vmcnt(30)
	v_cvt_scalef32_pk32_f32_fp6 v[32:63], v[118:123], 1.0
	v_pk_fma_f32 v[0:1], v[176:177], v[32:33], v[0:1] op_sel:[1,0,0] op_sel_hi:[1,1,1]
	v_pk_fma_f32 v[2:3], v[176:177], v[34:35], v[2:3] op_sel:[1,0,0] op_sel_hi:[1,1,1]
	v_pk_fma_f32 v[4:5], v[176:177], v[36:37], v[4:5] op_sel:[1,0,0] op_sel_hi:[1,1,1]
	v_pk_fma_f32 v[6:7], v[176:177], v[38:39], v[6:7] op_sel:[1,0,0] op_sel_hi:[1,1,1]
	v_pk_fma_f32 v[8:9], v[176:177], v[40:41], v[8:9] op_sel:[1,0,0] op_sel_hi:[1,1,1]
	v_pk_fma_f32 v[10:11], v[176:177], v[42:43], v[10:11] op_sel:[1,0,0] op_sel_hi:[1,1,1]
	v_pk_fma_f32 v[12:13], v[176:177], v[44:45], v[12:13] op_sel:[1,0,0] op_sel_hi:[1,1,1]
	v_pk_fma_f32 v[14:15], v[176:177], v[46:47], v[14:15] op_sel:[1,0,0] op_sel_hi:[1,1,1]
	v_pk_fma_f32 v[16:17], v[176:177], v[48:49], v[16:17] op_sel:[1,0,0] op_sel_hi:[1,1,1]
	v_pk_fma_f32 v[18:19], v[176:177], v[50:51], v[18:19] op_sel:[1,0,0] op_sel_hi:[1,1,1]
	v_pk_fma_f32 v[20:21], v[176:177], v[52:53], v[20:21] op_sel:[1,0,0] op_sel_hi:[1,1,1]
	v_pk_fma_f32 v[22:23], v[176:177], v[54:55], v[22:23] op_sel:[1,0,0] op_sel_hi:[1,1,1]
	v_pk_fma_f32 v[24:25], v[176:177], v[56:57], v[24:25] op_sel:[1,0,0] op_sel_hi:[1,1,1]
	v_pk_fma_f32 v[26:27], v[176:177], v[58:59], v[26:27] op_sel:[1,0,0] op_sel_hi:[1,1,1]
	v_pk_fma_f32 v[28:29], v[176:177], v[60:61], v[28:29] op_sel:[1,0,0] op_sel_hi:[1,1,1]
	v_pk_fma_f32 v[30:31], v[176:177], v[62:63], v[30:31] op_sel:[1,0,0] op_sel_hi:[1,1,1]
	s_waitcnt vmcnt(28)
	v_cvt_scalef32_pk32_f32_fp6 v[32:63], v[124:129], 1.0
	v_pk_fma_f32 v[0:1], v[178:179], v[32:33], v[0:1] op_sel_hi:[0,1,1]
	v_pk_fma_f32 v[2:3], v[178:179], v[34:35], v[2:3] op_sel_hi:[0,1,1]
	v_pk_fma_f32 v[4:5], v[178:179], v[36:37], v[4:5] op_sel_hi:[0,1,1]
	v_pk_fma_f32 v[6:7], v[178:179], v[38:39], v[6:7] op_sel_hi:[0,1,1]
	v_pk_fma_f32 v[8:9], v[178:179], v[40:41], v[8:9] op_sel_hi:[0,1,1]
	v_pk_fma_f32 v[10:11], v[178:179], v[42:43], v[10:11] op_sel_hi:[0,1,1]
	v_pk_fma_f32 v[12:13], v[178:179], v[44:45], v[12:13] op_sel_hi:[0,1,1]
	v_pk_fma_f32 v[14:15], v[178:179], v[46:47], v[14:15] op_sel_hi:[0,1,1]
	v_pk_fma_f32 v[16:17], v[178:179], v[48:49], v[16:17] op_sel_hi:[0,1,1]
	v_pk_fma_f32 v[18:19], v[178:179], v[50:51], v[18:19] op_sel_hi:[0,1,1]
	v_pk_fma_f32 v[20:21], v[178:179], v[52:53], v[20:21] op_sel_hi:[0,1,1]
	v_pk_fma_f32 v[22:23], v[178:179], v[54:55], v[22:23] op_sel_hi:[0,1,1]
	v_pk_fma_f32 v[24:25], v[178:179], v[56:57], v[24:25] op_sel_hi:[0,1,1]
	v_pk_fma_f32 v[26:27], v[178:179], v[58:59], v[26:27] op_sel_hi:[0,1,1]
	v_pk_fma_f32 v[28:29], v[178:179], v[60:61], v[28:29] op_sel_hi:[0,1,1]
	v_pk_fma_f32 v[30:31], v[178:179], v[62:63], v[30:31] op_sel_hi:[0,1,1]
	s_waitcnt vmcnt(26)
	v_cvt_scalef32_pk32_f32_fp6 v[32:63], v[130:135], 1.0
	v_pk_fma_f32 v[0:1], v[178:179], v[32:33], v[0:1] op_sel:[1,0,0] op_sel_hi:[1,1,1]
	v_pk_fma_f32 v[2:3], v[178:179], v[34:35], v[2:3] op_sel:[1,0,0] op_sel_hi:[1,1,1]
	v_pk_fma_f32 v[4:5], v[178:179], v[36:37], v[4:5] op_sel:[1,0,0] op_sel_hi:[1,1,1]
	v_pk_fma_f32 v[6:7], v[178:179], v[38:39], v[6:7] op_sel:[1,0,0] op_sel_hi:[1,1,1]
	v_pk_fma_f32 v[8:9], v[178:179], v[40:41], v[8:9] op_sel:[1,0,0] op_sel_hi:[1,1,1]
	v_pk_fma_f32 v[10:11], v[178:179], v[42:43], v[10:11] op_sel:[1,0,0] op_sel_hi:[1,1,1]
	v_pk_fma_f32 v[12:13], v[178:179], v[44:45], v[12:13] op_sel:[1,0,0] op_sel_hi:[1,1,1]
	v_pk_fma_f32 v[14:15], v[178:179], v[46:47], v[14:15] op_sel:[1,0,0] op_sel_hi:[1,1,1]
	v_pk_fma_f32 v[16:17], v[178:179], v[48:49], v[16:17] op_sel:[1,0,0] op_sel_hi:[1,1,1]
	v_pk_fma_f32 v[18:19], v[178:179], v[50:51], v[18:19] op_sel:[1,0,0] op_sel_hi:[1,1,1]
	v_pk_fma_f32 v[20:21], v[178:179], v[52:53], v[20:21] op_sel:[1,0,0] op_sel_hi:[1,1,1]
	v_pk_fma_f32 v[22:23], v[178:179], v[54:55], v[22:23] op_sel:[1,0,0] op_sel_hi:[1,1,1]
	v_pk_fma_f32 v[24:25], v[178:179], v[56:57], v[24:25] op_sel:[1,0,0] op_sel_hi:[1,1,1]
	v_pk_fma_f32 v[26:27], v[178:179], v[58:59], v[26:27] op_sel:[1,0,0] op_sel_hi:[1,1,1]
	v_pk_fma_f32 v[28:29], v[178:179], v[60:61], v[28:29] op_sel:[1,0,0] op_sel_hi:[1,1,1]
	v_pk_fma_f32 v[30:31], v[178:179], v[62:63], v[30:31] op_sel:[1,0,0] op_sel_hi:[1,1,1]
	s_waitcnt lgkmcnt(0)
	v_mad_u32_u24 v160, v160, s100, v199
	v_mad_u32_u24 v161, v161, s100, v199
	v_mad_u32_u24 v162, v162, s100, v199
	v_mad_u32_u24 v163, v163, s100, v199
	global_load_dwordx4 v[112:115], v160, s[4:5]
	global_load_dwordx2 v[116:117], v160, s[4:5] offset:16
	global_load_dwordx4 v[118:121], v161, s[4:5]
	global_load_dwordx2 v[122:123], v161, s[4:5] offset:16
	global_load_dwordx4 v[124:127], v162, s[4:5]
	global_load_dwordx2 v[128:129], v162, s[4:5] offset:16
	global_load_dwordx4 v[130:133], v163, s[4:5]
	global_load_dwordx2 v[134:135], v163, s[4:5] offset:16
	ds_read2_b32 v[168:169], v201 offset0:96 offset1:104
	ds_read2_b32 v[170:171], v201 offset0:112 offset1:120
	ds_read2_b32 v[176:177], v203 offset0:0 offset1:8
	ds_read2_b32 v[178:179], v203 offset0:16 offset1:24
	s_waitcnt vmcnt(32)
	v_cvt_scalef32_pk32_f32_fp6 v[32:63], v[136:141], 1.0
	v_pk_fma_f32 v[0:1], v[184:185], v[32:33], v[0:1] op_sel_hi:[0,1,1]
	v_pk_fma_f32 v[2:3], v[184:185], v[34:35], v[2:3] op_sel_hi:[0,1,1]
	v_pk_fma_f32 v[4:5], v[184:185], v[36:37], v[4:5] op_sel_hi:[0,1,1]
	v_pk_fma_f32 v[6:7], v[184:185], v[38:39], v[6:7] op_sel_hi:[0,1,1]
	v_pk_fma_f32 v[8:9], v[184:185], v[40:41], v[8:9] op_sel_hi:[0,1,1]
	v_pk_fma_f32 v[10:11], v[184:185], v[42:43], v[10:11] op_sel_hi:[0,1,1]
	v_pk_fma_f32 v[12:13], v[184:185], v[44:45], v[12:13] op_sel_hi:[0,1,1]
	v_pk_fma_f32 v[14:15], v[184:185], v[46:47], v[14:15] op_sel_hi:[0,1,1]
	v_pk_fma_f32 v[16:17], v[184:185], v[48:49], v[16:17] op_sel_hi:[0,1,1]
	v_pk_fma_f32 v[18:19], v[184:185], v[50:51], v[18:19] op_sel_hi:[0,1,1]
	v_pk_fma_f32 v[20:21], v[184:185], v[52:53], v[20:21] op_sel_hi:[0,1,1]
	v_pk_fma_f32 v[22:23], v[184:185], v[54:55], v[22:23] op_sel_hi:[0,1,1]
	v_pk_fma_f32 v[24:25], v[184:185], v[56:57], v[24:25] op_sel_hi:[0,1,1]
	v_pk_fma_f32 v[26:27], v[184:185], v[58:59], v[26:27] op_sel_hi:[0,1,1]
	v_pk_fma_f32 v[28:29], v[184:185], v[60:61], v[28:29] op_sel_hi:[0,1,1]
	v_pk_fma_f32 v[30:31], v[184:185], v[62:63], v[30:31] op_sel_hi:[0,1,1]
	s_waitcnt vmcnt(30)
	v_cvt_scalef32_pk32_f32_fp6 v[32:63], v[142:147], 1.0
	v_pk_fma_f32 v[0:1], v[184:185], v[32:33], v[0:1] op_sel:[1,0,0] op_sel_hi:[1,1,1]
	v_pk_fma_f32 v[2:3], v[184:185], v[34:35], v[2:3] op_sel:[1,0,0] op_sel_hi:[1,1,1]
	v_pk_fma_f32 v[4:5], v[184:185], v[36:37], v[4:5] op_sel:[1,0,0] op_sel_hi:[1,1,1]
	v_pk_fma_f32 v[6:7], v[184:185], v[38:39], v[6:7] op_sel:[1,0,0] op_sel_hi:[1,1,1]
	v_pk_fma_f32 v[8:9], v[184:185], v[40:41], v[8:9] op_sel:[1,0,0] op_sel_hi:[1,1,1]
	v_pk_fma_f32 v[10:11], v[184:185], v[42:43], v[10:11] op_sel:[1,0,0] op_sel_hi:[1,1,1]
	v_pk_fma_f32 v[12:13], v[184:185], v[44:45], v[12:13] op_sel:[1,0,0] op_sel_hi:[1,1,1]
	v_pk_fma_f32 v[14:15], v[184:185], v[46:47], v[14:15] op_sel:[1,0,0] op_sel_hi:[1,1,1]
	v_pk_fma_f32 v[16:17], v[184:185], v[48:49], v[16:17] op_sel:[1,0,0] op_sel_hi:[1,1,1]
	v_pk_fma_f32 v[18:19], v[184:185], v[50:51], v[18:19] op_sel:[1,0,0] op_sel_hi:[1,1,1]
	v_pk_fma_f32 v[20:21], v[184:185], v[52:53], v[20:21] op_sel:[1,0,0] op_sel_hi:[1,1,1]
	v_pk_fma_f32 v[22:23], v[184:185], v[54:55], v[22:23] op_sel:[1,0,0] op_sel_hi:[1,1,1]
	v_pk_fma_f32 v[24:25], v[184:185], v[56:57], v[24:25] op_sel:[1,0,0] op_sel_hi:[1,1,1]
	v_pk_fma_f32 v[26:27], v[184:185], v[58:59], v[26:27] op_sel:[1,0,0] op_sel_hi:[1,1,1]
	v_pk_fma_f32 v[28:29], v[184:185], v[60:61], v[28:29] op_sel:[1,0,0] op_sel_hi:[1,1,1]
	v_pk_fma_f32 v[30:31], v[184:185], v[62:63], v[30:31] op_sel:[1,0,0] op_sel_hi:[1,1,1]
	s_waitcnt vmcnt(28)
	v_cvt_scalef32_pk32_f32_fp6 v[32:63], v[148:153], 1.0
	v_pk_fma_f32 v[0:1], v[186:187], v[32:33], v[0:1] op_sel_hi:[0,1,1]
	v_pk_fma_f32 v[2:3], v[186:187], v[34:35], v[2:3] op_sel_hi:[0,1,1]
	v_pk_fma_f32 v[4:5], v[186:187], v[36:37], v[4:5] op_sel_hi:[0,1,1]
	v_pk_fma_f32 v[6:7], v[186:187], v[38:39], v[6:7] op_sel_hi:[0,1,1]
	v_pk_fma_f32 v[8:9], v[186:187], v[40:41], v[8:9] op_sel_hi:[0,1,1]
	v_pk_fma_f32 v[10:11], v[186:187], v[42:43], v[10:11] op_sel_hi:[0,1,1]
	v_pk_fma_f32 v[12:13], v[186:187], v[44:45], v[12:13] op_sel_hi:[0,1,1]
	v_pk_fma_f32 v[14:15], v[186:187], v[46:47], v[14:15] op_sel_hi:[0,1,1]
	v_pk_fma_f32 v[16:17], v[186:187], v[48:49], v[16:17] op_sel_hi:[0,1,1]
	v_pk_fma_f32 v[18:19], v[186:187], v[50:51], v[18:19] op_sel_hi:[0,1,1]
	v_pk_fma_f32 v[20:21], v[186:187], v[52:53], v[20:21] op_sel_hi:[0,1,1]
	v_pk_fma_f32 v[22:23], v[186:187], v[54:55], v[22:23] op_sel_hi:[0,1,1]
	v_pk_fma_f32 v[24:25], v[186:187], v[56:57], v[24:25] op_sel_hi:[0,1,1]
	v_pk_fma_f32 v[26:27], v[186:187], v[58:59], v[26:27] op_sel_hi:[0,1,1]
	v_pk_fma_f32 v[28:29], v[186:187], v[60:61], v[28:29] op_sel_hi:[0,1,1]
	v_pk_fma_f32 v[30:31], v[186:187], v[62:63], v[30:31] op_sel_hi:[0,1,1]
	s_waitcnt vmcnt(26)
	v_cvt_scalef32_pk32_f32_fp6 v[32:63], v[154:159], 1.0
	v_pk_fma_f32 v[0:1], v[186:187], v[32:33], v[0:1] op_sel:[1,0,0] op_sel_hi:[1,1,1]
	v_pk_fma_f32 v[2:3], v[186:187], v[34:35], v[2:3] op_sel:[1,0,0] op_sel_hi:[1,1,1]
	v_pk_fma_f32 v[4:5], v[186:187], v[36:37], v[4:5] op_sel:[1,0,0] op_sel_hi:[1,1,1]
	v_pk_fma_f32 v[6:7], v[186:187], v[38:39], v[6:7] op_sel:[1,0,0] op_sel_hi:[1,1,1]
	v_pk_fma_f32 v[8:9], v[186:187], v[40:41], v[8:9] op_sel:[1,0,0] op_sel_hi:[1,1,1]
	v_pk_fma_f32 v[10:11], v[186:187], v[42:43], v[10:11] op_sel:[1,0,0] op_sel_hi:[1,1,1]
	v_pk_fma_f32 v[12:13], v[186:187], v[44:45], v[12:13] op_sel:[1,0,0] op_sel_hi:[1,1,1]
	v_pk_fma_f32 v[14:15], v[186:187], v[46:47], v[14:15] op_sel:[1,0,0] op_sel_hi:[1,1,1]
	v_pk_fma_f32 v[16:17], v[186:187], v[48:49], v[16:17] op_sel:[1,0,0] op_sel_hi:[1,1,1]
	v_pk_fma_f32 v[18:19], v[186:187], v[50:51], v[18:19] op_sel:[1,0,0] op_sel_hi:[1,1,1]
	v_pk_fma_f32 v[20:21], v[186:187], v[52:53], v[20:21] op_sel:[1,0,0] op_sel_hi:[1,1,1]
	v_pk_fma_f32 v[22:23], v[186:187], v[54:55], v[22:23] op_sel:[1,0,0] op_sel_hi:[1,1,1]
	v_pk_fma_f32 v[24:25], v[186:187], v[56:57], v[24:25] op_sel:[1,0,0] op_sel_hi:[1,1,1]
	v_pk_fma_f32 v[26:27], v[186:187], v[58:59], v[26:27] op_sel:[1,0,0] op_sel_hi:[1,1,1]
	v_pk_fma_f32 v[28:29], v[186:187], v[60:61], v[28:29] op_sel:[1,0,0] op_sel_hi:[1,1,1]
	v_pk_fma_f32 v[30:31], v[186:187], v[62:63], v[30:31] op_sel:[1,0,0] op_sel_hi:[1,1,1]
	s_waitcnt lgkmcnt(0)
	v_mad_u32_u24 v168, v168, s100, v199
	v_mad_u32_u24 v169, v169, s100, v199
	v_mad_u32_u24 v170, v170, s100, v199
	v_mad_u32_u24 v171, v171, s100, v199
	global_load_dwordx4 v[136:139], v168, s[4:5]
	global_load_dwordx2 v[140:141], v168, s[4:5] offset:16
	global_load_dwordx4 v[142:145], v169, s[4:5]
	global_load_dwordx2 v[146:147], v169, s[4:5] offset:16
	global_load_dwordx4 v[148:151], v170, s[4:5]
	global_load_dwordx2 v[152:153], v170, s[4:5] offset:16
	global_load_dwordx4 v[154:157], v171, s[4:5]
	global_load_dwordx2 v[158:159], v171, s[4:5] offset:16
	s_nop 1
	v_permlane32_swap_b32_e32 v0, v16
	v_permlane32_swap_b32_e32 v1, v17
	v_permlane32_swap_b32_e32 v2, v18
	v_permlane32_swap_b32_e32 v3, v19
	v_permlane32_swap_b32_e32 v4, v20
	v_permlane32_swap_b32_e32 v5, v21
	v_permlane32_swap_b32_e32 v6, v22
	v_permlane32_swap_b32_e32 v7, v23
	v_permlane32_swap_b32_e32 v8, v24
	v_permlane32_swap_b32_e32 v9, v25
	v_permlane32_swap_b32_e32 v10, v26
	v_permlane32_swap_b32_e32 v11, v27
	v_permlane32_swap_b32_e32 v12, v28
	v_permlane32_swap_b32_e32 v13, v29
	v_permlane32_swap_b32_e32 v14, v30
	v_permlane32_swap_b32_e32 v15, v31
	v_pk_add_f32 v[0:1], v[0:1], v[16:17]
	v_pk_add_f32 v[2:3], v[2:3], v[18:19]
	v_pk_add_f32 v[4:5], v[4:5], v[20:21]
	v_pk_add_f32 v[6:7], v[6:7], v[22:23]
	v_pk_add_f32 v[8:9], v[8:9], v[24:25]
	v_pk_add_f32 v[10:11], v[10:11], v[26:27]
	v_pk_add_f32 v[12:13], v[12:13], v[28:29]
	v_pk_add_f32 v[14:15], v[14:15], v[30:31]
	s_nop 1
	v_permlane16_swap_b32_e32 v0, v8
	v_permlane16_swap_b32_e32 v1, v9
	v_permlane16_swap_b32_e32 v2, v10
	v_permlane16_swap_b32_e32 v3, v11
	v_permlane16_swap_b32_e32 v4, v12
	v_permlane16_swap_b32_e32 v5, v13
	v_permlane16_swap_b32_e32 v6, v14
	v_permlane16_swap_b32_e32 v7, v15
	v_pk_add_f32 v[0:1], v[0:1], v[8:9]
	v_pk_add_f32 v[2:3], v[2:3], v[10:11]
	v_pk_add_f32 v[4:5], v[4:5], v[12:13]
	v_pk_add_f32 v[6:7], v[6:7], v[14:15]
	s_nop 1
	v_add_f32_dpp v0, v0, v0 row_ror:8 row_mask:0xf bank_mask:0x3
	v_add_f32_dpp v1, v1, v1 row_ror:8 row_mask:0xf bank_mask:0x3
	v_add_f32_dpp v2, v2, v2 row_ror:8 row_mask:0xf bank_mask:0x3
	v_add_f32_dpp v3, v3, v3 row_ror:8 row_mask:0xf bank_mask:0x3
	v_add_f32_dpp v0, v4, v4 row_ror:8 row_mask:0xf bank_mask:0xc
	v_add_f32_dpp v1, v5, v5 row_ror:8 row_mask:0xf bank_mask:0xc
	v_add_f32_dpp v2, v6, v6 row_ror:8 row_mask:0xf bank_mask:0xc
	v_add_f32_dpp v3, v7, v7 row_ror:8 row_mask:0xf bank_mask:0xc
	s_waitcnt vmcnt(32)
	v_pk_add_f32 v[192:193], v[192:193], v[0:1]
	v_pk_add_f32 v[194:195], v[194:195], v[2:3]
	global_store_dwordx4 v200, v[192:195], s[10:11]
	s_add_u32 s14, s14, 1
	s_and_b32 s14, s14, 63
	s_add_u32 s18, s14, 1
	s_and_b32 s98, s18, 63
	s_mov_b32 s100, s98
	s_and_b32 s19, s100, 15
	s_lshr_b32 s98, s100, 4
	s_lshl_b32 s99, s19, 9
	s_mul_i32 s15, s19, s16
	s_lshl_b32 s18, s98, 7
	s_add_u32 s15, s15, s18
	s_lshl_b32 s18, s101, 12
	s_add_u32 s15, s15, s18
	s_add_u32 s10, s24, s15
	s_addc_u32 s11, s25, 0
	s_mul_i32 s15, s98, 0x300000
	s_add_u32 s4, s26, 0x3800000
	s_addc_u32 s5, s27, 0
	s_add_u32 s4, s4, s15
	s_addc_u32 s5, s5, 0
	v_add_u32_e32 v202, s99, v197
	v_add_u32_e32 v204, s99, v198
	s_movk_i32 s100, 0xc0
	ds_read2_b32 v[160:161], v202 offset0:0 offset1:8
	ds_read2_b32 v[162:163], v202 offset0:16 offset1:24
	s_cmp_lg_u32 s14, 0
	s_cbranch_scc1 .Lgv0_loop
	s_waitcnt vmcnt(0) lgkmcnt(0)
	s_add_u32 s4, s40, 0x1000
	s_addc_u32 s5, s41, 0
	global_load_dwordx4 v[64:67], v211, s[4:5] offset:0
	global_load_dwordx4 v[68:71], v211, s[4:5] offset:1024
	global_load_dwordx4 v[72:75], v211, s[4:5] offset:2048
	global_load_dwordx4 v[76:79], v211, s[4:5] offset:3072
	s_lshl_b32 s15, s101, 12
	s_add_u32 s8, s24, s15
	s_addc_u32 s9, s25, 0
	s_lshl_b32 s15, s101, 11
	s_add_u32 s10, s34, s15
	s_addc_u32 s11, s35, 0
	s_lshl_b32 s18, s92, 13
	v_lshlrev_b32_e32 v146, 3, v210
	v_mov_b32_e32 v147, 0x358637bd
	s_mov_b32 s19, 0x800000
	v_mov_b32_e32 v148, v146
	global_load_dwordx4 v[80:83], v211, s[8:9] offset:0
	global_load_dwordx4 v[84:87], v211, s[8:9] offset:1024
	global_load_dwordx4 v[88:91], v211, s[8:9] offset:2048
	global_load_dwordx4 v[92:95], v211, s[8:9] offset:3072
	s_add_u32 s8, s8, s16
	s_addc_u32 s9, s9, 0
	global_load_dwordx4 v[96:99], v211, s[8:9] offset:0
	global_load_dwordx4 v[100:103], v211, s[8:9] offset:1024
	global_load_dwordx4 v[104:107], v211, s[8:9] offset:2048
	global_load_dwordx4 v[108:111], v211, s[8:9] offset:3072
	s_add_u32 s8, s8, s16
	s_addc_u32 s9, s9, 0
	global_load_dwordx4 v[112:115], v211, s[8:9] offset:0
	global_load_dwordx4 v[116:119], v211, s[8:9] offset:1024
	global_load_dwordx4 v[120:123], v211, s[8:9] offset:2048
	global_load_dwordx4 v[124:127], v211, s[8:9] offset:3072
	s_add_u32 s8, s8, s16
	s_addc_u32 s9, s9, 0
	global_load_dwordx4 v[128:131], v211, s[8:9] offset:0
	global_load_dwordx4 v[132:135], v211, s[8:9] offset:1024
	global_load_dwordx4 v[136:139], v211, s[8:9] offset:2048
	global_load_dwordx4 v[140:143], v211, s[8:9] offset:3072
	s_add_u32 s8, s8, s16
	s_addc_u32 s9, s9, 0
	s_waitcnt vmcnt(0)
	v_mul_f32_e32 v144, v80, v80
	v_fmac_f32_e32 v144, v81, v81
	v_fmac_f32_e32 v144, v82, v82
	v_fmac_f32_e32 v144, v83, v83
	v_fmac_f32_e32 v144, v84, v84
	v_fmac_f32_e32 v144, v85, v85
	v_fmac_f32_e32 v144, v86, v86
	v_fmac_f32_e32 v144, v87, v87
	v_fmac_f32_e32 v144, v88, v88
	v_fmac_f32_e32 v144, v89, v89
	v_fmac_f32_e32 v144, v90, v90
	v_fmac_f32_e32 v144, v91, v91
	v_fmac_f32_e32 v144, v92, v92
	v_fmac_f32_e32 v144, v93, v93
	v_fmac_f32_e32 v144, v94, v94
	v_fmac_f32_e32 v144, v95, v95
	s_nop 1
	v_add_f32_dpp v144, v144, v144 quad_perm:[1,0,3,2] row_mask:0xf bank_mask:0xf
	s_nop 1
	v_add_f32_dpp v144, v144, v144 quad_perm:[2,3,0,1] row_mask:0xf bank_mask:0xf
	s_nop 1
	v_add_f32_dpp v144, v144, v144 row_half_mirror row_mask:0xf bank_mask:0xf
	s_nop 1
	v_add_f32_dpp v144, v144, v144 row_mirror row_mask:0xf bank_mask:0xf
	v_mov_b32_e32 v145, v144
	s_nop 1
	v_permlane16_swap_b32_e32 v144, v145
	v_add_f32_e32 v144, v144, v145
	v_mov_b32_e32 v145, v144
	s_nop 1
	v_permlane32_swap_b32_e32 v144, v145
	v_add_f32_e32 v144, v144, v145
	v_fmamk_f32 v144, v144, 0x3a800000, v147
	v_mul_f32_e32 v145, 0x4b800000, v144
	v_cmp_gt_f32_e32 vcc, s19, v144
	s_nop 1
	v_cndmask_b32_e32 v144, v144, v145, vcc
	v_rsq_f32_e32 v144, v144
	s_nop 0
	v_mul_f32_e32 v145, 0x45800000, v144
	v_cndmask_b32_e32 v144, v144, v145, vcc
	v_mul_f32_e32 v80, v80, v144
	v_mul_f32_e32 v80, v64, v80
	v_mul_f32_e32 v81, v81, v144
	v_mul_f32_e32 v81, v65, v81
	v_mul_f32_e32 v82, v82, v144
	v_mul_f32_e32 v82, v66, v82
	v_mul_f32_e32 v83, v83, v144
	v_mul_f32_e32 v83, v67, v83
	v_cvt_pk_bf16_f32 v80, v80, v81
	v_cvt_pk_bf16_f32 v81, v82, v83
	global_store_dwordx2 v148, v[80:81], s[10:11] offset:0
	v_mul_f32_e32 v84, v84, v144
	v_mul_f32_e32 v84, v68, v84
	v_mul_f32_e32 v85, v85, v144
	v_mul_f32_e32 v85, v69, v85
	v_mul_f32_e32 v86, v86, v144
	v_mul_f32_e32 v86, v70, v86
	v_mul_f32_e32 v87, v87, v144
	v_mul_f32_e32 v87, v71, v87
	v_cvt_pk_bf16_f32 v84, v84, v85
	v_cvt_pk_bf16_f32 v85, v86, v87
	global_store_dwordx2 v148, v[84:85], s[10:11] offset:512
	v_mul_f32_e32 v88, v88, v144
	v_mul_f32_e32 v88, v72, v88
	v_mul_f32_e32 v89, v89, v144
	v_mul_f32_e32 v89, v73, v89
	v_mul_f32_e32 v90, v90, v144
	v_mul_f32_e32 v90, v74, v90
	v_mul_f32_e32 v91, v91, v144
	v_mul_f32_e32 v91, v75, v91
	v_cvt_pk_bf16_f32 v88, v88, v89
	v_cvt_pk_bf16_f32 v89, v90, v91
	global_store_dwordx2 v148, v[88:89], s[10:11] offset:1024
	v_mul_f32_e32 v92, v92, v144
	v_mul_f32_e32 v92, v76, v92
	v_mul_f32_e32 v93, v93, v144
	v_mul_f32_e32 v93, v77, v93
	v_mul_f32_e32 v94, v94, v144
	v_mul_f32_e32 v94, v78, v94
	v_mul_f32_e32 v95, v95, v144
	v_mul_f32_e32 v95, v79, v95
	v_cvt_pk_bf16_f32 v92, v92, v93
	v_cvt_pk_bf16_f32 v93, v94, v95
	global_store_dwordx2 v148, v[92:93], s[10:11] offset:1536
	s_add_u32 s10, s10, s18
	s_addc_u32 s11, s11, 0
	v_mul_f32_e32 v144, v96, v96
	v_fmac_f32_e32 v144, v97, v97
	v_fmac_f32_e32 v144, v98, v98
	v_fmac_f32_e32 v144, v99, v99
	v_fmac_f32_e32 v144, v100, v100
	v_fmac_f32_e32 v144, v101, v101
	v_fmac_f32_e32 v144, v102, v102
	v_fmac_f32_e32 v144, v103, v103
	v_fmac_f32_e32 v144, v104, v104
	v_fmac_f32_e32 v144, v105, v105
	v_fmac_f32_e32 v144, v106, v106
	v_fmac_f32_e32 v144, v107, v107
	v_fmac_f32_e32 v144, v108, v108
	v_fmac_f32_e32 v144, v109, v109
	v_fmac_f32_e32 v144, v110, v110
	v_fmac_f32_e32 v144, v111, v111
	s_nop 1
	v_add_f32_dpp v144, v144, v144 quad_perm:[1,0,3,2] row_mask:0xf bank_mask:0xf
	s_nop 1
	v_add_f32_dpp v144, v144, v144 quad_perm:[2,3,0,1] row_mask:0xf bank_mask:0xf
	s_nop 1
	v_add_f32_dpp v144, v144, v144 row_half_mirror row_mask:0xf bank_mask:0xf
	s_nop 1
	v_add_f32_dpp v144, v144, v144 row_mirror row_mask:0xf bank_mask:0xf
	v_mov_b32_e32 v145, v144
	s_nop 1
	v_permlane16_swap_b32_e32 v144, v145
	v_add_f32_e32 v144, v144, v145
	v_mov_b32_e32 v145, v144
	s_nop 1
	v_permlane32_swap_b32_e32 v144, v145
	v_add_f32_e32 v144, v144, v145
	v_fmamk_f32 v144, v144, 0x3a800000, v147
	v_mul_f32_e32 v145, 0x4b800000, v144
	v_cmp_gt_f32_e32 vcc, s19, v144
	s_nop 1
	v_cndmask_b32_e32 v144, v144, v145, vcc
	v_rsq_f32_e32 v144, v144
	s_nop 0
	v_mul_f32_e32 v145, 0x45800000, v144
	v_cndmask_b32_e32 v144, v144, v145, vcc
	v_mul_f32_e32 v96, v96, v144
	v_mul_f32_e32 v96, v64, v96
	v_mul_f32_e32 v97, v97, v144
	v_mul_f32_e32 v97, v65, v97
	v_mul_f32_e32 v98, v98, v144
	v_mul_f32_e32 v98, v66, v98
	v_mul_f32_e32 v99, v99, v144
	v_mul_f32_e32 v99, v67, v99
	v_cvt_pk_bf16_f32 v96, v96, v97
	v_cvt_pk_bf16_f32 v97, v98, v99
	global_store_dwordx2 v148, v[96:97], s[10:11] offset:0
	v_mul_f32_e32 v100, v100, v144
	v_mul_f32_e32 v100, v68, v100
	v_mul_f32_e32 v101, v101, v144
	v_mul_f32_e32 v101, v69, v101
	v_mul_f32_e32 v102, v102, v144
	v_mul_f32_e32 v102, v70, v102
	v_mul_f32_e32 v103, v103, v144
	v_mul_f32_e32 v103, v71, v103
	v_cvt_pk_bf16_f32 v100, v100, v101
	v_cvt_pk_bf16_f32 v101, v102, v103
	global_store_dwordx2 v148, v[100:101], s[10:11] offset:512
	v_mul_f32_e32 v104, v104, v144
	v_mul_f32_e32 v104, v72, v104
	v_mul_f32_e32 v105, v105, v144
	v_mul_f32_e32 v105, v73, v105
	v_mul_f32_e32 v106, v106, v144
	v_mul_f32_e32 v106, v74, v106
	v_mul_f32_e32 v107, v107, v144
	v_mul_f32_e32 v107, v75, v107
	v_cvt_pk_bf16_f32 v104, v104, v105
	v_cvt_pk_bf16_f32 v105, v106, v107
	global_store_dwordx2 v148, v[104:105], s[10:11] offset:1024
	v_mul_f32_e32 v108, v108, v144
	v_mul_f32_e32 v108, v76, v108
	v_mul_f32_e32 v109, v109, v144
	v_mul_f32_e32 v109, v77, v109
	v_mul_f32_e32 v110, v110, v144
	v_mul_f32_e32 v110, v78, v110
	v_mul_f32_e32 v111, v111, v144
	v_mul_f32_e32 v111, v79, v111
	v_cvt_pk_bf16_f32 v108, v108, v109
	v_cvt_pk_bf16_f32 v109, v110, v111
	global_store_dwordx2 v148, v[108:109], s[10:11] offset:1536
	s_add_u32 s10, s10, s18
	s_addc_u32 s11, s11, 0
	v_mul_f32_e32 v144, v112, v112
	v_fmac_f32_e32 v144, v113, v113
	v_fmac_f32_e32 v144, v114, v114
	v_fmac_f32_e32 v144, v115, v115
	v_fmac_f32_e32 v144, v116, v116
	v_fmac_f32_e32 v144, v117, v117
	v_fmac_f32_e32 v144, v118, v118
	v_fmac_f32_e32 v144, v119, v119
	v_fmac_f32_e32 v144, v120, v120
	v_fmac_f32_e32 v144, v121, v121
	v_fmac_f32_e32 v144, v122, v122
	v_fmac_f32_e32 v144, v123, v123
	v_fmac_f32_e32 v144, v124, v124
	v_fmac_f32_e32 v144, v125, v125
	v_fmac_f32_e32 v144, v126, v126
	v_fmac_f32_e32 v144, v127, v127
	s_nop 1
	v_add_f32_dpp v144, v144, v144 quad_perm:[1,0,3,2] row_mask:0xf bank_mask:0xf
	s_nop 1
	v_add_f32_dpp v144, v144, v144 quad_perm:[2,3,0,1] row_mask:0xf bank_mask:0xf
	s_nop 1
	v_add_f32_dpp v144, v144, v144 row_half_mirror row_mask:0xf bank_mask:0xf
	s_nop 1
	v_add_f32_dpp v144, v144, v144 row_mirror row_mask:0xf bank_mask:0xf
	v_mov_b32_e32 v145, v144
	s_nop 1
	v_permlane16_swap_b32_e32 v144, v145
	v_add_f32_e32 v144, v144, v145
	v_mov_b32_e32 v145, v144
	s_nop 1
	v_permlane32_swap_b32_e32 v144, v145
	v_add_f32_e32 v144, v144, v145
	v_fmamk_f32 v144, v144, 0x3a800000, v147
	v_mul_f32_e32 v145, 0x4b800000, v144
	v_cmp_gt_f32_e32 vcc, s19, v144
	s_nop 1
	v_cndmask_b32_e32 v144, v144, v145, vcc
	v_rsq_f32_e32 v144, v144
	s_nop 0
	v_mul_f32_e32 v145, 0x45800000, v144
	v_cndmask_b32_e32 v144, v144, v145, vcc
	v_mul_f32_e32 v112, v112, v144
	v_mul_f32_e32 v112, v64, v112
	v_mul_f32_e32 v113, v113, v144
	v_mul_f32_e32 v113, v65, v113
	v_mul_f32_e32 v114, v114, v144
	v_mul_f32_e32 v114, v66, v114
	v_mul_f32_e32 v115, v115, v144
	v_mul_f32_e32 v115, v67, v115
	v_cvt_pk_bf16_f32 v112, v112, v113
	v_cvt_pk_bf16_f32 v113, v114, v115
	global_store_dwordx2 v148, v[112:113], s[10:11] offset:0
	v_mul_f32_e32 v116, v116, v144
	v_mul_f32_e32 v116, v68, v116
	v_mul_f32_e32 v117, v117, v144
	v_mul_f32_e32 v117, v69, v117
	v_mul_f32_e32 v118, v118, v144
	v_mul_f32_e32 v118, v70, v118
	v_mul_f32_e32 v119, v119, v144
	v_mul_f32_e32 v119, v71, v119
	v_cvt_pk_bf16_f32 v116, v116, v117
	v_cvt_pk_bf16_f32 v117, v118, v119
	global_store_dwordx2 v148, v[116:117], s[10:11] offset:512
	v_mul_f32_e32 v120, v120, v144
	v_mul_f32_e32 v120, v72, v120
	v_mul_f32_e32 v121, v121, v144
	v_mul_f32_e32 v121, v73, v121
	v_mul_f32_e32 v122, v122, v144
	v_mul_f32_e32 v122, v74, v122
	v_mul_f32_e32 v123, v123, v144
	v_mul_f32_e32 v123, v75, v123
	v_cvt_pk_bf16_f32 v120, v120, v121
	v_cvt_pk_bf16_f32 v121, v122, v123
	global_store_dwordx2 v148, v[120:121], s[10:11] offset:1024
	v_mul_f32_e32 v124, v124, v144
	v_mul_f32_e32 v124, v76, v124
	v_mul_f32_e32 v125, v125, v144
	v_mul_f32_e32 v125, v77, v125
	v_mul_f32_e32 v126, v126, v144
	v_mul_f32_e32 v126, v78, v126
	v_mul_f32_e32 v127, v127, v144
	v_mul_f32_e32 v127, v79, v127
	v_cvt_pk_bf16_f32 v124, v124, v125
	v_cvt_pk_bf16_f32 v125, v126, v127
	global_store_dwordx2 v148, v[124:125], s[10:11] offset:1536
	s_add_u32 s10, s10, s18
	s_addc_u32 s11, s11, 0
	v_mul_f32_e32 v144, v128, v128
	v_fmac_f32_e32 v144, v129, v129
	v_fmac_f32_e32 v144, v130, v130
	v_fmac_f32_e32 v144, v131, v131
	v_fmac_f32_e32 v144, v132, v132
	v_fmac_f32_e32 v144, v133, v133
	v_fmac_f32_e32 v144, v134, v134
	v_fmac_f32_e32 v144, v135, v135
	v_fmac_f32_e32 v144, v136, v136
	v_fmac_f32_e32 v144, v137, v137
	v_fmac_f32_e32 v144, v138, v138
	v_fmac_f32_e32 v144, v139, v139
	v_fmac_f32_e32 v144, v140, v140
	v_fmac_f32_e32 v144, v141, v141
	v_fmac_f32_e32 v144, v142, v142
	v_fmac_f32_e32 v144, v143, v143
	s_nop 1
	v_add_f32_dpp v144, v144, v144 quad_perm:[1,0,3,2] row_mask:0xf bank_mask:0xf
	s_nop 1
	v_add_f32_dpp v144, v144, v144 quad_perm:[2,3,0,1] row_mask:0xf bank_mask:0xf
	s_nop 1
	v_add_f32_dpp v144, v144, v144 row_half_mirror row_mask:0xf bank_mask:0xf
	s_nop 1
	v_add_f32_dpp v144, v144, v144 row_mirror row_mask:0xf bank_mask:0xf
	v_mov_b32_e32 v145, v144
	s_nop 1
	v_permlane16_swap_b32_e32 v144, v145
	v_add_f32_e32 v144, v144, v145
	v_mov_b32_e32 v145, v144
	s_nop 1
	v_permlane32_swap_b32_e32 v144, v145
	v_add_f32_e32 v144, v144, v145
	v_fmamk_f32 v144, v144, 0x3a800000, v147
	v_mul_f32_e32 v145, 0x4b800000, v144
	v_cmp_gt_f32_e32 vcc, s19, v144
	s_nop 1
	v_cndmask_b32_e32 v144, v144, v145, vcc
	v_rsq_f32_e32 v144, v144
	s_nop 0
	v_mul_f32_e32 v145, 0x45800000, v144
	v_cndmask_b32_e32 v144, v144, v145, vcc
	v_mul_f32_e32 v128, v128, v144
	v_mul_f32_e32 v128, v64, v128
	v_mul_f32_e32 v129, v129, v144
	v_mul_f32_e32 v129, v65, v129
	v_mul_f32_e32 v130, v130, v144
	v_mul_f32_e32 v130, v66, v130
	v_mul_f32_e32 v131, v131, v144
	v_mul_f32_e32 v131, v67, v131
	v_cvt_pk_bf16_f32 v128, v128, v129
	v_cvt_pk_bf16_f32 v129, v130, v131
	global_store_dwordx2 v148, v[128:129], s[10:11] offset:0
	v_mul_f32_e32 v132, v132, v144
	v_mul_f32_e32 v132, v68, v132
	v_mul_f32_e32 v133, v133, v144
	v_mul_f32_e32 v133, v69, v133
	v_mul_f32_e32 v134, v134, v144
	v_mul_f32_e32 v134, v70, v134
	v_mul_f32_e32 v135, v135, v144
	v_mul_f32_e32 v135, v71, v135
	v_cvt_pk_bf16_f32 v132, v132, v133
	v_cvt_pk_bf16_f32 v133, v134, v135
	global_store_dwordx2 v148, v[132:133], s[10:11] offset:512
	v_mul_f32_e32 v136, v136, v144
	v_mul_f32_e32 v136, v72, v136
	v_mul_f32_e32 v137, v137, v144
	v_mul_f32_e32 v137, v73, v137
	v_mul_f32_e32 v138, v138, v144
	v_mul_f32_e32 v138, v74, v138
	v_mul_f32_e32 v139, v139, v144
	v_mul_f32_e32 v139, v75, v139
	v_cvt_pk_bf16_f32 v136, v136, v137
	v_cvt_pk_bf16_f32 v137, v138, v139
	global_store_dwordx2 v148, v[136:137], s[10:11] offset:1024
	v_mul_f32_e32 v140, v140, v144
	v_mul_f32_e32 v140, v76, v140
	v_mul_f32_e32 v141, v141, v144
	v_mul_f32_e32 v141, v77, v141
	v_mul_f32_e32 v142, v142, v144
	v_mul_f32_e32 v142, v78, v142
	v_mul_f32_e32 v143, v143, v144
	v_mul_f32_e32 v143, v79, v143
	v_cvt_pk_bf16_f32 v140, v140, v141
	v_cvt_pk_bf16_f32 v141, v142, v143
	global_store_dwordx2 v148, v[140:141], s[10:11] offset:1536
	s_add_u32 s10, s10, s18
	s_addc_u32 s11, s11, 0
	global_load_dwordx4 v[80:83], v211, s[8:9] offset:0
	global_load_dwordx4 v[84:87], v211, s[8:9] offset:1024
	global_load_dwordx4 v[88:91], v211, s[8:9] offset:2048
	global_load_dwordx4 v[92:95], v211, s[8:9] offset:3072
	s_add_u32 s8, s8, s16
	s_addc_u32 s9, s9, 0
	global_load_dwordx4 v[96:99], v211, s[8:9] offset:0
	global_load_dwordx4 v[100:103], v211, s[8:9] offset:1024
	global_load_dwordx4 v[104:107], v211, s[8:9] offset:2048
	global_load_dwordx4 v[108:111], v211, s[8:9] offset:3072
	s_add_u32 s8, s8, s16
	s_addc_u32 s9, s9, 0
	global_load_dwordx4 v[112:115], v211, s[8:9] offset:0
	global_load_dwordx4 v[116:119], v211, s[8:9] offset:1024
	global_load_dwordx4 v[120:123], v211, s[8:9] offset:2048
	global_load_dwordx4 v[124:127], v211, s[8:9] offset:3072
	s_add_u32 s8, s8, s16
	s_addc_u32 s9, s9, 0
	global_load_dwordx4 v[128:131], v211, s[8:9] offset:0
	global_load_dwordx4 v[132:135], v211, s[8:9] offset:1024
	global_load_dwordx4 v[136:139], v211, s[8:9] offset:2048
	global_load_dwordx4 v[140:143], v211, s[8:9] offset:3072
	s_add_u32 s8, s8, s16
	s_addc_u32 s9, s9, 0
	s_waitcnt vmcnt(0)
	v_mul_f32_e32 v144, v80, v80
	v_fmac_f32_e32 v144, v81, v81
	v_fmac_f32_e32 v144, v82, v82
	v_fmac_f32_e32 v144, v83, v83
	v_fmac_f32_e32 v144, v84, v84
	v_fmac_f32_e32 v144, v85, v85
	v_fmac_f32_e32 v144, v86, v86
	v_fmac_f32_e32 v144, v87, v87
	v_fmac_f32_e32 v144, v88, v88
	v_fmac_f32_e32 v144, v89, v89
	v_fmac_f32_e32 v144, v90, v90
	v_fmac_f32_e32 v144, v91, v91
	v_fmac_f32_e32 v144, v92, v92
	v_fmac_f32_e32 v144, v93, v93
	v_fmac_f32_e32 v144, v94, v94
	v_fmac_f32_e32 v144, v95, v95
	s_nop 1
	v_add_f32_dpp v144, v144, v144 quad_perm:[1,0,3,2] row_mask:0xf bank_mask:0xf
	s_nop 1
	v_add_f32_dpp v144, v144, v144 quad_perm:[2,3,0,1] row_mask:0xf bank_mask:0xf
	s_nop 1
	v_add_f32_dpp v144, v144, v144 row_half_mirror row_mask:0xf bank_mask:0xf
	s_nop 1
	v_add_f32_dpp v144, v144, v144 row_mirror row_mask:0xf bank_mask:0xf
	v_mov_b32_e32 v145, v144
	s_nop 1
	v_permlane16_swap_b32_e32 v144, v145
	v_add_f32_e32 v144, v144, v145
	v_mov_b32_e32 v145, v144
	s_nop 1
	v_permlane32_swap_b32_e32 v144, v145
	v_add_f32_e32 v144, v144, v145
	v_fmamk_f32 v144, v144, 0x3a800000, v147
	v_mul_f32_e32 v145, 0x4b800000, v144
	v_cmp_gt_f32_e32 vcc, s19, v144
	s_nop 1
	v_cndmask_b32_e32 v144, v144, v145, vcc
	v_rsq_f32_e32 v144, v144
	s_nop 0
	v_mul_f32_e32 v145, 0x45800000, v144
	v_cndmask_b32_e32 v144, v144, v145, vcc
	v_mul_f32_e32 v80, v80, v144
	v_mul_f32_e32 v80, v64, v80
	v_mul_f32_e32 v81, v81, v144
	v_mul_f32_e32 v81, v65, v81
	v_mul_f32_e32 v82, v82, v144
	v_mul_f32_e32 v82, v66, v82
	v_mul_f32_e32 v83, v83, v144
	v_mul_f32_e32 v83, v67, v83
	v_cvt_pk_bf16_f32 v80, v80, v81
	v_cvt_pk_bf16_f32 v81, v82, v83
	global_store_dwordx2 v148, v[80:81], s[10:11] offset:0
	v_mul_f32_e32 v84, v84, v144
	v_mul_f32_e32 v84, v68, v84
	v_mul_f32_e32 v85, v85, v144
	v_mul_f32_e32 v85, v69, v85
	v_mul_f32_e32 v86, v86, v144
	v_mul_f32_e32 v86, v70, v86
	v_mul_f32_e32 v87, v87, v144
	v_mul_f32_e32 v87, v71, v87
	v_cvt_pk_bf16_f32 v84, v84, v85
	v_cvt_pk_bf16_f32 v85, v86, v87
	global_store_dwordx2 v148, v[84:85], s[10:11] offset:512
	v_mul_f32_e32 v88, v88, v144
	v_mul_f32_e32 v88, v72, v88
	v_mul_f32_e32 v89, v89, v144
	v_mul_f32_e32 v89, v73, v89
	v_mul_f32_e32 v90, v90, v144
	v_mul_f32_e32 v90, v74, v90
	v_mul_f32_e32 v91, v91, v144
	v_mul_f32_e32 v91, v75, v91
	v_cvt_pk_bf16_f32 v88, v88, v89
	v_cvt_pk_bf16_f32 v89, v90, v91
	global_store_dwordx2 v148, v[88:89], s[10:11] offset:1024
	v_mul_f32_e32 v92, v92, v144
	v_mul_f32_e32 v92, v76, v92
	v_mul_f32_e32 v93, v93, v144
	v_mul_f32_e32 v93, v77, v93
	v_mul_f32_e32 v94, v94, v144
	v_mul_f32_e32 v94, v78, v94
	v_mul_f32_e32 v95, v95, v144
	v_mul_f32_e32 v95, v79, v95
	v_cvt_pk_bf16_f32 v92, v92, v93
	v_cvt_pk_bf16_f32 v93, v94, v95
	global_store_dwordx2 v148, v[92:93], s[10:11] offset:1536
	s_add_u32 s10, s10, s18
	s_addc_u32 s11, s11, 0
	v_mul_f32_e32 v144, v96, v96
	v_fmac_f32_e32 v144, v97, v97
	v_fmac_f32_e32 v144, v98, v98
	v_fmac_f32_e32 v144, v99, v99
	v_fmac_f32_e32 v144, v100, v100
	v_fmac_f32_e32 v144, v101, v101
	v_fmac_f32_e32 v144, v102, v102
	v_fmac_f32_e32 v144, v103, v103
	v_fmac_f32_e32 v144, v104, v104
	v_fmac_f32_e32 v144, v105, v105
	v_fmac_f32_e32 v144, v106, v106
	v_fmac_f32_e32 v144, v107, v107
	v_fmac_f32_e32 v144, v108, v108
	v_fmac_f32_e32 v144, v109, v109
	v_fmac_f32_e32 v144, v110, v110
	v_fmac_f32_e32 v144, v111, v111
	s_nop 1
	v_add_f32_dpp v144, v144, v144 quad_perm:[1,0,3,2] row_mask:0xf bank_mask:0xf
	s_nop 1
	v_add_f32_dpp v144, v144, v144 quad_perm:[2,3,0,1] row_mask:0xf bank_mask:0xf
	s_nop 1
	v_add_f32_dpp v144, v144, v144 row_half_mirror row_mask:0xf bank_mask:0xf
	s_nop 1
	v_add_f32_dpp v144, v144, v144 row_mirror row_mask:0xf bank_mask:0xf
	v_mov_b32_e32 v145, v144
	s_nop 1
	v_permlane16_swap_b32_e32 v144, v145
	v_add_f32_e32 v144, v144, v145
	v_mov_b32_e32 v145, v144
	s_nop 1
	v_permlane32_swap_b32_e32 v144, v145
	v_add_f32_e32 v144, v144, v145
	v_fmamk_f32 v144, v144, 0x3a800000, v147
	v_mul_f32_e32 v145, 0x4b800000, v144
	v_cmp_gt_f32_e32 vcc, s19, v144
	s_nop 1
	v_cndmask_b32_e32 v144, v144, v145, vcc
	v_rsq_f32_e32 v144, v144
	s_nop 0
	v_mul_f32_e32 v145, 0x45800000, v144
	v_cndmask_b32_e32 v144, v144, v145, vcc
	v_mul_f32_e32 v96, v96, v144
	v_mul_f32_e32 v96, v64, v96
	v_mul_f32_e32 v97, v97, v144
	v_mul_f32_e32 v97, v65, v97
	v_mul_f32_e32 v98, v98, v144
	v_mul_f32_e32 v98, v66, v98
	v_mul_f32_e32 v99, v99, v144
	v_mul_f32_e32 v99, v67, v99
	v_cvt_pk_bf16_f32 v96, v96, v97
	v_cvt_pk_bf16_f32 v97, v98, v99
	global_store_dwordx2 v148, v[96:97], s[10:11] offset:0
	v_mul_f32_e32 v100, v100, v144
	v_mul_f32_e32 v100, v68, v100
	v_mul_f32_e32 v101, v101, v144
	v_mul_f32_e32 v101, v69, v101
	v_mul_f32_e32 v102, v102, v144
	v_mul_f32_e32 v102, v70, v102
	v_mul_f32_e32 v103, v103, v144
	v_mul_f32_e32 v103, v71, v103
	v_cvt_pk_bf16_f32 v100, v100, v101
	v_cvt_pk_bf16_f32 v101, v102, v103
	global_store_dwordx2 v148, v[100:101], s[10:11] offset:512
	v_mul_f32_e32 v104, v104, v144
	v_mul_f32_e32 v104, v72, v104
	v_mul_f32_e32 v105, v105, v144
	v_mul_f32_e32 v105, v73, v105
	v_mul_f32_e32 v106, v106, v144
	v_mul_f32_e32 v106, v74, v106
	v_mul_f32_e32 v107, v107, v144
	v_mul_f32_e32 v107, v75, v107
	v_cvt_pk_bf16_f32 v104, v104, v105
	v_cvt_pk_bf16_f32 v105, v106, v107
	global_store_dwordx2 v148, v[104:105], s[10:11] offset:1024
	v_mul_f32_e32 v108, v108, v144
	v_mul_f32_e32 v108, v76, v108
	v_mul_f32_e32 v109, v109, v144
	v_mul_f32_e32 v109, v77, v109
	v_mul_f32_e32 v110, v110, v144
	v_mul_f32_e32 v110, v78, v110
	v_mul_f32_e32 v111, v111, v144
	v_mul_f32_e32 v111, v79, v111
	v_cvt_pk_bf16_f32 v108, v108, v109
	v_cvt_pk_bf16_f32 v109, v110, v111
	global_store_dwordx2 v148, v[108:109], s[10:11] offset:1536
	s_add_u32 s10, s10, s18
	s_addc_u32 s11, s11, 0
	v_mul_f32_e32 v144, v112, v112
	v_fmac_f32_e32 v144, v113, v113
	v_fmac_f32_e32 v144, v114, v114
	v_fmac_f32_e32 v144, v115, v115
	v_fmac_f32_e32 v144, v116, v116
	v_fmac_f32_e32 v144, v117, v117
	v_fmac_f32_e32 v144, v118, v118
	v_fmac_f32_e32 v144, v119, v119
	v_fmac_f32_e32 v144, v120, v120
	v_fmac_f32_e32 v144, v121, v121
	v_fmac_f32_e32 v144, v122, v122
	v_fmac_f32_e32 v144, v123, v123
	v_fmac_f32_e32 v144, v124, v124
	v_fmac_f32_e32 v144, v125, v125
	v_fmac_f32_e32 v144, v126, v126
	v_fmac_f32_e32 v144, v127, v127
	s_nop 1
	v_add_f32_dpp v144, v144, v144 quad_perm:[1,0,3,2] row_mask:0xf bank_mask:0xf
	s_nop 1
	v_add_f32_dpp v144, v144, v144 quad_perm:[2,3,0,1] row_mask:0xf bank_mask:0xf
	s_nop 1
	v_add_f32_dpp v144, v144, v144 row_half_mirror row_mask:0xf bank_mask:0xf
	s_nop 1
	v_add_f32_dpp v144, v144, v144 row_mirror row_mask:0xf bank_mask:0xf
	v_mov_b32_e32 v145, v144
	s_nop 1
	v_permlane16_swap_b32_e32 v144, v145
	v_add_f32_e32 v144, v144, v145
	v_mov_b32_e32 v145, v144
	s_nop 1
	v_permlane32_swap_b32_e32 v144, v145
	v_add_f32_e32 v144, v144, v145
	v_fmamk_f32 v144, v144, 0x3a800000, v147
	v_mul_f32_e32 v145, 0x4b800000, v144
	v_cmp_gt_f32_e32 vcc, s19, v144
	s_nop 1
	v_cndmask_b32_e32 v144, v144, v145, vcc
	v_rsq_f32_e32 v144, v144
	s_nop 0
	v_mul_f32_e32 v145, 0x45800000, v144
	v_cndmask_b32_e32 v144, v144, v145, vcc
	v_mul_f32_e32 v112, v112, v144
	v_mul_f32_e32 v112, v64, v112
	v_mul_f32_e32 v113, v113, v144
	v_mul_f32_e32 v113, v65, v113
	v_mul_f32_e32 v114, v114, v144
	v_mul_f32_e32 v114, v66, v114
	v_mul_f32_e32 v115, v115, v144
	v_mul_f32_e32 v115, v67, v115
	v_cvt_pk_bf16_f32 v112, v112, v113
	v_cvt_pk_bf16_f32 v113, v114, v115
	global_store_dwordx2 v148, v[112:113], s[10:11] offset:0
	v_mul_f32_e32 v116, v116, v144
	v_mul_f32_e32 v116, v68, v116
	v_mul_f32_e32 v117, v117, v144
	v_mul_f32_e32 v117, v69, v117
	v_mul_f32_e32 v118, v118, v144
	v_mul_f32_e32 v118, v70, v118
	v_mul_f32_e32 v119, v119, v144
	v_mul_f32_e32 v119, v71, v119
	v_cvt_pk_bf16_f32 v116, v116, v117
	v_cvt_pk_bf16_f32 v117, v118, v119
	global_store_dwordx2 v148, v[116:117], s[10:11] offset:512
	v_mul_f32_e32 v120, v120, v144
	v_mul_f32_e32 v120, v72, v120
	v_mul_f32_e32 v121, v121, v144
	v_mul_f32_e32 v121, v73, v121
	v_mul_f32_e32 v122, v122, v144
	v_mul_f32_e32 v122, v74, v122
	v_mul_f32_e32 v123, v123, v144
	v_mul_f32_e32 v123, v75, v123
	v_cvt_pk_bf16_f32 v120, v120, v121
	v_cvt_pk_bf16_f32 v121, v122, v123
	global_store_dwordx2 v148, v[120:121], s[10:11] offset:1024
	v_mul_f32_e32 v124, v124, v144
	v_mul_f32_e32 v124, v76, v124
	v_mul_f32_e32 v125, v125, v144
	v_mul_f32_e32 v125, v77, v125
	v_mul_f32_e32 v126, v126, v144
	v_mul_f32_e32 v126, v78, v126
	v_mul_f32_e32 v127, v127, v144
	v_mul_f32_e32 v127, v79, v127
	v_cvt_pk_bf16_f32 v124, v124, v125
	v_cvt_pk_bf16_f32 v125, v126, v127
	global_store_dwordx2 v148, v[124:125], s[10:11] offset:1536
	s_add_u32 s10, s10, s18
	s_addc_u32 s11, s11, 0
	v_mul_f32_e32 v144, v128, v128
	v_fmac_f32_e32 v144, v129, v129
	v_fmac_f32_e32 v144, v130, v130
	v_fmac_f32_e32 v144, v131, v131
	v_fmac_f32_e32 v144, v132, v132
	v_fmac_f32_e32 v144, v133, v133
	v_fmac_f32_e32 v144, v134, v134
	v_fmac_f32_e32 v144, v135, v135
	v_fmac_f32_e32 v144, v136, v136
	v_fmac_f32_e32 v144, v137, v137
	v_fmac_f32_e32 v144, v138, v138
	v_fmac_f32_e32 v144, v139, v139
	v_fmac_f32_e32 v144, v140, v140
	v_fmac_f32_e32 v144, v141, v141
	v_fmac_f32_e32 v144, v142, v142
	v_fmac_f32_e32 v144, v143, v143
	s_nop 1
	v_add_f32_dpp v144, v144, v144 quad_perm:[1,0,3,2] row_mask:0xf bank_mask:0xf
	s_nop 1
	v_add_f32_dpp v144, v144, v144 quad_perm:[2,3,0,1] row_mask:0xf bank_mask:0xf
	s_nop 1
	v_add_f32_dpp v144, v144, v144 row_half_mirror row_mask:0xf bank_mask:0xf
	s_nop 1
	v_add_f32_dpp v144, v144, v144 row_mirror row_mask:0xf bank_mask:0xf
	v_mov_b32_e32 v145, v144
	s_nop 1
	v_permlane16_swap_b32_e32 v144, v145
	v_add_f32_e32 v144, v144, v145
	v_mov_b32_e32 v145, v144
	s_nop 1
	v_permlane32_swap_b32_e32 v144, v145
	v_add_f32_e32 v144, v144, v145
	v_fmamk_f32 v144, v144, 0x3a800000, v147
	v_mul_f32_e32 v145, 0x4b800000, v144
	v_cmp_gt_f32_e32 vcc, s19, v144
	s_nop 1
	v_cndmask_b32_e32 v144, v144, v145, vcc
	v_rsq_f32_e32 v144, v144
	s_nop 0
	v_mul_f32_e32 v145, 0x45800000, v144
	v_cndmask_b32_e32 v144, v144, v145, vcc
	v_mul_f32_e32 v128, v128, v144
	v_mul_f32_e32 v128, v64, v128
	v_mul_f32_e32 v129, v129, v144
	v_mul_f32_e32 v129, v65, v129
	v_mul_f32_e32 v130, v130, v144
	v_mul_f32_e32 v130, v66, v130
	v_mul_f32_e32 v131, v131, v144
	v_mul_f32_e32 v131, v67, v131
	v_cvt_pk_bf16_f32 v128, v128, v129
	v_cvt_pk_bf16_f32 v129, v130, v131
	global_store_dwordx2 v148, v[128:129], s[10:11] offset:0
	v_mul_f32_e32 v132, v132, v144
	v_mul_f32_e32 v132, v68, v132
	v_mul_f32_e32 v133, v133, v144
	v_mul_f32_e32 v133, v69, v133
	v_mul_f32_e32 v134, v134, v144
	v_mul_f32_e32 v134, v70, v134
	v_mul_f32_e32 v135, v135, v144
	v_mul_f32_e32 v135, v71, v135
	v_cvt_pk_bf16_f32 v132, v132, v133
	v_cvt_pk_bf16_f32 v133, v134, v135
	global_store_dwordx2 v148, v[132:133], s[10:11] offset:512
	v_mul_f32_e32 v136, v136, v144
	v_mul_f32_e32 v136, v72, v136
	v_mul_f32_e32 v137, v137, v144
	v_mul_f32_e32 v137, v73, v137
	v_mul_f32_e32 v138, v138, v144
	v_mul_f32_e32 v138, v74, v138
	v_mul_f32_e32 v139, v139, v144
	v_mul_f32_e32 v139, v75, v139
	v_cvt_pk_bf16_f32 v136, v136, v137
	v_cvt_pk_bf16_f32 v137, v138, v139
	global_store_dwordx2 v148, v[136:137], s[10:11] offset:1024
	v_mul_f32_e32 v140, v140, v144
	v_mul_f32_e32 v140, v76, v140
	v_mul_f32_e32 v141, v141, v144
	v_mul_f32_e32 v141, v77, v141
	v_mul_f32_e32 v142, v142, v144
	v_mul_f32_e32 v142, v78, v142
	v_mul_f32_e32 v143, v143, v144
	v_mul_f32_e32 v143, v79, v143
	v_cvt_pk_bf16_f32 v140, v140, v141
	v_cvt_pk_bf16_f32 v141, v142, v143
	global_store_dwordx2 v148, v[140:141], s[10:11] offset:1536
	s_add_u32 s10, s10, s18
	s_addc_u32 s11, s11, 0
	global_load_dwordx4 v[80:83], v211, s[8:9] offset:0
	global_load_dwordx4 v[84:87], v211, s[8:9] offset:1024
	global_load_dwordx4 v[88:91], v211, s[8:9] offset:2048
	global_load_dwordx4 v[92:95], v211, s[8:9] offset:3072
	s_add_u32 s8, s8, s16
	s_addc_u32 s9, s9, 0
	global_load_dwordx4 v[96:99], v211, s[8:9] offset:0
	global_load_dwordx4 v[100:103], v211, s[8:9] offset:1024
	global_load_dwordx4 v[104:107], v211, s[8:9] offset:2048
	global_load_dwordx4 v[108:111], v211, s[8:9] offset:3072
	s_add_u32 s8, s8, s16
	s_addc_u32 s9, s9, 0
	global_load_dwordx4 v[112:115], v211, s[8:9] offset:0
	global_load_dwordx4 v[116:119], v211, s[8:9] offset:1024
	global_load_dwordx4 v[120:123], v211, s[8:9] offset:2048
	global_load_dwordx4 v[124:127], v211, s[8:9] offset:3072
	s_add_u32 s8, s8, s16
	s_addc_u32 s9, s9, 0
	global_load_dwordx4 v[128:131], v211, s[8:9] offset:0
	global_load_dwordx4 v[132:135], v211, s[8:9] offset:1024
	global_load_dwordx4 v[136:139], v211, s[8:9] offset:2048
	global_load_dwordx4 v[140:143], v211, s[8:9] offset:3072
	s_add_u32 s8, s8, s16
	s_addc_u32 s9, s9, 0
	s_waitcnt vmcnt(0)
	v_mul_f32_e32 v144, v80, v80
	v_fmac_f32_e32 v144, v81, v81
	v_fmac_f32_e32 v144, v82, v82
	v_fmac_f32_e32 v144, v83, v83
	v_fmac_f32_e32 v144, v84, v84
	v_fmac_f32_e32 v144, v85, v85
	v_fmac_f32_e32 v144, v86, v86
	v_fmac_f32_e32 v144, v87, v87
	v_fmac_f32_e32 v144, v88, v88
	v_fmac_f32_e32 v144, v89, v89
	v_fmac_f32_e32 v144, v90, v90
	v_fmac_f32_e32 v144, v91, v91
	v_fmac_f32_e32 v144, v92, v92
	v_fmac_f32_e32 v144, v93, v93
	v_fmac_f32_e32 v144, v94, v94
	v_fmac_f32_e32 v144, v95, v95
	s_nop 1
	v_add_f32_dpp v144, v144, v144 quad_perm:[1,0,3,2] row_mask:0xf bank_mask:0xf
	s_nop 1
	v_add_f32_dpp v144, v144, v144 quad_perm:[2,3,0,1] row_mask:0xf bank_mask:0xf
	s_nop 1
	v_add_f32_dpp v144, v144, v144 row_half_mirror row_mask:0xf bank_mask:0xf
	s_nop 1
	v_add_f32_dpp v144, v144, v144 row_mirror row_mask:0xf bank_mask:0xf
	v_mov_b32_e32 v145, v144
	s_nop 1
	v_permlane16_swap_b32_e32 v144, v145
	v_add_f32_e32 v144, v144, v145
	v_mov_b32_e32 v145, v144
	s_nop 1
	v_permlane32_swap_b32_e32 v144, v145
	v_add_f32_e32 v144, v144, v145
	v_fmamk_f32 v144, v144, 0x3a800000, v147
	v_mul_f32_e32 v145, 0x4b800000, v144
	v_cmp_gt_f32_e32 vcc, s19, v144
	s_nop 1
	v_cndmask_b32_e32 v144, v144, v145, vcc
	v_rsq_f32_e32 v144, v144
	s_nop 0
	v_mul_f32_e32 v145, 0x45800000, v144
	v_cndmask_b32_e32 v144, v144, v145, vcc
	v_mul_f32_e32 v80, v80, v144
	v_mul_f32_e32 v80, v64, v80
	v_mul_f32_e32 v81, v81, v144
	v_mul_f32_e32 v81, v65, v81
	v_mul_f32_e32 v82, v82, v144
	v_mul_f32_e32 v82, v66, v82
	v_mul_f32_e32 v83, v83, v144
	v_mul_f32_e32 v83, v67, v83
	v_cvt_pk_bf16_f32 v80, v80, v81
	v_cvt_pk_bf16_f32 v81, v82, v83
	global_store_dwordx2 v148, v[80:81], s[10:11] offset:0
	v_mul_f32_e32 v84, v84, v144
	v_mul_f32_e32 v84, v68, v84
	v_mul_f32_e32 v85, v85, v144
	v_mul_f32_e32 v85, v69, v85
	v_mul_f32_e32 v86, v86, v144
	v_mul_f32_e32 v86, v70, v86
	v_mul_f32_e32 v87, v87, v144
	v_mul_f32_e32 v87, v71, v87
	v_cvt_pk_bf16_f32 v84, v84, v85
	v_cvt_pk_bf16_f32 v85, v86, v87
	global_store_dwordx2 v148, v[84:85], s[10:11] offset:512
	v_mul_f32_e32 v88, v88, v144
	v_mul_f32_e32 v88, v72, v88
	v_mul_f32_e32 v89, v89, v144
	v_mul_f32_e32 v89, v73, v89
	v_mul_f32_e32 v90, v90, v144
	v_mul_f32_e32 v90, v74, v90
	v_mul_f32_e32 v91, v91, v144
	v_mul_f32_e32 v91, v75, v91
	v_cvt_pk_bf16_f32 v88, v88, v89
	v_cvt_pk_bf16_f32 v89, v90, v91
	global_store_dwordx2 v148, v[88:89], s[10:11] offset:1024
	v_mul_f32_e32 v92, v92, v144
	v_mul_f32_e32 v92, v76, v92
	v_mul_f32_e32 v93, v93, v144
	v_mul_f32_e32 v93, v77, v93
	v_mul_f32_e32 v94, v94, v144
	v_mul_f32_e32 v94, v78, v94
	v_mul_f32_e32 v95, v95, v144
	v_mul_f32_e32 v95, v79, v95
	v_cvt_pk_bf16_f32 v92, v92, v93
	v_cvt_pk_bf16_f32 v93, v94, v95
	global_store_dwordx2 v148, v[92:93], s[10:11] offset:1536
	s_add_u32 s10, s10, s18
	s_addc_u32 s11, s11, 0
	v_mul_f32_e32 v144, v96, v96
	v_fmac_f32_e32 v144, v97, v97
	v_fmac_f32_e32 v144, v98, v98
	v_fmac_f32_e32 v144, v99, v99
	v_fmac_f32_e32 v144, v100, v100
	v_fmac_f32_e32 v144, v101, v101
	v_fmac_f32_e32 v144, v102, v102
	v_fmac_f32_e32 v144, v103, v103
	v_fmac_f32_e32 v144, v104, v104
	v_fmac_f32_e32 v144, v105, v105
	v_fmac_f32_e32 v144, v106, v106
	v_fmac_f32_e32 v144, v107, v107
	v_fmac_f32_e32 v144, v108, v108
	v_fmac_f32_e32 v144, v109, v109
	v_fmac_f32_e32 v144, v110, v110
	v_fmac_f32_e32 v144, v111, v111
	s_nop 1
	v_add_f32_dpp v144, v144, v144 quad_perm:[1,0,3,2] row_mask:0xf bank_mask:0xf
	s_nop 1
	v_add_f32_dpp v144, v144, v144 quad_perm:[2,3,0,1] row_mask:0xf bank_mask:0xf
	s_nop 1
	v_add_f32_dpp v144, v144, v144 row_half_mirror row_mask:0xf bank_mask:0xf
	s_nop 1
	v_add_f32_dpp v144, v144, v144 row_mirror row_mask:0xf bank_mask:0xf
	v_mov_b32_e32 v145, v144
	s_nop 1
	v_permlane16_swap_b32_e32 v144, v145
	v_add_f32_e32 v144, v144, v145
	v_mov_b32_e32 v145, v144
	s_nop 1
	v_permlane32_swap_b32_e32 v144, v145
	v_add_f32_e32 v144, v144, v145
	v_fmamk_f32 v144, v144, 0x3a800000, v147
	v_mul_f32_e32 v145, 0x4b800000, v144
	v_cmp_gt_f32_e32 vcc, s19, v144
	s_nop 1
	v_cndmask_b32_e32 v144, v144, v145, vcc
	v_rsq_f32_e32 v144, v144
	s_nop 0
	v_mul_f32_e32 v145, 0x45800000, v144
	v_cndmask_b32_e32 v144, v144, v145, vcc
	v_mul_f32_e32 v96, v96, v144
	v_mul_f32_e32 v96, v64, v96
	v_mul_f32_e32 v97, v97, v144
	v_mul_f32_e32 v97, v65, v97
	v_mul_f32_e32 v98, v98, v144
	v_mul_f32_e32 v98, v66, v98
	v_mul_f32_e32 v99, v99, v144
	v_mul_f32_e32 v99, v67, v99
	v_cvt_pk_bf16_f32 v96, v96, v97
	v_cvt_pk_bf16_f32 v97, v98, v99
	global_store_dwordx2 v148, v[96:97], s[10:11] offset:0
	v_mul_f32_e32 v100, v100, v144
	v_mul_f32_e32 v100, v68, v100
	v_mul_f32_e32 v101, v101, v144
	v_mul_f32_e32 v101, v69, v101
	v_mul_f32_e32 v102, v102, v144
	v_mul_f32_e32 v102, v70, v102
	v_mul_f32_e32 v103, v103, v144
	v_mul_f32_e32 v103, v71, v103
	v_cvt_pk_bf16_f32 v100, v100, v101
	v_cvt_pk_bf16_f32 v101, v102, v103
	global_store_dwordx2 v148, v[100:101], s[10:11] offset:512
	v_mul_f32_e32 v104, v104, v144
	v_mul_f32_e32 v104, v72, v104
	v_mul_f32_e32 v105, v105, v144
	v_mul_f32_e32 v105, v73, v105
	v_mul_f32_e32 v106, v106, v144
	v_mul_f32_e32 v106, v74, v106
	v_mul_f32_e32 v107, v107, v144
	v_mul_f32_e32 v107, v75, v107
	v_cvt_pk_bf16_f32 v104, v104, v105
	v_cvt_pk_bf16_f32 v105, v106, v107
	global_store_dwordx2 v148, v[104:105], s[10:11] offset:1024
	v_mul_f32_e32 v108, v108, v144
	v_mul_f32_e32 v108, v76, v108
	v_mul_f32_e32 v109, v109, v144
	v_mul_f32_e32 v109, v77, v109
	v_mul_f32_e32 v110, v110, v144
	v_mul_f32_e32 v110, v78, v110
	v_mul_f32_e32 v111, v111, v144
	v_mul_f32_e32 v111, v79, v111
	v_cvt_pk_bf16_f32 v108, v108, v109
	v_cvt_pk_bf16_f32 v109, v110, v111
	global_store_dwordx2 v148, v[108:109], s[10:11] offset:1536
	s_add_u32 s10, s10, s18
	s_addc_u32 s11, s11, 0
	v_mul_f32_e32 v144, v112, v112
	v_fmac_f32_e32 v144, v113, v113
	v_fmac_f32_e32 v144, v114, v114
	v_fmac_f32_e32 v144, v115, v115
	v_fmac_f32_e32 v144, v116, v116
	v_fmac_f32_e32 v144, v117, v117
	v_fmac_f32_e32 v144, v118, v118
	v_fmac_f32_e32 v144, v119, v119
	v_fmac_f32_e32 v144, v120, v120
	v_fmac_f32_e32 v144, v121, v121
	v_fmac_f32_e32 v144, v122, v122
	v_fmac_f32_e32 v144, v123, v123
	v_fmac_f32_e32 v144, v124, v124
	v_fmac_f32_e32 v144, v125, v125
	v_fmac_f32_e32 v144, v126, v126
	v_fmac_f32_e32 v144, v127, v127
	s_nop 1
	v_add_f32_dpp v144, v144, v144 quad_perm:[1,0,3,2] row_mask:0xf bank_mask:0xf
	s_nop 1
	v_add_f32_dpp v144, v144, v144 quad_perm:[2,3,0,1] row_mask:0xf bank_mask:0xf
	s_nop 1
	v_add_f32_dpp v144, v144, v144 row_half_mirror row_mask:0xf bank_mask:0xf
	s_nop 1
	v_add_f32_dpp v144, v144, v144 row_mirror row_mask:0xf bank_mask:0xf
	v_mov_b32_e32 v145, v144
	s_nop 1
	v_permlane16_swap_b32_e32 v144, v145
	v_add_f32_e32 v144, v144, v145
	v_mov_b32_e32 v145, v144
	s_nop 1
	v_permlane32_swap_b32_e32 v144, v145
	v_add_f32_e32 v144, v144, v145
	v_fmamk_f32 v144, v144, 0x3a800000, v147
	v_mul_f32_e32 v145, 0x4b800000, v144
	v_cmp_gt_f32_e32 vcc, s19, v144
	s_nop 1
	v_cndmask_b32_e32 v144, v144, v145, vcc
	v_rsq_f32_e32 v144, v144
	s_nop 0
	v_mul_f32_e32 v145, 0x45800000, v144
	v_cndmask_b32_e32 v144, v144, v145, vcc
	v_mul_f32_e32 v112, v112, v144
	v_mul_f32_e32 v112, v64, v112
	v_mul_f32_e32 v113, v113, v144
	v_mul_f32_e32 v113, v65, v113
	v_mul_f32_e32 v114, v114, v144
	v_mul_f32_e32 v114, v66, v114
	v_mul_f32_e32 v115, v115, v144
	v_mul_f32_e32 v115, v67, v115
	v_cvt_pk_bf16_f32 v112, v112, v113
	v_cvt_pk_bf16_f32 v113, v114, v115
	global_store_dwordx2 v148, v[112:113], s[10:11] offset:0
	v_mul_f32_e32 v116, v116, v144
	v_mul_f32_e32 v116, v68, v116
	v_mul_f32_e32 v117, v117, v144
	v_mul_f32_e32 v117, v69, v117
	v_mul_f32_e32 v118, v118, v144
	v_mul_f32_e32 v118, v70, v118
	v_mul_f32_e32 v119, v119, v144
	v_mul_f32_e32 v119, v71, v119
	v_cvt_pk_bf16_f32 v116, v116, v117
	v_cvt_pk_bf16_f32 v117, v118, v119
	global_store_dwordx2 v148, v[116:117], s[10:11] offset:512
	v_mul_f32_e32 v120, v120, v144
	v_mul_f32_e32 v120, v72, v120
	v_mul_f32_e32 v121, v121, v144
	v_mul_f32_e32 v121, v73, v121
	v_mul_f32_e32 v122, v122, v144
	v_mul_f32_e32 v122, v74, v122
	v_mul_f32_e32 v123, v123, v144
	v_mul_f32_e32 v123, v75, v123
	v_cvt_pk_bf16_f32 v120, v120, v121
	v_cvt_pk_bf16_f32 v121, v122, v123
	global_store_dwordx2 v148, v[120:121], s[10:11] offset:1024
	v_mul_f32_e32 v124, v124, v144
	v_mul_f32_e32 v124, v76, v124
	v_mul_f32_e32 v125, v125, v144
	v_mul_f32_e32 v125, v77, v125
	v_mul_f32_e32 v126, v126, v144
	v_mul_f32_e32 v126, v78, v126
	v_mul_f32_e32 v127, v127, v144
	v_mul_f32_e32 v127, v79, v127
	v_cvt_pk_bf16_f32 v124, v124, v125
	v_cvt_pk_bf16_f32 v125, v126, v127
	global_store_dwordx2 v148, v[124:125], s[10:11] offset:1536
	s_add_u32 s10, s10, s18
	s_addc_u32 s11, s11, 0
	v_mul_f32_e32 v144, v128, v128
	v_fmac_f32_e32 v144, v129, v129
	v_fmac_f32_e32 v144, v130, v130
	v_fmac_f32_e32 v144, v131, v131
	v_fmac_f32_e32 v144, v132, v132
	v_fmac_f32_e32 v144, v133, v133
	v_fmac_f32_e32 v144, v134, v134
	v_fmac_f32_e32 v144, v135, v135
	v_fmac_f32_e32 v144, v136, v136
	v_fmac_f32_e32 v144, v137, v137
	v_fmac_f32_e32 v144, v138, v138
	v_fmac_f32_e32 v144, v139, v139
	v_fmac_f32_e32 v144, v140, v140
	v_fmac_f32_e32 v144, v141, v141
	v_fmac_f32_e32 v144, v142, v142
	v_fmac_f32_e32 v144, v143, v143
	s_nop 1
	v_add_f32_dpp v144, v144, v144 quad_perm:[1,0,3,2] row_mask:0xf bank_mask:0xf
	s_nop 1
	v_add_f32_dpp v144, v144, v144 quad_perm:[2,3,0,1] row_mask:0xf bank_mask:0xf
	s_nop 1
	v_add_f32_dpp v144, v144, v144 row_half_mirror row_mask:0xf bank_mask:0xf
	s_nop 1
	v_add_f32_dpp v144, v144, v144 row_mirror row_mask:0xf bank_mask:0xf
	v_mov_b32_e32 v145, v144
	s_nop 1
	v_permlane16_swap_b32_e32 v144, v145
	v_add_f32_e32 v144, v144, v145
	v_mov_b32_e32 v145, v144
	s_nop 1
	v_permlane32_swap_b32_e32 v144, v145
	v_add_f32_e32 v144, v144, v145
	v_fmamk_f32 v144, v144, 0x3a800000, v147
	v_mul_f32_e32 v145, 0x4b800000, v144
	v_cmp_gt_f32_e32 vcc, s19, v144
	s_nop 1
	v_cndmask_b32_e32 v144, v144, v145, vcc
	v_rsq_f32_e32 v144, v144
	s_nop 0
	v_mul_f32_e32 v145, 0x45800000, v144
	v_cndmask_b32_e32 v144, v144, v145, vcc
	v_mul_f32_e32 v128, v128, v144
	v_mul_f32_e32 v128, v64, v128
	v_mul_f32_e32 v129, v129, v144
	v_mul_f32_e32 v129, v65, v129
	v_mul_f32_e32 v130, v130, v144
	v_mul_f32_e32 v130, v66, v130
	v_mul_f32_e32 v131, v131, v144
	v_mul_f32_e32 v131, v67, v131
	v_cvt_pk_bf16_f32 v128, v128, v129
	v_cvt_pk_bf16_f32 v129, v130, v131
	global_store_dwordx2 v148, v[128:129], s[10:11] offset:0
	v_mul_f32_e32 v132, v132, v144
	v_mul_f32_e32 v132, v68, v132
	v_mul_f32_e32 v133, v133, v144
	v_mul_f32_e32 v133, v69, v133
	v_mul_f32_e32 v134, v134, v144
	v_mul_f32_e32 v134, v70, v134
	v_mul_f32_e32 v135, v135, v144
	v_mul_f32_e32 v135, v71, v135
	v_cvt_pk_bf16_f32 v132, v132, v133
	v_cvt_pk_bf16_f32 v133, v134, v135
	global_store_dwordx2 v148, v[132:133], s[10:11] offset:512
	v_mul_f32_e32 v136, v136, v144
	v_mul_f32_e32 v136, v72, v136
	v_mul_f32_e32 v137, v137, v144
	v_mul_f32_e32 v137, v73, v137
	v_mul_f32_e32 v138, v138, v144
	v_mul_f32_e32 v138, v74, v138
	v_mul_f32_e32 v139, v139, v144
	v_mul_f32_e32 v139, v75, v139
	v_cvt_pk_bf16_f32 v136, v136, v137
	v_cvt_pk_bf16_f32 v137, v138, v139
	global_store_dwordx2 v148, v[136:137], s[10:11] offset:1024
	v_mul_f32_e32 v140, v140, v144
	v_mul_f32_e32 v140, v76, v140
	v_mul_f32_e32 v141, v141, v144
	v_mul_f32_e32 v141, v77, v141
	v_mul_f32_e32 v142, v142, v144
	v_mul_f32_e32 v142, v78, v142
	v_mul_f32_e32 v143, v143, v144
	v_mul_f32_e32 v143, v79, v143
	v_cvt_pk_bf16_f32 v140, v140, v141
	v_cvt_pk_bf16_f32 v141, v142, v143
	global_store_dwordx2 v148, v[140:141], s[10:11] offset:1536
	s_add_u32 s10, s10, s18
	s_addc_u32 s11, s11, 0
	global_load_dwordx4 v[80:83], v211, s[8:9] offset:0
	global_load_dwordx4 v[84:87], v211, s[8:9] offset:1024
	global_load_dwordx4 v[88:91], v211, s[8:9] offset:2048
	global_load_dwordx4 v[92:95], v211, s[8:9] offset:3072
	s_add_u32 s8, s8, s16
	s_addc_u32 s9, s9, 0
	global_load_dwordx4 v[96:99], v211, s[8:9] offset:0
	global_load_dwordx4 v[100:103], v211, s[8:9] offset:1024
	global_load_dwordx4 v[104:107], v211, s[8:9] offset:2048
	global_load_dwordx4 v[108:111], v211, s[8:9] offset:3072
	s_add_u32 s8, s8, s16
	s_addc_u32 s9, s9, 0
	global_load_dwordx4 v[112:115], v211, s[8:9] offset:0
	global_load_dwordx4 v[116:119], v211, s[8:9] offset:1024
	global_load_dwordx4 v[120:123], v211, s[8:9] offset:2048
	global_load_dwordx4 v[124:127], v211, s[8:9] offset:3072
	s_add_u32 s8, s8, s16
	s_addc_u32 s9, s9, 0
	global_load_dwordx4 v[128:131], v211, s[8:9] offset:0
	global_load_dwordx4 v[132:135], v211, s[8:9] offset:1024
	global_load_dwordx4 v[136:139], v211, s[8:9] offset:2048
	global_load_dwordx4 v[140:143], v211, s[8:9] offset:3072
	s_add_u32 s8, s8, s16
	s_addc_u32 s9, s9, 0
	s_waitcnt vmcnt(0)
	v_mul_f32_e32 v144, v80, v80
	v_fmac_f32_e32 v144, v81, v81
	v_fmac_f32_e32 v144, v82, v82
	v_fmac_f32_e32 v144, v83, v83
	v_fmac_f32_e32 v144, v84, v84
	v_fmac_f32_e32 v144, v85, v85
	v_fmac_f32_e32 v144, v86, v86
	v_fmac_f32_e32 v144, v87, v87
	v_fmac_f32_e32 v144, v88, v88
	v_fmac_f32_e32 v144, v89, v89
	v_fmac_f32_e32 v144, v90, v90
	v_fmac_f32_e32 v144, v91, v91
	v_fmac_f32_e32 v144, v92, v92
	v_fmac_f32_e32 v144, v93, v93
	v_fmac_f32_e32 v144, v94, v94
	v_fmac_f32_e32 v144, v95, v95
	s_nop 1
	v_add_f32_dpp v144, v144, v144 quad_perm:[1,0,3,2] row_mask:0xf bank_mask:0xf
	s_nop 1
	v_add_f32_dpp v144, v144, v144 quad_perm:[2,3,0,1] row_mask:0xf bank_mask:0xf
	s_nop 1
	v_add_f32_dpp v144, v144, v144 row_half_mirror row_mask:0xf bank_mask:0xf
	s_nop 1
	v_add_f32_dpp v144, v144, v144 row_mirror row_mask:0xf bank_mask:0xf
	v_mov_b32_e32 v145, v144
	s_nop 1
	v_permlane16_swap_b32_e32 v144, v145
	v_add_f32_e32 v144, v144, v145
	v_mov_b32_e32 v145, v144
	s_nop 1
	v_permlane32_swap_b32_e32 v144, v145
	v_add_f32_e32 v144, v144, v145
	v_fmamk_f32 v144, v144, 0x3a800000, v147
	v_mul_f32_e32 v145, 0x4b800000, v144
	v_cmp_gt_f32_e32 vcc, s19, v144
	s_nop 1
	v_cndmask_b32_e32 v144, v144, v145, vcc
	v_rsq_f32_e32 v144, v144
	s_nop 0
	v_mul_f32_e32 v145, 0x45800000, v144
	v_cndmask_b32_e32 v144, v144, v145, vcc
	v_mul_f32_e32 v80, v80, v144
	v_mul_f32_e32 v80, v64, v80
	v_mul_f32_e32 v81, v81, v144
	v_mul_f32_e32 v81, v65, v81
	v_mul_f32_e32 v82, v82, v144
	v_mul_f32_e32 v82, v66, v82
	v_mul_f32_e32 v83, v83, v144
	v_mul_f32_e32 v83, v67, v83
	v_cvt_pk_bf16_f32 v80, v80, v81
	v_cvt_pk_bf16_f32 v81, v82, v83
	global_store_dwordx2 v148, v[80:81], s[10:11] offset:0
	v_mul_f32_e32 v84, v84, v144
	v_mul_f32_e32 v84, v68, v84
	v_mul_f32_e32 v85, v85, v144
	v_mul_f32_e32 v85, v69, v85
	v_mul_f32_e32 v86, v86, v144
	v_mul_f32_e32 v86, v70, v86
	v_mul_f32_e32 v87, v87, v144
	v_mul_f32_e32 v87, v71, v87
	v_cvt_pk_bf16_f32 v84, v84, v85
	v_cvt_pk_bf16_f32 v85, v86, v87
	global_store_dwordx2 v148, v[84:85], s[10:11] offset:512
	v_mul_f32_e32 v88, v88, v144
	v_mul_f32_e32 v88, v72, v88
	v_mul_f32_e32 v89, v89, v144
	v_mul_f32_e32 v89, v73, v89
	v_mul_f32_e32 v90, v90, v144
	v_mul_f32_e32 v90, v74, v90
	v_mul_f32_e32 v91, v91, v144
	v_mul_f32_e32 v91, v75, v91
	v_cvt_pk_bf16_f32 v88, v88, v89
	v_cvt_pk_bf16_f32 v89, v90, v91
	global_store_dwordx2 v148, v[88:89], s[10:11] offset:1024
	v_mul_f32_e32 v92, v92, v144
	v_mul_f32_e32 v92, v76, v92
	v_mul_f32_e32 v93, v93, v144
	v_mul_f32_e32 v93, v77, v93
	v_mul_f32_e32 v94, v94, v144
	v_mul_f32_e32 v94, v78, v94
	v_mul_f32_e32 v95, v95, v144
	v_mul_f32_e32 v95, v79, v95
	v_cvt_pk_bf16_f32 v92, v92, v93
	v_cvt_pk_bf16_f32 v93, v94, v95
	global_store_dwordx2 v148, v[92:93], s[10:11] offset:1536
	s_add_u32 s10, s10, s18
	s_addc_u32 s11, s11, 0
	v_mul_f32_e32 v144, v96, v96
	v_fmac_f32_e32 v144, v97, v97
	v_fmac_f32_e32 v144, v98, v98
	v_fmac_f32_e32 v144, v99, v99
	v_fmac_f32_e32 v144, v100, v100
	v_fmac_f32_e32 v144, v101, v101
	v_fmac_f32_e32 v144, v102, v102
	v_fmac_f32_e32 v144, v103, v103
	v_fmac_f32_e32 v144, v104, v104
	v_fmac_f32_e32 v144, v105, v105
	v_fmac_f32_e32 v144, v106, v106
	v_fmac_f32_e32 v144, v107, v107
	v_fmac_f32_e32 v144, v108, v108
	v_fmac_f32_e32 v144, v109, v109
	v_fmac_f32_e32 v144, v110, v110
	v_fmac_f32_e32 v144, v111, v111
	s_nop 1
	v_add_f32_dpp v144, v144, v144 quad_perm:[1,0,3,2] row_mask:0xf bank_mask:0xf
	s_nop 1
	v_add_f32_dpp v144, v144, v144 quad_perm:[2,3,0,1] row_mask:0xf bank_mask:0xf
	s_nop 1
	v_add_f32_dpp v144, v144, v144 row_half_mirror row_mask:0xf bank_mask:0xf
	s_nop 1
	v_add_f32_dpp v144, v144, v144 row_mirror row_mask:0xf bank_mask:0xf
	v_mov_b32_e32 v145, v144
	s_nop 1
	v_permlane16_swap_b32_e32 v144, v145
	v_add_f32_e32 v144, v144, v145
	v_mov_b32_e32 v145, v144
	s_nop 1
	v_permlane32_swap_b32_e32 v144, v145
	v_add_f32_e32 v144, v144, v145
	v_fmamk_f32 v144, v144, 0x3a800000, v147
	v_mul_f32_e32 v145, 0x4b800000, v144
	v_cmp_gt_f32_e32 vcc, s19, v144
	s_nop 1
	v_cndmask_b32_e32 v144, v144, v145, vcc
	v_rsq_f32_e32 v144, v144
	s_nop 0
	v_mul_f32_e32 v145, 0x45800000, v144
	v_cndmask_b32_e32 v144, v144, v145, vcc
	v_mul_f32_e32 v96, v96, v144
	v_mul_f32_e32 v96, v64, v96
	v_mul_f32_e32 v97, v97, v144
	v_mul_f32_e32 v97, v65, v97
	v_mul_f32_e32 v98, v98, v144
	v_mul_f32_e32 v98, v66, v98
	v_mul_f32_e32 v99, v99, v144
	v_mul_f32_e32 v99, v67, v99
	v_cvt_pk_bf16_f32 v96, v96, v97
	v_cvt_pk_bf16_f32 v97, v98, v99
	global_store_dwordx2 v148, v[96:97], s[10:11] offset:0
	v_mul_f32_e32 v100, v100, v144
	v_mul_f32_e32 v100, v68, v100
	v_mul_f32_e32 v101, v101, v144
	v_mul_f32_e32 v101, v69, v101
	v_mul_f32_e32 v102, v102, v144
	v_mul_f32_e32 v102, v70, v102
	v_mul_f32_e32 v103, v103, v144
	v_mul_f32_e32 v103, v71, v103
	v_cvt_pk_bf16_f32 v100, v100, v101
	v_cvt_pk_bf16_f32 v101, v102, v103
	global_store_dwordx2 v148, v[100:101], s[10:11] offset:512
	v_mul_f32_e32 v104, v104, v144
	v_mul_f32_e32 v104, v72, v104
	v_mul_f32_e32 v105, v105, v144
	v_mul_f32_e32 v105, v73, v105
	v_mul_f32_e32 v106, v106, v144
	v_mul_f32_e32 v106, v74, v106
	v_mul_f32_e32 v107, v107, v144
	v_mul_f32_e32 v107, v75, v107
	v_cvt_pk_bf16_f32 v104, v104, v105
	v_cvt_pk_bf16_f32 v105, v106, v107
	global_store_dwordx2 v148, v[104:105], s[10:11] offset:1024
	v_mul_f32_e32 v108, v108, v144
	v_mul_f32_e32 v108, v76, v108
	v_mul_f32_e32 v109, v109, v144
	v_mul_f32_e32 v109, v77, v109
	v_mul_f32_e32 v110, v110, v144
	v_mul_f32_e32 v110, v78, v110
	v_mul_f32_e32 v111, v111, v144
	v_mul_f32_e32 v111, v79, v111
	v_cvt_pk_bf16_f32 v108, v108, v109
	v_cvt_pk_bf16_f32 v109, v110, v111
	global_store_dwordx2 v148, v[108:109], s[10:11] offset:1536
	s_add_u32 s10, s10, s18
	s_addc_u32 s11, s11, 0
	v_mul_f32_e32 v144, v112, v112
	v_fmac_f32_e32 v144, v113, v113
	v_fmac_f32_e32 v144, v114, v114
	v_fmac_f32_e32 v144, v115, v115
	v_fmac_f32_e32 v144, v116, v116
	v_fmac_f32_e32 v144, v117, v117
	v_fmac_f32_e32 v144, v118, v118
	v_fmac_f32_e32 v144, v119, v119
	v_fmac_f32_e32 v144, v120, v120
	v_fmac_f32_e32 v144, v121, v121
	v_fmac_f32_e32 v144, v122, v122
	v_fmac_f32_e32 v144, v123, v123
	v_fmac_f32_e32 v144, v124, v124
	v_fmac_f32_e32 v144, v125, v125
	v_fmac_f32_e32 v144, v126, v126
	v_fmac_f32_e32 v144, v127, v127
	s_nop 1
	v_add_f32_dpp v144, v144, v144 quad_perm:[1,0,3,2] row_mask:0xf bank_mask:0xf
	s_nop 1
	v_add_f32_dpp v144, v144, v144 quad_perm:[2,3,0,1] row_mask:0xf bank_mask:0xf
	s_nop 1
	v_add_f32_dpp v144, v144, v144 row_half_mirror row_mask:0xf bank_mask:0xf
	s_nop 1
	v_add_f32_dpp v144, v144, v144 row_mirror row_mask:0xf bank_mask:0xf
	v_mov_b32_e32 v145, v144
	s_nop 1
	v_permlane16_swap_b32_e32 v144, v145
	v_add_f32_e32 v144, v144, v145
	v_mov_b32_e32 v145, v144
	s_nop 1
	v_permlane32_swap_b32_e32 v144, v145
	v_add_f32_e32 v144, v144, v145
	v_fmamk_f32 v144, v144, 0x3a800000, v147
	v_mul_f32_e32 v145, 0x4b800000, v144
	v_cmp_gt_f32_e32 vcc, s19, v144
	s_nop 1
	v_cndmask_b32_e32 v144, v144, v145, vcc
	v_rsq_f32_e32 v144, v144
	s_nop 0
	v_mul_f32_e32 v145, 0x45800000, v144
	v_cndmask_b32_e32 v144, v144, v145, vcc
	v_mul_f32_e32 v112, v112, v144
	v_mul_f32_e32 v112, v64, v112
	v_mul_f32_e32 v113, v113, v144
	v_mul_f32_e32 v113, v65, v113
	v_mul_f32_e32 v114, v114, v144
	v_mul_f32_e32 v114, v66, v114
	v_mul_f32_e32 v115, v115, v144
	v_mul_f32_e32 v115, v67, v115
	v_cvt_pk_bf16_f32 v112, v112, v113
	v_cvt_pk_bf16_f32 v113, v114, v115
	global_store_dwordx2 v148, v[112:113], s[10:11] offset:0
	v_mul_f32_e32 v116, v116, v144
	v_mul_f32_e32 v116, v68, v116
	v_mul_f32_e32 v117, v117, v144
	v_mul_f32_e32 v117, v69, v117
	v_mul_f32_e32 v118, v118, v144
	v_mul_f32_e32 v118, v70, v118
	v_mul_f32_e32 v119, v119, v144
	v_mul_f32_e32 v119, v71, v119
	v_cvt_pk_bf16_f32 v116, v116, v117
	v_cvt_pk_bf16_f32 v117, v118, v119
	global_store_dwordx2 v148, v[116:117], s[10:11] offset:512
	v_mul_f32_e32 v120, v120, v144
	v_mul_f32_e32 v120, v72, v120
	v_mul_f32_e32 v121, v121, v144
	v_mul_f32_e32 v121, v73, v121
	v_mul_f32_e32 v122, v122, v144
	v_mul_f32_e32 v122, v74, v122
	v_mul_f32_e32 v123, v123, v144
	v_mul_f32_e32 v123, v75, v123
	v_cvt_pk_bf16_f32 v120, v120, v121
	v_cvt_pk_bf16_f32 v121, v122, v123
	global_store_dwordx2 v148, v[120:121], s[10:11] offset:1024
	v_mul_f32_e32 v124, v124, v144
	v_mul_f32_e32 v124, v76, v124
	v_mul_f32_e32 v125, v125, v144
	v_mul_f32_e32 v125, v77, v125
	v_mul_f32_e32 v126, v126, v144
	v_mul_f32_e32 v126, v78, v126
	v_mul_f32_e32 v127, v127, v144
	v_mul_f32_e32 v127, v79, v127
	v_cvt_pk_bf16_f32 v124, v124, v125
	v_cvt_pk_bf16_f32 v125, v126, v127
	global_store_dwordx2 v148, v[124:125], s[10:11] offset:1536
	s_add_u32 s10, s10, s18
	s_addc_u32 s11, s11, 0
	v_mul_f32_e32 v144, v128, v128
	v_fmac_f32_e32 v144, v129, v129
	v_fmac_f32_e32 v144, v130, v130
	v_fmac_f32_e32 v144, v131, v131
	v_fmac_f32_e32 v144, v132, v132
	v_fmac_f32_e32 v144, v133, v133
	v_fmac_f32_e32 v144, v134, v134
	v_fmac_f32_e32 v144, v135, v135
	v_fmac_f32_e32 v144, v136, v136
	v_fmac_f32_e32 v144, v137, v137
	v_fmac_f32_e32 v144, v138, v138
	v_fmac_f32_e32 v144, v139, v139
	v_fmac_f32_e32 v144, v140, v140
	v_fmac_f32_e32 v144, v141, v141
	v_fmac_f32_e32 v144, v142, v142
	v_fmac_f32_e32 v144, v143, v143
	s_nop 1
	v_add_f32_dpp v144, v144, v144 quad_perm:[1,0,3,2] row_mask:0xf bank_mask:0xf
	s_nop 1
	v_add_f32_dpp v144, v144, v144 quad_perm:[2,3,0,1] row_mask:0xf bank_mask:0xf
	s_nop 1
	v_add_f32_dpp v144, v144, v144 row_half_mirror row_mask:0xf bank_mask:0xf
	s_nop 1
	v_add_f32_dpp v144, v144, v144 row_mirror row_mask:0xf bank_mask:0xf
	v_mov_b32_e32 v145, v144
	s_nop 1
	v_permlane16_swap_b32_e32 v144, v145
	v_add_f32_e32 v144, v144, v145
	v_mov_b32_e32 v145, v144
	s_nop 1
	v_permlane32_swap_b32_e32 v144, v145
	v_add_f32_e32 v144, v144, v145
	v_fmamk_f32 v144, v144, 0x3a800000, v147
	v_mul_f32_e32 v145, 0x4b800000, v144
	v_cmp_gt_f32_e32 vcc, s19, v144
	s_nop 1
	v_cndmask_b32_e32 v144, v144, v145, vcc
	v_rsq_f32_e32 v144, v144
	s_nop 0
	v_mul_f32_e32 v145, 0x45800000, v144
	v_cndmask_b32_e32 v144, v144, v145, vcc
	v_mul_f32_e32 v128, v128, v144
	v_mul_f32_e32 v128, v64, v128
	v_mul_f32_e32 v129, v129, v144
	v_mul_f32_e32 v129, v65, v129
	v_mul_f32_e32 v130, v130, v144
	v_mul_f32_e32 v130, v66, v130
	v_mul_f32_e32 v131, v131, v144
	v_mul_f32_e32 v131, v67, v131
	v_cvt_pk_bf16_f32 v128, v128, v129
	v_cvt_pk_bf16_f32 v129, v130, v131
	global_store_dwordx2 v148, v[128:129], s[10:11] offset:0
	v_mul_f32_e32 v132, v132, v144
	v_mul_f32_e32 v132, v68, v132
	v_mul_f32_e32 v133, v133, v144
	v_mul_f32_e32 v133, v69, v133
	v_mul_f32_e32 v134, v134, v144
	v_mul_f32_e32 v134, v70, v134
	v_mul_f32_e32 v135, v135, v144
	v_mul_f32_e32 v135, v71, v135
	v_cvt_pk_bf16_f32 v132, v132, v133
	v_cvt_pk_bf16_f32 v133, v134, v135
	global_store_dwordx2 v148, v[132:133], s[10:11] offset:512
	v_mul_f32_e32 v136, v136, v144
	v_mul_f32_e32 v136, v72, v136
	v_mul_f32_e32 v137, v137, v144
	v_mul_f32_e32 v137, v73, v137
	v_mul_f32_e32 v138, v138, v144
	v_mul_f32_e32 v138, v74, v138
	v_mul_f32_e32 v139, v139, v144
	v_mul_f32_e32 v139, v75, v139
	v_cvt_pk_bf16_f32 v136, v136, v137
	v_cvt_pk_bf16_f32 v137, v138, v139
	global_store_dwordx2 v148, v[136:137], s[10:11] offset:1024
	v_mul_f32_e32 v140, v140, v144
	v_mul_f32_e32 v140, v76, v140
	v_mul_f32_e32 v141, v141, v144
	v_mul_f32_e32 v141, v77, v141
	v_mul_f32_e32 v142, v142, v144
	v_mul_f32_e32 v142, v78, v142
	v_mul_f32_e32 v143, v143, v144
	v_mul_f32_e32 v143, v79, v143
	v_cvt_pk_bf16_f32 v140, v140, v141
	v_cvt_pk_bf16_f32 v141, v142, v143
	global_store_dwordx2 v148, v[140:141], s[10:11] offset:1536
	s_add_u32 s10, s10, s18
	s_addc_u32 s11, s11, 0
	s_waitcnt vmcnt(0)
	s_lshl_b32 s15, s92, 6
	s_add_u32 s101, s101, s15
	s_cmpk_lt_u32 s101, 0x8000
	s_cbranch_scc1 .Lgv0_chunk
	s_branch .LBB0_637

.Lgu1_start:
	s_mov_b64 exec, -1
	v_and_b32_e32 v171, 63, v205
	v_lshrrev_b32_e32 v172, 6, v205
	v_lshlrev_b32_e32 v160, 2, v171
	v_readfirstlane_b32 s34, v172
	v_and_b32_e32 v172, 7, v171
	v_lshlrev_b32_e32 v163, 3, v172
	v_mul_u32_u24_e32 v164, 24, v172
	s_nop 3
	s_lshl_b32 s13, s34, 14
	s_add_i32 s35, s93, s34
	v_lshrrev_b32_e32 v172, 3, v171
	v_lshl_add_u32 v162, v172, 2, s13
	v_add_u32_e32 v161, 0x2000, v162
	v_and_b32_e32 v172, 7, v171
	v_lshl_add_u32 v162, v172, 5, v162
	v_lshl_add_u32 v173, v171, 4, s13
	v_add_u32_e32 v175, s13, v160
	v_add_u32_e32 v174, 0x2000, v175
.Lgu1_chunk:
	s_movk_i32 s18, 0xc0
	s_lshl_b32 s19, s92, 13
	s_mov_b32 s10, 0xaaaaaaaa
	s_mov_b32 s11, 0xaaaaaaaa
	s_mov_b32 s100, 0xcccccccc
	s_mov_b32 s101, 0xcccccccc
	s_add_u32 s6, s26, 0xd800000
	s_addc_u32 s7, s27, 0
	s_lshl_b32 s13, s35, 9
	s_add_u32 s6, s6, s13
	s_addc_u32 s7, s7, 0
	s_lshl_b32 s14, s92, 11
	global_load_dword v16, v160, s[6:7]
	global_load_dword v17, v160, s[6:7] offset:256
	s_add_u32 s6, s6, s14
	s_addc_u32 s7, s7, 0
	global_load_dword v18, v160, s[6:7]
	global_load_dword v19, v160, s[6:7] offset:256
	s_add_u32 s6, s6, s14
	s_addc_u32 s7, s7, 0
	global_load_dword v20, v160, s[6:7]
	global_load_dword v21, v160, s[6:7] offset:256
	s_add_u32 s6, s6, s14
	s_addc_u32 s7, s7, 0
	global_load_dword v22, v160, s[6:7]
	global_load_dword v23, v160, s[6:7] offset:256
	s_add_u32 s6, s6, s14
	s_addc_u32 s7, s7, 0
	global_load_dword v24, v160, s[6:7]
	global_load_dword v25, v160, s[6:7] offset:256
	s_add_u32 s6, s6, s14
	s_addc_u32 s7, s7, 0
	global_load_dword v26, v160, s[6:7]
	global_load_dword v27, v160, s[6:7] offset:256
	s_add_u32 s6, s6, s14
	s_addc_u32 s7, s7, 0
	global_load_dword v28, v160, s[6:7]
	global_load_dword v29, v160, s[6:7] offset:256
	s_add_u32 s6, s6, s14
	s_addc_u32 s7, s7, 0
	global_load_dword v30, v160, s[6:7]
	global_load_dword v31, v160, s[6:7] offset:256
	s_add_u32 s6, s6, s14
	s_addc_u32 s7, s7, 0
	global_load_dword v32, v160, s[6:7]
	global_load_dword v33, v160, s[6:7] offset:256
	s_add_u32 s6, s6, s14
	s_addc_u32 s7, s7, 0
	global_load_dword v34, v160, s[6:7]
	global_load_dword v35, v160, s[6:7] offset:256
	s_add_u32 s6, s6, s14
	s_addc_u32 s7, s7, 0
	global_load_dword v36, v160, s[6:7]
	global_load_dword v37, v160, s[6:7] offset:256
	s_add_u32 s6, s6, s14
	s_addc_u32 s7, s7, 0
	global_load_dword v38, v160, s[6:7]
	global_load_dword v39, v160, s[6:7] offset:256
	s_add_u32 s6, s6, s14
	s_addc_u32 s7, s7, 0
	global_load_dword v40, v160, s[6:7]
	global_load_dword v41, v160, s[6:7] offset:256
	s_add_u32 s6, s6, s14
	s_addc_u32 s7, s7, 0
	global_load_dword v42, v160, s[6:7]
	global_load_dword v43, v160, s[6:7] offset:256
	s_add_u32 s6, s6, s14
	s_addc_u32 s7, s7, 0
	global_load_dword v44, v160, s[6:7]
	global_load_dword v45, v160, s[6:7] offset:256
	s_add_u32 s6, s6, s14
	s_addc_u32 s7, s7, 0
	global_load_dword v46, v160, s[6:7]
	global_load_dword v47, v160, s[6:7] offset:256
	s_add_u32 s6, s6, s14
	s_addc_u32 s7, s7, 0
	v_mov_b32_e32 v0, 0
	v_mov_b32_e32 v1, 0
	v_mov_b32_e32 v2, 0
	v_mov_b32_e32 v3, 0
	ds_write_b128 v173, v[0:3] offset:0
	ds_write_b128 v173, v[0:3] offset:1024
	ds_write_b128 v173, v[0:3] offset:2048
	ds_write_b128 v173, v[0:3] offset:3072
	ds_write_b128 v173, v[0:3] offset:4096
	ds_write_b128 v173, v[0:3] offset:5120
	ds_write_b128 v173, v[0:3] offset:6144
	ds_write_b128 v173, v[0:3] offset:7168
	s_waitcnt vmcnt(0)
	ds_write2st64_b32 v174, v16, v17 offset0:0 offset1:1
	ds_write2st64_b32 v174, v18, v19 offset0:2 offset1:3
	ds_write2st64_b32 v174, v20, v21 offset0:4 offset1:5
	ds_write2st64_b32 v174, v22, v23 offset0:6 offset1:7
	ds_write2st64_b32 v174, v24, v25 offset0:8 offset1:9
	ds_write2st64_b32 v174, v26, v27 offset0:10 offset1:11
	ds_write2st64_b32 v174, v28, v29 offset0:12 offset1:13
	ds_write2st64_b32 v174, v30, v31 offset0:14 offset1:15
	ds_write2st64_b32 v174, v32, v33 offset0:16 offset1:17
	ds_write2st64_b32 v174, v34, v35 offset0:18 offset1:19
	ds_write2st64_b32 v174, v36, v37 offset0:20 offset1:21
	ds_write2st64_b32 v174, v38, v39 offset0:22 offset1:23
	ds_write2st64_b32 v174, v40, v41 offset0:24 offset1:25
	ds_write2st64_b32 v174, v42, v43 offset0:26 offset1:27
	ds_write2st64_b32 v174, v44, v45 offset0:28 offset1:29
	ds_write2st64_b32 v174, v46, v47 offset0:30 offset1:31
	s_waitcnt lgkmcnt(0)
	s_add_u32 s0, s26, 0x2800000
	s_addc_u32 s1, s27, 0
	s_add_u32 s4, s26, 0x5800000
	s_addc_u32 s5, s27, 0
	s_lshl_b32 s13, s35, 11
	s_add_u32 s4, s4, s13
	s_addc_u32 s5, s5, 0
	s_mov_b32 s12, 0
	s_and_b32 s15, s12, 15
	s_lshr_b32 s16, s12, 4
	s_lshl_b32 s17, s15, 9
	s_mul_i32 s13, s15, s19
	s_lshl_b32 s14, s16, 6
	s_add_u32 s13, s13, s14
	s_add_u32 s6, s4, s13
	s_addc_u32 s7, s5, 0
	s_mul_i32 s13, s16, 0x300000
	s_add_u32 s0, s26, 0x2800000
	s_addc_u32 s1, s27, 0
	s_add_u32 s0, s0, s13
	s_addc_u32 s1, s1, 0
	v_add_u32_e32 v167, s17, v161
	ds_read2_b32 v[144:145], v167 offset0:0 offset1:8
	ds_read2_b32 v[146:147], v167 offset0:16 offset1:24
	global_load_dwordx2 v[112:113], v163, s[6:7]
	global_load_dwordx2 v[114:115], v163, s[6:7] offset:256
	global_load_dwordx2 v[116:117], v163, s[6:7] offset:512
	global_load_dwordx2 v[118:119], v163, s[6:7] offset:768
	global_load_dwordx2 v[120:121], v163, s[6:7] offset:1024
	global_load_dwordx2 v[122:123], v163, s[6:7] offset:1280
	global_load_dwordx2 v[124:125], v163, s[6:7] offset:1536
	global_load_dwordx2 v[126:127], v163, s[6:7] offset:1792
	s_waitcnt lgkmcnt(0)
	v_mad_u32_u24 v144, v144, s18, v164
	v_mad_u32_u24 v145, v145, s18, v164
	v_mad_u32_u24 v146, v146, s18, v164
	v_mad_u32_u24 v147, v147, s18, v164
	global_load_dwordx4 v[16:19], v144, s[0:1]
	global_load_dwordx2 v[20:21], v144, s[0:1] offset:16
	global_load_dwordx4 v[22:25], v145, s[0:1]
	global_load_dwordx2 v[26:27], v145, s[0:1] offset:16
	global_load_dwordx4 v[28:31], v146, s[0:1]
	global_load_dwordx2 v[32:33], v146, s[0:1] offset:16
	global_load_dwordx4 v[34:37], v147, s[0:1]
	global_load_dwordx2 v[38:39], v147, s[0:1] offset:16
	ds_read2_b32 v[176:177], v167 offset0:32 offset1:40
	ds_read2_b32 v[178:179], v167 offset0:48 offset1:56
	s_waitcnt lgkmcnt(0)
	v_mad_u32_u24 v176, v176, s18, v164
	v_mad_u32_u24 v177, v177, s18, v164
	v_mad_u32_u24 v178, v178, s18, v164
	v_mad_u32_u24 v179, v179, s18, v164
	global_load_dwordx4 v[40:43], v176, s[0:1]
	global_load_dwordx2 v[44:45], v176, s[0:1] offset:16
	global_load_dwordx4 v[46:49], v177, s[0:1]
	global_load_dwordx2 v[50:51], v177, s[0:1] offset:16
	global_load_dwordx4 v[52:55], v178, s[0:1]
	global_load_dwordx2 v[56:57], v178, s[0:1] offset:16
	global_load_dwordx4 v[58:61], v179, s[0:1]
	global_load_dwordx2 v[62:63], v179, s[0:1] offset:16
	ds_read2_b32 v[144:145], v167 offset0:64 offset1:72
	ds_read2_b32 v[146:147], v167 offset0:80 offset1:88
	s_waitcnt lgkmcnt(0)
	v_mad_u32_u24 v144, v144, s18, v164
	v_mad_u32_u24 v145, v145, s18, v164
	v_mad_u32_u24 v146, v146, s18, v164
	v_mad_u32_u24 v147, v147, s18, v164
	global_load_dwordx4 v[64:67], v144, s[0:1]
	global_load_dwordx2 v[68:69], v144, s[0:1] offset:16
	global_load_dwordx4 v[70:73], v145, s[0:1]
	global_load_dwordx2 v[74:75], v145, s[0:1] offset:16
	global_load_dwordx4 v[76:79], v146, s[0:1]
	global_load_dwordx2 v[80:81], v146, s[0:1] offset:16
	global_load_dwordx4 v[82:85], v147, s[0:1]
	global_load_dwordx2 v[86:87], v147, s[0:1] offset:16
	ds_read2_b32 v[176:177], v167 offset0:96 offset1:104
	ds_read2_b32 v[178:179], v167 offset0:112 offset1:120
	s_waitcnt lgkmcnt(0)
	v_mad_u32_u24 v176, v176, s18, v164
	v_mad_u32_u24 v177, v177, s18, v164
	v_mad_u32_u24 v178, v178, s18, v164
	v_mad_u32_u24 v179, v179, s18, v164
	global_load_dwordx4 v[88:91], v176, s[0:1]
	global_load_dwordx2 v[92:93], v176, s[0:1] offset:16
	global_load_dwordx4 v[94:97], v177, s[0:1]
	global_load_dwordx2 v[98:99], v177, s[0:1] offset:16
	global_load_dwordx4 v[100:103], v178, s[0:1]
	global_load_dwordx2 v[104:105], v178, s[0:1] offset:16
	global_load_dwordx4 v[106:109], v179, s[0:1]
	global_load_dwordx2 v[110:111], v179, s[0:1] offset:16
	s_mov_b32 s38, 1
	s_and_b32 s15, s38, 15
	s_lshr_b32 s16, s38, 4
	s_lshl_b32 s17, s15, 9
	s_mul_i32 s13, s15, s19
	s_lshl_b32 s14, s16, 6
	s_add_u32 s13, s13, s14
	s_add_u32 s8, s4, s13
	s_addc_u32 s9, s5, 0
	s_mul_i32 s13, s16, 0x300000
	s_add_u32 s0, s26, 0x2800000
	s_addc_u32 s1, s27, 0
	s_add_u32 s0, s0, s13
	s_addc_u32 s1, s1, 0
	v_add_u32_e32 v168, s17, v161
	ds_read2_b32 v[144:145], v168 offset0:0 offset1:8
	ds_read2_b32 v[146:147], v168 offset0:16 offset1:24
.Lgu1_loop:
	s_and_b32 s15, s12, 15
	s_lshl_b32 s17, s15, 9
	v_add_u32_e32 v169, s17, v162
	s_waitcnt vmcnt(30)
	v_cvt_scalef32_pk32_bf16_fp6 v[0:15], v[16:21], 1.0
	v_dot2_f32_bf16 v152, v0, v112, 0
	v_dot2_f32_bf16 v153, v1, v113, 0
	v_dot2_f32_bf16 v154, v2, v114, 0
	v_dot2_f32_bf16 v155, v3, v115, 0
	v_dot2c_f32_bf16_e32 v152, v4, v116
	v_dot2c_f32_bf16_e32 v153, v5, v117
	v_dot2c_f32_bf16_e32 v154, v6, v118
	v_dot2c_f32_bf16_e32 v155, v7, v119
	v_dot2c_f32_bf16_e32 v152, v8, v120
	v_dot2c_f32_bf16_e32 v153, v9, v121
	v_dot2c_f32_bf16_e32 v154, v10, v122
	v_dot2c_f32_bf16_e32 v155, v11, v123
	v_dot2c_f32_bf16_e32 v152, v12, v124
	v_dot2c_f32_bf16_e32 v153, v13, v125
	v_dot2c_f32_bf16_e32 v154, v14, v126
	v_dot2c_f32_bf16_e32 v155, v15, v127
	s_waitcnt vmcnt(28)
	v_cvt_scalef32_pk32_bf16_fp6 v[0:15], v[22:27], 1.0
	v_dot2_f32_bf16 v192, v0, v112, 0
	v_dot2_f32_bf16 v193, v1, v113, 0
	v_dot2_f32_bf16 v194, v2, v114, 0
	v_dot2_f32_bf16 v195, v3, v115, 0
	v_dot2c_f32_bf16_e32 v192, v4, v116
	v_dot2c_f32_bf16_e32 v193, v5, v117
	v_add_f32_e32 v156, v152, v153
	v_dot2c_f32_bf16_e32 v194, v6, v118
	v_dot2c_f32_bf16_e32 v195, v7, v119
	v_dot2c_f32_bf16_e32 v192, v8, v120
	v_add_f32_e32 v157, v154, v155
	v_dot2c_f32_bf16_e32 v193, v9, v121
	v_dot2c_f32_bf16_e32 v194, v10, v122
	v_dot2c_f32_bf16_e32 v195, v11, v123
	v_add_f32_e32 v184, v156, v157
	v_dot2c_f32_bf16_e32 v192, v12, v124
	v_dot2c_f32_bf16_e32 v193, v13, v125
	v_dot2c_f32_bf16_e32 v194, v14, v126
	v_dot2c_f32_bf16_e32 v195, v15, v127
	s_waitcnt vmcnt(26)
	v_cvt_scalef32_pk32_bf16_fp6 v[0:15], v[28:33], 1.0
	v_dot2_f32_bf16 v152, v0, v112, 0
	v_dot2_f32_bf16 v153, v1, v113, 0
	v_dot2_f32_bf16 v154, v2, v114, 0
	v_dot2_f32_bf16 v155, v3, v115, 0
	v_dot2c_f32_bf16_e32 v152, v4, v116
	v_dot2c_f32_bf16_e32 v153, v5, v117
	v_add_f32_e32 v156, v192, v193
	v_dot2c_f32_bf16_e32 v154, v6, v118
	v_dot2c_f32_bf16_e32 v155, v7, v119
	v_dot2c_f32_bf16_e32 v152, v8, v120
	v_add_f32_e32 v157, v194, v195
	v_dot2c_f32_bf16_e32 v153, v9, v121
	v_dot2c_f32_bf16_e32 v154, v10, v122
	v_dot2c_f32_bf16_e32 v155, v11, v123
	v_add_f32_e32 v185, v156, v157
	v_dot2c_f32_bf16_e32 v152, v12, v124
	v_dot2c_f32_bf16_e32 v153, v13, v125
	v_dot2c_f32_bf16_e32 v154, v14, v126
	v_dot2c_f32_bf16_e32 v155, v15, v127
	s_waitcnt vmcnt(24)
	v_cvt_scalef32_pk32_bf16_fp6 v[0:15], v[34:39], 1.0
	v_dot2_f32_bf16 v192, v0, v112, 0
	v_dot2_f32_bf16 v193, v1, v113, 0
	v_dot2_f32_bf16 v194, v2, v114, 0
	v_dot2_f32_bf16 v195, v3, v115, 0
	v_dot2c_f32_bf16_e32 v192, v4, v116
	v_dot2c_f32_bf16_e32 v193, v5, v117
	v_add_f32_e32 v156, v152, v153
	v_dot2c_f32_bf16_e32 v194, v6, v118
	v_dot2c_f32_bf16_e32 v195, v7, v119
	v_dot2c_f32_bf16_e32 v192, v8, v120
	v_add_f32_e32 v157, v154, v155
	v_dot2c_f32_bf16_e32 v193, v9, v121
	v_dot2c_f32_bf16_e32 v194, v10, v122
	v_dot2c_f32_bf16_e32 v195, v11, v123
	v_add_f32_e32 v186, v156, v157
	v_dot2c_f32_bf16_e32 v192, v12, v124
	v_dot2c_f32_bf16_e32 v193, v13, v125
	v_dot2c_f32_bf16_e32 v194, v14, v126
	v_dot2c_f32_bf16_e32 v195, v15, v127
	global_load_dwordx2 v[128:129], v163, s[8:9]
	global_load_dwordx2 v[130:131], v163, s[8:9] offset:256
	global_load_dwordx2 v[132:133], v163, s[8:9] offset:512
	global_load_dwordx2 v[134:135], v163, s[8:9] offset:768
	global_load_dwordx2 v[136:137], v163, s[8:9] offset:1024
	global_load_dwordx2 v[138:139], v163, s[8:9] offset:1280
	global_load_dwordx2 v[140:141], v163, s[8:9] offset:1536
	global_load_dwordx2 v[142:143], v163, s[8:9] offset:1792
	s_waitcnt lgkmcnt(0)
	v_mad_u32_u24 v144, v144, s18, v164
	v_mad_u32_u24 v145, v145, s18, v164
	v_mad_u32_u24 v146, v146, s18, v164
	v_mad_u32_u24 v147, v147, s18, v164
	global_load_dwordx4 v[16:19], v144, s[0:1]
	global_load_dwordx2 v[20:21], v144, s[0:1] offset:16
	global_load_dwordx4 v[22:25], v145, s[0:1]
	global_load_dwordx2 v[26:27], v145, s[0:1] offset:16
	global_load_dwordx4 v[28:31], v146, s[0:1]
	global_load_dwordx2 v[32:33], v146, s[0:1] offset:16
	global_load_dwordx4 v[34:37], v147, s[0:1]
	global_load_dwordx2 v[38:39], v147, s[0:1] offset:16
	ds_read2_b32 v[176:177], v168 offset0:32 offset1:40
	ds_read2_b32 v[178:179], v168 offset0:48 offset1:56
	s_waitcnt vmcnt(38)
	v_cvt_scalef32_pk32_bf16_fp6 v[0:15], v[40:45], 1.0
	v_dot2_f32_bf16 v152, v0, v112, 0
	v_dot2_f32_bf16 v153, v1, v113, 0
	v_dot2_f32_bf16 v154, v2, v114, 0
	v_dot2_f32_bf16 v155, v3, v115, 0
	v_dot2c_f32_bf16_e32 v152, v4, v116
	v_dot2c_f32_bf16_e32 v153, v5, v117
	v_add_f32_e32 v156, v192, v193
	v_dot2c_f32_bf16_e32 v154, v6, v118
	v_dot2c_f32_bf16_e32 v155, v7, v119
	v_dot2c_f32_bf16_e32 v152, v8, v120
	v_add_f32_e32 v157, v194, v195
	v_dot2c_f32_bf16_e32 v153, v9, v121
	v_dot2c_f32_bf16_e32 v154, v10, v122
	v_dot2c_f32_bf16_e32 v155, v11, v123
	v_add_f32_e32 v187, v156, v157
	v_dot2c_f32_bf16_e32 v152, v12, v124
	v_dot2c_f32_bf16_e32 v153, v13, v125
	v_dot2c_f32_bf16_e32 v154, v14, v126
	v_dot2c_f32_bf16_e32 v155, v15, v127
	s_waitcnt vmcnt(36)
	v_cvt_scalef32_pk32_bf16_fp6 v[0:15], v[46:51], 1.0
	v_dot2_f32_bf16 v192, v0, v112, 0
	v_dot2_f32_bf16 v193, v1, v113, 0
	v_dot2_f32_bf16 v194, v2, v114, 0
	v_dot2_f32_bf16 v195, v3, v115, 0
	v_dot2c_f32_bf16_e32 v192, v4, v116
	v_dot2c_f32_bf16_e32 v193, v5, v117
	v_add_f32_e32 v156, v152, v153
	v_dot2c_f32_bf16_e32 v194, v6, v118
	v_dot2c_f32_bf16_e32 v195, v7, v119
	v_dot2c_f32_bf16_e32 v192, v8, v120
	v_add_f32_e32 v157, v154, v155
	v_dot2c_f32_bf16_e32 v193, v9, v121
	v_dot2c_f32_bf16_e32 v194, v10, v122
	v_dot2c_f32_bf16_e32 v195, v11, v123
	v_add_f32_e32 v188, v156, v157
	v_dot2c_f32_bf16_e32 v192, v12, v124
	v_dot2c_f32_bf16_e32 v193, v13, v125
	v_dot2c_f32_bf16_e32 v194, v14, v126
	v_dot2c_f32_bf16_e32 v195, v15, v127
	s_waitcnt vmcnt(34)
	v_cvt_scalef32_pk32_bf16_fp6 v[0:15], v[52:57], 1.0
	v_dot2_f32_bf16 v152, v0, v112, 0
	v_dot2_f32_bf16 v153, v1, v113, 0
	v_dot2_f32_bf16 v154, v2, v114, 0
	v_dot2_f32_bf16 v155, v3, v115, 0
	v_dot2c_f32_bf16_e32 v152, v4, v116
	v_dot2c_f32_bf16_e32 v153, v5, v117
	v_add_f32_e32 v156, v192, v193
	v_dot2c_f32_bf16_e32 v154, v6, v118
	v_dot2c_f32_bf16_e32 v155, v7, v119
	v_dot2c_f32_bf16_e32 v152, v8, v120
	v_add_f32_e32 v157, v194, v195
	v_dot2c_f32_bf16_e32 v153, v9, v121
	v_dot2c_f32_bf16_e32 v154, v10, v122
	v_dot2c_f32_bf16_e32 v155, v11, v123
	v_add_f32_e32 v189, v156, v157
	v_dot2c_f32_bf16_e32 v152, v12, v124
	v_dot2c_f32_bf16_e32 v153, v13, v125
	v_dot2c_f32_bf16_e32 v154, v14, v126
	v_dot2c_f32_bf16_e32 v155, v15, v127
	s_waitcnt vmcnt(32)
	v_cvt_scalef32_pk32_bf16_fp6 v[0:15], v[58:63], 1.0
	v_dot2_f32_bf16 v192, v0, v112, 0
	v_dot2_f32_bf16 v193, v1, v113, 0
	v_dot2_f32_bf16 v194, v2, v114, 0
	v_dot2_f32_bf16 v195, v3, v115, 0
	v_dot2c_f32_bf16_e32 v192, v4, v116
	v_dot2c_f32_bf16_e32 v193, v5, v117
	v_add_f32_e32 v156, v152, v153
	v_dot2c_f32_bf16_e32 v194, v6, v118
	v_dot2c_f32_bf16_e32 v195, v7, v119
	v_dot2c_f32_bf16_e32 v192, v8, v120
	v_add_f32_e32 v157, v154, v155
	v_dot2c_f32_bf16_e32 v193, v9, v121
	v_dot2c_f32_bf16_e32 v194, v10, v122
	v_dot2c_f32_bf16_e32 v195, v11, v123
	v_add_f32_e32 v190, v156, v157
	v_dot2c_f32_bf16_e32 v192, v12, v124
	v_dot2c_f32_bf16_e32 v193, v13, v125
	v_dot2c_f32_bf16_e32 v194, v14, v126
	v_dot2c_f32_bf16_e32 v195, v15, v127
	s_nop 1
	v_add_f32_e32 v156, v192, v193
	v_add_f32_e32 v157, v194, v195
	v_add_f32_e32 v191, v156, v157
	v_add_f32_dpp v184, v184, v184 row_half_mirror row_mask:0xf bank_mask:0x5
	v_add_f32_dpp v185, v185, v185 row_half_mirror row_mask:0xf bank_mask:0x5
	v_add_f32_dpp v186, v186, v186 row_half_mirror row_mask:0xf bank_mask:0x5
	v_add_f32_dpp v187, v187, v187 row_half_mirror row_mask:0xf bank_mask:0x5
	v_add_f32_dpp v184, v188, v188 row_half_mirror row_mask:0xf bank_mask:0xa
	v_add_f32_dpp v185, v189, v189 row_half_mirror row_mask:0xf bank_mask:0xa
	v_add_f32_dpp v186, v190, v190 row_half_mirror row_mask:0xf bank_mask:0xa
	v_add_f32_dpp v187, v191, v191 row_half_mirror row_mask:0xf bank_mask:0xa
	v_add_f32_dpp v184, v184, v184 quad_perm:[1,0,3,2] row_mask:0xf bank_mask:0xf
	v_add_f32_dpp v185, v185, v185 quad_perm:[1,0,3,2] row_mask:0xf bank_mask:0xf
	v_add_f32_dpp v186, v186, v186 quad_perm:[1,0,3,2] row_mask:0xf bank_mask:0xf
	v_add_f32_dpp v187, v187, v187 quad_perm:[1,0,3,2] row_mask:0xf bank_mask:0xf
	v_add_f32_dpp v184, v184, v184 quad_perm:[2,3,0,1] row_mask:0xf bank_mask:0xf
	v_add_f32_dpp v185, v185, v185 quad_perm:[2,3,0,1] row_mask:0xf bank_mask:0xf
	v_add_f32_dpp v186, v186, v186 quad_perm:[2,3,0,1] row_mask:0xf bank_mask:0xf
	v_add_f32_dpp v187, v187, v187 quad_perm:[2,3,0,1] row_mask:0xf bank_mask:0xf
	v_cndmask_b32_e64 v156, v184, v185, s[10:11]
	v_cndmask_b32_e64 v157, v186, v187, s[10:11]
	v_cndmask_b32_e64 v198, v156, v157, s[100:101]
	s_waitcnt lgkmcnt(0)
	v_mad_u32_u24 v176, v176, s18, v164
	v_mad_u32_u24 v177, v177, s18, v164
	v_mad_u32_u24 v178, v178, s18, v164
	v_mad_u32_u24 v179, v179, s18, v164
	global_load_dwordx4 v[40:43], v176, s[0:1]
	global_load_dwordx2 v[44:45], v176, s[0:1] offset:16
	global_load_dwordx4 v[46:49], v177, s[0:1]
	global_load_dwordx2 v[50:51], v177, s[0:1] offset:16
	global_load_dwordx4 v[52:55], v178, s[0:1]
	global_load_dwordx2 v[56:57], v178, s[0:1] offset:16
	global_load_dwordx4 v[58:61], v179, s[0:1]
	global_load_dwordx2 v[62:63], v179, s[0:1] offset:16
	ds_add_f32 v169, v198 offset:0
	ds_read2_b32 v[144:145], v168 offset0:64 offset1:72
	ds_read2_b32 v[146:147], v168 offset0:80 offset1:88
	s_waitcnt vmcnt(38)
	v_cvt_scalef32_pk32_bf16_fp6 v[0:15], v[64:69], 1.0
	v_dot2_f32_bf16 v152, v0, v112, 0
	v_dot2_f32_bf16 v153, v1, v113, 0
	v_dot2_f32_bf16 v154, v2, v114, 0
	v_dot2_f32_bf16 v155, v3, v115, 0
	v_dot2c_f32_bf16_e32 v152, v4, v116
	v_dot2c_f32_bf16_e32 v153, v5, v117
	v_dot2c_f32_bf16_e32 v154, v6, v118
	v_dot2c_f32_bf16_e32 v155, v7, v119
	v_dot2c_f32_bf16_e32 v152, v8, v120
	v_dot2c_f32_bf16_e32 v153, v9, v121
	v_dot2c_f32_bf16_e32 v154, v10, v122
	v_dot2c_f32_bf16_e32 v155, v11, v123
	v_dot2c_f32_bf16_e32 v152, v12, v124
	v_dot2c_f32_bf16_e32 v153, v13, v125
	v_dot2c_f32_bf16_e32 v154, v14, v126
	v_dot2c_f32_bf16_e32 v155, v15, v127
	s_waitcnt vmcnt(36)
	v_cvt_scalef32_pk32_bf16_fp6 v[0:15], v[70:75], 1.0
	v_dot2_f32_bf16 v192, v0, v112, 0
	v_dot2_f32_bf16 v193, v1, v113, 0
	v_dot2_f32_bf16 v194, v2, v114, 0
	v_dot2_f32_bf16 v195, v3, v115, 0
	v_dot2c_f32_bf16_e32 v192, v4, v116
	v_dot2c_f32_bf16_e32 v193, v5, v117
	v_add_f32_e32 v156, v152, v153
	v_dot2c_f32_bf16_e32 v194, v6, v118
	v_dot2c_f32_bf16_e32 v195, v7, v119
	v_dot2c_f32_bf16_e32 v192, v8, v120
	v_add_f32_e32 v157, v154, v155
	v_dot2c_f32_bf16_e32 v193, v9, v121
	v_dot2c_f32_bf16_e32 v194, v10, v122
	v_dot2c_f32_bf16_e32 v195, v11, v123
	v_add_f32_e32 v184, v156, v157
	v_dot2c_f32_bf16_e32 v192, v12, v124
	v_dot2c_f32_bf16_e32 v193, v13, v125
	v_dot2c_f32_bf16_e32 v194, v14, v126
	v_dot2c_f32_bf16_e32 v195, v15, v127
	s_waitcnt vmcnt(34)
	v_cvt_scalef32_pk32_bf16_fp6 v[0:15], v[76:81], 1.0
	v_dot2_f32_bf16 v152, v0, v112, 0
	v_dot2_f32_bf16 v153, v1, v113, 0
	v_dot2_f32_bf16 v154, v2, v114, 0
	v_dot2_f32_bf16 v155, v3, v115, 0
	v_dot2c_f32_bf16_e32 v152, v4, v116
	v_dot2c_f32_bf16_e32 v153, v5, v117
	v_add_f32_e32 v156, v192, v193
	v_dot2c_f32_bf16_e32 v154, v6, v118
	v_dot2c_f32_bf16_e32 v155, v7, v119
	v_dot2c_f32_bf16_e32 v152, v8, v120
	v_add_f32_e32 v157, v194, v195
	v_dot2c_f32_bf16_e32 v153, v9, v121
	v_dot2c_f32_bf16_e32 v154, v10, v122
	v_dot2c_f32_bf16_e32 v155, v11, v123
	v_add_f32_e32 v185, v156, v157
	v_dot2c_f32_bf16_e32 v152, v12, v124
	v_dot2c_f32_bf16_e32 v153, v13, v125
	v_dot2c_f32_bf16_e32 v154, v14, v126
	v_dot2c_f32_bf16_e32 v155, v15, v127
	s_waitcnt vmcnt(32)
	v_cvt_scalef32_pk32_bf16_fp6 v[0:15], v[82:87], 1.0
	v_dot2_f32_bf16 v192, v0, v112, 0
	v_dot2_f32_bf16 v193, v1, v113, 0
	v_dot2_f32_bf16 v194, v2, v114, 0
	v_dot2_f32_bf16 v195, v3, v115, 0
	v_dot2c_f32_bf16_e32 v192, v4, v116
	v_dot2c_f32_bf16_e32 v193, v5, v117
	v_add_f32_e32 v156, v152, v153
	v_dot2c_f32_bf16_e32 v194, v6, v118
	v_dot2c_f32_bf16_e32 v195, v7, v119
	v_dot2c_f32_bf16_e32 v192, v8, v120
	v_add_f32_e32 v157, v154, v155
	v_dot2c_f32_bf16_e32 v193, v9, v121
	v_dot2c_f32_bf16_e32 v194, v10, v122
	v_dot2c_f32_bf16_e32 v195, v11, v123
	v_add_f32_e32 v186, v156, v157
	v_dot2c_f32_bf16_e32 v192, v12, v124
	v_dot2c_f32_bf16_e32 v193, v13, v125
	v_dot2c_f32_bf16_e32 v194, v14, v126
	v_dot2c_f32_bf16_e32 v195, v15, v127
	s_waitcnt lgkmcnt(0)
	v_mad_u32_u24 v144, v144, s18, v164
	v_mad_u32_u24 v145, v145, s18, v164
	v_mad_u32_u24 v146, v146, s18, v164
	v_mad_u32_u24 v147, v147, s18, v164
	global_load_dwordx4 v[64:67], v144, s[0:1]
	global_load_dwordx2 v[68:69], v144, s[0:1] offset:16
	global_load_dwordx4 v[70:73], v145, s[0:1]
	global_load_dwordx2 v[74:75], v145, s[0:1] offset:16
	global_load_dwordx4 v[76:79], v146, s[0:1]
	global_load_dwordx2 v[80:81], v146, s[0:1] offset:16
	global_load_dwordx4 v[82:85], v147, s[0:1]
	global_load_dwordx2 v[86:87], v147, s[0:1] offset:16
	ds_read2_b32 v[176:177], v168 offset0:96 offset1:104
	ds_read2_b32 v[178:179], v168 offset0:112 offset1:120
	s_waitcnt vmcnt(38)
	v_cvt_scalef32_pk32_bf16_fp6 v[0:15], v[88:93], 1.0
	v_dot2_f32_bf16 v152, v0, v112, 0
	v_dot2_f32_bf16 v153, v1, v113, 0
	v_dot2_f32_bf16 v154, v2, v114, 0
	v_dot2_f32_bf16 v155, v3, v115, 0
	v_dot2c_f32_bf16_e32 v152, v4, v116
	v_dot2c_f32_bf16_e32 v153, v5, v117
	v_add_f32_e32 v156, v192, v193
	v_dot2c_f32_bf16_e32 v154, v6, v118
	v_dot2c_f32_bf16_e32 v155, v7, v119
	v_dot2c_f32_bf16_e32 v152, v8, v120
	v_add_f32_e32 v157, v194, v195
	v_dot2c_f32_bf16_e32 v153, v9, v121
	v_dot2c_f32_bf16_e32 v154, v10, v122
	v_dot2c_f32_bf16_e32 v155, v11, v123
	v_add_f32_e32 v187, v156, v157
	v_dot2c_f32_bf16_e32 v152, v12, v124
	v_dot2c_f32_bf16_e32 v153, v13, v125
	v_dot2c_f32_bf16_e32 v154, v14, v126
	v_dot2c_f32_bf16_e32 v155, v15, v127
	s_waitcnt vmcnt(36)
	v_cvt_scalef32_pk32_bf16_fp6 v[0:15], v[94:99], 1.0
	v_dot2_f32_bf16 v192, v0, v112, 0
	v_dot2_f32_bf16 v193, v1, v113, 0
	v_dot2_f32_bf16 v194, v2, v114, 0
	v_dot2_f32_bf16 v195, v3, v115, 0
	v_dot2c_f32_bf16_e32 v192, v4, v116
	v_dot2c_f32_bf16_e32 v193, v5, v117
	v_add_f32_e32 v156, v152, v153
	v_dot2c_f32_bf16_e32 v194, v6, v118
	v_dot2c_f32_bf16_e32 v195, v7, v119
	v_dot2c_f32_bf16_e32 v192, v8, v120
	v_add_f32_e32 v157, v154, v155
	v_dot2c_f32_bf16_e32 v193, v9, v121
	v_dot2c_f32_bf16_e32 v194, v10, v122
	v_dot2c_f32_bf16_e32 v195, v11, v123
	v_add_f32_e32 v188, v156, v157
	v_dot2c_f32_bf16_e32 v192, v12, v124
	v_dot2c_f32_bf16_e32 v193, v13, v125
	v_dot2c_f32_bf16_e32 v194, v14, v126
	v_dot2c_f32_bf16_e32 v195, v15, v127
	s_waitcnt vmcnt(34)
	v_cvt_scalef32_pk32_bf16_fp6 v[0:15], v[100:105], 1.0
	v_dot2_f32_bf16 v152, v0, v112, 0
	v_dot2_f32_bf16 v153, v1, v113, 0
	v_dot2_f32_bf16 v154, v2, v114, 0
	v_dot2_f32_bf16 v155, v3, v115, 0
	v_dot2c_f32_bf16_e32 v152, v4, v116
	v_dot2c_f32_bf16_e32 v153, v5, v117
	v_add_f32_e32 v156, v192, v193
	v_dot2c_f32_bf16_e32 v154, v6, v118
	v_dot2c_f32_bf16_e32 v155, v7, v119
	v_dot2c_f32_bf16_e32 v152, v8, v120
	v_add_f32_e32 v157, v194, v195
	v_dot2c_f32_bf16_e32 v153, v9, v121
	v_dot2c_f32_bf16_e32 v154, v10, v122
	v_dot2c_f32_bf16_e32 v155, v11, v123
	v_add_f32_e32 v189, v156, v157
	v_dot2c_f32_bf16_e32 v152, v12, v124
	v_dot2c_f32_bf16_e32 v153, v13, v125
	v_dot2c_f32_bf16_e32 v154, v14, v126
	v_dot2c_f32_bf16_e32 v155, v15, v127
	s_waitcnt vmcnt(32)
	v_cvt_scalef32_pk32_bf16_fp6 v[0:15], v[106:111], 1.0
	v_dot2_f32_bf16 v192, v0, v112, 0
	v_dot2_f32_bf16 v193, v1, v113, 0
	v_dot2_f32_bf16 v194, v2, v114, 0
	v_dot2_f32_bf16 v195, v3, v115, 0
	v_dot2c_f32_bf16_e32 v192, v4, v116
	v_dot2c_f32_bf16_e32 v193, v5, v117
	v_add_f32_e32 v156, v152, v153
	v_dot2c_f32_bf16_e32 v194, v6, v118
	v_dot2c_f32_bf16_e32 v195, v7, v119
	v_dot2c_f32_bf16_e32 v192, v8, v120
	v_add_f32_e32 v157, v154, v155
	v_dot2c_f32_bf16_e32 v193, v9, v121
	v_dot2c_f32_bf16_e32 v194, v10, v122
	v_dot2c_f32_bf16_e32 v195, v11, v123
	v_add_f32_e32 v190, v156, v157
	v_dot2c_f32_bf16_e32 v192, v12, v124
	v_dot2c_f32_bf16_e32 v193, v13, v125
	v_dot2c_f32_bf16_e32 v194, v14, v126
	v_dot2c_f32_bf16_e32 v195, v15, v127
	s_nop 1
	v_add_f32_e32 v156, v192, v193
	v_add_f32_e32 v157, v194, v195
	v_add_f32_e32 v191, v156, v157
	v_add_f32_dpp v184, v184, v184 row_half_mirror row_mask:0xf bank_mask:0x5
	v_add_f32_dpp v185, v185, v185 row_half_mirror row_mask:0xf bank_mask:0x5
	v_add_f32_dpp v186, v186, v186 row_half_mirror row_mask:0xf bank_mask:0x5
	v_add_f32_dpp v187, v187, v187 row_half_mirror row_mask:0xf bank_mask:0x5
	v_add_f32_dpp v184, v188, v188 row_half_mirror row_mask:0xf bank_mask:0xa
	v_add_f32_dpp v185, v189, v189 row_half_mirror row_mask:0xf bank_mask:0xa
	v_add_f32_dpp v186, v190, v190 row_half_mirror row_mask:0xf bank_mask:0xa
	v_add_f32_dpp v187, v191, v191 row_half_mirror row_mask:0xf bank_mask:0xa
	v_add_f32_dpp v184, v184, v184 quad_perm:[1,0,3,2] row_mask:0xf bank_mask:0xf
	v_add_f32_dpp v185, v185, v185 quad_perm:[1,0,3,2] row_mask:0xf bank_mask:0xf
	v_add_f32_dpp v186, v186, v186 quad_perm:[1,0,3,2] row_mask:0xf bank_mask:0xf
	v_add_f32_dpp v187, v187, v187 quad_perm:[1,0,3,2] row_mask:0xf bank_mask:0xf
	v_add_f32_dpp v184, v184, v184 quad_perm:[2,3,0,1] row_mask:0xf bank_mask:0xf
	v_add_f32_dpp v185, v185, v185 quad_perm:[2,3,0,1] row_mask:0xf bank_mask:0xf
	v_add_f32_dpp v186, v186, v186 quad_perm:[2,3,0,1] row_mask:0xf bank_mask:0xf
	v_add_f32_dpp v187, v187, v187 quad_perm:[2,3,0,1] row_mask:0xf bank_mask:0xf
	v_cndmask_b32_e64 v156, v184, v185, s[10:11]
	v_cndmask_b32_e64 v157, v186, v187, s[10:11]
	v_cndmask_b32_e64 v198, v156, v157, s[100:101]
	s_waitcnt lgkmcnt(0)
	v_mad_u32_u24 v176, v176, s18, v164
	v_mad_u32_u24 v177, v177, s18, v164
	v_mad_u32_u24 v178, v178, s18, v164
	v_mad_u32_u24 v179, v179, s18, v164
	global_load_dwordx4 v[88:91], v176, s[0:1]
	global_load_dwordx2 v[92:93], v176, s[0:1] offset:16
	global_load_dwordx4 v[94:97], v177, s[0:1]
	global_load_dwordx2 v[98:99], v177, s[0:1] offset:16
	global_load_dwordx4 v[100:103], v178, s[0:1]
	global_load_dwordx2 v[104:105], v178, s[0:1] offset:16
	global_load_dwordx4 v[106:109], v179, s[0:1]
	global_load_dwordx2 v[110:111], v179, s[0:1] offset:16
	ds_add_f32 v169, v198 offset:256
	s_add_u32 s12, s12, 1
	s_and_b32 s12, s12, 63
	s_add_u32 s14, s12, 1
	s_and_b32 s38, s14, 63
	s_and_b32 s15, s38, 15
	s_lshr_b32 s16, s38, 4
	s_lshl_b32 s17, s15, 9
	s_mul_i32 s13, s15, s19
	s_lshl_b32 s14, s16, 6
	s_add_u32 s13, s13, s14
	s_add_u32 s6, s4, s13
	s_addc_u32 s7, s5, 0
	s_mul_i32 s13, s16, 0x300000
	s_add_u32 s0, s26, 0x2800000
	s_addc_u32 s1, s27, 0
	s_add_u32 s0, s0, s13
	s_addc_u32 s1, s1, 0
	v_add_u32_e32 v167, s17, v161
	ds_read2_b32 v[144:145], v167 offset0:0 offset1:8
	ds_read2_b32 v[146:147], v167 offset0:16 offset1:24
	s_and_b32 s15, s12, 15
	s_lshl_b32 s17, s15, 9
	v_add_u32_e32 v170, s17, v162
	s_waitcnt vmcnt(30)
	v_cvt_scalef32_pk32_bf16_fp6 v[0:15], v[16:21], 1.0
	v_dot2_f32_bf16 v152, v0, v128, 0
	v_dot2_f32_bf16 v153, v1, v129, 0
	v_dot2_f32_bf16 v154, v2, v130, 0
	v_dot2_f32_bf16 v155, v3, v131, 0
	v_dot2c_f32_bf16_e32 v152, v4, v132
	v_dot2c_f32_bf16_e32 v153, v5, v133
	v_dot2c_f32_bf16_e32 v154, v6, v134
	v_dot2c_f32_bf16_e32 v155, v7, v135
	v_dot2c_f32_bf16_e32 v152, v8, v136
	v_dot2c_f32_bf16_e32 v153, v9, v137
	v_dot2c_f32_bf16_e32 v154, v10, v138
	v_dot2c_f32_bf16_e32 v155, v11, v139
	v_dot2c_f32_bf16_e32 v152, v12, v140
	v_dot2c_f32_bf16_e32 v153, v13, v141
	v_dot2c_f32_bf16_e32 v154, v14, v142
	v_dot2c_f32_bf16_e32 v155, v15, v143
	s_waitcnt vmcnt(28)
	v_cvt_scalef32_pk32_bf16_fp6 v[0:15], v[22:27], 1.0
	v_dot2_f32_bf16 v192, v0, v128, 0
	v_dot2_f32_bf16 v193, v1, v129, 0
	v_dot2_f32_bf16 v194, v2, v130, 0
	v_dot2_f32_bf16 v195, v3, v131, 0
	v_dot2c_f32_bf16_e32 v192, v4, v132
	v_dot2c_f32_bf16_e32 v193, v5, v133
	v_add_f32_e32 v156, v152, v153
	v_dot2c_f32_bf16_e32 v194, v6, v134
	v_dot2c_f32_bf16_e32 v195, v7, v135
	v_dot2c_f32_bf16_e32 v192, v8, v136
	v_add_f32_e32 v157, v154, v155
	v_dot2c_f32_bf16_e32 v193, v9, v137
	v_dot2c_f32_bf16_e32 v194, v10, v138
	v_dot2c_f32_bf16_e32 v195, v11, v139
	v_add_f32_e32 v184, v156, v157
	v_dot2c_f32_bf16_e32 v192, v12, v140
	v_dot2c_f32_bf16_e32 v193, v13, v141
	v_dot2c_f32_bf16_e32 v194, v14, v142
	v_dot2c_f32_bf16_e32 v195, v15, v143
	s_waitcnt vmcnt(26)
	v_cvt_scalef32_pk32_bf16_fp6 v[0:15], v[28:33], 1.0
	v_dot2_f32_bf16 v152, v0, v128, 0
	v_dot2_f32_bf16 v153, v1, v129, 0
	v_dot2_f32_bf16 v154, v2, v130, 0
	v_dot2_f32_bf16 v155, v3, v131, 0
	v_dot2c_f32_bf16_e32 v152, v4, v132
	v_dot2c_f32_bf16_e32 v153, v5, v133
	v_add_f32_e32 v156, v192, v193
	v_dot2c_f32_bf16_e32 v154, v6, v134
	v_dot2c_f32_bf16_e32 v155, v7, v135
	v_dot2c_f32_bf16_e32 v152, v8, v136
	v_add_f32_e32 v157, v194, v195
	v_dot2c_f32_bf16_e32 v153, v9, v137
	v_dot2c_f32_bf16_e32 v154, v10, v138
	v_dot2c_f32_bf16_e32 v155, v11, v139
	v_add_f32_e32 v185, v156, v157
	v_dot2c_f32_bf16_e32 v152, v12, v140
	v_dot2c_f32_bf16_e32 v153, v13, v141
	v_dot2c_f32_bf16_e32 v154, v14, v142
	v_dot2c_f32_bf16_e32 v155, v15, v143
	s_waitcnt vmcnt(24)
	v_cvt_scalef32_pk32_bf16_fp6 v[0:15], v[34:39], 1.0
	v_dot2_f32_bf16 v192, v0, v128, 0
	v_dot2_f32_bf16 v193, v1, v129, 0
	v_dot2_f32_bf16 v194, v2, v130, 0
	v_dot2_f32_bf16 v195, v3, v131, 0
	v_dot2c_f32_bf16_e32 v192, v4, v132
	v_dot2c_f32_bf16_e32 v193, v5, v133
	v_add_f32_e32 v156, v152, v153
	v_dot2c_f32_bf16_e32 v194, v6, v134
	v_dot2c_f32_bf16_e32 v195, v7, v135
	v_dot2c_f32_bf16_e32 v192, v8, v136
	v_add_f32_e32 v157, v154, v155
	v_dot2c_f32_bf16_e32 v193, v9, v137
	v_dot2c_f32_bf16_e32 v194, v10, v138
	v_dot2c_f32_bf16_e32 v195, v11, v139
	v_add_f32_e32 v186, v156, v157
	v_dot2c_f32_bf16_e32 v192, v12, v140
	v_dot2c_f32_bf16_e32 v193, v13, v141
	v_dot2c_f32_bf16_e32 v194, v14, v142
	v_dot2c_f32_bf16_e32 v195, v15, v143
	global_load_dwordx2 v[112:113], v163, s[6:7]
	global_load_dwordx2 v[114:115], v163, s[6:7] offset:256
	global_load_dwordx2 v[116:117], v163, s[6:7] offset:512
	global_load_dwordx2 v[118:119], v163, s[6:7] offset:768
	global_load_dwordx2 v[120:121], v163, s[6:7] offset:1024
	global_load_dwordx2 v[122:123], v163, s[6:7] offset:1280
	global_load_dwordx2 v[124:125], v163, s[6:7] offset:1536
	global_load_dwordx2 v[126:127], v163, s[6:7] offset:1792
	s_waitcnt lgkmcnt(0)
	v_mad_u32_u24 v144, v144, s18, v164
	v_mad_u32_u24 v145, v145, s18, v164
	v_mad_u32_u24 v146, v146, s18, v164
	v_mad_u32_u24 v147, v147, s18, v164
	global_load_dwordx4 v[16:19], v144, s[0:1]
	global_load_dwordx2 v[20:21], v144, s[0:1] offset:16
	global_load_dwordx4 v[22:25], v145, s[0:1]
	global_load_dwordx2 v[26:27], v145, s[0:1] offset:16
	global_load_dwordx4 v[28:31], v146, s[0:1]
	global_load_dwordx2 v[32:33], v146, s[0:1] offset:16
	global_load_dwordx4 v[34:37], v147, s[0:1]
	global_load_dwordx2 v[38:39], v147, s[0:1] offset:16
	ds_read2_b32 v[176:177], v167 offset0:32 offset1:40
	ds_read2_b32 v[178:179], v167 offset0:48 offset1:56
	s_waitcnt vmcnt(38)
	v_cvt_scalef32_pk32_bf16_fp6 v[0:15], v[40:45], 1.0
	v_dot2_f32_bf16 v152, v0, v128, 0
	v_dot2_f32_bf16 v153, v1, v129, 0
	v_dot2_f32_bf16 v154, v2, v130, 0
	v_dot2_f32_bf16 v155, v3, v131, 0
	v_dot2c_f32_bf16_e32 v152, v4, v132
	v_dot2c_f32_bf16_e32 v153, v5, v133
	v_add_f32_e32 v156, v192, v193
	v_dot2c_f32_bf16_e32 v154, v6, v134
	v_dot2c_f32_bf16_e32 v155, v7, v135
	v_dot2c_f32_bf16_e32 v152, v8, v136
	v_add_f32_e32 v157, v194, v195
	v_dot2c_f32_bf16_e32 v153, v9, v137
	v_dot2c_f32_bf16_e32 v154, v10, v138
	v_dot2c_f32_bf16_e32 v155, v11, v139
	v_add_f32_e32 v187, v156, v157
	v_dot2c_f32_bf16_e32 v152, v12, v140
	v_dot2c_f32_bf16_e32 v153, v13, v141
	v_dot2c_f32_bf16_e32 v154, v14, v142
	v_dot2c_f32_bf16_e32 v155, v15, v143
	s_waitcnt vmcnt(36)
	v_cvt_scalef32_pk32_bf16_fp6 v[0:15], v[46:51], 1.0
	v_dot2_f32_bf16 v192, v0, v128, 0
	v_dot2_f32_bf16 v193, v1, v129, 0
	v_dot2_f32_bf16 v194, v2, v130, 0
	v_dot2_f32_bf16 v195, v3, v131, 0
	v_dot2c_f32_bf16_e32 v192, v4, v132
	v_dot2c_f32_bf16_e32 v193, v5, v133
	v_add_f32_e32 v156, v152, v153
	v_dot2c_f32_bf16_e32 v194, v6, v134
	v_dot2c_f32_bf16_e32 v195, v7, v135
	v_dot2c_f32_bf16_e32 v192, v8, v136
	v_add_f32_e32 v157, v154, v155
	v_dot2c_f32_bf16_e32 v193, v9, v137
	v_dot2c_f32_bf16_e32 v194, v10, v138
	v_dot2c_f32_bf16_e32 v195, v11, v139
	v_add_f32_e32 v188, v156, v157
	v_dot2c_f32_bf16_e32 v192, v12, v140
	v_dot2c_f32_bf16_e32 v193, v13, v141
	v_dot2c_f32_bf16_e32 v194, v14, v142
	v_dot2c_f32_bf16_e32 v195, v15, v143
	s_waitcnt vmcnt(34)
	v_cvt_scalef32_pk32_bf16_fp6 v[0:15], v[52:57], 1.0
	v_dot2_f32_bf16 v152, v0, v128, 0
	v_dot2_f32_bf16 v153, v1, v129, 0
	v_dot2_f32_bf16 v154, v2, v130, 0
	v_dot2_f32_bf16 v155, v3, v131, 0
	v_dot2c_f32_bf16_e32 v152, v4, v132
	v_dot2c_f32_bf16_e32 v153, v5, v133
	v_add_f32_e32 v156, v192, v193
	v_dot2c_f32_bf16_e32 v154, v6, v134
	v_dot2c_f32_bf16_e32 v155, v7, v135
	v_dot2c_f32_bf16_e32 v152, v8, v136
	v_add_f32_e32 v157, v194, v195
	v_dot2c_f32_bf16_e32 v153, v9, v137
	v_dot2c_f32_bf16_e32 v154, v10, v138
	v_dot2c_f32_bf16_e32 v155, v11, v139
	v_add_f32_e32 v189, v156, v157
	v_dot2c_f32_bf16_e32 v152, v12, v140
	v_dot2c_f32_bf16_e32 v153, v13, v141
	v_dot2c_f32_bf16_e32 v154, v14, v142
	v_dot2c_f32_bf16_e32 v155, v15, v143
	s_waitcnt vmcnt(32)
	v_cvt_scalef32_pk32_bf16_fp6 v[0:15], v[58:63], 1.0
	v_dot2_f32_bf16 v192, v0, v128, 0
	v_dot2_f32_bf16 v193, v1, v129, 0
	v_dot2_f32_bf16 v194, v2, v130, 0
	v_dot2_f32_bf16 v195, v3, v131, 0
	v_dot2c_f32_bf16_e32 v192, v4, v132
	v_dot2c_f32_bf16_e32 v193, v5, v133
	v_add_f32_e32 v156, v152, v153
	v_dot2c_f32_bf16_e32 v194, v6, v134
	v_dot2c_f32_bf16_e32 v195, v7, v135
	v_dot2c_f32_bf16_e32 v192, v8, v136
	v_add_f32_e32 v157, v154, v155
	v_dot2c_f32_bf16_e32 v193, v9, v137
	v_dot2c_f32_bf16_e32 v194, v10, v138
	v_dot2c_f32_bf16_e32 v195, v11, v139
	v_add_f32_e32 v190, v156, v157
	v_dot2c_f32_bf16_e32 v192, v12, v140
	v_dot2c_f32_bf16_e32 v193, v13, v141
	v_dot2c_f32_bf16_e32 v194, v14, v142
	v_dot2c_f32_bf16_e32 v195, v15, v143
	s_nop 1
	v_add_f32_e32 v156, v192, v193
	v_add_f32_e32 v157, v194, v195
	v_add_f32_e32 v191, v156, v157
	v_add_f32_dpp v184, v184, v184 row_half_mirror row_mask:0xf bank_mask:0x5
	v_add_f32_dpp v185, v185, v185 row_half_mirror row_mask:0xf bank_mask:0x5
	v_add_f32_dpp v186, v186, v186 row_half_mirror row_mask:0xf bank_mask:0x5
	v_add_f32_dpp v187, v187, v187 row_half_mirror row_mask:0xf bank_mask:0x5
	v_add_f32_dpp v184, v188, v188 row_half_mirror row_mask:0xf bank_mask:0xa
	v_add_f32_dpp v185, v189, v189 row_half_mirror row_mask:0xf bank_mask:0xa
	v_add_f32_dpp v186, v190, v190 row_half_mirror row_mask:0xf bank_mask:0xa
	v_add_f32_dpp v187, v191, v191 row_half_mirror row_mask:0xf bank_mask:0xa
	v_add_f32_dpp v184, v184, v184 quad_perm:[1,0,3,2] row_mask:0xf bank_mask:0xf
	v_add_f32_dpp v185, v185, v185 quad_perm:[1,0,3,2] row_mask:0xf bank_mask:0xf
	v_add_f32_dpp v186, v186, v186 quad_perm:[1,0,3,2] row_mask:0xf bank_mask:0xf
	v_add_f32_dpp v187, v187, v187 quad_perm:[1,0,3,2] row_mask:0xf bank_mask:0xf
	v_add_f32_dpp v184, v184, v184 quad_perm:[2,3,0,1] row_mask:0xf bank_mask:0xf
	v_add_f32_dpp v185, v185, v185 quad_perm:[2,3,0,1] row_mask:0xf bank_mask:0xf
	v_add_f32_dpp v186, v186, v186 quad_perm:[2,3,0,1] row_mask:0xf bank_mask:0xf
	v_add_f32_dpp v187, v187, v187 quad_perm:[2,3,0,1] row_mask:0xf bank_mask:0xf
	v_cndmask_b32_e64 v156, v184, v185, s[10:11]
	v_cndmask_b32_e64 v157, v186, v187, s[10:11]
	v_cndmask_b32_e64 v198, v156, v157, s[100:101]
	s_waitcnt lgkmcnt(0)
	v_mad_u32_u24 v176, v176, s18, v164
	v_mad_u32_u24 v177, v177, s18, v164
	v_mad_u32_u24 v178, v178, s18, v164
	v_mad_u32_u24 v179, v179, s18, v164
	global_load_dwordx4 v[40:43], v176, s[0:1]
	global_load_dwordx2 v[44:45], v176, s[0:1] offset:16
	global_load_dwordx4 v[46:49], v177, s[0:1]
	global_load_dwordx2 v[50:51], v177, s[0:1] offset:16
	global_load_dwordx4 v[52:55], v178, s[0:1]
	global_load_dwordx2 v[56:57], v178, s[0:1] offset:16
	global_load_dwordx4 v[58:61], v179, s[0:1]
	global_load_dwordx2 v[62:63], v179, s[0:1] offset:16
	ds_add_f32 v170, v198 offset:0
	ds_read2_b32 v[144:145], v167 offset0:64 offset1:72
	ds_read2_b32 v[146:147], v167 offset0:80 offset1:88
	s_waitcnt vmcnt(38)
	v_cvt_scalef32_pk32_bf16_fp6 v[0:15], v[64:69], 1.0
	v_dot2_f32_bf16 v152, v0, v128, 0
	v_dot2_f32_bf16 v153, v1, v129, 0
	v_dot2_f32_bf16 v154, v2, v130, 0
	v_dot2_f32_bf16 v155, v3, v131, 0
	v_dot2c_f32_bf16_e32 v152, v4, v132
	v_dot2c_f32_bf16_e32 v153, v5, v133
	v_dot2c_f32_bf16_e32 v154, v6, v134
	v_dot2c_f32_bf16_e32 v155, v7, v135
	v_dot2c_f32_bf16_e32 v152, v8, v136
	v_dot2c_f32_bf16_e32 v153, v9, v137
	v_dot2c_f32_bf16_e32 v154, v10, v138
	v_dot2c_f32_bf16_e32 v155, v11, v139
	v_dot2c_f32_bf16_e32 v152, v12, v140
	v_dot2c_f32_bf16_e32 v153, v13, v141
	v_dot2c_f32_bf16_e32 v154, v14, v142
	v_dot2c_f32_bf16_e32 v155, v15, v143
	s_waitcnt vmcnt(36)
	v_cvt_scalef32_pk32_bf16_fp6 v[0:15], v[70:75], 1.0
	v_dot2_f32_bf16 v192, v0, v128, 0
	v_dot2_f32_bf16 v193, v1, v129, 0
	v_dot2_f32_bf16 v194, v2, v130, 0
	v_dot2_f32_bf16 v195, v3, v131, 0
	v_dot2c_f32_bf16_e32 v192, v4, v132
	v_dot2c_f32_bf16_e32 v193, v5, v133
	v_add_f32_e32 v156, v152, v153
	v_dot2c_f32_bf16_e32 v194, v6, v134
	v_dot2c_f32_bf16_e32 v195, v7, v135
	v_dot2c_f32_bf16_e32 v192, v8, v136
	v_add_f32_e32 v157, v154, v155
	v_dot2c_f32_bf16_e32 v193, v9, v137
	v_dot2c_f32_bf16_e32 v194, v10, v138
	v_dot2c_f32_bf16_e32 v195, v11, v139
	v_add_f32_e32 v184, v156, v157
	v_dot2c_f32_bf16_e32 v192, v12, v140
	v_dot2c_f32_bf16_e32 v193, v13, v141
	v_dot2c_f32_bf16_e32 v194, v14, v142
	v_dot2c_f32_bf16_e32 v195, v15, v143
	s_waitcnt vmcnt(34)
	v_cvt_scalef32_pk32_bf16_fp6 v[0:15], v[76:81], 1.0
	v_dot2_f32_bf16 v152, v0, v128, 0
	v_dot2_f32_bf16 v153, v1, v129, 0
	v_dot2_f32_bf16 v154, v2, v130, 0
	v_dot2_f32_bf16 v155, v3, v131, 0
	v_dot2c_f32_bf16_e32 v152, v4, v132
	v_dot2c_f32_bf16_e32 v153, v5, v133
	v_add_f32_e32 v156, v192, v193
	v_dot2c_f32_bf16_e32 v154, v6, v134
	v_dot2c_f32_bf16_e32 v155, v7, v135
	v_dot2c_f32_bf16_e32 v152, v8, v136
	v_add_f32_e32 v157, v194, v195
	v_dot2c_f32_bf16_e32 v153, v9, v137
	v_dot2c_f32_bf16_e32 v154, v10, v138
	v_dot2c_f32_bf16_e32 v155, v11, v139
	v_add_f32_e32 v185, v156, v157
	v_dot2c_f32_bf16_e32 v152, v12, v140
	v_dot2c_f32_bf16_e32 v153, v13, v141
	v_dot2c_f32_bf16_e32 v154, v14, v142
	v_dot2c_f32_bf16_e32 v155, v15, v143
	s_waitcnt vmcnt(32)
	v_cvt_scalef32_pk32_bf16_fp6 v[0:15], v[82:87], 1.0
	v_dot2_f32_bf16 v192, v0, v128, 0
	v_dot2_f32_bf16 v193, v1, v129, 0
	v_dot2_f32_bf16 v194, v2, v130, 0
	v_dot2_f32_bf16 v195, v3, v131, 0
	v_dot2c_f32_bf16_e32 v192, v4, v132
	v_dot2c_f32_bf16_e32 v193, v5, v133
	v_add_f32_e32 v156, v152, v153
	v_dot2c_f32_bf16_e32 v194, v6, v134
	v_dot2c_f32_bf16_e32 v195, v7, v135
	v_dot2c_f32_bf16_e32 v192, v8, v136
	v_add_f32_e32 v157, v154, v155
	v_dot2c_f32_bf16_e32 v193, v9, v137
	v_dot2c_f32_bf16_e32 v194, v10, v138
	v_dot2c_f32_bf16_e32 v195, v11, v139
	v_add_f32_e32 v186, v156, v157
	v_dot2c_f32_bf16_e32 v192, v12, v140
	v_dot2c_f32_bf16_e32 v193, v13, v141
	v_dot2c_f32_bf16_e32 v194, v14, v142
	v_dot2c_f32_bf16_e32 v195, v15, v143
	s_waitcnt lgkmcnt(0)
	v_mad_u32_u24 v144, v144, s18, v164
	v_mad_u32_u24 v145, v145, s18, v164
	v_mad_u32_u24 v146, v146, s18, v164
	v_mad_u32_u24 v147, v147, s18, v164
	global_load_dwordx4 v[64:67], v144, s[0:1]
	global_load_dwordx2 v[68:69], v144, s[0:1] offset:16
	global_load_dwordx4 v[70:73], v145, s[0:1]
	global_load_dwordx2 v[74:75], v145, s[0:1] offset:16
	global_load_dwordx4 v[76:79], v146, s[0:1]
	global_load_dwordx2 v[80:81], v146, s[0:1] offset:16
	global_load_dwordx4 v[82:85], v147, s[0:1]
	global_load_dwordx2 v[86:87], v147, s[0:1] offset:16
	ds_read2_b32 v[176:177], v167 offset0:96 offset1:104
	ds_read2_b32 v[178:179], v167 offset0:112 offset1:120
	s_waitcnt vmcnt(38)
	v_cvt_scalef32_pk32_bf16_fp6 v[0:15], v[88:93], 1.0
	v_dot2_f32_bf16 v152, v0, v128, 0
	v_dot2_f32_bf16 v153, v1, v129, 0
	v_dot2_f32_bf16 v154, v2, v130, 0
	v_dot2_f32_bf16 v155, v3, v131, 0
	v_dot2c_f32_bf16_e32 v152, v4, v132
	v_dot2c_f32_bf16_e32 v153, v5, v133
	v_add_f32_e32 v156, v192, v193
	v_dot2c_f32_bf16_e32 v154, v6, v134
	v_dot2c_f32_bf16_e32 v155, v7, v135
	v_dot2c_f32_bf16_e32 v152, v8, v136
	v_add_f32_e32 v157, v194, v195
	v_dot2c_f32_bf16_e32 v153, v9, v137
	v_dot2c_f32_bf16_e32 v154, v10, v138
	v_dot2c_f32_bf16_e32 v155, v11, v139
	v_add_f32_e32 v187, v156, v157
	v_dot2c_f32_bf16_e32 v152, v12, v140
	v_dot2c_f32_bf16_e32 v153, v13, v141
	v_dot2c_f32_bf16_e32 v154, v14, v142
	v_dot2c_f32_bf16_e32 v155, v15, v143
	s_waitcnt vmcnt(36)
	v_cvt_scalef32_pk32_bf16_fp6 v[0:15], v[94:99], 1.0
	v_dot2_f32_bf16 v192, v0, v128, 0
	v_dot2_f32_bf16 v193, v1, v129, 0
	v_dot2_f32_bf16 v194, v2, v130, 0
	v_dot2_f32_bf16 v195, v3, v131, 0
	v_dot2c_f32_bf16_e32 v192, v4, v132
	v_dot2c_f32_bf16_e32 v193, v5, v133
	v_add_f32_e32 v156, v152, v153
	v_dot2c_f32_bf16_e32 v194, v6, v134
	v_dot2c_f32_bf16_e32 v195, v7, v135
	v_dot2c_f32_bf16_e32 v192, v8, v136
	v_add_f32_e32 v157, v154, v155
	v_dot2c_f32_bf16_e32 v193, v9, v137
	v_dot2c_f32_bf16_e32 v194, v10, v138
	v_dot2c_f32_bf16_e32 v195, v11, v139
	v_add_f32_e32 v188, v156, v157
	v_dot2c_f32_bf16_e32 v192, v12, v140
	v_dot2c_f32_bf16_e32 v193, v13, v141
	v_dot2c_f32_bf16_e32 v194, v14, v142
	v_dot2c_f32_bf16_e32 v195, v15, v143
	s_waitcnt vmcnt(34)
	v_cvt_scalef32_pk32_bf16_fp6 v[0:15], v[100:105], 1.0
	v_dot2_f32_bf16 v152, v0, v128, 0
	v_dot2_f32_bf16 v153, v1, v129, 0
	v_dot2_f32_bf16 v154, v2, v130, 0
	v_dot2_f32_bf16 v155, v3, v131, 0
	v_dot2c_f32_bf16_e32 v152, v4, v132
	v_dot2c_f32_bf16_e32 v153, v5, v133
	v_add_f32_e32 v156, v192, v193
	v_dot2c_f32_bf16_e32 v154, v6, v134
	v_dot2c_f32_bf16_e32 v155, v7, v135
	v_dot2c_f32_bf16_e32 v152, v8, v136
	v_add_f32_e32 v157, v194, v195
	v_dot2c_f32_bf16_e32 v153, v9, v137
	v_dot2c_f32_bf16_e32 v154, v10, v138
	v_dot2c_f32_bf16_e32 v155, v11, v139
	v_add_f32_e32 v189, v156, v157
	v_dot2c_f32_bf16_e32 v152, v12, v140
	v_dot2c_f32_bf16_e32 v153, v13, v141
	v_dot2c_f32_bf16_e32 v154, v14, v142
	v_dot2c_f32_bf16_e32 v155, v15, v143
	s_waitcnt vmcnt(32)
	v_cvt_scalef32_pk32_bf16_fp6 v[0:15], v[106:111], 1.0
	v_dot2_f32_bf16 v192, v0, v128, 0
	v_dot2_f32_bf16 v193, v1, v129, 0
	v_dot2_f32_bf16 v194, v2, v130, 0
	v_dot2_f32_bf16 v195, v3, v131, 0
	v_dot2c_f32_bf16_e32 v192, v4, v132
	v_dot2c_f32_bf16_e32 v193, v5, v133
	v_add_f32_e32 v156, v152, v153
	v_dot2c_f32_bf16_e32 v194, v6, v134
	v_dot2c_f32_bf16_e32 v195, v7, v135
	v_dot2c_f32_bf16_e32 v192, v8, v136
	v_add_f32_e32 v157, v154, v155
	v_dot2c_f32_bf16_e32 v193, v9, v137
	v_dot2c_f32_bf16_e32 v194, v10, v138
	v_dot2c_f32_bf16_e32 v195, v11, v139
	v_add_f32_e32 v190, v156, v157
	v_dot2c_f32_bf16_e32 v192, v12, v140
	v_dot2c_f32_bf16_e32 v193, v13, v141
	v_dot2c_f32_bf16_e32 v194, v14, v142
	v_dot2c_f32_bf16_e32 v195, v15, v143
	s_nop 1
	v_add_f32_e32 v156, v192, v193
	v_add_f32_e32 v157, v194, v195
	v_add_f32_e32 v191, v156, v157
	v_add_f32_dpp v184, v184, v184 row_half_mirror row_mask:0xf bank_mask:0x5
	v_add_f32_dpp v185, v185, v185 row_half_mirror row_mask:0xf bank_mask:0x5
	v_add_f32_dpp v186, v186, v186 row_half_mirror row_mask:0xf bank_mask:0x5
	v_add_f32_dpp v187, v187, v187 row_half_mirror row_mask:0xf bank_mask:0x5
	v_add_f32_dpp v184, v188, v188 row_half_mirror row_mask:0xf bank_mask:0xa
	v_add_f32_dpp v185, v189, v189 row_half_mirror row_mask:0xf bank_mask:0xa
	v_add_f32_dpp v186, v190, v190 row_half_mirror row_mask:0xf bank_mask:0xa
	v_add_f32_dpp v187, v191, v191 row_half_mirror row_mask:0xf bank_mask:0xa
	v_add_f32_dpp v184, v184, v184 quad_perm:[1,0,3,2] row_mask:0xf bank_mask:0xf
	v_add_f32_dpp v185, v185, v185 quad_perm:[1,0,3,2] row_mask:0xf bank_mask:0xf
	v_add_f32_dpp v186, v186, v186 quad_perm:[1,0,3,2] row_mask:0xf bank_mask:0xf
	v_add_f32_dpp v187, v187, v187 quad_perm:[1,0,3,2] row_mask:0xf bank_mask:0xf
	v_add_f32_dpp v184, v184, v184 quad_perm:[2,3,0,1] row_mask:0xf bank_mask:0xf
	v_add_f32_dpp v185, v185, v185 quad_perm:[2,3,0,1] row_mask:0xf bank_mask:0xf
	v_add_f32_dpp v186, v186, v186 quad_perm:[2,3,0,1] row_mask:0xf bank_mask:0xf
	v_add_f32_dpp v187, v187, v187 quad_perm:[2,3,0,1] row_mask:0xf bank_mask:0xf
	v_cndmask_b32_e64 v156, v184, v185, s[10:11]
	v_cndmask_b32_e64 v157, v186, v187, s[10:11]
	v_cndmask_b32_e64 v198, v156, v157, s[100:101]
	s_waitcnt lgkmcnt(0)
	v_mad_u32_u24 v176, v176, s18, v164
	v_mad_u32_u24 v177, v177, s18, v164
	v_mad_u32_u24 v178, v178, s18, v164
	v_mad_u32_u24 v179, v179, s18, v164
	global_load_dwordx4 v[88:91], v176, s[0:1]
	global_load_dwordx2 v[92:93], v176, s[0:1] offset:16
	global_load_dwordx4 v[94:97], v177, s[0:1]
	global_load_dwordx2 v[98:99], v177, s[0:1] offset:16
	global_load_dwordx4 v[100:103], v178, s[0:1]
	global_load_dwordx2 v[104:105], v178, s[0:1] offset:16
	global_load_dwordx4 v[106:109], v179, s[0:1]
	global_load_dwordx2 v[110:111], v179, s[0:1] offset:16
	ds_add_f32 v170, v198 offset:256
	s_add_u32 s12, s12, 1
	s_and_b32 s12, s12, 63
	s_add_u32 s14, s12, 1
	s_and_b32 s38, s14, 63
	s_and_b32 s15, s38, 15
	s_lshr_b32 s16, s38, 4
	s_lshl_b32 s17, s15, 9
	s_mul_i32 s13, s15, s19
	s_lshl_b32 s14, s16, 6
	s_add_u32 s13, s13, s14
	s_add_u32 s8, s4, s13
	s_addc_u32 s9, s5, 0
	s_mul_i32 s13, s16, 0x300000
	s_add_u32 s0, s26, 0x2800000
	s_addc_u32 s1, s27, 0
	s_add_u32 s0, s0, s13
	s_addc_u32 s1, s1, 0
	v_add_u32_e32 v168, s17, v161
	ds_read2_b32 v[144:145], v168 offset0:0 offset1:8
	ds_read2_b32 v[146:147], v168 offset0:16 offset1:24
	s_cmp_lg_u32 s12, 0
	s_cbranch_scc1 .Lgu1_loop
	s_waitcnt vmcnt(0) lgkmcnt(0)
	s_add_u32 s0, s26, 0x1420000
	s_addc_u32 s1, s27, 0
	s_add_u32 s4, s26, 0x1430000
	s_addc_u32 s5, s27, 0
	s_lshl_b32 s13, s35, 9
	s_add_u32 s6, s26, 0xe800000
	s_addc_u32 s7, s27, 0
	s_add_u32 s6, s6, s13
	s_addc_u32 s7, s7, 0
	s_add_u32 s8, s26, 0xf800000
	s_addc_u32 s9, s27, 0
	s_add_u32 s8, s8, s13
	s_addc_u32 s9, s9, 0
	s_lshl_b32 s14, s92, 11
	s_mov_b32 s12, 0x378e98ab
	s_mov_b32 s15, 0x3b7cd369
	s_mov_b32 s16, 0xbcc618b2
	s_mov_b32 s17, 0x3dda74e4
	s_mov_b32 s18, 0x3f228afd
	s_mov_b32 s19, 0x3e03c728
	s_mov_b32 s98, 0xbfb8aa3b
	s_mov_b32 s38, 0x42ce8ed0
	s_mov_b32 s39, 0xc2b17218
	s_mov_b32 s10, 0x7fffffff
	v_mov_b32_e32 v176, 0x3ba10414
	v_mov_b32_e32 v177, 0xb9c68948
	v_mov_b32_e32 v178, 0x7f800000
	ds_read2st64_b32 v[16:17], v174 offset0:0 offset1:1
	ds_read2st64_b32 v[80:81], v175 offset0:0 offset1:1
	ds_read2st64_b32 v[18:19], v174 offset0:2 offset1:3
	ds_read2st64_b32 v[82:83], v175 offset0:2 offset1:3
	ds_read2st64_b32 v[20:21], v174 offset0:4 offset1:5
	ds_read2st64_b32 v[84:85], v175 offset0:4 offset1:5
	ds_read2st64_b32 v[22:23], v174 offset0:6 offset1:7
	ds_read2st64_b32 v[86:87], v175 offset0:6 offset1:7
	ds_read2st64_b32 v[24:25], v174 offset0:8 offset1:9
	ds_read2st64_b32 v[88:89], v175 offset0:8 offset1:9
	ds_read2st64_b32 v[26:27], v174 offset0:10 offset1:11
	ds_read2st64_b32 v[90:91], v175 offset0:10 offset1:11
	ds_read2st64_b32 v[28:29], v174 offset0:12 offset1:13
	ds_read2st64_b32 v[92:93], v175 offset0:12 offset1:13
	ds_read2st64_b32 v[30:31], v174 offset0:14 offset1:15
	ds_read2st64_b32 v[94:95], v175 offset0:14 offset1:15
	s_waitcnt lgkmcnt(0)
	v_lshlrev_b32_e32 v16, 2, v16
	v_lshlrev_b32_e32 v17, 2, v17
	v_lshlrev_b32_e32 v18, 2, v18
	v_lshlrev_b32_e32 v19, 2, v19
	v_lshlrev_b32_e32 v20, 2, v20
	v_lshlrev_b32_e32 v21, 2, v21
	v_lshlrev_b32_e32 v22, 2, v22
	v_lshlrev_b32_e32 v23, 2, v23
	v_lshlrev_b32_e32 v24, 2, v24
	v_lshlrev_b32_e32 v25, 2, v25
	v_lshlrev_b32_e32 v26, 2, v26
	v_lshlrev_b32_e32 v27, 2, v27
	v_lshlrev_b32_e32 v28, 2, v28
	v_lshlrev_b32_e32 v29, 2, v29
	v_lshlrev_b32_e32 v30, 2, v30
	v_lshlrev_b32_e32 v31, 2, v31
	global_load_dword v32, v160, s[6:7]
	global_load_dword v33, v160, s[6:7] offset:256
	global_load_dword v34, v16, s[0:1]
	global_load_dword v35, v17, s[0:1]
	global_load_dword v36, v16, s[4:5]
	global_load_dword v37, v17, s[4:5]
	s_add_u32 s6, s6, s14
	s_addc_u32 s7, s7, 0
	global_load_dword v38, v160, s[6:7]
	global_load_dword v39, v160, s[6:7] offset:256
	global_load_dword v40, v18, s[0:1]
	global_load_dword v41, v19, s[0:1]
	global_load_dword v42, v18, s[4:5]
	global_load_dword v43, v19, s[4:5]
	s_add_u32 s6, s6, s14
	s_addc_u32 s7, s7, 0
	global_load_dword v44, v160, s[6:7]
	global_load_dword v45, v160, s[6:7] offset:256
	global_load_dword v46, v20, s[0:1]
	global_load_dword v47, v21, s[0:1]
	global_load_dword v48, v20, s[4:5]
	global_load_dword v49, v21, s[4:5]
	s_add_u32 s6, s6, s14
	s_addc_u32 s7, s7, 0
	global_load_dword v50, v160, s[6:7]
	global_load_dword v51, v160, s[6:7] offset:256
	global_load_dword v52, v22, s[0:1]
	global_load_dword v53, v23, s[0:1]
	global_load_dword v54, v22, s[4:5]
	global_load_dword v55, v23, s[4:5]
	s_add_u32 s6, s6, s14
	s_addc_u32 s7, s7, 0
	global_load_dword v56, v160, s[6:7]
	global_load_dword v57, v160, s[6:7] offset:256
	global_load_dword v58, v24, s[0:1]
	global_load_dword v59, v25, s[0:1]
	global_load_dword v60, v24, s[4:5]
	global_load_dword v61, v25, s[4:5]
	s_add_u32 s6, s6, s14
	s_addc_u32 s7, s7, 0
	global_load_dword v62, v160, s[6:7]
	global_load_dword v63, v160, s[6:7] offset:256
	global_load_dword v64, v26, s[0:1]
	global_load_dword v65, v27, s[0:1]
	global_load_dword v66, v26, s[4:5]
	global_load_dword v67, v27, s[4:5]
	s_add_u32 s6, s6, s14
	s_addc_u32 s7, s7, 0
	global_load_dword v68, v160, s[6:7]
	global_load_dword v69, v160, s[6:7] offset:256
	global_load_dword v70, v28, s[0:1]
	global_load_dword v71, v29, s[0:1]
	global_load_dword v72, v28, s[4:5]
	global_load_dword v73, v29, s[4:5]
	s_add_u32 s6, s6, s14
	s_addc_u32 s7, s7, 0
	global_load_dword v74, v160, s[6:7]
	global_load_dword v75, v160, s[6:7] offset:256
	global_load_dword v76, v30, s[0:1]
	global_load_dword v77, v31, s[0:1]
	global_load_dword v78, v30, s[4:5]
	global_load_dword v79, v31, s[4:5]
	s_add_u32 s6, s6, s14
	s_addc_u32 s7, s7, 0
	s_waitcnt vmcnt(0)
	v_mul_f32_e32 v80, v34, v80
	v_mul_f32_e32 v180, 0x3f3504f3, v80
	v_fma_f32 v182, |v180|, s12, v177
	v_fma_f32 v182, |v180|, v182, s15
	v_fma_f32 v182, |v180|, v182, s16
	v_fma_f32 v182, |v180|, v182, s17
	v_fma_f32 v182, |v180|, v182, s18
	v_fma_f32 v182, |v180|, v182, s19
	v_fma_f32 v182, |v180|, v182, |v180|
	v_mul_f32_e32 v184, 0xbfb8aa3b, v182
	v_fma_f32 v185, v182, s98, -v184
	v_rndne_f32_e32 v186, v184
	v_fmac_f32_e32 v185, 0xb2a5705f, v182
	v_sub_f32_e32 v184, v184, v186
	v_add_f32_e32 v184, v184, v185
	v_cvt_i32_f32_e32 v185, v186
	v_exp_f32_e32 v184, v184
	v_cmp_nlt_f32_e32 vcc, s38, v182
	v_ldexp_f32 v184, v184, v185
	s_nop 0
	v_cndmask_b32_e32 v184, 0, v184, vcc
	v_cmp_ngt_f32_e32 vcc, s39, v182
	s_nop 1
	v_cndmask_b32_e32 v184, v178, v184, vcc
	v_sub_f32_e32 v184, 1.0, v184
	v_mul_f32_e32 v183, v180, v180
	v_fmamk_f32 v185, v183, 0xba1345e1, v176
	v_fmaak_f32 v185, v183, v185, 0xbcdac9b8
	v_fmaak_f32 v185, v183, v185, 0x3de703be
	v_fmaak_f32 v185, v183, v185, 0xbec09330
	v_fmaak_f32 v183, v183, v185, 0x3e0375d0
	v_fma_f32 v183, |v180|, v183, |v180|
	v_cmp_nlt_f32_e64 vcc, |v180|, 1.0
	s_nop 1
	v_cndmask_b32_e32 v184, v183, v184, vcc
	v_bfi_b32 v184, s10, v184, v180
	v_add_f32_e32 v184, 1.0, v184
	v_mul_f32_e32 v80, 0.5, v80
	v_mul_f32_e32 v32, v32, v36
	v_mul_f32_e32 v80, v80, v184
	v_mul_f32_e32 v80, v32, v80
	v_mul_f32_e32 v81, v35, v81
	v_mul_f32_e32 v180, 0x3f3504f3, v81
	v_fma_f32 v182, |v180|, s12, v177
	v_fma_f32 v182, |v180|, v182, s15
	v_fma_f32 v182, |v180|, v182, s16
	v_fma_f32 v182, |v180|, v182, s17
	v_fma_f32 v182, |v180|, v182, s18
	v_fma_f32 v182, |v180|, v182, s19
	v_fma_f32 v182, |v180|, v182, |v180|
	v_mul_f32_e32 v184, 0xbfb8aa3b, v182
	v_fma_f32 v185, v182, s98, -v184
	v_rndne_f32_e32 v186, v184
	v_fmac_f32_e32 v185, 0xb2a5705f, v182
	v_sub_f32_e32 v184, v184, v186
	v_add_f32_e32 v184, v184, v185
	v_cvt_i32_f32_e32 v185, v186
	v_exp_f32_e32 v184, v184
	v_cmp_nlt_f32_e32 vcc, s38, v182
	v_ldexp_f32 v184, v184, v185
	s_nop 0
	v_cndmask_b32_e32 v184, 0, v184, vcc
	v_cmp_ngt_f32_e32 vcc, s39, v182
	s_nop 1
	v_cndmask_b32_e32 v184, v178, v184, vcc
	v_sub_f32_e32 v184, 1.0, v184
	v_mul_f32_e32 v183, v180, v180
	v_fmamk_f32 v185, v183, 0xba1345e1, v176
	v_fmaak_f32 v185, v183, v185, 0xbcdac9b8
	v_fmaak_f32 v185, v183, v185, 0x3de703be
	v_fmaak_f32 v185, v183, v185, 0xbec09330
	v_fmaak_f32 v183, v183, v185, 0x3e0375d0
	v_fma_f32 v183, |v180|, v183, |v180|
	v_cmp_nlt_f32_e64 vcc, |v180|, 1.0
	s_nop 1
	v_cndmask_b32_e32 v184, v183, v184, vcc
	v_bfi_b32 v184, s10, v184, v180
	v_add_f32_e32 v184, 1.0, v184
	v_mul_f32_e32 v81, 0.5, v81
	v_mul_f32_e32 v33, v33, v37
	v_mul_f32_e32 v81, v81, v184
	v_mul_f32_e32 v81, v33, v81
	global_store_dword v160, v80, s[8:9]
	global_store_dword v160, v81, s[8:9] offset:256
	s_add_u32 s8, s8, s14
	s_addc_u32 s9, s9, 0
	v_mul_f32_e32 v82, v40, v82
	v_mul_f32_e32 v180, 0x3f3504f3, v82
	v_fma_f32 v182, |v180|, s12, v177
	v_fma_f32 v182, |v180|, v182, s15
	v_fma_f32 v182, |v180|, v182, s16
	v_fma_f32 v182, |v180|, v182, s17
	v_fma_f32 v182, |v180|, v182, s18
	v_fma_f32 v182, |v180|, v182, s19
	v_fma_f32 v182, |v180|, v182, |v180|
	v_mul_f32_e32 v184, 0xbfb8aa3b, v182
	v_fma_f32 v185, v182, s98, -v184
	v_rndne_f32_e32 v186, v184
	v_fmac_f32_e32 v185, 0xb2a5705f, v182
	v_sub_f32_e32 v184, v184, v186
	v_add_f32_e32 v184, v184, v185
	v_cvt_i32_f32_e32 v185, v186
	v_exp_f32_e32 v184, v184
	v_cmp_nlt_f32_e32 vcc, s38, v182
	v_ldexp_f32 v184, v184, v185
	s_nop 0
	v_cndmask_b32_e32 v184, 0, v184, vcc
	v_cmp_ngt_f32_e32 vcc, s39, v182
	s_nop 1
	v_cndmask_b32_e32 v184, v178, v184, vcc
	v_sub_f32_e32 v184, 1.0, v184
	v_mul_f32_e32 v183, v180, v180
	v_fmamk_f32 v185, v183, 0xba1345e1, v176
	v_fmaak_f32 v185, v183, v185, 0xbcdac9b8
	v_fmaak_f32 v185, v183, v185, 0x3de703be
	v_fmaak_f32 v185, v183, v185, 0xbec09330
	v_fmaak_f32 v183, v183, v185, 0x3e0375d0
	v_fma_f32 v183, |v180|, v183, |v180|
	v_cmp_nlt_f32_e64 vcc, |v180|, 1.0
	s_nop 1
	v_cndmask_b32_e32 v184, v183, v184, vcc
	v_bfi_b32 v184, s10, v184, v180
	v_add_f32_e32 v184, 1.0, v184
	v_mul_f32_e32 v82, 0.5, v82
	v_mul_f32_e32 v38, v38, v42
	v_mul_f32_e32 v82, v82, v184
	v_mul_f32_e32 v82, v38, v82
	v_mul_f32_e32 v83, v41, v83
	v_mul_f32_e32 v180, 0x3f3504f3, v83
	v_fma_f32 v182, |v180|, s12, v177
	v_fma_f32 v182, |v180|, v182, s15
	v_fma_f32 v182, |v180|, v182, s16
	v_fma_f32 v182, |v180|, v182, s17
	v_fma_f32 v182, |v180|, v182, s18
	v_fma_f32 v182, |v180|, v182, s19
	v_fma_f32 v182, |v180|, v182, |v180|
	v_mul_f32_e32 v184, 0xbfb8aa3b, v182
	v_fma_f32 v185, v182, s98, -v184
	v_rndne_f32_e32 v186, v184
	v_fmac_f32_e32 v185, 0xb2a5705f, v182
	v_sub_f32_e32 v184, v184, v186
	v_add_f32_e32 v184, v184, v185
	v_cvt_i32_f32_e32 v185, v186
	v_exp_f32_e32 v184, v184
	v_cmp_nlt_f32_e32 vcc, s38, v182
	v_ldexp_f32 v184, v184, v185
	s_nop 0
	v_cndmask_b32_e32 v184, 0, v184, vcc
	v_cmp_ngt_f32_e32 vcc, s39, v182
	s_nop 1
	v_cndmask_b32_e32 v184, v178, v184, vcc
	v_sub_f32_e32 v184, 1.0, v184
	v_mul_f32_e32 v183, v180, v180
	v_fmamk_f32 v185, v183, 0xba1345e1, v176
	v_fmaak_f32 v185, v183, v185, 0xbcdac9b8
	v_fmaak_f32 v185, v183, v185, 0x3de703be
	v_fmaak_f32 v185, v183, v185, 0xbec09330
	v_fmaak_f32 v183, v183, v185, 0x3e0375d0
	v_fma_f32 v183, |v180|, v183, |v180|
	v_cmp_nlt_f32_e64 vcc, |v180|, 1.0
	s_nop 1
	v_cndmask_b32_e32 v184, v183, v184, vcc
	v_bfi_b32 v184, s10, v184, v180
	v_add_f32_e32 v184, 1.0, v184
	v_mul_f32_e32 v83, 0.5, v83
	v_mul_f32_e32 v39, v39, v43
	v_mul_f32_e32 v83, v83, v184
	v_mul_f32_e32 v83, v39, v83
	global_store_dword v160, v82, s[8:9]
	global_store_dword v160, v83, s[8:9] offset:256
	s_add_u32 s8, s8, s14
	s_addc_u32 s9, s9, 0
	v_mul_f32_e32 v84, v46, v84
	v_mul_f32_e32 v180, 0x3f3504f3, v84
	v_fma_f32 v182, |v180|, s12, v177
	v_fma_f32 v182, |v180|, v182, s15
	v_fma_f32 v182, |v180|, v182, s16
	v_fma_f32 v182, |v180|, v182, s17
	v_fma_f32 v182, |v180|, v182, s18
	v_fma_f32 v182, |v180|, v182, s19
	v_fma_f32 v182, |v180|, v182, |v180|
	v_mul_f32_e32 v184, 0xbfb8aa3b, v182
	v_fma_f32 v185, v182, s98, -v184
	v_rndne_f32_e32 v186, v184
	v_fmac_f32_e32 v185, 0xb2a5705f, v182
	v_sub_f32_e32 v184, v184, v186
	v_add_f32_e32 v184, v184, v185
	v_cvt_i32_f32_e32 v185, v186
	v_exp_f32_e32 v184, v184
	v_cmp_nlt_f32_e32 vcc, s38, v182
	v_ldexp_f32 v184, v184, v185
	s_nop 0
	v_cndmask_b32_e32 v184, 0, v184, vcc
	v_cmp_ngt_f32_e32 vcc, s39, v182
	s_nop 1
	v_cndmask_b32_e32 v184, v178, v184, vcc
	v_sub_f32_e32 v184, 1.0, v184
	v_mul_f32_e32 v183, v180, v180
	v_fmamk_f32 v185, v183, 0xba1345e1, v176
	v_fmaak_f32 v185, v183, v185, 0xbcdac9b8
	v_fmaak_f32 v185, v183, v185, 0x3de703be
	v_fmaak_f32 v185, v183, v185, 0xbec09330
	v_fmaak_f32 v183, v183, v185, 0x3e0375d0
	v_fma_f32 v183, |v180|, v183, |v180|
	v_cmp_nlt_f32_e64 vcc, |v180|, 1.0
	s_nop 1
	v_cndmask_b32_e32 v184, v183, v184, vcc
	v_bfi_b32 v184, s10, v184, v180
	v_add_f32_e32 v184, 1.0, v184
	v_mul_f32_e32 v84, 0.5, v84
	v_mul_f32_e32 v44, v44, v48
	v_mul_f32_e32 v84, v84, v184
	v_mul_f32_e32 v84, v44, v84
	v_mul_f32_e32 v85, v47, v85
	v_mul_f32_e32 v180, 0x3f3504f3, v85
	v_fma_f32 v182, |v180|, s12, v177
	v_fma_f32 v182, |v180|, v182, s15
	v_fma_f32 v182, |v180|, v182, s16
	v_fma_f32 v182, |v180|, v182, s17
	v_fma_f32 v182, |v180|, v182, s18
	v_fma_f32 v182, |v180|, v182, s19
	v_fma_f32 v182, |v180|, v182, |v180|
	v_mul_f32_e32 v184, 0xbfb8aa3b, v182
	v_fma_f32 v185, v182, s98, -v184
	v_rndne_f32_e32 v186, v184
	v_fmac_f32_e32 v185, 0xb2a5705f, v182
	v_sub_f32_e32 v184, v184, v186
	v_add_f32_e32 v184, v184, v185
	v_cvt_i32_f32_e32 v185, v186
	v_exp_f32_e32 v184, v184
	v_cmp_nlt_f32_e32 vcc, s38, v182
	v_ldexp_f32 v184, v184, v185
	s_nop 0
	v_cndmask_b32_e32 v184, 0, v184, vcc
	v_cmp_ngt_f32_e32 vcc, s39, v182
	s_nop 1
	v_cndmask_b32_e32 v184, v178, v184, vcc
	v_sub_f32_e32 v184, 1.0, v184
	v_mul_f32_e32 v183, v180, v180
	v_fmamk_f32 v185, v183, 0xba1345e1, v176
	v_fmaak_f32 v185, v183, v185, 0xbcdac9b8
	v_fmaak_f32 v185, v183, v185, 0x3de703be
	v_fmaak_f32 v185, v183, v185, 0xbec09330
	v_fmaak_f32 v183, v183, v185, 0x3e0375d0
	v_fma_f32 v183, |v180|, v183, |v180|
	v_cmp_nlt_f32_e64 vcc, |v180|, 1.0
	s_nop 1
	v_cndmask_b32_e32 v184, v183, v184, vcc
	v_bfi_b32 v184, s10, v184, v180
	v_add_f32_e32 v184, 1.0, v184
	v_mul_f32_e32 v85, 0.5, v85
	v_mul_f32_e32 v45, v45, v49
	v_mul_f32_e32 v85, v85, v184
	v_mul_f32_e32 v85, v45, v85
	global_store_dword v160, v84, s[8:9]
	global_store_dword v160, v85, s[8:9] offset:256
	s_add_u32 s8, s8, s14
	s_addc_u32 s9, s9, 0
	v_mul_f32_e32 v86, v52, v86
	v_mul_f32_e32 v180, 0x3f3504f3, v86
	v_fma_f32 v182, |v180|, s12, v177
	v_fma_f32 v182, |v180|, v182, s15
	v_fma_f32 v182, |v180|, v182, s16
	v_fma_f32 v182, |v180|, v182, s17
	v_fma_f32 v182, |v180|, v182, s18
	v_fma_f32 v182, |v180|, v182, s19
	v_fma_f32 v182, |v180|, v182, |v180|
	v_mul_f32_e32 v184, 0xbfb8aa3b, v182
	v_fma_f32 v185, v182, s98, -v184
	v_rndne_f32_e32 v186, v184
	v_fmac_f32_e32 v185, 0xb2a5705f, v182
	v_sub_f32_e32 v184, v184, v186
	v_add_f32_e32 v184, v184, v185
	v_cvt_i32_f32_e32 v185, v186
	v_exp_f32_e32 v184, v184
	v_cmp_nlt_f32_e32 vcc, s38, v182
	v_ldexp_f32 v184, v184, v185
	s_nop 0
	v_cndmask_b32_e32 v184, 0, v184, vcc
	v_cmp_ngt_f32_e32 vcc, s39, v182
	s_nop 1
	v_cndmask_b32_e32 v184, v178, v184, vcc
	v_sub_f32_e32 v184, 1.0, v184
	v_mul_f32_e32 v183, v180, v180
	v_fmamk_f32 v185, v183, 0xba1345e1, v176
	v_fmaak_f32 v185, v183, v185, 0xbcdac9b8
	v_fmaak_f32 v185, v183, v185, 0x3de703be
	v_fmaak_f32 v185, v183, v185, 0xbec09330
	v_fmaak_f32 v183, v183, v185, 0x3e0375d0
	v_fma_f32 v183, |v180|, v183, |v180|
	v_cmp_nlt_f32_e64 vcc, |v180|, 1.0
	s_nop 1
	v_cndmask_b32_e32 v184, v183, v184, vcc
	v_bfi_b32 v184, s10, v184, v180
	v_add_f32_e32 v184, 1.0, v184
	v_mul_f32_e32 v86, 0.5, v86
	v_mul_f32_e32 v50, v50, v54
	v_mul_f32_e32 v86, v86, v184
	v_mul_f32_e32 v86, v50, v86
	v_mul_f32_e32 v87, v53, v87
	v_mul_f32_e32 v180, 0x3f3504f3, v87
	v_fma_f32 v182, |v180|, s12, v177
	v_fma_f32 v182, |v180|, v182, s15
	v_fma_f32 v182, |v180|, v182, s16
	v_fma_f32 v182, |v180|, v182, s17
	v_fma_f32 v182, |v180|, v182, s18
	v_fma_f32 v182, |v180|, v182, s19
	v_fma_f32 v182, |v180|, v182, |v180|
	v_mul_f32_e32 v184, 0xbfb8aa3b, v182
	v_fma_f32 v185, v182, s98, -v184
	v_rndne_f32_e32 v186, v184
	v_fmac_f32_e32 v185, 0xb2a5705f, v182
	v_sub_f32_e32 v184, v184, v186
	v_add_f32_e32 v184, v184, v185
	v_cvt_i32_f32_e32 v185, v186
	v_exp_f32_e32 v184, v184
	v_cmp_nlt_f32_e32 vcc, s38, v182
	v_ldexp_f32 v184, v184, v185
	s_nop 0
	v_cndmask_b32_e32 v184, 0, v184, vcc
	v_cmp_ngt_f32_e32 vcc, s39, v182
	s_nop 1
	v_cndmask_b32_e32 v184, v178, v184, vcc
	v_sub_f32_e32 v184, 1.0, v184
	v_mul_f32_e32 v183, v180, v180
	v_fmamk_f32 v185, v183, 0xba1345e1, v176
	v_fmaak_f32 v185, v183, v185, 0xbcdac9b8
	v_fmaak_f32 v185, v183, v185, 0x3de703be
	v_fmaak_f32 v185, v183, v185, 0xbec09330
	v_fmaak_f32 v183, v183, v185, 0x3e0375d0
	v_fma_f32 v183, |v180|, v183, |v180|
	v_cmp_nlt_f32_e64 vcc, |v180|, 1.0
	s_nop 1
	v_cndmask_b32_e32 v184, v183, v184, vcc
	v_bfi_b32 v184, s10, v184, v180
	v_add_f32_e32 v184, 1.0, v184
	v_mul_f32_e32 v87, 0.5, v87
	v_mul_f32_e32 v51, v51, v55
	v_mul_f32_e32 v87, v87, v184
	v_mul_f32_e32 v87, v51, v87
	global_store_dword v160, v86, s[8:9]
	global_store_dword v160, v87, s[8:9] offset:256
	s_add_u32 s8, s8, s14
	s_addc_u32 s9, s9, 0
	v_mul_f32_e32 v88, v58, v88
	v_mul_f32_e32 v180, 0x3f3504f3, v88
	v_fma_f32 v182, |v180|, s12, v177
	v_fma_f32 v182, |v180|, v182, s15
	v_fma_f32 v182, |v180|, v182, s16
	v_fma_f32 v182, |v180|, v182, s17
	v_fma_f32 v182, |v180|, v182, s18
	v_fma_f32 v182, |v180|, v182, s19
	v_fma_f32 v182, |v180|, v182, |v180|
	v_mul_f32_e32 v184, 0xbfb8aa3b, v182
	v_fma_f32 v185, v182, s98, -v184
	v_rndne_f32_e32 v186, v184
	v_fmac_f32_e32 v185, 0xb2a5705f, v182
	v_sub_f32_e32 v184, v184, v186
	v_add_f32_e32 v184, v184, v185
	v_cvt_i32_f32_e32 v185, v186
	v_exp_f32_e32 v184, v184
	v_cmp_nlt_f32_e32 vcc, s38, v182
	v_ldexp_f32 v184, v184, v185
	s_nop 0
	v_cndmask_b32_e32 v184, 0, v184, vcc
	v_cmp_ngt_f32_e32 vcc, s39, v182
	s_nop 1
	v_cndmask_b32_e32 v184, v178, v184, vcc
	v_sub_f32_e32 v184, 1.0, v184
	v_mul_f32_e32 v183, v180, v180
	v_fmamk_f32 v185, v183, 0xba1345e1, v176
	v_fmaak_f32 v185, v183, v185, 0xbcdac9b8
	v_fmaak_f32 v185, v183, v185, 0x3de703be
	v_fmaak_f32 v185, v183, v185, 0xbec09330
	v_fmaak_f32 v183, v183, v185, 0x3e0375d0
	v_fma_f32 v183, |v180|, v183, |v180|
	v_cmp_nlt_f32_e64 vcc, |v180|, 1.0
	s_nop 1
	v_cndmask_b32_e32 v184, v183, v184, vcc
	v_bfi_b32 v184, s10, v184, v180
	v_add_f32_e32 v184, 1.0, v184
	v_mul_f32_e32 v88, 0.5, v88
	v_mul_f32_e32 v56, v56, v60
	v_mul_f32_e32 v88, v88, v184
	v_mul_f32_e32 v88, v56, v88
	v_mul_f32_e32 v89, v59, v89
	v_mul_f32_e32 v180, 0x3f3504f3, v89
	v_fma_f32 v182, |v180|, s12, v177
	v_fma_f32 v182, |v180|, v182, s15
	v_fma_f32 v182, |v180|, v182, s16
	v_fma_f32 v182, |v180|, v182, s17
	v_fma_f32 v182, |v180|, v182, s18
	v_fma_f32 v182, |v180|, v182, s19
	v_fma_f32 v182, |v180|, v182, |v180|
	v_mul_f32_e32 v184, 0xbfb8aa3b, v182
	v_fma_f32 v185, v182, s98, -v184
	v_rndne_f32_e32 v186, v184
	v_fmac_f32_e32 v185, 0xb2a5705f, v182
	v_sub_f32_e32 v184, v184, v186
	v_add_f32_e32 v184, v184, v185
	v_cvt_i32_f32_e32 v185, v186
	v_exp_f32_e32 v184, v184
	v_cmp_nlt_f32_e32 vcc, s38, v182
	v_ldexp_f32 v184, v184, v185
	s_nop 0
	v_cndmask_b32_e32 v184, 0, v184, vcc
	v_cmp_ngt_f32_e32 vcc, s39, v182
	s_nop 1
	v_cndmask_b32_e32 v184, v178, v184, vcc
	v_sub_f32_e32 v184, 1.0, v184
	v_mul_f32_e32 v183, v180, v180
	v_fmamk_f32 v185, v183, 0xba1345e1, v176
	v_fmaak_f32 v185, v183, v185, 0xbcdac9b8
	v_fmaak_f32 v185, v183, v185, 0x3de703be
	v_fmaak_f32 v185, v183, v185, 0xbec09330
	v_fmaak_f32 v183, v183, v185, 0x3e0375d0
	v_fma_f32 v183, |v180|, v183, |v180|
	v_cmp_nlt_f32_e64 vcc, |v180|, 1.0
	s_nop 1
	v_cndmask_b32_e32 v184, v183, v184, vcc
	v_bfi_b32 v184, s10, v184, v180
	v_add_f32_e32 v184, 1.0, v184
	v_mul_f32_e32 v89, 0.5, v89
	v_mul_f32_e32 v57, v57, v61
	v_mul_f32_e32 v89, v89, v184
	v_mul_f32_e32 v89, v57, v89
	global_store_dword v160, v88, s[8:9]
	global_store_dword v160, v89, s[8:9] offset:256
	s_add_u32 s8, s8, s14
	s_addc_u32 s9, s9, 0
	v_mul_f32_e32 v90, v64, v90
	v_mul_f32_e32 v180, 0x3f3504f3, v90
	v_fma_f32 v182, |v180|, s12, v177
	v_fma_f32 v182, |v180|, v182, s15
	v_fma_f32 v182, |v180|, v182, s16
	v_fma_f32 v182, |v180|, v182, s17
	v_fma_f32 v182, |v180|, v182, s18
	v_fma_f32 v182, |v180|, v182, s19
	v_fma_f32 v182, |v180|, v182, |v180|
	v_mul_f32_e32 v184, 0xbfb8aa3b, v182
	v_fma_f32 v185, v182, s98, -v184
	v_rndne_f32_e32 v186, v184
	v_fmac_f32_e32 v185, 0xb2a5705f, v182
	v_sub_f32_e32 v184, v184, v186
	v_add_f32_e32 v184, v184, v185
	v_cvt_i32_f32_e32 v185, v186
	v_exp_f32_e32 v184, v184
	v_cmp_nlt_f32_e32 vcc, s38, v182
	v_ldexp_f32 v184, v184, v185
	s_nop 0
	v_cndmask_b32_e32 v184, 0, v184, vcc
	v_cmp_ngt_f32_e32 vcc, s39, v182
	s_nop 1
	v_cndmask_b32_e32 v184, v178, v184, vcc
	v_sub_f32_e32 v184, 1.0, v184
	v_mul_f32_e32 v183, v180, v180
	v_fmamk_f32 v185, v183, 0xba1345e1, v176
	v_fmaak_f32 v185, v183, v185, 0xbcdac9b8
	v_fmaak_f32 v185, v183, v185, 0x3de703be
	v_fmaak_f32 v185, v183, v185, 0xbec09330
	v_fmaak_f32 v183, v183, v185, 0x3e0375d0
	v_fma_f32 v183, |v180|, v183, |v180|
	v_cmp_nlt_f32_e64 vcc, |v180|, 1.0
	s_nop 1
	v_cndmask_b32_e32 v184, v183, v184, vcc
	v_bfi_b32 v184, s10, v184, v180
	v_add_f32_e32 v184, 1.0, v184
	v_mul_f32_e32 v90, 0.5, v90
	v_mul_f32_e32 v62, v62, v66
	v_mul_f32_e32 v90, v90, v184
	v_mul_f32_e32 v90, v62, v90
	v_mul_f32_e32 v91, v65, v91
	v_mul_f32_e32 v180, 0x3f3504f3, v91
	v_fma_f32 v182, |v180|, s12, v177
	v_fma_f32 v182, |v180|, v182, s15
	v_fma_f32 v182, |v180|, v182, s16
	v_fma_f32 v182, |v180|, v182, s17
	v_fma_f32 v182, |v180|, v182, s18
	v_fma_f32 v182, |v180|, v182, s19
	v_fma_f32 v182, |v180|, v182, |v180|
	v_mul_f32_e32 v184, 0xbfb8aa3b, v182
	v_fma_f32 v185, v182, s98, -v184
	v_rndne_f32_e32 v186, v184
	v_fmac_f32_e32 v185, 0xb2a5705f, v182
	v_sub_f32_e32 v184, v184, v186
	v_add_f32_e32 v184, v184, v185
	v_cvt_i32_f32_e32 v185, v186
	v_exp_f32_e32 v184, v184
	v_cmp_nlt_f32_e32 vcc, s38, v182
	v_ldexp_f32 v184, v184, v185
	s_nop 0
	v_cndmask_b32_e32 v184, 0, v184, vcc
	v_cmp_ngt_f32_e32 vcc, s39, v182
	s_nop 1
	v_cndmask_b32_e32 v184, v178, v184, vcc
	v_sub_f32_e32 v184, 1.0, v184
	v_mul_f32_e32 v183, v180, v180
	v_fmamk_f32 v185, v183, 0xba1345e1, v176
	v_fmaak_f32 v185, v183, v185, 0xbcdac9b8
	v_fmaak_f32 v185, v183, v185, 0x3de703be
	v_fmaak_f32 v185, v183, v185, 0xbec09330
	v_fmaak_f32 v183, v183, v185, 0x3e0375d0
	v_fma_f32 v183, |v180|, v183, |v180|
	v_cmp_nlt_f32_e64 vcc, |v180|, 1.0
	s_nop 1
	v_cndmask_b32_e32 v184, v183, v184, vcc
	v_bfi_b32 v184, s10, v184, v180
	v_add_f32_e32 v184, 1.0, v184
	v_mul_f32_e32 v91, 0.5, v91
	v_mul_f32_e32 v63, v63, v67
	v_mul_f32_e32 v91, v91, v184
	v_mul_f32_e32 v91, v63, v91
	global_store_dword v160, v90, s[8:9]
	global_store_dword v160, v91, s[8:9] offset:256
	s_add_u32 s8, s8, s14
	s_addc_u32 s9, s9, 0
	v_mul_f32_e32 v92, v70, v92
	v_mul_f32_e32 v180, 0x3f3504f3, v92
	v_fma_f32 v182, |v180|, s12, v177
	v_fma_f32 v182, |v180|, v182, s15
	v_fma_f32 v182, |v180|, v182, s16
	v_fma_f32 v182, |v180|, v182, s17
	v_fma_f32 v182, |v180|, v182, s18
	v_fma_f32 v182, |v180|, v182, s19
	v_fma_f32 v182, |v180|, v182, |v180|
	v_mul_f32_e32 v184, 0xbfb8aa3b, v182
	v_fma_f32 v185, v182, s98, -v184
	v_rndne_f32_e32 v186, v184
	v_fmac_f32_e32 v185, 0xb2a5705f, v182
	v_sub_f32_e32 v184, v184, v186
	v_add_f32_e32 v184, v184, v185
	v_cvt_i32_f32_e32 v185, v186
	v_exp_f32_e32 v184, v184
	v_cmp_nlt_f32_e32 vcc, s38, v182
	v_ldexp_f32 v184, v184, v185
	s_nop 0
	v_cndmask_b32_e32 v184, 0, v184, vcc
	v_cmp_ngt_f32_e32 vcc, s39, v182
	s_nop 1
	v_cndmask_b32_e32 v184, v178, v184, vcc
	v_sub_f32_e32 v184, 1.0, v184
	v_mul_f32_e32 v183, v180, v180
	v_fmamk_f32 v185, v183, 0xba1345e1, v176
	v_fmaak_f32 v185, v183, v185, 0xbcdac9b8
	v_fmaak_f32 v185, v183, v185, 0x3de703be
	v_fmaak_f32 v185, v183, v185, 0xbec09330
	v_fmaak_f32 v183, v183, v185, 0x3e0375d0
	v_fma_f32 v183, |v180|, v183, |v180|
	v_cmp_nlt_f32_e64 vcc, |v180|, 1.0
	s_nop 1
	v_cndmask_b32_e32 v184, v183, v184, vcc
	v_bfi_b32 v184, s10, v184, v180
	v_add_f32_e32 v184, 1.0, v184
	v_mul_f32_e32 v92, 0.5, v92
	v_mul_f32_e32 v68, v68, v72
	v_mul_f32_e32 v92, v92, v184
	v_mul_f32_e32 v92, v68, v92
	v_mul_f32_e32 v93, v71, v93
	v_mul_f32_e32 v180, 0x3f3504f3, v93
	v_fma_f32 v182, |v180|, s12, v177
	v_fma_f32 v182, |v180|, v182, s15
	v_fma_f32 v182, |v180|, v182, s16
	v_fma_f32 v182, |v180|, v182, s17
	v_fma_f32 v182, |v180|, v182, s18
	v_fma_f32 v182, |v180|, v182, s19
	v_fma_f32 v182, |v180|, v182, |v180|
	v_mul_f32_e32 v184, 0xbfb8aa3b, v182
	v_fma_f32 v185, v182, s98, -v184
	v_rndne_f32_e32 v186, v184
	v_fmac_f32_e32 v185, 0xb2a5705f, v182
	v_sub_f32_e32 v184, v184, v186
	v_add_f32_e32 v184, v184, v185
	v_cvt_i32_f32_e32 v185, v186
	v_exp_f32_e32 v184, v184
	v_cmp_nlt_f32_e32 vcc, s38, v182
	v_ldexp_f32 v184, v184, v185
	s_nop 0
	v_cndmask_b32_e32 v184, 0, v184, vcc
	v_cmp_ngt_f32_e32 vcc, s39, v182
	s_nop 1
	v_cndmask_b32_e32 v184, v178, v184, vcc
	v_sub_f32_e32 v184, 1.0, v184
	v_mul_f32_e32 v183, v180, v180
	v_fmamk_f32 v185, v183, 0xba1345e1, v176
	v_fmaak_f32 v185, v183, v185, 0xbcdac9b8
	v_fmaak_f32 v185, v183, v185, 0x3de703be
	v_fmaak_f32 v185, v183, v185, 0xbec09330
	v_fmaak_f32 v183, v183, v185, 0x3e0375d0
	v_fma_f32 v183, |v180|, v183, |v180|
	v_cmp_nlt_f32_e64 vcc, |v180|, 1.0
	s_nop 1
	v_cndmask_b32_e32 v184, v183, v184, vcc
	v_bfi_b32 v184, s10, v184, v180
	v_add_f32_e32 v184, 1.0, v184
	v_mul_f32_e32 v93, 0.5, v93
	v_mul_f32_e32 v69, v69, v73
	v_mul_f32_e32 v93, v93, v184
	v_mul_f32_e32 v93, v69, v93
	global_store_dword v160, v92, s[8:9]
	global_store_dword v160, v93, s[8:9] offset:256
	s_add_u32 s8, s8, s14
	s_addc_u32 s9, s9, 0
	v_mul_f32_e32 v94, v76, v94
	v_mul_f32_e32 v180, 0x3f3504f3, v94
	v_fma_f32 v182, |v180|, s12, v177
	v_fma_f32 v182, |v180|, v182, s15
	v_fma_f32 v182, |v180|, v182, s16
	v_fma_f32 v182, |v180|, v182, s17
	v_fma_f32 v182, |v180|, v182, s18
	v_fma_f32 v182, |v180|, v182, s19
	v_fma_f32 v182, |v180|, v182, |v180|
	v_mul_f32_e32 v184, 0xbfb8aa3b, v182
	v_fma_f32 v185, v182, s98, -v184
	v_rndne_f32_e32 v186, v184
	v_fmac_f32_e32 v185, 0xb2a5705f, v182
	v_sub_f32_e32 v184, v184, v186
	v_add_f32_e32 v184, v184, v185
	v_cvt_i32_f32_e32 v185, v186
	v_exp_f32_e32 v184, v184
	v_cmp_nlt_f32_e32 vcc, s38, v182
	v_ldexp_f32 v184, v184, v185
	s_nop 0
	v_cndmask_b32_e32 v184, 0, v184, vcc
	v_cmp_ngt_f32_e32 vcc, s39, v182
	s_nop 1
	v_cndmask_b32_e32 v184, v178, v184, vcc
	v_sub_f32_e32 v184, 1.0, v184
	v_mul_f32_e32 v183, v180, v180
	v_fmamk_f32 v185, v183, 0xba1345e1, v176
	v_fmaak_f32 v185, v183, v185, 0xbcdac9b8
	v_fmaak_f32 v185, v183, v185, 0x3de703be
	v_fmaak_f32 v185, v183, v185, 0xbec09330
	v_fmaak_f32 v183, v183, v185, 0x3e0375d0
	v_fma_f32 v183, |v180|, v183, |v180|
	v_cmp_nlt_f32_e64 vcc, |v180|, 1.0
	s_nop 1
	v_cndmask_b32_e32 v184, v183, v184, vcc
	v_bfi_b32 v184, s10, v184, v180
	v_add_f32_e32 v184, 1.0, v184
	v_mul_f32_e32 v94, 0.5, v94
	v_mul_f32_e32 v74, v74, v78
	v_mul_f32_e32 v94, v94, v184
	v_mul_f32_e32 v94, v74, v94
	v_mul_f32_e32 v95, v77, v95
	v_mul_f32_e32 v180, 0x3f3504f3, v95
	v_fma_f32 v182, |v180|, s12, v177
	v_fma_f32 v182, |v180|, v182, s15
	v_fma_f32 v182, |v180|, v182, s16
	v_fma_f32 v182, |v180|, v182, s17
	v_fma_f32 v182, |v180|, v182, s18
	v_fma_f32 v182, |v180|, v182, s19
	v_fma_f32 v182, |v180|, v182, |v180|
	v_mul_f32_e32 v184, 0xbfb8aa3b, v182
	v_fma_f32 v185, v182, s98, -v184
	v_rndne_f32_e32 v186, v184
	v_fmac_f32_e32 v185, 0xb2a5705f, v182
	v_sub_f32_e32 v184, v184, v186
	v_add_f32_e32 v184, v184, v185
	v_cvt_i32_f32_e32 v185, v186
	v_exp_f32_e32 v184, v184
	v_cmp_nlt_f32_e32 vcc, s38, v182
	v_ldexp_f32 v184, v184, v185
	s_nop 0
	v_cndmask_b32_e32 v184, 0, v184, vcc
	v_cmp_ngt_f32_e32 vcc, s39, v182
	s_nop 1
	v_cndmask_b32_e32 v184, v178, v184, vcc
	v_sub_f32_e32 v184, 1.0, v184
	v_mul_f32_e32 v183, v180, v180
	v_fmamk_f32 v185, v183, 0xba1345e1, v176
	v_fmaak_f32 v185, v183, v185, 0xbcdac9b8
	v_fmaak_f32 v185, v183, v185, 0x3de703be
	v_fmaak_f32 v185, v183, v185, 0xbec09330
	v_fmaak_f32 v183, v183, v185, 0x3e0375d0
	v_fma_f32 v183, |v180|, v183, |v180|
	v_cmp_nlt_f32_e64 vcc, |v180|, 1.0
	s_nop 1
	v_cndmask_b32_e32 v184, v183, v184, vcc
	v_bfi_b32 v184, s10, v184, v180
	v_add_f32_e32 v184, 1.0, v184
	v_mul_f32_e32 v95, 0.5, v95
	v_mul_f32_e32 v75, v75, v79
	v_mul_f32_e32 v95, v95, v184
	v_mul_f32_e32 v95, v75, v95
	global_store_dword v160, v94, s[8:9]
	global_store_dword v160, v95, s[8:9] offset:256
	s_add_u32 s8, s8, s14
	s_addc_u32 s9, s9, 0
	ds_read2st64_b32 v[16:17], v174 offset0:16 offset1:17
	ds_read2st64_b32 v[80:81], v175 offset0:16 offset1:17
	ds_read2st64_b32 v[18:19], v174 offset0:18 offset1:19
	ds_read2st64_b32 v[82:83], v175 offset0:18 offset1:19
	ds_read2st64_b32 v[20:21], v174 offset0:20 offset1:21
	ds_read2st64_b32 v[84:85], v175 offset0:20 offset1:21
	ds_read2st64_b32 v[22:23], v174 offset0:22 offset1:23
	ds_read2st64_b32 v[86:87], v175 offset0:22 offset1:23
	ds_read2st64_b32 v[24:25], v174 offset0:24 offset1:25
	ds_read2st64_b32 v[88:89], v175 offset0:24 offset1:25
	ds_read2st64_b32 v[26:27], v174 offset0:26 offset1:27
	ds_read2st64_b32 v[90:91], v175 offset0:26 offset1:27
	ds_read2st64_b32 v[28:29], v174 offset0:28 offset1:29
	ds_read2st64_b32 v[92:93], v175 offset0:28 offset1:29
	ds_read2st64_b32 v[30:31], v174 offset0:30 offset1:31
	ds_read2st64_b32 v[94:95], v175 offset0:30 offset1:31
	s_waitcnt lgkmcnt(0)
	v_lshlrev_b32_e32 v16, 2, v16
	v_lshlrev_b32_e32 v17, 2, v17
	v_lshlrev_b32_e32 v18, 2, v18
	v_lshlrev_b32_e32 v19, 2, v19
	v_lshlrev_b32_e32 v20, 2, v20
	v_lshlrev_b32_e32 v21, 2, v21
	v_lshlrev_b32_e32 v22, 2, v22
	v_lshlrev_b32_e32 v23, 2, v23
	v_lshlrev_b32_e32 v24, 2, v24
	v_lshlrev_b32_e32 v25, 2, v25
	v_lshlrev_b32_e32 v26, 2, v26
	v_lshlrev_b32_e32 v27, 2, v27
	v_lshlrev_b32_e32 v28, 2, v28
	v_lshlrev_b32_e32 v29, 2, v29
	v_lshlrev_b32_e32 v30, 2, v30
	v_lshlrev_b32_e32 v31, 2, v31
	global_load_dword v32, v160, s[6:7]
	global_load_dword v33, v160, s[6:7] offset:256
	global_load_dword v34, v16, s[0:1]
	global_load_dword v35, v17, s[0:1]
	global_load_dword v36, v16, s[4:5]
	global_load_dword v37, v17, s[4:5]
	s_add_u32 s6, s6, s14
	s_addc_u32 s7, s7, 0
	global_load_dword v38, v160, s[6:7]
	global_load_dword v39, v160, s[6:7] offset:256
	global_load_dword v40, v18, s[0:1]
	global_load_dword v41, v19, s[0:1]
	global_load_dword v42, v18, s[4:5]
	global_load_dword v43, v19, s[4:5]
	s_add_u32 s6, s6, s14
	s_addc_u32 s7, s7, 0
	global_load_dword v44, v160, s[6:7]
	global_load_dword v45, v160, s[6:7] offset:256
	global_load_dword v46, v20, s[0:1]
	global_load_dword v47, v21, s[0:1]
	global_load_dword v48, v20, s[4:5]
	global_load_dword v49, v21, s[4:5]
	s_add_u32 s6, s6, s14
	s_addc_u32 s7, s7, 0
	global_load_dword v50, v160, s[6:7]
	global_load_dword v51, v160, s[6:7] offset:256
	global_load_dword v52, v22, s[0:1]
	global_load_dword v53, v23, s[0:1]
	global_load_dword v54, v22, s[4:5]
	global_load_dword v55, v23, s[4:5]
	s_add_u32 s6, s6, s14
	s_addc_u32 s7, s7, 0
	global_load_dword v56, v160, s[6:7]
	global_load_dword v57, v160, s[6:7] offset:256
	global_load_dword v58, v24, s[0:1]
	global_load_dword v59, v25, s[0:1]
	global_load_dword v60, v24, s[4:5]
	global_load_dword v61, v25, s[4:5]
	s_add_u32 s6, s6, s14
	s_addc_u32 s7, s7, 0
	global_load_dword v62, v160, s[6:7]
	global_load_dword v63, v160, s[6:7] offset:256
	global_load_dword v64, v26, s[0:1]
	global_load_dword v65, v27, s[0:1]
	global_load_dword v66, v26, s[4:5]
	global_load_dword v67, v27, s[4:5]
	s_add_u32 s6, s6, s14
	s_addc_u32 s7, s7, 0
	global_load_dword v68, v160, s[6:7]
	global_load_dword v69, v160, s[6:7] offset:256
	global_load_dword v70, v28, s[0:1]
	global_load_dword v71, v29, s[0:1]
	global_load_dword v72, v28, s[4:5]
	global_load_dword v73, v29, s[4:5]
	s_add_u32 s6, s6, s14
	s_addc_u32 s7, s7, 0
	global_load_dword v74, v160, s[6:7]
	global_load_dword v75, v160, s[6:7] offset:256
	global_load_dword v76, v30, s[0:1]
	global_load_dword v77, v31, s[0:1]
	global_load_dword v78, v30, s[4:5]
	global_load_dword v79, v31, s[4:5]
	s_add_u32 s6, s6, s14
	s_addc_u32 s7, s7, 0
	s_waitcnt vmcnt(0)
	v_mul_f32_e32 v80, v34, v80
	v_mul_f32_e32 v180, 0x3f3504f3, v80
	v_fma_f32 v182, |v180|, s12, v177
	v_fma_f32 v182, |v180|, v182, s15
	v_fma_f32 v182, |v180|, v182, s16
	v_fma_f32 v182, |v180|, v182, s17
	v_fma_f32 v182, |v180|, v182, s18
	v_fma_f32 v182, |v180|, v182, s19
	v_fma_f32 v182, |v180|, v182, |v180|
	v_mul_f32_e32 v184, 0xbfb8aa3b, v182
	v_fma_f32 v185, v182, s98, -v184
	v_rndne_f32_e32 v186, v184
	v_fmac_f32_e32 v185, 0xb2a5705f, v182
	v_sub_f32_e32 v184, v184, v186
	v_add_f32_e32 v184, v184, v185
	v_cvt_i32_f32_e32 v185, v186
	v_exp_f32_e32 v184, v184
	v_cmp_nlt_f32_e32 vcc, s38, v182
	v_ldexp_f32 v184, v184, v185
	s_nop 0
	v_cndmask_b32_e32 v184, 0, v184, vcc
	v_cmp_ngt_f32_e32 vcc, s39, v182
	s_nop 1
	v_cndmask_b32_e32 v184, v178, v184, vcc
	v_sub_f32_e32 v184, 1.0, v184
	v_mul_f32_e32 v183, v180, v180
	v_fmamk_f32 v185, v183, 0xba1345e1, v176
	v_fmaak_f32 v185, v183, v185, 0xbcdac9b8
	v_fmaak_f32 v185, v183, v185, 0x3de703be
	v_fmaak_f32 v185, v183, v185, 0xbec09330
	v_fmaak_f32 v183, v183, v185, 0x3e0375d0
	v_fma_f32 v183, |v180|, v183, |v180|
	v_cmp_nlt_f32_e64 vcc, |v180|, 1.0
	s_nop 1
	v_cndmask_b32_e32 v184, v183, v184, vcc
	v_bfi_b32 v184, s10, v184, v180
	v_add_f32_e32 v184, 1.0, v184
	v_mul_f32_e32 v80, 0.5, v80
	v_mul_f32_e32 v32, v32, v36
	v_mul_f32_e32 v80, v80, v184
	v_mul_f32_e32 v80, v32, v80
	v_mul_f32_e32 v81, v35, v81
	v_mul_f32_e32 v180, 0x3f3504f3, v81
	v_fma_f32 v182, |v180|, s12, v177
	v_fma_f32 v182, |v180|, v182, s15
	v_fma_f32 v182, |v180|, v182, s16
	v_fma_f32 v182, |v180|, v182, s17
	v_fma_f32 v182, |v180|, v182, s18
	v_fma_f32 v182, |v180|, v182, s19
	v_fma_f32 v182, |v180|, v182, |v180|
	v_mul_f32_e32 v184, 0xbfb8aa3b, v182
	v_fma_f32 v185, v182, s98, -v184
	v_rndne_f32_e32 v186, v184
	v_fmac_f32_e32 v185, 0xb2a5705f, v182
	v_sub_f32_e32 v184, v184, v186
	v_add_f32_e32 v184, v184, v185
	v_cvt_i32_f32_e32 v185, v186
	v_exp_f32_e32 v184, v184
	v_cmp_nlt_f32_e32 vcc, s38, v182
	v_ldexp_f32 v184, v184, v185
	s_nop 0
	v_cndmask_b32_e32 v184, 0, v184, vcc
	v_cmp_ngt_f32_e32 vcc, s39, v182
	s_nop 1
	v_cndmask_b32_e32 v184, v178, v184, vcc
	v_sub_f32_e32 v184, 1.0, v184
	v_mul_f32_e32 v183, v180, v180
	v_fmamk_f32 v185, v183, 0xba1345e1, v176
	v_fmaak_f32 v185, v183, v185, 0xbcdac9b8
	v_fmaak_f32 v185, v183, v185, 0x3de703be
	v_fmaak_f32 v185, v183, v185, 0xbec09330
	v_fmaak_f32 v183, v183, v185, 0x3e0375d0
	v_fma_f32 v183, |v180|, v183, |v180|
	v_cmp_nlt_f32_e64 vcc, |v180|, 1.0
	s_nop 1
	v_cndmask_b32_e32 v184, v183, v184, vcc
	v_bfi_b32 v184, s10, v184, v180
	v_add_f32_e32 v184, 1.0, v184
	v_mul_f32_e32 v81, 0.5, v81
	v_mul_f32_e32 v33, v33, v37
	v_mul_f32_e32 v81, v81, v184
	v_mul_f32_e32 v81, v33, v81
	global_store_dword v160, v80, s[8:9]
	global_store_dword v160, v81, s[8:9] offset:256
	s_add_u32 s8, s8, s14
	s_addc_u32 s9, s9, 0
	v_mul_f32_e32 v82, v40, v82
	v_mul_f32_e32 v180, 0x3f3504f3, v82
	v_fma_f32 v182, |v180|, s12, v177
	v_fma_f32 v182, |v180|, v182, s15
	v_fma_f32 v182, |v180|, v182, s16
	v_fma_f32 v182, |v180|, v182, s17
	v_fma_f32 v182, |v180|, v182, s18
	v_fma_f32 v182, |v180|, v182, s19
	v_fma_f32 v182, |v180|, v182, |v180|
	v_mul_f32_e32 v184, 0xbfb8aa3b, v182
	v_fma_f32 v185, v182, s98, -v184
	v_rndne_f32_e32 v186, v184
	v_fmac_f32_e32 v185, 0xb2a5705f, v182
	v_sub_f32_e32 v184, v184, v186
	v_add_f32_e32 v184, v184, v185
	v_cvt_i32_f32_e32 v185, v186
	v_exp_f32_e32 v184, v184
	v_cmp_nlt_f32_e32 vcc, s38, v182
	v_ldexp_f32 v184, v184, v185
	s_nop 0
	v_cndmask_b32_e32 v184, 0, v184, vcc
	v_cmp_ngt_f32_e32 vcc, s39, v182
	s_nop 1
	v_cndmask_b32_e32 v184, v178, v184, vcc
	v_sub_f32_e32 v184, 1.0, v184
	v_mul_f32_e32 v183, v180, v180
	v_fmamk_f32 v185, v183, 0xba1345e1, v176
	v_fmaak_f32 v185, v183, v185, 0xbcdac9b8
	v_fmaak_f32 v185, v183, v185, 0x3de703be
	v_fmaak_f32 v185, v183, v185, 0xbec09330
	v_fmaak_f32 v183, v183, v185, 0x3e0375d0
	v_fma_f32 v183, |v180|, v183, |v180|
	v_cmp_nlt_f32_e64 vcc, |v180|, 1.0
	s_nop 1
	v_cndmask_b32_e32 v184, v183, v184, vcc
	v_bfi_b32 v184, s10, v184, v180
	v_add_f32_e32 v184, 1.0, v184
	v_mul_f32_e32 v82, 0.5, v82
	v_mul_f32_e32 v38, v38, v42
	v_mul_f32_e32 v82, v82, v184
	v_mul_f32_e32 v82, v38, v82
	v_mul_f32_e32 v83, v41, v83
	v_mul_f32_e32 v180, 0x3f3504f3, v83
	v_fma_f32 v182, |v180|, s12, v177
	v_fma_f32 v182, |v180|, v182, s15
	v_fma_f32 v182, |v180|, v182, s16
	v_fma_f32 v182, |v180|, v182, s17
	v_fma_f32 v182, |v180|, v182, s18
	v_fma_f32 v182, |v180|, v182, s19
	v_fma_f32 v182, |v180|, v182, |v180|
	v_mul_f32_e32 v184, 0xbfb8aa3b, v182
	v_fma_f32 v185, v182, s98, -v184
	v_rndne_f32_e32 v186, v184
	v_fmac_f32_e32 v185, 0xb2a5705f, v182
	v_sub_f32_e32 v184, v184, v186
	v_add_f32_e32 v184, v184, v185
	v_cvt_i32_f32_e32 v185, v186
	v_exp_f32_e32 v184, v184
	v_cmp_nlt_f32_e32 vcc, s38, v182
	v_ldexp_f32 v184, v184, v185
	s_nop 0
	v_cndmask_b32_e32 v184, 0, v184, vcc
	v_cmp_ngt_f32_e32 vcc, s39, v182
	s_nop 1
	v_cndmask_b32_e32 v184, v178, v184, vcc
	v_sub_f32_e32 v184, 1.0, v184
	v_mul_f32_e32 v183, v180, v180
	v_fmamk_f32 v185, v183, 0xba1345e1, v176
	v_fmaak_f32 v185, v183, v185, 0xbcdac9b8
	v_fmaak_f32 v185, v183, v185, 0x3de703be
	v_fmaak_f32 v185, v183, v185, 0xbec09330
	v_fmaak_f32 v183, v183, v185, 0x3e0375d0
	v_fma_f32 v183, |v180|, v183, |v180|
	v_cmp_nlt_f32_e64 vcc, |v180|, 1.0
	s_nop 1
	v_cndmask_b32_e32 v184, v183, v184, vcc
	v_bfi_b32 v184, s10, v184, v180
	v_add_f32_e32 v184, 1.0, v184
	v_mul_f32_e32 v83, 0.5, v83
	v_mul_f32_e32 v39, v39, v43
	v_mul_f32_e32 v83, v83, v184
	v_mul_f32_e32 v83, v39, v83
	global_store_dword v160, v82, s[8:9]
	global_store_dword v160, v83, s[8:9] offset:256
	s_add_u32 s8, s8, s14
	s_addc_u32 s9, s9, 0
	v_mul_f32_e32 v84, v46, v84
	v_mul_f32_e32 v180, 0x3f3504f3, v84
	v_fma_f32 v182, |v180|, s12, v177
	v_fma_f32 v182, |v180|, v182, s15
	v_fma_f32 v182, |v180|, v182, s16
	v_fma_f32 v182, |v180|, v182, s17
	v_fma_f32 v182, |v180|, v182, s18
	v_fma_f32 v182, |v180|, v182, s19
	v_fma_f32 v182, |v180|, v182, |v180|
	v_mul_f32_e32 v184, 0xbfb8aa3b, v182
	v_fma_f32 v185, v182, s98, -v184
	v_rndne_f32_e32 v186, v184
	v_fmac_f32_e32 v185, 0xb2a5705f, v182
	v_sub_f32_e32 v184, v184, v186
	v_add_f32_e32 v184, v184, v185
	v_cvt_i32_f32_e32 v185, v186
	v_exp_f32_e32 v184, v184
	v_cmp_nlt_f32_e32 vcc, s38, v182
	v_ldexp_f32 v184, v184, v185
	s_nop 0
	v_cndmask_b32_e32 v184, 0, v184, vcc
	v_cmp_ngt_f32_e32 vcc, s39, v182
	s_nop 1
	v_cndmask_b32_e32 v184, v178, v184, vcc
	v_sub_f32_e32 v184, 1.0, v184
	v_mul_f32_e32 v183, v180, v180
	v_fmamk_f32 v185, v183, 0xba1345e1, v176
	v_fmaak_f32 v185, v183, v185, 0xbcdac9b8
	v_fmaak_f32 v185, v183, v185, 0x3de703be
	v_fmaak_f32 v185, v183, v185, 0xbec09330
	v_fmaak_f32 v183, v183, v185, 0x3e0375d0
	v_fma_f32 v183, |v180|, v183, |v180|
	v_cmp_nlt_f32_e64 vcc, |v180|, 1.0
	s_nop 1
	v_cndmask_b32_e32 v184, v183, v184, vcc
	v_bfi_b32 v184, s10, v184, v180
	v_add_f32_e32 v184, 1.0, v184
	v_mul_f32_e32 v84, 0.5, v84
	v_mul_f32_e32 v44, v44, v48
	v_mul_f32_e32 v84, v84, v184
	v_mul_f32_e32 v84, v44, v84
	v_mul_f32_e32 v85, v47, v85
	v_mul_f32_e32 v180, 0x3f3504f3, v85
	v_fma_f32 v182, |v180|, s12, v177
	v_fma_f32 v182, |v180|, v182, s15
	v_fma_f32 v182, |v180|, v182, s16
	v_fma_f32 v182, |v180|, v182, s17
	v_fma_f32 v182, |v180|, v182, s18
	v_fma_f32 v182, |v180|, v182, s19
	v_fma_f32 v182, |v180|, v182, |v180|
	v_mul_f32_e32 v184, 0xbfb8aa3b, v182
	v_fma_f32 v185, v182, s98, -v184
	v_rndne_f32_e32 v186, v184
	v_fmac_f32_e32 v185, 0xb2a5705f, v182
	v_sub_f32_e32 v184, v184, v186
	v_add_f32_e32 v184, v184, v185
	v_cvt_i32_f32_e32 v185, v186
	v_exp_f32_e32 v184, v184
	v_cmp_nlt_f32_e32 vcc, s38, v182
	v_ldexp_f32 v184, v184, v185
	s_nop 0
	v_cndmask_b32_e32 v184, 0, v184, vcc
	v_cmp_ngt_f32_e32 vcc, s39, v182
	s_nop 1
	v_cndmask_b32_e32 v184, v178, v184, vcc
	v_sub_f32_e32 v184, 1.0, v184
	v_mul_f32_e32 v183, v180, v180
	v_fmamk_f32 v185, v183, 0xba1345e1, v176
	v_fmaak_f32 v185, v183, v185, 0xbcdac9b8
	v_fmaak_f32 v185, v183, v185, 0x3de703be
	v_fmaak_f32 v185, v183, v185, 0xbec09330
	v_fmaak_f32 v183, v183, v185, 0x3e0375d0
	v_fma_f32 v183, |v180|, v183, |v180|
	v_cmp_nlt_f32_e64 vcc, |v180|, 1.0
	s_nop 1
	v_cndmask_b32_e32 v184, v183, v184, vcc
	v_bfi_b32 v184, s10, v184, v180
	v_add_f32_e32 v184, 1.0, v184
	v_mul_f32_e32 v85, 0.5, v85
	v_mul_f32_e32 v45, v45, v49
	v_mul_f32_e32 v85, v85, v184
	v_mul_f32_e32 v85, v45, v85
	global_store_dword v160, v84, s[8:9]
	global_store_dword v160, v85, s[8:9] offset:256
	s_add_u32 s8, s8, s14
	s_addc_u32 s9, s9, 0
	v_mul_f32_e32 v86, v52, v86
	v_mul_f32_e32 v180, 0x3f3504f3, v86
	v_fma_f32 v182, |v180|, s12, v177
	v_fma_f32 v182, |v180|, v182, s15
	v_fma_f32 v182, |v180|, v182, s16
	v_fma_f32 v182, |v180|, v182, s17
	v_fma_f32 v182, |v180|, v182, s18
	v_fma_f32 v182, |v180|, v182, s19
	v_fma_f32 v182, |v180|, v182, |v180|
	v_mul_f32_e32 v184, 0xbfb8aa3b, v182
	v_fma_f32 v185, v182, s98, -v184
	v_rndne_f32_e32 v186, v184
	v_fmac_f32_e32 v185, 0xb2a5705f, v182
	v_sub_f32_e32 v184, v184, v186
	v_add_f32_e32 v184, v184, v185
	v_cvt_i32_f32_e32 v185, v186
	v_exp_f32_e32 v184, v184
	v_cmp_nlt_f32_e32 vcc, s38, v182
	v_ldexp_f32 v184, v184, v185
	s_nop 0
	v_cndmask_b32_e32 v184, 0, v184, vcc
	v_cmp_ngt_f32_e32 vcc, s39, v182
	s_nop 1
	v_cndmask_b32_e32 v184, v178, v184, vcc
	v_sub_f32_e32 v184, 1.0, v184
	v_mul_f32_e32 v183, v180, v180
	v_fmamk_f32 v185, v183, 0xba1345e1, v176
	v_fmaak_f32 v185, v183, v185, 0xbcdac9b8
	v_fmaak_f32 v185, v183, v185, 0x3de703be
	v_fmaak_f32 v185, v183, v185, 0xbec09330
	v_fmaak_f32 v183, v183, v185, 0x3e0375d0
	v_fma_f32 v183, |v180|, v183, |v180|
	v_cmp_nlt_f32_e64 vcc, |v180|, 1.0
	s_nop 1
	v_cndmask_b32_e32 v184, v183, v184, vcc
	v_bfi_b32 v184, s10, v184, v180
	v_add_f32_e32 v184, 1.0, v184
	v_mul_f32_e32 v86, 0.5, v86
	v_mul_f32_e32 v50, v50, v54
	v_mul_f32_e32 v86, v86, v184
	v_mul_f32_e32 v86, v50, v86
	v_mul_f32_e32 v87, v53, v87
	v_mul_f32_e32 v180, 0x3f3504f3, v87
	v_fma_f32 v182, |v180|, s12, v177
	v_fma_f32 v182, |v180|, v182, s15
	v_fma_f32 v182, |v180|, v182, s16
	v_fma_f32 v182, |v180|, v182, s17
	v_fma_f32 v182, |v180|, v182, s18
	v_fma_f32 v182, |v180|, v182, s19
	v_fma_f32 v182, |v180|, v182, |v180|
	v_mul_f32_e32 v184, 0xbfb8aa3b, v182
	v_fma_f32 v185, v182, s98, -v184
	v_rndne_f32_e32 v186, v184
	v_fmac_f32_e32 v185, 0xb2a5705f, v182
	v_sub_f32_e32 v184, v184, v186
	v_add_f32_e32 v184, v184, v185
	v_cvt_i32_f32_e32 v185, v186
	v_exp_f32_e32 v184, v184
	v_cmp_nlt_f32_e32 vcc, s38, v182
	v_ldexp_f32 v184, v184, v185
	s_nop 0
	v_cndmask_b32_e32 v184, 0, v184, vcc
	v_cmp_ngt_f32_e32 vcc, s39, v182
	s_nop 1
	v_cndmask_b32_e32 v184, v178, v184, vcc
	v_sub_f32_e32 v184, 1.0, v184
	v_mul_f32_e32 v183, v180, v180
	v_fmamk_f32 v185, v183, 0xba1345e1, v176
	v_fmaak_f32 v185, v183, v185, 0xbcdac9b8
	v_fmaak_f32 v185, v183, v185, 0x3de703be
	v_fmaak_f32 v185, v183, v185, 0xbec09330
	v_fmaak_f32 v183, v183, v185, 0x3e0375d0
	v_fma_f32 v183, |v180|, v183, |v180|
	v_cmp_nlt_f32_e64 vcc, |v180|, 1.0
	s_nop 1
	v_cndmask_b32_e32 v184, v183, v184, vcc
	v_bfi_b32 v184, s10, v184, v180
	v_add_f32_e32 v184, 1.0, v184
	v_mul_f32_e32 v87, 0.5, v87
	v_mul_f32_e32 v51, v51, v55
	v_mul_f32_e32 v87, v87, v184
	v_mul_f32_e32 v87, v51, v87
	global_store_dword v160, v86, s[8:9]
	global_store_dword v160, v87, s[8:9] offset:256
	s_add_u32 s8, s8, s14
	s_addc_u32 s9, s9, 0
	v_mul_f32_e32 v88, v58, v88
	v_mul_f32_e32 v180, 0x3f3504f3, v88
	v_fma_f32 v182, |v180|, s12, v177
	v_fma_f32 v182, |v180|, v182, s15
	v_fma_f32 v182, |v180|, v182, s16
	v_fma_f32 v182, |v180|, v182, s17
	v_fma_f32 v182, |v180|, v182, s18
	v_fma_f32 v182, |v180|, v182, s19
	v_fma_f32 v182, |v180|, v182, |v180|
	v_mul_f32_e32 v184, 0xbfb8aa3b, v182
	v_fma_f32 v185, v182, s98, -v184
	v_rndne_f32_e32 v186, v184
	v_fmac_f32_e32 v185, 0xb2a5705f, v182
	v_sub_f32_e32 v184, v184, v186
	v_add_f32_e32 v184, v184, v185
	v_cvt_i32_f32_e32 v185, v186
	v_exp_f32_e32 v184, v184
	v_cmp_nlt_f32_e32 vcc, s38, v182
	v_ldexp_f32 v184, v184, v185
	s_nop 0
	v_cndmask_b32_e32 v184, 0, v184, vcc
	v_cmp_ngt_f32_e32 vcc, s39, v182
	s_nop 1
	v_cndmask_b32_e32 v184, v178, v184, vcc
	v_sub_f32_e32 v184, 1.0, v184
	v_mul_f32_e32 v183, v180, v180
	v_fmamk_f32 v185, v183, 0xba1345e1, v176
	v_fmaak_f32 v185, v183, v185, 0xbcdac9b8
	v_fmaak_f32 v185, v183, v185, 0x3de703be
	v_fmaak_f32 v185, v183, v185, 0xbec09330
	v_fmaak_f32 v183, v183, v185, 0x3e0375d0
	v_fma_f32 v183, |v180|, v183, |v180|
	v_cmp_nlt_f32_e64 vcc, |v180|, 1.0
	s_nop 1
	v_cndmask_b32_e32 v184, v183, v184, vcc
	v_bfi_b32 v184, s10, v184, v180
	v_add_f32_e32 v184, 1.0, v184
	v_mul_f32_e32 v88, 0.5, v88
	v_mul_f32_e32 v56, v56, v60
	v_mul_f32_e32 v88, v88, v184
	v_mul_f32_e32 v88, v56, v88
	v_mul_f32_e32 v89, v59, v89
	v_mul_f32_e32 v180, 0x3f3504f3, v89
	v_fma_f32 v182, |v180|, s12, v177
	v_fma_f32 v182, |v180|, v182, s15
	v_fma_f32 v182, |v180|, v182, s16
	v_fma_f32 v182, |v180|, v182, s17
	v_fma_f32 v182, |v180|, v182, s18
	v_fma_f32 v182, |v180|, v182, s19
	v_fma_f32 v182, |v180|, v182, |v180|
	v_mul_f32_e32 v184, 0xbfb8aa3b, v182
	v_fma_f32 v185, v182, s98, -v184
	v_rndne_f32_e32 v186, v184
	v_fmac_f32_e32 v185, 0xb2a5705f, v182
	v_sub_f32_e32 v184, v184, v186
	v_add_f32_e32 v184, v184, v185
	v_cvt_i32_f32_e32 v185, v186
	v_exp_f32_e32 v184, v184
	v_cmp_nlt_f32_e32 vcc, s38, v182
	v_ldexp_f32 v184, v184, v185
	s_nop 0
	v_cndmask_b32_e32 v184, 0, v184, vcc
	v_cmp_ngt_f32_e32 vcc, s39, v182
	s_nop 1
	v_cndmask_b32_e32 v184, v178, v184, vcc
	v_sub_f32_e32 v184, 1.0, v184
	v_mul_f32_e32 v183, v180, v180
	v_fmamk_f32 v185, v183, 0xba1345e1, v176
	v_fmaak_f32 v185, v183, v185, 0xbcdac9b8
	v_fmaak_f32 v185, v183, v185, 0x3de703be
	v_fmaak_f32 v185, v183, v185, 0xbec09330
	v_fmaak_f32 v183, v183, v185, 0x3e0375d0
	v_fma_f32 v183, |v180|, v183, |v180|
	v_cmp_nlt_f32_e64 vcc, |v180|, 1.0
	s_nop 1
	v_cndmask_b32_e32 v184, v183, v184, vcc
	v_bfi_b32 v184, s10, v184, v180
	v_add_f32_e32 v184, 1.0, v184
	v_mul_f32_e32 v89, 0.5, v89
	v_mul_f32_e32 v57, v57, v61
	v_mul_f32_e32 v89, v89, v184
	v_mul_f32_e32 v89, v57, v89
	global_store_dword v160, v88, s[8:9]
	global_store_dword v160, v89, s[8:9] offset:256
	s_add_u32 s8, s8, s14
	s_addc_u32 s9, s9, 0
	v_mul_f32_e32 v90, v64, v90
	v_mul_f32_e32 v180, 0x3f3504f3, v90
	v_fma_f32 v182, |v180|, s12, v177
	v_fma_f32 v182, |v180|, v182, s15
	v_fma_f32 v182, |v180|, v182, s16
	v_fma_f32 v182, |v180|, v182, s17
	v_fma_f32 v182, |v180|, v182, s18
	v_fma_f32 v182, |v180|, v182, s19
	v_fma_f32 v182, |v180|, v182, |v180|
	v_mul_f32_e32 v184, 0xbfb8aa3b, v182
	v_fma_f32 v185, v182, s98, -v184
	v_rndne_f32_e32 v186, v184
	v_fmac_f32_e32 v185, 0xb2a5705f, v182
	v_sub_f32_e32 v184, v184, v186
	v_add_f32_e32 v184, v184, v185
	v_cvt_i32_f32_e32 v185, v186
	v_exp_f32_e32 v184, v184
	v_cmp_nlt_f32_e32 vcc, s38, v182
	v_ldexp_f32 v184, v184, v185
	s_nop 0
	v_cndmask_b32_e32 v184, 0, v184, vcc
	v_cmp_ngt_f32_e32 vcc, s39, v182
	s_nop 1
	v_cndmask_b32_e32 v184, v178, v184, vcc
	v_sub_f32_e32 v184, 1.0, v184
	v_mul_f32_e32 v183, v180, v180
	v_fmamk_f32 v185, v183, 0xba1345e1, v176
	v_fmaak_f32 v185, v183, v185, 0xbcdac9b8
	v_fmaak_f32 v185, v183, v185, 0x3de703be
	v_fmaak_f32 v185, v183, v185, 0xbec09330
	v_fmaak_f32 v183, v183, v185, 0x3e0375d0
	v_fma_f32 v183, |v180|, v183, |v180|
	v_cmp_nlt_f32_e64 vcc, |v180|, 1.0
	s_nop 1
	v_cndmask_b32_e32 v184, v183, v184, vcc
	v_bfi_b32 v184, s10, v184, v180
	v_add_f32_e32 v184, 1.0, v184
	v_mul_f32_e32 v90, 0.5, v90
	v_mul_f32_e32 v62, v62, v66
	v_mul_f32_e32 v90, v90, v184
	v_mul_f32_e32 v90, v62, v90
	v_mul_f32_e32 v91, v65, v91
	v_mul_f32_e32 v180, 0x3f3504f3, v91
	v_fma_f32 v182, |v180|, s12, v177
	v_fma_f32 v182, |v180|, v182, s15
	v_fma_f32 v182, |v180|, v182, s16
	v_fma_f32 v182, |v180|, v182, s17
	v_fma_f32 v182, |v180|, v182, s18
	v_fma_f32 v182, |v180|, v182, s19
	v_fma_f32 v182, |v180|, v182, |v180|
	v_mul_f32_e32 v184, 0xbfb8aa3b, v182
	v_fma_f32 v185, v182, s98, -v184
	v_rndne_f32_e32 v186, v184
	v_fmac_f32_e32 v185, 0xb2a5705f, v182
	v_sub_f32_e32 v184, v184, v186
	v_add_f32_e32 v184, v184, v185
	v_cvt_i32_f32_e32 v185, v186
	v_exp_f32_e32 v184, v184
	v_cmp_nlt_f32_e32 vcc, s38, v182
	v_ldexp_f32 v184, v184, v185
	s_nop 0
	v_cndmask_b32_e32 v184, 0, v184, vcc
	v_cmp_ngt_f32_e32 vcc, s39, v182
	s_nop 1
	v_cndmask_b32_e32 v184, v178, v184, vcc
	v_sub_f32_e32 v184, 1.0, v184
	v_mul_f32_e32 v183, v180, v180
	v_fmamk_f32 v185, v183, 0xba1345e1, v176
	v_fmaak_f32 v185, v183, v185, 0xbcdac9b8
	v_fmaak_f32 v185, v183, v185, 0x3de703be
	v_fmaak_f32 v185, v183, v185, 0xbec09330
	v_fmaak_f32 v183, v183, v185, 0x3e0375d0
	v_fma_f32 v183, |v180|, v183, |v180|
	v_cmp_nlt_f32_e64 vcc, |v180|, 1.0
	s_nop 1
	v_cndmask_b32_e32 v184, v183, v184, vcc
	v_bfi_b32 v184, s10, v184, v180
	v_add_f32_e32 v184, 1.0, v184
	v_mul_f32_e32 v91, 0.5, v91
	v_mul_f32_e32 v63, v63, v67
	v_mul_f32_e32 v91, v91, v184
	v_mul_f32_e32 v91, v63, v91
	global_store_dword v160, v90, s[8:9]
	global_store_dword v160, v91, s[8:9] offset:256
	s_add_u32 s8, s8, s14
	s_addc_u32 s9, s9, 0
	v_mul_f32_e32 v92, v70, v92
	v_mul_f32_e32 v180, 0x3f3504f3, v92
	v_fma_f32 v182, |v180|, s12, v177
	v_fma_f32 v182, |v180|, v182, s15
	v_fma_f32 v182, |v180|, v182, s16
	v_fma_f32 v182, |v180|, v182, s17
	v_fma_f32 v182, |v180|, v182, s18
	v_fma_f32 v182, |v180|, v182, s19
	v_fma_f32 v182, |v180|, v182, |v180|
	v_mul_f32_e32 v184, 0xbfb8aa3b, v182
	v_fma_f32 v185, v182, s98, -v184
	v_rndne_f32_e32 v186, v184
	v_fmac_f32_e32 v185, 0xb2a5705f, v182
	v_sub_f32_e32 v184, v184, v186
	v_add_f32_e32 v184, v184, v185
	v_cvt_i32_f32_e32 v185, v186
	v_exp_f32_e32 v184, v184
	v_cmp_nlt_f32_e32 vcc, s38, v182
	v_ldexp_f32 v184, v184, v185
	s_nop 0
	v_cndmask_b32_e32 v184, 0, v184, vcc
	v_cmp_ngt_f32_e32 vcc, s39, v182
	s_nop 1
	v_cndmask_b32_e32 v184, v178, v184, vcc
	v_sub_f32_e32 v184, 1.0, v184
	v_mul_f32_e32 v183, v180, v180
	v_fmamk_f32 v185, v183, 0xba1345e1, v176
	v_fmaak_f32 v185, v183, v185, 0xbcdac9b8
	v_fmaak_f32 v185, v183, v185, 0x3de703be
	v_fmaak_f32 v185, v183, v185, 0xbec09330
	v_fmaak_f32 v183, v183, v185, 0x3e0375d0
	v_fma_f32 v183, |v180|, v183, |v180|
	v_cmp_nlt_f32_e64 vcc, |v180|, 1.0
	s_nop 1
	v_cndmask_b32_e32 v184, v183, v184, vcc
	v_bfi_b32 v184, s10, v184, v180
	v_add_f32_e32 v184, 1.0, v184
	v_mul_f32_e32 v92, 0.5, v92
	v_mul_f32_e32 v68, v68, v72
	v_mul_f32_e32 v92, v92, v184
	v_mul_f32_e32 v92, v68, v92
	v_mul_f32_e32 v93, v71, v93
	v_mul_f32_e32 v180, 0x3f3504f3, v93
	v_fma_f32 v182, |v180|, s12, v177
	v_fma_f32 v182, |v180|, v182, s15
	v_fma_f32 v182, |v180|, v182, s16
	v_fma_f32 v182, |v180|, v182, s17
	v_fma_f32 v182, |v180|, v182, s18
	v_fma_f32 v182, |v180|, v182, s19
	v_fma_f32 v182, |v180|, v182, |v180|
	v_mul_f32_e32 v184, 0xbfb8aa3b, v182
	v_fma_f32 v185, v182, s98, -v184
	v_rndne_f32_e32 v186, v184
	v_fmac_f32_e32 v185, 0xb2a5705f, v182
	v_sub_f32_e32 v184, v184, v186
	v_add_f32_e32 v184, v184, v185
	v_cvt_i32_f32_e32 v185, v186
	v_exp_f32_e32 v184, v184
	v_cmp_nlt_f32_e32 vcc, s38, v182
	v_ldexp_f32 v184, v184, v185
	s_nop 0
	v_cndmask_b32_e32 v184, 0, v184, vcc
	v_cmp_ngt_f32_e32 vcc, s39, v182
	s_nop 1
	v_cndmask_b32_e32 v184, v178, v184, vcc
	v_sub_f32_e32 v184, 1.0, v184
	v_mul_f32_e32 v183, v180, v180
	v_fmamk_f32 v185, v183, 0xba1345e1, v176
	v_fmaak_f32 v185, v183, v185, 0xbcdac9b8
	v_fmaak_f32 v185, v183, v185, 0x3de703be
	v_fmaak_f32 v185, v183, v185, 0xbec09330
	v_fmaak_f32 v183, v183, v185, 0x3e0375d0
	v_fma_f32 v183, |v180|, v183, |v180|
	v_cmp_nlt_f32_e64 vcc, |v180|, 1.0
	s_nop 1
	v_cndmask_b32_e32 v184, v183, v184, vcc
	v_bfi_b32 v184, s10, v184, v180
	v_add_f32_e32 v184, 1.0, v184
	v_mul_f32_e32 v93, 0.5, v93
	v_mul_f32_e32 v69, v69, v73
	v_mul_f32_e32 v93, v93, v184
	v_mul_f32_e32 v93, v69, v93
	global_store_dword v160, v92, s[8:9]
	global_store_dword v160, v93, s[8:9] offset:256
	s_add_u32 s8, s8, s14
	s_addc_u32 s9, s9, 0
	v_mul_f32_e32 v94, v76, v94
	v_mul_f32_e32 v180, 0x3f3504f3, v94
	v_fma_f32 v182, |v180|, s12, v177
	v_fma_f32 v182, |v180|, v182, s15
	v_fma_f32 v182, |v180|, v182, s16
	v_fma_f32 v182, |v180|, v182, s17
	v_fma_f32 v182, |v180|, v182, s18
	v_fma_f32 v182, |v180|, v182, s19
	v_fma_f32 v182, |v180|, v182, |v180|
	v_mul_f32_e32 v184, 0xbfb8aa3b, v182
	v_fma_f32 v185, v182, s98, -v184
	v_rndne_f32_e32 v186, v184
	v_fmac_f32_e32 v185, 0xb2a5705f, v182
	v_sub_f32_e32 v184, v184, v186
	v_add_f32_e32 v184, v184, v185
	v_cvt_i32_f32_e32 v185, v186
	v_exp_f32_e32 v184, v184
	v_cmp_nlt_f32_e32 vcc, s38, v182
	v_ldexp_f32 v184, v184, v185
	s_nop 0
	v_cndmask_b32_e32 v184, 0, v184, vcc
	v_cmp_ngt_f32_e32 vcc, s39, v182
	s_nop 1
	v_cndmask_b32_e32 v184, v178, v184, vcc
	v_sub_f32_e32 v184, 1.0, v184
	v_mul_f32_e32 v183, v180, v180
	v_fmamk_f32 v185, v183, 0xba1345e1, v176
	v_fmaak_f32 v185, v183, v185, 0xbcdac9b8
	v_fmaak_f32 v185, v183, v185, 0x3de703be
	v_fmaak_f32 v185, v183, v185, 0xbec09330
	v_fmaak_f32 v183, v183, v185, 0x3e0375d0
	v_fma_f32 v183, |v180|, v183, |v180|
	v_cmp_nlt_f32_e64 vcc, |v180|, 1.0
	s_nop 1
	v_cndmask_b32_e32 v184, v183, v184, vcc
	v_bfi_b32 v184, s10, v184, v180
	v_add_f32_e32 v184, 1.0, v184
	v_mul_f32_e32 v94, 0.5, v94
	v_mul_f32_e32 v74, v74, v78
	v_mul_f32_e32 v94, v94, v184
	v_mul_f32_e32 v94, v74, v94
	v_mul_f32_e32 v95, v77, v95
	v_mul_f32_e32 v180, 0x3f3504f3, v95
	v_fma_f32 v182, |v180|, s12, v177
	v_fma_f32 v182, |v180|, v182, s15
	v_fma_f32 v182, |v180|, v182, s16
	v_fma_f32 v182, |v180|, v182, s17
	v_fma_f32 v182, |v180|, v182, s18
	v_fma_f32 v182, |v180|, v182, s19
	v_fma_f32 v182, |v180|, v182, |v180|
	v_mul_f32_e32 v184, 0xbfb8aa3b, v182
	v_fma_f32 v185, v182, s98, -v184
	v_rndne_f32_e32 v186, v184
	v_fmac_f32_e32 v185, 0xb2a5705f, v182
	v_sub_f32_e32 v184, v184, v186
	v_add_f32_e32 v184, v184, v185
	v_cvt_i32_f32_e32 v185, v186
	v_exp_f32_e32 v184, v184
	v_cmp_nlt_f32_e32 vcc, s38, v182
	v_ldexp_f32 v184, v184, v185
	s_nop 0
	v_cndmask_b32_e32 v184, 0, v184, vcc
	v_cmp_ngt_f32_e32 vcc, s39, v182
	s_nop 1
	v_cndmask_b32_e32 v184, v178, v184, vcc
	v_sub_f32_e32 v184, 1.0, v184
	v_mul_f32_e32 v183, v180, v180
	v_fmamk_f32 v185, v183, 0xba1345e1, v176
	v_fmaak_f32 v185, v183, v185, 0xbcdac9b8
	v_fmaak_f32 v185, v183, v185, 0x3de703be
	v_fmaak_f32 v185, v183, v185, 0xbec09330
	v_fmaak_f32 v183, v183, v185, 0x3e0375d0
	v_fma_f32 v183, |v180|, v183, |v180|
	v_cmp_nlt_f32_e64 vcc, |v180|, 1.0
	s_nop 1
	v_cndmask_b32_e32 v184, v183, v184, vcc
	v_bfi_b32 v184, s10, v184, v180
	v_add_f32_e32 v184, 1.0, v184
	v_mul_f32_e32 v95, 0.5, v95
	v_mul_f32_e32 v75, v75, v79
	v_mul_f32_e32 v95, v95, v184
	v_mul_f32_e32 v95, v75, v95
	global_store_dword v160, v94, s[8:9]
	global_store_dword v160, v95, s[8:9] offset:256
	s_add_u32 s8, s8, s14
	s_addc_u32 s9, s9, 0
	s_lshl_b32 s13, s92, 6
	s_add_u32 s35, s35, s13
	s_cmpk_lt_u32 s35, 0x8000
	s_cbranch_scc1 .Lgu1_chunk
	s_branch .LBB0_1045

.Lgv1_chunk:
	s_movk_i32 s100, 0xc0
	s_lshl_b32 s16, s92, 14
	s_add_u32 s12, s26, 0xd800000
	s_addc_u32 s13, s27, 0
	s_lshl_b32 s15, s101, 9
	s_add_u32 s12, s12, s15
	s_addc_u32 s13, s13, 0
	s_lshl_b32 s18, s92, 11
	global_load_dword v64, v196, s[12:13]
	global_load_dword v65, v196, s[12:13] offset:256
	s_add_u32 s12, s12, s18
	s_addc_u32 s13, s13, 0
	global_load_dword v66, v196, s[12:13]
	global_load_dword v67, v196, s[12:13] offset:256
	s_add_u32 s12, s12, s18
	s_addc_u32 s13, s13, 0
	global_load_dword v68, v196, s[12:13]
	global_load_dword v69, v196, s[12:13] offset:256
	s_add_u32 s12, s12, s18
	s_addc_u32 s13, s13, 0
	global_load_dword v70, v196, s[12:13]
	global_load_dword v71, v196, s[12:13] offset:256
	s_add_u32 s12, s12, s18
	s_addc_u32 s13, s13, 0
	global_load_dword v72, v196, s[12:13]
	global_load_dword v73, v196, s[12:13] offset:256
	s_add_u32 s12, s12, s18
	s_addc_u32 s13, s13, 0
	global_load_dword v74, v196, s[12:13]
	global_load_dword v75, v196, s[12:13] offset:256
	s_add_u32 s12, s12, s18
	s_addc_u32 s13, s13, 0
	global_load_dword v76, v196, s[12:13]
	global_load_dword v77, v196, s[12:13] offset:256
	s_add_u32 s12, s12, s18
	s_addc_u32 s13, s13, 0
	global_load_dword v78, v196, s[12:13]
	global_load_dword v79, v196, s[12:13] offset:256
	s_add_u32 s12, s12, s18
	s_addc_u32 s13, s13, 0
	global_load_dword v80, v196, s[12:13]
	global_load_dword v81, v196, s[12:13] offset:256
	s_add_u32 s12, s12, s18
	s_addc_u32 s13, s13, 0
	global_load_dword v82, v196, s[12:13]
	global_load_dword v83, v196, s[12:13] offset:256
	s_add_u32 s12, s12, s18
	s_addc_u32 s13, s13, 0
	global_load_dword v84, v196, s[12:13]
	global_load_dword v85, v196, s[12:13] offset:256
	s_add_u32 s12, s12, s18
	s_addc_u32 s13, s13, 0
	global_load_dword v86, v196, s[12:13]
	global_load_dword v87, v196, s[12:13] offset:256
	s_add_u32 s12, s12, s18
	s_addc_u32 s13, s13, 0
	global_load_dword v88, v196, s[12:13]
	global_load_dword v89, v196, s[12:13] offset:256
	s_add_u32 s12, s12, s18
	s_addc_u32 s13, s13, 0
	global_load_dword v90, v196, s[12:13]
	global_load_dword v91, v196, s[12:13] offset:256
	s_add_u32 s12, s12, s18
	s_addc_u32 s13, s13, 0
	global_load_dword v92, v196, s[12:13]
	global_load_dword v93, v196, s[12:13] offset:256
	s_add_u32 s12, s12, s18
	s_addc_u32 s13, s13, 0
	global_load_dword v94, v196, s[12:13]
	global_load_dword v95, v196, s[12:13] offset:256
	s_add_u32 s12, s12, s18
	s_addc_u32 s13, s13, 0
	s_waitcnt vmcnt(0)
	ds_write2st64_b32 v206, v64, v65 offset0:0 offset1:1
	ds_write2st64_b32 v206, v66, v67 offset0:2 offset1:3
	ds_write2st64_b32 v206, v68, v69 offset0:4 offset1:5
	ds_write2st64_b32 v206, v70, v71 offset0:6 offset1:7
	ds_write2st64_b32 v206, v72, v73 offset0:8 offset1:9
	ds_write2st64_b32 v206, v74, v75 offset0:10 offset1:11
	ds_write2st64_b32 v206, v76, v77 offset0:12 offset1:13
	ds_write2st64_b32 v206, v78, v79 offset0:14 offset1:15
	ds_write2st64_b32 v206, v80, v81 offset0:16 offset1:17
	ds_write2st64_b32 v206, v82, v83 offset0:18 offset1:19
	ds_write2st64_b32 v206, v84, v85 offset0:20 offset1:21
	ds_write2st64_b32 v206, v86, v87 offset0:22 offset1:23
	ds_write2st64_b32 v206, v88, v89 offset0:24 offset1:25
	ds_write2st64_b32 v206, v90, v91 offset0:26 offset1:27
	ds_write2st64_b32 v206, v92, v93 offset0:28 offset1:29
	ds_write2st64_b32 v206, v94, v95 offset0:30 offset1:31
	s_add_u32 s12, s26, 0xf800000
	s_addc_u32 s13, s27, 0
	s_lshl_b32 s15, s101, 9
	s_add_u32 s12, s12, s15
	s_addc_u32 s13, s13, 0
	s_lshl_b32 s18, s92, 11
	global_load_dword v64, v196, s[12:13]
	global_load_dword v65, v196, s[12:13] offset:256
	s_add_u32 s12, s12, s18
	s_addc_u32 s13, s13, 0
	global_load_dword v66, v196, s[12:13]
	global_load_dword v67, v196, s[12:13] offset:256
	s_add_u32 s12, s12, s18
	s_addc_u32 s13, s13, 0
	global_load_dword v68, v196, s[12:13]
	global_load_dword v69, v196, s[12:13] offset:256
	s_add_u32 s12, s12, s18
	s_addc_u32 s13, s13, 0
	global_load_dword v70, v196, s[12:13]
	global_load_dword v71, v196, s[12:13] offset:256
	s_add_u32 s12, s12, s18
	s_addc_u32 s13, s13, 0
	global_load_dword v72, v196, s[12:13]
	global_load_dword v73, v196, s[12:13] offset:256
	s_add_u32 s12, s12, s18
	s_addc_u32 s13, s13, 0
	global_load_dword v74, v196, s[12:13]
	global_load_dword v75, v196, s[12:13] offset:256
	s_add_u32 s12, s12, s18
	s_addc_u32 s13, s13, 0
	global_load_dword v76, v196, s[12:13]
	global_load_dword v77, v196, s[12:13] offset:256
	s_add_u32 s12, s12, s18
	s_addc_u32 s13, s13, 0
	global_load_dword v78, v196, s[12:13]
	global_load_dword v79, v196, s[12:13] offset:256
	s_add_u32 s12, s12, s18
	s_addc_u32 s13, s13, 0
	global_load_dword v80, v196, s[12:13]
	global_load_dword v81, v196, s[12:13] offset:256
	s_add_u32 s12, s12, s18
	s_addc_u32 s13, s13, 0
	global_load_dword v82, v196, s[12:13]
	global_load_dword v83, v196, s[12:13] offset:256
	s_add_u32 s12, s12, s18
	s_addc_u32 s13, s13, 0
	global_load_dword v84, v196, s[12:13]
	global_load_dword v85, v196, s[12:13] offset:256
	s_add_u32 s12, s12, s18
	s_addc_u32 s13, s13, 0
	global_load_dword v86, v196, s[12:13]
	global_load_dword v87, v196, s[12:13] offset:256
	s_add_u32 s12, s12, s18
	s_addc_u32 s13, s13, 0
	global_load_dword v88, v196, s[12:13]
	global_load_dword v89, v196, s[12:13] offset:256
	s_add_u32 s12, s12, s18
	s_addc_u32 s13, s13, 0
	global_load_dword v90, v196, s[12:13]
	global_load_dword v91, v196, s[12:13] offset:256
	s_add_u32 s12, s12, s18
	s_addc_u32 s13, s13, 0
	global_load_dword v92, v196, s[12:13]
	global_load_dword v93, v196, s[12:13] offset:256
	s_add_u32 s12, s12, s18
	s_addc_u32 s13, s13, 0
	global_load_dword v94, v196, s[12:13]
	global_load_dword v95, v196, s[12:13] offset:256
	s_add_u32 s12, s12, s18
	s_addc_u32 s13, s13, 0
	s_waitcnt vmcnt(0)
	ds_write2st64_b32 v208, v64, v65 offset0:0 offset1:1
	ds_write2st64_b32 v208, v66, v67 offset0:2 offset1:3
	ds_write2st64_b32 v208, v68, v69 offset0:4 offset1:5
	ds_write2st64_b32 v208, v70, v71 offset0:6 offset1:7
	ds_write2st64_b32 v208, v72, v73 offset0:8 offset1:9
	ds_write2st64_b32 v208, v74, v75 offset0:10 offset1:11
	ds_write2st64_b32 v208, v76, v77 offset0:12 offset1:13
	ds_write2st64_b32 v208, v78, v79 offset0:14 offset1:15
	ds_write2st64_b32 v208, v80, v81 offset0:16 offset1:17
	ds_write2st64_b32 v208, v82, v83 offset0:18 offset1:19
	ds_write2st64_b32 v208, v84, v85 offset0:20 offset1:21
	ds_write2st64_b32 v208, v86, v87 offset0:22 offset1:23
	ds_write2st64_b32 v208, v88, v89 offset0:24 offset1:25
	ds_write2st64_b32 v208, v90, v91 offset0:26 offset1:27
	ds_write2st64_b32 v208, v92, v93 offset0:28 offset1:29
	ds_write2st64_b32 v208, v94, v95 offset0:30 offset1:31
	s_waitcnt lgkmcnt(0)
	s_mov_b32 s14, 0
	s_mov_b32 s18, 0
	s_and_b32 s19, s18, 15
	s_lshr_b32 s98, s18, 4
	s_lshl_b32 s99, s19, 9
	s_mul_i32 s15, s19, s16
	s_lshl_b32 s18, s98, 7
	s_add_u32 s15, s15, s18
	s_lshl_b32 s18, s101, 12
	s_add_u32 s15, s15, s18
	s_add_u32 s8, s24, s15
	s_addc_u32 s9, s25, 0
	s_mul_i32 s15, s98, 0x300000
	s_add_u32 s4, s26, 0x4800000
	s_addc_u32 s5, s27, 0
	s_add_u32 s4, s4, s15
	s_addc_u32 s5, s5, 0
	v_add_u32_e32 v201, s99, v197
	v_add_u32_e32 v203, s99, v198
	ds_read2_b32 v[160:161], v201 offset0:0 offset1:8
	ds_read2_b32 v[162:163], v201 offset0:16 offset1:24
	s_waitcnt lgkmcnt(0)
	v_mad_u32_u24 v160, v160, s100, v199
	v_mad_u32_u24 v161, v161, s100, v199
	v_mad_u32_u24 v162, v162, s100, v199
	v_mad_u32_u24 v163, v163, s100, v199
	global_load_dwordx4 v[64:67], v160, s[4:5]
	global_load_dwordx2 v[68:69], v160, s[4:5] offset:16
	global_load_dwordx4 v[70:73], v161, s[4:5]
	global_load_dwordx2 v[74:75], v161, s[4:5] offset:16
	global_load_dwordx4 v[76:79], v162, s[4:5]
	global_load_dwordx2 v[80:81], v162, s[4:5] offset:16
	global_load_dwordx4 v[82:85], v163, s[4:5]
	global_load_dwordx2 v[86:87], v163, s[4:5] offset:16
	ds_read2_b32 v[168:169], v201 offset0:32 offset1:40
	ds_read2_b32 v[170:171], v201 offset0:48 offset1:56
	s_waitcnt lgkmcnt(0)
	v_mad_u32_u24 v168, v168, s100, v199
	v_mad_u32_u24 v169, v169, s100, v199
	v_mad_u32_u24 v170, v170, s100, v199
	v_mad_u32_u24 v171, v171, s100, v199
	global_load_dwordx4 v[88:91], v168, s[4:5]
	global_load_dwordx2 v[92:93], v168, s[4:5] offset:16
	global_load_dwordx4 v[94:97], v169, s[4:5]
	global_load_dwordx2 v[98:99], v169, s[4:5] offset:16
	global_load_dwordx4 v[100:103], v170, s[4:5]
	global_load_dwordx2 v[104:105], v170, s[4:5] offset:16
	global_load_dwordx4 v[106:109], v171, s[4:5]
	global_load_dwordx2 v[110:111], v171, s[4:5] offset:16
	ds_read2_b32 v[160:161], v201 offset0:64 offset1:72
	ds_read2_b32 v[162:163], v201 offset0:80 offset1:88
	s_waitcnt lgkmcnt(0)
	v_mad_u32_u24 v160, v160, s100, v199
	v_mad_u32_u24 v161, v161, s100, v199
	v_mad_u32_u24 v162, v162, s100, v199
	v_mad_u32_u24 v163, v163, s100, v199
	global_load_dwordx4 v[112:115], v160, s[4:5]
	global_load_dwordx2 v[116:117], v160, s[4:5] offset:16
	global_load_dwordx4 v[118:121], v161, s[4:5]
	global_load_dwordx2 v[122:123], v161, s[4:5] offset:16
	global_load_dwordx4 v[124:127], v162, s[4:5]
	global_load_dwordx2 v[128:129], v162, s[4:5] offset:16
	global_load_dwordx4 v[130:133], v163, s[4:5]
	global_load_dwordx2 v[134:135], v163, s[4:5] offset:16
	ds_read2_b32 v[168:169], v201 offset0:96 offset1:104
	ds_read2_b32 v[170:171], v201 offset0:112 offset1:120
	s_waitcnt lgkmcnt(0)
	v_mad_u32_u24 v168, v168, s100, v199
	v_mad_u32_u24 v169, v169, s100, v199
	v_mad_u32_u24 v170, v170, s100, v199
	v_mad_u32_u24 v171, v171, s100, v199
	global_load_dwordx4 v[136:139], v168, s[4:5]
	global_load_dwordx2 v[140:141], v168, s[4:5] offset:16
	global_load_dwordx4 v[142:145], v169, s[4:5]
	global_load_dwordx2 v[146:147], v169, s[4:5] offset:16
	global_load_dwordx4 v[148:151], v170, s[4:5]
	global_load_dwordx2 v[152:153], v170, s[4:5] offset:16
	global_load_dwordx4 v[154:157], v171, s[4:5]
	global_load_dwordx2 v[158:159], v171, s[4:5] offset:16
	global_load_dword v209, v200, s[8:9]
	ds_read2_b32 v[176:177], v203 offset0:0 offset1:8
	ds_read2_b32 v[178:179], v203 offset0:16 offset1:24
	s_mov_b32 s18, 1
	s_and_b32 s19, s18, 15
	s_lshr_b32 s98, s18, 4
	s_lshl_b32 s99, s19, 9
	s_mul_i32 s15, s19, s16
	s_lshl_b32 s18, s98, 7
	s_add_u32 s15, s15, s18
	s_lshl_b32 s18, s101, 12
	s_add_u32 s15, s15, s18
	s_add_u32 s10, s24, s15
	s_addc_u32 s11, s25, 0
	s_mul_i32 s15, s98, 0x300000
	s_add_u32 s4, s26, 0x4800000
	s_addc_u32 s5, s27, 0
	s_add_u32 s4, s4, s15
	s_addc_u32 s5, s5, 0
	v_add_u32_e32 v202, s99, v197
	v_add_u32_e32 v204, s99, v198
	ds_read2_b32 v[160:161], v202 offset0:0 offset1:8
	ds_read2_b32 v[162:163], v202 offset0:16 offset1:24
	s_waitcnt lgkmcnt(0)
.Lgv1_loop:
	global_load_dwordx4 v[192:195], v200, s[8:9]
	ds_read2_b32 v[184:185], v203 offset0:32 offset1:40
	ds_read2_b32 v[186:187], v203 offset0:48 offset1:56
	s_waitcnt vmcnt(32)
	v_cvt_scalef32_pk32_f32_fp6 v[32:63], v[64:69], 1.0
	v_pk_mul_f32 v[0:1], v[176:177], v[32:33] op_sel_hi:[0,1]
	v_pk_mul_f32 v[2:3], v[176:177], v[34:35] op_sel_hi:[0,1]
	v_pk_mul_f32 v[4:5], v[176:177], v[36:37] op_sel_hi:[0,1]
	v_pk_mul_f32 v[6:7], v[176:177], v[38:39] op_sel_hi:[0,1]
	v_pk_mul_f32 v[8:9], v[176:177], v[40:41] op_sel_hi:[0,1]
	v_pk_mul_f32 v[10:11], v[176:177], v[42:43] op_sel_hi:[0,1]
	v_pk_mul_f32 v[12:13], v[176:177], v[44:45] op_sel_hi:[0,1]
	v_pk_mul_f32 v[14:15], v[176:177], v[46:47] op_sel_hi:[0,1]
	v_pk_mul_f32 v[16:17], v[176:177], v[48:49] op_sel_hi:[0,1]
	v_pk_mul_f32 v[18:19], v[176:177], v[50:51] op_sel_hi:[0,1]
	v_pk_mul_f32 v[20:21], v[176:177], v[52:53] op_sel_hi:[0,1]
	v_pk_mul_f32 v[22:23], v[176:177], v[54:55] op_sel_hi:[0,1]
	v_pk_mul_f32 v[24:25], v[176:177], v[56:57] op_sel_hi:[0,1]
	v_pk_mul_f32 v[26:27], v[176:177], v[58:59] op_sel_hi:[0,1]
	v_pk_mul_f32 v[28:29], v[176:177], v[60:61] op_sel_hi:[0,1]
	v_pk_mul_f32 v[30:31], v[176:177], v[62:63] op_sel_hi:[0,1]
	s_waitcnt vmcnt(30)
	v_cvt_scalef32_pk32_f32_fp6 v[32:63], v[70:75], 1.0
	v_pk_fma_f32 v[0:1], v[176:177], v[32:33], v[0:1] op_sel:[1,0,0] op_sel_hi:[1,1,1]
	v_pk_fma_f32 v[2:3], v[176:177], v[34:35], v[2:3] op_sel:[1,0,0] op_sel_hi:[1,1,1]
	v_pk_fma_f32 v[4:5], v[176:177], v[36:37], v[4:5] op_sel:[1,0,0] op_sel_hi:[1,1,1]
	v_pk_fma_f32 v[6:7], v[176:177], v[38:39], v[6:7] op_sel:[1,0,0] op_sel_hi:[1,1,1]
	v_pk_fma_f32 v[8:9], v[176:177], v[40:41], v[8:9] op_sel:[1,0,0] op_sel_hi:[1,1,1]
	v_pk_fma_f32 v[10:11], v[176:177], v[42:43], v[10:11] op_sel:[1,0,0] op_sel_hi:[1,1,1]
	v_pk_fma_f32 v[12:13], v[176:177], v[44:45], v[12:13] op_sel:[1,0,0] op_sel_hi:[1,1,1]
	v_pk_fma_f32 v[14:15], v[176:177], v[46:47], v[14:15] op_sel:[1,0,0] op_sel_hi:[1,1,1]
	v_pk_fma_f32 v[16:17], v[176:177], v[48:49], v[16:17] op_sel:[1,0,0] op_sel_hi:[1,1,1]
	v_pk_fma_f32 v[18:19], v[176:177], v[50:51], v[18:19] op_sel:[1,0,0] op_sel_hi:[1,1,1]
	v_pk_fma_f32 v[20:21], v[176:177], v[52:53], v[20:21] op_sel:[1,0,0] op_sel_hi:[1,1,1]
	v_pk_fma_f32 v[22:23], v[176:177], v[54:55], v[22:23] op_sel:[1,0,0] op_sel_hi:[1,1,1]
	v_pk_fma_f32 v[24:25], v[176:177], v[56:57], v[24:25] op_sel:[1,0,0] op_sel_hi:[1,1,1]
	v_pk_fma_f32 v[26:27], v[176:177], v[58:59], v[26:27] op_sel:[1,0,0] op_sel_hi:[1,1,1]
	v_pk_fma_f32 v[28:29], v[176:177], v[60:61], v[28:29] op_sel:[1,0,0] op_sel_hi:[1,1,1]
	v_pk_fma_f32 v[30:31], v[176:177], v[62:63], v[30:31] op_sel:[1,0,0] op_sel_hi:[1,1,1]
	s_waitcnt vmcnt(28)
	v_cvt_scalef32_pk32_f32_fp6 v[32:63], v[76:81], 1.0
	v_pk_fma_f32 v[0:1], v[178:179], v[32:33], v[0:1] op_sel_hi:[0,1,1]
	v_pk_fma_f32 v[2:3], v[178:179], v[34:35], v[2:3] op_sel_hi:[0,1,1]
	v_pk_fma_f32 v[4:5], v[178:179], v[36:37], v[4:5] op_sel_hi:[0,1,1]
	v_pk_fma_f32 v[6:7], v[178:179], v[38:39], v[6:7] op_sel_hi:[0,1,1]
	v_pk_fma_f32 v[8:9], v[178:179], v[40:41], v[8:9] op_sel_hi:[0,1,1]
	v_pk_fma_f32 v[10:11], v[178:179], v[42:43], v[10:11] op_sel_hi:[0,1,1]
	v_pk_fma_f32 v[12:13], v[178:179], v[44:45], v[12:13] op_sel_hi:[0,1,1]
	v_pk_fma_f32 v[14:15], v[178:179], v[46:47], v[14:15] op_sel_hi:[0,1,1]
	v_pk_fma_f32 v[16:17], v[178:179], v[48:49], v[16:17] op_sel_hi:[0,1,1]
	v_pk_fma_f32 v[18:19], v[178:179], v[50:51], v[18:19] op_sel_hi:[0,1,1]
	v_pk_fma_f32 v[20:21], v[178:179], v[52:53], v[20:21] op_sel_hi:[0,1,1]
	v_pk_fma_f32 v[22:23], v[178:179], v[54:55], v[22:23] op_sel_hi:[0,1,1]
	v_pk_fma_f32 v[24:25], v[178:179], v[56:57], v[24:25] op_sel_hi:[0,1,1]
	v_pk_fma_f32 v[26:27], v[178:179], v[58:59], v[26:27] op_sel_hi:[0,1,1]
	v_pk_fma_f32 v[28:29], v[178:179], v[60:61], v[28:29] op_sel_hi:[0,1,1]
	v_pk_fma_f32 v[30:31], v[178:179], v[62:63], v[30:31] op_sel_hi:[0,1,1]
	s_waitcnt vmcnt(26)
	v_cvt_scalef32_pk32_f32_fp6 v[32:63], v[82:87], 1.0
	v_pk_fma_f32 v[0:1], v[178:179], v[32:33], v[0:1] op_sel:[1,0,0] op_sel_hi:[1,1,1]
	v_pk_fma_f32 v[2:3], v[178:179], v[34:35], v[2:3] op_sel:[1,0,0] op_sel_hi:[1,1,1]
	v_pk_fma_f32 v[4:5], v[178:179], v[36:37], v[4:5] op_sel:[1,0,0] op_sel_hi:[1,1,1]
	v_pk_fma_f32 v[6:7], v[178:179], v[38:39], v[6:7] op_sel:[1,0,0] op_sel_hi:[1,1,1]
	v_pk_fma_f32 v[8:9], v[178:179], v[40:41], v[8:9] op_sel:[1,0,0] op_sel_hi:[1,1,1]
	v_pk_fma_f32 v[10:11], v[178:179], v[42:43], v[10:11] op_sel:[1,0,0] op_sel_hi:[1,1,1]
	v_pk_fma_f32 v[12:13], v[178:179], v[44:45], v[12:13] op_sel:[1,0,0] op_sel_hi:[1,1,1]
	v_pk_fma_f32 v[14:15], v[178:179], v[46:47], v[14:15] op_sel:[1,0,0] op_sel_hi:[1,1,1]
	v_pk_fma_f32 v[16:17], v[178:179], v[48:49], v[16:17] op_sel:[1,0,0] op_sel_hi:[1,1,1]
	v_pk_fma_f32 v[18:19], v[178:179], v[50:51], v[18:19] op_sel:[1,0,0] op_sel_hi:[1,1,1]
	v_pk_fma_f32 v[20:21], v[178:179], v[52:53], v[20:21] op_sel:[1,0,0] op_sel_hi:[1,1,1]
	v_pk_fma_f32 v[22:23], v[178:179], v[54:55], v[22:23] op_sel:[1,0,0] op_sel_hi:[1,1,1]
	v_pk_fma_f32 v[24:25], v[178:179], v[56:57], v[24:25] op_sel:[1,0,0] op_sel_hi:[1,1,1]
	v_pk_fma_f32 v[26:27], v[178:179], v[58:59], v[26:27] op_sel:[1,0,0] op_sel_hi:[1,1,1]
	v_pk_fma_f32 v[28:29], v[178:179], v[60:61], v[28:29] op_sel:[1,0,0] op_sel_hi:[1,1,1]
	v_pk_fma_f32 v[30:31], v[178:179], v[62:63], v[30:31] op_sel:[1,0,0] op_sel_hi:[1,1,1]
	s_waitcnt lgkmcnt(0)
	v_mad_u32_u24 v160, v160, s100, v199
	v_mad_u32_u24 v161, v161, s100, v199
	v_mad_u32_u24 v162, v162, s100, v199
	v_mad_u32_u24 v163, v163, s100, v199
	global_load_dwordx4 v[64:67], v160, s[4:5]
	global_load_dwordx2 v[68:69], v160, s[4:5] offset:16
	global_load_dwordx4 v[70:73], v161, s[4:5]
	global_load_dwordx2 v[74:75], v161, s[4:5] offset:16
	global_load_dwordx4 v[76:79], v162, s[4:5]
	global_load_dwordx2 v[80:81], v162, s[4:5] offset:16
	global_load_dwordx4 v[82:85], v163, s[4:5]
	global_load_dwordx2 v[86:87], v163, s[4:5] offset:16
	ds_read2_b32 v[168:169], v202 offset0:32 offset1:40
	ds_read2_b32 v[170:171], v202 offset0:48 offset1:56
	ds_read2_b32 v[176:177], v203 offset0:64 offset1:72
	ds_read2_b32 v[178:179], v203 offset0:80 offset1:88
	s_waitcnt vmcnt(32)
	v_cvt_scalef32_pk32_f32_fp6 v[32:63], v[88:93], 1.0
	v_pk_fma_f32 v[0:1], v[184:185], v[32:33], v[0:1] op_sel_hi:[0,1,1]
	v_pk_fma_f32 v[2:3], v[184:185], v[34:35], v[2:3] op_sel_hi:[0,1,1]
	v_pk_fma_f32 v[4:5], v[184:185], v[36:37], v[4:5] op_sel_hi:[0,1,1]
	v_pk_fma_f32 v[6:7], v[184:185], v[38:39], v[6:7] op_sel_hi:[0,1,1]
	v_pk_fma_f32 v[8:9], v[184:185], v[40:41], v[8:9] op_sel_hi:[0,1,1]
	v_pk_fma_f32 v[10:11], v[184:185], v[42:43], v[10:11] op_sel_hi:[0,1,1]
	v_pk_fma_f32 v[12:13], v[184:185], v[44:45], v[12:13] op_sel_hi:[0,1,1]
	v_pk_fma_f32 v[14:15], v[184:185], v[46:47], v[14:15] op_sel_hi:[0,1,1]
	v_pk_fma_f32 v[16:17], v[184:185], v[48:49], v[16:17] op_sel_hi:[0,1,1]
	v_pk_fma_f32 v[18:19], v[184:185], v[50:51], v[18:19] op_sel_hi:[0,1,1]
	v_pk_fma_f32 v[20:21], v[184:185], v[52:53], v[20:21] op_sel_hi:[0,1,1]
	v_pk_fma_f32 v[22:23], v[184:185], v[54:55], v[22:23] op_sel_hi:[0,1,1]
	v_pk_fma_f32 v[24:25], v[184:185], v[56:57], v[24:25] op_sel_hi:[0,1,1]
	v_pk_fma_f32 v[26:27], v[184:185], v[58:59], v[26:27] op_sel_hi:[0,1,1]
	v_pk_fma_f32 v[28:29], v[184:185], v[60:61], v[28:29] op_sel_hi:[0,1,1]
	v_pk_fma_f32 v[30:31], v[184:185], v[62:63], v[30:31] op_sel_hi:[0,1,1]
	s_waitcnt vmcnt(30)
	v_cvt_scalef32_pk32_f32_fp6 v[32:63], v[94:99], 1.0
	v_pk_fma_f32 v[0:1], v[184:185], v[32:33], v[0:1] op_sel:[1,0,0] op_sel_hi:[1,1,1]
	v_pk_fma_f32 v[2:3], v[184:185], v[34:35], v[2:3] op_sel:[1,0,0] op_sel_hi:[1,1,1]
	v_pk_fma_f32 v[4:5], v[184:185], v[36:37], v[4:5] op_sel:[1,0,0] op_sel_hi:[1,1,1]
	v_pk_fma_f32 v[6:7], v[184:185], v[38:39], v[6:7] op_sel:[1,0,0] op_sel_hi:[1,1,1]
	v_pk_fma_f32 v[8:9], v[184:185], v[40:41], v[8:9] op_sel:[1,0,0] op_sel_hi:[1,1,1]
	v_pk_fma_f32 v[10:11], v[184:185], v[42:43], v[10:11] op_sel:[1,0,0] op_sel_hi:[1,1,1]
	v_pk_fma_f32 v[12:13], v[184:185], v[44:45], v[12:13] op_sel:[1,0,0] op_sel_hi:[1,1,1]
	v_pk_fma_f32 v[14:15], v[184:185], v[46:47], v[14:15] op_sel:[1,0,0] op_sel_hi:[1,1,1]
	v_pk_fma_f32 v[16:17], v[184:185], v[48:49], v[16:17] op_sel:[1,0,0] op_sel_hi:[1,1,1]
	v_pk_fma_f32 v[18:19], v[184:185], v[50:51], v[18:19] op_sel:[1,0,0] op_sel_hi:[1,1,1]
	v_pk_fma_f32 v[20:21], v[184:185], v[52:53], v[20:21] op_sel:[1,0,0] op_sel_hi:[1,1,1]
	v_pk_fma_f32 v[22:23], v[184:185], v[54:55], v[22:23] op_sel:[1,0,0] op_sel_hi:[1,1,1]
	v_pk_fma_f32 v[24:25], v[184:185], v[56:57], v[24:25] op_sel:[1,0,0] op_sel_hi:[1,1,1]
	v_pk_fma_f32 v[26:27], v[184:185], v[58:59], v[26:27] op_sel:[1,0,0] op_sel_hi:[1,1,1]
	v_pk_fma_f32 v[28:29], v[184:185], v[60:61], v[28:29] op_sel:[1,0,0] op_sel_hi:[1,1,1]
	v_pk_fma_f32 v[30:31], v[184:185], v[62:63], v[30:31] op_sel:[1,0,0] op_sel_hi:[1,1,1]
	s_waitcnt vmcnt(28)
	v_cvt_scalef32_pk32_f32_fp6 v[32:63], v[100:105], 1.0
	v_pk_fma_f32 v[0:1], v[186:187], v[32:33], v[0:1] op_sel_hi:[0,1,1]
	v_pk_fma_f32 v[2:3], v[186:187], v[34:35], v[2:3] op_sel_hi:[0,1,1]
	v_pk_fma_f32 v[4:5], v[186:187], v[36:37], v[4:5] op_sel_hi:[0,1,1]
	v_pk_fma_f32 v[6:7], v[186:187], v[38:39], v[6:7] op_sel_hi:[0,1,1]
	v_pk_fma_f32 v[8:9], v[186:187], v[40:41], v[8:9] op_sel_hi:[0,1,1]
	v_pk_fma_f32 v[10:11], v[186:187], v[42:43], v[10:11] op_sel_hi:[0,1,1]
	v_pk_fma_f32 v[12:13], v[186:187], v[44:45], v[12:13] op_sel_hi:[0,1,1]
	v_pk_fma_f32 v[14:15], v[186:187], v[46:47], v[14:15] op_sel_hi:[0,1,1]
	v_pk_fma_f32 v[16:17], v[186:187], v[48:49], v[16:17] op_sel_hi:[0,1,1]
	v_pk_fma_f32 v[18:19], v[186:187], v[50:51], v[18:19] op_sel_hi:[0,1,1]
	v_pk_fma_f32 v[20:21], v[186:187], v[52:53], v[20:21] op_sel_hi:[0,1,1]
	v_pk_fma_f32 v[22:23], v[186:187], v[54:55], v[22:23] op_sel_hi:[0,1,1]
	v_pk_fma_f32 v[24:25], v[186:187], v[56:57], v[24:25] op_sel_hi:[0,1,1]
	v_pk_fma_f32 v[26:27], v[186:187], v[58:59], v[26:27] op_sel_hi:[0,1,1]
	v_pk_fma_f32 v[28:29], v[186:187], v[60:61], v[28:29] op_sel_hi:[0,1,1]
	v_pk_fma_f32 v[30:31], v[186:187], v[62:63], v[30:31] op_sel_hi:[0,1,1]
	s_waitcnt vmcnt(26)
	v_cvt_scalef32_pk32_f32_fp6 v[32:63], v[106:111], 1.0
	v_pk_fma_f32 v[0:1], v[186:187], v[32:33], v[0:1] op_sel:[1,0,0] op_sel_hi:[1,1,1]
	v_pk_fma_f32 v[2:3], v[186:187], v[34:35], v[2:3] op_sel:[1,0,0] op_sel_hi:[1,1,1]
	v_pk_fma_f32 v[4:5], v[186:187], v[36:37], v[4:5] op_sel:[1,0,0] op_sel_hi:[1,1,1]
	v_pk_fma_f32 v[6:7], v[186:187], v[38:39], v[6:7] op_sel:[1,0,0] op_sel_hi:[1,1,1]
	v_pk_fma_f32 v[8:9], v[186:187], v[40:41], v[8:9] op_sel:[1,0,0] op_sel_hi:[1,1,1]
	v_pk_fma_f32 v[10:11], v[186:187], v[42:43], v[10:11] op_sel:[1,0,0] op_sel_hi:[1,1,1]
	v_pk_fma_f32 v[12:13], v[186:187], v[44:45], v[12:13] op_sel:[1,0,0] op_sel_hi:[1,1,1]
	v_pk_fma_f32 v[14:15], v[186:187], v[46:47], v[14:15] op_sel:[1,0,0] op_sel_hi:[1,1,1]
	v_pk_fma_f32 v[16:17], v[186:187], v[48:49], v[16:17] op_sel:[1,0,0] op_sel_hi:[1,1,1]
	v_pk_fma_f32 v[18:19], v[186:187], v[50:51], v[18:19] op_sel:[1,0,0] op_sel_hi:[1,1,1]
	v_pk_fma_f32 v[20:21], v[186:187], v[52:53], v[20:21] op_sel:[1,0,0] op_sel_hi:[1,1,1]
	v_pk_fma_f32 v[22:23], v[186:187], v[54:55], v[22:23] op_sel:[1,0,0] op_sel_hi:[1,1,1]
	v_pk_fma_f32 v[24:25], v[186:187], v[56:57], v[24:25] op_sel:[1,0,0] op_sel_hi:[1,1,1]
	v_pk_fma_f32 v[26:27], v[186:187], v[58:59], v[26:27] op_sel:[1,0,0] op_sel_hi:[1,1,1]
	v_pk_fma_f32 v[28:29], v[186:187], v[60:61], v[28:29] op_sel:[1,0,0] op_sel_hi:[1,1,1]
	v_pk_fma_f32 v[30:31], v[186:187], v[62:63], v[30:31] op_sel:[1,0,0] op_sel_hi:[1,1,1]
	s_waitcnt lgkmcnt(0)
	v_mad_u32_u24 v168, v168, s100, v199
	v_mad_u32_u24 v169, v169, s100, v199
	v_mad_u32_u24 v170, v170, s100, v199
	v_mad_u32_u24 v171, v171, s100, v199
	global_load_dwordx4 v[88:91], v168, s[4:5]
	global_load_dwordx2 v[92:93], v168, s[4:5] offset:16
	global_load_dwordx4 v[94:97], v169, s[4:5]
	global_load_dwordx2 v[98:99], v169, s[4:5] offset:16
	global_load_dwordx4 v[100:103], v170, s[4:5]
	global_load_dwordx2 v[104:105], v170, s[4:5] offset:16
	global_load_dwordx4 v[106:109], v171, s[4:5]
	global_load_dwordx2 v[110:111], v171, s[4:5] offset:16
	ds_read2_b32 v[160:161], v202 offset0:64 offset1:72
	ds_read2_b32 v[162:163], v202 offset0:80 offset1:88
	ds_read2_b32 v[184:185], v203 offset0:96 offset1:104
	ds_read2_b32 v[186:187], v203 offset0:112 offset1:120
	s_waitcnt vmcnt(32)
	v_cvt_scalef32_pk32_f32_fp6 v[32:63], v[112:117], 1.0
	v_pk_fma_f32 v[0:1], v[176:177], v[32:33], v[0:1] op_sel_hi:[0,1,1]
	v_pk_fma_f32 v[2:3], v[176:177], v[34:35], v[2:3] op_sel_hi:[0,1,1]
	v_pk_fma_f32 v[4:5], v[176:177], v[36:37], v[4:5] op_sel_hi:[0,1,1]
	v_pk_fma_f32 v[6:7], v[176:177], v[38:39], v[6:7] op_sel_hi:[0,1,1]
	v_pk_fma_f32 v[8:9], v[176:177], v[40:41], v[8:9] op_sel_hi:[0,1,1]
	v_pk_fma_f32 v[10:11], v[176:177], v[42:43], v[10:11] op_sel_hi:[0,1,1]
	v_pk_fma_f32 v[12:13], v[176:177], v[44:45], v[12:13] op_sel_hi:[0,1,1]
	v_pk_fma_f32 v[14:15], v[176:177], v[46:47], v[14:15] op_sel_hi:[0,1,1]
	v_pk_fma_f32 v[16:17], v[176:177], v[48:49], v[16:17] op_sel_hi:[0,1,1]
	v_pk_fma_f32 v[18:19], v[176:177], v[50:51], v[18:19] op_sel_hi:[0,1,1]
	v_pk_fma_f32 v[20:21], v[176:177], v[52:53], v[20:21] op_sel_hi:[0,1,1]
	v_pk_fma_f32 v[22:23], v[176:177], v[54:55], v[22:23] op_sel_hi:[0,1,1]
	v_pk_fma_f32 v[24:25], v[176:177], v[56:57], v[24:25] op_sel_hi:[0,1,1]
	v_pk_fma_f32 v[26:27], v[176:177], v[58:59], v[26:27] op_sel_hi:[0,1,1]
	v_pk_fma_f32 v[28:29], v[176:177], v[60:61], v[28:29] op_sel_hi:[0,1,1]
	v_pk_fma_f32 v[30:31], v[176:177], v[62:63], v[30:31] op_sel_hi:[0,1,1]
	s_waitcnt vmcnt(30)
	v_cvt_scalef32_pk32_f32_fp6 v[32:63], v[118:123], 1.0
	v_pk_fma_f32 v[0:1], v[176:177], v[32:33], v[0:1] op_sel:[1,0,0] op_sel_hi:[1,1,1]
	v_pk_fma_f32 v[2:3], v[176:177], v[34:35], v[2:3] op_sel:[1,0,0] op_sel_hi:[1,1,1]
	v_pk_fma_f32 v[4:5], v[176:177], v[36:37], v[4:5] op_sel:[1,0,0] op_sel_hi:[1,1,1]
	v_pk_fma_f32 v[6:7], v[176:177], v[38:39], v[6:7] op_sel:[1,0,0] op_sel_hi:[1,1,1]
	v_pk_fma_f32 v[8:9], v[176:177], v[40:41], v[8:9] op_sel:[1,0,0] op_sel_hi:[1,1,1]
	v_pk_fma_f32 v[10:11], v[176:177], v[42:43], v[10:11] op_sel:[1,0,0] op_sel_hi:[1,1,1]
	v_pk_fma_f32 v[12:13], v[176:177], v[44:45], v[12:13] op_sel:[1,0,0] op_sel_hi:[1,1,1]
	v_pk_fma_f32 v[14:15], v[176:177], v[46:47], v[14:15] op_sel:[1,0,0] op_sel_hi:[1,1,1]
	v_pk_fma_f32 v[16:17], v[176:177], v[48:49], v[16:17] op_sel:[1,0,0] op_sel_hi:[1,1,1]
	v_pk_fma_f32 v[18:19], v[176:177], v[50:51], v[18:19] op_sel:[1,0,0] op_sel_hi:[1,1,1]
	v_pk_fma_f32 v[20:21], v[176:177], v[52:53], v[20:21] op_sel:[1,0,0] op_sel_hi:[1,1,1]
	v_pk_fma_f32 v[22:23], v[176:177], v[54:55], v[22:23] op_sel:[1,0,0] op_sel_hi:[1,1,1]
	v_pk_fma_f32 v[24:25], v[176:177], v[56:57], v[24:25] op_sel:[1,0,0] op_sel_hi:[1,1,1]
	v_pk_fma_f32 v[26:27], v[176:177], v[58:59], v[26:27] op_sel:[1,0,0] op_sel_hi:[1,1,1]
	v_pk_fma_f32 v[28:29], v[176:177], v[60:61], v[28:29] op_sel:[1,0,0] op_sel_hi:[1,1,1]
	v_pk_fma_f32 v[30:31], v[176:177], v[62:63], v[30:31] op_sel:[1,0,0] op_sel_hi:[1,1,1]
	s_waitcnt vmcnt(28)
	v_cvt_scalef32_pk32_f32_fp6 v[32:63], v[124:129], 1.0
	v_pk_fma_f32 v[0:1], v[178:179], v[32:33], v[0:1] op_sel_hi:[0,1,1]
	v_pk_fma_f32 v[2:3], v[178:179], v[34:35], v[2:3] op_sel_hi:[0,1,1]
	v_pk_fma_f32 v[4:5], v[178:179], v[36:37], v[4:5] op_sel_hi:[0,1,1]
	v_pk_fma_f32 v[6:7], v[178:179], v[38:39], v[6:7] op_sel_hi:[0,1,1]
	v_pk_fma_f32 v[8:9], v[178:179], v[40:41], v[8:9] op_sel_hi:[0,1,1]
	v_pk_fma_f32 v[10:11], v[178:179], v[42:43], v[10:11] op_sel_hi:[0,1,1]
	v_pk_fma_f32 v[12:13], v[178:179], v[44:45], v[12:13] op_sel_hi:[0,1,1]
	v_pk_fma_f32 v[14:15], v[178:179], v[46:47], v[14:15] op_sel_hi:[0,1,1]
	v_pk_fma_f32 v[16:17], v[178:179], v[48:49], v[16:17] op_sel_hi:[0,1,1]
	v_pk_fma_f32 v[18:19], v[178:179], v[50:51], v[18:19] op_sel_hi:[0,1,1]
	v_pk_fma_f32 v[20:21], v[178:179], v[52:53], v[20:21] op_sel_hi:[0,1,1]
	v_pk_fma_f32 v[22:23], v[178:179], v[54:55], v[22:23] op_sel_hi:[0,1,1]
	v_pk_fma_f32 v[24:25], v[178:179], v[56:57], v[24:25] op_sel_hi:[0,1,1]
	v_pk_fma_f32 v[26:27], v[178:179], v[58:59], v[26:27] op_sel_hi:[0,1,1]
	v_pk_fma_f32 v[28:29], v[178:179], v[60:61], v[28:29] op_sel_hi:[0,1,1]
	v_pk_fma_f32 v[30:31], v[178:179], v[62:63], v[30:31] op_sel_hi:[0,1,1]
	s_waitcnt vmcnt(26)
	v_cvt_scalef32_pk32_f32_fp6 v[32:63], v[130:135], 1.0
	v_pk_fma_f32 v[0:1], v[178:179], v[32:33], v[0:1] op_sel:[1,0,0] op_sel_hi:[1,1,1]
	v_pk_fma_f32 v[2:3], v[178:179], v[34:35], v[2:3] op_sel:[1,0,0] op_sel_hi:[1,1,1]
	v_pk_fma_f32 v[4:5], v[178:179], v[36:37], v[4:5] op_sel:[1,0,0] op_sel_hi:[1,1,1]
	v_pk_fma_f32 v[6:7], v[178:179], v[38:39], v[6:7] op_sel:[1,0,0] op_sel_hi:[1,1,1]
	v_pk_fma_f32 v[8:9], v[178:179], v[40:41], v[8:9] op_sel:[1,0,0] op_sel_hi:[1,1,1]
	v_pk_fma_f32 v[10:11], v[178:179], v[42:43], v[10:11] op_sel:[1,0,0] op_sel_hi:[1,1,1]
	v_pk_fma_f32 v[12:13], v[178:179], v[44:45], v[12:13] op_sel:[1,0,0] op_sel_hi:[1,1,1]
	v_pk_fma_f32 v[14:15], v[178:179], v[46:47], v[14:15] op_sel:[1,0,0] op_sel_hi:[1,1,1]
	v_pk_fma_f32 v[16:17], v[178:179], v[48:49], v[16:17] op_sel:[1,0,0] op_sel_hi:[1,1,1]
	v_pk_fma_f32 v[18:19], v[178:179], v[50:51], v[18:19] op_sel:[1,0,0] op_sel_hi:[1,1,1]
	v_pk_fma_f32 v[20:21], v[178:179], v[52:53], v[20:21] op_sel:[1,0,0] op_sel_hi:[1,1,1]
	v_pk_fma_f32 v[22:23], v[178:179], v[54:55], v[22:23] op_sel:[1,0,0] op_sel_hi:[1,1,1]
	v_pk_fma_f32 v[24:25], v[178:179], v[56:57], v[24:25] op_sel:[1,0,0] op_sel_hi:[1,1,1]
	v_pk_fma_f32 v[26:27], v[178:179], v[58:59], v[26:27] op_sel:[1,0,0] op_sel_hi:[1,1,1]
	v_pk_fma_f32 v[28:29], v[178:179], v[60:61], v[28:29] op_sel:[1,0,0] op_sel_hi:[1,1,1]
	v_pk_fma_f32 v[30:31], v[178:179], v[62:63], v[30:31] op_sel:[1,0,0] op_sel_hi:[1,1,1]
	s_waitcnt lgkmcnt(0)
	v_mad_u32_u24 v160, v160, s100, v199
	v_mad_u32_u24 v161, v161, s100, v199
	v_mad_u32_u24 v162, v162, s100, v199
	v_mad_u32_u24 v163, v163, s100, v199
	global_load_dwordx4 v[112:115], v160, s[4:5]
	global_load_dwordx2 v[116:117], v160, s[4:5] offset:16
	global_load_dwordx4 v[118:121], v161, s[4:5]
	global_load_dwordx2 v[122:123], v161, s[4:5] offset:16
	global_load_dwordx4 v[124:127], v162, s[4:5]
	global_load_dwordx2 v[128:129], v162, s[4:5] offset:16
	global_load_dwordx4 v[130:133], v163, s[4:5]
	global_load_dwordx2 v[134:135], v163, s[4:5] offset:16
	ds_read2_b32 v[168:169], v202 offset0:96 offset1:104
	ds_read2_b32 v[170:171], v202 offset0:112 offset1:120
	ds_read2_b32 v[176:177], v204 offset0:0 offset1:8
	ds_read2_b32 v[178:179], v204 offset0:16 offset1:24
	s_waitcnt vmcnt(32)
	v_cvt_scalef32_pk32_f32_fp6 v[32:63], v[136:141], 1.0
	v_pk_fma_f32 v[0:1], v[184:185], v[32:33], v[0:1] op_sel_hi:[0,1,1]
	v_pk_fma_f32 v[2:3], v[184:185], v[34:35], v[2:3] op_sel_hi:[0,1,1]
	v_pk_fma_f32 v[4:5], v[184:185], v[36:37], v[4:5] op_sel_hi:[0,1,1]
	v_pk_fma_f32 v[6:7], v[184:185], v[38:39], v[6:7] op_sel_hi:[0,1,1]
	v_pk_fma_f32 v[8:9], v[184:185], v[40:41], v[8:9] op_sel_hi:[0,1,1]
	v_pk_fma_f32 v[10:11], v[184:185], v[42:43], v[10:11] op_sel_hi:[0,1,1]
	v_pk_fma_f32 v[12:13], v[184:185], v[44:45], v[12:13] op_sel_hi:[0,1,1]
	v_pk_fma_f32 v[14:15], v[184:185], v[46:47], v[14:15] op_sel_hi:[0,1,1]
	v_pk_fma_f32 v[16:17], v[184:185], v[48:49], v[16:17] op_sel_hi:[0,1,1]
	v_pk_fma_f32 v[18:19], v[184:185], v[50:51], v[18:19] op_sel_hi:[0,1,1]
	v_pk_fma_f32 v[20:21], v[184:185], v[52:53], v[20:21] op_sel_hi:[0,1,1]
	v_pk_fma_f32 v[22:23], v[184:185], v[54:55], v[22:23] op_sel_hi:[0,1,1]
	v_pk_fma_f32 v[24:25], v[184:185], v[56:57], v[24:25] op_sel_hi:[0,1,1]
	v_pk_fma_f32 v[26:27], v[184:185], v[58:59], v[26:27] op_sel_hi:[0,1,1]
	v_pk_fma_f32 v[28:29], v[184:185], v[60:61], v[28:29] op_sel_hi:[0,1,1]
	v_pk_fma_f32 v[30:31], v[184:185], v[62:63], v[30:31] op_sel_hi:[0,1,1]
	s_waitcnt vmcnt(30)
	v_cvt_scalef32_pk32_f32_fp6 v[32:63], v[142:147], 1.0
	v_pk_fma_f32 v[0:1], v[184:185], v[32:33], v[0:1] op_sel:[1,0,0] op_sel_hi:[1,1,1]
	v_pk_fma_f32 v[2:3], v[184:185], v[34:35], v[2:3] op_sel:[1,0,0] op_sel_hi:[1,1,1]
	v_pk_fma_f32 v[4:5], v[184:185], v[36:37], v[4:5] op_sel:[1,0,0] op_sel_hi:[1,1,1]
	v_pk_fma_f32 v[6:7], v[184:185], v[38:39], v[6:7] op_sel:[1,0,0] op_sel_hi:[1,1,1]
	v_pk_fma_f32 v[8:9], v[184:185], v[40:41], v[8:9] op_sel:[1,0,0] op_sel_hi:[1,1,1]
	v_pk_fma_f32 v[10:11], v[184:185], v[42:43], v[10:11] op_sel:[1,0,0] op_sel_hi:[1,1,1]
	v_pk_fma_f32 v[12:13], v[184:185], v[44:45], v[12:13] op_sel:[1,0,0] op_sel_hi:[1,1,1]
	v_pk_fma_f32 v[14:15], v[184:185], v[46:47], v[14:15] op_sel:[1,0,0] op_sel_hi:[1,1,1]
	v_pk_fma_f32 v[16:17], v[184:185], v[48:49], v[16:17] op_sel:[1,0,0] op_sel_hi:[1,1,1]
	v_pk_fma_f32 v[18:19], v[184:185], v[50:51], v[18:19] op_sel:[1,0,0] op_sel_hi:[1,1,1]
	v_pk_fma_f32 v[20:21], v[184:185], v[52:53], v[20:21] op_sel:[1,0,0] op_sel_hi:[1,1,1]
	v_pk_fma_f32 v[22:23], v[184:185], v[54:55], v[22:23] op_sel:[1,0,0] op_sel_hi:[1,1,1]
	v_pk_fma_f32 v[24:25], v[184:185], v[56:57], v[24:25] op_sel:[1,0,0] op_sel_hi:[1,1,1]
	v_pk_fma_f32 v[26:27], v[184:185], v[58:59], v[26:27] op_sel:[1,0,0] op_sel_hi:[1,1,1]
	v_pk_fma_f32 v[28:29], v[184:185], v[60:61], v[28:29] op_sel:[1,0,0] op_sel_hi:[1,1,1]
	v_pk_fma_f32 v[30:31], v[184:185], v[62:63], v[30:31] op_sel:[1,0,0] op_sel_hi:[1,1,1]
	s_waitcnt vmcnt(28)
	v_cvt_scalef32_pk32_f32_fp6 v[32:63], v[148:153], 1.0
	v_pk_fma_f32 v[0:1], v[186:187], v[32:33], v[0:1] op_sel_hi:[0,1,1]
	v_pk_fma_f32 v[2:3], v[186:187], v[34:35], v[2:3] op_sel_hi:[0,1,1]
	v_pk_fma_f32 v[4:5], v[186:187], v[36:37], v[4:5] op_sel_hi:[0,1,1]
	v_pk_fma_f32 v[6:7], v[186:187], v[38:39], v[6:7] op_sel_hi:[0,1,1]
	v_pk_fma_f32 v[8:9], v[186:187], v[40:41], v[8:9] op_sel_hi:[0,1,1]
	v_pk_fma_f32 v[10:11], v[186:187], v[42:43], v[10:11] op_sel_hi:[0,1,1]
	v_pk_fma_f32 v[12:13], v[186:187], v[44:45], v[12:13] op_sel_hi:[0,1,1]
	v_pk_fma_f32 v[14:15], v[186:187], v[46:47], v[14:15] op_sel_hi:[0,1,1]
	v_pk_fma_f32 v[16:17], v[186:187], v[48:49], v[16:17] op_sel_hi:[0,1,1]
	v_pk_fma_f32 v[18:19], v[186:187], v[50:51], v[18:19] op_sel_hi:[0,1,1]
	v_pk_fma_f32 v[20:21], v[186:187], v[52:53], v[20:21] op_sel_hi:[0,1,1]
	v_pk_fma_f32 v[22:23], v[186:187], v[54:55], v[22:23] op_sel_hi:[0,1,1]
	v_pk_fma_f32 v[24:25], v[186:187], v[56:57], v[24:25] op_sel_hi:[0,1,1]
	v_pk_fma_f32 v[26:27], v[186:187], v[58:59], v[26:27] op_sel_hi:[0,1,1]
	v_pk_fma_f32 v[28:29], v[186:187], v[60:61], v[28:29] op_sel_hi:[0,1,1]
	v_pk_fma_f32 v[30:31], v[186:187], v[62:63], v[30:31] op_sel_hi:[0,1,1]
	s_waitcnt vmcnt(26)
	v_cvt_scalef32_pk32_f32_fp6 v[32:63], v[154:159], 1.0
	v_pk_fma_f32 v[0:1], v[186:187], v[32:33], v[0:1] op_sel:[1,0,0] op_sel_hi:[1,1,1]
	v_pk_fma_f32 v[2:3], v[186:187], v[34:35], v[2:3] op_sel:[1,0,0] op_sel_hi:[1,1,1]
	v_pk_fma_f32 v[4:5], v[186:187], v[36:37], v[4:5] op_sel:[1,0,0] op_sel_hi:[1,1,1]
	v_pk_fma_f32 v[6:7], v[186:187], v[38:39], v[6:7] op_sel:[1,0,0] op_sel_hi:[1,1,1]
	v_pk_fma_f32 v[8:9], v[186:187], v[40:41], v[8:9] op_sel:[1,0,0] op_sel_hi:[1,1,1]
	v_pk_fma_f32 v[10:11], v[186:187], v[42:43], v[10:11] op_sel:[1,0,0] op_sel_hi:[1,1,1]
	v_pk_fma_f32 v[12:13], v[186:187], v[44:45], v[12:13] op_sel:[1,0,0] op_sel_hi:[1,1,1]
	v_pk_fma_f32 v[14:15], v[186:187], v[46:47], v[14:15] op_sel:[1,0,0] op_sel_hi:[1,1,1]
	v_pk_fma_f32 v[16:17], v[186:187], v[48:49], v[16:17] op_sel:[1,0,0] op_sel_hi:[1,1,1]
	v_pk_fma_f32 v[18:19], v[186:187], v[50:51], v[18:19] op_sel:[1,0,0] op_sel_hi:[1,1,1]
	v_pk_fma_f32 v[20:21], v[186:187], v[52:53], v[20:21] op_sel:[1,0,0] op_sel_hi:[1,1,1]
	v_pk_fma_f32 v[22:23], v[186:187], v[54:55], v[22:23] op_sel:[1,0,0] op_sel_hi:[1,1,1]
	v_pk_fma_f32 v[24:25], v[186:187], v[56:57], v[24:25] op_sel:[1,0,0] op_sel_hi:[1,1,1]
	v_pk_fma_f32 v[26:27], v[186:187], v[58:59], v[26:27] op_sel:[1,0,0] op_sel_hi:[1,1,1]
	v_pk_fma_f32 v[28:29], v[186:187], v[60:61], v[28:29] op_sel:[1,0,0] op_sel_hi:[1,1,1]
	v_pk_fma_f32 v[30:31], v[186:187], v[62:63], v[30:31] op_sel:[1,0,0] op_sel_hi:[1,1,1]
	s_waitcnt lgkmcnt(0)
	v_mad_u32_u24 v168, v168, s100, v199
	v_mad_u32_u24 v169, v169, s100, v199
	v_mad_u32_u24 v170, v170, s100, v199
	v_mad_u32_u24 v171, v171, s100, v199
	global_load_dwordx4 v[136:139], v168, s[4:5]
	global_load_dwordx2 v[140:141], v168, s[4:5] offset:16
	global_load_dwordx4 v[142:145], v169, s[4:5]
	global_load_dwordx2 v[146:147], v169, s[4:5] offset:16
	global_load_dwordx4 v[148:151], v170, s[4:5]
	global_load_dwordx2 v[152:153], v170, s[4:5] offset:16
	global_load_dwordx4 v[154:157], v171, s[4:5]
	global_load_dwordx2 v[158:159], v171, s[4:5] offset:16
	s_nop 1
	v_permlane32_swap_b32_e32 v0, v16
	v_permlane32_swap_b32_e32 v1, v17
	v_permlane32_swap_b32_e32 v2, v18
	v_permlane32_swap_b32_e32 v3, v19
	v_permlane32_swap_b32_e32 v4, v20
	v_permlane32_swap_b32_e32 v5, v21
	v_permlane32_swap_b32_e32 v6, v22
	v_permlane32_swap_b32_e32 v7, v23
	v_permlane32_swap_b32_e32 v8, v24
	v_permlane32_swap_b32_e32 v9, v25
	v_permlane32_swap_b32_e32 v10, v26
	v_permlane32_swap_b32_e32 v11, v27
	v_permlane32_swap_b32_e32 v12, v28
	v_permlane32_swap_b32_e32 v13, v29
	v_permlane32_swap_b32_e32 v14, v30
	v_permlane32_swap_b32_e32 v15, v31
	v_pk_add_f32 v[0:1], v[0:1], v[16:17]
	v_pk_add_f32 v[2:3], v[2:3], v[18:19]
	v_pk_add_f32 v[4:5], v[4:5], v[20:21]
	v_pk_add_f32 v[6:7], v[6:7], v[22:23]
	v_pk_add_f32 v[8:9], v[8:9], v[24:25]
	v_pk_add_f32 v[10:11], v[10:11], v[26:27]
	v_pk_add_f32 v[12:13], v[12:13], v[28:29]
	v_pk_add_f32 v[14:15], v[14:15], v[30:31]
	s_nop 1
	v_permlane16_swap_b32_e32 v0, v8
	v_permlane16_swap_b32_e32 v1, v9
	v_permlane16_swap_b32_e32 v2, v10
	v_permlane16_swap_b32_e32 v3, v11
	v_permlane16_swap_b32_e32 v4, v12
	v_permlane16_swap_b32_e32 v5, v13
	v_permlane16_swap_b32_e32 v6, v14
	v_permlane16_swap_b32_e32 v7, v15
	v_pk_add_f32 v[0:1], v[0:1], v[8:9]
	v_pk_add_f32 v[2:3], v[2:3], v[10:11]
	v_pk_add_f32 v[4:5], v[4:5], v[12:13]
	v_pk_add_f32 v[6:7], v[6:7], v[14:15]
	s_nop 1
	v_add_f32_dpp v0, v0, v0 row_ror:8 row_mask:0xf bank_mask:0x3
	v_add_f32_dpp v1, v1, v1 row_ror:8 row_mask:0xf bank_mask:0x3
	v_add_f32_dpp v2, v2, v2 row_ror:8 row_mask:0xf bank_mask:0x3
	v_add_f32_dpp v3, v3, v3 row_ror:8 row_mask:0xf bank_mask:0x3
	v_add_f32_dpp v0, v4, v4 row_ror:8 row_mask:0xf bank_mask:0xc
	v_add_f32_dpp v1, v5, v5 row_ror:8 row_mask:0xf bank_mask:0xc
	v_add_f32_dpp v2, v6, v6 row_ror:8 row_mask:0xf bank_mask:0xc
	v_add_f32_dpp v3, v7, v7 row_ror:8 row_mask:0xf bank_mask:0xc
	s_waitcnt vmcnt(32)
	v_pk_add_f32 v[192:193], v[192:193], v[0:1]
	v_pk_add_f32 v[194:195], v[194:195], v[2:3]
	global_store_dwordx4 v200, v[192:195], s[8:9]
	s_add_u32 s14, s14, 1
	s_and_b32 s14, s14, 63
	s_add_u32 s18, s14, 1
	s_and_b32 s98, s18, 63
	s_mov_b32 s100, s98
	s_and_b32 s19, s100, 15
	s_lshr_b32 s98, s100, 4
	s_lshl_b32 s99, s19, 9
	s_mul_i32 s15, s19, s16
	s_lshl_b32 s18, s98, 7
	s_add_u32 s15, s15, s18
	s_lshl_b32 s18, s101, 12
	s_add_u32 s15, s15, s18
	s_add_u32 s8, s24, s15
	s_addc_u32 s9, s25, 0
	s_mul_i32 s15, s98, 0x300000
	s_add_u32 s4, s26, 0x4800000
	s_addc_u32 s5, s27, 0
	s_add_u32 s4, s4, s15
	s_addc_u32 s5, s5, 0
	v_add_u32_e32 v201, s99, v197
	v_add_u32_e32 v203, s99, v198
	s_movk_i32 s100, 0xc0
	ds_read2_b32 v[160:161], v201 offset0:0 offset1:8
	ds_read2_b32 v[162:163], v201 offset0:16 offset1:24
	global_load_dwordx4 v[192:195], v200, s[10:11]
	ds_read2_b32 v[184:185], v204 offset0:32 offset1:40
	ds_read2_b32 v[186:187], v204 offset0:48 offset1:56
	s_waitcnt vmcnt(32)
	v_cvt_scalef32_pk32_f32_fp6 v[32:63], v[64:69], 1.0
	v_pk_mul_f32 v[0:1], v[176:177], v[32:33] op_sel_hi:[0,1]
	v_pk_mul_f32 v[2:3], v[176:177], v[34:35] op_sel_hi:[0,1]
	v_pk_mul_f32 v[4:5], v[176:177], v[36:37] op_sel_hi:[0,1]
	v_pk_mul_f32 v[6:7], v[176:177], v[38:39] op_sel_hi:[0,1]
	v_pk_mul_f32 v[8:9], v[176:177], v[40:41] op_sel_hi:[0,1]
	v_pk_mul_f32 v[10:11], v[176:177], v[42:43] op_sel_hi:[0,1]
	v_pk_mul_f32 v[12:13], v[176:177], v[44:45] op_sel_hi:[0,1]
	v_pk_mul_f32 v[14:15], v[176:177], v[46:47] op_sel_hi:[0,1]
	v_pk_mul_f32 v[16:17], v[176:177], v[48:49] op_sel_hi:[0,1]
	v_pk_mul_f32 v[18:19], v[176:177], v[50:51] op_sel_hi:[0,1]
	v_pk_mul_f32 v[20:21], v[176:177], v[52:53] op_sel_hi:[0,1]
	v_pk_mul_f32 v[22:23], v[176:177], v[54:55] op_sel_hi:[0,1]
	v_pk_mul_f32 v[24:25], v[176:177], v[56:57] op_sel_hi:[0,1]
	v_pk_mul_f32 v[26:27], v[176:177], v[58:59] op_sel_hi:[0,1]
	v_pk_mul_f32 v[28:29], v[176:177], v[60:61] op_sel_hi:[0,1]
	v_pk_mul_f32 v[30:31], v[176:177], v[62:63] op_sel_hi:[0,1]
	s_waitcnt vmcnt(30)
	v_cvt_scalef32_pk32_f32_fp6 v[32:63], v[70:75], 1.0
	v_pk_fma_f32 v[0:1], v[176:177], v[32:33], v[0:1] op_sel:[1,0,0] op_sel_hi:[1,1,1]
	v_pk_fma_f32 v[2:3], v[176:177], v[34:35], v[2:3] op_sel:[1,0,0] op_sel_hi:[1,1,1]
	v_pk_fma_f32 v[4:5], v[176:177], v[36:37], v[4:5] op_sel:[1,0,0] op_sel_hi:[1,1,1]
	v_pk_fma_f32 v[6:7], v[176:177], v[38:39], v[6:7] op_sel:[1,0,0] op_sel_hi:[1,1,1]
	v_pk_fma_f32 v[8:9], v[176:177], v[40:41], v[8:9] op_sel:[1,0,0] op_sel_hi:[1,1,1]
	v_pk_fma_f32 v[10:11], v[176:177], v[42:43], v[10:11] op_sel:[1,0,0] op_sel_hi:[1,1,1]
	v_pk_fma_f32 v[12:13], v[176:177], v[44:45], v[12:13] op_sel:[1,0,0] op_sel_hi:[1,1,1]
	v_pk_fma_f32 v[14:15], v[176:177], v[46:47], v[14:15] op_sel:[1,0,0] op_sel_hi:[1,1,1]
	v_pk_fma_f32 v[16:17], v[176:177], v[48:49], v[16:17] op_sel:[1,0,0] op_sel_hi:[1,1,1]
	v_pk_fma_f32 v[18:19], v[176:177], v[50:51], v[18:19] op_sel:[1,0,0] op_sel_hi:[1,1,1]
	v_pk_fma_f32 v[20:21], v[176:177], v[52:53], v[20:21] op_sel:[1,0,0] op_sel_hi:[1,1,1]
	v_pk_fma_f32 v[22:23], v[176:177], v[54:55], v[22:23] op_sel:[1,0,0] op_sel_hi:[1,1,1]
	v_pk_fma_f32 v[24:25], v[176:177], v[56:57], v[24:25] op_sel:[1,0,0] op_sel_hi:[1,1,1]
	v_pk_fma_f32 v[26:27], v[176:177], v[58:59], v[26:27] op_sel:[1,0,0] op_sel_hi:[1,1,1]
	v_pk_fma_f32 v[28:29], v[176:177], v[60:61], v[28:29] op_sel:[1,0,0] op_sel_hi:[1,1,1]
	v_pk_fma_f32 v[30:31], v[176:177], v[62:63], v[30:31] op_sel:[1,0,0] op_sel_hi:[1,1,1]
	s_waitcnt vmcnt(28)
	v_cvt_scalef32_pk32_f32_fp6 v[32:63], v[76:81], 1.0
	v_pk_fma_f32 v[0:1], v[178:179], v[32:33], v[0:1] op_sel_hi:[0,1,1]
	v_pk_fma_f32 v[2:3], v[178:179], v[34:35], v[2:3] op_sel_hi:[0,1,1]
	v_pk_fma_f32 v[4:5], v[178:179], v[36:37], v[4:5] op_sel_hi:[0,1,1]
	v_pk_fma_f32 v[6:7], v[178:179], v[38:39], v[6:7] op_sel_hi:[0,1,1]
	v_pk_fma_f32 v[8:9], v[178:179], v[40:41], v[8:9] op_sel_hi:[0,1,1]
	v_pk_fma_f32 v[10:11], v[178:179], v[42:43], v[10:11] op_sel_hi:[0,1,1]
	v_pk_fma_f32 v[12:13], v[178:179], v[44:45], v[12:13] op_sel_hi:[0,1,1]
	v_pk_fma_f32 v[14:15], v[178:179], v[46:47], v[14:15] op_sel_hi:[0,1,1]
	v_pk_fma_f32 v[16:17], v[178:179], v[48:49], v[16:17] op_sel_hi:[0,1,1]
	v_pk_fma_f32 v[18:19], v[178:179], v[50:51], v[18:19] op_sel_hi:[0,1,1]
	v_pk_fma_f32 v[20:21], v[178:179], v[52:53], v[20:21] op_sel_hi:[0,1,1]
	v_pk_fma_f32 v[22:23], v[178:179], v[54:55], v[22:23] op_sel_hi:[0,1,1]
	v_pk_fma_f32 v[24:25], v[178:179], v[56:57], v[24:25] op_sel_hi:[0,1,1]
	v_pk_fma_f32 v[26:27], v[178:179], v[58:59], v[26:27] op_sel_hi:[0,1,1]
	v_pk_fma_f32 v[28:29], v[178:179], v[60:61], v[28:29] op_sel_hi:[0,1,1]
	v_pk_fma_f32 v[30:31], v[178:179], v[62:63], v[30:31] op_sel_hi:[0,1,1]
	s_waitcnt vmcnt(26)
	v_cvt_scalef32_pk32_f32_fp6 v[32:63], v[82:87], 1.0
	v_pk_fma_f32 v[0:1], v[178:179], v[32:33], v[0:1] op_sel:[1,0,0] op_sel_hi:[1,1,1]
	v_pk_fma_f32 v[2:3], v[178:179], v[34:35], v[2:3] op_sel:[1,0,0] op_sel_hi:[1,1,1]
	v_pk_fma_f32 v[4:5], v[178:179], v[36:37], v[4:5] op_sel:[1,0,0] op_sel_hi:[1,1,1]
	v_pk_fma_f32 v[6:7], v[178:179], v[38:39], v[6:7] op_sel:[1,0,0] op_sel_hi:[1,1,1]
	v_pk_fma_f32 v[8:9], v[178:179], v[40:41], v[8:9] op_sel:[1,0,0] op_sel_hi:[1,1,1]
	v_pk_fma_f32 v[10:11], v[178:179], v[42:43], v[10:11] op_sel:[1,0,0] op_sel_hi:[1,1,1]
	v_pk_fma_f32 v[12:13], v[178:179], v[44:45], v[12:13] op_sel:[1,0,0] op_sel_hi:[1,1,1]
	v_pk_fma_f32 v[14:15], v[178:179], v[46:47], v[14:15] op_sel:[1,0,0] op_sel_hi:[1,1,1]
	v_pk_fma_f32 v[16:17], v[178:179], v[48:49], v[16:17] op_sel:[1,0,0] op_sel_hi:[1,1,1]
	v_pk_fma_f32 v[18:19], v[178:179], v[50:51], v[18:19] op_sel:[1,0,0] op_sel_hi:[1,1,1]
	v_pk_fma_f32 v[20:21], v[178:179], v[52:53], v[20:21] op_sel:[1,0,0] op_sel_hi:[1,1,1]
	v_pk_fma_f32 v[22:23], v[178:179], v[54:55], v[22:23] op_sel:[1,0,0] op_sel_hi:[1,1,1]
	v_pk_fma_f32 v[24:25], v[178:179], v[56:57], v[24:25] op_sel:[1,0,0] op_sel_hi:[1,1,1]
	v_pk_fma_f32 v[26:27], v[178:179], v[58:59], v[26:27] op_sel:[1,0,0] op_sel_hi:[1,1,1]
	v_pk_fma_f32 v[28:29], v[178:179], v[60:61], v[28:29] op_sel:[1,0,0] op_sel_hi:[1,1,1]
	v_pk_fma_f32 v[30:31], v[178:179], v[62:63], v[30:31] op_sel:[1,0,0] op_sel_hi:[1,1,1]
	s_waitcnt lgkmcnt(0)
	v_mad_u32_u24 v160, v160, s100, v199
	v_mad_u32_u24 v161, v161, s100, v199
	v_mad_u32_u24 v162, v162, s100, v199
	v_mad_u32_u24 v163, v163, s100, v199
	global_load_dwordx4 v[64:67], v160, s[4:5]
	global_load_dwordx2 v[68:69], v160, s[4:5] offset:16
	global_load_dwordx4 v[70:73], v161, s[4:5]
	global_load_dwordx2 v[74:75], v161, s[4:5] offset:16
	global_load_dwordx4 v[76:79], v162, s[4:5]
	global_load_dwordx2 v[80:81], v162, s[4:5] offset:16
	global_load_dwordx4 v[82:85], v163, s[4:5]
	global_load_dwordx2 v[86:87], v163, s[4:5] offset:16
	ds_read2_b32 v[168:169], v201 offset0:32 offset1:40
	ds_read2_b32 v[170:171], v201 offset0:48 offset1:56
	ds_read2_b32 v[176:177], v204 offset0:64 offset1:72
	ds_read2_b32 v[178:179], v204 offset0:80 offset1:88
	s_waitcnt vmcnt(32)
	v_cvt_scalef32_pk32_f32_fp6 v[32:63], v[88:93], 1.0
	v_pk_fma_f32 v[0:1], v[184:185], v[32:33], v[0:1] op_sel_hi:[0,1,1]
	v_pk_fma_f32 v[2:3], v[184:185], v[34:35], v[2:3] op_sel_hi:[0,1,1]
	v_pk_fma_f32 v[4:5], v[184:185], v[36:37], v[4:5] op_sel_hi:[0,1,1]
	v_pk_fma_f32 v[6:7], v[184:185], v[38:39], v[6:7] op_sel_hi:[0,1,1]
	v_pk_fma_f32 v[8:9], v[184:185], v[40:41], v[8:9] op_sel_hi:[0,1,1]
	v_pk_fma_f32 v[10:11], v[184:185], v[42:43], v[10:11] op_sel_hi:[0,1,1]
	v_pk_fma_f32 v[12:13], v[184:185], v[44:45], v[12:13] op_sel_hi:[0,1,1]
	v_pk_fma_f32 v[14:15], v[184:185], v[46:47], v[14:15] op_sel_hi:[0,1,1]
	v_pk_fma_f32 v[16:17], v[184:185], v[48:49], v[16:17] op_sel_hi:[0,1,1]
	v_pk_fma_f32 v[18:19], v[184:185], v[50:51], v[18:19] op_sel_hi:[0,1,1]
	v_pk_fma_f32 v[20:21], v[184:185], v[52:53], v[20:21] op_sel_hi:[0,1,1]
	v_pk_fma_f32 v[22:23], v[184:185], v[54:55], v[22:23] op_sel_hi:[0,1,1]
	v_pk_fma_f32 v[24:25], v[184:185], v[56:57], v[24:25] op_sel_hi:[0,1,1]
	v_pk_fma_f32 v[26:27], v[184:185], v[58:59], v[26:27] op_sel_hi:[0,1,1]
	v_pk_fma_f32 v[28:29], v[184:185], v[60:61], v[28:29] op_sel_hi:[0,1,1]
	v_pk_fma_f32 v[30:31], v[184:185], v[62:63], v[30:31] op_sel_hi:[0,1,1]
	s_waitcnt vmcnt(30)
	v_cvt_scalef32_pk32_f32_fp6 v[32:63], v[94:99], 1.0
	v_pk_fma_f32 v[0:1], v[184:185], v[32:33], v[0:1] op_sel:[1,0,0] op_sel_hi:[1,1,1]
	v_pk_fma_f32 v[2:3], v[184:185], v[34:35], v[2:3] op_sel:[1,0,0] op_sel_hi:[1,1,1]
	v_pk_fma_f32 v[4:5], v[184:185], v[36:37], v[4:5] op_sel:[1,0,0] op_sel_hi:[1,1,1]
	v_pk_fma_f32 v[6:7], v[184:185], v[38:39], v[6:7] op_sel:[1,0,0] op_sel_hi:[1,1,1]
	v_pk_fma_f32 v[8:9], v[184:185], v[40:41], v[8:9] op_sel:[1,0,0] op_sel_hi:[1,1,1]
	v_pk_fma_f32 v[10:11], v[184:185], v[42:43], v[10:11] op_sel:[1,0,0] op_sel_hi:[1,1,1]
	v_pk_fma_f32 v[12:13], v[184:185], v[44:45], v[12:13] op_sel:[1,0,0] op_sel_hi:[1,1,1]
	v_pk_fma_f32 v[14:15], v[184:185], v[46:47], v[14:15] op_sel:[1,0,0] op_sel_hi:[1,1,1]
	v_pk_fma_f32 v[16:17], v[184:185], v[48:49], v[16:17] op_sel:[1,0,0] op_sel_hi:[1,1,1]
	v_pk_fma_f32 v[18:19], v[184:185], v[50:51], v[18:19] op_sel:[1,0,0] op_sel_hi:[1,1,1]
	v_pk_fma_f32 v[20:21], v[184:185], v[52:53], v[20:21] op_sel:[1,0,0] op_sel_hi:[1,1,1]
	v_pk_fma_f32 v[22:23], v[184:185], v[54:55], v[22:23] op_sel:[1,0,0] op_sel_hi:[1,1,1]
	v_pk_fma_f32 v[24:25], v[184:185], v[56:57], v[24:25] op_sel:[1,0,0] op_sel_hi:[1,1,1]
	v_pk_fma_f32 v[26:27], v[184:185], v[58:59], v[26:27] op_sel:[1,0,0] op_sel_hi:[1,1,1]
	v_pk_fma_f32 v[28:29], v[184:185], v[60:61], v[28:29] op_sel:[1,0,0] op_sel_hi:[1,1,1]
	v_pk_fma_f32 v[30:31], v[184:185], v[62:63], v[30:31] op_sel:[1,0,0] op_sel_hi:[1,1,1]
	s_waitcnt vmcnt(28)
	v_cvt_scalef32_pk32_f32_fp6 v[32:63], v[100:105], 1.0
	v_pk_fma_f32 v[0:1], v[186:187], v[32:33], v[0:1] op_sel_hi:[0,1,1]
	v_pk_fma_f32 v[2:3], v[186:187], v[34:35], v[2:3] op_sel_hi:[0,1,1]
	v_pk_fma_f32 v[4:5], v[186:187], v[36:37], v[4:5] op_sel_hi:[0,1,1]
	v_pk_fma_f32 v[6:7], v[186:187], v[38:39], v[6:7] op_sel_hi:[0,1,1]
	v_pk_fma_f32 v[8:9], v[186:187], v[40:41], v[8:9] op_sel_hi:[0,1,1]
	v_pk_fma_f32 v[10:11], v[186:187], v[42:43], v[10:11] op_sel_hi:[0,1,1]
	v_pk_fma_f32 v[12:13], v[186:187], v[44:45], v[12:13] op_sel_hi:[0,1,1]
	v_pk_fma_f32 v[14:15], v[186:187], v[46:47], v[14:15] op_sel_hi:[0,1,1]
	v_pk_fma_f32 v[16:17], v[186:187], v[48:49], v[16:17] op_sel_hi:[0,1,1]
	v_pk_fma_f32 v[18:19], v[186:187], v[50:51], v[18:19] op_sel_hi:[0,1,1]
	v_pk_fma_f32 v[20:21], v[186:187], v[52:53], v[20:21] op_sel_hi:[0,1,1]
	v_pk_fma_f32 v[22:23], v[186:187], v[54:55], v[22:23] op_sel_hi:[0,1,1]
	v_pk_fma_f32 v[24:25], v[186:187], v[56:57], v[24:25] op_sel_hi:[0,1,1]
	v_pk_fma_f32 v[26:27], v[186:187], v[58:59], v[26:27] op_sel_hi:[0,1,1]
	v_pk_fma_f32 v[28:29], v[186:187], v[60:61], v[28:29] op_sel_hi:[0,1,1]
	v_pk_fma_f32 v[30:31], v[186:187], v[62:63], v[30:31] op_sel_hi:[0,1,1]
	s_waitcnt vmcnt(26)
	v_cvt_scalef32_pk32_f32_fp6 v[32:63], v[106:111], 1.0
	v_pk_fma_f32 v[0:1], v[186:187], v[32:33], v[0:1] op_sel:[1,0,0] op_sel_hi:[1,1,1]
	v_pk_fma_f32 v[2:3], v[186:187], v[34:35], v[2:3] op_sel:[1,0,0] op_sel_hi:[1,1,1]
	v_pk_fma_f32 v[4:5], v[186:187], v[36:37], v[4:5] op_sel:[1,0,0] op_sel_hi:[1,1,1]
	v_pk_fma_f32 v[6:7], v[186:187], v[38:39], v[6:7] op_sel:[1,0,0] op_sel_hi:[1,1,1]
	v_pk_fma_f32 v[8:9], v[186:187], v[40:41], v[8:9] op_sel:[1,0,0] op_sel_hi:[1,1,1]
	v_pk_fma_f32 v[10:11], v[186:187], v[42:43], v[10:11] op_sel:[1,0,0] op_sel_hi:[1,1,1]
	v_pk_fma_f32 v[12:13], v[186:187], v[44:45], v[12:13] op_sel:[1,0,0] op_sel_hi:[1,1,1]
	v_pk_fma_f32 v[14:15], v[186:187], v[46:47], v[14:15] op_sel:[1,0,0] op_sel_hi:[1,1,1]
	v_pk_fma_f32 v[16:17], v[186:187], v[48:49], v[16:17] op_sel:[1,0,0] op_sel_hi:[1,1,1]
	v_pk_fma_f32 v[18:19], v[186:187], v[50:51], v[18:19] op_sel:[1,0,0] op_sel_hi:[1,1,1]
	v_pk_fma_f32 v[20:21], v[186:187], v[52:53], v[20:21] op_sel:[1,0,0] op_sel_hi:[1,1,1]
	v_pk_fma_f32 v[22:23], v[186:187], v[54:55], v[22:23] op_sel:[1,0,0] op_sel_hi:[1,1,1]
	v_pk_fma_f32 v[24:25], v[186:187], v[56:57], v[24:25] op_sel:[1,0,0] op_sel_hi:[1,1,1]
	v_pk_fma_f32 v[26:27], v[186:187], v[58:59], v[26:27] op_sel:[1,0,0] op_sel_hi:[1,1,1]
	v_pk_fma_f32 v[28:29], v[186:187], v[60:61], v[28:29] op_sel:[1,0,0] op_sel_hi:[1,1,1]
	v_pk_fma_f32 v[30:31], v[186:187], v[62:63], v[30:31] op_sel:[1,0,0] op_sel_hi:[1,1,1]
	s_waitcnt lgkmcnt(0)
	v_mad_u32_u24 v168, v168, s100, v199
	v_mad_u32_u24 v169, v169, s100, v199
	v_mad_u32_u24 v170, v170, s100, v199
	v_mad_u32_u24 v171, v171, s100, v199
	global_load_dwordx4 v[88:91], v168, s[4:5]
	global_load_dwordx2 v[92:93], v168, s[4:5] offset:16
	global_load_dwordx4 v[94:97], v169, s[4:5]
	global_load_dwordx2 v[98:99], v169, s[4:5] offset:16
	global_load_dwordx4 v[100:103], v170, s[4:5]
	global_load_dwordx2 v[104:105], v170, s[4:5] offset:16
	global_load_dwordx4 v[106:109], v171, s[4:5]
	global_load_dwordx2 v[110:111], v171, s[4:5] offset:16
	ds_read2_b32 v[160:161], v201 offset0:64 offset1:72
	ds_read2_b32 v[162:163], v201 offset0:80 offset1:88
	ds_read2_b32 v[184:185], v204 offset0:96 offset1:104
	ds_read2_b32 v[186:187], v204 offset0:112 offset1:120
	s_waitcnt vmcnt(32)
	v_cvt_scalef32_pk32_f32_fp6 v[32:63], v[112:117], 1.0
	v_pk_fma_f32 v[0:1], v[176:177], v[32:33], v[0:1] op_sel_hi:[0,1,1]
	v_pk_fma_f32 v[2:3], v[176:177], v[34:35], v[2:3] op_sel_hi:[0,1,1]
	v_pk_fma_f32 v[4:5], v[176:177], v[36:37], v[4:5] op_sel_hi:[0,1,1]
	v_pk_fma_f32 v[6:7], v[176:177], v[38:39], v[6:7] op_sel_hi:[0,1,1]
	v_pk_fma_f32 v[8:9], v[176:177], v[40:41], v[8:9] op_sel_hi:[0,1,1]
	v_pk_fma_f32 v[10:11], v[176:177], v[42:43], v[10:11] op_sel_hi:[0,1,1]
	v_pk_fma_f32 v[12:13], v[176:177], v[44:45], v[12:13] op_sel_hi:[0,1,1]
	v_pk_fma_f32 v[14:15], v[176:177], v[46:47], v[14:15] op_sel_hi:[0,1,1]
	v_pk_fma_f32 v[16:17], v[176:177], v[48:49], v[16:17] op_sel_hi:[0,1,1]
	v_pk_fma_f32 v[18:19], v[176:177], v[50:51], v[18:19] op_sel_hi:[0,1,1]
	v_pk_fma_f32 v[20:21], v[176:177], v[52:53], v[20:21] op_sel_hi:[0,1,1]
	v_pk_fma_f32 v[22:23], v[176:177], v[54:55], v[22:23] op_sel_hi:[0,1,1]
	v_pk_fma_f32 v[24:25], v[176:177], v[56:57], v[24:25] op_sel_hi:[0,1,1]
	v_pk_fma_f32 v[26:27], v[176:177], v[58:59], v[26:27] op_sel_hi:[0,1,1]
	v_pk_fma_f32 v[28:29], v[176:177], v[60:61], v[28:29] op_sel_hi:[0,1,1]
	v_pk_fma_f32 v[30:31], v[176:177], v[62:63], v[30:31] op_sel_hi:[0,1,1]
	s_waitcnt vmcnt(30)
	v_cvt_scalef32_pk32_f32_fp6 v[32:63], v[118:123], 1.0
	v_pk_fma_f32 v[0:1], v[176:177], v[32:33], v[0:1] op_sel:[1,0,0] op_sel_hi:[1,1,1]
	v_pk_fma_f32 v[2:3], v[176:177], v[34:35], v[2:3] op_sel:[1,0,0] op_sel_hi:[1,1,1]
	v_pk_fma_f32 v[4:5], v[176:177], v[36:37], v[4:5] op_sel:[1,0,0] op_sel_hi:[1,1,1]
	v_pk_fma_f32 v[6:7], v[176:177], v[38:39], v[6:7] op_sel:[1,0,0] op_sel_hi:[1,1,1]
	v_pk_fma_f32 v[8:9], v[176:177], v[40:41], v[8:9] op_sel:[1,0,0] op_sel_hi:[1,1,1]
	v_pk_fma_f32 v[10:11], v[176:177], v[42:43], v[10:11] op_sel:[1,0,0] op_sel_hi:[1,1,1]
	v_pk_fma_f32 v[12:13], v[176:177], v[44:45], v[12:13] op_sel:[1,0,0] op_sel_hi:[1,1,1]
	v_pk_fma_f32 v[14:15], v[176:177], v[46:47], v[14:15] op_sel:[1,0,0] op_sel_hi:[1,1,1]
	v_pk_fma_f32 v[16:17], v[176:177], v[48:49], v[16:17] op_sel:[1,0,0] op_sel_hi:[1,1,1]
	v_pk_fma_f32 v[18:19], v[176:177], v[50:51], v[18:19] op_sel:[1,0,0] op_sel_hi:[1,1,1]
	v_pk_fma_f32 v[20:21], v[176:177], v[52:53], v[20:21] op_sel:[1,0,0] op_sel_hi:[1,1,1]
	v_pk_fma_f32 v[22:23], v[176:177], v[54:55], v[22:23] op_sel:[1,0,0] op_sel_hi:[1,1,1]
	v_pk_fma_f32 v[24:25], v[176:177], v[56:57], v[24:25] op_sel:[1,0,0] op_sel_hi:[1,1,1]
	v_pk_fma_f32 v[26:27], v[176:177], v[58:59], v[26:27] op_sel:[1,0,0] op_sel_hi:[1,1,1]
	v_pk_fma_f32 v[28:29], v[176:177], v[60:61], v[28:29] op_sel:[1,0,0] op_sel_hi:[1,1,1]
	v_pk_fma_f32 v[30:31], v[176:177], v[62:63], v[30:31] op_sel:[1,0,0] op_sel_hi:[1,1,1]
	s_waitcnt vmcnt(28)
	v_cvt_scalef32_pk32_f32_fp6 v[32:63], v[124:129], 1.0
	v_pk_fma_f32 v[0:1], v[178:179], v[32:33], v[0:1] op_sel_hi:[0,1,1]
	v_pk_fma_f32 v[2:3], v[178:179], v[34:35], v[2:3] op_sel_hi:[0,1,1]
	v_pk_fma_f32 v[4:5], v[178:179], v[36:37], v[4:5] op_sel_hi:[0,1,1]
	v_pk_fma_f32 v[6:7], v[178:179], v[38:39], v[6:7] op_sel_hi:[0,1,1]
	v_pk_fma_f32 v[8:9], v[178:179], v[40:41], v[8:9] op_sel_hi:[0,1,1]
	v_pk_fma_f32 v[10:11], v[178:179], v[42:43], v[10:11] op_sel_hi:[0,1,1]
	v_pk_fma_f32 v[12:13], v[178:179], v[44:45], v[12:13] op_sel_hi:[0,1,1]
	v_pk_fma_f32 v[14:15], v[178:179], v[46:47], v[14:15] op_sel_hi:[0,1,1]
	v_pk_fma_f32 v[16:17], v[178:179], v[48:49], v[16:17] op_sel_hi:[0,1,1]
	v_pk_fma_f32 v[18:19], v[178:179], v[50:51], v[18:19] op_sel_hi:[0,1,1]
	v_pk_fma_f32 v[20:21], v[178:179], v[52:53], v[20:21] op_sel_hi:[0,1,1]
	v_pk_fma_f32 v[22:23], v[178:179], v[54:55], v[22:23] op_sel_hi:[0,1,1]
	v_pk_fma_f32 v[24:25], v[178:179], v[56:57], v[24:25] op_sel_hi:[0,1,1]
	v_pk_fma_f32 v[26:27], v[178:179], v[58:59], v[26:27] op_sel_hi:[0,1,1]
	v_pk_fma_f32 v[28:29], v[178:179], v[60:61], v[28:29] op_sel_hi:[0,1,1]
	v_pk_fma_f32 v[30:31], v[178:179], v[62:63], v[30:31] op_sel_hi:[0,1,1]
	s_waitcnt vmcnt(26)
	v_cvt_scalef32_pk32_f32_fp6 v[32:63], v[130:135], 1.0
	v_pk_fma_f32 v[0:1], v[178:179], v[32:33], v[0:1] op_sel:[1,0,0] op_sel_hi:[1,1,1]
	v_pk_fma_f32 v[2:3], v[178:179], v[34:35], v[2:3] op_sel:[1,0,0] op_sel_hi:[1,1,1]
	v_pk_fma_f32 v[4:5], v[178:179], v[36:37], v[4:5] op_sel:[1,0,0] op_sel_hi:[1,1,1]
	v_pk_fma_f32 v[6:7], v[178:179], v[38:39], v[6:7] op_sel:[1,0,0] op_sel_hi:[1,1,1]
	v_pk_fma_f32 v[8:9], v[178:179], v[40:41], v[8:9] op_sel:[1,0,0] op_sel_hi:[1,1,1]
	v_pk_fma_f32 v[10:11], v[178:179], v[42:43], v[10:11] op_sel:[1,0,0] op_sel_hi:[1,1,1]
	v_pk_fma_f32 v[12:13], v[178:179], v[44:45], v[12:13] op_sel:[1,0,0] op_sel_hi:[1,1,1]
	v_pk_fma_f32 v[14:15], v[178:179], v[46:47], v[14:15] op_sel:[1,0,0] op_sel_hi:[1,1,1]
	v_pk_fma_f32 v[16:17], v[178:179], v[48:49], v[16:17] op_sel:[1,0,0] op_sel_hi:[1,1,1]
	v_pk_fma_f32 v[18:19], v[178:179], v[50:51], v[18:19] op_sel:[1,0,0] op_sel_hi:[1,1,1]
	v_pk_fma_f32 v[20:21], v[178:179], v[52:53], v[20:21] op_sel:[1,0,0] op_sel_hi:[1,1,1]
	v_pk_fma_f32 v[22:23], v[178:179], v[54:55], v[22:23] op_sel:[1,0,0] op_sel_hi:[1,1,1]
	v_pk_fma_f32 v[24:25], v[178:179], v[56:57], v[24:25] op_sel:[1,0,0] op_sel_hi:[1,1,1]
	v_pk_fma_f32 v[26:27], v[178:179], v[58:59], v[26:27] op_sel:[1,0,0] op_sel_hi:[1,1,1]
	v_pk_fma_f32 v[28:29], v[178:179], v[60:61], v[28:29] op_sel:[1,0,0] op_sel_hi:[1,1,1]
	v_pk_fma_f32 v[30:31], v[178:179], v[62:63], v[30:31] op_sel:[1,0,0] op_sel_hi:[1,1,1]
	s_waitcnt lgkmcnt(0)
	v_mad_u32_u24 v160, v160, s100, v199
	v_mad_u32_u24 v161, v161, s100, v199
	v_mad_u32_u24 v162, v162, s100, v199
	v_mad_u32_u24 v163, v163, s100, v199
	global_load_dwordx4 v[112:115], v160, s[4:5]
	global_load_dwordx2 v[116:117], v160, s[4:5] offset:16
	global_load_dwordx4 v[118:121], v161, s[4:5]
	global_load_dwordx2 v[122:123], v161, s[4:5] offset:16
	global_load_dwordx4 v[124:127], v162, s[4:5]
	global_load_dwordx2 v[128:129], v162, s[4:5] offset:16
	global_load_dwordx4 v[130:133], v163, s[4:5]
	global_load_dwordx2 v[134:135], v163, s[4:5] offset:16
	ds_read2_b32 v[168:169], v201 offset0:96 offset1:104
	ds_read2_b32 v[170:171], v201 offset0:112 offset1:120
	ds_read2_b32 v[176:177], v203 offset0:0 offset1:8
	ds_read2_b32 v[178:179], v203 offset0:16 offset1:24
	s_waitcnt vmcnt(32)
	v_cvt_scalef32_pk32_f32_fp6 v[32:63], v[136:141], 1.0
	v_pk_fma_f32 v[0:1], v[184:185], v[32:33], v[0:1] op_sel_hi:[0,1,1]
	v_pk_fma_f32 v[2:3], v[184:185], v[34:35], v[2:3] op_sel_hi:[0,1,1]
	v_pk_fma_f32 v[4:5], v[184:185], v[36:37], v[4:5] op_sel_hi:[0,1,1]
	v_pk_fma_f32 v[6:7], v[184:185], v[38:39], v[6:7] op_sel_hi:[0,1,1]
	v_pk_fma_f32 v[8:9], v[184:185], v[40:41], v[8:9] op_sel_hi:[0,1,1]
	v_pk_fma_f32 v[10:11], v[184:185], v[42:43], v[10:11] op_sel_hi:[0,1,1]
	v_pk_fma_f32 v[12:13], v[184:185], v[44:45], v[12:13] op_sel_hi:[0,1,1]
	v_pk_fma_f32 v[14:15], v[184:185], v[46:47], v[14:15] op_sel_hi:[0,1,1]
	v_pk_fma_f32 v[16:17], v[184:185], v[48:49], v[16:17] op_sel_hi:[0,1,1]
	v_pk_fma_f32 v[18:19], v[184:185], v[50:51], v[18:19] op_sel_hi:[0,1,1]
	v_pk_fma_f32 v[20:21], v[184:185], v[52:53], v[20:21] op_sel_hi:[0,1,1]
	v_pk_fma_f32 v[22:23], v[184:185], v[54:55], v[22:23] op_sel_hi:[0,1,1]
	v_pk_fma_f32 v[24:25], v[184:185], v[56:57], v[24:25] op_sel_hi:[0,1,1]
	v_pk_fma_f32 v[26:27], v[184:185], v[58:59], v[26:27] op_sel_hi:[0,1,1]
	v_pk_fma_f32 v[28:29], v[184:185], v[60:61], v[28:29] op_sel_hi:[0,1,1]
	v_pk_fma_f32 v[30:31], v[184:185], v[62:63], v[30:31] op_sel_hi:[0,1,1]
	s_waitcnt vmcnt(30)
	v_cvt_scalef32_pk32_f32_fp6 v[32:63], v[142:147], 1.0
	v_pk_fma_f32 v[0:1], v[184:185], v[32:33], v[0:1] op_sel:[1,0,0] op_sel_hi:[1,1,1]
	v_pk_fma_f32 v[2:3], v[184:185], v[34:35], v[2:3] op_sel:[1,0,0] op_sel_hi:[1,1,1]
	v_pk_fma_f32 v[4:5], v[184:185], v[36:37], v[4:5] op_sel:[1,0,0] op_sel_hi:[1,1,1]
	v_pk_fma_f32 v[6:7], v[184:185], v[38:39], v[6:7] op_sel:[1,0,0] op_sel_hi:[1,1,1]
	v_pk_fma_f32 v[8:9], v[184:185], v[40:41], v[8:9] op_sel:[1,0,0] op_sel_hi:[1,1,1]
	v_pk_fma_f32 v[10:11], v[184:185], v[42:43], v[10:11] op_sel:[1,0,0] op_sel_hi:[1,1,1]
	v_pk_fma_f32 v[12:13], v[184:185], v[44:45], v[12:13] op_sel:[1,0,0] op_sel_hi:[1,1,1]
	v_pk_fma_f32 v[14:15], v[184:185], v[46:47], v[14:15] op_sel:[1,0,0] op_sel_hi:[1,1,1]
	v_pk_fma_f32 v[16:17], v[184:185], v[48:49], v[16:17] op_sel:[1,0,0] op_sel_hi:[1,1,1]
	v_pk_fma_f32 v[18:19], v[184:185], v[50:51], v[18:19] op_sel:[1,0,0] op_sel_hi:[1,1,1]
	v_pk_fma_f32 v[20:21], v[184:185], v[52:53], v[20:21] op_sel:[1,0,0] op_sel_hi:[1,1,1]
	v_pk_fma_f32 v[22:23], v[184:185], v[54:55], v[22:23] op_sel:[1,0,0] op_sel_hi:[1,1,1]
	v_pk_fma_f32 v[24:25], v[184:185], v[56:57], v[24:25] op_sel:[1,0,0] op_sel_hi:[1,1,1]
	v_pk_fma_f32 v[26:27], v[184:185], v[58:59], v[26:27] op_sel:[1,0,0] op_sel_hi:[1,1,1]
	v_pk_fma_f32 v[28:29], v[184:185], v[60:61], v[28:29] op_sel:[1,0,0] op_sel_hi:[1,1,1]
	v_pk_fma_f32 v[30:31], v[184:185], v[62:63], v[30:31] op_sel:[1,0,0] op_sel_hi:[1,1,1]
	s_waitcnt vmcnt(28)
	v_cvt_scalef32_pk32_f32_fp6 v[32:63], v[148:153], 1.0
	v_pk_fma_f32 v[0:1], v[186:187], v[32:33], v[0:1] op_sel_hi:[0,1,1]
	v_pk_fma_f32 v[2:3], v[186:187], v[34:35], v[2:3] op_sel_hi:[0,1,1]
	v_pk_fma_f32 v[4:5], v[186:187], v[36:37], v[4:5] op_sel_hi:[0,1,1]
	v_pk_fma_f32 v[6:7], v[186:187], v[38:39], v[6:7] op_sel_hi:[0,1,1]
	v_pk_fma_f32 v[8:9], v[186:187], v[40:41], v[8:9] op_sel_hi:[0,1,1]
	v_pk_fma_f32 v[10:11], v[186:187], v[42:43], v[10:11] op_sel_hi:[0,1,1]
	v_pk_fma_f32 v[12:13], v[186:187], v[44:45], v[12:13] op_sel_hi:[0,1,1]
	v_pk_fma_f32 v[14:15], v[186:187], v[46:47], v[14:15] op_sel_hi:[0,1,1]
	v_pk_fma_f32 v[16:17], v[186:187], v[48:49], v[16:17] op_sel_hi:[0,1,1]
	v_pk_fma_f32 v[18:19], v[186:187], v[50:51], v[18:19] op_sel_hi:[0,1,1]
	v_pk_fma_f32 v[20:21], v[186:187], v[52:53], v[20:21] op_sel_hi:[0,1,1]
	v_pk_fma_f32 v[22:23], v[186:187], v[54:55], v[22:23] op_sel_hi:[0,1,1]
	v_pk_fma_f32 v[24:25], v[186:187], v[56:57], v[24:25] op_sel_hi:[0,1,1]
	v_pk_fma_f32 v[26:27], v[186:187], v[58:59], v[26:27] op_sel_hi:[0,1,1]
	v_pk_fma_f32 v[28:29], v[186:187], v[60:61], v[28:29] op_sel_hi:[0,1,1]
	v_pk_fma_f32 v[30:31], v[186:187], v[62:63], v[30:31] op_sel_hi:[0,1,1]
	s_waitcnt vmcnt(26)
	v_cvt_scalef32_pk32_f32_fp6 v[32:63], v[154:159], 1.0
	v_pk_fma_f32 v[0:1], v[186:187], v[32:33], v[0:1] op_sel:[1,0,0] op_sel_hi:[1,1,1]
	v_pk_fma_f32 v[2:3], v[186:187], v[34:35], v[2:3] op_sel:[1,0,0] op_sel_hi:[1,1,1]
	v_pk_fma_f32 v[4:5], v[186:187], v[36:37], v[4:5] op_sel:[1,0,0] op_sel_hi:[1,1,1]
	v_pk_fma_f32 v[6:7], v[186:187], v[38:39], v[6:7] op_sel:[1,0,0] op_sel_hi:[1,1,1]
	v_pk_fma_f32 v[8:9], v[186:187], v[40:41], v[8:9] op_sel:[1,0,0] op_sel_hi:[1,1,1]
	v_pk_fma_f32 v[10:11], v[186:187], v[42:43], v[10:11] op_sel:[1,0,0] op_sel_hi:[1,1,1]
	v_pk_fma_f32 v[12:13], v[186:187], v[44:45], v[12:13] op_sel:[1,0,0] op_sel_hi:[1,1,1]
	v_pk_fma_f32 v[14:15], v[186:187], v[46:47], v[14:15] op_sel:[1,0,0] op_sel_hi:[1,1,1]
	v_pk_fma_f32 v[16:17], v[186:187], v[48:49], v[16:17] op_sel:[1,0,0] op_sel_hi:[1,1,1]
	v_pk_fma_f32 v[18:19], v[186:187], v[50:51], v[18:19] op_sel:[1,0,0] op_sel_hi:[1,1,1]
	v_pk_fma_f32 v[20:21], v[186:187], v[52:53], v[20:21] op_sel:[1,0,0] op_sel_hi:[1,1,1]
	v_pk_fma_f32 v[22:23], v[186:187], v[54:55], v[22:23] op_sel:[1,0,0] op_sel_hi:[1,1,1]
	v_pk_fma_f32 v[24:25], v[186:187], v[56:57], v[24:25] op_sel:[1,0,0] op_sel_hi:[1,1,1]
	v_pk_fma_f32 v[26:27], v[186:187], v[58:59], v[26:27] op_sel:[1,0,0] op_sel_hi:[1,1,1]
	v_pk_fma_f32 v[28:29], v[186:187], v[60:61], v[28:29] op_sel:[1,0,0] op_sel_hi:[1,1,1]
	v_pk_fma_f32 v[30:31], v[186:187], v[62:63], v[30:31] op_sel:[1,0,0] op_sel_hi:[1,1,1]
	s_waitcnt lgkmcnt(0)
	v_mad_u32_u24 v168, v168, s100, v199
	v_mad_u32_u24 v169, v169, s100, v199
	v_mad_u32_u24 v170, v170, s100, v199
	v_mad_u32_u24 v171, v171, s100, v199
	global_load_dwordx4 v[136:139], v168, s[4:5]
	global_load_dwordx2 v[140:141], v168, s[4:5] offset:16
	global_load_dwordx4 v[142:145], v169, s[4:5]
	global_load_dwordx2 v[146:147], v169, s[4:5] offset:16
	global_load_dwordx4 v[148:151], v170, s[4:5]
	global_load_dwordx2 v[152:153], v170, s[4:5] offset:16
	global_load_dwordx4 v[154:157], v171, s[4:5]
	global_load_dwordx2 v[158:159], v171, s[4:5] offset:16
	s_nop 1
	v_permlane32_swap_b32_e32 v0, v16
	v_permlane32_swap_b32_e32 v1, v17
	v_permlane32_swap_b32_e32 v2, v18
	v_permlane32_swap_b32_e32 v3, v19
	v_permlane32_swap_b32_e32 v4, v20
	v_permlane32_swap_b32_e32 v5, v21
	v_permlane32_swap_b32_e32 v6, v22
	v_permlane32_swap_b32_e32 v7, v23
	v_permlane32_swap_b32_e32 v8, v24
	v_permlane32_swap_b32_e32 v9, v25
	v_permlane32_swap_b32_e32 v10, v26
	v_permlane32_swap_b32_e32 v11, v27
	v_permlane32_swap_b32_e32 v12, v28
	v_permlane32_swap_b32_e32 v13, v29
	v_permlane32_swap_b32_e32 v14, v30
	v_permlane32_swap_b32_e32 v15, v31
	v_pk_add_f32 v[0:1], v[0:1], v[16:17]
	v_pk_add_f32 v[2:3], v[2:3], v[18:19]
	v_pk_add_f32 v[4:5], v[4:5], v[20:21]
	v_pk_add_f32 v[6:7], v[6:7], v[22:23]
	v_pk_add_f32 v[8:9], v[8:9], v[24:25]
	v_pk_add_f32 v[10:11], v[10:11], v[26:27]
	v_pk_add_f32 v[12:13], v[12:13], v[28:29]
	v_pk_add_f32 v[14:15], v[14:15], v[30:31]
	s_nop 1
	v_permlane16_swap_b32_e32 v0, v8
	v_permlane16_swap_b32_e32 v1, v9
	v_permlane16_swap_b32_e32 v2, v10
	v_permlane16_swap_b32_e32 v3, v11
	v_permlane16_swap_b32_e32 v4, v12
	v_permlane16_swap_b32_e32 v5, v13
	v_permlane16_swap_b32_e32 v6, v14
	v_permlane16_swap_b32_e32 v7, v15
	v_pk_add_f32 v[0:1], v[0:1], v[8:9]
	v_pk_add_f32 v[2:3], v[2:3], v[10:11]
	v_pk_add_f32 v[4:5], v[4:5], v[12:13]
	v_pk_add_f32 v[6:7], v[6:7], v[14:15]
	s_nop 1
	v_add_f32_dpp v0, v0, v0 row_ror:8 row_mask:0xf bank_mask:0x3
	v_add_f32_dpp v1, v1, v1 row_ror:8 row_mask:0xf bank_mask:0x3
	v_add_f32_dpp v2, v2, v2 row_ror:8 row_mask:0xf bank_mask:0x3
	v_add_f32_dpp v3, v3, v3 row_ror:8 row_mask:0xf bank_mask:0x3
	v_add_f32_dpp v0, v4, v4 row_ror:8 row_mask:0xf bank_mask:0xc
	v_add_f32_dpp v1, v5, v5 row_ror:8 row_mask:0xf bank_mask:0xc
	v_add_f32_dpp v2, v6, v6 row_ror:8 row_mask:0xf bank_mask:0xc
	v_add_f32_dpp v3, v7, v7 row_ror:8 row_mask:0xf bank_mask:0xc
	s_waitcnt vmcnt(32)
	v_pk_add_f32 v[192:193], v[192:193], v[0:1]
	v_pk_add_f32 v[194:195], v[194:195], v[2:3]
	global_store_dwordx4 v200, v[192:195], s[10:11]
	s_add_u32 s14, s14, 1
	s_and_b32 s14, s14, 63
	s_add_u32 s18, s14, 1
	s_and_b32 s98, s18, 63
	s_mov_b32 s100, s98
	s_and_b32 s19, s100, 15
	s_lshr_b32 s98, s100, 4
	s_lshl_b32 s99, s19, 9
	s_mul_i32 s15, s19, s16
	s_lshl_b32 s18, s98, 7
	s_add_u32 s15, s15, s18
	s_lshl_b32 s18, s101, 12
	s_add_u32 s15, s15, s18
	s_add_u32 s10, s24, s15
	s_addc_u32 s11, s25, 0
	s_mul_i32 s15, s98, 0x300000
	s_add_u32 s4, s26, 0x4800000
	s_addc_u32 s5, s27, 0
	s_add_u32 s4, s4, s15
	s_addc_u32 s5, s5, 0
	v_add_u32_e32 v202, s99, v197
	v_add_u32_e32 v204, s99, v198
	s_movk_i32 s100, 0xc0
	ds_read2_b32 v[160:161], v202 offset0:0 offset1:8
	ds_read2_b32 v[162:163], v202 offset0:16 offset1:24
	s_cmp_lg_u32 s14, 0
	s_cbranch_scc1 .Lgv1_loop
	s_waitcnt vmcnt(0) lgkmcnt(0)
	s_lshl_b32 s15, s92, 6
	s_add_u32 s101, s101, s15
	s_cmpk_lt_u32 s101, 0x8000
	s_cbranch_scc1 .Lgv1_chunk
	s_branch .LBB0_1104
